# all flat_* memory ops converted to global_* (addresses are global; LGKM now counts LDS/SMEM only)
# speedup vs baseline: 1.0156x; 1.0006x over previous
; DI int opaque_tid() { int t = threadIdx.x; asm volatile("" : "+v"(t)); return t; }
; DI float mod_val(const float* modp_l, const float* ada_b_l, int idx) { float s = ada_b_l[idx];
; #pragma unroll
;   for (int k = 0; k < 16; ++k) s += modp_l[(size_t)k * 12288 + idx]; return s; }
; DI void rownorm_phase(const Params& P, const float* xin, const bf16_t* yin, float* xout, bf16_t* hout, int lg, int gate_idx, const float* w_post,
;                       int lh, int scale_idx, int shift_idx, const float* w_pre, char* smem) {
;   float* A1 = (float*)smem; float* A2 = A1 + 2048; float* B2 = A2 + 2048;
;   const int tid = opaque_tid(), lane = tid & 63, w = tid >> 6;
;   const float* modp = (const float*)(P.ws + OFF_MODP);
;   for (int cidx = tid; cidx < 2048; cidx += NT) {
;     if (yin) A1[cidx] = mod_val(modp + (size_t)lg * 16 * 12288, P.ada_b + (size_t)lg * 12288, gate_idx * 2048 + cidx) * w_post[cidx];
;     if (hout) { A2[cidx] = w_pre[cidx] * (1.f + mod_val(modp + (size_t)lh * 16 * 12288, P.ada_b + (size_t)lh * 12288, scale_idx * 2048 + cidx));
;       B2[cidx] = mod_val(modp + (size_t)lh * 16 * 12288, P.ada_b + (size_t)lh * 12288, shift_idx * 2048 + cidx); }
;   }
.LBB0_106:
	v_lshl_add_u64 v[14:15], v[2:3], 0, s[4:5]
	v_lshl_add_u64 v[18:19], v[4:5], 0, s[4:5]
	v_lshl_add_u64 v[16:17], v[6:7], 0, s[4:5]
	global_load_dword v1, v[14:15], off
	global_load_dword v52, v[16:17], off
	v_add_co_u32_e32 v14, vcc, 0x1000, v18
	v_lshl_add_u64 v[22:23], v[10:11], 0, s[4:5]
	s_nop 0
	v_addc_co_u32_e32 v15, vcc, 0, v19, vcc
	v_add_co_u32_e32 v16, vcc, 0xd000, v18
	v_lshl_add_u64 v[20:21], v[8:9], 0, s[4:5]
	s_nop 0
	v_addc_co_u32_e32 v17, vcc, 0, v19, vcc
	v_add_co_u32_e32 v24, vcc, 0x19000, v18
	global_load_dword v53, v[14:15], off
	global_load_dword v54, v[16:17], off
	v_addc_co_u32_e32 v25, vcc, 0, v19, vcc
	v_add_co_u32_e32 v14, vcc, 0x25000, v18
	v_add_u32_e32 v12, 0x200, v12
	s_nop 0
	v_addc_co_u32_e32 v15, vcc, 0, v19, vcc
	v_add_co_u32_e32 v16, vcc, 0x31000, v18
	global_load_dword v55, v[24:25], off
	global_load_dword v56, v[14:15], off
	v_addc_co_u32_e32 v17, vcc, 0, v19, vcc
	v_add_co_u32_e32 v14, vcc, 0x3d000, v18
	s_add_u32 s4, s4, 0x800
	s_nop 0
	v_addc_co_u32_e32 v15, vcc, 0, v19, vcc
	v_add_co_u32_e32 v24, vcc, 0x49000, v18
	global_load_dword v57, v[16:17], off
	global_load_dword v58, v[14:15], off
	v_addc_co_u32_e32 v25, vcc, 0, v19, vcc
	v_add_co_u32_e32 v14, vcc, 0x55000, v18
	s_addc_u32 s5, s5, 0
	s_nop 0
	v_addc_co_u32_e32 v15, vcc, 0, v19, vcc
	v_add_co_u32_e32 v16, vcc, 0x61000, v18
	global_load_dword v59, v[24:25], off
	global_load_dword v60, v[14:15], off
	v_addc_co_u32_e32 v17, vcc, 0, v19, vcc
	v_add_co_u32_e32 v14, vcc, 0x6d000, v18
	s_waitcnt vmcnt(0) lgkmcnt(0)
	v_add_f32_e32 v52, v52, v53
	v_addc_co_u32_e32 v15, vcc, 0, v19, vcc
	v_add_co_u32_e32 v24, vcc, 0x79000, v18
	global_load_dword v61, v[16:17], off
	global_load_dword v62, v[14:15], off
	v_addc_co_u32_e32 v25, vcc, 0, v19, vcc
	v_add_co_u32_e32 v14, vcc, 0x85000, v18
	v_add_f32_e32 v52, v52, v54
	s_nop 0
	v_addc_co_u32_e32 v15, vcc, 0, v19, vcc
	v_add_co_u32_e32 v16, vcc, 0x91000, v18
	global_load_dword v63, v[24:25], off
	global_load_dword v64, v[14:15], off
	v_addc_co_u32_e32 v17, vcc, 0, v19, vcc
	v_add_co_u32_e32 v14, vcc, 0x9d000, v18
	v_add_f32_e32 v52, v52, v55
	s_nop 0
	v_addc_co_u32_e32 v15, vcc, 0, v19, vcc
	v_add_co_u32_e32 v24, vcc, 0xa9000, v18
	global_load_dword v65, v[16:17], off
	global_load_dword v66, v[14:15], off
	v_addc_co_u32_e32 v25, vcc, 0, v19, vcc
	v_add_co_u32_e32 v14, vcc, 0xb5000, v18
	v_add_f32_e32 v52, v52, v56
	s_nop 0
	v_addc_co_u32_e32 v15, vcc, 0, v19, vcc
	global_load_dword v67, v[24:25], off
	global_load_dword v68, v[14:15], off
	v_add_co_u32_e32 v16, vcc, s6, v22
	v_add_f32_e32 v52, v52, v57
	s_nop 0
	v_addc_co_u32_e32 v17, vcc, 0, v23, vcc
	v_add_co_u32_e32 v14, vcc, s7, v22
	v_add_f32_e32 v52, v52, v58
	s_nop 0
	v_addc_co_u32_e32 v15, vcc, 0, v23, vcc
	v_add_co_u32_e32 v18, vcc, s8, v22
	v_add_f32_e32 v52, v52, v59
	s_nop 0
	v_addc_co_u32_e32 v19, vcc, 0, v23, vcc
	v_add_co_u32_e32 v24, vcc, s9, v22
	v_add_f32_e32 v52, v52, v60
	s_nop 0
	v_addc_co_u32_e32 v25, vcc, 0, v23, vcc
	v_add_co_u32_e32 v26, vcc, s10, v22
	s_waitcnt vmcnt(0) lgkmcnt(0)
	v_add_f32_e32 v52, v52, v61
	v_addc_co_u32_e32 v27, vcc, 0, v23, vcc
	v_add_co_u32_e32 v28, vcc, s11, v22
	v_add_f32_e32 v52, v52, v62
	s_nop 0
	v_addc_co_u32_e32 v29, vcc, 0, v23, vcc
	v_add_co_u32_e32 v30, vcc, s12, v22
	v_add_f32_e32 v52, v52, v63
	s_nop 0
	v_addc_co_u32_e32 v31, vcc, 0, v23, vcc
	v_add_co_u32_e32 v36, vcc, s13, v22
	v_add_f32_e32 v52, v52, v64
	s_nop 0
	v_addc_co_u32_e32 v37, vcc, 0, v23, vcc
	v_add_co_u32_e32 v38, vcc, s14, v22
	v_add_f32_e32 v52, v52, v65
	s_nop 0
	v_addc_co_u32_e32 v39, vcc, 0, v23, vcc
	v_add_co_u32_e32 v40, vcc, s15, v22
	v_add_f32_e32 v52, v52, v66
	s_nop 0
	v_addc_co_u32_e32 v41, vcc, 0, v23, vcc
	v_add_co_u32_e32 v42, vcc, s16, v22
	v_add_f32_e32 v52, v52, v67
	s_nop 0
	v_addc_co_u32_e32 v43, vcc, 0, v23, vcc
	v_add_co_u32_e32 v44, vcc, s17, v22
	v_add_f32_e32 v52, v52, v68
	s_nop 0
	v_addc_co_u32_e32 v45, vcc, 0, v23, vcc
	v_add_co_u32_e32 v46, vcc, s18, v22
	v_add_f32_e32 v52, 1.0, v52
	s_nop 0
	v_addc_co_u32_e32 v47, vcc, 0, v23, vcc
	v_add_co_u32_e32 v48, vcc, s19, v22
	v_mul_f32_e32 v1, v1, v52
	s_nop 0
	v_addc_co_u32_e32 v49, vcc, 0, v23, vcc
	v_add_co_u32_e32 v50, vcc, s20, v22
	ds_write_b32 v13, v1
	s_nop 0
	v_addc_co_u32_e32 v51, vcc, 0, v23, vcc
	v_add_co_u32_e32 v22, vcc, s21, v22
	s_nop 1
	v_addc_co_u32_e32 v23, vcc, 0, v23, vcc
	global_load_dword v1, v[20:21], off
	global_load_dword v52, v[16:17], off
	global_load_dword v53, v[14:15], off
	global_load_dword v54, v[18:19], off
	global_load_dword v55, v[24:25], off
	global_load_dword v56, v[26:27], off
	global_load_dword v57, v[28:29], off
	global_load_dword v58, v[30:31], off
	global_load_dword v59, v[36:37], off
	global_load_dword v60, v[38:39], off
	global_load_dword v61, v[40:41], off
	global_load_dword v62, v[42:43], off
	global_load_dword v63, v[44:45], off
	global_load_dword v64, v[46:47], off
	global_load_dword v65, v[48:49], off
	global_load_dword v14, v[50:51], off
	global_load_dword v15, v[22:23], off
	v_cmp_lt_i32_e32 vcc, s22, v12
	s_or_b64 s[2:3], vcc, s[2:3]
	s_waitcnt vmcnt(0) lgkmcnt(0)
	v_add_f32_e32 v1, v1, v52
	v_add_f32_e32 v1, v1, v53
	v_add_f32_e32 v1, v1, v54
	v_add_f32_e32 v1, v1, v55
	v_add_f32_e32 v1, v1, v56
	v_add_f32_e32 v1, v1, v57
	v_add_f32_e32 v1, v1, v58
	v_add_f32_e32 v1, v1, v59
	v_add_f32_e32 v1, v1, v60
	v_add_f32_e32 v1, v1, v61
	v_add_f32_e32 v1, v1, v62
	v_add_f32_e32 v1, v1, v63
	v_add_f32_e32 v1, v1, v64
	v_add_f32_e32 v1, v1, v65
	v_add_f32_e32 v1, v1, v14
	v_add_f32_e32 v1, v1, v15
	ds_write_b32 v13, v1 offset:8192
	v_add_u32_e32 v13, 0x800, v13
	s_andn2_b64 exec, exec, s[2:3]
	s_cbranch_execnz .LBB0_106

; DI float bflo(unsigned u) { return __uint_as_float(u << 16); }
; DI float bfhi(unsigned u) { return __uint_as_float(u & 0xffff0000u); }
; DI float wave_sum(float v) { v += __shfl_xor(v, 32); v += __shfl_xor(v, 16); v += __shfl_xor(v, 8); v += __shfl_xor(v, 4); v += __shfl_xor(v, 2); v += __shfl_xor(v, 1); return v; }
; DI void rownorm_phase(const Params& P, const float* xin, const bf16_t* yin, float* xout, bf16_t* hout, int lg, int gate_idx, const float* w_post,
;                       int lh, int scale_idx, int shift_idx, const float* w_pre, char* smem) {
;     ...
;   for (int row = blockIdx.x * 8 + w; row < S_; row += gridDim.x * 8) {
;     f32x4 xv[8];
; #pragma unroll
;     for (int j = 0; j < 8; ++j) xv[j] = __builtin_nontemporal_load((const f32x4*)(xin + (size_t)row * 2048 + (j * 64 + lane) * 4));
;     if (yin) {
;       f32x4 yv[8]; float ss = 0.f;
; #pragma unroll
;       for (int j = 0; j < 8; ++j) { const u32x2 yb = __builtin_nontemporal_load((const u32x2*)(yin + (size_t)row * 2048 + (j * 64 + lane) * 4)); yv[j] = (f32x4){bflo(yb.x), bfhi(yb.x), bflo(yb.y), bfhi(yb.y)};
;         ss += yv[j].x * yv[j].x + yv[j].y * yv[j].y + yv[j].z * yv[j].z + yv[j].w * yv[j].w; }
;       ss = wave_sum(ss); const float r = rsqrtf(ss * (1.f / 2048.f) + EPS);
; #pragma unroll
;       for (int j = 0; j < 8; ++j) { const f32x4 a = *(const f32x4*)(A1 + (j * 64 + lane) * 4); xv[j] += a * (yv[j] * r); }
;     }
;     if (yin || xout != xin) {
; #pragma unroll
;       for (int j = 0; j < 8; ++j) __builtin_nontemporal_store(xv[j], (f32x4*)(xout + (size_t)row * 2048 + (j * 64 + lane) * 4));
;     }
.LBB0_110:
	v_ashrrev_i32_e32 v37, 31, v36
	v_lshlrev_b64 v[50:51], 13, v[36:37]
	v_lshl_add_u64 v[0:1], v[32:33], 0, v[50:51]
	v_lshl_add_u64 v[2:3], v[0:1], 0, v[38:39]
	global_load_dwordx4 v[28:31], v[2:3], off nt
	global_load_dwordx4 v[24:27], v[2:3], off offset:1024 nt
	global_load_dwordx4 v[20:23], v[2:3], off offset:2048 nt
	global_load_dwordx4 v[16:19], v[2:3], off offset:3072 nt
	v_lshl_add_u64 v[2:3], v[0:1], 0, v[42:43]
	v_lshl_add_u64 v[4:5], v[0:1], 0, v[44:45]
	v_lshl_add_u64 v[60:61], v[0:1], 0, v[46:47]
	global_load_dwordx4 v[12:15], v[2:3], off nt
	global_load_dwordx4 v[8:11], v[4:5], off nt
	v_lshl_add_u64 v[62:63], v[0:1], 0, v[48:49]
	global_load_dwordx4 v[4:7], v[60:61], off nt
	global_load_dwordx4 v[0:3], v[62:63], off nt
	s_and_b64 vcc, exec, s[2:3]
	s_cbranch_vccnz .LBB0_109
	v_lshl_add_u64 v[50:51], v[34:35], 0, v[50:51]
	v_lshl_add_u64 v[60:61], v[50:51], 0, v[38:39]
	s_waitcnt vmcnt(0) lgkmcnt(0)
	global_store_dwordx4 v[60:61], v[28:31], off nt
	global_store_dwordx4 v[60:61], v[24:27], off offset:1024 nt
	global_store_dwordx4 v[60:61], v[20:23], off offset:2048 nt
	global_store_dwordx4 v[60:61], v[16:19], off offset:3072 nt
	v_lshl_add_u64 v[60:61], v[50:51], 0, v[42:43]
	global_store_dwordx4 v[60:61], v[12:15], off nt
	v_lshl_add_u64 v[60:61], v[50:51], 0, v[44:45]
	global_store_dwordx4 v[60:61], v[8:11], off nt
	v_lshl_add_u64 v[60:61], v[50:51], 0, v[46:47]
	v_lshl_add_u64 v[50:51], v[50:51], 0, v[48:49]
	global_store_dwordx4 v[60:61], v[4:7], off nt
	global_store_dwordx4 v[50:51], v[0:3], off nt
	s_branch .LBB0_109

; #define MFMA32(a, b, c) __builtin_amdgcn_mfma_f32_32x32x16_bf16((a), (b), (c), 0, 0, 0)
; template <class Epi>
; DI void gemm_tile_s(const bf16_t* __restrict__ A, int lda, const bf16_t* __restrict__ Bt, int ldb, int K, int m0, int n0, char* smem, const Epi& epi) {
;     ...
;   const int r0 = tid >> 3, c0 = tid & 7;
;   const bf16_t* ag = A + (size_t)(m0 + r0) * lda + c0 * 8;
;   const bf16_t* bg = Bt + (size_t)(n0 + r0) * ldb + c0 * 8;
;   const int wofs = r0 * 128 + ((c0 ^ ((r0 >> 1) & 7)) << 4);
;   char* sA = smem; char* sB = smem + 32768;
;   u32x4 ra[4], rb[4];
; #pragma unroll
;   for (int i = 0; i < 4; ++i) { ra[i] = *(const u32x4*)(ag + (size_t)i * 64 * lda); rb[i] = *(const u32x4*)(bg + (size_t)i * 64 * ldb); }
; #pragma unroll
;   for (int i = 0; i < 4; ++i) { *(u32x4*)(sA + wofs + i * 8192) = ra[i]; *(u32x4*)(sB + wofs + i * 8192) = rb[i]; }
;   __syncthreads();
;   const int nk = K >> 6, swz = (lane >> 1) & 7;
;   const int aoff = (64 * wn + lq) * 128, boff = (128 * wm + lq) * 128;
;   for (int kt = 0; kt < nk; ++kt) {
;     const char* cA = sA + (kt & 1) * 65536; const char* cB = sB + (kt & 1) * 65536;
;     const bool more = (kt + 1 < nk);
;     if (more) { ag += 64; bg += 64;
; #pragma unroll
;       for (int i = 0; i < 4; ++i) { ra[i] = *(const u32x4*)(ag + (size_t)i * 64 * lda); rb[i] = *(const u32x4*)(bg + (size_t)i * 64 * ldb); } }
; #pragma unroll
;     for (int s = 0; s < 4; ++s) {
;       const int co = (((2 * s + h) ^ swz) << 4);
;       bf16x8 fa[2], fb[4];
; #pragma unroll
;       for (int ni = 0; ni < 2; ++ni) fa[ni] = *(const bf16x8*)(cB + aoff + ni * 4096 + co);
; #pragma unroll
;       for (int mi = 0; mi < 4; ++mi) fb[mi] = *(const bf16x8*)(cA + boff + mi * 4096 + co);
; #pragma unroll
;       for (int ni = 0; ni < 2; ++ni)
; #pragma unroll
;         for (int mi = 0; mi < 4; ++mi) acc[ni][mi] = MFMA32(fa[ni], fb[mi], acc[ni][mi]);
.LBB0_276:
	s_or_b64 exec, exec, s[0:1]
	global_load_dwordx2 v[138:139], v1, s[40:41] offset:1224
	v_mov_b32_e32 v209, v206
	s_mov_b32 s1, 0x1239a000
	v_ashrrev_i32_e32 v34, 3, v209
	v_lshlrev_b32_e32 v35, 4, v209
	s_waitcnt lgkmcnt(0)
	v_add_u32_e32 v2, s2, v34
	v_and_b32_e32 v0, 0x70, v35
	v_mad_i64_i32 v[2:3], s[8:9], v2, s81, v[6:7]
	v_lshl_add_u64 v[144:145], v[2:3], 0, v[0:1]
	v_add_co_u32_e32 v2, vcc, s85, v144
	s_mul_i32 s3, s3, 3
	s_nop 0
	v_addc_co_u32_e32 v3, vcc, 0, v145, vcc
	v_add_co_u32_e32 v130, vcc, s1, v144
	s_mov_b32 s1, 0x1244a000
	s_nop 0
	v_addc_co_u32_e32 v131, vcc, 0, v145, vcc
	s_sub_i32 s0, s4, s3
	v_add_co_u32_e32 v132, vcc, s1, v144
	s_lshl_b32 s0, s0, 8
	s_nop 0
	v_addc_co_u32_e32 v133, vcc, 0, v145, vcc
	s_mov_b32 s1, 0x124fa000
	v_add_u32_e32 v18, s0, v34
	v_add_co_u32_e32 v134, vcc, s1, v144
	s_movk_i32 s1, 0x380
	s_nop 0
	v_addc_co_u32_e32 v135, vcc, 0, v145, vcc
	global_load_dwordx4 v[2:5], v[2:3], off offset:32
	s_nop 0
	global_load_dwordx4 v[6:9], v[130:131], off offset:32
	global_load_dwordx4 v[10:13], v[132:133], off offset:32
	global_load_dwordx4 v[14:17], v[134:135], off offset:32
	v_lshrrev_b32_e32 v36, 5, v209
	v_bfe_u32 v180, v209, 1, 3
	v_lshlrev_b32_e32 v37, 7, v209
	v_bitop3_b32 v36, v36, v180, 1 bitop3:0x6c
	v_xor_b32_e32 v35, v35, v209
	v_lshlrev_b32_e32 v34, 7, v34
	v_and_b32_e32 v210, 0x6f80, v37
	v_lshlrev_b32_e32 v211, 4, v36
	v_ashrrev_i32_e32 v38, 1, v209
	v_or_b32_e32 v149, v210, v211
	v_and_b32_e32 v212, 0xffffff80, v38
	v_bfe_u32 v213, v209, 5, 1
	v_bitop3_b32 v153, v213, v180, 4 bitop3:0x36
	v_lshlrev_b32_e32 v224, 4, v153
	v_or_b32_e32 v153, v210, v224
	s_movk_i32 s3, 0xc00
	s_waitcnt vmcnt(0)
	v_mad_i64_i32 v[18:19], s[8:9], v18, s1, v[138:139]
	v_lshl_add_u64 v[146:147], v[18:19], 0, v[0:1]
	s_mov_b32 s1, 0x6200000
	v_add_co_u32_e32 v18, vcc, s1, v146
	s_mov_b32 s1, 0x620e000
	s_nop 0
	v_addc_co_u32_e32 v19, vcc, 0, v147, vcc
	v_add_co_u32_e32 v136, vcc, s1, v146
	s_mov_b32 s1, 0x621c000
	s_nop 0
	v_addc_co_u32_e32 v137, vcc, 0, v147, vcc
	v_add_co_u32_e32 v140, vcc, s1, v146
	s_mov_b32 s1, 0x622a000
	s_nop 0
	v_addc_co_u32_e32 v141, vcc, 0, v147, vcc
	v_add_co_u32_e32 v142, vcc, s1, v146
	s_movk_i32 s1, 0x70
	s_nop 0
	v_addc_co_u32_e32 v143, vcc, 0, v147, vcc
	global_load_dwordx4 v[18:21], v[18:19], off
	s_nop 0
	global_load_dwordx4 v[22:25], v[136:137], off
	global_load_dwordx4 v[26:29], v[140:141], off
	global_load_dwordx4 v[30:33], v[142:143], off
	v_and_or_b32 v151, v35, s1, v34
	v_and_b32_e32 v0, 31, v209
	s_mov_b64 s[8:9], 0x122ea020
	v_lshl_add_u64 v[144:145], v[144:145], 0, s[8:9]
	s_mov_b64 s[8:9], 0x6200000
	v_lshl_add_u64 v[146:147], v[146:147], 0, s[8:9]
	s_mov_b64 s[8:9], 0xa2e8000
	v_and_b32_e32 v209, 0xc0, v209
	s_waitcnt lgkmcnt(0)
	ds_write_b128 v151, v[2:5]
	ds_write_b128 v151, v[6:9] offset:8192
	ds_write_b128 v151, v[10:13] offset:16384
	ds_write_b128 v151, v[14:17] offset:24576
	s_waitcnt vmcnt(0)
	ds_write_b128 v151, v[18:21] offset:32768
	ds_write_b128 v151, v[22:25] offset:40960
	ds_write_b128 v151, v[26:29] offset:49152
	ds_write_b128 v151, v[30:33] offset:57344
	s_waitcnt lgkmcnt(0)
	s_barrier
	ds_read_b128 v[2:5], v149 offset:32768
	v_or_b32_e32 v6, v212, v0
	v_lshlrev_b32_e32 v222, 7, v6
	v_or_b32_e32 v150, v222, v211
	ds_read_b128 v[6:9], v150
	ds_read_b128 v[10:13], v149 offset:36864
	ds_read_b128 v[14:17], v150 offset:4096
	ds_read_b128 v[18:21], v150 offset:8192
	ds_read_b128 v[154:157], v150 offset:12288
	s_waitcnt lgkmcnt(4)
	v_mfma_f32_32x32x16_bf16 v[114:129], v[2:5], v[6:9], 0
	v_or_b32_e32 v0, s2, v0
	v_add_u32_e32 v234, v0, v212
	v_subrev_u32_e32 v0, s2, v234
	v_lshl_add_u32 v235, v0, 2, v240
	v_lshlrev_b32_e32 v212, 2, v213
	v_or3_b32 v212, v212, v209, s0
	s_waitcnt lgkmcnt(2)
	v_mfma_f32_32x32x16_bf16 v[98:113], v[2:5], v[14:17], 0
	s_waitcnt lgkmcnt(1)
	v_mfma_f32_32x32x16_bf16 v[82:97], v[2:5], v[18:21], 0
	s_waitcnt lgkmcnt(0)
	v_mfma_f32_32x32x16_bf16 v[66:81], v[2:5], v[154:157], 0
	v_bitop3_b32 v2, v213, v180, 2 bitop3:0x36
	v_lshlrev_b32_e32 v223, 4, v2
	v_or_b32_e32 v152, v210, v223
	v_or_b32_e32 v148, v222, v223
	v_mfma_f32_32x32x16_bf16 v[50:65], v[10:13], v[6:9], 0
	v_mfma_f32_32x32x16_bf16 v[34:49], v[10:13], v[14:17], 0
	v_mfma_f32_32x32x16_bf16 v[18:33], v[10:13], v[18:21], 0
	v_mfma_f32_32x32x16_bf16 v[2:17], v[10:13], v[154:157], 0
	ds_read_b128 v[154:157], v152 offset:32768
	ds_read_b128 v[158:161], v148
	ds_read_b128 v[162:165], v152 offset:36864
	ds_read_b128 v[166:169], v148 offset:4096
	ds_read_b128 v[170:173], v148 offset:8192
	ds_read_b128 v[174:177], v148 offset:12288
	s_waitcnt lgkmcnt(4)
	v_mfma_f32_32x32x16_bf16 v[114:129], v[154:157], v[158:161], v[114:129]
	s_waitcnt lgkmcnt(2)
	v_mfma_f32_32x32x16_bf16 v[98:113], v[154:157], v[166:169], v[98:113]
	s_waitcnt lgkmcnt(1)
	v_mfma_f32_32x32x16_bf16 v[82:97], v[154:157], v[170:173], v[82:97]
	s_waitcnt lgkmcnt(0)
	v_mfma_f32_32x32x16_bf16 v[66:81], v[154:157], v[174:177], v[66:81]
	v_or_b32_e32 v154, v222, v224
	v_bitop3_b32 v155, v213, v180, 6 bitop3:0x36
	v_lshlrev_b32_e32 v225, 4, v155
	v_or_b32_e32 v155, v222, v225
	v_ashrrev_i32_e32 v213, 31, v212
	v_lshlrev_b64 v[212:213], 2, v[212:213]
	v_mfma_f32_32x32x16_bf16 v[50:65], v[162:165], v[158:161], v[50:65]
	ds_read_b128 v[156:159], v153 offset:32768
	v_mfma_f32_32x32x16_bf16 v[34:49], v[162:165], v[166:169], v[34:49]
	v_mfma_f32_32x32x16_bf16 v[18:33], v[162:165], v[170:173], v[18:33]
	v_mfma_f32_32x32x16_bf16 v[2:17], v[162:165], v[174:177], v[2:17]
	ds_read_b128 v[160:163], v154
	ds_read_b128 v[164:167], v153 offset:36864
	ds_read_b128 v[168:171], v154 offset:4096
	ds_read_b128 v[172:175], v154 offset:8192
	ds_read_b128 v[176:179], v154 offset:12288
	s_waitcnt lgkmcnt(4)
; #define MFMA32(a, b, c) __builtin_amdgcn_mfma_f32_32x32x16_bf16((a), (b), (c), 0, 0, 0)
; template <class Epi>
; DI void gemm_tile_s(const bf16_t* __restrict__ A, int lda, const bf16_t* __restrict__ Bt, int ldb, int K, int m0, int n0, char* smem, const Epi& epi) {
;     ...
;   for (int kt = 0; kt < nk; ++kt) {
;     const char* cA = sA + (kt & 1) * 65536; const char* cB = sB + (kt & 1) * 65536;
;     const bool more = (kt + 1 < nk);
;     if (more) { ag += 64; bg += 64;
; #pragma unroll
;       for (int i = 0; i < 4; ++i) { ra[i] = *(const u32x4*)(ag + (size_t)i * 64 * lda); rb[i] = *(const u32x4*)(bg + (size_t)i * 64 * ldb); } }
; #pragma unroll
;     for (int s = 0; s < 4; ++s) {
;       const int co = (((2 * s + h) ^ swz) << 4);
;       bf16x8 fa[2], fb[4];
; #pragma unroll
;       for (int ni = 0; ni < 2; ++ni) fa[ni] = *(const bf16x8*)(cB + aoff + ni * 4096 + co);
; #pragma unroll
;       for (int mi = 0; mi < 4; ++mi) fb[mi] = *(const bf16x8*)(cA + boff + mi * 4096 + co);
; #pragma unroll
;       for (int ni = 0; ni < 2; ++ni)
; #pragma unroll
;         for (int mi = 0; mi < 4; ++mi) acc[ni][mi] = MFMA32(fa[ni], fb[mi], acc[ni][mi]);
;     }
;     if (more) { char* dA = sA + ((kt + 1) & 1) * 65536; char* dB = sB + ((kt + 1) & 1) * 65536;
; #pragma unroll
;       for (int i = 0; i < 4; ++i) { *(u32x4*)(dA + wofs + i * 8192) = ra[i]; *(u32x4*)(dB + wofs + i * 8192) = rb[i]; } }
;     __syncthreads();
	v_mfma_f32_32x32x16_bf16 v[114:129], v[156:159], v[160:163], v[114:129]
	s_waitcnt lgkmcnt(2)
	v_mfma_f32_32x32x16_bf16 v[98:113], v[156:159], v[168:171], v[98:113]
	s_waitcnt lgkmcnt(1)
	v_mfma_f32_32x32x16_bf16 v[82:97], v[156:159], v[172:175], v[82:97]
	s_waitcnt lgkmcnt(0)
	v_mfma_f32_32x32x16_bf16 v[66:81], v[156:159], v[176:179], v[66:81]
	v_or_b32_e32 v156, v210, v225
	v_add_u32_e32 v157, 0x10000, v151
	v_mfma_f32_32x32x16_bf16 v[50:65], v[164:167], v[160:163], v[50:65]
	ds_read_b128 v[158:161], v156 offset:32768
	v_mfma_f32_32x32x16_bf16 v[34:49], v[164:167], v[168:171], v[34:49]
	v_mfma_f32_32x32x16_bf16 v[18:33], v[164:167], v[172:175], v[18:33]
	v_mfma_f32_32x32x16_bf16 v[2:17], v[164:167], v[176:179], v[2:17]
	ds_read_b128 v[162:165], v155
	ds_read_b128 v[170:173], v156 offset:36864
	ds_read_b128 v[166:169], v155 offset:4096
	ds_read_b128 v[174:177], v155 offset:8192
	ds_read_b128 v[178:181], v155 offset:12288
	global_load_dwordx4 v[182:185], v[144:145], off offset:128
	global_load_dwordx4 v[186:189], v[146:147], off offset:128
	global_load_dwordx4 v[190:193], v[130:131], off offset:160
	global_load_dwordx4 v[194:197], v[136:137], off offset:128
	global_load_dwordx4 v[198:201], v[132:133], off offset:160
	global_load_dwordx4 v[202:205], v[140:141], off offset:128
	global_load_dwordx4 v[214:217], v[134:135], off offset:160
	global_load_dwordx4 v[218:221], v[142:143], off offset:128
	s_waitcnt lgkmcnt(0)
	v_mfma_f32_32x32x16_bf16 v[98:113], v[158:161], v[166:169], v[98:113]
	v_mfma_f32_32x32x16_bf16 v[34:49], v[170:173], v[166:169], v[34:49]
	v_or_b32_e32 v167, 0x18000, v210
	v_add_u32_e32 v166, 0x16000, v151
	v_add_u32_e32 v168, 0x1e000, v151
	v_or_b32_e32 v169, v167, v211
	v_mfma_f32_32x32x16_bf16 v[114:129], v[158:161], v[162:165], v[114:129]
	v_mfma_f32_32x32x16_bf16 v[82:97], v[158:161], v[174:177], v[82:97]
	v_mfma_f32_32x32x16_bf16 v[66:81], v[158:161], v[178:181], v[66:81]
	v_add_u32_e32 v160, 0x12000, v151
	v_add_u32_e32 v158, 0x18000, v151
	s_waitcnt vmcnt(0)
	ds_write_b128 v157, v[182:185]
	ds_write_b128 v158, v[186:189]
	v_mfma_f32_32x32x16_bf16 v[50:65], v[170:173], v[162:165], v[50:65]
	v_add_u32_e32 v162, 0x1a000, v151
	v_add_u32_e32 v163, 0x14000, v151
	v_add_u32_e32 v165, 0x1c000, v151
	ds_write_b128 v160, v[190:193]
	ds_write_b128 v162, v[194:197]
	ds_write_b128 v163, v[198:201]
	ds_write_b128 v165, v[202:205]
	v_mfma_f32_32x32x16_bf16 v[18:33], v[170:173], v[174:177], v[18:33]
	ds_write_b128 v166, v[214:217]
	ds_write_b128 v168, v[218:221]
	s_waitcnt lgkmcnt(0)
	s_barrier
	ds_read_b128 v[174:177], v169
	v_add_u32_e32 v196, 0x10000, v222
	v_or_b32_e32 v159, v196, v211
	v_mfma_f32_32x32x16_bf16 v[2:17], v[170:173], v[178:181], v[2:17]
	ds_read_b128 v[170:173], v159
	ds_read_b128 v[178:181], v169 offset:4096
	ds_read_b128 v[182:185], v159 offset:4096
	ds_read_b128 v[186:189], v159 offset:8192
	ds_read_b128 v[190:193], v159 offset:12288
	v_or_b32_e32 v161, v196, v223
	v_or_b32_e32 v164, v196, v224
	v_lshl_add_u64 v[210:211], v[138:139], 0, s[8:9]
	s_waitcnt lgkmcnt(4)
	v_mfma_f32_32x32x16_bf16 v[114:129], v[174:177], v[170:173], v[114:129]
	s_waitcnt lgkmcnt(3)
	v_mfma_f32_32x32x16_bf16 v[50:65], v[178:181], v[170:173], v[50:65]
	v_or_b32_e32 v170, v167, v223
	v_or_b32_e32 v171, v167, v224
	s_waitcnt lgkmcnt(2)
	v_mfma_f32_32x32x16_bf16 v[98:113], v[174:177], v[182:185], v[98:113]
	s_waitcnt lgkmcnt(1)
	v_mfma_f32_32x32x16_bf16 v[82:97], v[174:177], v[186:189], v[82:97]
	s_waitcnt lgkmcnt(0)
	v_mfma_f32_32x32x16_bf16 v[66:81], v[174:177], v[190:193], v[66:81]
	ds_read_b128 v[172:175], v170
	v_mfma_f32_32x32x16_bf16 v[34:49], v[178:181], v[182:185], v[34:49]
	v_mfma_f32_32x32x16_bf16 v[18:33], v[178:181], v[186:189], v[18:33]
	v_mfma_f32_32x32x16_bf16 v[2:17], v[178:181], v[190:193], v[2:17]
	ds_read_b128 v[176:179], v161
	ds_read_b128 v[180:183], v170 offset:4096
	ds_read_b128 v[184:187], v161 offset:4096
	ds_read_b128 v[188:191], v161 offset:8192
	ds_read_b128 v[192:195], v161 offset:12288
	s_waitcnt lgkmcnt(4)
	v_mfma_f32_32x32x16_bf16 v[114:129], v[172:175], v[176:179], v[114:129]
	s_waitcnt lgkmcnt(2)
	v_mfma_f32_32x32x16_bf16 v[98:113], v[172:175], v[184:187], v[98:113]
	s_waitcnt lgkmcnt(1)
	v_mfma_f32_32x32x16_bf16 v[82:97], v[172:175], v[188:191], v[82:97]
	s_waitcnt lgkmcnt(0)
	v_mfma_f32_32x32x16_bf16 v[66:81], v[172:175], v[192:195], v[66:81]
	ds_read_b128 v[172:175], v171
	v_mfma_f32_32x32x16_bf16 v[50:65], v[180:183], v[176:179], v[50:65]
	v_mfma_f32_32x32x16_bf16 v[34:49], v[180:183], v[184:187], v[34:49]
	v_mfma_f32_32x32x16_bf16 v[18:33], v[180:183], v[188:191], v[18:33]
	v_mfma_f32_32x32x16_bf16 v[2:17], v[180:183], v[192:195], v[2:17]
	ds_read_b128 v[176:179], v164
	ds_read_b128 v[180:183], v171 offset:4096
	ds_read_b128 v[184:187], v164 offset:4096
	ds_read_b128 v[188:191], v164 offset:8192
	ds_read_b128 v[192:195], v164 offset:12288
	s_waitcnt lgkmcnt(4)
	v_mfma_f32_32x32x16_bf16 v[114:129], v[172:175], v[176:179], v[114:129]
	s_waitcnt lgkmcnt(2)
	v_mfma_f32_32x32x16_bf16 v[98:113], v[172:175], v[184:187], v[98:113]
	s_waitcnt lgkmcnt(1)
	v_mfma_f32_32x32x16_bf16 v[82:97], v[172:175], v[188:191], v[82:97]
	s_waitcnt lgkmcnt(0)
	v_mfma_f32_32x32x16_bf16 v[66:81], v[172:175], v[192:195], v[66:81]
	v_or_b32_e32 v172, v167, v225
	v_or_b32_e32 v167, v196, v225
	v_mfma_f32_32x32x16_bf16 v[50:65], v[180:183], v[176:179], v[50:65]
	ds_read_b128 v[174:177], v172
	v_mfma_f32_32x32x16_bf16 v[34:49], v[180:183], v[184:187], v[34:49]
	v_mfma_f32_32x32x16_bf16 v[18:33], v[180:183], v[188:191], v[18:33]
	v_mfma_f32_32x32x16_bf16 v[2:17], v[180:183], v[192:195], v[2:17]
	ds_read_b128 v[178:181], v167
	ds_read_b128 v[182:185], v172 offset:4096
	ds_read_b128 v[186:189], v167 offset:4096
	ds_read_b128 v[190:193], v167 offset:8192
	ds_read_b128 v[194:197], v167 offset:12288
	s_waitcnt lgkmcnt(4)
; #define MFMA32(a, b, c) __builtin_amdgcn_mfma_f32_32x32x16_bf16((a), (b), (c), 0, 0, 0)
; template <class Epi>
; DI void gemm_tile_s(const bf16_t* __restrict__ A, int lda, const bf16_t* __restrict__ Bt, int ldb, int K, int m0, int n0, char* smem, const Epi& epi) {
;     ...
;   for (int kt = 0; kt < nk; ++kt) {
;     const char* cA = sA + (kt & 1) * 65536; const char* cB = sB + (kt & 1) * 65536;
;     const bool more = (kt + 1 < nk);
;     if (more) { ag += 64; bg += 64;
; #pragma unroll
;       for (int i = 0; i < 4; ++i) { ra[i] = *(const u32x4*)(ag + (size_t)i * 64 * lda); rb[i] = *(const u32x4*)(bg + (size_t)i * 64 * ldb); } }
; #pragma unroll
;     for (int s = 0; s < 4; ++s) {
;       const int co = (((2 * s + h) ^ swz) << 4);
;       bf16x8 fa[2], fb[4];
; #pragma unroll
;       for (int ni = 0; ni < 2; ++ni) fa[ni] = *(const bf16x8*)(cB + aoff + ni * 4096 + co);
; #pragma unroll
;       for (int mi = 0; mi < 4; ++mi) fb[mi] = *(const bf16x8*)(cA + boff + mi * 4096 + co);
; #pragma unroll
;       for (int ni = 0; ni < 2; ++ni)
; #pragma unroll
;         for (int mi = 0; mi < 4; ++mi) acc[ni][mi] = MFMA32(fa[ni], fb[mi], acc[ni][mi]);
;     }
;     if (more) { char* dA = sA + ((kt + 1) & 1) * 65536; char* dB = sB + ((kt + 1) & 1) * 65536;
; #pragma unroll
;       for (int i = 0; i < 4; ++i) { *(u32x4*)(dA + wofs + i * 8192) = ra[i]; *(u32x4*)(dB + wofs + i * 8192) = rb[i]; } }
;     __syncthreads();
	v_mfma_f32_32x32x16_bf16 v[114:129], v[174:177], v[178:181], v[114:129]
	s_waitcnt lgkmcnt(2)
	v_mfma_f32_32x32x16_bf16 v[98:113], v[174:177], v[186:189], v[98:113]
	s_waitcnt lgkmcnt(1)
	v_mfma_f32_32x32x16_bf16 v[82:97], v[174:177], v[190:193], v[82:97]
	s_waitcnt lgkmcnt(0)
	v_mfma_f32_32x32x16_bf16 v[66:81], v[174:177], v[194:197], v[66:81]
	v_mfma_f32_32x32x16_bf16 v[50:65], v[182:185], v[178:181], v[50:65]
	v_mfma_f32_32x32x16_bf16 v[34:49], v[182:185], v[186:189], v[34:49]
	global_load_dwordx4 v[174:177], v[144:145], off offset:256
	global_load_dwordx4 v[178:181], v[146:147], off offset:256
	global_load_dwordx4 v[186:189], v[130:131], off offset:288
	global_load_dwordx4 v[198:201], v[136:137], off offset:256
	global_load_dwordx4 v[202:205], v[132:133], off offset:288
	global_load_dwordx4 v[214:217], v[140:141], off offset:256
	global_load_dwordx4 v[218:221], v[134:135], off offset:288
	v_mfma_f32_32x32x16_bf16 v[18:33], v[182:185], v[190:193], v[18:33]
	global_load_dwordx4 v[190:193], v[142:143], off offset:256
	s_waitcnt vmcnt(0) lgkmcnt(0)
	ds_write_b128 v151, v[174:177]
	ds_write_b128 v151, v[178:181] offset:32768
	ds_write_b128 v151, v[186:189] offset:8192
	ds_write_b128 v151, v[198:201] offset:40960
	ds_write_b128 v151, v[202:205] offset:16384
	ds_write_b128 v151, v[214:217] offset:49152
	ds_write_b128 v151, v[218:221] offset:24576
	ds_write_b128 v151, v[190:193] offset:57344
	v_mfma_f32_32x32x16_bf16 v[2:17], v[182:185], v[194:197], v[2:17]
	s_waitcnt lgkmcnt(0)
	s_barrier
	ds_read_b128 v[174:177], v149 offset:32768
	ds_read_b128 v[178:181], v150
	ds_read_b128 v[182:185], v149 offset:36864
	ds_read_b128 v[186:189], v150 offset:4096
	ds_read_b128 v[190:193], v150 offset:8192
	ds_read_b128 v[194:197], v150 offset:12288
	s_waitcnt lgkmcnt(4)
	v_mfma_f32_32x32x16_bf16 v[114:129], v[174:177], v[178:181], v[114:129]
	s_waitcnt lgkmcnt(2)
	v_mfma_f32_32x32x16_bf16 v[98:113], v[174:177], v[186:189], v[98:113]
	s_waitcnt lgkmcnt(1)
	v_mfma_f32_32x32x16_bf16 v[82:97], v[174:177], v[190:193], v[82:97]
	s_waitcnt lgkmcnt(0)
	v_mfma_f32_32x32x16_bf16 v[66:81], v[174:177], v[194:197], v[66:81]
	v_mfma_f32_32x32x16_bf16 v[50:65], v[182:185], v[178:181], v[50:65]
	v_mfma_f32_32x32x16_bf16 v[34:49], v[182:185], v[186:189], v[34:49]
	v_mfma_f32_32x32x16_bf16 v[18:33], v[182:185], v[190:193], v[18:33]
	v_mfma_f32_32x32x16_bf16 v[2:17], v[182:185], v[194:197], v[2:17]
	ds_read_b128 v[174:177], v152 offset:32768
	ds_read_b128 v[178:181], v148
	ds_read_b128 v[182:185], v152 offset:36864
	ds_read_b128 v[186:189], v148 offset:4096
	ds_read_b128 v[190:193], v148 offset:8192
	ds_read_b128 v[194:197], v148 offset:12288
	s_waitcnt lgkmcnt(4)
	v_mfma_f32_32x32x16_bf16 v[114:129], v[174:177], v[178:181], v[114:129]
	s_waitcnt lgkmcnt(2)
	v_mfma_f32_32x32x16_bf16 v[98:113], v[174:177], v[186:189], v[98:113]
	s_waitcnt lgkmcnt(1)
	v_mfma_f32_32x32x16_bf16 v[82:97], v[174:177], v[190:193], v[82:97]
	s_waitcnt lgkmcnt(0)
	v_mfma_f32_32x32x16_bf16 v[66:81], v[174:177], v[194:197], v[66:81]
	v_mfma_f32_32x32x16_bf16 v[50:65], v[182:185], v[178:181], v[50:65]
	v_mfma_f32_32x32x16_bf16 v[34:49], v[182:185], v[186:189], v[34:49]
	v_mfma_f32_32x32x16_bf16 v[18:33], v[182:185], v[190:193], v[18:33]
	v_mfma_f32_32x32x16_bf16 v[2:17], v[182:185], v[194:197], v[2:17]
	ds_read_b128 v[174:177], v153 offset:32768
	ds_read_b128 v[178:181], v154
	ds_read_b128 v[182:185], v153 offset:36864
	ds_read_b128 v[186:189], v154 offset:4096
	ds_read_b128 v[190:193], v154 offset:8192
	ds_read_b128 v[194:197], v154 offset:12288
	s_waitcnt lgkmcnt(4)
	v_mfma_f32_32x32x16_bf16 v[114:129], v[174:177], v[178:181], v[114:129]
	s_waitcnt lgkmcnt(2)
	v_mfma_f32_32x32x16_bf16 v[98:113], v[174:177], v[186:189], v[98:113]
	s_waitcnt lgkmcnt(1)
	v_mfma_f32_32x32x16_bf16 v[82:97], v[174:177], v[190:193], v[82:97]
	s_waitcnt lgkmcnt(0)
	v_mfma_f32_32x32x16_bf16 v[66:81], v[174:177], v[194:197], v[66:81]
	v_mfma_f32_32x32x16_bf16 v[50:65], v[182:185], v[178:181], v[50:65]
	v_mfma_f32_32x32x16_bf16 v[34:49], v[182:185], v[186:189], v[34:49]
	v_mfma_f32_32x32x16_bf16 v[18:33], v[182:185], v[190:193], v[18:33]
	v_mfma_f32_32x32x16_bf16 v[2:17], v[182:185], v[194:197], v[2:17]
	ds_read_b128 v[174:177], v156 offset:32768
	ds_read_b128 v[178:181], v155
	ds_read_b128 v[182:185], v156 offset:36864
	ds_read_b128 v[186:189], v155 offset:4096
	ds_read_b128 v[190:193], v155 offset:8192
	ds_read_b128 v[194:197], v155 offset:12288
	s_waitcnt lgkmcnt(4)
	v_mfma_f32_32x32x16_bf16 v[114:129], v[174:177], v[178:181], v[114:129]
	s_waitcnt lgkmcnt(2)
	v_mfma_f32_32x32x16_bf16 v[98:113], v[174:177], v[186:189], v[98:113]
	s_waitcnt lgkmcnt(1)
	v_mfma_f32_32x32x16_bf16 v[82:97], v[174:177], v[190:193], v[82:97]
	s_waitcnt lgkmcnt(0)
	v_mfma_f32_32x32x16_bf16 v[66:81], v[174:177], v[194:197], v[66:81]
	v_mfma_f32_32x32x16_bf16 v[50:65], v[182:185], v[178:181], v[50:65]
	v_mfma_f32_32x32x16_bf16 v[34:49], v[182:185], v[186:189], v[34:49]
	global_load_dwordx4 v[174:177], v[144:145], off offset:384
	global_load_dwordx4 v[178:181], v[146:147], off offset:384
	global_load_dwordx4 v[186:189], v[130:131], off offset:416
	global_load_dwordx4 v[198:201], v[136:137], off offset:384
	global_load_dwordx4 v[202:205], v[132:133], off offset:416
	global_load_dwordx4 v[214:217], v[140:141], off offset:384
	global_load_dwordx4 v[218:221], v[134:135], off offset:416
	v_mfma_f32_32x32x16_bf16 v[18:33], v[182:185], v[190:193], v[18:33]
	global_load_dwordx4 v[190:193], v[142:143], off offset:384
	s_waitcnt vmcnt(0) lgkmcnt(0)
	ds_write_b128 v157, v[174:177]
	ds_write_b128 v158, v[178:181]
	ds_write_b128 v160, v[186:189]
	ds_write_b128 v162, v[198:201]
	ds_write_b128 v163, v[202:205]
	ds_write_b128 v165, v[214:217]
	ds_write_b128 v166, v[218:221]
	ds_write_b128 v168, v[190:193]
	v_mfma_f32_32x32x16_bf16 v[2:17], v[182:185], v[194:197], v[2:17]
	s_waitcnt lgkmcnt(0)
	s_barrier
; #define MFMA32(a, b, c) __builtin_amdgcn_mfma_f32_32x32x16_bf16((a), (b), (c), 0, 0, 0)
; template <class Epi>
; DI void gemm_tile_s(const bf16_t* __restrict__ A, int lda, const bf16_t* __restrict__ Bt, int ldb, int K, int m0, int n0, char* smem, const Epi& epi) {
;     ...
;   for (int kt = 0; kt < nk; ++kt) {
;     const char* cA = sA + (kt & 1) * 65536; const char* cB = sB + (kt & 1) * 65536;
;     const bool more = (kt + 1 < nk);
;     if (more) { ag += 64; bg += 64;
; #pragma unroll
;       for (int i = 0; i < 4; ++i) { ra[i] = *(const u32x4*)(ag + (size_t)i * 64 * lda); rb[i] = *(const u32x4*)(bg + (size_t)i * 64 * ldb); } }
; #pragma unroll
;     for (int s = 0; s < 4; ++s) {
;       const int co = (((2 * s + h) ^ swz) << 4);
;       bf16x8 fa[2], fb[4];
; #pragma unroll
;       for (int ni = 0; ni < 2; ++ni) fa[ni] = *(const bf16x8*)(cB + aoff + ni * 4096 + co);
; #pragma unroll
;       for (int mi = 0; mi < 4; ++mi) fb[mi] = *(const bf16x8*)(cA + boff + mi * 4096 + co);
; #pragma unroll
;       for (int ni = 0; ni < 2; ++ni)
; #pragma unroll
;         for (int mi = 0; mi < 4; ++mi) acc[ni][mi] = MFMA32(fa[ni], fb[mi], acc[ni][mi]);
;     }
;     if (more) { char* dA = sA + ((kt + 1) & 1) * 65536; char* dB = sB + ((kt + 1) & 1) * 65536;
; #pragma unroll
;       for (int i = 0; i < 4; ++i) { *(u32x4*)(dA + wofs + i * 8192) = ra[i]; *(u32x4*)(dB + wofs + i * 8192) = rb[i]; } }
;     __syncthreads();
	ds_read_b128 v[174:177], v169
	ds_read_b128 v[178:181], v159
	ds_read_b128 v[182:185], v169 offset:4096
	ds_read_b128 v[186:189], v159 offset:4096
	ds_read_b128 v[190:193], v159 offset:8192
	ds_read_b128 v[194:197], v159 offset:12288
	s_waitcnt lgkmcnt(4)
	v_mfma_f32_32x32x16_bf16 v[114:129], v[174:177], v[178:181], v[114:129]
	s_waitcnt lgkmcnt(2)
	v_mfma_f32_32x32x16_bf16 v[98:113], v[174:177], v[186:189], v[98:113]
	s_waitcnt lgkmcnt(1)
	v_mfma_f32_32x32x16_bf16 v[82:97], v[174:177], v[190:193], v[82:97]
	s_waitcnt lgkmcnt(0)
	v_mfma_f32_32x32x16_bf16 v[66:81], v[174:177], v[194:197], v[66:81]
	v_mfma_f32_32x32x16_bf16 v[50:65], v[182:185], v[178:181], v[50:65]
	v_mfma_f32_32x32x16_bf16 v[34:49], v[182:185], v[186:189], v[34:49]
	v_mfma_f32_32x32x16_bf16 v[18:33], v[182:185], v[190:193], v[18:33]
	v_mfma_f32_32x32x16_bf16 v[2:17], v[182:185], v[194:197], v[2:17]
	ds_read_b128 v[174:177], v170
	ds_read_b128 v[178:181], v161
	ds_read_b128 v[182:185], v170 offset:4096
	ds_read_b128 v[186:189], v161 offset:4096
	ds_read_b128 v[190:193], v161 offset:8192
	ds_read_b128 v[194:197], v161 offset:12288
	s_waitcnt lgkmcnt(4)
	v_mfma_f32_32x32x16_bf16 v[114:129], v[174:177], v[178:181], v[114:129]
	s_waitcnt lgkmcnt(2)
	v_mfma_f32_32x32x16_bf16 v[98:113], v[174:177], v[186:189], v[98:113]
	s_waitcnt lgkmcnt(1)
	v_mfma_f32_32x32x16_bf16 v[82:97], v[174:177], v[190:193], v[82:97]
	s_waitcnt lgkmcnt(0)
	v_mfma_f32_32x32x16_bf16 v[66:81], v[174:177], v[194:197], v[66:81]
	v_mfma_f32_32x32x16_bf16 v[50:65], v[182:185], v[178:181], v[50:65]
	v_mfma_f32_32x32x16_bf16 v[34:49], v[182:185], v[186:189], v[34:49]
	v_mfma_f32_32x32x16_bf16 v[18:33], v[182:185], v[190:193], v[18:33]
	v_mfma_f32_32x32x16_bf16 v[2:17], v[182:185], v[194:197], v[2:17]
	ds_read_b128 v[174:177], v171
	ds_read_b128 v[178:181], v164
	ds_read_b128 v[182:185], v171 offset:4096
	ds_read_b128 v[186:189], v164 offset:4096
	ds_read_b128 v[190:193], v164 offset:8192
	ds_read_b128 v[194:197], v164 offset:12288
	s_waitcnt lgkmcnt(4)
	v_mfma_f32_32x32x16_bf16 v[114:129], v[174:177], v[178:181], v[114:129]
	s_waitcnt lgkmcnt(2)
	v_mfma_f32_32x32x16_bf16 v[98:113], v[174:177], v[186:189], v[98:113]
	s_waitcnt lgkmcnt(1)
	v_mfma_f32_32x32x16_bf16 v[82:97], v[174:177], v[190:193], v[82:97]
	s_waitcnt lgkmcnt(0)
	v_mfma_f32_32x32x16_bf16 v[66:81], v[174:177], v[194:197], v[66:81]
	v_mfma_f32_32x32x16_bf16 v[50:65], v[182:185], v[178:181], v[50:65]
	v_mfma_f32_32x32x16_bf16 v[34:49], v[182:185], v[186:189], v[34:49]
	v_mfma_f32_32x32x16_bf16 v[18:33], v[182:185], v[190:193], v[18:33]
	v_mfma_f32_32x32x16_bf16 v[2:17], v[182:185], v[194:197], v[2:17]
	ds_read_b128 v[174:177], v172
	ds_read_b128 v[178:181], v167
	ds_read_b128 v[182:185], v172 offset:4096
	ds_read_b128 v[186:189], v167 offset:4096
	ds_read_b128 v[190:193], v167 offset:8192
	ds_read_b128 v[194:197], v167 offset:12288
	s_waitcnt lgkmcnt(4)
	v_mfma_f32_32x32x16_bf16 v[114:129], v[174:177], v[178:181], v[114:129]
	s_waitcnt lgkmcnt(2)
	v_mfma_f32_32x32x16_bf16 v[98:113], v[174:177], v[186:189], v[98:113]
	s_waitcnt lgkmcnt(1)
	v_mfma_f32_32x32x16_bf16 v[82:97], v[174:177], v[190:193], v[82:97]
	s_waitcnt lgkmcnt(0)
	v_mfma_f32_32x32x16_bf16 v[66:81], v[174:177], v[194:197], v[66:81]
	v_mfma_f32_32x32x16_bf16 v[50:65], v[182:185], v[178:181], v[50:65]
	v_mfma_f32_32x32x16_bf16 v[34:49], v[182:185], v[186:189], v[34:49]
	global_load_dwordx4 v[174:177], v[144:145], off offset:512
	global_load_dwordx4 v[178:181], v[146:147], off offset:512
	global_load_dwordx4 v[186:189], v[130:131], off offset:544
	global_load_dwordx4 v[198:201], v[136:137], off offset:512
	global_load_dwordx4 v[202:205], v[132:133], off offset:544
	global_load_dwordx4 v[214:217], v[140:141], off offset:512
	global_load_dwordx4 v[218:221], v[134:135], off offset:544
	v_mfma_f32_32x32x16_bf16 v[18:33], v[182:185], v[190:193], v[18:33]
	global_load_dwordx4 v[190:193], v[142:143], off offset:512
	s_waitcnt vmcnt(0) lgkmcnt(0)
	ds_write_b128 v151, v[174:177]
	ds_write_b128 v151, v[178:181] offset:32768
	ds_write_b128 v151, v[186:189] offset:8192
	ds_write_b128 v151, v[198:201] offset:40960
	ds_write_b128 v151, v[202:205] offset:16384
	ds_write_b128 v151, v[214:217] offset:49152
	ds_write_b128 v151, v[218:221] offset:24576
	ds_write_b128 v151, v[190:193] offset:57344
	v_mfma_f32_32x32x16_bf16 v[2:17], v[182:185], v[194:197], v[2:17]
	s_waitcnt lgkmcnt(0)
	s_barrier
; #define MFMA32(a, b, c) __builtin_amdgcn_mfma_f32_32x32x16_bf16((a), (b), (c), 0, 0, 0)
; template <class Epi>
; DI void gemm_tile_s(const bf16_t* __restrict__ A, int lda, const bf16_t* __restrict__ Bt, int ldb, int K, int m0, int n0, char* smem, const Epi& epi) {
;     ...
;   for (int kt = 0; kt < nk; ++kt) {
;     const char* cA = sA + (kt & 1) * 65536; const char* cB = sB + (kt & 1) * 65536;
;     const bool more = (kt + 1 < nk);
;     if (more) { ag += 64; bg += 64;
; #pragma unroll
;       for (int i = 0; i < 4; ++i) { ra[i] = *(const u32x4*)(ag + (size_t)i * 64 * lda); rb[i] = *(const u32x4*)(bg + (size_t)i * 64 * ldb); } }
; #pragma unroll
;     for (int s = 0; s < 4; ++s) {
;       const int co = (((2 * s + h) ^ swz) << 4);
;       bf16x8 fa[2], fb[4];
; #pragma unroll
;       for (int ni = 0; ni < 2; ++ni) fa[ni] = *(const bf16x8*)(cB + aoff + ni * 4096 + co);
; #pragma unroll
;       for (int mi = 0; mi < 4; ++mi) fb[mi] = *(const bf16x8*)(cA + boff + mi * 4096 + co);
; #pragma unroll
;       for (int ni = 0; ni < 2; ++ni)
; #pragma unroll
;         for (int mi = 0; mi < 4; ++mi) acc[ni][mi] = MFMA32(fa[ni], fb[mi], acc[ni][mi]);
;     }
;     if (more) { char* dA = sA + ((kt + 1) & 1) * 65536; char* dB = sB + ((kt + 1) & 1) * 65536;
; #pragma unroll
;       for (int i = 0; i < 4; ++i) { *(u32x4*)(dA + wofs + i * 8192) = ra[i]; *(u32x4*)(dB + wofs + i * 8192) = rb[i]; } }
;     __syncthreads();
	ds_read_b128 v[174:177], v149 offset:32768
	ds_read_b128 v[178:181], v150
	ds_read_b128 v[182:185], v149 offset:36864
	ds_read_b128 v[186:189], v150 offset:4096
	ds_read_b128 v[190:193], v150 offset:8192
	ds_read_b128 v[194:197], v150 offset:12288
	s_waitcnt lgkmcnt(4)
	v_mfma_f32_32x32x16_bf16 v[114:129], v[174:177], v[178:181], v[114:129]
	s_waitcnt lgkmcnt(2)
	v_mfma_f32_32x32x16_bf16 v[98:113], v[174:177], v[186:189], v[98:113]
	s_waitcnt lgkmcnt(1)
	v_mfma_f32_32x32x16_bf16 v[82:97], v[174:177], v[190:193], v[82:97]
	s_waitcnt lgkmcnt(0)
	v_mfma_f32_32x32x16_bf16 v[66:81], v[174:177], v[194:197], v[66:81]
	v_mfma_f32_32x32x16_bf16 v[50:65], v[182:185], v[178:181], v[50:65]
	v_mfma_f32_32x32x16_bf16 v[34:49], v[182:185], v[186:189], v[34:49]
	v_mfma_f32_32x32x16_bf16 v[18:33], v[182:185], v[190:193], v[18:33]
	v_mfma_f32_32x32x16_bf16 v[2:17], v[182:185], v[194:197], v[2:17]
	ds_read_b128 v[174:177], v152 offset:32768
	ds_read_b128 v[178:181], v148
	ds_read_b128 v[182:185], v152 offset:36864
	ds_read_b128 v[186:189], v148 offset:4096
	ds_read_b128 v[190:193], v148 offset:8192
	ds_read_b128 v[194:197], v148 offset:12288
	s_waitcnt lgkmcnt(4)
	v_mfma_f32_32x32x16_bf16 v[114:129], v[174:177], v[178:181], v[114:129]
	s_waitcnt lgkmcnt(2)
	v_mfma_f32_32x32x16_bf16 v[98:113], v[174:177], v[186:189], v[98:113]
	s_waitcnt lgkmcnt(1)
	v_mfma_f32_32x32x16_bf16 v[82:97], v[174:177], v[190:193], v[82:97]
	s_waitcnt lgkmcnt(0)
	v_mfma_f32_32x32x16_bf16 v[66:81], v[174:177], v[194:197], v[66:81]
	v_mfma_f32_32x32x16_bf16 v[50:65], v[182:185], v[178:181], v[50:65]
	v_mfma_f32_32x32x16_bf16 v[34:49], v[182:185], v[186:189], v[34:49]
	v_mfma_f32_32x32x16_bf16 v[18:33], v[182:185], v[190:193], v[18:33]
	v_mfma_f32_32x32x16_bf16 v[2:17], v[182:185], v[194:197], v[2:17]
	ds_read_b128 v[174:177], v153 offset:32768
	ds_read_b128 v[178:181], v154
	ds_read_b128 v[182:185], v153 offset:36864
	ds_read_b128 v[186:189], v154 offset:4096
	ds_read_b128 v[190:193], v154 offset:8192
	ds_read_b128 v[194:197], v154 offset:12288
	s_waitcnt lgkmcnt(4)
	v_mfma_f32_32x32x16_bf16 v[114:129], v[174:177], v[178:181], v[114:129]
	s_waitcnt lgkmcnt(2)
	v_mfma_f32_32x32x16_bf16 v[98:113], v[174:177], v[186:189], v[98:113]
	s_waitcnt lgkmcnt(1)
	v_mfma_f32_32x32x16_bf16 v[82:97], v[174:177], v[190:193], v[82:97]
	s_waitcnt lgkmcnt(0)
	v_mfma_f32_32x32x16_bf16 v[66:81], v[174:177], v[194:197], v[66:81]
	v_mfma_f32_32x32x16_bf16 v[50:65], v[182:185], v[178:181], v[50:65]
	v_mfma_f32_32x32x16_bf16 v[34:49], v[182:185], v[186:189], v[34:49]
	v_mfma_f32_32x32x16_bf16 v[18:33], v[182:185], v[190:193], v[18:33]
	v_mfma_f32_32x32x16_bf16 v[2:17], v[182:185], v[194:197], v[2:17]
	ds_read_b128 v[174:177], v156 offset:32768
	ds_read_b128 v[178:181], v155
	ds_read_b128 v[182:185], v156 offset:36864
	ds_read_b128 v[186:189], v155 offset:4096
	ds_read_b128 v[190:193], v155 offset:8192
	ds_read_b128 v[194:197], v155 offset:12288
	s_waitcnt lgkmcnt(4)
	v_mfma_f32_32x32x16_bf16 v[114:129], v[174:177], v[178:181], v[114:129]
	s_waitcnt lgkmcnt(2)
	v_mfma_f32_32x32x16_bf16 v[98:113], v[174:177], v[186:189], v[98:113]
	s_waitcnt lgkmcnt(1)
	v_mfma_f32_32x32x16_bf16 v[82:97], v[174:177], v[190:193], v[82:97]
	s_waitcnt lgkmcnt(0)
	v_mfma_f32_32x32x16_bf16 v[66:81], v[174:177], v[194:197], v[66:81]
	v_mfma_f32_32x32x16_bf16 v[50:65], v[182:185], v[178:181], v[50:65]
	v_mfma_f32_32x32x16_bf16 v[34:49], v[182:185], v[186:189], v[34:49]
	global_load_dwordx4 v[174:177], v[144:145], off offset:640
	global_load_dwordx4 v[178:181], v[146:147], off offset:640
	global_load_dwordx4 v[186:189], v[130:131], off offset:672
	global_load_dwordx4 v[198:201], v[136:137], off offset:640
	global_load_dwordx4 v[202:205], v[132:133], off offset:672
	global_load_dwordx4 v[214:217], v[140:141], off offset:640
	global_load_dwordx4 v[218:221], v[134:135], off offset:672
	v_mfma_f32_32x32x16_bf16 v[18:33], v[182:185], v[190:193], v[18:33]
	global_load_dwordx4 v[190:193], v[142:143], off offset:640
	s_waitcnt vmcnt(0) lgkmcnt(0)
	ds_write_b128 v157, v[174:177]
	ds_write_b128 v158, v[178:181]
	ds_write_b128 v160, v[186:189]
	ds_write_b128 v162, v[198:201]
	ds_write_b128 v163, v[202:205]
	ds_write_b128 v165, v[214:217]
	ds_write_b128 v166, v[218:221]
	ds_write_b128 v168, v[190:193]
	v_mfma_f32_32x32x16_bf16 v[2:17], v[182:185], v[194:197], v[2:17]
	s_waitcnt lgkmcnt(0)
	s_barrier
; #define MFMA32(a, b, c) __builtin_amdgcn_mfma_f32_32x32x16_bf16((a), (b), (c), 0, 0, 0)
; template <class Epi>
; DI void gemm_tile_s(const bf16_t* __restrict__ A, int lda, const bf16_t* __restrict__ Bt, int ldb, int K, int m0, int n0, char* smem, const Epi& epi) {
;     ...
;   for (int kt = 0; kt < nk; ++kt) {
;     const char* cA = sA + (kt & 1) * 65536; const char* cB = sB + (kt & 1) * 65536;
;     const bool more = (kt + 1 < nk);
;     if (more) { ag += 64; bg += 64;
; #pragma unroll
;       for (int i = 0; i < 4; ++i) { ra[i] = *(const u32x4*)(ag + (size_t)i * 64 * lda); rb[i] = *(const u32x4*)(bg + (size_t)i * 64 * ldb); } }
; #pragma unroll
;     for (int s = 0; s < 4; ++s) {
;       const int co = (((2 * s + h) ^ swz) << 4);
;       bf16x8 fa[2], fb[4];
; #pragma unroll
;       for (int ni = 0; ni < 2; ++ni) fa[ni] = *(const bf16x8*)(cB + aoff + ni * 4096 + co);
; #pragma unroll
;       for (int mi = 0; mi < 4; ++mi) fb[mi] = *(const bf16x8*)(cA + boff + mi * 4096 + co);
; #pragma unroll
;       for (int ni = 0; ni < 2; ++ni)
; #pragma unroll
;         for (int mi = 0; mi < 4; ++mi) acc[ni][mi] = MFMA32(fa[ni], fb[mi], acc[ni][mi]);
;     }
;     if (more) { char* dA = sA + ((kt + 1) & 1) * 65536; char* dB = sB + ((kt + 1) & 1) * 65536;
; #pragma unroll
;       for (int i = 0; i < 4; ++i) { *(u32x4*)(dA + wofs + i * 8192) = ra[i]; *(u32x4*)(dB + wofs + i * 8192) = rb[i]; } }
;     __syncthreads();
	ds_read_b128 v[174:177], v169
	ds_read_b128 v[178:181], v159
	ds_read_b128 v[182:185], v169 offset:4096
	ds_read_b128 v[186:189], v159 offset:4096
	ds_read_b128 v[190:193], v159 offset:8192
	ds_read_b128 v[194:197], v159 offset:12288
	s_waitcnt lgkmcnt(4)
	v_mfma_f32_32x32x16_bf16 v[114:129], v[174:177], v[178:181], v[114:129]
	s_waitcnt lgkmcnt(2)
	v_mfma_f32_32x32x16_bf16 v[98:113], v[174:177], v[186:189], v[98:113]
	s_waitcnt lgkmcnt(1)
	v_mfma_f32_32x32x16_bf16 v[82:97], v[174:177], v[190:193], v[82:97]
	s_waitcnt lgkmcnt(0)
	v_mfma_f32_32x32x16_bf16 v[66:81], v[174:177], v[194:197], v[66:81]
	v_mfma_f32_32x32x16_bf16 v[50:65], v[182:185], v[178:181], v[50:65]
	v_mfma_f32_32x32x16_bf16 v[34:49], v[182:185], v[186:189], v[34:49]
	v_mfma_f32_32x32x16_bf16 v[18:33], v[182:185], v[190:193], v[18:33]
	v_mfma_f32_32x32x16_bf16 v[2:17], v[182:185], v[194:197], v[2:17]
	ds_read_b128 v[174:177], v170
	ds_read_b128 v[178:181], v161
	ds_read_b128 v[182:185], v170 offset:4096
	ds_read_b128 v[186:189], v161 offset:4096
	ds_read_b128 v[190:193], v161 offset:8192
	ds_read_b128 v[158:161], v161 offset:12288
	s_waitcnt lgkmcnt(4)
	v_mfma_f32_32x32x16_bf16 v[114:129], v[174:177], v[178:181], v[114:129]
	s_waitcnt lgkmcnt(2)
	v_mfma_f32_32x32x16_bf16 v[98:113], v[174:177], v[186:189], v[98:113]
	s_waitcnt lgkmcnt(1)
	v_mfma_f32_32x32x16_bf16 v[82:97], v[174:177], v[190:193], v[82:97]
	s_waitcnt lgkmcnt(0)
	v_mfma_f32_32x32x16_bf16 v[66:81], v[174:177], v[158:161], v[66:81]
	v_mfma_f32_32x32x16_bf16 v[50:65], v[182:185], v[178:181], v[50:65]
	v_mfma_f32_32x32x16_bf16 v[34:49], v[182:185], v[186:189], v[34:49]
	v_mfma_f32_32x32x16_bf16 v[18:33], v[182:185], v[190:193], v[18:33]
	v_mfma_f32_32x32x16_bf16 v[2:17], v[182:185], v[158:161], v[2:17]
	ds_read_b128 v[158:161], v171
	ds_read_b128 v[174:177], v164
	ds_read_b128 v[168:171], v171 offset:4096
	ds_read_b128 v[178:181], v164 offset:4096
	ds_read_b128 v[182:185], v164 offset:8192
	ds_read_b128 v[162:165], v164 offset:12288
	s_waitcnt lgkmcnt(4)
	v_mfma_f32_32x32x16_bf16 v[114:129], v[158:161], v[174:177], v[114:129]
	s_waitcnt lgkmcnt(2)
	v_mfma_f32_32x32x16_bf16 v[98:113], v[158:161], v[178:181], v[98:113]
	s_waitcnt lgkmcnt(1)
	v_mfma_f32_32x32x16_bf16 v[82:97], v[158:161], v[182:185], v[82:97]
	s_waitcnt lgkmcnt(0)
	v_mfma_f32_32x32x16_bf16 v[66:81], v[158:161], v[162:165], v[66:81]
	v_mfma_f32_32x32x16_bf16 v[50:65], v[168:171], v[174:177], v[50:65]
	v_mfma_f32_32x32x16_bf16 v[34:49], v[168:171], v[178:181], v[34:49]
	v_mfma_f32_32x32x16_bf16 v[18:33], v[168:171], v[182:185], v[18:33]
	v_mfma_f32_32x32x16_bf16 v[2:17], v[168:171], v[162:165], v[2:17]
	ds_read_b128 v[158:161], v172
	ds_read_b128 v[162:165], v167
	ds_read_b128 v[168:171], v172 offset:4096
	ds_read_b128 v[172:175], v167 offset:4096
	ds_read_b128 v[176:179], v167 offset:8192
	ds_read_b128 v[180:183], v167 offset:12288
	s_waitcnt lgkmcnt(4)
	v_mfma_f32_32x32x16_bf16 v[114:129], v[158:161], v[162:165], v[114:129]
	s_waitcnt lgkmcnt(2)
	v_mfma_f32_32x32x16_bf16 v[98:113], v[158:161], v[172:175], v[98:113]
	s_waitcnt lgkmcnt(1)
	v_mfma_f32_32x32x16_bf16 v[82:97], v[158:161], v[176:179], v[82:97]
	s_waitcnt lgkmcnt(0)
	v_mfma_f32_32x32x16_bf16 v[66:81], v[158:161], v[180:183], v[66:81]
	v_mfma_f32_32x32x16_bf16 v[50:65], v[168:171], v[162:165], v[50:65]
	v_mfma_f32_32x32x16_bf16 v[34:49], v[168:171], v[172:175], v[34:49]
	global_load_dwordx4 v[158:161], v[144:145], off offset:768
	s_nop 0
	global_load_dwordx4 v[144:147], v[146:147], off offset:768
	s_nop 0
	global_load_dwordx4 v[162:165], v[130:131], off offset:800
	global_load_dwordx4 v[172:175], v[136:137], off offset:768
	s_nop 0
	global_load_dwordx4 v[130:133], v[132:133], off offset:800
	s_nop 0
	global_load_dwordx4 v[184:187], v[140:141], off offset:768
	s_nop 0
	global_load_dwordx4 v[134:137], v[134:135], off offset:800
	s_nop 0
	global_load_dwordx4 v[140:143], v[142:143], off offset:768
	s_waitcnt vmcnt(0) lgkmcnt(0)
	ds_write_b128 v151, v[158:161]
	ds_write_b128 v151, v[144:147] offset:32768
	ds_write_b128 v151, v[162:165] offset:8192
	ds_write_b128 v151, v[172:175] offset:40960
	ds_write_b128 v151, v[130:133] offset:16384
	ds_write_b128 v151, v[184:187] offset:49152
	ds_write_b128 v151, v[134:137] offset:24576
	ds_write_b128 v151, v[140:143] offset:57344
	s_waitcnt lgkmcnt(0)
	s_barrier
	ds_read_b128 v[140:143], v149 offset:32768
	ds_read_b128 v[214:217], v150
	ds_read_b128 v[130:133], v149 offset:36864
	ds_read_b128 v[218:221], v150 offset:4096
	s_waitcnt lgkmcnt(2)
	v_mfma_f32_32x32x16_bf16 v[114:129], v[140:143], v[214:217], v[114:129]
	ds_read_b128 v[198:201], v150 offset:8192
	ds_read_b128 v[134:137], v150 offset:12288
	ds_read_b128 v[202:205], v152 offset:32768
	ds_read_b128 v[186:189], v148
	s_waitcnt lgkmcnt(0)
	v_mfma_f32_32x32x16_bf16 v[114:129], v[202:205], v[186:189], v[114:129]
	v_mfma_f32_32x32x16_bf16 v[18:33], v[168:171], v[176:179], v[18:33]
	v_mfma_f32_32x32x16_bf16 v[98:113], v[140:143], v[218:221], v[98:113]
	v_mfma_f32_32x32x16_bf16 v[82:97], v[140:143], v[198:201], v[82:97]
	v_mfma_f32_32x32x16_bf16 v[66:81], v[140:143], v[134:137], v[66:81]
	ds_read_b128 v[138:141], v152 offset:36864
	ds_read_b128 v[174:177], v148 offset:4096
	ds_read_b128 v[222:225], v153 offset:32768
	v_mfma_f32_32x32x16_bf16 v[2:17], v[168:171], v[180:183], v[2:17]
	ds_read_b128 v[170:173], v148 offset:8192
	ds_read_b128 v[158:161], v148 offset:12288
	ds_read_b128 v[194:197], v154
	ds_read_b128 v[142:145], v153 offset:36864
	ds_read_b128 v[182:185], v154 offset:4096
	ds_read_b128 v[162:165], v154 offset:8192
	ds_read_b128 v[146:149], v154 offset:12288
	ds_read_b128 v[226:229], v156 offset:32768
	ds_read_b128 v[150:153], v156 offset:36864
	ds_read_b128 v[190:193], v155
	ds_read_b128 v[178:181], v155 offset:4096
	ds_read_b128 v[166:169], v155 offset:8192
	ds_read_b128 v[154:157], v155 offset:12288
	s_waitcnt lgkmcnt(0)
	s_barrier
; template <class Epi>
; DI void gemm_tile_s(const bf16_t* __restrict__ A, int lda, const bf16_t* __restrict__ Bt, int ldb, int K, int m0, int n0, char* smem, const Epi& epi) {
;     ...
; #pragma unroll
;   for (int ni = 0; ni < 2; ++ni)
; #pragma unroll
;     for (int mi = 0; mi < 4; ++mi)
; #pragma unroll
;       for (int rg = 0; rg < 4; ++rg) {
;         const int m = m0 + 128 * wm + 32 * mi + lq, n = n0 + 64 * wn + 32 * ni + 8 * rg + 4 * h;
;         epi(m, n, acc[ni][mi][4 * rg], acc[ni][mi][4 * rg + 1], acc[ni][mi][4 * rg + 2], acc[ni][mi][4 * rg + 3]);
;       }
	ds_read_b32 v0, v235
	v_mfma_f32_32x32x16_bf16 v[114:129], v[222:225], v[194:197], v[114:129]
	v_mfma_f32_32x32x16_bf16 v[114:129], v[226:229], v[190:193], v[114:129]
	v_mfma_f32_32x32x16_bf16 v[98:113], v[202:205], v[174:177], v[98:113]
	s_waitcnt lgkmcnt(0)
	s_nop 9
	v_mul_f32_e64 v230, v114, v0
	v_mul_f32_e64 v231, v115, v0
	v_mad_i64_i32 v[114:115], s[0:1], v234, s3, v[210:211]
	v_mul_f32_e64 v232, v116, v0
	v_mul_f32_e64 v233, v117, v0
	v_lshl_add_u64 v[114:115], v[114:115], 0, v[212:213]
	global_store_dwordx4 v[114:115], v[230:233], off
	ds_read_b32 v0, v235
	v_mfma_f32_32x32x16_bf16 v[98:113], v[222:225], v[182:185], v[98:113]
	s_waitcnt lgkmcnt(0)
	v_mul_f32_e64 v116, v118, v0
	v_mul_f32_e64 v117, v119, v0
	v_mul_f32_e64 v118, v120, v0
	v_mul_f32_e64 v119, v121, v0
	global_store_dwordx4 v[114:115], v[116:119], off offset:32
	ds_read_b32 v0, v235
	v_or_b32_e32 v120, 32, v234
	v_mfma_f32_32x32x16_bf16 v[98:113], v[226:229], v[178:181], v[98:113]
	s_waitcnt lgkmcnt(0)
	v_mul_f32_e64 v116, v122, v0
	v_mul_f32_e64 v117, v123, v0
	v_mul_f32_e64 v118, v124, v0
	v_mul_f32_e64 v119, v125, v0
	global_store_dwordx4 v[114:115], v[116:119], off offset:64
	ds_read_b32 v0, v235
	v_mfma_f32_32x32x16_bf16 v[82:97], v[202:205], v[170:173], v[82:97]
	s_waitcnt lgkmcnt(0)
	v_mul_f32_e64 v116, v126, v0
	v_mul_f32_e64 v117, v127, v0
	v_mul_f32_e64 v118, v128, v0
	v_mul_f32_e64 v119, v129, v0
	v_subrev_u32_e32 v0, s2, v120
	global_store_dwordx4 v[114:115], v[116:119], off offset:96
	v_lshl_add_u32 v121, v0, 2, v240
	ds_read_b32 v0, v121
	v_mfma_f32_32x32x16_bf16 v[82:97], v[222:225], v[162:165], v[82:97]
	s_waitcnt lgkmcnt(0)
	v_mul_f32_e64 v116, v98, v0
	v_mul_f32_e64 v117, v99, v0
	v_mad_i64_i32 v[98:99], s[0:1], v120, s3, v[210:211]
	v_mul_f32_e64 v118, v100, v0
	v_mul_f32_e64 v119, v101, v0
	v_lshl_add_u64 v[98:99], v[98:99], 0, v[212:213]
	global_store_dwordx4 v[98:99], v[116:119], off
	ds_read_b32 v0, v121
	v_mfma_f32_32x32x16_bf16 v[82:97], v[226:229], v[166:169], v[82:97]
	s_waitcnt lgkmcnt(0)
	v_mul_f32_e64 v100, v102, v0
	v_mul_f32_e64 v101, v103, v0
	v_mul_f32_e64 v102, v104, v0
	v_mul_f32_e64 v103, v105, v0
	global_store_dwordx4 v[98:99], v[100:103], off offset:32
	ds_read_b32 v0, v121
	v_or_b32_e32 v104, 64, v234
	v_mfma_f32_32x32x16_bf16 v[66:81], v[202:205], v[158:161], v[66:81]
	s_waitcnt lgkmcnt(0)
	v_mul_f32_e64 v100, v106, v0
	v_mul_f32_e64 v101, v107, v0
	v_mul_f32_e64 v102, v108, v0
	v_mul_f32_e64 v103, v109, v0
	global_store_dwordx4 v[98:99], v[100:103], off offset:64
	ds_read_b32 v0, v121
	v_mfma_f32_32x32x16_bf16 v[66:81], v[222:225], v[146:149], v[66:81]
	s_waitcnt lgkmcnt(0)
	v_mul_f32_e64 v100, v110, v0
	v_mul_f32_e64 v101, v111, v0
	v_mul_f32_e64 v102, v112, v0
	v_mul_f32_e64 v103, v113, v0
	v_subrev_u32_e32 v0, s2, v104
	global_store_dwordx4 v[98:99], v[100:103], off offset:96
	v_lshl_add_u32 v105, v0, 2, v240
	ds_read_b32 v0, v105
	v_mfma_f32_32x32x16_bf16 v[66:81], v[226:229], v[154:157], v[66:81]
	s_waitcnt lgkmcnt(0)
	v_mul_f32_e64 v100, v82, v0
	v_mul_f32_e64 v101, v83, v0
	v_mad_i64_i32 v[82:83], s[0:1], v104, s3, v[210:211]
	v_mul_f32_e64 v102, v84, v0
	v_mul_f32_e64 v103, v85, v0
	v_lshl_add_u64 v[82:83], v[82:83], 0, v[212:213]
	global_store_dwordx4 v[82:83], v[100:103], off
	ds_read_b32 v0, v105
	v_mfma_f32_32x32x16_bf16 v[50:65], v[130:133], v[214:217], v[50:65]
	s_waitcnt lgkmcnt(0)
	v_mul_f32_e64 v84, v86, v0
	v_mul_f32_e64 v85, v87, v0
	v_mul_f32_e64 v86, v88, v0
	v_mul_f32_e64 v87, v89, v0
	global_store_dwordx4 v[82:83], v[84:87], off offset:32
	ds_read_b32 v0, v105
	v_or_b32_e32 v88, 0x60, v234
	v_mfma_f32_32x32x16_bf16 v[50:65], v[138:141], v[186:189], v[50:65]
	s_waitcnt lgkmcnt(0)
	v_mul_f32_e64 v84, v90, v0
	v_mul_f32_e64 v85, v91, v0
	v_mul_f32_e64 v86, v92, v0
	v_mul_f32_e64 v87, v93, v0
	global_store_dwordx4 v[82:83], v[84:87], off offset:64
	ds_read_b32 v0, v105
	v_mfma_f32_32x32x16_bf16 v[50:65], v[142:145], v[194:197], v[50:65]
	s_waitcnt lgkmcnt(0)
	v_mul_f32_e64 v84, v94, v0
	v_mul_f32_e64 v85, v95, v0
	v_mul_f32_e64 v86, v96, v0
	v_mul_f32_e64 v87, v97, v0
	v_subrev_u32_e32 v0, s2, v88
	global_store_dwordx4 v[82:83], v[84:87], off offset:96
	v_lshl_add_u32 v89, v0, 2, v240
	ds_read_b32 v0, v89
	v_mfma_f32_32x32x16_bf16 v[50:65], v[150:153], v[190:193], v[50:65]
	s_waitcnt lgkmcnt(0)
	v_mul_f32_e64 v84, v66, v0
	v_mul_f32_e64 v85, v67, v0
	v_mad_i64_i32 v[66:67], s[0:1], v88, s3, v[210:211]
	v_mul_f32_e64 v86, v68, v0
	v_mul_f32_e64 v87, v69, v0
	v_lshl_add_u64 v[66:67], v[66:67], 0, v[212:213]
	global_store_dwordx4 v[66:67], v[84:87], off
	ds_read_b32 v0, v89
	v_mfma_f32_32x32x16_bf16 v[34:49], v[130:133], v[218:221], v[34:49]
	s_waitcnt lgkmcnt(0)
; template <class Epi>
; DI void gemm_tile_s(const bf16_t* __restrict__ A, int lda, const bf16_t* __restrict__ Bt, int ldb, int K, int m0, int n0, char* smem, const Epi& epi) {
;     ...
; #pragma unroll
;   for (int ni = 0; ni < 2; ++ni)
; #pragma unroll
;     for (int mi = 0; mi < 4; ++mi)
; #pragma unroll
;       for (int rg = 0; rg < 4; ++rg) {
;         const int m = m0 + 128 * wm + 32 * mi + lq, n = n0 + 64 * wn + 32 * ni + 8 * rg + 4 * h;
;         epi(m, n, acc[ni][mi][4 * rg], acc[ni][mi][4 * rg + 1], acc[ni][mi][4 * rg + 2], acc[ni][mi][4 * rg + 3]);
;       }
	v_mul_f32_e64 v68, v70, v0
	v_mul_f32_e64 v69, v71, v0
	v_mul_f32_e64 v70, v72, v0
	v_mul_f32_e64 v71, v73, v0
	global_store_dwordx4 v[66:67], v[68:71], off offset:32
	ds_read_b32 v0, v89
	v_mfma_f32_32x32x16_bf16 v[34:49], v[138:141], v[174:177], v[34:49]
	s_waitcnt lgkmcnt(0)
	v_mul_f32_e64 v68, v74, v0
	v_mul_f32_e64 v69, v75, v0
	v_mul_f32_e64 v70, v76, v0
	v_mul_f32_e64 v71, v77, v0
	global_store_dwordx4 v[66:67], v[68:71], off offset:64
	ds_read_b32 v0, v89
	v_mfma_f32_32x32x16_bf16 v[34:49], v[142:145], v[182:185], v[34:49]
	s_waitcnt lgkmcnt(0)
	v_mul_f32_e64 v68, v78, v0
	v_mul_f32_e64 v69, v79, v0
	v_mul_f32_e64 v70, v80, v0
	v_mul_f32_e64 v71, v81, v0
	global_store_dwordx4 v[66:67], v[68:71], off offset:96
	ds_read_b32 v0, v235
	v_mfma_f32_32x32x16_bf16 v[34:49], v[150:153], v[178:181], v[34:49]
	s_waitcnt lgkmcnt(0)
	v_mul_f32_e64 v50, v50, v0
	v_mul_f32_e64 v51, v51, v0
	v_mul_f32_e64 v52, v52, v0
	v_mul_f32_e64 v53, v53, v0
	global_store_dwordx4 v[114:115], v[50:53], off offset:128
	ds_read_b32 v0, v235
	v_mfma_f32_32x32x16_bf16 v[18:33], v[130:133], v[198:201], v[18:33]
	s_waitcnt lgkmcnt(0)
	v_mul_f32_e64 v50, v54, v0
	v_mul_f32_e64 v51, v55, v0
	v_mul_f32_e64 v52, v56, v0
	v_mul_f32_e64 v53, v57, v0
	global_store_dwordx4 v[114:115], v[50:53], off offset:160
	ds_read_b32 v0, v235
	v_mfma_f32_32x32x16_bf16 v[18:33], v[138:141], v[170:173], v[18:33]
	s_waitcnt lgkmcnt(0)
	v_mul_f32_e64 v50, v58, v0
	v_mul_f32_e64 v51, v59, v0
	v_mul_f32_e64 v52, v60, v0
	v_mul_f32_e64 v53, v61, v0
	global_store_dwordx4 v[114:115], v[50:53], off offset:192
	ds_read_b32 v0, v235
	v_mfma_f32_32x32x16_bf16 v[18:33], v[142:145], v[162:165], v[18:33]
	s_waitcnt lgkmcnt(0)
	v_mul_f32_e64 v50, v62, v0
	v_mul_f32_e64 v51, v63, v0
	v_mul_f32_e64 v52, v64, v0
	v_mul_f32_e64 v53, v65, v0
	global_store_dwordx4 v[114:115], v[50:53], off offset:224
	ds_read_b32 v0, v121
	v_mfma_f32_32x32x16_bf16 v[18:33], v[150:153], v[166:169], v[18:33]
	s_waitcnt lgkmcnt(0)
	v_mul_f32_e64 v34, v34, v0
	v_mul_f32_e64 v35, v35, v0
	v_mul_f32_e64 v36, v36, v0
	v_mul_f32_e64 v37, v37, v0
	global_store_dwordx4 v[98:99], v[34:37], off offset:128
	ds_read_b32 v0, v121
	v_mfma_f32_32x32x16_bf16 v[2:17], v[130:133], v[134:137], v[2:17]
	s_waitcnt lgkmcnt(0)
	v_mul_f32_e64 v34, v38, v0
	v_mul_f32_e64 v35, v39, v0
	v_mul_f32_e64 v36, v40, v0
	v_mul_f32_e64 v37, v41, v0
	global_store_dwordx4 v[98:99], v[34:37], off offset:160
	ds_read_b32 v0, v121
	v_mfma_f32_32x32x16_bf16 v[2:17], v[138:141], v[158:161], v[2:17]
	s_waitcnt lgkmcnt(0)
	v_mul_f32_e64 v34, v42, v0
	v_mul_f32_e64 v35, v43, v0
	v_mul_f32_e64 v36, v44, v0
	v_mul_f32_e64 v37, v45, v0
	global_store_dwordx4 v[98:99], v[34:37], off offset:192
	ds_read_b32 v0, v121
	v_mfma_f32_32x32x16_bf16 v[2:17], v[142:145], v[146:149], v[2:17]
	s_waitcnt lgkmcnt(0)
	v_mul_f32_e64 v34, v46, v0
	v_mul_f32_e64 v35, v47, v0
	v_mul_f32_e64 v36, v48, v0
	v_mul_f32_e64 v37, v49, v0
	global_store_dwordx4 v[98:99], v[34:37], off offset:224
	ds_read_b32 v0, v105
	v_mfma_f32_32x32x16_bf16 v[2:17], v[150:153], v[154:157], v[2:17]
	s_waitcnt lgkmcnt(0)
	v_mul_f32_e64 v18, v18, v0
	v_mul_f32_e64 v19, v19, v0
	v_mul_f32_e64 v20, v20, v0
	v_mul_f32_e64 v21, v21, v0
	global_store_dwordx4 v[82:83], v[18:21], off offset:128
	ds_read_b32 v0, v105
	s_waitcnt lgkmcnt(0)
	v_pk_mul_f32 v[18:19], v[22:23], v[0:1] op_sel_hi:[1,0]
	v_pk_mul_f32 v[20:21], v[24:25], v[0:1] op_sel_hi:[1,0]
	global_store_dwordx4 v[82:83], v[18:21], off offset:160
	ds_read_b32 v0, v105
	s_waitcnt lgkmcnt(0)
	v_pk_mul_f32 v[18:19], v[26:27], v[0:1] op_sel_hi:[1,0]
	v_pk_mul_f32 v[20:21], v[28:29], v[0:1] op_sel_hi:[1,0]
	global_store_dwordx4 v[82:83], v[18:21], off offset:192
	ds_read_b32 v0, v105
	s_waitcnt lgkmcnt(0)
	v_pk_mul_f32 v[18:19], v[30:31], v[0:1] op_sel_hi:[1,0]
	v_pk_mul_f32 v[20:21], v[32:33], v[0:1] op_sel_hi:[1,0]
	global_store_dwordx4 v[82:83], v[18:21], off offset:224
	ds_read_b32 v0, v89
	s_waitcnt lgkmcnt(0)
	v_pk_mul_f32 v[2:3], v[2:3], v[0:1] op_sel_hi:[1,0]
	v_pk_mul_f32 v[4:5], v[4:5], v[0:1] op_sel_hi:[1,0]
	global_store_dwordx4 v[66:67], v[2:5], off offset:128
	ds_read_b32 v0, v89
	s_waitcnt lgkmcnt(0)
	v_pk_mul_f32 v[2:3], v[6:7], v[0:1] op_sel_hi:[1,0]
	v_pk_mul_f32 v[4:5], v[8:9], v[0:1] op_sel_hi:[1,0]
	global_store_dwordx4 v[66:67], v[2:5], off offset:160
	ds_read_b32 v0, v89
	s_waitcnt lgkmcnt(0)
	v_pk_mul_f32 v[2:3], v[10:11], v[0:1] op_sel_hi:[1,0]
	v_pk_mul_f32 v[4:5], v[12:13], v[0:1] op_sel_hi:[1,0]
	global_store_dwordx4 v[66:67], v[2:5], off offset:192
	ds_read_b32 v0, v89
	s_waitcnt lgkmcnt(0)
	v_pk_mul_f32 v[2:3], v[14:15], v[0:1] op_sel_hi:[1,0]
	v_pk_mul_f32 v[4:5], v[16:17], v[0:1] op_sel_hi:[1,0]
	global_store_dwordx4 v[66:67], v[2:5], off offset:224
	s_waitcnt lgkmcnt(0)
	s_barrier

; DI void unpack8(const u32x4& v, float* f) { f[0] = bflo(v.x); f[1] = bfhi(v.x); f[2] = bflo(v.y); f[3] = bfhi(v.y); f[4] = bflo(v.z); f[5] = bfhi(v.z); f[6] = bflo(v.w); f[7] = bfhi(v.w); }
; DI int opaque_tid() { int t = threadIdx.x; asm volatile("" : "+v"(t)); return t; }
; DI void mla_kv_tile(const Params& P, int pm, int pn, char* smem) {
;   const bf16_t* proj = (const bf16_t*)(P.ws + OFF_PROJ); const int tid = opaque_tid(), m0 = pm * 256; float* rs = (float*)(smem + 131072);
;   { const int row = tid >> 1, half = tid & 1; const bf16_t* p = proj + (size_t)(m0 + row) * DINP + C_BCKV + half * 64; float ss = 0.f;
; #pragma unroll
;     for (int i = 0; i < 8; ++i) { const u32x4 v = *(const u32x4*)(p + i * 8); float f[8]; unpack8(v, f);
; #pragma unroll
;       for (int e = 0; e < 8; ++e) ss += f[e] * f[e]; }
;     ss += __shfl_xor(ss, 1); if (half == 0) rs[row] = rsqrtf(ss * (1.f / 128.f) + EPS); }
.LBB0_280:
	global_load_dwordx2 v[2:3], v1, s[40:41] offset:1224
	s_lshl_b32 s0, s4, 6
	v_mov_b32_e32 v145, v206
	s_and_b32 s5, s0, 0x7fffff00
	s_addk_i32 s5, 0xd000
	v_ashrrev_i32_e32 v6, 1, v145
	v_and_b32_e32 v7, 1, v145
	v_add_u32_e32 v0, s5, v6
	s_waitcnt vmcnt(0)
	v_lshl_add_u64 v[130:131], v[2:3], 0, s[30:31]
	v_mad_i64_i32 v[4:5], s[0:1], v0, s81, v[130:131]
	v_lshlrev_b32_e32 v0, 7, v7
	v_lshl_add_u64 v[8:9], v[4:5], 0, v[0:1]
	s_mov_b64 s[0:1], 0x23a0
	v_lshl_add_u64 v[4:5], v[8:9], 0, s[0:1]
	v_add_co_u32_e32 v8, vcc, 0x2000, v8
	s_nop 1
	v_addc_co_u32_e32 v9, vcc, 0, v9, vcc
	global_load_dwordx4 v[8:11], v[8:9], off offset:928
	s_waitcnt vmcnt(0) lgkmcnt(0)
	v_and_b32_e32 v0, 0xffff0000, v8
	v_lshlrev_b32_e32 v12, 16, v8
	v_mul_f32_e32 v0, v0, v0
	v_lshlrev_b32_e32 v8, 16, v9
	v_fmac_f32_e32 v0, v12, v12
	v_and_b32_e32 v9, 0xffff0000, v9
	v_fmac_f32_e32 v0, v8, v8
	v_lshlrev_b32_e32 v13, 16, v10
	v_fmac_f32_e32 v0, v9, v9
	v_and_b32_e32 v10, 0xffff0000, v10
	v_fmac_f32_e32 v0, v13, v13
	v_lshlrev_b32_e32 v14, 16, v11
	v_fmac_f32_e32 v0, v10, v10
	v_and_b32_e32 v11, 0xffff0000, v11
	v_fmac_f32_e32 v0, v14, v14
	v_fmac_f32_e32 v0, v11, v11
	global_load_dwordx4 v[8:11], v[4:5], off offset:16
	s_waitcnt vmcnt(0) lgkmcnt(0)
	v_lshlrev_b32_e32 v12, 16, v8
	v_and_b32_e32 v8, 0xffff0000, v8
	v_fmac_f32_e32 v0, v12, v12
	v_lshlrev_b32_e32 v13, 16, v9
	v_fmac_f32_e32 v0, v8, v8
	v_and_b32_e32 v9, 0xffff0000, v9
	v_fmac_f32_e32 v0, v13, v13
	v_lshlrev_b32_e32 v14, 16, v10
	v_fmac_f32_e32 v0, v9, v9
	v_and_b32_e32 v10, 0xffff0000, v10
	v_fmac_f32_e32 v0, v14, v14
	v_lshlrev_b32_e32 v15, 16, v11
	v_fmac_f32_e32 v0, v10, v10
	v_and_b32_e32 v11, 0xffff0000, v11
	v_fmac_f32_e32 v0, v15, v15
	v_fmac_f32_e32 v0, v11, v11
	global_load_dwordx4 v[8:11], v[4:5], off offset:32
	s_waitcnt vmcnt(0) lgkmcnt(0)
	v_lshlrev_b32_e32 v12, 16, v8
	v_and_b32_e32 v8, 0xffff0000, v8
	v_fmac_f32_e32 v0, v12, v12
	v_lshlrev_b32_e32 v13, 16, v9
	v_fmac_f32_e32 v0, v8, v8
	v_and_b32_e32 v9, 0xffff0000, v9
	v_fmac_f32_e32 v0, v13, v13
	v_lshlrev_b32_e32 v14, 16, v10
	v_fmac_f32_e32 v0, v9, v9
	v_and_b32_e32 v10, 0xffff0000, v10
	v_fmac_f32_e32 v0, v14, v14
	v_lshlrev_b32_e32 v15, 16, v11
	v_fmac_f32_e32 v0, v10, v10
	v_and_b32_e32 v11, 0xffff0000, v11
	v_fmac_f32_e32 v0, v15, v15
	v_fmac_f32_e32 v0, v11, v11
	global_load_dwordx4 v[8:11], v[4:5], off offset:48
	s_waitcnt vmcnt(0) lgkmcnt(0)
	v_lshlrev_b32_e32 v12, 16, v8
	v_and_b32_e32 v8, 0xffff0000, v8
	v_fmac_f32_e32 v0, v12, v12
	v_lshlrev_b32_e32 v13, 16, v9
	v_fmac_f32_e32 v0, v8, v8
	v_and_b32_e32 v9, 0xffff0000, v9
	v_fmac_f32_e32 v0, v13, v13
	v_lshlrev_b32_e32 v14, 16, v10
	v_fmac_f32_e32 v0, v9, v9
	v_and_b32_e32 v10, 0xffff0000, v10
	v_fmac_f32_e32 v0, v14, v14
	v_lshlrev_b32_e32 v15, 16, v11
	v_fmac_f32_e32 v0, v10, v10
	v_and_b32_e32 v11, 0xffff0000, v11
	v_fmac_f32_e32 v0, v15, v15
	v_fmac_f32_e32 v0, v11, v11
	global_load_dwordx4 v[8:11], v[4:5], off offset:64
	s_waitcnt vmcnt(0) lgkmcnt(0)
	v_lshlrev_b32_e32 v12, 16, v8
	v_and_b32_e32 v8, 0xffff0000, v8
	v_fmac_f32_e32 v0, v12, v12
	v_lshlrev_b32_e32 v13, 16, v9
	v_fmac_f32_e32 v0, v8, v8
	v_and_b32_e32 v9, 0xffff0000, v9
	v_fmac_f32_e32 v0, v13, v13
	v_lshlrev_b32_e32 v14, 16, v10
	v_fmac_f32_e32 v0, v9, v9
	v_and_b32_e32 v10, 0xffff0000, v10
	v_fmac_f32_e32 v0, v14, v14
	v_lshlrev_b32_e32 v15, 16, v11
	v_fmac_f32_e32 v0, v10, v10
	v_and_b32_e32 v11, 0xffff0000, v11
	v_fmac_f32_e32 v0, v15, v15
	v_fmac_f32_e32 v0, v11, v11
	global_load_dwordx4 v[8:11], v[4:5], off offset:80
	s_waitcnt vmcnt(0) lgkmcnt(0)
	v_lshlrev_b32_e32 v12, 16, v8
	v_and_b32_e32 v8, 0xffff0000, v8
	v_fmac_f32_e32 v0, v12, v12
	v_lshlrev_b32_e32 v13, 16, v9
	v_fmac_f32_e32 v0, v8, v8
	v_and_b32_e32 v9, 0xffff0000, v9
	v_fmac_f32_e32 v0, v13, v13
	v_lshlrev_b32_e32 v14, 16, v10
	v_fmac_f32_e32 v0, v9, v9
	v_and_b32_e32 v10, 0xffff0000, v10
	v_fmac_f32_e32 v0, v14, v14
	v_lshlrev_b32_e32 v15, 16, v11
	v_fmac_f32_e32 v0, v10, v10
	v_and_b32_e32 v11, 0xffff0000, v11
	v_fmac_f32_e32 v0, v15, v15
	v_fmac_f32_e32 v0, v11, v11
	global_load_dwordx4 v[8:11], v[4:5], off offset:96
	s_waitcnt vmcnt(0) lgkmcnt(0)
	v_lshlrev_b32_e32 v12, 16, v8
	v_and_b32_e32 v8, 0xffff0000, v8
	v_fmac_f32_e32 v0, v12, v12
	v_lshlrev_b32_e32 v13, 16, v9
	v_fmac_f32_e32 v0, v8, v8
	v_and_b32_e32 v9, 0xffff0000, v9
	v_fmac_f32_e32 v0, v13, v13
	v_lshlrev_b32_e32 v14, 16, v10
	v_fmac_f32_e32 v0, v9, v9
	v_and_b32_e32 v10, 0xffff0000, v10
	v_fmac_f32_e32 v0, v14, v14
	v_lshlrev_b32_e32 v15, 16, v11
	v_fmac_f32_e32 v0, v10, v10
	v_and_b32_e32 v11, 0xffff0000, v11
	v_fmac_f32_e32 v0, v15, v15
	v_fmac_f32_e32 v0, v11, v11
	global_load_dwordx4 v[8:11], v[4:5], off offset:112
	s_waitcnt vmcnt(0) lgkmcnt(0)
	v_lshlrev_b32_e32 v4, 16, v8
	v_and_b32_e32 v5, 0xffff0000, v8
	v_fmac_f32_e32 v0, v4, v4
	v_lshlrev_b32_e32 v8, 16, v9
	v_fmac_f32_e32 v0, v5, v5
	v_and_b32_e32 v9, 0xffff0000, v9
	v_fmac_f32_e32 v0, v8, v8
	v_lshlrev_b32_e32 v12, 16, v10
	v_fmac_f32_e32 v0, v9, v9
	v_and_b32_e32 v5, 64, v239
	v_and_b32_e32 v10, 0xffff0000, v10
	v_fmac_f32_e32 v0, v12, v12
	v_xor_b32_e32 v4, 1, v239
	v_add_u32_e32 v5, 64, v5
	v_lshlrev_b32_e32 v13, 16, v11
	v_fmac_f32_e32 v0, v10, v10
	v_cmp_lt_i32_e32 vcc, v4, v5
	v_and_b32_e32 v11, 0xffff0000, v11
	v_fmac_f32_e32 v0, v13, v13
	v_cndmask_b32_e32 v4, v239, v4, vcc
	v_fmac_f32_e32 v0, v11, v11
	v_lshlrev_b32_e32 v4, 2, v4
	ds_bpermute_b32 v4, v4, v0
	v_cmp_eq_u32_e32 vcc, 0, v7
	s_and_saveexec_b64 s[0:1], vcc
	s_cbranch_execz .LBB0_282
	s_waitcnt lgkmcnt(0)
	v_add_f32_e32 v0, v0, v4
	v_fmamk_f32 v0, v0, 0x3c000000, v245
	v_mul_f32_e32 v4, 0x4b800000, v0
	v_cmp_gt_f32_e32 vcc, s84, v0
	s_nop 1
	v_cndmask_b32_e32 v0, v0, v4, vcc
	v_rsq_f32_e32 v0, v0
	s_nop 0
	v_mul_f32_e32 v4, 0x45800000, v0
	v_cndmask_b32_e32 v0, v0, v4, vcc
	v_lshl_add_u32 v4, v6, 2, v240
	ds_write_b32 v4, v0
; #define MFMA32(a, b, c) __builtin_amdgcn_mfma_f32_32x32x16_bf16((a), (b), (c), 0, 0, 0)
; template <class Epi>
; DI void gemm_tile_s(const bf16_t* __restrict__ A, int lda, const bf16_t* __restrict__ Bt, int ldb, int K, int m0, int n0, char* smem, const Epi& epi) {
;     ...
;   const int r0 = tid >> 3, c0 = tid & 7;
;   const bf16_t* ag = A + (size_t)(m0 + r0) * lda + c0 * 8;
;   const bf16_t* bg = Bt + (size_t)(n0 + r0) * ldb + c0 * 8;
;   const int wofs = r0 * 128 + ((c0 ^ ((r0 >> 1) & 7)) << 4);
;   char* sA = smem; char* sB = smem + 32768;
;   u32x4 ra[4], rb[4];
; #pragma unroll
;   for (int i = 0; i < 4; ++i) { ra[i] = *(const u32x4*)(ag + (size_t)i * 64 * lda); rb[i] = *(const u32x4*)(bg + (size_t)i * 64 * ldb); }
; #pragma unroll
;   for (int i = 0; i < 4; ++i) { *(u32x4*)(sA + wofs + i * 8192) = ra[i]; *(u32x4*)(sB + wofs + i * 8192) = rb[i]; }
;   __syncthreads();
;   const int nk = K >> 6, swz = (lane >> 1) & 7;
;   const int aoff = (64 * wn + lq) * 128, boff = (128 * wm + lq) * 128;
;   for (int kt = 0; kt < nk; ++kt) {
;     const char* cA = sA + (kt & 1) * 65536; const char* cB = sB + (kt & 1) * 65536;
;     const bool more = (kt + 1 < nk);
;     if (more) { ag += 64; bg += 64;
; #pragma unroll
;       for (int i = 0; i < 4; ++i) { ra[i] = *(const u32x4*)(ag + (size_t)i * 64 * lda); rb[i] = *(const u32x4*)(bg + (size_t)i * 64 * ldb); } }
; #pragma unroll
;     for (int s = 0; s < 4; ++s) {
;       const int co = (((2 * s + h) ^ swz) << 4);
;       bf16x8 fa[2], fb[4];
; #pragma unroll
;       for (int ni = 0; ni < 2; ++ni) fa[ni] = *(const bf16x8*)(cB + aoff + ni * 4096 + co);
; #pragma unroll
;       for (int mi = 0; mi < 4; ++mi) fb[mi] = *(const bf16x8*)(cA + boff + mi * 4096 + co);
; #pragma unroll
;       for (int ni = 0; ni < 2; ++ni)
; #pragma unroll
;         for (int mi = 0; mi < 4; ++mi) acc[ni][mi] = MFMA32(fa[ni], fb[mi], acc[ni][mi]);
.LBB0_282:
	s_or_b64 exec, exec, s[0:1]
	global_load_dwordx2 v[132:133], v1, s[40:41] offset:1224
	v_mov_b32_e32 v144, v206
	s_and_b32 s8, s4, 3
	v_ashrrev_i32_e32 v34, 3, v144
	v_lshlrev_b32_e32 v35, 4, v144
	v_add_u32_e32 v5, s5, v34
	v_and_b32_e32 v0, 0x70, v35
	v_mad_i64_i32 v[2:3], s[0:1], v5, s81, v[2:3]
	v_lshl_add_u64 v[138:139], v[2:3], 0, v[0:1]
	v_add_co_u32_e32 v2, vcc, s85, v138
	s_mov_b32 s0, 0x1239a000
	s_nop 0
	v_addc_co_u32_e32 v3, vcc, 0, v139, vcc
	v_add_co_u32_e32 v134, vcc, s0, v138
	s_waitcnt lgkmcnt(0)
	v_lshl_add_u32 v4, s8, 8, v34
	v_addc_co_u32_e32 v135, vcc, 0, v139, vcc
	s_mov_b32 s0, 0x1244a000
	v_ashrrev_i32_e32 v5, 31, v4
	v_add_co_u32_e32 v136, vcc, s0, v138
	v_lshlrev_b64 v[18:19], 8, v[4:5]
	s_nop 0
	v_addc_co_u32_e32 v137, vcc, 0, v139, vcc
	s_mov_b32 s0, 0x124fa000
	v_add_co_u32_e32 v140, vcc, s0, v138
	s_mov_b32 s0, 0x62a8000
	s_nop 0
	v_addc_co_u32_e32 v141, vcc, 0, v139, vcc
	global_load_dwordx4 v[2:5], v[2:3], off offset:928
	s_nop 0
	global_load_dwordx4 v[6:9], v[134:135], off offset:928
	global_load_dwordx4 v[10:13], v[136:137], off offset:928
	global_load_dwordx4 v[14:17], v[140:141], off offset:928
	v_bfe_u32 v170, v144, 1, 3
	v_lshlrev_b32_e32 v36, 7, v144
	v_xor_b32_e32 v35, v35, v144
	v_lshlrev_b32_e32 v34, 7, v34
	v_and_b32_e32 v185, 0x6f80, v36
	v_ashrrev_i32_e32 v37, 1, v144
	v_and_b32_e32 v184, 31, v144
	v_and_b32_e32 v186, 0xffffff80, v37
	v_bfe_u32 v189, v144, 5, 1
	s_waitcnt vmcnt(0)
	v_lshl_add_u64 v[18:19], v[132:133], 0, v[18:19]
	v_lshl_add_u64 v[142:143], v[18:19], 0, v[0:1]
	v_add_co_u32_e32 v18, vcc, s0, v142
	s_mov_b32 s0, 0x62ac000
	s_nop 0
	v_addc_co_u32_e32 v19, vcc, 0, v143, vcc
	v_add_co_u32_e32 v174, vcc, s0, v142
	s_mov_b32 s0, 0x62b0000
	s_nop 0
	v_addc_co_u32_e32 v175, vcc, 0, v143, vcc
	v_add_co_u32_e32 v178, vcc, s0, v142
	s_mov_b32 s0, 0x62b4000
	s_nop 0
	v_addc_co_u32_e32 v179, vcc, 0, v143, vcc
	v_add_co_u32_e32 v182, vcc, s0, v142
	v_lshrrev_b32_e32 v0, 5, v144
	s_nop 0
	v_addc_co_u32_e32 v183, vcc, 0, v143, vcc
	global_load_dwordx4 v[18:21], v[18:19], off
	s_nop 0
	global_load_dwordx4 v[22:25], v[174:175], off
	global_load_dwordx4 v[26:29], v[178:179], off
	global_load_dwordx4 v[30:33], v[182:183], off
	v_bitop3_b32 v0, v0, v170, 1 bitop3:0x6c
	s_movk_i32 s0, 0x70
	v_lshlrev_b32_e32 v0, 4, v0
	v_and_or_b32 v187, v35, s0, v34
	v_or_b32_e32 v34, v185, v0
	s_mov_b64 s[0:1], 0x122ea3a0
	v_lshl_add_u64 v[138:139], v[138:139], 0, s[0:1]
	s_mov_b64 s[0:1], 0x62a8000
	v_lshl_add_u64 v[142:143], v[142:143], 0, s[0:1]
	v_readfirstlane_b32 s0, v132
	v_readfirstlane_b32 s1, v133
	s_add_u32 s9, s0, 0xeae8000
	s_movk_i32 s0, 0x7f
	s_addc_u32 s10, s1, 0
	s_waitcnt lgkmcnt(0)
	ds_write_b128 v187, v[2:5]
	ds_write_b128 v187, v[6:9] offset:8192
	ds_write_b128 v187, v[10:13] offset:16384
	ds_write_b128 v187, v[14:17] offset:24576
	s_waitcnt vmcnt(0)
	ds_write_b128 v187, v[18:21] offset:32768
	ds_write_b128 v187, v[22:25] offset:40960
	ds_write_b128 v187, v[26:29] offset:49152
	ds_write_b128 v187, v[30:33] offset:57344
	s_waitcnt lgkmcnt(0)
	s_barrier
	ds_read_b128 v[2:5], v34 offset:32768
	v_or_b32_e32 v6, v186, v184
	v_lshlrev_b32_e32 v188, 7, v6
	v_or_b32_e32 v22, v188, v0
	ds_read_b128 v[6:9], v22
	ds_read_b128 v[10:13], v34 offset:36864
	ds_read_b128 v[14:17], v22 offset:4096
	ds_read_b128 v[18:21], v22 offset:8192
	ds_read_b128 v[146:149], v22 offset:12288
	s_waitcnt lgkmcnt(4)
	v_mfma_f32_32x32x16_bf16 v[114:129], v[2:5], v[6:9], 0
	s_waitcnt lgkmcnt(2)
	v_mfma_f32_32x32x16_bf16 v[98:113], v[2:5], v[14:17], 0
	s_waitcnt lgkmcnt(1)
	v_mfma_f32_32x32x16_bf16 v[82:97], v[2:5], v[18:21], 0
	s_waitcnt lgkmcnt(0)
	v_mfma_f32_32x32x16_bf16 v[66:81], v[2:5], v[146:149], 0
	v_bitop3_b32 v2, v189, v170, 2 bitop3:0x36
	v_lshlrev_b32_e32 v190, 4, v2
	v_or_b32_e32 v154, v185, v190
	v_or_b32_e32 v166, v188, v190
	v_mfma_f32_32x32x16_bf16 v[50:65], v[10:13], v[6:9], 0
	v_mfma_f32_32x32x16_bf16 v[34:49], v[10:13], v[14:17], 0
	v_mfma_f32_32x32x16_bf16 v[18:33], v[10:13], v[18:21], 0
	v_mfma_f32_32x32x16_bf16 v[2:17], v[10:13], v[146:149], 0
	ds_read_b128 v[146:149], v154 offset:32768
	ds_read_b128 v[150:153], v166
	ds_read_b128 v[154:157], v154 offset:36864
	ds_read_b128 v[158:161], v166 offset:4096
	ds_read_b128 v[162:165], v166 offset:8192
	ds_read_b128 v[166:169], v166 offset:12288
	s_waitcnt lgkmcnt(4)
	v_mfma_f32_32x32x16_bf16 v[114:129], v[146:149], v[150:153], v[114:129]
	s_waitcnt lgkmcnt(2)
	v_mfma_f32_32x32x16_bf16 v[98:113], v[146:149], v[158:161], v[98:113]
	s_waitcnt lgkmcnt(1)
	v_mfma_f32_32x32x16_bf16 v[82:97], v[146:149], v[162:165], v[82:97]
	s_waitcnt lgkmcnt(0)
	v_mfma_f32_32x32x16_bf16 v[66:81], v[146:149], v[166:169], v[66:81]
	v_bitop3_b32 v146, v189, v170, 4 bitop3:0x36
	v_lshlrev_b32_e32 v191, 4, v146
	v_mfma_f32_32x32x16_bf16 v[34:49], v[154:157], v[158:161], v[34:49]
	v_or_b32_e32 v158, v185, v191
	ds_read_b128 v[146:149], v158 offset:32768
	v_mfma_f32_32x32x16_bf16 v[50:65], v[154:157], v[150:153], v[50:65]
	v_mfma_f32_32x32x16_bf16 v[18:33], v[154:157], v[162:165], v[18:33]
	v_mfma_f32_32x32x16_bf16 v[2:17], v[154:157], v[166:169], v[2:17]
	v_or_b32_e32 v166, v188, v191
	ds_read_b128 v[150:153], v166
	ds_read_b128 v[154:157], v158 offset:36864
	ds_read_b128 v[158:161], v166 offset:4096
	ds_read_b128 v[162:165], v166 offset:8192
	ds_read_b128 v[166:169], v166 offset:12288
	s_waitcnt lgkmcnt(4)
	v_mfma_f32_32x32x16_bf16 v[114:129], v[146:149], v[150:153], v[114:129]
	s_waitcnt lgkmcnt(2)
	v_mfma_f32_32x32x16_bf16 v[98:113], v[146:149], v[158:161], v[98:113]
	s_waitcnt lgkmcnt(1)
	v_mfma_f32_32x32x16_bf16 v[82:97], v[146:149], v[162:165], v[82:97]
	s_waitcnt lgkmcnt(0)
; #define MFMA32(a, b, c) __builtin_amdgcn_mfma_f32_32x32x16_bf16((a), (b), (c), 0, 0, 0)
; template <class Epi>
; DI void gemm_tile_s(const bf16_t* __restrict__ A, int lda, const bf16_t* __restrict__ Bt, int ldb, int K, int m0, int n0, char* smem, const Epi& epi) {
;     ...
;   for (int kt = 0; kt < nk; ++kt) {
;     const char* cA = sA + (kt & 1) * 65536; const char* cB = sB + (kt & 1) * 65536;
;     const bool more = (kt + 1 < nk);
;     if (more) { ag += 64; bg += 64;
; #pragma unroll
;       for (int i = 0; i < 4; ++i) { ra[i] = *(const u32x4*)(ag + (size_t)i * 64 * lda); rb[i] = *(const u32x4*)(bg + (size_t)i * 64 * ldb); } }
; #pragma unroll
;     for (int s = 0; s < 4; ++s) {
;       const int co = (((2 * s + h) ^ swz) << 4);
;       bf16x8 fa[2], fb[4];
; #pragma unroll
;       for (int ni = 0; ni < 2; ++ni) fa[ni] = *(const bf16x8*)(cB + aoff + ni * 4096 + co);
; #pragma unroll
;       for (int mi = 0; mi < 4; ++mi) fb[mi] = *(const bf16x8*)(cA + boff + mi * 4096 + co);
; #pragma unroll
;       for (int ni = 0; ni < 2; ++ni)
; #pragma unroll
;         for (int mi = 0; mi < 4; ++mi) acc[ni][mi] = MFMA32(fa[ni], fb[mi], acc[ni][mi]);
;     }
;     if (more) { char* dA = sA + ((kt + 1) & 1) * 65536; char* dB = sB + ((kt + 1) & 1) * 65536;
; #pragma unroll
;       for (int i = 0; i < 4; ++i) { *(u32x4*)(dA + wofs + i * 8192) = ra[i]; *(u32x4*)(dB + wofs + i * 8192) = rb[i]; } }
;     __syncthreads();
	v_mfma_f32_32x32x16_bf16 v[66:81], v[146:149], v[166:169], v[66:81]
	v_bitop3_b32 v146, v189, v170, 6 bitop3:0x36
	v_lshlrev_b32_e32 v192, 4, v146
	v_mfma_f32_32x32x16_bf16 v[50:65], v[154:157], v[150:153], v[50:65]
	v_mfma_f32_32x32x16_bf16 v[34:49], v[154:157], v[158:161], v[34:49]
	v_mfma_f32_32x32x16_bf16 v[18:33], v[154:157], v[162:165], v[18:33]
	v_mfma_f32_32x32x16_bf16 v[2:17], v[154:157], v[166:169], v[2:17]
	v_or_b32_e32 v154, v185, v192
	ds_read_b128 v[146:149], v154 offset:32768
	v_or_b32_e32 v166, v188, v192
	ds_read_b128 v[150:153], v166
	ds_read_b128 v[154:157], v154 offset:36864
	ds_read_b128 v[158:161], v166 offset:4096
	ds_read_b128 v[162:165], v166 offset:8192
	ds_read_b128 v[166:169], v166 offset:12288
	s_waitcnt lgkmcnt(4)
	v_mfma_f32_32x32x16_bf16 v[114:129], v[146:149], v[150:153], v[114:129]
	s_waitcnt lgkmcnt(2)
	v_mfma_f32_32x32x16_bf16 v[98:113], v[146:149], v[158:161], v[98:113]
	s_waitcnt lgkmcnt(1)
	v_mfma_f32_32x32x16_bf16 v[82:97], v[146:149], v[162:165], v[82:97]
	s_waitcnt lgkmcnt(0)
	v_mfma_f32_32x32x16_bf16 v[66:81], v[146:149], v[166:169], v[66:81]
	v_mfma_f32_32x32x16_bf16 v[50:65], v[154:157], v[150:153], v[50:65]
	global_load_dwordx4 v[146:149], v[138:139], off offset:128
	global_load_dwordx4 v[150:153], v[142:143], off offset:128
	global_load_dwordx4 v[170:173], v[134:135], off offset:1056
	s_nop 0
	global_load_dwordx4 v[174:177], v[174:175], off offset:128
	s_nop 0
	global_load_dwordx4 v[134:137], v[136:137], off offset:1056
	s_nop 0
	global_load_dwordx4 v[178:181], v[178:179], off offset:128
	s_nop 0
	global_load_dwordx4 v[138:141], v[140:141], off offset:1056
	v_add_u32_e32 v142, 0x10000, v187
	v_add_u32_e32 v143, 0x18000, v187
	v_mfma_f32_32x32x16_bf16 v[34:49], v[154:157], v[158:161], v[34:49]
	global_load_dwordx4 v[158:161], v[182:183], off offset:128
	s_waitcnt vmcnt(0) lgkmcnt(0)
	ds_write_b128 v142, v[146:149]
	ds_write_b128 v143, v[150:153]
	ds_write_b128 v142, v[170:173] offset:8192
	ds_write_b128 v143, v[174:177] offset:8192
	ds_write_b128 v142, v[134:137] offset:16384
	ds_write_b128 v143, v[178:181] offset:16384
	ds_write_b128 v142, v[138:141] offset:24576
	ds_write_b128 v143, v[158:161] offset:24576
	v_or_b32_e32 v142, 0x18000, v185
	v_or_b32_e32 v143, v142, v0
	s_waitcnt lgkmcnt(0)
	s_barrier
	ds_read_b128 v[134:137], v143
	v_mfma_f32_32x32x16_bf16 v[18:33], v[154:157], v[162:165], v[18:33]
	v_add_u32_e32 v162, 0x10000, v188
	v_or_b32_e32 v0, v162, v0
	ds_read_b128 v[138:141], v0
	ds_read_b128 v[146:149], v143 offset:4096
	ds_read_b128 v[150:153], v0 offset:4096
	v_or_b32_e32 v143, v162, v190
	v_mfma_f32_32x32x16_bf16 v[2:17], v[154:157], v[166:169], v[2:17]
	ds_read_b128 v[154:157], v0 offset:8192
	ds_read_b128 v[158:161], v0 offset:12288
	v_or_b32_e32 v0, v142, v190
	s_waitcnt lgkmcnt(4)
	v_mfma_f32_32x32x16_bf16 v[114:129], v[134:137], v[138:141], v[114:129]
	s_waitcnt lgkmcnt(2)
	v_mfma_f32_32x32x16_bf16 v[98:113], v[134:137], v[150:153], v[98:113]
	s_waitcnt lgkmcnt(1)
	v_mfma_f32_32x32x16_bf16 v[82:97], v[134:137], v[154:157], v[82:97]
	s_waitcnt lgkmcnt(0)
	v_mfma_f32_32x32x16_bf16 v[66:81], v[134:137], v[158:161], v[66:81]
	ds_read_b128 v[134:137], v0
	v_mfma_f32_32x32x16_bf16 v[50:65], v[146:149], v[138:141], v[50:65]
	v_mfma_f32_32x32x16_bf16 v[34:49], v[146:149], v[150:153], v[34:49]
	v_mfma_f32_32x32x16_bf16 v[18:33], v[146:149], v[154:157], v[18:33]
	v_mfma_f32_32x32x16_bf16 v[2:17], v[146:149], v[158:161], v[2:17]
	ds_read_b128 v[138:141], v143
	ds_read_b128 v[146:149], v0 offset:4096
	ds_read_b128 v[150:153], v143 offset:4096
	ds_read_b128 v[154:157], v143 offset:8192
	ds_read_b128 v[158:161], v143 offset:12288
	v_or_b32_e32 v0, v142, v191
	v_or_b32_e32 v143, v162, v191
	s_waitcnt lgkmcnt(4)
	v_mfma_f32_32x32x16_bf16 v[114:129], v[134:137], v[138:141], v[114:129]
	s_waitcnt lgkmcnt(2)
	v_mfma_f32_32x32x16_bf16 v[98:113], v[134:137], v[150:153], v[98:113]
	s_waitcnt lgkmcnt(1)
	v_mfma_f32_32x32x16_bf16 v[82:97], v[134:137], v[154:157], v[82:97]
	s_waitcnt lgkmcnt(0)
	v_mfma_f32_32x32x16_bf16 v[66:81], v[134:137], v[158:161], v[66:81]
	ds_read_b128 v[134:137], v0
	v_mfma_f32_32x32x16_bf16 v[50:65], v[146:149], v[138:141], v[50:65]
	v_mfma_f32_32x32x16_bf16 v[34:49], v[146:149], v[150:153], v[34:49]
	v_mfma_f32_32x32x16_bf16 v[18:33], v[146:149], v[154:157], v[18:33]
	v_mfma_f32_32x32x16_bf16 v[2:17], v[146:149], v[158:161], v[2:17]
	ds_read_b128 v[138:141], v143
	ds_read_b128 v[146:149], v0 offset:4096
	ds_read_b128 v[150:153], v143 offset:4096
	ds_read_b128 v[154:157], v143 offset:8192
	ds_read_b128 v[158:161], v143 offset:12288
	v_or_b32_e32 v0, v142, v192
	v_or_b32_e32 v142, v162, v192
	s_waitcnt lgkmcnt(4)
	v_mfma_f32_32x32x16_bf16 v[114:129], v[134:137], v[138:141], v[114:129]
	s_waitcnt lgkmcnt(2)
	v_mfma_f32_32x32x16_bf16 v[98:113], v[134:137], v[150:153], v[98:113]
	s_waitcnt lgkmcnt(1)
	v_mfma_f32_32x32x16_bf16 v[82:97], v[134:137], v[154:157], v[82:97]
	s_waitcnt lgkmcnt(0)
	v_mfma_f32_32x32x16_bf16 v[66:81], v[134:137], v[158:161], v[66:81]
	ds_read_b128 v[134:137], v0
	v_mfma_f32_32x32x16_bf16 v[50:65], v[146:149], v[138:141], v[50:65]
	v_mfma_f32_32x32x16_bf16 v[34:49], v[146:149], v[150:153], v[34:49]
	v_mfma_f32_32x32x16_bf16 v[18:33], v[146:149], v[154:157], v[18:33]
	v_mfma_f32_32x32x16_bf16 v[2:17], v[146:149], v[158:161], v[2:17]
	ds_read_b128 v[138:141], v142
	ds_read_b128 v[148:151], v0 offset:4096
	ds_read_b128 v[152:155], v142 offset:4096
	ds_read_b128 v[156:159], v142 offset:8192
	ds_read_b128 v[160:163], v142 offset:12288
	v_and_b32_e32 v0, 0xc0, v144
	s_waitcnt lgkmcnt(0)
	s_barrier
; #define MFMA32(a, b, c) __builtin_amdgcn_mfma_f32_32x32x16_bf16((a), (b), (c), 0, 0, 0)
; template <class Epi>
; DI void gemm_tile_s(const bf16_t* __restrict__ A, int lda, const bf16_t* __restrict__ Bt, int ldb, int K, int m0, int n0, char* smem, const Epi& epi) {
;     ...
;         for (int mi = 0; mi < 4; ++mi) acc[ni][mi] = MFMA32(fa[ni], fb[mi], acc[ni][mi]);
;     }
;     if (more) { char* dA = sA + ((kt + 1) & 1) * 65536; char* dB = sB + ((kt + 1) & 1) * 65536;
; #pragma unroll
;       for (int i = 0; i < 4; ++i) { *(u32x4*)(dA + wofs + i * 8192) = ra[i]; *(u32x4*)(dB + wofs + i * 8192) = rb[i]; } }
;     __syncthreads();
;   }
; #pragma unroll
;   for (int ni = 0; ni < 2; ++ni)
; #pragma unroll
;     for (int mi = 0; mi < 4; ++mi)
; #pragma unroll
;       for (int rg = 0; rg < 4; ++rg) {
;         const int m = m0 + 128 * wm + 32 * mi + lq, n = n0 + 64 * wn + 32 * ni + 8 * rg + 4 * h;
;         epi(m, n, acc[ni][mi][4 * rg], acc[ni][mi][4 * rg + 1], acc[ni][mi][4 * rg + 2], acc[ni][mi][4 * rg + 3]);
;       }
	v_lshl_or_b32 v146, v189, 2, v0
	v_mfma_f32_32x32x16_bf16 v[114:129], v[134:137], v[138:141], v[114:129]
	v_cmp_lt_u32_e64 s[2:3], s0, v0
	v_mfma_f32_32x32x16_bf16 v[98:113], v[134:137], v[152:155], v[98:113]
	v_mfma_f32_32x32x16_bf16 v[82:97], v[134:137], v[156:159], v[82:97]
	v_mfma_f32_32x32x16_bf16 v[66:81], v[134:137], v[160:163], v[66:81]
	v_or_b32_e32 v134, s5, v184
	v_add_u32_e32 v134, v134, v186
	v_subrev_u32_e32 v136, s5, v134
	v_lshl_add_u32 v147, v136, 2, v240
	ds_read_b32 v144, v147
	v_ashrrev_i32_e32 v135, 31, v134
	v_add_u32_e32 v136, 0xffffff80, v146
	v_mfma_f32_32x32x16_bf16 v[50:65], v[148:151], v[138:141], v[50:65]
	v_mfma_f32_32x32x16_bf16 v[34:49], v[148:151], v[152:155], v[34:49]
	v_mfma_f32_32x32x16_bf16 v[18:33], v[148:151], v[156:159], v[18:33]
	v_mfma_f32_32x32x16_bf16 v[2:17], v[148:151], v[160:163], v[2:17]
	s_and_saveexec_b64 s[0:1], s[2:3]
	s_xor_b64 s[0:1], exec, s[0:1]
	s_cbranch_execz .LBB0_284
	s_lshl_b32 s11, s8, 22
	v_mov_b32_e32 v137, v1
	s_add_u32 s12, s9, s11
	s_addc_u32 s13, s10, 0
	v_lshlrev_b64 v[138:139], 15, v[136:137]
	v_lshl_add_u64 v[138:139], s[12:13], 0, v[138:139]
	s_waitcnt lgkmcnt(0)
	v_mul_f32_e32 v0, v114, v144
	v_lshl_add_u64 v[138:139], v[134:135], 1, v[138:139]
	v_cvt_pk_bf16_f32 v0, v0, s0
	global_store_short v[138:139], v0, off
	v_mul_f32_e32 v0, v115, v144
	v_add_co_u32_e32 v140, vcc, 0x8000, v138
	v_cvt_pk_bf16_f32 v0, v0, s0
	s_nop 0
	v_addc_co_u32_e32 v141, vcc, 0, v139, vcc
	global_store_short v[140:141], v0, off
	v_mul_f32_e32 v0, v116, v144
	v_add_co_u32_e32 v140, vcc, 0x10000, v138
	v_cvt_pk_bf16_f32 v0, v0, s0
	s_nop 0
	v_addc_co_u32_e32 v141, vcc, 0, v139, vcc
	global_store_short v[140:141], v0, off
	v_mul_f32_e32 v0, v117, v144
	v_add_co_u32_e32 v138, vcc, 0x18000, v138
	v_cvt_pk_bf16_f32 v0, v0, s0
	s_nop 0
	v_addc_co_u32_e32 v139, vcc, 0, v139, vcc
	global_store_short v[138:139], v0, off
.LBB0_284:
	s_or_saveexec_b64 s[0:1], s[0:1]
	s_mov_b64 s[12:13], 0xd2e8000
	v_lshl_add_u64 v[132:133], v[132:133], 0, s[12:13]
	v_lshlrev_b32_e32 v0, 1, v146
	s_xor_b64 exec, exec, s[0:1]
	s_cbranch_execz .LBB0_286
	s_waitcnt lgkmcnt(0)
	v_pk_mul_f32 v[114:115], v[114:115], v[144:145] op_sel_hi:[1,0]
	v_pk_mul_f32 v[116:117], v[116:117], v[144:145] op_sel_hi:[1,0]
	s_lshl_b32 s62, s8, 14
	v_cvt_pk_bf16_f32 v114, v114, v115
	v_cvt_pk_bf16_f32 v115, v116, v117
	v_lshl_add_u64 v[116:117], v[134:135], 0, s[62:63]
	v_mad_u64_u32 v[138:139], s[12:13], v116, s86, v[132:133]
	v_mad_i32_i24 v139, v117, s86, v139
	v_lshl_add_u64 v[116:117], v[138:139], 0, v[0:1]
	global_store_dwordx2 v[116:117], v[114:115], off
	ds_read_b32 v144, v147
.LBB0_286:
	s_or_b64 exec, exec, s[0:1]
	v_add_u32_e32 v140, 0xffffff88, v146
	s_and_saveexec_b64 s[0:1], s[2:3]
	s_xor_b64 s[0:1], exec, s[0:1]
	s_cbranch_execz .LBB0_288
	s_lshl_b32 s11, s8, 22
	v_mov_b32_e32 v141, v1
	s_add_u32 s12, s9, s11
	s_addc_u32 s13, s10, 0
	v_lshlrev_b64 v[114:115], 15, v[140:141]
	v_lshl_add_u64 v[114:115], s[12:13], 0, v[114:115]
	s_waitcnt lgkmcnt(0)
	v_mul_f32_e32 v116, v118, v144
	v_lshl_add_u64 v[114:115], v[134:135], 1, v[114:115]
	v_cvt_pk_bf16_f32 v116, v116, s0
	global_store_short v[114:115], v116, off
	v_mul_f32_e32 v116, v119, v144
	v_cvt_pk_bf16_f32 v137, v116, s0
	v_add_co_u32_e32 v116, vcc, 0x8000, v114
	s_nop 1
	v_addc_co_u32_e32 v117, vcc, 0, v115, vcc
	global_store_short v[116:117], v137, off
	v_mul_f32_e32 v116, v120, v144
	v_cvt_pk_bf16_f32 v137, v116, s0
	v_add_co_u32_e32 v116, vcc, 0x10000, v114
	s_nop 1
	v_addc_co_u32_e32 v117, vcc, 0, v115, vcc
	global_store_short v[116:117], v137, off
	v_mul_f32_e32 v116, v121, v144
	v_add_co_u32_e32 v114, vcc, 0x18000, v114
	v_cvt_pk_bf16_f32 v116, v116, s0
	s_nop 0
	v_addc_co_u32_e32 v115, vcc, 0, v115, vcc
	global_store_short v[114:115], v116, off
.LBB0_288:
	s_andn2_saveexec_b64 s[0:1], s[0:1]
	s_cbranch_execz .LBB0_290
	s_waitcnt lgkmcnt(0)
	v_pk_mul_f32 v[114:115], v[118:119], v[144:145] op_sel_hi:[1,0]
	v_pk_mul_f32 v[116:117], v[120:121], v[144:145] op_sel_hi:[1,0]
	s_lshl_b32 s62, s8, 14
	v_cvt_pk_bf16_f32 v114, v114, v115
	v_cvt_pk_bf16_f32 v115, v116, v117
	v_lshl_add_u64 v[116:117], v[134:135], 0, s[62:63]
	v_mad_u64_u32 v[118:119], s[12:13], v116, s86, v[132:133]
	v_mad_i32_i24 v119, v117, s86, v119
	v_lshl_add_u64 v[116:117], v[118:119], 0, v[0:1]
	global_store_dwordx2 v[116:117], v[114:115], off offset:16
	ds_read_b32 v144, v147
.LBB0_290:
	s_or_b64 exec, exec, s[0:1]
	v_add_u32_e32 v142, 0xffffff90, v146
	s_and_saveexec_b64 s[0:1], s[2:3]
	s_xor_b64 s[0:1], exec, s[0:1]
	s_cbranch_execz .LBB0_292
	s_lshl_b32 s11, s8, 22
	v_mov_b32_e32 v143, v1
	s_add_u32 s12, s9, s11
	s_addc_u32 s13, s10, 0
	v_lshlrev_b64 v[114:115], 15, v[142:143]
	v_lshl_add_u64 v[114:115], s[12:13], 0, v[114:115]
	s_waitcnt lgkmcnt(0)
	v_mul_f32_e32 v116, v122, v144
	v_lshl_add_u64 v[114:115], v[134:135], 1, v[114:115]
	v_cvt_pk_bf16_f32 v116, v116, s0
	global_store_short v[114:115], v116, off
	v_mul_f32_e32 v116, v123, v144
	v_cvt_pk_bf16_f32 v118, v116, s0
	v_add_co_u32_e32 v116, vcc, 0x8000, v114
	s_nop 1
	v_addc_co_u32_e32 v117, vcc, 0, v115, vcc
	global_store_short v[116:117], v118, off
	v_mul_f32_e32 v116, v124, v144
	v_cvt_pk_bf16_f32 v118, v116, s0
	v_add_co_u32_e32 v116, vcc, 0x10000, v114
	s_nop 1
	v_addc_co_u32_e32 v117, vcc, 0, v115, vcc
	global_store_short v[116:117], v118, off
	v_mul_f32_e32 v116, v125, v144
	v_add_co_u32_e32 v114, vcc, 0x18000, v114
	v_cvt_pk_bf16_f32 v116, v116, s0
	s_nop 0
	v_addc_co_u32_e32 v115, vcc, 0, v115, vcc
	global_store_short v[114:115], v116, off
.LBB0_292:
	s_andn2_saveexec_b64 s[0:1], s[0:1]
	s_cbranch_execz .LBB0_294
	s_waitcnt lgkmcnt(0)
	v_pk_mul_f32 v[114:115], v[122:123], v[144:145] op_sel_hi:[1,0]
	v_pk_mul_f32 v[116:117], v[124:125], v[144:145] op_sel_hi:[1,0]
	s_lshl_b32 s62, s8, 14
	v_cvt_pk_bf16_f32 v114, v114, v115
	v_cvt_pk_bf16_f32 v115, v116, v117
	v_lshl_add_u64 v[116:117], v[134:135], 0, s[62:63]
	v_mad_u64_u32 v[118:119], s[12:13], v116, s86, v[132:133]
	v_mad_i32_i24 v119, v117, s86, v119
	v_lshl_add_u64 v[116:117], v[118:119], 0, v[0:1]
	global_store_dwordx2 v[116:117], v[114:115], off offset:32
	ds_read_b32 v144, v147
.LBB0_294:
	s_or_b64 exec, exec, s[0:1]
	v_add_u32_e32 v138, 0xffffff98, v146
	s_and_saveexec_b64 s[0:1], s[2:3]
	s_xor_b64 s[0:1], exec, s[0:1]
	s_cbranch_execz .LBB0_296
	s_lshl_b32 s11, s8, 22
	v_mov_b32_e32 v139, v1
	s_add_u32 s12, s9, s11
	s_addc_u32 s13, s10, 0
	v_lshlrev_b64 v[114:115], 15, v[138:139]
	v_lshl_add_u64 v[114:115], s[12:13], 0, v[114:115]
	s_waitcnt lgkmcnt(0)
	v_mul_f32_e32 v116, v126, v144
	v_lshl_add_u64 v[114:115], v[134:135], 1, v[114:115]
	v_cvt_pk_bf16_f32 v116, v116, s0
	global_store_short v[114:115], v116, off
	v_mul_f32_e32 v116, v127, v144
	v_cvt_pk_bf16_f32 v118, v116, s0
	v_add_co_u32_e32 v116, vcc, 0x8000, v114
	s_nop 1
	v_addc_co_u32_e32 v117, vcc, 0, v115, vcc
	global_store_short v[116:117], v118, off
	v_mul_f32_e32 v116, v128, v144
	v_cvt_pk_bf16_f32 v118, v116, s0
	v_add_co_u32_e32 v116, vcc, 0x10000, v114
	s_nop 1
	v_addc_co_u32_e32 v117, vcc, 0, v115, vcc
	global_store_short v[116:117], v118, off
	v_mul_f32_e32 v116, v129, v144
	v_add_co_u32_e32 v114, vcc, 0x18000, v114
	v_cvt_pk_bf16_f32 v116, v116, s0
	s_nop 0
	v_addc_co_u32_e32 v115, vcc, 0, v115, vcc
	global_store_short v[114:115], v116, off
.LBB0_296:
	s_andn2_saveexec_b64 s[0:1], s[0:1]
	s_cbranch_execz .LBB0_298
	s_waitcnt lgkmcnt(0)
	v_pk_mul_f32 v[114:115], v[126:127], v[144:145] op_sel_hi:[1,0]
	v_pk_mul_f32 v[116:117], v[128:129], v[144:145] op_sel_hi:[1,0]
	s_lshl_b32 s62, s8, 14
	v_cvt_pk_bf16_f32 v114, v114, v115
	v_cvt_pk_bf16_f32 v115, v116, v117
	v_lshl_add_u64 v[116:117], v[134:135], 0, s[62:63]
	v_mad_u64_u32 v[118:119], s[12:13], v116, s86, v[132:133]
	v_mad_i32_i24 v119, v117, s86, v119
	v_lshl_add_u64 v[116:117], v[118:119], 0, v[0:1]
	global_store_dwordx2 v[116:117], v[114:115], off offset:48

.LBB0_306:
	s_waitcnt lgkmcnt(0)
	v_pk_mul_f32 v[98:99], v[110:111], v[116:117] op_sel_hi:[1,0]
	v_pk_mul_f32 v[100:101], v[112:113], v[116:117] op_sel_hi:[1,0]
	s_lshl_b32 s62, s8, 14
	v_cvt_pk_bf16_f32 v98, v98, v99
	v_cvt_pk_bf16_f32 v99, v100, v101
	v_lshl_add_u64 v[100:101], v[114:115], 0, s[62:63]
	v_mad_u64_u32 v[102:103], s[12:13], v100, s86, v[132:133]
	v_mad_i32_i24 v103, v101, s86, v103
	v_lshl_add_u64 v[100:101], v[102:103], 0, v[0:1]
	global_store_dwordx2 v[100:101], v[98:99], off offset:48

.LBB0_315:
	s_waitcnt lgkmcnt(0)
	v_pk_mul_f32 v[82:83], v[94:95], v[100:101] op_sel_hi:[1,0]
	v_pk_mul_f32 v[84:85], v[96:97], v[100:101] op_sel_hi:[1,0]
	s_lshl_b32 s62, s8, 14
	v_cvt_pk_bf16_f32 v82, v82, v83
	v_cvt_pk_bf16_f32 v83, v84, v85
	v_lshl_add_u64 v[84:85], v[98:99], 0, s[62:63]
	v_mad_u64_u32 v[86:87], s[12:13], v84, s86, v[132:133]
	v_mad_i32_i24 v87, v85, s86, v87
	v_lshl_add_u64 v[84:85], v[86:87], 0, v[0:1]
	global_store_dwordx2 v[84:85], v[82:83], off offset:48

.LBB0_324:
	s_waitcnt lgkmcnt(0)
	v_pk_mul_f32 v[66:67], v[78:79], v[84:85] op_sel_hi:[1,0]
	v_pk_mul_f32 v[68:69], v[80:81], v[84:85] op_sel_hi:[1,0]
	s_lshl_b32 s62, s8, 14
	v_cvt_pk_bf16_f32 v66, v66, v67
	v_cvt_pk_bf16_f32 v67, v68, v69
	v_lshl_add_u64 v[68:69], v[82:83], 0, s[62:63]
	v_mad_u64_u32 v[70:71], s[12:13], v68, s86, v[132:133]
	v_mad_i32_i24 v71, v69, s86, v71
	v_lshl_add_u64 v[68:69], v[70:71], 0, v[0:1]
	global_store_dwordx2 v[68:69], v[66:67], off offset:48
.LBB0_325:
	s_or_b64 exec, exec, s[0:1]
	ds_read_b32 v74, v147
	v_add_u32_e32 v68, 0xffffffa0, v146
	s_and_saveexec_b64 s[0:1], s[2:3]
	s_xor_b64 s[0:1], exec, s[0:1]
	s_cbranch_execz .LBB0_327
	s_lshl_b32 s11, s8, 22
	v_mov_b32_e32 v69, v1
	s_add_u32 s12, s9, s11
	s_addc_u32 s13, s10, 0
	v_lshlrev_b64 v[66:67], 15, v[68:69]
	v_lshl_add_u64 v[66:67], s[12:13], 0, v[66:67]
	s_waitcnt lgkmcnt(0)
	v_mul_f32_e32 v69, v50, v74
	v_lshl_add_u64 v[66:67], v[134:135], 1, v[66:67]
	v_cvt_pk_bf16_f32 v69, v69, s0
	global_store_short v[66:67], v69, off
	v_mul_f32_e32 v69, v51, v74
	v_add_co_u32_e32 v70, vcc, 0x8000, v66
	v_cvt_pk_bf16_f32 v69, v69, s0
	s_nop 0
	v_addc_co_u32_e32 v71, vcc, 0, v67, vcc
	global_store_short v[70:71], v69, off
	v_mul_f32_e32 v69, v52, v74
	v_add_co_u32_e32 v70, vcc, 0x10000, v66
	v_cvt_pk_bf16_f32 v69, v69, s0
	s_nop 0
	v_addc_co_u32_e32 v71, vcc, 0, v67, vcc
	global_store_short v[70:71], v69, off
	v_mul_f32_e32 v69, v53, v74
	v_add_co_u32_e32 v66, vcc, 0x18000, v66
	v_cvt_pk_bf16_f32 v69, v69, s0
	s_nop 0
	v_addc_co_u32_e32 v67, vcc, 0, v67, vcc
	global_store_short v[66:67], v69, off
.LBB0_327:
	s_andn2_saveexec_b64 s[0:1], s[0:1]
	s_cbranch_execz .LBB0_329
	s_waitcnt lgkmcnt(0)
	v_pk_mul_f32 v[50:51], v[50:51], v[74:75] op_sel_hi:[1,0]
	v_pk_mul_f32 v[52:53], v[52:53], v[74:75] op_sel_hi:[1,0]
	s_lshl_b32 s62, s8, 14
	v_cvt_pk_bf16_f32 v50, v50, v51
	v_cvt_pk_bf16_f32 v51, v52, v53
	v_lshl_add_u64 v[52:53], v[134:135], 0, s[62:63]
	v_mad_u64_u32 v[66:67], s[12:13], v52, s86, v[132:133]
	v_mad_i32_i24 v67, v53, s86, v67
	v_lshl_add_u64 v[52:53], v[66:67], 0, v[0:1]
	global_store_dwordx2 v[52:53], v[50:51], off offset:64
	ds_read_b32 v74, v147
.LBB0_329:
	s_or_b64 exec, exec, s[0:1]
	v_add_u32_e32 v72, 0xffffffa8, v146
	s_and_saveexec_b64 s[0:1], s[2:3]
	s_xor_b64 s[0:1], exec, s[0:1]
	s_cbranch_execz .LBB0_331
	s_lshl_b32 s11, s8, 22
	v_mov_b32_e32 v73, v1
	s_add_u32 s12, s9, s11
	s_addc_u32 s13, s10, 0
	v_lshlrev_b64 v[50:51], 15, v[72:73]
	v_lshl_add_u64 v[50:51], s[12:13], 0, v[50:51]
	s_waitcnt lgkmcnt(0)
	v_mul_f32_e32 v52, v54, v74
	v_lshl_add_u64 v[50:51], v[134:135], 1, v[50:51]
	v_cvt_pk_bf16_f32 v52, v52, s0
	global_store_short v[50:51], v52, off
	v_mul_f32_e32 v52, v55, v74
	v_cvt_pk_bf16_f32 v66, v52, s0
	v_add_co_u32_e32 v52, vcc, 0x8000, v50
	s_nop 1
	v_addc_co_u32_e32 v53, vcc, 0, v51, vcc
	global_store_short v[52:53], v66, off
	v_mul_f32_e32 v52, v56, v74
	v_cvt_pk_bf16_f32 v66, v52, s0
	v_add_co_u32_e32 v52, vcc, 0x10000, v50
	s_nop 1
	v_addc_co_u32_e32 v53, vcc, 0, v51, vcc
	global_store_short v[52:53], v66, off
	v_mul_f32_e32 v52, v57, v74
	v_add_co_u32_e32 v50, vcc, 0x18000, v50
	v_cvt_pk_bf16_f32 v52, v52, s0
	s_nop 0
	v_addc_co_u32_e32 v51, vcc, 0, v51, vcc
	global_store_short v[50:51], v52, off
.LBB0_331:
	s_andn2_saveexec_b64 s[0:1], s[0:1]
	s_cbranch_execz .LBB0_333
	s_waitcnt lgkmcnt(0)
	v_pk_mul_f32 v[50:51], v[54:55], v[74:75] op_sel_hi:[1,0]
	v_pk_mul_f32 v[52:53], v[56:57], v[74:75] op_sel_hi:[1,0]
	s_lshl_b32 s62, s8, 14
	v_cvt_pk_bf16_f32 v50, v50, v51
	v_cvt_pk_bf16_f32 v51, v52, v53
	v_lshl_add_u64 v[52:53], v[134:135], 0, s[62:63]
	v_mad_u64_u32 v[54:55], s[12:13], v52, s86, v[132:133]
	v_mad_i32_i24 v55, v53, s86, v55
	v_lshl_add_u64 v[52:53], v[54:55], 0, v[0:1]
	global_store_dwordx2 v[52:53], v[50:51], off offset:80
	ds_read_b32 v74, v147
.LBB0_333:
	s_or_b64 exec, exec, s[0:1]
	v_add_u32_e32 v70, 0xffffffb0, v146
	s_and_saveexec_b64 s[0:1], s[2:3]
	s_xor_b64 s[0:1], exec, s[0:1]
	s_cbranch_execz .LBB0_335
	s_lshl_b32 s11, s8, 22
	v_mov_b32_e32 v71, v1
	s_add_u32 s12, s9, s11
	s_addc_u32 s13, s10, 0
	v_lshlrev_b64 v[50:51], 15, v[70:71]
	v_lshl_add_u64 v[50:51], s[12:13], 0, v[50:51]
	s_waitcnt lgkmcnt(0)
	v_mul_f32_e32 v52, v58, v74
	v_lshl_add_u64 v[50:51], v[134:135], 1, v[50:51]
	v_cvt_pk_bf16_f32 v52, v52, s0
	global_store_short v[50:51], v52, off
	v_mul_f32_e32 v52, v59, v74
	v_cvt_pk_bf16_f32 v54, v52, s0
	v_add_co_u32_e32 v52, vcc, 0x8000, v50
	s_nop 1
	v_addc_co_u32_e32 v53, vcc, 0, v51, vcc
	global_store_short v[52:53], v54, off
	v_mul_f32_e32 v52, v60, v74
	v_cvt_pk_bf16_f32 v54, v52, s0
	v_add_co_u32_e32 v52, vcc, 0x10000, v50
	s_nop 1
	v_addc_co_u32_e32 v53, vcc, 0, v51, vcc
	global_store_short v[52:53], v54, off
	v_mul_f32_e32 v52, v61, v74
	v_add_co_u32_e32 v50, vcc, 0x18000, v50
	v_cvt_pk_bf16_f32 v52, v52, s0
	s_nop 0
	v_addc_co_u32_e32 v51, vcc, 0, v51, vcc
	global_store_short v[50:51], v52, off
.LBB0_335:
	s_andn2_saveexec_b64 s[0:1], s[0:1]
	s_cbranch_execz .LBB0_337
	s_waitcnt lgkmcnt(0)
	v_pk_mul_f32 v[50:51], v[58:59], v[74:75] op_sel_hi:[1,0]
	v_pk_mul_f32 v[52:53], v[60:61], v[74:75] op_sel_hi:[1,0]
	s_lshl_b32 s62, s8, 14
	v_cvt_pk_bf16_f32 v50, v50, v51
	v_cvt_pk_bf16_f32 v51, v52, v53
	v_lshl_add_u64 v[52:53], v[134:135], 0, s[62:63]
	v_mad_u64_u32 v[54:55], s[12:13], v52, s86, v[132:133]
	v_mad_i32_i24 v55, v53, s86, v55
	v_lshl_add_u64 v[52:53], v[54:55], 0, v[0:1]
	global_store_dwordx2 v[52:53], v[50:51], off offset:96
	ds_read_b32 v74, v147
.LBB0_337:
	s_or_b64 exec, exec, s[0:1]
	v_add_u32_e32 v66, 0xffffffb8, v146
	s_and_saveexec_b64 s[0:1], s[2:3]
	s_xor_b64 s[0:1], exec, s[0:1]
	s_cbranch_execz .LBB0_339
	s_lshl_b32 s11, s8, 22
	v_mov_b32_e32 v67, v1
	s_add_u32 s12, s9, s11
	s_addc_u32 s13, s10, 0
	v_lshlrev_b64 v[50:51], 15, v[66:67]
	v_lshl_add_u64 v[50:51], s[12:13], 0, v[50:51]
	s_waitcnt lgkmcnt(0)
	v_mul_f32_e32 v52, v62, v74
	v_lshl_add_u64 v[50:51], v[134:135], 1, v[50:51]
	v_cvt_pk_bf16_f32 v52, v52, s0
	global_store_short v[50:51], v52, off
	v_mul_f32_e32 v52, v63, v74
	v_cvt_pk_bf16_f32 v54, v52, s0
	v_add_co_u32_e32 v52, vcc, 0x8000, v50
	s_nop 1
	v_addc_co_u32_e32 v53, vcc, 0, v51, vcc
	global_store_short v[52:53], v54, off
	v_mul_f32_e32 v52, v64, v74
	v_cvt_pk_bf16_f32 v54, v52, s0
	v_add_co_u32_e32 v52, vcc, 0x10000, v50
	s_nop 1
	v_addc_co_u32_e32 v53, vcc, 0, v51, vcc
	global_store_short v[52:53], v54, off
	v_mul_f32_e32 v52, v65, v74
	v_add_co_u32_e32 v50, vcc, 0x18000, v50
	v_cvt_pk_bf16_f32 v52, v52, s0
	s_nop 0
	v_addc_co_u32_e32 v51, vcc, 0, v51, vcc
	global_store_short v[50:51], v52, off
.LBB0_339:
	s_andn2_saveexec_b64 s[0:1], s[0:1]
	s_cbranch_execz .LBB0_341
	s_waitcnt lgkmcnt(0)
	v_pk_mul_f32 v[50:51], v[62:63], v[74:75] op_sel_hi:[1,0]
	v_pk_mul_f32 v[52:53], v[64:65], v[74:75] op_sel_hi:[1,0]
	s_lshl_b32 s62, s8, 14
	v_cvt_pk_bf16_f32 v50, v50, v51
	v_cvt_pk_bf16_f32 v51, v52, v53
	v_lshl_add_u64 v[52:53], v[134:135], 0, s[62:63]
	v_mad_u64_u32 v[54:55], s[12:13], v52, s86, v[132:133]
	v_mad_i32_i24 v55, v53, s86, v55
	v_lshl_add_u64 v[52:53], v[54:55], 0, v[0:1]
	global_store_dwordx2 v[52:53], v[50:51], off offset:112

.LBB0_349:
	s_waitcnt lgkmcnt(0)
	v_pk_mul_f32 v[34:35], v[46:47], v[50:51] op_sel_hi:[1,0]
	v_pk_mul_f32 v[36:37], v[48:49], v[50:51] op_sel_hi:[1,0]
	s_lshl_b32 s62, s8, 14
	v_cvt_pk_bf16_f32 v34, v34, v35
	v_cvt_pk_bf16_f32 v35, v36, v37
	v_lshl_add_u64 v[36:37], v[114:115], 0, s[62:63]
	v_mad_u64_u32 v[38:39], s[12:13], v36, s86, v[132:133]
	v_mad_i32_i24 v39, v37, s86, v39
	v_lshl_add_u64 v[36:37], v[38:39], 0, v[0:1]
	global_store_dwordx2 v[36:37], v[34:35], off offset:112

.LBB0_358:
	s_waitcnt lgkmcnt(0)
	v_pk_mul_f32 v[18:19], v[30:31], v[34:35] op_sel_hi:[1,0]
	v_pk_mul_f32 v[20:21], v[32:33], v[34:35] op_sel_hi:[1,0]
	s_lshl_b32 s62, s8, 14
	v_cvt_pk_bf16_f32 v18, v18, v19
	v_cvt_pk_bf16_f32 v19, v20, v21
	v_lshl_add_u64 v[20:21], v[98:99], 0, s[62:63]
	v_mad_u64_u32 v[22:23], s[12:13], v20, s86, v[132:133]
	v_mad_i32_i24 v23, v21, s86, v23
	v_lshl_add_u64 v[20:21], v[22:23], 0, v[0:1]
	global_store_dwordx2 v[20:21], v[18:19], off offset:112

.LBB0_368:
	s_lshl_b32 s11, s8, 22
	v_mov_b32_e32 v137, v1
	s_add_u32 s12, s9, s11
	s_addc_u32 s13, s10, 0
	v_lshlrev_b64 v[118:119], 15, v[136:137]
	v_lshl_add_u64 v[118:119], s[12:13], 0, v[118:119]
	s_waitcnt lgkmcnt(0)
	v_mul_f32_e32 v120, v98, v116
	v_lshl_add_u64 v[118:119], v[114:115], 1, v[118:119]
	v_cvt_pk_bf16_f32 v120, v120, s0
	global_store_short v[118:119], v120, off
	v_mul_f32_e32 v120, v99, v116
	v_cvt_pk_bf16_f32 v122, v120, s0
	v_add_co_u32_e32 v120, vcc, 0x8000, v118
	s_nop 1
	v_addc_co_u32_e32 v121, vcc, 0, v119, vcc
	global_store_short v[120:121], v122, off
	v_mul_f32_e32 v120, v100, v116
	v_cvt_pk_bf16_f32 v122, v120, s0
	v_add_co_u32_e32 v120, vcc, 0x10000, v118
	s_nop 1
	v_addc_co_u32_e32 v121, vcc, 0, v119, vcc
	global_store_short v[120:121], v122, off
	v_mul_f32_e32 v120, v101, v116
	v_add_co_u32_e32 v118, vcc, 0x18000, v118
	v_cvt_pk_bf16_f32 v120, v120, s0
	s_nop 0
	v_addc_co_u32_e32 v119, vcc, 0, v119, vcc
	global_store_short v[118:119], v120, off
	s_andn2_saveexec_b64 s[0:1], s[0:1]
	s_cbranch_execz .LBB0_300
.LBB0_369:
	s_waitcnt lgkmcnt(0)
	v_pk_mul_f32 v[98:99], v[98:99], v[116:117] op_sel_hi:[1,0]
	v_pk_mul_f32 v[100:101], v[100:101], v[116:117] op_sel_hi:[1,0]
	s_lshl_b32 s62, s8, 14
	v_cvt_pk_bf16_f32 v98, v98, v99
	v_cvt_pk_bf16_f32 v99, v100, v101
	v_lshl_add_u64 v[100:101], v[114:115], 0, s[62:63]
	v_mad_u64_u32 v[118:119], s[12:13], v100, s86, v[132:133]
	v_mad_i32_i24 v119, v101, s86, v119
	v_lshl_add_u64 v[100:101], v[118:119], 0, v[0:1]
	global_store_dwordx2 v[100:101], v[98:99], off
	ds_read_b32 v116, v117
	s_or_b64 exec, exec, s[0:1]
	s_and_saveexec_b64 s[0:1], s[2:3]
	s_xor_b64 s[0:1], exec, s[0:1]
	s_cbranch_execz .LBB0_301
.LBB0_370:
	s_lshl_b32 s11, s8, 22
	v_mov_b32_e32 v141, v1
	s_add_u32 s12, s9, s11
	s_addc_u32 s13, s10, 0
	v_lshlrev_b64 v[98:99], 15, v[140:141]
	v_lshl_add_u64 v[98:99], s[12:13], 0, v[98:99]
	s_waitcnt lgkmcnt(0)
	v_mul_f32_e32 v100, v102, v116
	v_lshl_add_u64 v[98:99], v[114:115], 1, v[98:99]
	v_cvt_pk_bf16_f32 v100, v100, s0
	global_store_short v[98:99], v100, off
	v_mul_f32_e32 v100, v103, v116
	v_cvt_pk_bf16_f32 v118, v100, s0
	v_add_co_u32_e32 v100, vcc, 0x8000, v98
	s_nop 1
	v_addc_co_u32_e32 v101, vcc, 0, v99, vcc
	global_store_short v[100:101], v118, off
	v_mul_f32_e32 v100, v104, v116
	v_cvt_pk_bf16_f32 v118, v100, s0
	v_add_co_u32_e32 v100, vcc, 0x10000, v98
	s_nop 1
	v_addc_co_u32_e32 v101, vcc, 0, v99, vcc
	global_store_short v[100:101], v118, off
	v_mul_f32_e32 v100, v105, v116
	v_add_co_u32_e32 v98, vcc, 0x18000, v98
	v_cvt_pk_bf16_f32 v100, v100, s0
	s_nop 0
	v_addc_co_u32_e32 v99, vcc, 0, v99, vcc
	global_store_short v[98:99], v100, off
	s_andn2_saveexec_b64 s[0:1], s[0:1]
	s_cbranch_execz .LBB0_302
.LBB0_371:
	s_waitcnt lgkmcnt(0)
	v_pk_mul_f32 v[98:99], v[102:103], v[116:117] op_sel_hi:[1,0]
	v_pk_mul_f32 v[100:101], v[104:105], v[116:117] op_sel_hi:[1,0]
	s_lshl_b32 s62, s8, 14
	v_cvt_pk_bf16_f32 v98, v98, v99
	v_cvt_pk_bf16_f32 v99, v100, v101
	v_lshl_add_u64 v[100:101], v[114:115], 0, s[62:63]
	v_mad_u64_u32 v[102:103], s[12:13], v100, s86, v[132:133]
	v_mad_i32_i24 v103, v101, s86, v103
	v_lshl_add_u64 v[100:101], v[102:103], 0, v[0:1]
	global_store_dwordx2 v[100:101], v[98:99], off offset:16
	ds_read_b32 v116, v117
	s_or_b64 exec, exec, s[0:1]
	s_and_saveexec_b64 s[0:1], s[2:3]
	s_xor_b64 s[0:1], exec, s[0:1]
	s_cbranch_execz .LBB0_303
.LBB0_372:
	s_lshl_b32 s11, s8, 22
	v_mov_b32_e32 v143, v1
	s_add_u32 s12, s9, s11
	s_addc_u32 s13, s10, 0
	v_lshlrev_b64 v[98:99], 15, v[142:143]
	v_lshl_add_u64 v[98:99], s[12:13], 0, v[98:99]
	s_waitcnt lgkmcnt(0)
	v_mul_f32_e32 v100, v106, v116
	v_lshl_add_u64 v[98:99], v[114:115], 1, v[98:99]
	v_cvt_pk_bf16_f32 v100, v100, s0
	global_store_short v[98:99], v100, off
	v_mul_f32_e32 v100, v107, v116
	v_cvt_pk_bf16_f32 v102, v100, s0
	v_add_co_u32_e32 v100, vcc, 0x8000, v98
	s_nop 1
	v_addc_co_u32_e32 v101, vcc, 0, v99, vcc
	global_store_short v[100:101], v102, off
	v_mul_f32_e32 v100, v108, v116
	v_cvt_pk_bf16_f32 v102, v100, s0
	v_add_co_u32_e32 v100, vcc, 0x10000, v98
	s_nop 1
	v_addc_co_u32_e32 v101, vcc, 0, v99, vcc
	global_store_short v[100:101], v102, off
	v_mul_f32_e32 v100, v109, v116
	v_add_co_u32_e32 v98, vcc, 0x18000, v98
	v_cvt_pk_bf16_f32 v100, v100, s0
	s_nop 0
	v_addc_co_u32_e32 v99, vcc, 0, v99, vcc
	global_store_short v[98:99], v100, off
	s_andn2_saveexec_b64 s[0:1], s[0:1]
	s_cbranch_execz .LBB0_304
.LBB0_373:
	s_waitcnt lgkmcnt(0)
	v_pk_mul_f32 v[98:99], v[106:107], v[116:117] op_sel_hi:[1,0]
	v_pk_mul_f32 v[100:101], v[108:109], v[116:117] op_sel_hi:[1,0]
	s_lshl_b32 s62, s8, 14
	v_cvt_pk_bf16_f32 v98, v98, v99
	v_cvt_pk_bf16_f32 v99, v100, v101
	v_lshl_add_u64 v[100:101], v[114:115], 0, s[62:63]
	v_mad_u64_u32 v[102:103], s[12:13], v100, s86, v[132:133]
	v_mad_i32_i24 v103, v101, s86, v103
	v_lshl_add_u64 v[100:101], v[102:103], 0, v[0:1]
	global_store_dwordx2 v[100:101], v[98:99], off offset:32
	ds_read_b32 v116, v117
	s_or_b64 exec, exec, s[0:1]
	s_and_saveexec_b64 s[0:1], s[2:3]
	s_xor_b64 s[0:1], exec, s[0:1]
	s_cbranch_execz .LBB0_305
.LBB0_374:
	s_lshl_b32 s11, s8, 22
	v_mov_b32_e32 v139, v1
	s_add_u32 s12, s9, s11
	s_addc_u32 s13, s10, 0
	v_lshlrev_b64 v[98:99], 15, v[138:139]
	v_lshl_add_u64 v[98:99], s[12:13], 0, v[98:99]
	s_waitcnt lgkmcnt(0)
	v_mul_f32_e32 v100, v110, v116
	v_lshl_add_u64 v[98:99], v[114:115], 1, v[98:99]
	v_cvt_pk_bf16_f32 v100, v100, s0
	global_store_short v[98:99], v100, off
	v_mul_f32_e32 v100, v111, v116
	v_cvt_pk_bf16_f32 v102, v100, s0
	v_add_co_u32_e32 v100, vcc, 0x8000, v98
	s_nop 1
	v_addc_co_u32_e32 v101, vcc, 0, v99, vcc
	global_store_short v[100:101], v102, off
	v_mul_f32_e32 v100, v112, v116
	v_cvt_pk_bf16_f32 v102, v100, s0
	v_add_co_u32_e32 v100, vcc, 0x10000, v98
	s_nop 1
	v_addc_co_u32_e32 v101, vcc, 0, v99, vcc
	global_store_short v[100:101], v102, off
	v_mul_f32_e32 v100, v113, v116
	v_add_co_u32_e32 v98, vcc, 0x18000, v98
	v_cvt_pk_bf16_f32 v100, v100, s0
	s_nop 0
	v_addc_co_u32_e32 v99, vcc, 0, v99, vcc
	global_store_short v[98:99], v100, off
	s_andn2_saveexec_b64 s[0:1], s[0:1]
	s_cbranch_execnz .LBB0_306
	s_branch .LBB0_307
.LBB0_375:
	s_lshl_b32 s11, s8, 22
	v_mov_b32_e32 v137, v1
	s_add_u32 s12, s9, s11
	s_addc_u32 s13, s10, 0
	v_lshlrev_b64 v[102:103], 15, v[136:137]
	v_lshl_add_u64 v[102:103], s[12:13], 0, v[102:103]
	s_waitcnt lgkmcnt(0)
	v_mul_f32_e32 v104, v82, v100
	v_lshl_add_u64 v[102:103], v[98:99], 1, v[102:103]
	v_cvt_pk_bf16_f32 v104, v104, s0
	global_store_short v[102:103], v104, off
	v_mul_f32_e32 v104, v83, v100
	v_cvt_pk_bf16_f32 v106, v104, s0
	v_add_co_u32_e32 v104, vcc, 0x8000, v102
	s_nop 1
	v_addc_co_u32_e32 v105, vcc, 0, v103, vcc
	global_store_short v[104:105], v106, off
	v_mul_f32_e32 v104, v84, v100
	v_cvt_pk_bf16_f32 v106, v104, s0
	v_add_co_u32_e32 v104, vcc, 0x10000, v102
	s_nop 1
	v_addc_co_u32_e32 v105, vcc, 0, v103, vcc
	global_store_short v[104:105], v106, off
	v_mul_f32_e32 v104, v85, v100
	v_add_co_u32_e32 v102, vcc, 0x18000, v102
	v_cvt_pk_bf16_f32 v104, v104, s0
	s_nop 0
	v_addc_co_u32_e32 v103, vcc, 0, v103, vcc
	global_store_short v[102:103], v104, off
	s_andn2_saveexec_b64 s[0:1], s[0:1]
	s_cbranch_execz .LBB0_309
.LBB0_376:
	s_waitcnt lgkmcnt(0)
	v_pk_mul_f32 v[82:83], v[82:83], v[100:101] op_sel_hi:[1,0]
	v_pk_mul_f32 v[84:85], v[84:85], v[100:101] op_sel_hi:[1,0]
	s_lshl_b32 s62, s8, 14
	v_cvt_pk_bf16_f32 v82, v82, v83
	v_cvt_pk_bf16_f32 v83, v84, v85
	v_lshl_add_u64 v[84:85], v[98:99], 0, s[62:63]
	v_mad_u64_u32 v[102:103], s[12:13], v84, s86, v[132:133]
	v_mad_i32_i24 v103, v85, s86, v103
	v_lshl_add_u64 v[84:85], v[102:103], 0, v[0:1]
	global_store_dwordx2 v[84:85], v[82:83], off
	ds_read_b32 v100, v101
	s_or_b64 exec, exec, s[0:1]
	s_and_saveexec_b64 s[0:1], s[2:3]
	s_xor_b64 s[0:1], exec, s[0:1]
	s_cbranch_execz .LBB0_310
.LBB0_377:
	s_lshl_b32 s11, s8, 22
	v_mov_b32_e32 v141, v1
	s_add_u32 s12, s9, s11
	s_addc_u32 s13, s10, 0
	v_lshlrev_b64 v[82:83], 15, v[140:141]
	v_lshl_add_u64 v[82:83], s[12:13], 0, v[82:83]
	s_waitcnt lgkmcnt(0)
	v_mul_f32_e32 v84, v86, v100
	v_lshl_add_u64 v[82:83], v[98:99], 1, v[82:83]
	v_cvt_pk_bf16_f32 v84, v84, s0
	global_store_short v[82:83], v84, off
	v_mul_f32_e32 v84, v87, v100
	v_cvt_pk_bf16_f32 v102, v84, s0
	v_add_co_u32_e32 v84, vcc, 0x8000, v82
	s_nop 1
	v_addc_co_u32_e32 v85, vcc, 0, v83, vcc
	global_store_short v[84:85], v102, off
	v_mul_f32_e32 v84, v88, v100
	v_cvt_pk_bf16_f32 v102, v84, s0
	v_add_co_u32_e32 v84, vcc, 0x10000, v82
	s_nop 1
	v_addc_co_u32_e32 v85, vcc, 0, v83, vcc
	global_store_short v[84:85], v102, off
	v_mul_f32_e32 v84, v89, v100
	v_add_co_u32_e32 v82, vcc, 0x18000, v82
	v_cvt_pk_bf16_f32 v84, v84, s0
	s_nop 0
	v_addc_co_u32_e32 v83, vcc, 0, v83, vcc
	global_store_short v[82:83], v84, off
	s_andn2_saveexec_b64 s[0:1], s[0:1]
	s_cbranch_execz .LBB0_311
.LBB0_378:
	s_waitcnt lgkmcnt(0)
	v_pk_mul_f32 v[82:83], v[86:87], v[100:101] op_sel_hi:[1,0]
	v_pk_mul_f32 v[84:85], v[88:89], v[100:101] op_sel_hi:[1,0]
	s_lshl_b32 s62, s8, 14
	v_cvt_pk_bf16_f32 v82, v82, v83
	v_cvt_pk_bf16_f32 v83, v84, v85
	v_lshl_add_u64 v[84:85], v[98:99], 0, s[62:63]
	v_mad_u64_u32 v[86:87], s[12:13], v84, s86, v[132:133]
	v_mad_i32_i24 v87, v85, s86, v87
	v_lshl_add_u64 v[84:85], v[86:87], 0, v[0:1]
	global_store_dwordx2 v[84:85], v[82:83], off offset:16
	ds_read_b32 v100, v101
	s_or_b64 exec, exec, s[0:1]
	s_and_saveexec_b64 s[0:1], s[2:3]
	s_xor_b64 s[0:1], exec, s[0:1]
	s_cbranch_execz .LBB0_312
.LBB0_379:
	s_lshl_b32 s11, s8, 22
	v_mov_b32_e32 v143, v1
	s_add_u32 s12, s9, s11
	s_addc_u32 s13, s10, 0
	v_lshlrev_b64 v[82:83], 15, v[142:143]
	v_lshl_add_u64 v[82:83], s[12:13], 0, v[82:83]
	s_waitcnt lgkmcnt(0)
	v_mul_f32_e32 v84, v90, v100
	v_lshl_add_u64 v[82:83], v[98:99], 1, v[82:83]
	v_cvt_pk_bf16_f32 v84, v84, s0
	global_store_short v[82:83], v84, off
	v_mul_f32_e32 v84, v91, v100
	v_cvt_pk_bf16_f32 v86, v84, s0
	v_add_co_u32_e32 v84, vcc, 0x8000, v82
	s_nop 1
	v_addc_co_u32_e32 v85, vcc, 0, v83, vcc
	global_store_short v[84:85], v86, off
	v_mul_f32_e32 v84, v92, v100
	v_cvt_pk_bf16_f32 v86, v84, s0
	v_add_co_u32_e32 v84, vcc, 0x10000, v82
	s_nop 1
	v_addc_co_u32_e32 v85, vcc, 0, v83, vcc
	global_store_short v[84:85], v86, off
	v_mul_f32_e32 v84, v93, v100
	v_add_co_u32_e32 v82, vcc, 0x18000, v82
	v_cvt_pk_bf16_f32 v84, v84, s0
	s_nop 0
	v_addc_co_u32_e32 v83, vcc, 0, v83, vcc
	global_store_short v[82:83], v84, off
	s_andn2_saveexec_b64 s[0:1], s[0:1]
	s_cbranch_execz .LBB0_313
.LBB0_380:
	s_waitcnt lgkmcnt(0)
	v_pk_mul_f32 v[82:83], v[90:91], v[100:101] op_sel_hi:[1,0]
	v_pk_mul_f32 v[84:85], v[92:93], v[100:101] op_sel_hi:[1,0]
	s_lshl_b32 s62, s8, 14
	v_cvt_pk_bf16_f32 v82, v82, v83
	v_cvt_pk_bf16_f32 v83, v84, v85
	v_lshl_add_u64 v[84:85], v[98:99], 0, s[62:63]
	v_mad_u64_u32 v[86:87], s[12:13], v84, s86, v[132:133]
	v_mad_i32_i24 v87, v85, s86, v87
	v_lshl_add_u64 v[84:85], v[86:87], 0, v[0:1]
	global_store_dwordx2 v[84:85], v[82:83], off offset:32
	ds_read_b32 v100, v101
	s_or_b64 exec, exec, s[0:1]
	s_and_saveexec_b64 s[0:1], s[2:3]
	s_xor_b64 s[0:1], exec, s[0:1]
	s_cbranch_execz .LBB0_314
.LBB0_381:
	s_lshl_b32 s11, s8, 22
	v_mov_b32_e32 v139, v1
	s_add_u32 s12, s9, s11
	s_addc_u32 s13, s10, 0
	v_lshlrev_b64 v[82:83], 15, v[138:139]
	v_lshl_add_u64 v[82:83], s[12:13], 0, v[82:83]
	s_waitcnt lgkmcnt(0)
	v_mul_f32_e32 v84, v94, v100
	v_lshl_add_u64 v[82:83], v[98:99], 1, v[82:83]
	v_cvt_pk_bf16_f32 v84, v84, s0
	global_store_short v[82:83], v84, off
	v_mul_f32_e32 v84, v95, v100
	v_cvt_pk_bf16_f32 v86, v84, s0
	v_add_co_u32_e32 v84, vcc, 0x8000, v82
	s_nop 1
	v_addc_co_u32_e32 v85, vcc, 0, v83, vcc
	global_store_short v[84:85], v86, off
	v_mul_f32_e32 v84, v96, v100
	v_cvt_pk_bf16_f32 v86, v84, s0
	v_add_co_u32_e32 v84, vcc, 0x10000, v82
	s_nop 1
	v_addc_co_u32_e32 v85, vcc, 0, v83, vcc
	global_store_short v[84:85], v86, off
	v_mul_f32_e32 v84, v97, v100
	v_add_co_u32_e32 v82, vcc, 0x18000, v82
	v_cvt_pk_bf16_f32 v84, v84, s0
	s_nop 0
	v_addc_co_u32_e32 v83, vcc, 0, v83, vcc
	global_store_short v[82:83], v84, off
	s_andn2_saveexec_b64 s[0:1], s[0:1]
	s_cbranch_execnz .LBB0_315
	s_branch .LBB0_316
.LBB0_382:
	s_lshl_b32 s11, s8, 22
	v_mov_b32_e32 v137, v1
	s_add_u32 s12, s9, s11
	s_addc_u32 s13, s10, 0
	v_lshlrev_b64 v[86:87], 15, v[136:137]
	v_lshl_add_u64 v[86:87], s[12:13], 0, v[86:87]
	s_waitcnt lgkmcnt(0)
	v_mul_f32_e32 v88, v66, v84
	v_lshl_add_u64 v[86:87], v[82:83], 1, v[86:87]
	v_cvt_pk_bf16_f32 v88, v88, s0
	global_store_short v[86:87], v88, off
	v_mul_f32_e32 v88, v67, v84
	v_cvt_pk_bf16_f32 v90, v88, s0
	v_add_co_u32_e32 v88, vcc, 0x8000, v86
	s_nop 1
	v_addc_co_u32_e32 v89, vcc, 0, v87, vcc
	global_store_short v[88:89], v90, off
	v_mul_f32_e32 v88, v68, v84
	v_cvt_pk_bf16_f32 v90, v88, s0
	v_add_co_u32_e32 v88, vcc, 0x10000, v86
	s_nop 1
	v_addc_co_u32_e32 v89, vcc, 0, v87, vcc
	global_store_short v[88:89], v90, off
	v_mul_f32_e32 v88, v69, v84
	v_add_co_u32_e32 v86, vcc, 0x18000, v86
	v_cvt_pk_bf16_f32 v88, v88, s0
	s_nop 0
	v_addc_co_u32_e32 v87, vcc, 0, v87, vcc
	global_store_short v[86:87], v88, off
	s_andn2_saveexec_b64 s[0:1], s[0:1]
	s_cbranch_execz .LBB0_318
.LBB0_383:
	s_waitcnt lgkmcnt(0)
	v_pk_mul_f32 v[66:67], v[66:67], v[84:85] op_sel_hi:[1,0]
	v_pk_mul_f32 v[68:69], v[68:69], v[84:85] op_sel_hi:[1,0]
	s_lshl_b32 s62, s8, 14
	v_cvt_pk_bf16_f32 v66, v66, v67
	v_cvt_pk_bf16_f32 v67, v68, v69
	v_lshl_add_u64 v[68:69], v[82:83], 0, s[62:63]
	v_mad_u64_u32 v[86:87], s[12:13], v68, s86, v[132:133]
	v_mad_i32_i24 v87, v69, s86, v87
	v_lshl_add_u64 v[68:69], v[86:87], 0, v[0:1]
	global_store_dwordx2 v[68:69], v[66:67], off
	ds_read_b32 v84, v85
	s_or_b64 exec, exec, s[0:1]
	s_and_saveexec_b64 s[0:1], s[2:3]
	s_xor_b64 s[0:1], exec, s[0:1]
	s_cbranch_execz .LBB0_319
.LBB0_384:
	s_lshl_b32 s11, s8, 22
	v_mov_b32_e32 v141, v1
	s_add_u32 s12, s9, s11
	s_addc_u32 s13, s10, 0
	v_lshlrev_b64 v[66:67], 15, v[140:141]
	v_lshl_add_u64 v[66:67], s[12:13], 0, v[66:67]
	s_waitcnt lgkmcnt(0)
	v_mul_f32_e32 v68, v70, v84
	v_lshl_add_u64 v[66:67], v[82:83], 1, v[66:67]
	v_cvt_pk_bf16_f32 v68, v68, s0
	global_store_short v[66:67], v68, off
	v_mul_f32_e32 v68, v71, v84
	v_cvt_pk_bf16_f32 v86, v68, s0
	v_add_co_u32_e32 v68, vcc, 0x8000, v66
	s_nop 1
	v_addc_co_u32_e32 v69, vcc, 0, v67, vcc
	global_store_short v[68:69], v86, off
	v_mul_f32_e32 v68, v72, v84
	v_cvt_pk_bf16_f32 v86, v68, s0
	v_add_co_u32_e32 v68, vcc, 0x10000, v66
	s_nop 1
	v_addc_co_u32_e32 v69, vcc, 0, v67, vcc
	global_store_short v[68:69], v86, off
	v_mul_f32_e32 v68, v73, v84
	v_add_co_u32_e32 v66, vcc, 0x18000, v66
	v_cvt_pk_bf16_f32 v68, v68, s0
	s_nop 0
	v_addc_co_u32_e32 v67, vcc, 0, v67, vcc
	global_store_short v[66:67], v68, off
	s_andn2_saveexec_b64 s[0:1], s[0:1]
	s_cbranch_execz .LBB0_320
.LBB0_385:
	s_waitcnt lgkmcnt(0)
	v_pk_mul_f32 v[66:67], v[70:71], v[84:85] op_sel_hi:[1,0]
	v_pk_mul_f32 v[68:69], v[72:73], v[84:85] op_sel_hi:[1,0]
	s_lshl_b32 s62, s8, 14
	v_cvt_pk_bf16_f32 v66, v66, v67
	v_cvt_pk_bf16_f32 v67, v68, v69
	v_lshl_add_u64 v[68:69], v[82:83], 0, s[62:63]
	v_mad_u64_u32 v[70:71], s[12:13], v68, s86, v[132:133]
	v_mad_i32_i24 v71, v69, s86, v71
	v_lshl_add_u64 v[68:69], v[70:71], 0, v[0:1]
	global_store_dwordx2 v[68:69], v[66:67], off offset:16
	ds_read_b32 v84, v85
	s_or_b64 exec, exec, s[0:1]
	s_and_saveexec_b64 s[0:1], s[2:3]
	s_xor_b64 s[0:1], exec, s[0:1]
	s_cbranch_execz .LBB0_321
.LBB0_386:
	s_lshl_b32 s11, s8, 22
	v_mov_b32_e32 v143, v1
	s_add_u32 s12, s9, s11
	s_addc_u32 s13, s10, 0
	v_lshlrev_b64 v[66:67], 15, v[142:143]
	v_lshl_add_u64 v[66:67], s[12:13], 0, v[66:67]
	s_waitcnt lgkmcnt(0)
	v_mul_f32_e32 v68, v74, v84
	v_lshl_add_u64 v[66:67], v[82:83], 1, v[66:67]
	v_cvt_pk_bf16_f32 v68, v68, s0
	global_store_short v[66:67], v68, off
	v_mul_f32_e32 v68, v75, v84
	v_cvt_pk_bf16_f32 v70, v68, s0
	v_add_co_u32_e32 v68, vcc, 0x8000, v66
	s_nop 1
	v_addc_co_u32_e32 v69, vcc, 0, v67, vcc
	global_store_short v[68:69], v70, off
	v_mul_f32_e32 v68, v76, v84
	v_cvt_pk_bf16_f32 v70, v68, s0
	v_add_co_u32_e32 v68, vcc, 0x10000, v66
	s_nop 1
	v_addc_co_u32_e32 v69, vcc, 0, v67, vcc
	global_store_short v[68:69], v70, off
	v_mul_f32_e32 v68, v77, v84
	v_add_co_u32_e32 v66, vcc, 0x18000, v66
	v_cvt_pk_bf16_f32 v68, v68, s0
	s_nop 0
	v_addc_co_u32_e32 v67, vcc, 0, v67, vcc
	global_store_short v[66:67], v68, off
	s_andn2_saveexec_b64 s[0:1], s[0:1]
	s_cbranch_execz .LBB0_322
.LBB0_387:
	s_waitcnt lgkmcnt(0)
	v_pk_mul_f32 v[66:67], v[74:75], v[84:85] op_sel_hi:[1,0]
	v_pk_mul_f32 v[68:69], v[76:77], v[84:85] op_sel_hi:[1,0]
	s_lshl_b32 s62, s8, 14
	v_cvt_pk_bf16_f32 v66, v66, v67
	v_cvt_pk_bf16_f32 v67, v68, v69
	v_lshl_add_u64 v[68:69], v[82:83], 0, s[62:63]
	v_mad_u64_u32 v[70:71], s[12:13], v68, s86, v[132:133]
	v_mad_i32_i24 v71, v69, s86, v71
	v_lshl_add_u64 v[68:69], v[70:71], 0, v[0:1]
	global_store_dwordx2 v[68:69], v[66:67], off offset:32
	ds_read_b32 v84, v85
	s_or_b64 exec, exec, s[0:1]
	s_and_saveexec_b64 s[0:1], s[2:3]
	s_xor_b64 s[0:1], exec, s[0:1]
	s_cbranch_execz .LBB0_323
.LBB0_388:
	s_lshl_b32 s11, s8, 22
	v_mov_b32_e32 v139, v1
	s_add_u32 s12, s9, s11
	s_addc_u32 s13, s10, 0
	v_lshlrev_b64 v[66:67], 15, v[138:139]
	v_lshl_add_u64 v[66:67], s[12:13], 0, v[66:67]
	s_waitcnt lgkmcnt(0)
	v_mul_f32_e32 v68, v78, v84
	v_lshl_add_u64 v[66:67], v[82:83], 1, v[66:67]
	v_cvt_pk_bf16_f32 v68, v68, s0
	global_store_short v[66:67], v68, off
	v_mul_f32_e32 v68, v79, v84
	v_cvt_pk_bf16_f32 v70, v68, s0
	v_add_co_u32_e32 v68, vcc, 0x8000, v66
	s_nop 1
	v_addc_co_u32_e32 v69, vcc, 0, v67, vcc
	global_store_short v[68:69], v70, off
	v_mul_f32_e32 v68, v80, v84
	v_cvt_pk_bf16_f32 v70, v68, s0
	v_add_co_u32_e32 v68, vcc, 0x10000, v66
	s_nop 1
	v_addc_co_u32_e32 v69, vcc, 0, v67, vcc
	global_store_short v[68:69], v70, off
	v_mul_f32_e32 v68, v81, v84
	v_add_co_u32_e32 v66, vcc, 0x18000, v66
	v_cvt_pk_bf16_f32 v68, v68, s0
	s_nop 0
	v_addc_co_u32_e32 v67, vcc, 0, v67, vcc
	global_store_short v[66:67], v68, off
	s_andn2_saveexec_b64 s[0:1], s[0:1]
	s_cbranch_execnz .LBB0_324
	s_branch .LBB0_325
.LBB0_389:
	s_lshl_b32 s11, s8, 22
	v_mov_b32_e32 v69, v1
	s_add_u32 s12, s9, s11
	s_addc_u32 s13, s10, 0
	v_lshlrev_b64 v[52:53], 15, v[68:69]
	v_lshl_add_u64 v[52:53], s[12:13], 0, v[52:53]
	s_waitcnt lgkmcnt(0)
	v_mul_f32_e32 v51, v34, v50
	v_lshl_add_u64 v[52:53], v[114:115], 1, v[52:53]
	v_cvt_pk_bf16_f32 v51, v51, s0
	global_store_short v[52:53], v51, off
	v_mul_f32_e32 v51, v35, v50
	v_add_co_u32_e32 v54, vcc, 0x8000, v52
	v_cvt_pk_bf16_f32 v51, v51, s0
	s_nop 0
	v_addc_co_u32_e32 v55, vcc, 0, v53, vcc
	global_store_short v[54:55], v51, off
	v_mul_f32_e32 v51, v36, v50
	v_add_co_u32_e32 v54, vcc, 0x10000, v52
	v_cvt_pk_bf16_f32 v51, v51, s0
	s_nop 0
	v_addc_co_u32_e32 v55, vcc, 0, v53, vcc
	global_store_short v[54:55], v51, off
	v_mul_f32_e32 v51, v37, v50
	v_add_co_u32_e32 v52, vcc, 0x18000, v52
	v_cvt_pk_bf16_f32 v51, v51, s0
	s_nop 0
	v_addc_co_u32_e32 v53, vcc, 0, v53, vcc
	global_store_short v[52:53], v51, off
	s_andn2_saveexec_b64 s[0:1], s[0:1]
	s_cbranch_execz .LBB0_343
.LBB0_390:
	s_waitcnt lgkmcnt(0)
	v_pk_mul_f32 v[34:35], v[34:35], v[50:51] op_sel_hi:[1,0]
	v_pk_mul_f32 v[36:37], v[36:37], v[50:51] op_sel_hi:[1,0]
	s_lshl_b32 s62, s8, 14
	v_cvt_pk_bf16_f32 v34, v34, v35
	v_cvt_pk_bf16_f32 v35, v36, v37
	v_lshl_add_u64 v[36:37], v[114:115], 0, s[62:63]
	v_mad_u64_u32 v[50:51], s[12:13], v36, s86, v[132:133]
	v_mad_i32_i24 v51, v37, s86, v51
	v_lshl_add_u64 v[36:37], v[50:51], 0, v[0:1]
	global_store_dwordx2 v[36:37], v[34:35], off offset:64
	ds_read_b32 v50, v117
	s_or_b64 exec, exec, s[0:1]
	s_and_saveexec_b64 s[0:1], s[2:3]
	s_xor_b64 s[0:1], exec, s[0:1]
	s_cbranch_execz .LBB0_344
.LBB0_391:
	s_lshl_b32 s11, s8, 22
	v_mov_b32_e32 v73, v1
	s_add_u32 s12, s9, s11
	s_addc_u32 s13, s10, 0
	v_lshlrev_b64 v[34:35], 15, v[72:73]
	v_lshl_add_u64 v[34:35], s[12:13], 0, v[34:35]
	s_waitcnt lgkmcnt(0)
	v_mul_f32_e32 v36, v38, v50
	v_lshl_add_u64 v[34:35], v[114:115], 1, v[34:35]
	v_cvt_pk_bf16_f32 v36, v36, s0
	global_store_short v[34:35], v36, off
	v_mul_f32_e32 v36, v39, v50
	v_cvt_pk_bf16_f32 v51, v36, s0
	v_add_co_u32_e32 v36, vcc, 0x8000, v34
	s_nop 1
	v_addc_co_u32_e32 v37, vcc, 0, v35, vcc
	global_store_short v[36:37], v51, off
	v_mul_f32_e32 v36, v40, v50
	v_cvt_pk_bf16_f32 v51, v36, s0
	v_add_co_u32_e32 v36, vcc, 0x10000, v34
	s_nop 1
	v_addc_co_u32_e32 v37, vcc, 0, v35, vcc
	global_store_short v[36:37], v51, off
	v_mul_f32_e32 v36, v41, v50
	v_add_co_u32_e32 v34, vcc, 0x18000, v34
	v_cvt_pk_bf16_f32 v36, v36, s0
	s_nop 0
	v_addc_co_u32_e32 v35, vcc, 0, v35, vcc
	global_store_short v[34:35], v36, off
	s_andn2_saveexec_b64 s[0:1], s[0:1]
	s_cbranch_execz .LBB0_345
.LBB0_392:
	s_waitcnt lgkmcnt(0)
	v_pk_mul_f32 v[34:35], v[38:39], v[50:51] op_sel_hi:[1,0]
	v_pk_mul_f32 v[36:37], v[40:41], v[50:51] op_sel_hi:[1,0]
	s_lshl_b32 s62, s8, 14
	v_cvt_pk_bf16_f32 v34, v34, v35
	v_cvt_pk_bf16_f32 v35, v36, v37
	v_lshl_add_u64 v[36:37], v[114:115], 0, s[62:63]
	v_mad_u64_u32 v[38:39], s[12:13], v36, s86, v[132:133]
	v_mad_i32_i24 v39, v37, s86, v39
	v_lshl_add_u64 v[36:37], v[38:39], 0, v[0:1]
	global_store_dwordx2 v[36:37], v[34:35], off offset:80
	ds_read_b32 v50, v117
	s_or_b64 exec, exec, s[0:1]
	s_and_saveexec_b64 s[0:1], s[2:3]
	s_xor_b64 s[0:1], exec, s[0:1]
	s_cbranch_execz .LBB0_346
.LBB0_393:
	s_lshl_b32 s11, s8, 22
	v_mov_b32_e32 v71, v1
	s_add_u32 s12, s9, s11
	s_addc_u32 s13, s10, 0
	v_lshlrev_b64 v[34:35], 15, v[70:71]
	v_lshl_add_u64 v[34:35], s[12:13], 0, v[34:35]
	s_waitcnt lgkmcnt(0)
	v_mul_f32_e32 v36, v42, v50
	v_lshl_add_u64 v[34:35], v[114:115], 1, v[34:35]
	v_cvt_pk_bf16_f32 v36, v36, s0
	global_store_short v[34:35], v36, off
	v_mul_f32_e32 v36, v43, v50
	v_cvt_pk_bf16_f32 v38, v36, s0
	v_add_co_u32_e32 v36, vcc, 0x8000, v34
	s_nop 1
	v_addc_co_u32_e32 v37, vcc, 0, v35, vcc
	global_store_short v[36:37], v38, off
	v_mul_f32_e32 v36, v44, v50
	v_cvt_pk_bf16_f32 v38, v36, s0
	v_add_co_u32_e32 v36, vcc, 0x10000, v34
	s_nop 1
	v_addc_co_u32_e32 v37, vcc, 0, v35, vcc
	global_store_short v[36:37], v38, off
	v_mul_f32_e32 v36, v45, v50
	v_add_co_u32_e32 v34, vcc, 0x18000, v34
	v_cvt_pk_bf16_f32 v36, v36, s0
	s_nop 0
	v_addc_co_u32_e32 v35, vcc, 0, v35, vcc
	global_store_short v[34:35], v36, off
	s_andn2_saveexec_b64 s[0:1], s[0:1]
	s_cbranch_execz .LBB0_347
.LBB0_394:
	s_waitcnt lgkmcnt(0)
	v_pk_mul_f32 v[34:35], v[42:43], v[50:51] op_sel_hi:[1,0]
	v_pk_mul_f32 v[36:37], v[44:45], v[50:51] op_sel_hi:[1,0]
	s_lshl_b32 s62, s8, 14
	v_cvt_pk_bf16_f32 v34, v34, v35
	v_cvt_pk_bf16_f32 v35, v36, v37
	v_lshl_add_u64 v[36:37], v[114:115], 0, s[62:63]
	v_mad_u64_u32 v[38:39], s[12:13], v36, s86, v[132:133]
	v_mad_i32_i24 v39, v37, s86, v39
	v_lshl_add_u64 v[36:37], v[38:39], 0, v[0:1]
	global_store_dwordx2 v[36:37], v[34:35], off offset:96
	ds_read_b32 v50, v117
	s_or_b64 exec, exec, s[0:1]
	s_and_saveexec_b64 s[0:1], s[2:3]
	s_xor_b64 s[0:1], exec, s[0:1]
	s_cbranch_execz .LBB0_348
.LBB0_395:
	s_lshl_b32 s11, s8, 22
	v_mov_b32_e32 v67, v1
	s_add_u32 s12, s9, s11
	s_addc_u32 s13, s10, 0
	v_lshlrev_b64 v[34:35], 15, v[66:67]
	v_lshl_add_u64 v[34:35], s[12:13], 0, v[34:35]
	s_waitcnt lgkmcnt(0)
	v_mul_f32_e32 v36, v46, v50
	v_lshl_add_u64 v[34:35], v[114:115], 1, v[34:35]
	v_cvt_pk_bf16_f32 v36, v36, s0
	global_store_short v[34:35], v36, off
	v_mul_f32_e32 v36, v47, v50
	v_cvt_pk_bf16_f32 v38, v36, s0
	v_add_co_u32_e32 v36, vcc, 0x8000, v34
	s_nop 1
	v_addc_co_u32_e32 v37, vcc, 0, v35, vcc
	global_store_short v[36:37], v38, off
	v_mul_f32_e32 v36, v48, v50
	v_cvt_pk_bf16_f32 v38, v36, s0
	v_add_co_u32_e32 v36, vcc, 0x10000, v34
	s_nop 1
	v_addc_co_u32_e32 v37, vcc, 0, v35, vcc
	global_store_short v[36:37], v38, off
	v_mul_f32_e32 v36, v49, v50
	v_add_co_u32_e32 v34, vcc, 0x18000, v34
	v_cvt_pk_bf16_f32 v36, v36, s0
	s_nop 0
	v_addc_co_u32_e32 v35, vcc, 0, v35, vcc
	global_store_short v[34:35], v36, off
	s_andn2_saveexec_b64 s[0:1], s[0:1]
	s_cbranch_execnz .LBB0_349
	s_branch .LBB0_350
.LBB0_396:
	s_lshl_b32 s11, s8, 22
	v_mov_b32_e32 v69, v1
	s_add_u32 s12, s9, s11
	s_addc_u32 s13, s10, 0
	v_lshlrev_b64 v[36:37], 15, v[68:69]
	v_lshl_add_u64 v[36:37], s[12:13], 0, v[36:37]
	s_waitcnt lgkmcnt(0)
	v_mul_f32_e32 v35, v18, v34
	v_lshl_add_u64 v[36:37], v[98:99], 1, v[36:37]
	v_cvt_pk_bf16_f32 v35, v35, s0
	global_store_short v[36:37], v35, off
	v_mul_f32_e32 v35, v19, v34
	v_add_co_u32_e32 v38, vcc, 0x8000, v36
	v_cvt_pk_bf16_f32 v35, v35, s0
	s_nop 0
	v_addc_co_u32_e32 v39, vcc, 0, v37, vcc
	global_store_short v[38:39], v35, off
	v_mul_f32_e32 v35, v20, v34
	v_add_co_u32_e32 v38, vcc, 0x10000, v36
	v_cvt_pk_bf16_f32 v35, v35, s0
	s_nop 0
	v_addc_co_u32_e32 v39, vcc, 0, v37, vcc
	global_store_short v[38:39], v35, off
	v_mul_f32_e32 v35, v21, v34
	v_add_co_u32_e32 v36, vcc, 0x18000, v36
	v_cvt_pk_bf16_f32 v35, v35, s0
	s_nop 0
	v_addc_co_u32_e32 v37, vcc, 0, v37, vcc
	global_store_short v[36:37], v35, off
	s_andn2_saveexec_b64 s[0:1], s[0:1]
	s_cbranch_execz .LBB0_352
.LBB0_397:
	s_waitcnt lgkmcnt(0)
	v_pk_mul_f32 v[18:19], v[18:19], v[34:35] op_sel_hi:[1,0]
	v_pk_mul_f32 v[20:21], v[20:21], v[34:35] op_sel_hi:[1,0]
	s_lshl_b32 s62, s8, 14
	v_cvt_pk_bf16_f32 v18, v18, v19
	v_cvt_pk_bf16_f32 v19, v20, v21
	v_lshl_add_u64 v[20:21], v[98:99], 0, s[62:63]
	v_mad_u64_u32 v[34:35], s[12:13], v20, s86, v[132:133]
	v_mad_i32_i24 v35, v21, s86, v35
	v_lshl_add_u64 v[20:21], v[34:35], 0, v[0:1]
	global_store_dwordx2 v[20:21], v[18:19], off offset:64
	ds_read_b32 v34, v101
	s_or_b64 exec, exec, s[0:1]
	s_and_saveexec_b64 s[0:1], s[2:3]
	s_xor_b64 s[0:1], exec, s[0:1]
	s_cbranch_execz .LBB0_353
.LBB0_398:
	s_lshl_b32 s11, s8, 22
	v_mov_b32_e32 v73, v1
	s_add_u32 s12, s9, s11
	s_addc_u32 s13, s10, 0
	v_lshlrev_b64 v[18:19], 15, v[72:73]
	v_lshl_add_u64 v[18:19], s[12:13], 0, v[18:19]
	s_waitcnt lgkmcnt(0)
	v_mul_f32_e32 v20, v22, v34
	v_lshl_add_u64 v[18:19], v[98:99], 1, v[18:19]
	v_cvt_pk_bf16_f32 v20, v20, s0
	global_store_short v[18:19], v20, off
	v_mul_f32_e32 v20, v23, v34
	v_cvt_pk_bf16_f32 v35, v20, s0
	v_add_co_u32_e32 v20, vcc, 0x8000, v18
	s_nop 1
	v_addc_co_u32_e32 v21, vcc, 0, v19, vcc
	global_store_short v[20:21], v35, off
	v_mul_f32_e32 v20, v24, v34
	v_cvt_pk_bf16_f32 v35, v20, s0
	v_add_co_u32_e32 v20, vcc, 0x10000, v18
	s_nop 1
	v_addc_co_u32_e32 v21, vcc, 0, v19, vcc
	global_store_short v[20:21], v35, off
	v_mul_f32_e32 v20, v25, v34
	v_add_co_u32_e32 v18, vcc, 0x18000, v18
	v_cvt_pk_bf16_f32 v20, v20, s0
	s_nop 0
	v_addc_co_u32_e32 v19, vcc, 0, v19, vcc
	global_store_short v[18:19], v20, off
	s_andn2_saveexec_b64 s[0:1], s[0:1]
	s_cbranch_execz .LBB0_354
.LBB0_399:
	s_waitcnt lgkmcnt(0)
	v_pk_mul_f32 v[18:19], v[22:23], v[34:35] op_sel_hi:[1,0]
	v_pk_mul_f32 v[20:21], v[24:25], v[34:35] op_sel_hi:[1,0]
	s_lshl_b32 s62, s8, 14
	v_cvt_pk_bf16_f32 v18, v18, v19
	v_cvt_pk_bf16_f32 v19, v20, v21
	v_lshl_add_u64 v[20:21], v[98:99], 0, s[62:63]
	v_mad_u64_u32 v[22:23], s[12:13], v20, s86, v[132:133]
	v_mad_i32_i24 v23, v21, s86, v23
	v_lshl_add_u64 v[20:21], v[22:23], 0, v[0:1]
	global_store_dwordx2 v[20:21], v[18:19], off offset:80
	ds_read_b32 v34, v101
	s_or_b64 exec, exec, s[0:1]
	s_and_saveexec_b64 s[0:1], s[2:3]
	s_xor_b64 s[0:1], exec, s[0:1]
	s_cbranch_execz .LBB0_355
.LBB0_400:
	s_lshl_b32 s11, s8, 22
	v_mov_b32_e32 v71, v1
	s_add_u32 s12, s9, s11
	s_addc_u32 s13, s10, 0
	v_lshlrev_b64 v[18:19], 15, v[70:71]
	v_lshl_add_u64 v[18:19], s[12:13], 0, v[18:19]
	s_waitcnt lgkmcnt(0)
	v_mul_f32_e32 v20, v26, v34
	v_lshl_add_u64 v[18:19], v[98:99], 1, v[18:19]
	v_cvt_pk_bf16_f32 v20, v20, s0
	global_store_short v[18:19], v20, off
	v_mul_f32_e32 v20, v27, v34
	v_cvt_pk_bf16_f32 v22, v20, s0
	v_add_co_u32_e32 v20, vcc, 0x8000, v18
	s_nop 1
	v_addc_co_u32_e32 v21, vcc, 0, v19, vcc
	global_store_short v[20:21], v22, off
	v_mul_f32_e32 v20, v28, v34
	v_cvt_pk_bf16_f32 v22, v20, s0
	v_add_co_u32_e32 v20, vcc, 0x10000, v18
	s_nop 1
	v_addc_co_u32_e32 v21, vcc, 0, v19, vcc
	global_store_short v[20:21], v22, off
	v_mul_f32_e32 v20, v29, v34
	v_add_co_u32_e32 v18, vcc, 0x18000, v18
	v_cvt_pk_bf16_f32 v20, v20, s0
	s_nop 0
	v_addc_co_u32_e32 v19, vcc, 0, v19, vcc
	global_store_short v[18:19], v20, off
	s_andn2_saveexec_b64 s[0:1], s[0:1]
	s_cbranch_execz .LBB0_356
.LBB0_401:
	s_waitcnt lgkmcnt(0)
	v_pk_mul_f32 v[18:19], v[26:27], v[34:35] op_sel_hi:[1,0]
	v_pk_mul_f32 v[20:21], v[28:29], v[34:35] op_sel_hi:[1,0]
	s_lshl_b32 s62, s8, 14
	v_cvt_pk_bf16_f32 v18, v18, v19
	v_cvt_pk_bf16_f32 v19, v20, v21
	v_lshl_add_u64 v[20:21], v[98:99], 0, s[62:63]
	v_mad_u64_u32 v[22:23], s[12:13], v20, s86, v[132:133]
	v_mad_i32_i24 v23, v21, s86, v23
	v_lshl_add_u64 v[20:21], v[22:23], 0, v[0:1]
	global_store_dwordx2 v[20:21], v[18:19], off offset:96
	ds_read_b32 v34, v101
	s_or_b64 exec, exec, s[0:1]
	s_and_saveexec_b64 s[0:1], s[2:3]
	s_xor_b64 s[0:1], exec, s[0:1]
	s_cbranch_execz .LBB0_357
.LBB0_402:
	s_lshl_b32 s11, s8, 22
	v_mov_b32_e32 v67, v1
	s_add_u32 s12, s9, s11
	s_addc_u32 s13, s10, 0
	v_lshlrev_b64 v[18:19], 15, v[66:67]
	v_lshl_add_u64 v[18:19], s[12:13], 0, v[18:19]
	s_waitcnt lgkmcnt(0)
	v_mul_f32_e32 v20, v30, v34
	v_lshl_add_u64 v[18:19], v[98:99], 1, v[18:19]
	v_cvt_pk_bf16_f32 v20, v20, s0
	global_store_short v[18:19], v20, off
	v_mul_f32_e32 v20, v31, v34
	v_cvt_pk_bf16_f32 v22, v20, s0
	v_add_co_u32_e32 v20, vcc, 0x8000, v18
	s_nop 1
	v_addc_co_u32_e32 v21, vcc, 0, v19, vcc
	global_store_short v[20:21], v22, off
	v_mul_f32_e32 v20, v32, v34
	v_cvt_pk_bf16_f32 v22, v20, s0
	v_add_co_u32_e32 v20, vcc, 0x10000, v18
	s_nop 1
	v_addc_co_u32_e32 v21, vcc, 0, v19, vcc
	global_store_short v[20:21], v22, off
	v_mul_f32_e32 v20, v33, v34
	v_add_co_u32_e32 v18, vcc, 0x18000, v18
	v_cvt_pk_bf16_f32 v20, v20, s0
	s_nop 0
	v_addc_co_u32_e32 v19, vcc, 0, v19, vcc
	global_store_short v[18:19], v20, off
	s_andn2_saveexec_b64 s[0:1], s[0:1]
	s_cbranch_execnz .LBB0_358
	s_branch .LBB0_359
; DI void mla_kv_tile(const Params& P, int pm, int pn, char* smem) {
;     ...
;   if (pn == 0) {
.LBB0_403:
	s_lshl_b32 s11, s8, 22
	v_mov_b32_e32 v69, v1
	s_add_u32 s12, s9, s11
	s_addc_u32 s13, s10, 0
	v_lshlrev_b64 v[20:21], 15, v[68:69]
	v_lshl_add_u64 v[20:21], s[12:13], 0, v[20:21]
	s_waitcnt lgkmcnt(0)
	v_mul_f32_e32 v19, v2, v18
	v_lshl_add_u64 v[20:21], v[82:83], 1, v[20:21]
	v_cvt_pk_bf16_f32 v19, v19, s0
	global_store_short v[20:21], v19, off
	v_mul_f32_e32 v19, v3, v18
	v_add_co_u32_e32 v22, vcc, 0x8000, v20
	v_cvt_pk_bf16_f32 v19, v19, s0
	s_nop 0
	v_addc_co_u32_e32 v23, vcc, 0, v21, vcc
	global_store_short v[22:23], v19, off
	v_mul_f32_e32 v19, v4, v18
	v_add_co_u32_e32 v22, vcc, 0x10000, v20
	v_cvt_pk_bf16_f32 v19, v19, s0
	s_nop 0
	v_addc_co_u32_e32 v23, vcc, 0, v21, vcc
	global_store_short v[22:23], v19, off
	v_mul_f32_e32 v19, v5, v18
	v_add_co_u32_e32 v20, vcc, 0x18000, v20
	v_cvt_pk_bf16_f32 v19, v19, s0
	s_nop 0
	v_addc_co_u32_e32 v21, vcc, 0, v21, vcc
	global_store_short v[20:21], v19, off
	s_andn2_saveexec_b64 s[0:1], s[0:1]
	s_cbranch_execz .LBB0_361
.LBB0_404:
	s_waitcnt lgkmcnt(0)
	v_pk_mul_f32 v[2:3], v[2:3], v[18:19] op_sel_hi:[1,0]
	v_pk_mul_f32 v[4:5], v[4:5], v[18:19] op_sel_hi:[1,0]
	s_lshl_b32 s62, s8, 14
	v_cvt_pk_bf16_f32 v2, v2, v3
	v_cvt_pk_bf16_f32 v3, v4, v5
	v_lshl_add_u64 v[4:5], v[82:83], 0, s[62:63]
	v_mad_u64_u32 v[18:19], s[12:13], v4, s86, v[132:133]
	v_mad_i32_i24 v19, v5, s86, v19
	v_lshl_add_u64 v[4:5], v[18:19], 0, v[0:1]
	global_store_dwordx2 v[4:5], v[2:3], off offset:64
	ds_read_b32 v18, v85
	s_or_b64 exec, exec, s[0:1]
	s_and_saveexec_b64 s[0:1], s[2:3]
	s_xor_b64 s[0:1], exec, s[0:1]
	s_cbranch_execz .LBB0_362
.LBB0_405:
	s_lshl_b32 s11, s8, 22
	v_mov_b32_e32 v73, v1
	s_add_u32 s12, s9, s11
	s_addc_u32 s13, s10, 0
	v_lshlrev_b64 v[2:3], 15, v[72:73]
	v_lshl_add_u64 v[2:3], s[12:13], 0, v[2:3]
	s_waitcnt lgkmcnt(0)
	v_mul_f32_e32 v4, v6, v18
	v_lshl_add_u64 v[2:3], v[82:83], 1, v[2:3]
	v_cvt_pk_bf16_f32 v4, v4, s0
	global_store_short v[2:3], v4, off
	v_mul_f32_e32 v4, v7, v18
	v_cvt_pk_bf16_f32 v19, v4, s0
	v_add_co_u32_e32 v4, vcc, 0x8000, v2
	s_nop 1
	v_addc_co_u32_e32 v5, vcc, 0, v3, vcc
	global_store_short v[4:5], v19, off
	v_mul_f32_e32 v4, v8, v18
	v_cvt_pk_bf16_f32 v19, v4, s0
	v_add_co_u32_e32 v4, vcc, 0x10000, v2
	s_nop 1
	v_addc_co_u32_e32 v5, vcc, 0, v3, vcc
	global_store_short v[4:5], v19, off
	v_mul_f32_e32 v4, v9, v18
	v_add_co_u32_e32 v2, vcc, 0x18000, v2
	v_cvt_pk_bf16_f32 v4, v4, s0
	s_nop 0
	v_addc_co_u32_e32 v3, vcc, 0, v3, vcc
	global_store_short v[2:3], v4, off
	s_andn2_saveexec_b64 s[0:1], s[0:1]
	s_cbranch_execz .LBB0_363
.LBB0_406:
	s_waitcnt lgkmcnt(0)
	v_pk_mul_f32 v[2:3], v[6:7], v[18:19] op_sel_hi:[1,0]
	v_pk_mul_f32 v[4:5], v[8:9], v[18:19] op_sel_hi:[1,0]
	s_lshl_b32 s62, s8, 14
	v_cvt_pk_bf16_f32 v2, v2, v3
	v_cvt_pk_bf16_f32 v3, v4, v5
	v_lshl_add_u64 v[4:5], v[82:83], 0, s[62:63]
	v_mad_u64_u32 v[6:7], s[12:13], v4, s86, v[132:133]
	v_mad_i32_i24 v7, v5, s86, v7
	v_lshl_add_u64 v[4:5], v[6:7], 0, v[0:1]
	global_store_dwordx2 v[4:5], v[2:3], off offset:80
	ds_read_b32 v18, v85
	s_or_b64 exec, exec, s[0:1]
	s_and_saveexec_b64 s[0:1], s[2:3]
	s_xor_b64 s[0:1], exec, s[0:1]
	s_cbranch_execz .LBB0_364
.LBB0_407:
	s_lshl_b32 s11, s8, 22
	v_mov_b32_e32 v71, v1
	s_add_u32 s12, s9, s11
	s_addc_u32 s13, s10, 0
	v_lshlrev_b64 v[2:3], 15, v[70:71]
	v_lshl_add_u64 v[2:3], s[12:13], 0, v[2:3]
	s_waitcnt lgkmcnt(0)
	v_mul_f32_e32 v4, v10, v18
	v_lshl_add_u64 v[2:3], v[82:83], 1, v[2:3]
	v_cvt_pk_bf16_f32 v4, v4, s0
	global_store_short v[2:3], v4, off
	v_mul_f32_e32 v4, v11, v18
	v_cvt_pk_bf16_f32 v6, v4, s0
	v_add_co_u32_e32 v4, vcc, 0x8000, v2
	s_nop 1
	v_addc_co_u32_e32 v5, vcc, 0, v3, vcc
	global_store_short v[4:5], v6, off
	v_mul_f32_e32 v4, v12, v18
	v_cvt_pk_bf16_f32 v6, v4, s0
	v_add_co_u32_e32 v4, vcc, 0x10000, v2
	s_nop 1
	v_addc_co_u32_e32 v5, vcc, 0, v3, vcc
	global_store_short v[4:5], v6, off
	v_mul_f32_e32 v4, v13, v18
	v_add_co_u32_e32 v2, vcc, 0x18000, v2
	v_cvt_pk_bf16_f32 v4, v4, s0
	s_nop 0
	v_addc_co_u32_e32 v3, vcc, 0, v3, vcc
	global_store_short v[2:3], v4, off
	s_andn2_saveexec_b64 s[0:1], s[0:1]
	s_cbranch_execz .LBB0_365
.LBB0_408:
	s_waitcnt lgkmcnt(0)
	v_pk_mul_f32 v[2:3], v[10:11], v[18:19] op_sel_hi:[1,0]
	v_pk_mul_f32 v[4:5], v[12:13], v[18:19] op_sel_hi:[1,0]
	s_lshl_b32 s62, s8, 14
	v_cvt_pk_bf16_f32 v2, v2, v3
	v_cvt_pk_bf16_f32 v3, v4, v5
	v_lshl_add_u64 v[4:5], v[82:83], 0, s[62:63]
	v_mad_u64_u32 v[6:7], s[12:13], v4, s86, v[132:133]
	v_mad_i32_i24 v7, v5, s86, v7
	v_lshl_add_u64 v[4:5], v[6:7], 0, v[0:1]
	global_store_dwordx2 v[4:5], v[2:3], off offset:96
	ds_read_b32 v18, v85
	s_or_b64 exec, exec, s[0:1]
	s_and_saveexec_b64 s[0:1], s[2:3]
	s_xor_b64 s[0:1], exec, s[0:1]
	s_cbranch_execz .LBB0_366
.LBB0_409:
	s_lshl_b32 s2, s8, 22
	v_mov_b32_e32 v67, v1
	s_add_u32 s2, s9, s2
	s_addc_u32 s3, s10, 0
	v_lshlrev_b64 v[2:3], 15, v[66:67]
	v_lshl_add_u64 v[2:3], s[2:3], 0, v[2:3]
	s_waitcnt lgkmcnt(0)
	v_mul_f32_e32 v0, v14, v18
	v_lshl_add_u64 v[2:3], v[82:83], 1, v[2:3]
	v_cvt_pk_bf16_f32 v0, v0, s0
	global_store_short v[2:3], v0, off
	v_mul_f32_e32 v0, v15, v18
	v_add_co_u32_e32 v4, vcc, 0x8000, v2
	v_cvt_pk_bf16_f32 v0, v0, s0
	s_nop 0
	v_addc_co_u32_e32 v5, vcc, 0, v3, vcc
	global_store_short v[4:5], v0, off
	v_mul_f32_e32 v0, v16, v18
	v_add_co_u32_e32 v4, vcc, 0x10000, v2
	v_cvt_pk_bf16_f32 v0, v0, s0
	s_nop 0
	v_addc_co_u32_e32 v5, vcc, 0, v3, vcc
	global_store_short v[4:5], v0, off
	v_mul_f32_e32 v0, v17, v18
	v_add_co_u32_e32 v2, vcc, 0x18000, v2
	v_cvt_pk_bf16_f32 v0, v0, s0
	s_nop 0
	v_addc_co_u32_e32 v3, vcc, 0, v3, vcc
	global_store_short v[2:3], v0, off
	s_andn2_saveexec_b64 s[0:1], s[0:1]
	s_cbranch_execz .LBB0_367
.LBB0_410:
	s_waitcnt lgkmcnt(0)
	v_pk_mul_f32 v[2:3], v[14:15], v[18:19] op_sel_hi:[1,0]
	v_pk_mul_f32 v[4:5], v[16:17], v[18:19] op_sel_hi:[1,0]
	s_lshl_b32 s62, s8, 14
	v_cvt_pk_bf16_f32 v2, v2, v3
	v_cvt_pk_bf16_f32 v3, v4, v5
	v_lshl_add_u64 v[4:5], v[82:83], 0, s[62:63]
	v_mad_u64_u32 v[6:7], s[2:3], v4, s86, v[132:133]
	v_mad_i32_i24 v7, v5, s86, v7
	v_lshl_add_u64 v[4:5], v[6:7], 0, v[0:1]
	global_store_dwordx2 v[4:5], v[2:3], off offset:112
	s_or_b64 exec, exec, s[0:1]
	s_cmp_lg_u32 s8, 0
	s_cbranch_scc1 .LBB0_413

; DI bf16_t f2bf(float x) { return (bf16_t)(pack2(x, 0.f) & 0xffffu); }
; DI float bflo(unsigned u) { return __uint_as_float(u << 16); }
; DI void mla_kv_tile(const Params& P, int pm, int pn, char* smem) {
;     ...
;     for (int i = 0; i < 16; ++i) { const int idx = tid + NT * i, row = idx >> 5, pi = idx & 31, m = m0 + row;
;       const float x1 = bflo((unsigned)proj[(size_t)m * DINP + C_BKR + pi]), x2 = bflo((unsigned)proj[(size_t)m * DINP + C_BKR + 32 + pi]);
;       double fr = (double)P.pos[m] * kInvFreq2Pi[pi]; fr -= floor(fr); const float ff = (float)fr;
;       const float sn = __builtin_amdgcn_sinf(ff), cs = __builtin_amdgcn_cosf(ff);
;       const bf16_t o1 = f2bf(x1 * cs - x2 * sn), o2 = f2bf(x2 * cs + x1 * sn);
; #pragma unroll
;       for (int hd = 0; hd < 4; ++hd) { bf16_t* kp = kmla + ((size_t)hd * S_ + m) * 192 + 128; kp[pi] = o1; kp[32 + pi] = o2; } }
.LBB0_412:
	v_add_u32_e32 v12, s0, v145
	v_ashrrev_i32_e32 v6, 5, v12
	v_add_u32_e32 v6, s5, v6
	v_mad_i64_i32 v[8:9], s[2:3], v6, s81, v[130:131]
	v_lshl_add_u64 v[8:9], v[8:9], 0, v[0:1]
	v_add_co_u32_e32 v8, vcc, 0x2000, v8
	v_ashrrev_i32_e32 v7, 31, v6
	s_nop 0
	v_addc_co_u32_e32 v9, vcc, 0, v9, vcc
	global_load_ushort v10, v[8:9], off offset:1184
	s_mov_b32 s1, 0xc00000
	global_load_ushort v8, v[8:9], off offset:1248
	s_waitcnt vmcnt(0) lgkmcnt(0)
	v_lshlrev_b32_e32 v13, 16, v10
	v_lshlrev_b32_e32 v14, 16, v8
	v_lshl_add_u64 v[8:9], v[6:7], 2, v[2:3]
	global_load_dword v7, v[8:9], off
	s_waitcnt vmcnt(0) lgkmcnt(0)
	v_cvt_f64_i32_e32 v[8:9], v7
	v_mul_f64 v[10:11], v[4:5], v[8:9]
	v_floor_f64_e32 v[10:11], v[10:11]
	v_fma_f64 v[8:9], v[4:5], v[8:9], -v[10:11]
	v_cvt_f32_f64_e32 v7, v[8:9]
	v_sin_f32_e32 v8, v7
	v_cos_f32_e32 v7, v7
	v_mul_f32_e32 v9, v8, v14
	v_mul_f32_e32 v8, v8, v13
	v_fma_f32 v9, v7, v13, -v9
	v_fmac_f32_e32 v8, v7, v14
	v_mad_i64_i32 v[6:7], s[2:3], v6, s86, v[132:133]
	v_lshl_add_u64 v[6:7], v[6:7], 0, v[0:1]
	v_add_co_u32_e32 v10, vcc, s87, v6
	v_cvt_pk_bf16_f32 v15, v9, s0
	s_nop 0
	v_addc_co_u32_e32 v11, vcc, 0, v7, vcc
	v_cvt_pk_bf16_f32 v13, v8, s0
	global_store_short v[6:7], v15, off offset:256
	global_store_short v[6:7], v13, off offset:320
	v_lshl_add_u64 v[8:9], v[6:7], 0, s[52:53]
	global_store_short v[10:11], v15, off offset:256
	global_store_short v[8:9], v13, off offset:64
	v_add_co_u32_e32 v10, vcc, s1, v6
	v_lshl_add_u64 v[8:9], v[6:7], 0, s[50:51]
	s_nop 0
	v_addc_co_u32_e32 v11, vcc, 0, v7, vcc
	s_mov_b32 s1, 0x1200000
	global_store_short v[10:11], v15, off offset:256
	global_store_short v[8:9], v13, off offset:64
	v_lshl_add_u64 v[8:9], v[6:7], 0, s[36:37]
	v_add_co_u32_e32 v6, vcc, s1, v6
	s_nop 1
	v_addc_co_u32_e32 v7, vcc, 0, v7, vcc
	global_store_short v[6:7], v15, off offset:256
	global_store_short v[8:9], v13, off offset:64
	v_add_u32_e32 v6, 0x200, v12
	v_ashrrev_i32_e32 v6, 5, v6
	v_add_u32_e32 v6, s5, v6
	v_mad_i64_i32 v[8:9], s[2:3], v6, s81, v[130:131]
	v_lshl_add_u64 v[8:9], v[8:9], 0, v[0:1]
	v_add_co_u32_e32 v8, vcc, s83, v8
	v_ashrrev_i32_e32 v7, 31, v6
	s_nop 0
	v_addc_co_u32_e32 v9, vcc, 0, v9, vcc
	global_load_ushort v10, v[8:9], off offset:1184
	s_waitcnt vmcnt(0) lgkmcnt(0)
	v_lshlrev_b32_e32 v12, 16, v10
	global_load_ushort v8, v[8:9], off offset:1248
	s_waitcnt vmcnt(0) lgkmcnt(0)
	v_lshlrev_b32_e32 v13, 16, v8
	v_lshl_add_u64 v[8:9], v[6:7], 2, v[2:3]
	global_load_dword v7, v[8:9], off
	s_waitcnt vmcnt(0) lgkmcnt(0)
	v_cvt_f64_i32_e32 v[8:9], v7
	v_mul_f64 v[10:11], v[4:5], v[8:9]
	v_floor_f64_e32 v[10:11], v[10:11]
	v_fma_f64 v[8:9], v[4:5], v[8:9], -v[10:11]
	v_cvt_f32_f64_e32 v7, v[8:9]
	v_sin_f32_e32 v8, v7
	v_cos_f32_e32 v7, v7
	v_mul_f32_e32 v9, v8, v13
	v_mul_f32_e32 v8, v8, v12
	v_fma_f32 v9, v7, v12, -v9
	v_fmac_f32_e32 v8, v7, v13
	v_mad_i64_i32 v[6:7], s[2:3], v6, s86, v[132:133]
	v_lshl_add_u64 v[6:7], v[6:7], 0, v[0:1]
	v_add_co_u32_e32 v10, vcc, s87, v6
	v_cvt_pk_bf16_f32 v14, v9, s0
	s_nop 0
	v_addc_co_u32_e32 v11, vcc, 0, v7, vcc
	v_cvt_pk_bf16_f32 v12, v8, s0
	global_store_short v[6:7], v14, off offset:256
	global_store_short v[6:7], v12, off offset:320
	v_lshl_add_u64 v[8:9], v[6:7], 0, s[52:53]
	global_store_short v[10:11], v14, off offset:256
	global_store_short v[8:9], v12, off offset:64
	v_add_co_u32_e32 v10, vcc, 0xc00000, v6
	v_lshl_add_u64 v[8:9], v[6:7], 0, s[50:51]
	s_nop 0
	v_addc_co_u32_e32 v11, vcc, 0, v7, vcc
	global_store_short v[10:11], v14, off offset:256
	global_store_short v[8:9], v12, off offset:64
	v_lshl_add_u64 v[8:9], v[6:7], 0, s[36:37]
	v_add_co_u32_e32 v6, vcc, 0x1200000, v6
	s_addk_i32 s0, 0x400
	s_nop 0
	v_addc_co_u32_e32 v7, vcc, 0, v7, vcc
	s_cmpk_lg_i32 s0, 0x2000
	global_store_short v[6:7], v14, off offset:256
	global_store_short v[8:9], v12, off offset:64
	s_cbranch_scc1 .LBB0_412

; DI void unpack8(const u32x4& v, float* f) { f[0] = bflo(v.x); f[1] = bfhi(v.x); f[2] = bflo(v.y); f[3] = bfhi(v.y); f[4] = bflo(v.z); f[5] = bfhi(v.z); f[6] = bflo(v.w); f[7] = bfhi(v.w); }
; DI int opaque_tid() { int t = threadIdx.x; asm volatile("" : "+v"(t)); return t; }
; DI void mla_q_tile(const Params& P, int pm, int pn, char* smem) {
;   const bf16_t* proj = (const bf16_t*)(P.ws + OFF_PROJ); const int tid = opaque_tid(), m0 = pm * 256; float* rs = (float*)(smem + 131072);
;   { const int row = tid >> 1, half = tid & 1; const bf16_t* p = proj + (size_t)(m0 + row) * DINP + C_BCQ + half * 224; float ss = 0.f;
;     for (int i = 0; i < 28; ++i) { const u32x4 v = *(const u32x4*)(p + i * 8); float f[8]; unpack8(v, f);
; #pragma unroll
;       for (int e = 0; e < 8; ++e) ss += f[e] * f[e]; }
;     ss += __shfl_xor(ss, 1); if (half == 0) rs[row] = rsqrtf(ss * (1.f / 448.f) + EPS); }
.LBB0_414:
	global_load_dwordx2 v[6:7], v1, s[40:41] offset:1224
	s_mul_hi_i32 s3, s4, 0x55555556
	s_lshr_b32 s0, s3, 31
	s_add_i32 s3, s3, s0
	v_mov_b32_e32 v0, v206
	s_lshl_b32 s2, s3, 8
	v_ashrrev_i32_e32 v8, 1, v0
	v_and_b32_e32 v9, 1, v0
	v_add_u32_e32 v0, s2, v8
	s_waitcnt vmcnt(0)
	v_mad_i64_i32 v[2:3], s[0:1], v0, s81, v[6:7]
	v_mul_u32_u24_e32 v0, 0xe0, v9
	v_lshlrev_b32_e32 v0, 1, v0
	v_lshl_add_u64 v[4:5], v[2:3], 0, v[0:1]
	s_mov_b64 s[0:1], 0x122ea020
	v_lshl_add_u64 v[2:3], v[4:5], 0, s[0:1]
	v_add_co_u32_e32 v4, vcc, s85, v4
	s_nop 1
	v_addc_co_u32_e32 v5, vcc, 0, v5, vcc
	global_load_dwordx4 v[10:13], v[4:5], off offset:32
	s_waitcnt vmcnt(0) lgkmcnt(0)
	v_and_b32_e32 v0, 0xffff0000, v10
	v_lshlrev_b32_e32 v4, 16, v10
	v_mul_f32_e32 v0, v0, v0
	v_lshlrev_b32_e32 v5, 16, v11
	v_fmac_f32_e32 v0, v4, v4
	v_and_b32_e32 v10, 0xffff0000, v11
	v_fmac_f32_e32 v0, v5, v5
	v_lshlrev_b32_e32 v11, 16, v12
	v_fmac_f32_e32 v0, v10, v10
	v_and_b32_e32 v12, 0xffff0000, v12
	v_fmac_f32_e32 v0, v11, v11
	v_lshlrev_b32_e32 v14, 16, v13
	v_fmac_f32_e32 v0, v12, v12
	v_and_b32_e32 v13, 0xffff0000, v13
	v_fmac_f32_e32 v0, v14, v14
	v_fmac_f32_e32 v0, v13, v13
	global_load_dwordx4 v[10:13], v[2:3], off offset:16
	s_waitcnt vmcnt(0) lgkmcnt(0)
	v_lshlrev_b32_e32 v4, 16, v10
	v_and_b32_e32 v5, 0xffff0000, v10
	v_fmac_f32_e32 v0, v4, v4
	v_lshlrev_b32_e32 v10, 16, v11
	v_fmac_f32_e32 v0, v5, v5
	v_and_b32_e32 v11, 0xffff0000, v11
	v_fmac_f32_e32 v0, v10, v10
	v_lshlrev_b32_e32 v14, 16, v12
	v_fmac_f32_e32 v0, v11, v11
	v_and_b32_e32 v12, 0xffff0000, v12
	v_fmac_f32_e32 v0, v14, v14
	v_lshlrev_b32_e32 v15, 16, v13
	v_fmac_f32_e32 v0, v12, v12
	v_and_b32_e32 v13, 0xffff0000, v13
	v_fmac_f32_e32 v0, v15, v15
	v_fmac_f32_e32 v0, v13, v13
	global_load_dwordx4 v[10:13], v[2:3], off offset:32
	s_waitcnt vmcnt(0) lgkmcnt(0)
	v_lshlrev_b32_e32 v4, 16, v10
	v_and_b32_e32 v5, 0xffff0000, v10
	v_fmac_f32_e32 v0, v4, v4
	v_lshlrev_b32_e32 v10, 16, v11
	v_fmac_f32_e32 v0, v5, v5
	v_and_b32_e32 v11, 0xffff0000, v11
	v_fmac_f32_e32 v0, v10, v10
	v_lshlrev_b32_e32 v14, 16, v12
	v_fmac_f32_e32 v0, v11, v11
	v_and_b32_e32 v12, 0xffff0000, v12
	v_fmac_f32_e32 v0, v14, v14
	v_lshlrev_b32_e32 v15, 16, v13
	v_fmac_f32_e32 v0, v12, v12
	v_and_b32_e32 v13, 0xffff0000, v13
	v_fmac_f32_e32 v0, v15, v15
	v_fmac_f32_e32 v0, v13, v13
	global_load_dwordx4 v[10:13], v[2:3], off offset:48
	s_waitcnt vmcnt(0) lgkmcnt(0)
	v_lshlrev_b32_e32 v4, 16, v10
	v_and_b32_e32 v5, 0xffff0000, v10
	v_fmac_f32_e32 v0, v4, v4
	v_lshlrev_b32_e32 v10, 16, v11
	v_fmac_f32_e32 v0, v5, v5
	v_and_b32_e32 v11, 0xffff0000, v11
	v_fmac_f32_e32 v0, v10, v10
	v_lshlrev_b32_e32 v14, 16, v12
	v_fmac_f32_e32 v0, v11, v11
	v_and_b32_e32 v12, 0xffff0000, v12
	v_fmac_f32_e32 v0, v14, v14
	v_lshlrev_b32_e32 v15, 16, v13
	v_fmac_f32_e32 v0, v12, v12
	v_and_b32_e32 v13, 0xffff0000, v13
	v_fmac_f32_e32 v0, v15, v15
	v_fmac_f32_e32 v0, v13, v13
	global_load_dwordx4 v[10:13], v[2:3], off offset:64
	s_waitcnt vmcnt(0) lgkmcnt(0)
	v_lshlrev_b32_e32 v4, 16, v10
	v_and_b32_e32 v5, 0xffff0000, v10
	v_fmac_f32_e32 v0, v4, v4
	v_lshlrev_b32_e32 v10, 16, v11
	v_fmac_f32_e32 v0, v5, v5
	v_and_b32_e32 v11, 0xffff0000, v11
	v_fmac_f32_e32 v0, v10, v10
	v_lshlrev_b32_e32 v14, 16, v12
	v_fmac_f32_e32 v0, v11, v11
	v_and_b32_e32 v12, 0xffff0000, v12
	v_fmac_f32_e32 v0, v14, v14
	v_lshlrev_b32_e32 v15, 16, v13
	v_fmac_f32_e32 v0, v12, v12
	v_and_b32_e32 v13, 0xffff0000, v13
	v_fmac_f32_e32 v0, v15, v15
	v_fmac_f32_e32 v0, v13, v13
	global_load_dwordx4 v[10:13], v[2:3], off offset:80
	s_waitcnt vmcnt(0) lgkmcnt(0)
	v_lshlrev_b32_e32 v4, 16, v10
	v_and_b32_e32 v5, 0xffff0000, v10
	v_fmac_f32_e32 v0, v4, v4
	v_lshlrev_b32_e32 v10, 16, v11
	v_fmac_f32_e32 v0, v5, v5
	v_and_b32_e32 v11, 0xffff0000, v11
	v_fmac_f32_e32 v0, v10, v10
	v_lshlrev_b32_e32 v14, 16, v12
	v_fmac_f32_e32 v0, v11, v11
	v_and_b32_e32 v12, 0xffff0000, v12
	v_fmac_f32_e32 v0, v14, v14
	v_lshlrev_b32_e32 v15, 16, v13
	v_fmac_f32_e32 v0, v12, v12
	v_and_b32_e32 v13, 0xffff0000, v13
	v_fmac_f32_e32 v0, v15, v15
	v_fmac_f32_e32 v0, v13, v13
	global_load_dwordx4 v[10:13], v[2:3], off offset:96
	s_waitcnt vmcnt(0) lgkmcnt(0)
	v_lshlrev_b32_e32 v4, 16, v10
	v_and_b32_e32 v5, 0xffff0000, v10
	v_fmac_f32_e32 v0, v4, v4
	v_lshlrev_b32_e32 v10, 16, v11
	v_fmac_f32_e32 v0, v5, v5
	v_and_b32_e32 v11, 0xffff0000, v11
	v_fmac_f32_e32 v0, v10, v10
	v_lshlrev_b32_e32 v14, 16, v12
	v_fmac_f32_e32 v0, v11, v11
	v_and_b32_e32 v12, 0xffff0000, v12
	v_fmac_f32_e32 v0, v14, v14
	v_lshlrev_b32_e32 v15, 16, v13
	v_fmac_f32_e32 v0, v12, v12
	v_and_b32_e32 v13, 0xffff0000, v13
	v_fmac_f32_e32 v0, v15, v15
	v_fmac_f32_e32 v0, v13, v13
	global_load_dwordx4 v[10:13], v[2:3], off offset:112
	s_waitcnt vmcnt(0) lgkmcnt(0)
	v_lshlrev_b32_e32 v4, 16, v10
	v_and_b32_e32 v5, 0xffff0000, v10
	v_fmac_f32_e32 v0, v4, v4
	v_lshlrev_b32_e32 v10, 16, v11
	v_fmac_f32_e32 v0, v5, v5
	v_and_b32_e32 v11, 0xffff0000, v11
	v_fmac_f32_e32 v0, v10, v10
	v_lshlrev_b32_e32 v14, 16, v12
	v_fmac_f32_e32 v0, v11, v11
	v_and_b32_e32 v12, 0xffff0000, v12
	v_fmac_f32_e32 v0, v14, v14
	v_lshlrev_b32_e32 v15, 16, v13
	v_fmac_f32_e32 v0, v12, v12
	v_and_b32_e32 v13, 0xffff0000, v13
	v_fmac_f32_e32 v0, v15, v15
	v_fmac_f32_e32 v0, v13, v13
	global_load_dwordx4 v[10:13], v[2:3], off offset:128
	s_waitcnt vmcnt(0) lgkmcnt(0)
	v_lshlrev_b32_e32 v4, 16, v10
	v_and_b32_e32 v5, 0xffff0000, v10
	v_fmac_f32_e32 v0, v4, v4
	v_lshlrev_b32_e32 v10, 16, v11
	v_fmac_f32_e32 v0, v5, v5
	v_and_b32_e32 v11, 0xffff0000, v11
	v_fmac_f32_e32 v0, v10, v10
	v_lshlrev_b32_e32 v14, 16, v12
	v_fmac_f32_e32 v0, v11, v11
	v_and_b32_e32 v12, 0xffff0000, v12
	v_fmac_f32_e32 v0, v14, v14
	v_lshlrev_b32_e32 v15, 16, v13
	v_fmac_f32_e32 v0, v12, v12
	v_and_b32_e32 v13, 0xffff0000, v13
	v_fmac_f32_e32 v0, v15, v15
	v_fmac_f32_e32 v0, v13, v13
	global_load_dwordx4 v[10:13], v[2:3], off offset:144
	s_waitcnt vmcnt(0) lgkmcnt(0)
; DI void unpack8(const u32x4& v, float* f) { f[0] = bflo(v.x); f[1] = bfhi(v.x); f[2] = bflo(v.y); f[3] = bfhi(v.y); f[4] = bflo(v.z); f[5] = bfhi(v.z); f[6] = bflo(v.w); f[7] = bfhi(v.w); }
; DI void mla_q_tile(const Params& P, int pm, int pn, char* smem) {
;     ...
;   { const int row = tid >> 1, half = tid & 1; const bf16_t* p = proj + (size_t)(m0 + row) * DINP + C_BCQ + half * 224; float ss = 0.f;
;     for (int i = 0; i < 28; ++i) { const u32x4 v = *(const u32x4*)(p + i * 8); float f[8]; unpack8(v, f);
; #pragma unroll
;       for (int e = 0; e < 8; ++e) ss += f[e] * f[e]; }
	v_lshlrev_b32_e32 v4, 16, v10
	v_and_b32_e32 v5, 0xffff0000, v10
	v_fmac_f32_e32 v0, v4, v4
	v_lshlrev_b32_e32 v10, 16, v11
	v_fmac_f32_e32 v0, v5, v5
	v_and_b32_e32 v11, 0xffff0000, v11
	v_fmac_f32_e32 v0, v10, v10
	v_lshlrev_b32_e32 v14, 16, v12
	v_fmac_f32_e32 v0, v11, v11
	v_and_b32_e32 v12, 0xffff0000, v12
	v_fmac_f32_e32 v0, v14, v14
	v_lshlrev_b32_e32 v15, 16, v13
	v_fmac_f32_e32 v0, v12, v12
	v_and_b32_e32 v13, 0xffff0000, v13
	v_fmac_f32_e32 v0, v15, v15
	v_fmac_f32_e32 v0, v13, v13
	global_load_dwordx4 v[10:13], v[2:3], off offset:160
	s_waitcnt vmcnt(0) lgkmcnt(0)
	v_lshlrev_b32_e32 v4, 16, v10
	v_and_b32_e32 v5, 0xffff0000, v10
	v_fmac_f32_e32 v0, v4, v4
	v_lshlrev_b32_e32 v10, 16, v11
	v_fmac_f32_e32 v0, v5, v5
	v_and_b32_e32 v11, 0xffff0000, v11
	v_fmac_f32_e32 v0, v10, v10
	v_lshlrev_b32_e32 v14, 16, v12
	v_fmac_f32_e32 v0, v11, v11
	v_and_b32_e32 v12, 0xffff0000, v12
	v_fmac_f32_e32 v0, v14, v14
	v_lshlrev_b32_e32 v15, 16, v13
	v_fmac_f32_e32 v0, v12, v12
	v_and_b32_e32 v13, 0xffff0000, v13
	v_fmac_f32_e32 v0, v15, v15
	v_fmac_f32_e32 v0, v13, v13
	global_load_dwordx4 v[10:13], v[2:3], off offset:176
	s_waitcnt vmcnt(0) lgkmcnt(0)
	v_lshlrev_b32_e32 v4, 16, v10
	v_and_b32_e32 v5, 0xffff0000, v10
	v_fmac_f32_e32 v0, v4, v4
	v_lshlrev_b32_e32 v10, 16, v11
	v_fmac_f32_e32 v0, v5, v5
	v_and_b32_e32 v11, 0xffff0000, v11
	v_fmac_f32_e32 v0, v10, v10
	v_lshlrev_b32_e32 v14, 16, v12
	v_fmac_f32_e32 v0, v11, v11
	v_and_b32_e32 v12, 0xffff0000, v12
	v_fmac_f32_e32 v0, v14, v14
	v_lshlrev_b32_e32 v15, 16, v13
	v_fmac_f32_e32 v0, v12, v12
	v_and_b32_e32 v13, 0xffff0000, v13
	v_fmac_f32_e32 v0, v15, v15
	v_fmac_f32_e32 v0, v13, v13
	global_load_dwordx4 v[10:13], v[2:3], off offset:192
	s_waitcnt vmcnt(0) lgkmcnt(0)
	v_lshlrev_b32_e32 v4, 16, v10
	v_and_b32_e32 v5, 0xffff0000, v10
	v_fmac_f32_e32 v0, v4, v4
	v_lshlrev_b32_e32 v10, 16, v11
	v_fmac_f32_e32 v0, v5, v5
	v_and_b32_e32 v11, 0xffff0000, v11
	v_fmac_f32_e32 v0, v10, v10
	v_lshlrev_b32_e32 v14, 16, v12
	v_fmac_f32_e32 v0, v11, v11
	v_and_b32_e32 v12, 0xffff0000, v12
	v_fmac_f32_e32 v0, v14, v14
	v_lshlrev_b32_e32 v15, 16, v13
	v_fmac_f32_e32 v0, v12, v12
	v_and_b32_e32 v13, 0xffff0000, v13
	v_fmac_f32_e32 v0, v15, v15
	v_fmac_f32_e32 v0, v13, v13
	global_load_dwordx4 v[10:13], v[2:3], off offset:208
	s_waitcnt vmcnt(0) lgkmcnt(0)
	v_lshlrev_b32_e32 v4, 16, v10
	v_and_b32_e32 v5, 0xffff0000, v10
	v_fmac_f32_e32 v0, v4, v4
	v_lshlrev_b32_e32 v10, 16, v11
	v_fmac_f32_e32 v0, v5, v5
	v_and_b32_e32 v11, 0xffff0000, v11
	v_fmac_f32_e32 v0, v10, v10
	v_lshlrev_b32_e32 v14, 16, v12
	v_fmac_f32_e32 v0, v11, v11
	v_and_b32_e32 v12, 0xffff0000, v12
	v_fmac_f32_e32 v0, v14, v14
	v_lshlrev_b32_e32 v15, 16, v13
	v_fmac_f32_e32 v0, v12, v12
	v_and_b32_e32 v13, 0xffff0000, v13
	v_fmac_f32_e32 v0, v15, v15
	v_fmac_f32_e32 v0, v13, v13
	global_load_dwordx4 v[10:13], v[2:3], off offset:224
	s_waitcnt vmcnt(0) lgkmcnt(0)
	v_lshlrev_b32_e32 v4, 16, v10
	v_and_b32_e32 v5, 0xffff0000, v10
	v_fmac_f32_e32 v0, v4, v4
	v_lshlrev_b32_e32 v10, 16, v11
	v_fmac_f32_e32 v0, v5, v5
	v_and_b32_e32 v11, 0xffff0000, v11
	v_fmac_f32_e32 v0, v10, v10
	v_lshlrev_b32_e32 v14, 16, v12
	v_fmac_f32_e32 v0, v11, v11
	v_and_b32_e32 v12, 0xffff0000, v12
	v_fmac_f32_e32 v0, v14, v14
	v_lshlrev_b32_e32 v15, 16, v13
	v_fmac_f32_e32 v0, v12, v12
	v_and_b32_e32 v13, 0xffff0000, v13
	v_fmac_f32_e32 v0, v15, v15
	v_fmac_f32_e32 v0, v13, v13
	global_load_dwordx4 v[10:13], v[2:3], off offset:240
	s_waitcnt vmcnt(0) lgkmcnt(0)
	v_lshlrev_b32_e32 v4, 16, v10
	v_and_b32_e32 v5, 0xffff0000, v10
	v_fmac_f32_e32 v0, v4, v4
	v_lshlrev_b32_e32 v10, 16, v11
	v_fmac_f32_e32 v0, v5, v5
	v_and_b32_e32 v11, 0xffff0000, v11
	v_fmac_f32_e32 v0, v10, v10
	v_lshlrev_b32_e32 v14, 16, v12
	v_fmac_f32_e32 v0, v11, v11
	v_and_b32_e32 v12, 0xffff0000, v12
	v_fmac_f32_e32 v0, v14, v14
	v_lshlrev_b32_e32 v15, 16, v13
	v_fmac_f32_e32 v0, v12, v12
	v_and_b32_e32 v13, 0xffff0000, v13
	v_fmac_f32_e32 v0, v15, v15
	v_fmac_f32_e32 v0, v13, v13
	global_load_dwordx4 v[10:13], v[2:3], off offset:256
	s_waitcnt vmcnt(0) lgkmcnt(0)
	v_lshlrev_b32_e32 v4, 16, v10
	v_and_b32_e32 v5, 0xffff0000, v10
	v_fmac_f32_e32 v0, v4, v4
	v_lshlrev_b32_e32 v10, 16, v11
	v_fmac_f32_e32 v0, v5, v5
	v_and_b32_e32 v11, 0xffff0000, v11
	v_fmac_f32_e32 v0, v10, v10
	v_lshlrev_b32_e32 v14, 16, v12
	v_fmac_f32_e32 v0, v11, v11
	v_and_b32_e32 v12, 0xffff0000, v12
	v_fmac_f32_e32 v0, v14, v14
	v_lshlrev_b32_e32 v15, 16, v13
	v_fmac_f32_e32 v0, v12, v12
	v_and_b32_e32 v13, 0xffff0000, v13
	v_fmac_f32_e32 v0, v15, v15
	v_fmac_f32_e32 v0, v13, v13
	global_load_dwordx4 v[10:13], v[2:3], off offset:272
	s_waitcnt vmcnt(0) lgkmcnt(0)
	v_lshlrev_b32_e32 v4, 16, v10
	v_and_b32_e32 v5, 0xffff0000, v10
	v_fmac_f32_e32 v0, v4, v4
	v_lshlrev_b32_e32 v10, 16, v11
	v_fmac_f32_e32 v0, v5, v5
	v_and_b32_e32 v11, 0xffff0000, v11
	v_fmac_f32_e32 v0, v10, v10
	v_lshlrev_b32_e32 v14, 16, v12
	v_fmac_f32_e32 v0, v11, v11
	v_and_b32_e32 v12, 0xffff0000, v12
	v_fmac_f32_e32 v0, v14, v14
	v_lshlrev_b32_e32 v15, 16, v13
	v_fmac_f32_e32 v0, v12, v12
	v_and_b32_e32 v13, 0xffff0000, v13
	v_fmac_f32_e32 v0, v15, v15
	v_fmac_f32_e32 v0, v13, v13
	global_load_dwordx4 v[10:13], v[2:3], off offset:288
	s_waitcnt vmcnt(0) lgkmcnt(0)
	v_lshlrev_b32_e32 v4, 16, v10
	v_and_b32_e32 v5, 0xffff0000, v10
	v_fmac_f32_e32 v0, v4, v4
	v_lshlrev_b32_e32 v10, 16, v11
	v_fmac_f32_e32 v0, v5, v5
	v_and_b32_e32 v11, 0xffff0000, v11
	v_fmac_f32_e32 v0, v10, v10
	v_lshlrev_b32_e32 v14, 16, v12
	v_fmac_f32_e32 v0, v11, v11
	v_and_b32_e32 v12, 0xffff0000, v12
	v_fmac_f32_e32 v0, v14, v14
	v_lshlrev_b32_e32 v15, 16, v13
	v_fmac_f32_e32 v0, v12, v12
	v_and_b32_e32 v13, 0xffff0000, v13
	v_fmac_f32_e32 v0, v15, v15
	v_fmac_f32_e32 v0, v13, v13
	global_load_dwordx4 v[10:13], v[2:3], off offset:304
	s_waitcnt vmcnt(0) lgkmcnt(0)
; DI void unpack8(const u32x4& v, float* f) { f[0] = bflo(v.x); f[1] = bfhi(v.x); f[2] = bflo(v.y); f[3] = bfhi(v.y); f[4] = bflo(v.z); f[5] = bfhi(v.z); f[6] = bflo(v.w); f[7] = bfhi(v.w); }
; DI void mla_q_tile(const Params& P, int pm, int pn, char* smem) {
;     ...
;     for (int i = 0; i < 28; ++i) { const u32x4 v = *(const u32x4*)(p + i * 8); float f[8]; unpack8(v, f);
; #pragma unroll
;       for (int e = 0; e < 8; ++e) ss += f[e] * f[e]; }
;     ss += __shfl_xor(ss, 1); if (half == 0) rs[row] = rsqrtf(ss * (1.f / 448.f) + EPS); }
	v_lshlrev_b32_e32 v4, 16, v10
	v_and_b32_e32 v5, 0xffff0000, v10
	v_fmac_f32_e32 v0, v4, v4
	v_lshlrev_b32_e32 v10, 16, v11
	v_fmac_f32_e32 v0, v5, v5
	v_and_b32_e32 v11, 0xffff0000, v11
	v_fmac_f32_e32 v0, v10, v10
	v_lshlrev_b32_e32 v14, 16, v12
	v_fmac_f32_e32 v0, v11, v11
	v_and_b32_e32 v12, 0xffff0000, v12
	v_fmac_f32_e32 v0, v14, v14
	v_lshlrev_b32_e32 v15, 16, v13
	v_fmac_f32_e32 v0, v12, v12
	v_and_b32_e32 v13, 0xffff0000, v13
	v_fmac_f32_e32 v0, v15, v15
	v_fmac_f32_e32 v0, v13, v13
	global_load_dwordx4 v[10:13], v[2:3], off offset:320
	s_waitcnt vmcnt(0) lgkmcnt(0)
	v_lshlrev_b32_e32 v4, 16, v10
	v_and_b32_e32 v5, 0xffff0000, v10
	v_fmac_f32_e32 v0, v4, v4
	v_lshlrev_b32_e32 v10, 16, v11
	v_fmac_f32_e32 v0, v5, v5
	v_and_b32_e32 v11, 0xffff0000, v11
	v_fmac_f32_e32 v0, v10, v10
	v_lshlrev_b32_e32 v14, 16, v12
	v_fmac_f32_e32 v0, v11, v11
	v_and_b32_e32 v12, 0xffff0000, v12
	v_fmac_f32_e32 v0, v14, v14
	v_lshlrev_b32_e32 v15, 16, v13
	v_fmac_f32_e32 v0, v12, v12
	v_and_b32_e32 v13, 0xffff0000, v13
	v_fmac_f32_e32 v0, v15, v15
	v_fmac_f32_e32 v0, v13, v13
	global_load_dwordx4 v[10:13], v[2:3], off offset:336
	s_waitcnt vmcnt(0) lgkmcnt(0)
	v_lshlrev_b32_e32 v4, 16, v10
	v_and_b32_e32 v5, 0xffff0000, v10
	v_fmac_f32_e32 v0, v4, v4
	v_lshlrev_b32_e32 v10, 16, v11
	v_fmac_f32_e32 v0, v5, v5
	v_and_b32_e32 v11, 0xffff0000, v11
	v_fmac_f32_e32 v0, v10, v10
	v_lshlrev_b32_e32 v14, 16, v12
	v_fmac_f32_e32 v0, v11, v11
	v_and_b32_e32 v12, 0xffff0000, v12
	v_fmac_f32_e32 v0, v14, v14
	v_lshlrev_b32_e32 v15, 16, v13
	v_fmac_f32_e32 v0, v12, v12
	v_and_b32_e32 v13, 0xffff0000, v13
	v_fmac_f32_e32 v0, v15, v15
	v_fmac_f32_e32 v0, v13, v13
	global_load_dwordx4 v[10:13], v[2:3], off offset:352
	s_waitcnt vmcnt(0) lgkmcnt(0)
	v_lshlrev_b32_e32 v4, 16, v10
	v_and_b32_e32 v5, 0xffff0000, v10
	v_fmac_f32_e32 v0, v4, v4
	v_lshlrev_b32_e32 v10, 16, v11
	v_fmac_f32_e32 v0, v5, v5
	v_and_b32_e32 v11, 0xffff0000, v11
	v_fmac_f32_e32 v0, v10, v10
	v_lshlrev_b32_e32 v14, 16, v12
	v_fmac_f32_e32 v0, v11, v11
	v_and_b32_e32 v12, 0xffff0000, v12
	v_fmac_f32_e32 v0, v14, v14
	v_lshlrev_b32_e32 v15, 16, v13
	v_fmac_f32_e32 v0, v12, v12
	v_and_b32_e32 v13, 0xffff0000, v13
	v_fmac_f32_e32 v0, v15, v15
	v_fmac_f32_e32 v0, v13, v13
	global_load_dwordx4 v[10:13], v[2:3], off offset:368
	s_waitcnt vmcnt(0) lgkmcnt(0)
	v_lshlrev_b32_e32 v4, 16, v10
	v_and_b32_e32 v5, 0xffff0000, v10
	v_fmac_f32_e32 v0, v4, v4
	v_lshlrev_b32_e32 v10, 16, v11
	v_fmac_f32_e32 v0, v5, v5
	v_and_b32_e32 v11, 0xffff0000, v11
	v_fmac_f32_e32 v0, v10, v10
	v_lshlrev_b32_e32 v14, 16, v12
	v_fmac_f32_e32 v0, v11, v11
	v_and_b32_e32 v12, 0xffff0000, v12
	v_fmac_f32_e32 v0, v14, v14
	v_lshlrev_b32_e32 v15, 16, v13
	v_fmac_f32_e32 v0, v12, v12
	v_and_b32_e32 v13, 0xffff0000, v13
	v_fmac_f32_e32 v0, v15, v15
	v_fmac_f32_e32 v0, v13, v13
	global_load_dwordx4 v[10:13], v[2:3], off offset:384
	s_waitcnt vmcnt(0) lgkmcnt(0)
	v_lshlrev_b32_e32 v4, 16, v10
	v_and_b32_e32 v5, 0xffff0000, v10
	v_fmac_f32_e32 v0, v4, v4
	v_lshlrev_b32_e32 v10, 16, v11
	v_fmac_f32_e32 v0, v5, v5
	v_and_b32_e32 v11, 0xffff0000, v11
	v_fmac_f32_e32 v0, v10, v10
	v_lshlrev_b32_e32 v14, 16, v12
	v_fmac_f32_e32 v0, v11, v11
	v_and_b32_e32 v12, 0xffff0000, v12
	v_fmac_f32_e32 v0, v14, v14
	v_lshlrev_b32_e32 v15, 16, v13
	v_fmac_f32_e32 v0, v12, v12
	v_and_b32_e32 v13, 0xffff0000, v13
	v_fmac_f32_e32 v0, v15, v15
	v_fmac_f32_e32 v0, v13, v13
	global_load_dwordx4 v[10:13], v[2:3], off offset:400
	s_waitcnt vmcnt(0) lgkmcnt(0)
	v_lshlrev_b32_e32 v4, 16, v10
	v_and_b32_e32 v5, 0xffff0000, v10
	v_fmac_f32_e32 v0, v4, v4
	v_lshlrev_b32_e32 v10, 16, v11
	v_fmac_f32_e32 v0, v5, v5
	v_and_b32_e32 v11, 0xffff0000, v11
	v_fmac_f32_e32 v0, v10, v10
	v_lshlrev_b32_e32 v14, 16, v12
	v_fmac_f32_e32 v0, v11, v11
	v_and_b32_e32 v12, 0xffff0000, v12
	v_fmac_f32_e32 v0, v14, v14
	v_lshlrev_b32_e32 v15, 16, v13
	v_fmac_f32_e32 v0, v12, v12
	v_and_b32_e32 v13, 0xffff0000, v13
	v_fmac_f32_e32 v0, v15, v15
	v_fmac_f32_e32 v0, v13, v13
	global_load_dwordx4 v[10:13], v[2:3], off offset:416
	s_waitcnt vmcnt(0) lgkmcnt(0)
	v_lshlrev_b32_e32 v4, 16, v10
	v_and_b32_e32 v5, 0xffff0000, v10
	v_fmac_f32_e32 v0, v4, v4
	v_fmac_f32_e32 v0, v5, v5
	global_load_dwordx4 v[2:5], v[2:3], off offset:432
	v_lshlrev_b32_e32 v10, 16, v11
	v_and_b32_e32 v11, 0xffff0000, v11
	v_fmac_f32_e32 v0, v10, v10
	v_lshlrev_b32_e32 v14, 16, v12
	v_fmac_f32_e32 v0, v11, v11
	v_and_b32_e32 v12, 0xffff0000, v12
	v_fmac_f32_e32 v0, v14, v14
	v_lshlrev_b32_e32 v15, 16, v13
	v_fmac_f32_e32 v0, v12, v12
	v_and_b32_e32 v13, 0xffff0000, v13
	v_fmac_f32_e32 v0, v15, v15
	v_fmac_f32_e32 v0, v13, v13
	s_waitcnt vmcnt(0) lgkmcnt(0)
	v_lshlrev_b32_e32 v10, 16, v2
	v_and_b32_e32 v2, 0xffff0000, v2
	v_fmac_f32_e32 v0, v10, v10
	v_lshlrev_b32_e32 v11, 16, v3
	v_fmac_f32_e32 v0, v2, v2
	v_and_b32_e32 v3, 0xffff0000, v3
	v_fmac_f32_e32 v0, v11, v11
	v_lshlrev_b32_e32 v12, 16, v4
	v_fmac_f32_e32 v0, v3, v3
	v_and_b32_e32 v4, 0xffff0000, v4
	v_fmac_f32_e32 v0, v12, v12
	v_mbcnt_hi_u32_b32 v2, -1, v207
	v_fmac_f32_e32 v0, v4, v4
	v_and_b32_e32 v4, 64, v2
	v_xor_b32_e32 v3, 1, v2
	v_add_u32_e32 v4, 64, v4
	v_lshlrev_b32_e32 v13, 16, v5
	v_cmp_lt_i32_e32 vcc, v3, v4
	v_and_b32_e32 v5, 0xffff0000, v5
	v_fmac_f32_e32 v0, v13, v13
	v_cndmask_b32_e32 v2, v2, v3, vcc
	v_fmac_f32_e32 v0, v5, v5
	v_lshlrev_b32_e32 v2, 2, v2
	ds_bpermute_b32 v2, v2, v0
	v_cmp_eq_u32_e32 vcc, 0, v9
	s_and_saveexec_b64 s[0:1], vcc
	s_cbranch_execz .LBB0_276
	s_waitcnt lgkmcnt(0)
	v_add_f32_e32 v0, v0, v2
	v_fmamk_f32 v0, v0, 0x3b124925, v245
	v_mul_f32_e32 v2, 0x4b800000, v0
	v_cmp_gt_f32_e32 vcc, s84, v0
	s_nop 1
	v_cndmask_b32_e32 v0, v0, v2, vcc
	v_rsq_f32_e32 v0, v0
	s_nop 0
	v_mul_f32_e32 v2, 0x45800000, v0
	v_cndmask_b32_e32 v0, v0, v2, vcc
	v_lshl_add_u32 v2, v8, 2, v240
	ds_write_b32 v2, v0
	s_branch .LBB0_276

; DI void gdn_prep_item(const Params& P, int l, int n, int hh, char* smem) {
;     ...
;     const int t = lane; const float a_raw = ab[(size_t)(t0 + t) * 16 + hh], b_raw = ab[(size_t)(t0 + t) * 16 + 8 + hh];
;     const float Aa = __expf(P.gdn_a_log[l * 8 + hh]); const float xb = a_raw + P.gdn_dt_bias[l * 8 + hh];
;     const float ex = __expf(fminf(xb, 20.f));
;     const float sp = xb > 20.f ? xb : (ex < 0.01f ? ex * (1.f - ex * (0.5f - ex * (1.f / 3.f))) : __logf(1.f + ex));
.LBB0_419:
	v_mov_b32_e32 v82, v206
	global_load_dwordx2 v[50:51], v1, s[40:41] offset:1224
	s_ashr_i32 s12, s17, 3
	s_and_b32 s18, s17, 7
	s_lshl_b32 s2, s18, 8
	s_ashr_i32 s3, s12, 31
	s_add_u32 s8, s2, s12
	s_addc_u32 s9, 0, s3
	v_cmp_lt_u32_e32 vcc, 63, v82
	s_and_saveexec_b64 s[2:3], vcc
	s_xor_b64 s[2:3], exec, s[2:3]
	v_mbcnt_hi_u32_b32 v84, -1, v207
	v_and_b32_e32 v81, 64, v84
	s_or_saveexec_b64 s[10:11], s[2:3]
	s_lshl_b32 s19, s12, 6
	v_and_b32_e32 v34, 63, v82
	s_xor_b64 exec, exec, s[10:11]
	s_cbranch_execz .LBB0_431
	v_or_b32_e32 v2, s19, v82
	v_ashrrev_i32_e32 v3, 31, v2
	v_lshlrev_b64 v[2:3], 6, v[2:3]
	s_waitcnt vmcnt(0)
	v_lshl_add_u64 v[2:3], v[50:51], 0, v[2:3]
	s_lshl_b32 s62, s18, 2
	v_lshl_add_u64 v[2:3], v[2:3], 0, s[62:63]
	s_mov_b64 s[2:3], 0x262e8000
	v_lshl_add_u64 v[4:5], v[2:3], 0, s[2:3]
	v_add_co_u32_e32 v2, vcc, 0x262e8000, v2
	s_or_b32 s62, s18, s16
	s_nop 0
	v_addc_co_u32_e32 v3, vcc, 0, v3, vcc
	global_load_dword v6, v[2:3], off
	global_load_dword v0, v[4:5], off offset:32
	s_nop 0
	global_load_dwordx4 v[2:5], v1, s[40:41] offset:1104
	s_lshl_b64 s[2:3], s[62:63], 2
	s_waitcnt vmcnt(0)
	v_lshl_add_u64 v[2:3], v[2:3], 0, s[2:3]
	v_lshl_add_u64 v[4:5], v[4:5], 0, s[2:3]
	global_load_dword v2, v[2:3], off
	s_mov_b32 s2, 0x41a00000
	global_load_dword v3, v[4:5], off
	s_waitcnt vmcnt(0) lgkmcnt(0)
	v_add_f32_e32 v3, v6, v3
	v_cmp_nlt_f32_e32 vcc, s2, v3
	s_and_saveexec_b64 s[12:13], vcc
	s_cbranch_execz .LBB0_428
	v_max_f32_e32 v3, v3, v3
	v_min_f32_e32 v3, 0x41a00000, v3
	v_mul_f32_e32 v3, 0x3fb8aa3b, v3
	v_exp_f32_e32 v4, v3
	s_mov_b32 s2, 0x3c23d70a
	v_cmp_ngt_f32_e32 vcc, s2, v4
	s_and_saveexec_b64 s[2:3], vcc
	s_xor_b64 s[14:15], exec, s[2:3]
	s_cbranch_execz .LBB0_425
	v_add_f32_e32 v3, 1.0, v4
	v_cmp_gt_f32_e32 vcc, s84, v3
	s_mov_b32 s2, 0x3f317217
	s_nop 0
	v_cndmask_b32_e64 v4, 0, 32, vcc
	v_ldexp_f32 v3, v3, v4
	v_log_f32_e32 v3, v3
	s_nop 0
	v_mul_f32_e32 v4, 0x3f317217, v3
	v_fma_f32 v4, v3, s2, -v4
	v_fmac_f32_e32 v4, 0x3377d1cf, v3
	s_mov_b32 s2, 0x7f800000
	v_fmac_f32_e32 v4, 0x3f317217, v3
	v_cmp_lt_f32_e64 s[2:3], |v3|, s2
	s_nop 1
	v_cndmask_b32_e64 v3, v3, v4, s[2:3]
	v_mov_b32_e32 v4, 0x41b17218
	v_cndmask_b32_e32 v4, 0, v4, vcc
	v_sub_f32_e32 v3, v3, v4

; DI void gdn_prep_item(const Params& P, int l, int n, int hh, char* smem) {
;     ...
;     float g = -Aa * sp;
; #pragma unroll
;     for (int d = 1; d < 64; d <<= 1) { const float v = __shfl_up(g, d); if (lane >= d) g += v; }
;     const float bt = __builtin_amdgcn_rcpf(1.f + __expf(-b_raw)), eg = __expf(g); gcs[t] = g; gcs[64 + t] = bt; gcs[128 + t] = eg; gcs[192 + t] = bt * eg;
;     if (t == 63) ((float*)(P.ws + OFF_GTOT))[tile] = eg;
.LBB0_428:
	s_or_b64 exec, exec, s[12:13]
	v_mul_f32_e32 v2, 0x3fb8aa3b, v2
	v_exp_f32_e32 v2, v2
	v_and_b32_e32 v81, 64, v239
	v_add_u32_e32 v5, -1, v239
	v_cmp_lt_i32_e32 vcc, v5, v81
	v_mul_f32_e64 v4, v3, -v2
	v_mul_f32_e32 v0, 0xbfb8aa3b, v0
	v_cndmask_b32_e32 v5, v5, v239, vcc
	v_lshlrev_b32_e32 v5, 2, v5
	ds_bpermute_b32 v5, v5, v4
	v_cmp_eq_u32_e32 vcc, 0, v34
	v_exp_f32_e32 v0, v0
	s_waitcnt lgkmcnt(0)
	v_fma_f32 v2, v3, -v2, v5
	v_add_u32_e32 v3, -2, v239
	v_cndmask_b32_e32 v2, v2, v4, vcc
	v_cmp_lt_i32_e32 vcc, v3, v81
	v_add_f32_e32 v0, 1.0, v0
	v_lshl_or_b32 v4, v34, 2, v241
	v_cndmask_b32_e32 v3, v3, v239, vcc
	v_lshlrev_b32_e32 v3, 2, v3
	ds_bpermute_b32 v3, v3, v2
	v_cmp_gt_u32_e32 vcc, 2, v34
	s_waitcnt lgkmcnt(0)
	v_add_f32_e32 v3, v2, v3
	v_cndmask_b32_e32 v2, v3, v2, vcc
	v_add_u32_e32 v3, -4, v239
	v_cmp_lt_i32_e32 vcc, v3, v81
	s_nop 1
	v_cndmask_b32_e32 v3, v3, v239, vcc
	v_lshlrev_b32_e32 v3, 2, v3
	ds_bpermute_b32 v3, v3, v2
	v_cmp_gt_u32_e32 vcc, 4, v34
	s_waitcnt lgkmcnt(0)
	v_add_f32_e32 v3, v2, v3
	v_cndmask_b32_e32 v2, v3, v2, vcc
	v_add_u32_e32 v3, -8, v239
	v_cmp_lt_i32_e32 vcc, v3, v81
	s_nop 1
	v_cndmask_b32_e32 v3, v3, v239, vcc
	v_lshlrev_b32_e32 v3, 2, v3
	ds_bpermute_b32 v3, v3, v2
	v_cmp_gt_u32_e32 vcc, 8, v34
	s_waitcnt lgkmcnt(0)
	v_add_f32_e32 v3, v2, v3
	v_cndmask_b32_e32 v2, v3, v2, vcc
	v_add_u32_e32 v3, -16, v239
	v_cmp_lt_i32_e32 vcc, v3, v81
	s_nop 1
	v_cndmask_b32_e32 v3, v3, v239, vcc
	v_lshlrev_b32_e32 v3, 2, v3
	ds_bpermute_b32 v3, v3, v2
	v_cmp_gt_u32_e32 vcc, 16, v34
	s_waitcnt lgkmcnt(0)
	v_add_f32_e32 v3, v2, v3
	v_cndmask_b32_e32 v2, v3, v2, vcc
	v_subrev_u32_e32 v3, 32, v239
	v_cmp_lt_i32_e32 vcc, v3, v81
	s_nop 1
	v_cndmask_b32_e32 v3, v3, v239, vcc
	v_lshlrev_b32_e32 v3, 2, v3
	ds_bpermute_b32 v3, v3, v2
	v_cmp_gt_u32_e32 vcc, 32, v34
	s_waitcnt lgkmcnt(0)
	v_add_f32_e32 v3, v2, v3
	v_cndmask_b32_e32 v2, v3, v2, vcc
	v_rcp_f32_e32 v3, v0
	v_mul_f32_e32 v0, 0x3fb8aa3b, v2
	v_exp_f32_e32 v0, v0
	ds_write_b32 v4, v2
	v_lshl_add_u32 v2, v82, 2, v241
	v_cmp_eq_u32_e32 vcc, 63, v34
	ds_write2st64_b32 v2, v3, v0 offset0:1 offset1:2
	v_mul_f32_e32 v3, v3, v0
	ds_write_b32 v2, v3 offset:768
	s_and_saveexec_b64 s[2:3], vcc
	s_cbranch_execz .LBB0_430
	s_lshl_b64 s[12:13], s[8:9], 2
	v_lshl_add_u64 v[2:3], v[50:51], 0, s[12:13]
	v_add_co_u32_e32 v2, vcc, 0x263e8000, v2
	s_nop 1
	v_addc_co_u32_e32 v3, vcc, 0, v3, vcc
	global_store_dword v[2:3], v0, off

; DI void gdn_prep_item(const Params& P, int l, int n, int hh, char* smem) {
;     ...
;     const int t = tid >> 3, part = tid & 7, tabs = t0 + t;
;     const float gct = gcs[t], egct = gcs[128 + t], ktl = __expf(gcs[63] - gct);
;     const int pjt = 32 * (t >> 5) + perm32(t & 31);
; #pragma unroll
;     for (int X = 0; X < 3; ++X) {
;       const int cb = X * 1024 + hh * 128 + part * 16;
;       float y[16];
; #pragma unroll
;       for (int e = 0; e < 16; ++e) y[e] = 0.f;
;       u32x4 pv[4][2]; f32x4 wv[4][4];
; #pragma unroll
;       for (int j = 0; j < 4; ++j) { const int row = tabs - 3 + j, rr = row < 0 ? 0 : row;
;         pv[j][0] = *(const u32x4*)(proj + (size_t)rr * DINP + cb); pv[j][1] = *(const u32x4*)(proj + (size_t)rr * DINP + cb + 8);
;         const float* cw = P.gdn_conv + ((size_t)l * 4 + j) * 3072 + cb;
; #pragma unroll
;         for (int e4 = 0; e4 < 4; ++e4) wv[j][e4] = *(const f32x4*)(cw + 4 * e4); }
.LBB0_431:
	s_or_b64 exec, exec, s[10:11]
	s_waitcnt lgkmcnt(0)
	s_barrier
	global_load_dwordx2 v[38:39], v1, s[40:41] offset:1096
	v_ashrrev_i32_e32 v63, 3, v82
	s_lshl_b64 s[2:3], s[8:9], 14
	v_and_b32_e32 v79, 7, v82
	s_lshl_b32 s10, s18, 7
	v_lshlrev_b32_e32 v2, 7, v63
	s_waitcnt vmcnt(0)
	v_lshl_add_u64 v[54:55], v[50:51], 0, s[2:3]
	v_lshlrev_b32_e32 v58, 5, v79
	v_lshl_or_b32 v74, v79, 4, s10
	v_ashrrev_i32_e32 v3, 31, v2
	v_lshlrev_b32_e32 v4, 3, v82
	v_mov_b32_e32 v41, v1
	v_and_b32_e32 v0, 0xc0, v58
	v_lshlrev_b32_e32 v40, 2, v74
	v_lshl_add_u64 v[2:3], v[2:3], 1, v[54:55]
	v_add_u32_e32 v65, s19, v63
	v_lshl_add_u64 v[2:3], v[2:3], 0, v[0:1]
	v_and_b32_e32 v0, 8, v4
	v_lshl_add_u64 v[56:57], v[50:51], 0, s[30:31]
	v_max_i32_e32 v5, 3, v65
	v_max_i32_e32 v6, 2, v65
	v_max_i32_e32 v7, 1, v65
	v_lshl_add_u64 v[36:37], v[2:3], 0, v[0:1]
	v_lshlrev_b32_e32 v0, 1, v74
	s_movk_i32 s10, 0x6000
	v_max_i32_e32 v75, 0, v65
	v_add_u32_e32 v78, -3, v5
	v_add_u32_e32 v77, -2, v6
	v_add_u32_e32 v76, -1, v7
	v_lshl_add_u64 v[2:3], v[56:57], 0, v[0:1]
	v_mad_u64_u32 v[6:7], s[2:3], v78, s81, v[2:3]
	v_mad_u64_u32 v[10:11], s[2:3], v77, s81, v[2:3]
	v_mad_u64_u32 v[14:15], s[2:3], v76, s81, v[2:3]
	v_mad_u64_u32 v[30:31], s[2:3], v75, s81, v[2:3]
	s_mov_b64 s[12:13], 0x6000
	s_mov_b64 s[14:15], 0x9000
	s_mov_b32 s18, 0x9000
	global_load_dwordx4 v[2:5], v[6:7], off
	global_load_dwordx4 v[18:21], v[6:7], off offset:16
	s_nop 0
	global_load_dwordx4 v[6:9], v[10:11], off
	global_load_dwordx4 v[22:25], v[10:11], off offset:16
	s_nop 0
	global_load_dwordx4 v[10:13], v[14:15], off
	global_load_dwordx4 v[26:29], v[14:15], off offset:16
	s_nop 0
	global_load_dwordx4 v[14:17], v[30:31], off
	s_nop 0
	global_load_dwordx4 v[30:33], v[30:31], off offset:16
	v_lshl_add_u32 v35, v63, 2, v241
	s_lshl_b64 s[8:9], s[8:9], 13
	v_lshrrev_b32_e32 v59, 5, v34
	s_mov_b64 s[2:3], 0x252e8000
	s_movk_i32 s11, 0x110
	v_lshl_add_u64 v[38:39], v[38:39], 0, v[40:41]
	v_lshl_add_u64 v[40:41], v[38:39], 0, s[0:1]
	v_add_co_u32_e32 v52, vcc, s10, v40
	v_lshl_add_u64 v[38:39], v[38:39], 0, s[4:5]
	s_nop 0
	v_addc_co_u32_e32 v53, vcc, 0, v41, vcc
	global_load_dwordx4 v[42:45], v[40:41], off
	global_load_dwordx4 v[86:89], v[40:41], off offset:16
	global_load_dwordx4 v[90:93], v[40:41], off offset:32
	global_load_dwordx4 v[46:49], v[40:41], off offset:48
	global_load_dwordx4 v[70:73], v[38:39], off
	global_load_dwordx4 v[94:97], v[38:39], off offset:16
	global_load_dwordx4 v[98:101], v[38:39], off offset:32
	global_load_dwordx4 v[66:69], v[38:39], off offset:48
	v_lshl_add_u64 v[38:39], v[40:41], 0, s[12:13]
	v_lshl_add_u64 v[60:61], v[40:41], 0, s[14:15]
	v_add_co_u32_e32 v40, vcc, s18, v40
	s_nop 1
	v_addc_co_u32_e32 v41, vcc, 0, v41, vcc
	global_load_dwordx4 v[102:105], v[38:39], off offset:16
	global_load_dwordx4 v[106:109], v[38:39], off offset:32
	global_load_dwordx4 v[110:113], v[52:53], off
	global_load_dwordx4 v[114:117], v[38:39], off offset:48
	global_load_dwordx4 v[118:121], v[60:61], off offset:16
	global_load_dwordx4 v[122:125], v[60:61], off offset:32
	global_load_dwordx4 v[126:129], v[40:41], off
	global_load_dwordx4 v[130:133], v[60:61], off offset:48
	ds_read2st64_b32 v[40:41], v35 offset1:2
	v_mov_b32_e32 v35, 0x1c8fc
	ds_read_b32 v38, v35
	v_lshl_add_u64 v[34:35], v[50:51], 0, s[8:9]
	v_lshl_add_u64 v[52:53], v[34:35], 0, s[2:3]
	v_and_b32_e32 v61, 31, v82
	s_waitcnt lgkmcnt(0)
	v_sub_f32_e32 v34, v38, v40
	v_mul_f32_e32 v34, 0x3fb8aa3b, v34
	v_exp_f32_e32 v40, v34
	v_lshlrev_b32_e32 v34, 1, v63
	v_and_b32_e32 v38, 24, v34
	v_lshrrev_b32_e32 v34, 2, v63
	v_and_b32_e32 v39, 4, v34
	v_mad_u64_u32 v[34:35], s[2:3], v63, s11, v[58:59]
	v_lshlrev_b32_e32 v35, 9, v63
	v_lshl_or_b32 v80, v79, 6, v35
	v_and_b32_e32 v35, 0xffffffe3, v63
	s_mov_b64 s[2:3], 0x1f2e8000
	v_or3_b32 v35, v38, v35, v39
	v_lshl_add_u64 v[38:39], v[36:37], 0, s[2:3]
	v_add_u32_e32 v83, 0x10800, v80
	v_cmp_lt_i32_e32 vcc, 2, v65
	v_xor_b32_e32 v85, 1, v84
	v_add_u32_e32 v142, 64, v81
	v_cndmask_b32_e64 v58, 0, 1.0, vcc
	v_cmp_lt_i32_e32 vcc, 1, v65
	s_waitcnt vmcnt(0)
	v_pk_mul_f32 v[138:139], v[58:59], v[48:49] op_sel_hi:[0,1]
	v_pk_mul_f32 v[140:141], v[58:59], v[46:47] op_sel_hi:[0,1]
	v_cndmask_b32_e64 v60, 0, 1.0, vcc
	v_cmp_lt_i32_e32 vcc, 0, v65
	v_pk_mul_f32 v[134:135], v[60:61], v[68:69] op_sel_hi:[0,1]
	v_pk_mul_f32 v[68:69], v[60:61], v[72:73] op_sel_hi:[0,1]
	v_cndmask_b32_e64 v62, 0, 1.0, vcc
	v_cmp_lt_i32_e32 vcc, -1, v65
	v_pk_mul_f32 v[116:117], v[62:63], v[116:117] op_sel_hi:[0,1]
	v_pk_mul_f32 v[136:137], v[60:61], v[66:67] op_sel_hi:[0,1]
	v_cndmask_b32_e64 v64, 0, 1.0, vcc
	v_pk_mul_f32 v[72:73], v[64:65], v[128:129] op_sel_hi:[0,1]
	v_lshlrev_b32_e32 v128, 16, v21
	v_and_b32_e32 v129, 0xffff0000, v21
	v_pk_mul_f32 v[48:49], v[64:65], v[126:127] op_sel_hi:[0,1]
	v_lshlrev_b32_e32 v126, 16, v25
	v_and_b32_e32 v127, 0xffff0000, v25
	v_pk_fma_f32 v[128:129], v[138:139], v[128:129], 0 op_sel_hi:[1,1,0]
	v_pk_mul_f32 v[66:67], v[58:59], v[44:45] op_sel_hi:[0,1]
	v_pk_mul_f32 v[44:45], v[60:61], v[70:71] op_sel_hi:[0,1]
	v_pk_mul_f32 v[70:71], v[62:63], v[112:113] op_sel_hi:[0,1]
	v_pk_mul_f32 v[112:113], v[64:65], v[118:119] op_sel_hi:[0,1]
	v_pk_mul_f32 v[118:119], v[64:65], v[124:125] op_sel_hi:[0,1]
	v_lshlrev_b32_e32 v124, 16, v29
	v_and_b32_e32 v125, 0xffff0000, v29
	v_pk_fma_f32 v[126:127], v[134:135], v[126:127], v[128:129]
	v_pk_mul_f32 v[132:133], v[64:65], v[132:133] op_sel_hi:[0,1]
	v_pk_mul_f32 v[46:47], v[62:63], v[110:111] op_sel_hi:[0,1]
	v_pk_mul_f32 v[110:111], v[64:65], v[120:121] op_sel_hi:[0,1]
	v_pk_mul_f32 v[120:121], v[64:65], v[122:123] op_sel_hi:[0,1]
; DI void unpack8(const u32x4& v, float* f) { f[0] = bflo(v.x); f[1] = bfhi(v.x); f[2] = bflo(v.y); f[3] = bfhi(v.y); f[4] = bflo(v.z); f[5] = bfhi(v.z); f[6] = bflo(v.w); f[7] = bfhi(v.w); }
; DI float silu_f(float x) { return x * __builtin_amdgcn_rcpf(1.f + __expf(-x)); }
; DI void gdn_prep_item(const Params& P, int l, int n, int hh, char* smem) {
;     ...
; #pragma unroll
;       for (int j = 0; j < 4; ++j) { const float msk = (tabs - 3 + j) >= 0 ? 1.f : 0.f;
;         float xv[16]; unpack8(pv[j][0], xv); unpack8(pv[j][1], xv + 8);
; #pragma unroll
;         for (int e4 = 0; e4 < 4; ++e4) { const f32x4 wm = wv[j][e4] * msk; y[4 * e4] += wm.x * xv[4 * e4]; y[4 * e4 + 1] += wm.y * xv[4 * e4 + 1]; y[4 * e4 + 2] += wm.z * xv[4 * e4 + 2]; y[4 * e4 + 3] += wm.w * xv[4 * e4 + 3]; } }
; #pragma unroll
;       for (int e = 0; e < 16; ++e) y[e] = silu_f(y[e]);
	v_lshlrev_b32_e32 v122, 16, v33
	v_and_b32_e32 v123, 0xffff0000, v33
	v_pk_fma_f32 v[116:117], v[116:117], v[124:125], v[126:127]
	v_cmp_lt_i32_e32 vcc, v85, v142
	v_pk_fma_f32 v[116:117], v[132:133], v[122:123], v[116:117]
	v_lshlrev_b32_e32 v122, 16, v32
	v_mul_f32_e32 v25, 0xbfb8aa3b, v116
	v_exp_f32_e32 v25, v25
	v_cndmask_b32_e32 v81, v84, v85, vcc
	v_and_b32_e32 v123, 0xffff0000, v32
	v_lshlrev_b32_e32 v32, 16, v28
	v_add_f32_e32 v85, 1.0, v25
	v_and_b32_e32 v33, 0xffff0000, v28
	v_lshlrev_b32_e32 v28, 16, v24
	v_and_b32_e32 v29, 0xffff0000, v24
	v_lshlrev_b32_e32 v24, 16, v20
	v_and_b32_e32 v25, 0xffff0000, v20
	v_pk_fma_f32 v[24:25], v[140:141], v[24:25], 0 op_sel_hi:[1,1,0]
	v_pk_mul_f32 v[114:115], v[62:63], v[114:115] op_sel_hi:[0,1]
	v_pk_fma_f32 v[24:25], v[136:137], v[28:29], v[24:25]
	v_pk_mul_f32 v[130:131], v[64:65], v[130:131] op_sel_hi:[0,1]
	v_pk_fma_f32 v[24:25], v[114:115], v[32:33], v[24:25]
	v_mul_f32_e32 v21, 0xbfb8aa3b, v117
	v_pk_fma_f32 v[24:25], v[130:131], v[122:123], v[24:25]
	v_exp_f32_e32 v21, v21
	v_mul_f32_e32 v20, 0xbfb8aa3b, v24
	v_exp_f32_e32 v28, v20
	v_mul_f32_e32 v20, 0xbfb8aa3b, v25
	v_exp_f32_e32 v29, v20
	v_add_f32_e32 v21, 1.0, v21
	v_rcp_f32_e32 v21, v21
	v_rcp_f32_e32 v20, v85
	v_add_f32_e32 v28, 1.0, v28
	v_add_f32_e32 v29, 1.0, v29
	v_rcp_f32_e32 v28, v28
	v_rcp_f32_e32 v29, v29
	v_pk_mul_f32 v[92:93], v[58:59], v[92:93] op_sel_hi:[0,1]
	v_lshlrev_b32_e32 v122, 16, v19
	v_and_b32_e32 v123, 0xffff0000, v19
	v_pk_mul_f32 v[100:101], v[60:61], v[100:101] op_sel_hi:[0,1]
	v_pk_mul_f32 v[20:21], v[116:117], v[20:21]
	v_lshlrev_b32_e32 v116, 16, v23
	v_and_b32_e32 v117, 0xffff0000, v23
	v_pk_fma_f32 v[92:93], v[92:93], v[122:123], 0 op_sel_hi:[1,1,0]
	v_pk_mul_f32 v[108:109], v[62:63], v[108:109] op_sel_hi:[0,1]
	v_lshlrev_b32_e32 v114, 16, v27
	v_and_b32_e32 v115, 0xffff0000, v27
	v_pk_fma_f32 v[92:93], v[100:101], v[116:117], v[92:93]
	v_pk_mul_f32 v[24:25], v[24:25], v[28:29]
	v_lshlrev_b32_e32 v28, 16, v31
	v_and_b32_e32 v29, 0xffff0000, v31
	v_pk_fma_f32 v[92:93], v[108:109], v[114:115], v[92:93]
	v_pk_mul_f32 v[90:91], v[58:59], v[90:91] op_sel_hi:[0,1]
	v_pk_fma_f32 v[28:29], v[118:119], v[28:29], v[92:93]
	v_lshlrev_b32_e32 v108, 16, v30
	v_mul_f32_e32 v19, 0xbfb8aa3b, v28
	v_exp_f32_e32 v19, v19
	v_mul_f32_e32 v23, 0xbfb8aa3b, v29
	v_exp_f32_e32 v23, v23
	v_and_b32_e32 v109, 0xffff0000, v30
	v_add_f32_e32 v19, 1.0, v19
	v_rcp_f32_e32 v100, v19
	v_add_f32_e32 v19, 1.0, v23
	v_lshlrev_b32_e32 v30, 16, v26
	v_and_b32_e32 v31, 0xffff0000, v26
	v_lshlrev_b32_e32 v26, 16, v22
	v_and_b32_e32 v27, 0xffff0000, v22
	v_lshlrev_b32_e32 v22, 16, v18
	v_and_b32_e32 v23, 0xffff0000, v18
	v_pk_mul_f32 v[98:99], v[60:61], v[98:99] op_sel_hi:[0,1]
	v_rcp_f32_e32 v101, v19
	v_pk_fma_f32 v[18:19], v[90:91], v[22:23], 0 op_sel_hi:[1,1,0]
	v_pk_mul_f32 v[106:107], v[62:63], v[106:107] op_sel_hi:[0,1]
	v_pk_fma_f32 v[18:19], v[98:99], v[26:27], v[18:19]
	v_pk_mul_f32 v[88:89], v[58:59], v[88:89] op_sel_hi:[0,1]
	v_pk_fma_f32 v[18:19], v[106:107], v[30:31], v[18:19]
	v_lshlrev_b32_e32 v98, 16, v5
	v_pk_fma_f32 v[18:19], v[120:121], v[108:109], v[18:19]
	v_and_b32_e32 v99, 0xffff0000, v5
	v_pk_mul_f32 v[96:97], v[60:61], v[96:97] op_sel_hi:[0,1]
	v_mul_f32_e32 v22, 0xbfb8aa3b, v18
	v_lshlrev_b32_e32 v90, 16, v9
	v_and_b32_e32 v91, 0xffff0000, v9
	v_pk_fma_f32 v[88:89], v[88:89], v[98:99], 0 op_sel_hi:[1,1,0]
	v_pk_mul_f32 v[104:105], v[62:63], v[104:105] op_sel_hi:[0,1]
	v_exp_f32_e32 v26, v22
	v_mul_f32_e32 v22, 0xbfb8aa3b, v19
	v_lshlrev_b32_e32 v30, 16, v13
	v_and_b32_e32 v31, 0xffff0000, v13
	v_pk_fma_f32 v[88:89], v[96:97], v[90:91], v[88:89]
	v_exp_f32_e32 v27, v22
	v_pk_mul_f32 v[22:23], v[28:29], v[100:101]
	v_lshlrev_b32_e32 v28, 16, v17
	v_and_b32_e32 v29, 0xffff0000, v17
	v_pk_fma_f32 v[30:31], v[104:105], v[30:31], v[88:89]
	v_pk_mul_f32 v[86:87], v[58:59], v[86:87] op_sel_hi:[0,1]
	v_pk_fma_f32 v[28:29], v[110:111], v[28:29], v[30:31]
	v_and_b32_e32 v17, 0xffff0000, v12
	v_mul_f32_e32 v5, 0xbfb8aa3b, v28
	v_exp_f32_e32 v5, v5
	v_mul_f32_e32 v9, 0xbfb8aa3b, v29
	v_exp_f32_e32 v9, v9
	v_and_b32_e32 v13, 0xffff0000, v8
	v_add_f32_e32 v5, 1.0, v5
	v_rcp_f32_e32 v30, v5
	v_add_f32_e32 v5, 1.0, v9
	v_rcp_f32_e32 v31, v5
	v_and_b32_e32 v9, 0xffff0000, v4
	v_pk_mul_f32 v[94:95], v[60:61], v[94:95] op_sel_hi:[0,1]
	v_pk_mul_f32 v[102:103], v[62:63], v[102:103] op_sel_hi:[0,1]
	v_pk_mul_f32 v[28:29], v[28:29], v[30:31]
	v_lshlrev_b32_e32 v30, 16, v16
	v_and_b32_e32 v31, 0xffff0000, v16
	v_lshlrev_b32_e32 v16, 16, v12
	v_lshlrev_b32_e32 v12, 16, v8
	v_lshlrev_b32_e32 v8, 16, v4
	v_pk_fma_f32 v[4:5], v[86:87], v[8:9], 0 op_sel_hi:[1,1,0]
	v_lshlrev_b32_e32 v90, 16, v3
	v_pk_fma_f32 v[4:5], v[94:95], v[12:13], v[4:5]
	v_and_b32_e32 v91, 0xffff0000, v3
	v_pk_fma_f32 v[4:5], v[102:103], v[16:17], v[4:5]
	v_lshlrev_b32_e32 v86, 16, v7
	v_pk_fma_f32 v[4:5], v[112:113], v[30:31], v[4:5]
	v_and_b32_e32 v87, 0xffff0000, v7
	v_mul_f32_e32 v8, 0xbfb8aa3b, v4
	v_exp_f32_e32 v12, v8
	v_mul_f32_e32 v8, 0xbfb8aa3b, v5
	v_exp_f32_e32 v13, v8
	v_pk_fma_f32 v[66:67], v[66:67], v[90:91], 0 op_sel_hi:[1,1,0]
	v_lshlrev_b32_e32 v30, 16, v11
	v_and_b32_e32 v31, 0xffff0000, v11
	v_pk_fma_f32 v[66:67], v[68:69], v[86:87], v[66:67]
	v_lshlrev_b32_e32 v16, 16, v15
	v_and_b32_e32 v17, 0xffff0000, v15
	v_pk_fma_f32 v[30:31], v[70:71], v[30:31], v[66:67]
	v_add_f32_e32 v12, 1.0, v12
	v_pk_fma_f32 v[16:17], v[72:73], v[16:17], v[30:31]
	v_add_f32_e32 v13, 1.0, v13
	v_mul_f32_e32 v3, 0xbfb8aa3b, v16
	v_mul_f32_e32 v7, 0xbfb8aa3b, v17
	v_rcp_f32_e32 v12, v12
	v_rcp_f32_e32 v13, v13
	v_exp_f32_e32 v3, v3
	v_exp_f32_e32 v7, v7
; DI unsigned pack2(float lo, float hi) { f32x2 v = {lo, hi}; bf2_t b = __builtin_convertvector(v, bf2_t); return __builtin_bit_cast(unsigned, b); }
; DI void gdn_prep_item(const Params& P, int l, int n, int hh, char* smem) {
;     ...
;       if (X < 2) { float ss = 0.f;
; #pragma unroll
;         for (int e = 0; e < 16; ++e) ss += y[e] * y[e];
;         ss += __shfl_xor(ss, 1); ss += __shfl_xor(ss, 2); ss += __shfl_xor(ss, 4);
;         const float rn = rsqrtf(ss + EPS) * (X == 0 ? 0.08838834764831845f : 1.f);
; #pragma unroll
;         for (int e = 0; e < 16; ++e) y[e] *= rn; }
;       if (X == 0) {
;         u32x4 p0 = {pack2(y[0], y[1]), pack2(y[2], y[3]), pack2(y[4], y[5]), pack2(y[6], y[7])}, p1 = {pack2(y[8], y[9]), pack2(y[10], y[11]), pack2(y[12], y[13]), pack2(y[14], y[15])};
;         *(u32x4*)(qb16 + t * 272 + part * 32) = p0; *(u32x4*)(qb16 + t * 272 + part * 32 + 16) = p1;
; #pragma unroll
;         for (int b = 0; b < 4; ++b) { u32x2 pk = {pack2(y[4 * b] * egct, y[4 * b + 1] * egct), pack2(y[4 * b + 2] * egct, y[4 * b + 3] * egct)};
;           *(u32x2*)(Qd + t * 128 + 32 * (part >> 1) + 8 * b + 4 * (part & 1)) = pk; }
	v_pk_mul_f32 v[42:43], v[58:59], v[42:43] op_sel_hi:[0,1]
	v_pk_mul_f32 v[4:5], v[4:5], v[12:13]
	v_add_f32_e32 v3, 1.0, v3
	v_add_f32_e32 v13, 1.0, v7
	v_lshlrev_b32_e32 v30, 16, v14
	v_and_b32_e32 v31, 0xffff0000, v14
	v_lshlrev_b32_e32 v14, 16, v10
	v_and_b32_e32 v15, 0xffff0000, v10
	v_lshlrev_b32_e32 v10, 16, v6
	v_and_b32_e32 v11, 0xffff0000, v6
	v_lshlrev_b32_e32 v6, 16, v2
	v_and_b32_e32 v7, 0xffff0000, v2
	v_rcp_f32_e32 v12, v3
	v_pk_fma_f32 v[2:3], v[42:43], v[6:7], 0 op_sel_hi:[1,1,0]
	v_rcp_f32_e32 v13, v13
	v_pk_fma_f32 v[2:3], v[44:45], v[10:11], v[2:3]
	v_add_f32_e32 v26, 1.0, v26
	v_pk_fma_f32 v[2:3], v[46:47], v[14:15], v[2:3]
	v_pk_mul_f32 v[12:13], v[16:17], v[12:13]
	v_pk_fma_f32 v[2:3], v[48:49], v[30:31], v[2:3]
	v_add_f32_e32 v27, 1.0, v27
	v_mul_f32_e32 v6, 0xbfb8aa3b, v2
	v_mul_f32_e32 v7, 0xbfb8aa3b, v3
	v_exp_f32_e32 v6, v6
	v_exp_f32_e32 v7, v7
	v_pk_mul_f32 v[14:15], v[12:13], v[12:13]
	v_rcp_f32_e32 v26, v26
	v_add_f32_e32 v6, 1.0, v6
	v_add_f32_e32 v7, 1.0, v7
	v_rcp_f32_e32 v6, v6
	v_rcp_f32_e32 v7, v7
	v_rcp_f32_e32 v27, v27
	v_pk_mul_f32 v[10:11], v[4:5], v[4:5]
	v_pk_mul_f32 v[8:9], v[28:29], v[28:29]
	v_pk_mul_f32 v[2:3], v[2:3], v[6:7]
	v_pk_mul_f32 v[18:19], v[18:19], v[26:27]
	v_pk_mul_f32 v[6:7], v[2:3], v[2:3]
	v_pk_mul_f32 v[26:27], v[18:19], v[18:19]
	v_add_f32_e32 v6, v6, v7
	v_add_f32_e32 v6, v14, v6
	v_add_f32_e32 v6, v15, v6
	v_add_f32_e32 v6, v10, v6
	v_add_f32_e32 v6, v11, v6
	v_add_f32_e32 v6, v8, v6
	v_add_f32_e32 v6, v9, v6
	v_add_f32_e32 v6, v26, v6
	v_pk_mul_f32 v[88:89], v[22:23], v[22:23]
	v_add_f32_e32 v6, v27, v6
	v_add_f32_e32 v6, v88, v6
	v_pk_mul_f32 v[92:93], v[24:25], v[24:25]
	v_add_f32_e32 v6, v89, v6
	v_add_f32_e32 v6, v92, v6
	v_pk_mul_f32 v[32:33], v[20:21], v[20:21]
	v_add_f32_e32 v6, v93, v6
	v_add_f32_e32 v6, v32, v6
	v_lshlrev_b32_e32 v81, 2, v81
	v_add_f32_e32 v6, v33, v6
	ds_bpermute_b32 v7, v81, v6
	v_xor_b32_e32 v8, 2, v84
	v_cmp_lt_i32_e32 vcc, v8, v142
	s_mov_b32 s2, 0x1f2e8000
	s_waitcnt lgkmcnt(0)
	v_add_f32_e32 v6, v6, v7
	v_cndmask_b32_e32 v8, v84, v8, vcc
	v_lshlrev_b32_e32 v140, 2, v8
	ds_bpermute_b32 v7, v140, v6
	v_xor_b32_e32 v8, 4, v84
	v_cmp_lt_i32_e32 vcc, v8, v142
	s_waitcnt lgkmcnt(0)
	v_add_f32_e32 v6, v6, v7
	v_cndmask_b32_e32 v8, v84, v8, vcc
	v_lshlrev_b32_e32 v141, 2, v8
	ds_bpermute_b32 v7, v141, v6
	s_waitcnt lgkmcnt(0)
	v_add_f32_e32 v6, v6, v7
	v_add_f32_e32 v6, 0x358637bd, v6
	v_mul_f32_e32 v7, 0x4b800000, v6
	v_cmp_gt_f32_e32 vcc, s84, v6
	s_nop 1
	v_cndmask_b32_e32 v6, v6, v7, vcc
	v_rsq_f32_e32 v6, v6
	s_nop 0
	v_mul_f32_e32 v7, 0x45800000, v6
	v_cndmask_b32_e32 v6, v6, v7, vcc
	v_mul_f32_e32 v6, 0x3db504f3, v6
	v_pk_mul_f32 v[10:11], v[2:3], v[6:7] op_sel_hi:[1,0]
	v_pk_mul_f32 v[12:13], v[12:13], v[6:7] op_sel_hi:[1,0]
	v_pk_mul_f32 v[14:15], v[4:5], v[6:7] op_sel_hi:[1,0]
	v_pk_mul_f32 v[16:17], v[28:29], v[6:7] op_sel_hi:[1,0]
	v_pk_mul_f32 v[18:19], v[18:19], v[6:7] op_sel_hi:[1,0]
	v_pk_mul_f32 v[22:23], v[22:23], v[6:7] op_sel_hi:[1,0]
	v_pk_mul_f32 v[24:25], v[24:25], v[6:7] op_sel_hi:[1,0]
	v_pk_mul_f32 v[20:21], v[20:21], v[6:7] op_sel_hi:[1,0]
	v_cvt_pk_bf16_f32 v2, v10, v11
	v_cvt_pk_bf16_f32 v3, v12, v13
	v_cvt_pk_bf16_f32 v4, v14, v15
	v_cvt_pk_bf16_f32 v5, v16, v17
	v_cvt_pk_bf16_f32 v6, v18, v19
	v_cvt_pk_bf16_f32 v7, v22, v23
	v_cvt_pk_bf16_f32 v8, v24, v25
	v_cvt_pk_bf16_f32 v9, v20, v21
	ds_write_b128 v34, v[2:5] offset:17408
	ds_write_b128 v34, v[6:9] offset:17424
	v_mov_b32_e32 v2, v41
	v_pk_mul_f32 v[4:5], v[2:3], v[10:11] op_sel_hi:[0,1]
	v_pk_mul_f32 v[6:7], v[2:3], v[12:13] op_sel_hi:[0,1]
	v_cvt_pk_bf16_f32 v4, v4, v5
	v_cvt_pk_bf16_f32 v5, v6, v7
	v_add_co_u32_e32 v6, vcc, s2, v36
	s_nop 1
	v_addc_co_u32_e32 v7, vcc, 0, v37, vcc
	global_store_dwordx2 v[6:7], v[4:5], off
	v_pk_mul_f32 v[4:5], v[2:3], v[14:15] op_sel_hi:[0,1]
	v_pk_mul_f32 v[6:7], v[2:3], v[16:17] op_sel_hi:[0,1]
	v_cvt_pk_bf16_f32 v4, v4, v5
	v_cvt_pk_bf16_f32 v5, v6, v7
	global_store_dwordx2 v[38:39], v[4:5], off offset:16
	v_pk_mul_f32 v[4:5], v[2:3], v[18:19] op_sel_hi:[0,1]
	v_pk_mul_f32 v[6:7], v[2:3], v[22:23] op_sel_hi:[0,1]
	v_cvt_pk_bf16_f32 v4, v4, v5
	v_cvt_pk_bf16_f32 v5, v6, v7
	global_store_dwordx2 v[38:39], v[4:5], off offset:32
	v_pk_mul_f32 v[4:5], v[2:3], v[24:25] op_sel_hi:[0,1]
	v_pk_mul_f32 v[2:3], v[2:3], v[20:21] op_sel_hi:[0,1]
	v_cvt_pk_bf16_f32 v4, v4, v5
	v_cvt_pk_bf16_f32 v5, v2, v3
	global_store_dwordx2 v[38:39], v[4:5], off offset:48
	global_load_dwordx2 v[2:3], v1, s[40:41] offset:1096
	v_or_b32_e32 v6, 0x400, v74
	v_lshlrev_b32_e32 v4, 2, v6
	v_mov_b32_e32 v5, v1
	v_lshlrev_b32_e32 v14, 1, v6
	v_mov_b32_e32 v15, v1
	s_waitcnt vmcnt(0)
; DI void unpack8(const u32x4& v, float* f) { f[0] = bflo(v.x); f[1] = bfhi(v.x); f[2] = bflo(v.y); f[3] = bfhi(v.y); f[4] = bflo(v.z); f[5] = bfhi(v.z); f[6] = bflo(v.w); f[7] = bfhi(v.w); }
; DI float silu_f(float x) { return x * __builtin_amdgcn_rcpf(1.f + __expf(-x)); }
; DI void gdn_prep_item(const Params& P, int l, int n, int hh, char* smem) {
;     ...
;       for (int j = 0; j < 4; ++j) { const int row = tabs - 3 + j, rr = row < 0 ? 0 : row;
;         pv[j][0] = *(const u32x4*)(proj + (size_t)rr * DINP + cb); pv[j][1] = *(const u32x4*)(proj + (size_t)rr * DINP + cb + 8);
;         const float* cw = P.gdn_conv + ((size_t)l * 4 + j) * 3072 + cb;
; #pragma unroll
;         for (int e4 = 0; e4 < 4; ++e4) wv[j][e4] = *(const f32x4*)(cw + 4 * e4); }
;       __builtin_amdgcn_sched_barrier(0);
; #pragma unroll
;       for (int j = 0; j < 4; ++j) { const float msk = (tabs - 3 + j) >= 0 ? 1.f : 0.f;
;         float xv[16]; unpack8(pv[j][0], xv); unpack8(pv[j][1], xv + 8);
; #pragma unroll
;         for (int e4 = 0; e4 < 4; ++e4) { const f32x4 wm = wv[j][e4] * msk; y[4 * e4] += wm.x * xv[4 * e4]; y[4 * e4 + 1] += wm.y * xv[4 * e4 + 1]; y[4 * e4 + 2] += wm.z * xv[4 * e4 + 2]; y[4 * e4 + 3] += wm.w * xv[4 * e4 + 3]; } }
; #pragma unroll
;       for (int e = 0; e < 16; ++e) y[e] = silu_f(y[e]);
	v_lshl_add_u64 v[10:11], v[2:3], 0, v[4:5]
	v_mad_u64_u32 v[2:3], s[2:3], v78, s81, v[56:57]
	v_lshl_add_u64 v[6:7], v[2:3], 0, v[14:15]
	global_load_dwordx4 v[2:5], v[6:7], off
	global_load_dwordx4 v[42:45], v[6:7], off offset:16
	v_mad_u64_u32 v[6:7], s[2:3], v77, s81, v[56:57]
	v_lshl_add_u64 v[112:113], v[10:11], 0, s[0:1]
	v_lshl_add_u64 v[12:13], v[6:7], 0, v[14:15]
	v_lshl_add_u64 v[10:11], v[10:11], 0, s[4:5]
	global_load_dwordx4 v[18:21], v[112:113], off
	global_load_dwordx4 v[46:49], v[112:113], off offset:16
	global_load_dwordx4 v[66:69], v[112:113], off offset:32
	global_load_dwordx4 v[22:25], v[112:113], off offset:48
	global_load_dwordx4 v[6:9], v[12:13], off
	global_load_dwordx4 v[70:73], v[12:13], off offset:16
	global_load_dwordx4 v[26:29], v[10:11], off
	global_load_dwordx4 v[84:87], v[10:11], off offset:16
	global_load_dwordx4 v[88:91], v[10:11], off offset:32
	global_load_dwordx4 v[30:33], v[10:11], off offset:48
	v_mad_u64_u32 v[10:11], s[2:3], v76, s81, v[56:57]
	v_lshl_add_u64 v[16:17], v[10:11], 0, v[14:15]
	v_add_co_u32_e32 v36, vcc, s10, v112
	global_load_dwordx4 v[10:13], v[16:17], off
	global_load_dwordx4 v[92:95], v[16:17], off offset:16
	v_lshl_add_u64 v[16:17], v[112:113], 0, s[12:13]
	v_addc_co_u32_e32 v37, vcc, 0, v113, vcc
	global_load_dwordx4 v[96:99], v[16:17], off offset:16
	global_load_dwordx4 v[100:103], v[16:17], off offset:32
	global_load_dwordx4 v[104:107], v[36:37], off
	s_nop 0
	global_load_dwordx4 v[36:39], v[16:17], off offset:48
	v_mad_u64_u32 v[16:17], s[2:3], v75, s81, v[56:57]
	v_add_co_u32_e32 v120, vcc, s18, v112
	v_lshl_add_u64 v[108:109], v[16:17], 0, v[14:15]
	v_lshl_add_u64 v[124:125], v[112:113], 0, s[14:15]
	v_addc_co_u32_e32 v121, vcc, 0, v113, vcc
	global_load_dwordx4 v[14:17], v[108:109], off
	s_nop 0
	global_load_dwordx4 v[108:111], v[108:109], off offset:16
	s_nop 0
	global_load_dwordx4 v[112:115], v[124:125], off offset:16
	global_load_dwordx4 v[116:119], v[124:125], off offset:32
	s_nop 0
	global_load_dwordx4 v[120:123], v[120:121], off
	s_nop 0
	global_load_dwordx4 v[124:127], v[124:125], off offset:48
	s_waitcnt vmcnt(0) lgkmcnt(0)
	v_pk_mul_f32 v[136:137], v[58:59], v[24:25] op_sel_hi:[0,1]
	v_pk_mul_f32 v[24:25], v[60:61], v[26:27] op_sel_hi:[0,1]
	v_pk_mul_f32 v[26:27], v[62:63], v[104:105] op_sel_hi:[0,1]
	v_pk_mul_f32 v[104:105], v[64:65], v[114:115] op_sel_hi:[0,1]
	v_lshlrev_b32_e32 v114, 16, v45
	v_and_b32_e32 v115, 0xffff0000, v45
	v_pk_mul_f32 v[130:131], v[62:63], v[36:37] op_sel_hi:[0,1]
	v_pk_mul_f32 v[132:133], v[60:61], v[32:33] op_sel_hi:[0,1]
	v_pk_mul_f32 v[36:37], v[62:63], v[106:107] op_sel_hi:[0,1]
	v_pk_mul_f32 v[106:107], v[64:65], v[112:113] op_sel_hi:[0,1]
	v_lshlrev_b32_e32 v112, 16, v73
	v_and_b32_e32 v113, 0xffff0000, v73
	v_pk_fma_f32 v[114:115], v[136:137], v[114:115], 0 op_sel_hi:[1,1,0]
	v_pk_mul_f32 v[128:129], v[62:63], v[38:39] op_sel_hi:[0,1]
	v_pk_mul_f32 v[134:135], v[60:61], v[30:31] op_sel_hi:[0,1]
	v_pk_mul_f32 v[30:31], v[58:59], v[20:21] op_sel_hi:[0,1]
	v_lshlrev_b32_e32 v20, 16, v95
	v_and_b32_e32 v21, 0xffff0000, v95
	v_pk_fma_f32 v[112:113], v[132:133], v[112:113], v[114:115]
	v_pk_mul_f32 v[126:127], v[64:65], v[126:127] op_sel_hi:[0,1]
	v_pk_mul_f32 v[138:139], v[58:59], v[22:23] op_sel_hi:[0,1]
	v_pk_mul_f32 v[22:23], v[58:59], v[18:19] op_sel_hi:[0,1]
	v_lshlrev_b32_e32 v18, 16, v111
	v_and_b32_e32 v19, 0xffff0000, v111
	v_pk_fma_f32 v[20:21], v[128:129], v[20:21], v[112:113]
	v_lshlrev_b32_e32 v114, 16, v110
	v_pk_fma_f32 v[18:19], v[126:127], v[18:19], v[20:21]
	v_and_b32_e32 v115, 0xffff0000, v110
	v_mul_f32_e32 v20, 0xbfb8aa3b, v19
	v_exp_f32_e32 v20, v20
	v_mul_f32_e32 v21, 0xbfb8aa3b, v18
	v_lshlrev_b32_e32 v110, 16, v94
	v_and_b32_e32 v111, 0xffff0000, v94
	v_lshlrev_b32_e32 v94, 16, v72
	v_and_b32_e32 v95, 0xffff0000, v72
	v_lshlrev_b32_e32 v72, 16, v44
	v_and_b32_e32 v73, 0xffff0000, v44
	v_exp_f32_e32 v41, v21
	v_pk_fma_f32 v[44:45], v[138:139], v[72:73], 0 op_sel_hi:[1,1,0]
	v_pk_mul_f32 v[124:125], v[64:65], v[124:125] op_sel_hi:[0,1]
	v_pk_fma_f32 v[44:45], v[134:135], v[94:95], v[44:45]
	v_add_f32_e32 v20, 1.0, v20
	v_pk_fma_f32 v[44:45], v[130:131], v[110:111], v[44:45]
	v_rcp_f32_e32 v21, v20
	v_pk_fma_f32 v[44:45], v[124:125], v[114:115], v[44:45]
	v_add_f32_e32 v20, 1.0, v41
	v_mul_f32_e32 v41, 0xbfb8aa3b, v44
	v_exp_f32_e32 v41, v41
	v_mul_f32_e32 v72, 0xbfb8aa3b, v45
	v_exp_f32_e32 v73, v72
	v_rcp_f32_e32 v20, v20
	v_add_f32_e32 v41, 1.0, v41
	v_rcp_f32_e32 v72, v41
	v_add_f32_e32 v41, 1.0, v73
	v_rcp_f32_e32 v73, v41
	v_pk_mul_f32 v[68:69], v[58:59], v[68:69] op_sel_hi:[0,1]
	v_pk_mul_f32 v[94:95], v[64:65], v[116:117] op_sel_hi:[0,1]
	v_lshlrev_b32_e32 v116, 16, v43
	v_and_b32_e32 v117, 0xffff0000, v43
	v_pk_mul_f32 v[90:91], v[60:61], v[90:91] op_sel_hi:[0,1]
	v_lshlrev_b32_e32 v114, 16, v71
	v_and_b32_e32 v115, 0xffff0000, v71
	v_pk_fma_f32 v[68:69], v[68:69], v[116:117], 0 op_sel_hi:[1,1,0]
	v_pk_mul_f32 v[102:103], v[62:63], v[102:103] op_sel_hi:[0,1]
	v_pk_mul_f32 v[18:19], v[18:19], v[20:21]
	v_pk_mul_f32 v[20:21], v[44:45], v[72:73]
	v_lshlrev_b32_e32 v72, 16, v93
	v_and_b32_e32 v73, 0xffff0000, v93
	v_pk_fma_f32 v[68:69], v[90:91], v[114:115], v[68:69]
	v_pk_mul_f32 v[112:113], v[64:65], v[118:119] op_sel_hi:[0,1]
	v_lshlrev_b32_e32 v44, 16, v109
	v_and_b32_e32 v45, 0xffff0000, v109
	v_pk_fma_f32 v[68:69], v[102:103], v[72:73], v[68:69]
	v_pk_mul_f32 v[66:67], v[58:59], v[66:67] op_sel_hi:[0,1]
	v_pk_fma_f32 v[44:45], v[112:113], v[44:45], v[68:69]
	v_lshlrev_b32_e32 v102, 16, v92
	v_mul_f32_e32 v41, 0xbfb8aa3b, v44
	v_exp_f32_e32 v41, v41
	v_mul_f32_e32 v43, 0xbfb8aa3b, v45
	v_exp_f32_e32 v43, v43
; DI void unpack8(const u32x4& v, float* f) { f[0] = bflo(v.x); f[1] = bfhi(v.x); f[2] = bflo(v.y); f[3] = bfhi(v.y); f[4] = bflo(v.z); f[5] = bfhi(v.z); f[6] = bflo(v.w); f[7] = bfhi(v.w); }
; DI float silu_f(float x) { return x * __builtin_amdgcn_rcpf(1.f + __expf(-x)); }
; DI void gdn_prep_item(const Params& P, int l, int n, int hh, char* smem) {
;     ...
; #pragma unroll
;       for (int j = 0; j < 4; ++j) { const float msk = (tabs - 3 + j) >= 0 ? 1.f : 0.f;
;         float xv[16]; unpack8(pv[j][0], xv); unpack8(pv[j][1], xv + 8);
; #pragma unroll
;         for (int e4 = 0; e4 < 4; ++e4) { const f32x4 wm = wv[j][e4] * msk; y[4 * e4] += wm.x * xv[4 * e4]; y[4 * e4 + 1] += wm.y * xv[4 * e4 + 1]; y[4 * e4 + 2] += wm.z * xv[4 * e4 + 2]; y[4 * e4 + 3] += wm.w * xv[4 * e4 + 3]; } }
; #pragma unroll
;       for (int e = 0; e < 16; ++e) y[e] = silu_f(y[e]);
;       if (X < 2) { float ss = 0.f;
; #pragma unroll
;         for (int e = 0; e < 16; ++e) ss += y[e] * y[e];
;         ss += __shfl_xor(ss, 1); ss += __shfl_xor(ss, 2); ss += __shfl_xor(ss, 4);
	v_and_b32_e32 v103, 0xffff0000, v92
	v_add_f32_e32 v41, 1.0, v41
	v_lshlrev_b32_e32 v92, 16, v70
	v_and_b32_e32 v93, 0xffff0000, v70
	v_lshlrev_b32_e32 v70, 16, v42
	v_and_b32_e32 v71, 0xffff0000, v42
	v_pk_mul_f32 v[88:89], v[60:61], v[88:89] op_sel_hi:[0,1]
	v_rcp_f32_e32 v72, v41
	v_add_f32_e32 v41, 1.0, v43
	v_pk_fma_f32 v[42:43], v[66:67], v[70:71], 0 op_sel_hi:[1,1,0]
	v_pk_mul_f32 v[100:101], v[62:63], v[100:101] op_sel_hi:[0,1]
	v_rcp_f32_e32 v73, v41
	v_pk_fma_f32 v[42:43], v[88:89], v[92:93], v[42:43]
	v_lshlrev_b32_e32 v90, 16, v108
	v_and_b32_e32 v91, 0xffff0000, v108
	v_pk_fma_f32 v[42:43], v[100:101], v[102:103], v[42:43]
	v_pk_mul_f32 v[48:49], v[58:59], v[48:49] op_sel_hi:[0,1]
	v_pk_fma_f32 v[42:43], v[94:95], v[90:91], v[42:43]
	v_lshlrev_b32_e32 v90, 16, v5
	v_and_b32_e32 v91, 0xffff0000, v5
	v_pk_mul_f32 v[86:87], v[60:61], v[86:87] op_sel_hi:[0,1]
	v_lshlrev_b32_e32 v88, 16, v9
	v_and_b32_e32 v89, 0xffff0000, v9
	v_pk_fma_f32 v[48:49], v[48:49], v[90:91], 0 op_sel_hi:[1,1,0]
	v_pk_mul_f32 v[98:99], v[62:63], v[98:99] op_sel_hi:[0,1]
	v_pk_mul_f32 v[44:45], v[44:45], v[72:73]
	v_lshlrev_b32_e32 v72, 16, v13
	v_and_b32_e32 v73, 0xffff0000, v13
	v_pk_fma_f32 v[48:49], v[86:87], v[88:89], v[48:49]
	v_lshlrev_b32_e32 v70, 16, v17
	v_and_b32_e32 v71, 0xffff0000, v17
	v_pk_fma_f32 v[48:49], v[98:99], v[72:73], v[48:49]
	v_pk_mul_f32 v[46:47], v[58:59], v[46:47] op_sel_hi:[0,1]
	v_pk_fma_f32 v[48:49], v[104:105], v[70:71], v[48:49]
	v_and_b32_e32 v17, 0xffff0000, v12
	v_mul_f32_e32 v5, 0xbfb8aa3b, v48
	v_exp_f32_e32 v5, v5
	v_mul_f32_e32 v9, 0xbfb8aa3b, v49
	v_exp_f32_e32 v9, v9
	v_and_b32_e32 v13, 0xffff0000, v8
	v_add_f32_e32 v5, 1.0, v5
	v_rcp_f32_e32 v70, v5
	v_add_f32_e32 v5, 1.0, v9
	v_rcp_f32_e32 v71, v5
	v_and_b32_e32 v9, 0xffff0000, v4
	v_pk_mul_f32 v[84:85], v[60:61], v[84:85] op_sel_hi:[0,1]
	v_pk_mul_f32 v[96:97], v[62:63], v[96:97] op_sel_hi:[0,1]
	v_pk_mul_f32 v[48:49], v[48:49], v[70:71]
	v_lshlrev_b32_e32 v70, 16, v16
	v_and_b32_e32 v71, 0xffff0000, v16
	v_lshlrev_b32_e32 v16, 16, v12
	v_lshlrev_b32_e32 v12, 16, v8
	v_lshlrev_b32_e32 v8, 16, v4
	v_pk_fma_f32 v[4:5], v[46:47], v[8:9], 0 op_sel_hi:[1,1,0]
	v_pk_mul_f32 v[32:33], v[60:61], v[28:29] op_sel_hi:[0,1]
	v_pk_fma_f32 v[4:5], v[84:85], v[12:13], v[4:5]
	v_lshlrev_b32_e32 v84, 16, v3
	v_pk_fma_f32 v[4:5], v[96:97], v[16:17], v[4:5]
	v_and_b32_e32 v85, 0xffff0000, v3
	v_pk_fma_f32 v[4:5], v[106:107], v[70:71], v[4:5]
	v_lshlrev_b32_e32 v70, 16, v7
	v_mul_f32_e32 v8, 0xbfb8aa3b, v4
	v_exp_f32_e32 v12, v8
	v_mul_f32_e32 v8, 0xbfb8aa3b, v5
	v_exp_f32_e32 v13, v8
	v_and_b32_e32 v71, 0xffff0000, v7
	v_pk_fma_f32 v[30:31], v[30:31], v[84:85], 0 op_sel_hi:[1,1,0]
	v_lshlrev_b32_e32 v46, 16, v11
	v_and_b32_e32 v47, 0xffff0000, v11
	v_pk_fma_f32 v[30:31], v[32:33], v[70:71], v[30:31]
	v_pk_mul_f32 v[38:39], v[64:65], v[122:123] op_sel_hi:[0,1]
	v_lshlrev_b32_e32 v16, 16, v15
	v_and_b32_e32 v17, 0xffff0000, v15
	v_pk_fma_f32 v[30:31], v[36:37], v[46:47], v[30:31]
	v_add_f32_e32 v12, 1.0, v12
	v_pk_fma_f32 v[16:17], v[38:39], v[16:17], v[30:31]
	v_add_f32_e32 v13, 1.0, v13
	v_mul_f32_e32 v3, 0xbfb8aa3b, v16
	v_mul_f32_e32 v7, 0xbfb8aa3b, v17
	v_rcp_f32_e32 v12, v12
	v_rcp_f32_e32 v13, v13
	v_exp_f32_e32 v3, v3
	v_exp_f32_e32 v7, v7
	v_lshlrev_b32_e32 v30, 16, v14
	v_pk_mul_f32 v[12:13], v[4:5], v[12:13]
	v_add_f32_e32 v3, 1.0, v3
	v_add_f32_e32 v5, 1.0, v7
	v_and_b32_e32 v31, 0xffff0000, v14
	v_lshlrev_b32_e32 v14, 16, v10
	v_and_b32_e32 v15, 0xffff0000, v10
	v_lshlrev_b32_e32 v10, 16, v6
	v_and_b32_e32 v11, 0xffff0000, v6
	v_lshlrev_b32_e32 v6, 16, v2
	v_and_b32_e32 v7, 0xffff0000, v2
	v_rcp_f32_e32 v4, v3
	v_pk_fma_f32 v[2:3], v[22:23], v[6:7], 0 op_sel_hi:[1,1,0]
	v_pk_mul_f32 v[28:29], v[64:65], v[120:121] op_sel_hi:[0,1]
	v_pk_fma_f32 v[2:3], v[24:25], v[10:11], v[2:3]
	v_mul_f32_e32 v41, 0xbfb8aa3b, v42
	v_pk_fma_f32 v[2:3], v[26:27], v[14:15], v[2:3]
	v_exp_f32_e32 v41, v41
	v_pk_fma_f32 v[2:3], v[28:29], v[30:31], v[2:3]
	v_mul_f32_e32 v66, 0xbfb8aa3b, v43
	v_mul_f32_e32 v6, 0xbfb8aa3b, v2
	v_mul_f32_e32 v7, 0xbfb8aa3b, v3
	v_exp_f32_e32 v6, v6
	v_exp_f32_e32 v7, v7
	v_rcp_f32_e32 v5, v5
	v_exp_f32_e32 v67, v66
	v_add_f32_e32 v6, 1.0, v6
	v_add_f32_e32 v7, 1.0, v7
	v_rcp_f32_e32 v6, v6
	v_rcp_f32_e32 v7, v7
	v_add_f32_e32 v41, 1.0, v41
	v_pk_mul_f32 v[4:5], v[16:17], v[4:5]
	v_rcp_f32_e32 v66, v41
	v_pk_mul_f32 v[2:3], v[2:3], v[6:7]
	v_add_f32_e32 v41, 1.0, v67
	v_pk_mul_f32 v[6:7], v[2:3], v[2:3]
	v_pk_mul_f32 v[14:15], v[4:5], v[4:5]
	v_add_f32_e32 v6, v6, v7
	v_rcp_f32_e32 v67, v41
	v_add_f32_e32 v6, v14, v6
	v_pk_mul_f32 v[10:11], v[12:13], v[12:13]
	v_add_f32_e32 v6, v15, v6
	global_load_dwordx2 v[26:27], v1, s[40:41] offset:1096
	v_add_f32_e32 v6, v10, v6
	v_pk_mul_f32 v[8:9], v[48:49], v[48:49]
	v_add_f32_e32 v6, v11, v6
	v_pk_mul_f32 v[42:43], v[42:43], v[66:67]
	v_add_f32_e32 v6, v8, v6
	v_pk_mul_f32 v[66:67], v[42:43], v[42:43]
	v_add_f32_e32 v6, v9, v6
	v_add_f32_e32 v6, v66, v6
	v_pk_mul_f32 v[72:73], v[44:45], v[44:45]
	v_add_f32_e32 v6, v67, v6
	v_add_f32_e32 v6, v72, v6
	v_pk_mul_f32 v[68:69], v[20:21], v[20:21]
	v_add_f32_e32 v6, v73, v6
	v_add_f32_e32 v6, v68, v6
	v_pk_mul_f32 v[110:111], v[18:19], v[18:19]
	v_add_f32_e32 v6, v69, v6
	v_add_f32_e32 v6, v110, v6
	v_add_f32_e32 v6, v111, v6
	ds_bpermute_b32 v7, v81, v6
	v_lshlrev_b32_e32 v84, 10, v79
	s_mov_b64 s[2:3], 0x212e8000
	s_waitcnt lgkmcnt(0)
	v_add_f32_e32 v6, v6, v7
	ds_bpermute_b32 v7, v140, v6
	s_waitcnt lgkmcnt(0)
	v_add_f32_e32 v6, v6, v7
	ds_bpermute_b32 v7, v141, v6
	s_waitcnt lgkmcnt(0)
; DI unsigned pack2(float lo, float hi) { f32x2 v = {lo, hi}; bf2_t b = __builtin_convertvector(v, bf2_t); return __builtin_bit_cast(unsigned, b); }
; DI bf16_t f2bf(float x) { return (bf16_t)(pack2(x, 0.f) & 0xffffu); }
; DI void gdn_prep_item(const Params& P, int l, int n, int hh, char* smem) {
;     ...
;       for (int j = 0; j < 4; ++j) { const int row = tabs - 3 + j, rr = row < 0 ? 0 : row;
;         pv[j][0] = *(const u32x4*)(proj + (size_t)rr * DINP + cb); pv[j][1] = *(const u32x4*)(proj + (size_t)rr * DINP + cb + 8);
;         const float* cw = P.gdn_conv + ((size_t)l * 4 + j) * 3072 + cb;
; #pragma unroll
;         for (int e4 = 0; e4 < 4; ++e4) wv[j][e4] = *(const f32x4*)(cw + 4 * e4); }
;     ...
;         const float rn = rsqrtf(ss + EPS) * (X == 0 ? 0.08838834764831845f : 1.f);
; #pragma unroll
;         for (int e = 0; e < 16; ++e) y[e] *= rn; }
;       if (X == 0) {
;         u32x4 p0 = {pack2(y[0], y[1]), pack2(y[2], y[3]), pack2(y[4], y[5]), pack2(y[6], y[7])}, p1 = {pack2(y[8], y[9]), pack2(y[10], y[11]), pack2(y[12], y[13]), pack2(y[14], y[15])};
;         *(u32x4*)(qb16 + t * 272 + part * 32) = p0; *(u32x4*)(qb16 + t * 272 + part * 32 + 16) = p1;
; #pragma unroll
;         for (int b = 0; b < 4; ++b) { u32x2 pk = {pack2(y[4 * b] * egct, y[4 * b + 1] * egct), pack2(y[4 * b + 2] * egct, y[4 * b + 3] * egct)};
;           *(u32x2*)(Qd + t * 128 + 32 * (part >> 1) + 8 * b + 4 * (part & 1)) = pk; }
;       } else if (X == 1) {
;         u32x4 p0 = {pack2(y[0], y[1]), pack2(y[2], y[3]), pack2(y[4], y[5]), pack2(y[6], y[7])}, p1 = {pack2(y[8], y[9]), pack2(y[10], y[11]), pack2(y[12], y[13]), pack2(y[14], y[15])};
;         *(u32x4*)(kb16 + t * 272 + part * 32) = p0; *(u32x4*)(kb16 + t * 272 + part * 32 + 16) = p1;
; #pragma unroll
;         for (int e4 = 0; e4 < 4; ++e4) { f32x4 v = {y[4 * e4], y[4 * e4 + 1], y[4 * e4 + 2], y[4 * e4 + 3]}; *(f32x4*)(kf + t * 128 + part * 16 + 4 * e4) = v; }
; #pragma unroll
;         for (int e = 0; e < 16; ++e) Kt[(part * 16 + e) * 64 + pjt] = f2bf(y[e] * ktl);
	v_add_f32_e32 v6, v6, v7
	v_add_f32_e32 v6, 0x358637bd, v6
	v_mul_f32_e32 v7, 0x4b800000, v6
	v_cmp_gt_f32_e32 vcc, s84, v6
	s_nop 1
	v_cndmask_b32_e32 v6, v6, v7, vcc
	v_rsq_f32_e32 v6, v6
	s_nop 0
	v_mul_f32_e32 v7, 0x45800000, v6
	v_cndmask_b32_e32 v16, v6, v7, vcc
	v_pk_mul_f32 v[2:3], v[2:3], v[16:17] op_sel_hi:[1,0]
	v_pk_mul_f32 v[4:5], v[4:5], v[16:17] op_sel_hi:[1,0]
	v_pk_mul_f32 v[6:7], v[12:13], v[16:17] op_sel_hi:[1,0]
	v_pk_mul_f32 v[8:9], v[48:49], v[16:17] op_sel_hi:[1,0]
	v_pk_mul_f32 v[10:11], v[42:43], v[16:17] op_sel_hi:[1,0]
	v_pk_mul_f32 v[12:13], v[44:45], v[16:17] op_sel_hi:[1,0]
	v_pk_mul_f32 v[14:15], v[20:21], v[16:17] op_sel_hi:[1,0]
	v_pk_mul_f32 v[16:17], v[18:19], v[16:17] op_sel_hi:[1,0]
	v_cvt_pk_bf16_f32 v18, v2, v3
	v_cvt_pk_bf16_f32 v19, v4, v5
	v_cvt_pk_bf16_f32 v20, v6, v7
	v_cvt_pk_bf16_f32 v21, v8, v9
	v_cvt_pk_bf16_f32 v22, v10, v11
	v_cvt_pk_bf16_f32 v23, v12, v13
	v_cvt_pk_bf16_f32 v24, v14, v15
	v_cvt_pk_bf16_f32 v25, v16, v17
	ds_write_b128 v34, v[18:21]
	ds_write_b128 v34, v[22:25] offset:16
	ds_write_b128 v80, v[2:5] offset:34816
	ds_write_b128 v80, v[6:9] offset:34832
	ds_write_b128 v80, v[10:13] offset:34848
	ds_write_b128 v80, v[14:17] offset:34864
	v_add_u32_e32 v18, v35, v84
	v_ashrrev_i32_e32 v19, 31, v18
	v_lshl_add_u64 v[18:19], v[18:19], 1, v[54:55]
	v_lshl_add_u64 v[20:21], v[18:19], 0, s[2:3]
	s_mov_b32 s2, 0x212e8000
	v_mul_f32_e32 v2, v40, v2
	v_add_co_u32_e32 v18, vcc, s2, v18
	v_cvt_pk_bf16_f32 v2, v2, s0
	s_nop 0
	v_addc_co_u32_e32 v19, vcc, 0, v19, vcc
	global_store_short v[18:19], v2, off
	v_mul_f32_e32 v2, v40, v3
	v_cvt_pk_bf16_f32 v2, v2, s0
	global_store_short v[20:21], v2, off offset:128
	v_mul_f32_e32 v2, v40, v4
	v_cvt_pk_bf16_f32 v2, v2, s0
	global_store_short v[20:21], v2, off offset:256
	v_mul_f32_e32 v2, v40, v5
	v_cvt_pk_bf16_f32 v2, v2, s0
	global_store_short v[20:21], v2, off offset:384
	v_mul_f32_e32 v2, v40, v6
	v_cvt_pk_bf16_f32 v2, v2, s0
	global_store_short v[20:21], v2, off offset:512
	v_mul_f32_e32 v2, v40, v7
	v_cvt_pk_bf16_f32 v2, v2, s0
	global_store_short v[20:21], v2, off offset:640
	v_mul_f32_e32 v2, v40, v8
	v_cvt_pk_bf16_f32 v2, v2, s0
	global_store_short v[20:21], v2, off offset:768
	v_mul_f32_e32 v2, v40, v9
	v_cvt_pk_bf16_f32 v2, v2, s0
	global_store_short v[20:21], v2, off offset:896
	v_mul_f32_e32 v2, v40, v10
	v_cvt_pk_bf16_f32 v2, v2, s0
	global_store_short v[20:21], v2, off offset:1024
	v_mul_f32_e32 v2, v40, v11
	v_cvt_pk_bf16_f32 v2, v2, s0
	global_store_short v[20:21], v2, off offset:1152
	v_mul_f32_e32 v2, v40, v12
	v_cvt_pk_bf16_f32 v2, v2, s0
	global_store_short v[20:21], v2, off offset:1280
	v_mul_f32_e32 v2, v40, v13
	v_cvt_pk_bf16_f32 v2, v2, s0
	global_store_short v[20:21], v2, off offset:1408
	v_mul_f32_e32 v2, v40, v14
	v_cvt_pk_bf16_f32 v2, v2, s0
	global_store_short v[20:21], v2, off offset:1536
	v_mul_f32_e32 v2, v40, v15
	v_cvt_pk_bf16_f32 v2, v2, s0
	global_store_short v[20:21], v2, off offset:1664
	v_mul_f32_e32 v2, v40, v16
	v_cvt_pk_bf16_f32 v2, v2, s0
	global_store_short v[20:21], v2, off offset:1792
	v_mul_f32_e32 v2, v40, v17
	v_cvt_pk_bf16_f32 v2, v2, s0
	v_or_b32_e32 v4, 0x800, v74
	global_store_short v[20:21], v2, off offset:1920
	v_lshlrev_b32_e32 v2, 1, v4
	v_mov_b32_e32 v3, v1
	v_lshl_add_u64 v[14:15], v[56:57], 0, v[2:3]
	v_lshlrev_b32_e32 v2, 2, v4
	s_waitcnt vmcnt(0)
	v_lshl_add_u64 v[10:11], v[26:27], 0, v[2:3]
	v_lshl_add_u64 v[30:31], v[10:11], 0, s[0:1]
	v_add_co_u32_e32 v26, vcc, s10, v30
	v_mad_u64_u32 v[6:7], s[2:3], v78, s81, v[14:15]
	v_mad_u64_u32 v[12:13], s[2:3], v77, s81, v[14:15]
	v_lshl_add_u64 v[10:11], v[10:11], 0, s[4:5]
	v_mad_u64_u32 v[16:17], s[2:3], v76, s81, v[14:15]
	v_addc_co_u32_e32 v27, vcc, 0, v31, vcc
	global_load_dwordx4 v[2:5], v[6:7], off
	global_load_dwordx4 v[78:81], v[6:7], off offset:16
	global_load_dwordx4 v[18:21], v[30:31], off
	global_load_dwordx4 v[34:37], v[30:31], off offset:16
	global_load_dwordx4 v[86:89], v[30:31], off offset:32
	global_load_dwordx4 v[66:69], v[30:31], off offset:48
	s_nop 0
	global_load_dwordx4 v[6:9], v[12:13], off
	global_load_dwordx4 v[90:93], v[12:13], off offset:16
	global_load_dwordx4 v[22:25], v[10:11], off
	global_load_dwordx4 v[38:41], v[10:11], off offset:16
	global_load_dwordx4 v[94:97], v[10:11], off offset:32
	global_load_dwordx4 v[70:73], v[10:11], off offset:48
	s_nop 0
	global_load_dwordx4 v[10:13], v[16:17], off
	global_load_dwordx4 v[98:101], v[16:17], off offset:16
	v_lshl_add_u64 v[16:17], v[30:31], 0, s[12:13]
	v_lshl_add_u64 v[114:115], v[30:31], 0, s[14:15]
	v_add_co_u32_e32 v30, vcc, s18, v30
	v_mad_u64_u32 v[32:33], s[2:3], v75, s81, v[14:15]
	s_nop 0
	v_addc_co_u32_e32 v31, vcc, 0, v31, vcc
	global_load_dwordx4 v[42:45], v[16:17], off offset:16
	global_load_dwordx4 v[102:105], v[16:17], off offset:32
	s_nop 0
	global_load_dwordx4 v[26:29], v[26:27], off
	s_nop 0
	global_load_dwordx4 v[106:109], v[16:17], off offset:48
	s_nop 0
	global_load_dwordx4 v[14:17], v[32:33], off
	global_load_dwordx4 v[110:113], v[32:33], off offset:16
	global_load_dwordx4 v[46:49], v[114:115], off offset:16
	global_load_dwordx4 v[74:77], v[114:115], off offset:32
	s_nop 0
	global_load_dwordx4 v[30:33], v[30:31], off
	s_nop 0
	global_load_dwordx4 v[114:117], v[114:115], off offset:48
	s_waitcnt vmcnt(0) lgkmcnt(0)
; DI void unpack8(const u32x4& v, float* f) { f[0] = bflo(v.x); f[1] = bfhi(v.x); f[2] = bflo(v.y); f[3] = bfhi(v.y); f[4] = bflo(v.z); f[5] = bfhi(v.z); f[6] = bflo(v.w); f[7] = bfhi(v.w); }
; DI float silu_f(float x) { return x * __builtin_amdgcn_rcpf(1.f + __expf(-x)); }
; DI void gdn_prep_item(const Params& P, int l, int n, int hh, char* smem) {
;     ...
; #pragma unroll
;       for (int j = 0; j < 4; ++j) { const float msk = (tabs - 3 + j) >= 0 ? 1.f : 0.f;
;         float xv[16]; unpack8(pv[j][0], xv); unpack8(pv[j][1], xv + 8);
; #pragma unroll
;         for (int e4 = 0; e4 < 4; ++e4) { const f32x4 wm = wv[j][e4] * msk; y[4 * e4] += wm.x * xv[4 * e4]; y[4 * e4 + 1] += wm.y * xv[4 * e4 + 1]; y[4 * e4 + 2] += wm.z * xv[4 * e4 + 2]; y[4 * e4 + 3] += wm.w * xv[4 * e4 + 3]; } }
; #pragma unroll
;       for (int e = 0; e < 16; ++e) y[e] = silu_f(y[e]);
	v_pk_mul_f32 v[68:69], v[58:59], v[68:69] op_sel_hi:[0,1]
	v_lshlrev_b32_e32 v124, 16, v81
	v_and_b32_e32 v125, 0xffff0000, v81
	v_pk_mul_f32 v[72:73], v[60:61], v[72:73] op_sel_hi:[0,1]
	v_lshlrev_b32_e32 v122, 16, v93
	v_and_b32_e32 v123, 0xffff0000, v93
	v_pk_fma_f32 v[68:69], v[68:69], v[124:125], 0 op_sel_hi:[1,1,0]
	v_pk_mul_f32 v[118:119], v[58:59], v[66:67] op_sel_hi:[0,1]
	v_pk_fma_f32 v[68:69], v[72:73], v[122:123], v[68:69]
	v_lshlrev_b32_e32 v72, 16, v80
	v_and_b32_e32 v73, 0xffff0000, v80
	v_pk_mul_f32 v[70:71], v[60:61], v[70:71] op_sel_hi:[0,1]
	v_pk_fma_f32 v[72:73], v[118:119], v[72:73], 0 op_sel_hi:[1,1,0]
	v_lshlrev_b32_e32 v80, 16, v92
	v_and_b32_e32 v81, 0xffff0000, v92
	v_pk_mul_f32 v[106:107], v[62:63], v[106:107] op_sel_hi:[0,1]
	v_pk_fma_f32 v[70:71], v[70:71], v[80:81], v[72:73]
	v_lshlrev_b32_e32 v72, 16, v100
	v_and_b32_e32 v73, 0xffff0000, v100
	v_pk_fma_f32 v[70:71], v[106:107], v[72:73], v[70:71]
	v_pk_mul_f32 v[88:89], v[58:59], v[88:89] op_sel_hi:[0,1]
	v_lshlrev_b32_e32 v106, 16, v79
	v_and_b32_e32 v107, 0xffff0000, v79
	v_pk_mul_f32 v[80:81], v[64:65], v[74:75] op_sel_hi:[0,1]
	v_pk_mul_f32 v[74:75], v[62:63], v[104:105] op_sel_hi:[0,1]
	v_pk_mul_f32 v[96:97], v[60:61], v[96:97] op_sel_hi:[0,1]
	v_lshlrev_b32_e32 v104, 16, v91
	v_and_b32_e32 v105, 0xffff0000, v91
	v_pk_fma_f32 v[88:89], v[88:89], v[106:107], 0 op_sel_hi:[1,1,0]
	v_pk_mul_f32 v[92:93], v[62:63], v[102:103] op_sel_hi:[0,1]
	v_lshlrev_b32_e32 v102, 16, v99
	v_and_b32_e32 v103, 0xffff0000, v99
	v_pk_fma_f32 v[88:89], v[96:97], v[104:105], v[88:89]
	v_pk_mul_f32 v[86:87], v[58:59], v[86:87] op_sel_hi:[0,1]
	v_pk_fma_f32 v[74:75], v[74:75], v[102:103], v[88:89]
	v_lshlrev_b32_e32 v88, 16, v78
	v_and_b32_e32 v89, 0xffff0000, v78
	v_pk_mul_f32 v[94:95], v[60:61], v[94:95] op_sel_hi:[0,1]
	v_pk_fma_f32 v[78:79], v[86:87], v[88:89], 0 op_sel_hi:[1,1,0]
	v_lshlrev_b32_e32 v86, 16, v90
	v_and_b32_e32 v87, 0xffff0000, v90
	v_pk_fma_f32 v[78:79], v[94:95], v[86:87], v[78:79]
	v_lshlrev_b32_e32 v86, 16, v98
	v_and_b32_e32 v87, 0xffff0000, v98
	v_pk_fma_f32 v[78:79], v[92:93], v[86:87], v[78:79]
	v_pk_mul_f32 v[36:37], v[58:59], v[36:37] op_sel_hi:[0,1]
	v_lshlrev_b32_e32 v92, 16, v5
	v_and_b32_e32 v93, 0xffff0000, v5
	v_pk_mul_f32 v[40:41], v[60:61], v[40:41] op_sel_hi:[0,1]
	v_lshlrev_b32_e32 v90, 16, v9
	v_and_b32_e32 v91, 0xffff0000, v9
	v_pk_fma_f32 v[36:37], v[36:37], v[92:93], 0 op_sel_hi:[1,1,0]
	v_lshlrev_b32_e32 v86, 16, v110
	v_and_b32_e32 v87, 0xffff0000, v110
	v_pk_mul_f32 v[44:45], v[62:63], v[44:45] op_sel_hi:[0,1]
	v_lshlrev_b32_e32 v88, 16, v13
	v_and_b32_e32 v89, 0xffff0000, v13
	v_pk_fma_f32 v[36:37], v[40:41], v[90:91], v[36:37]
	v_pk_fma_f32 v[78:79], v[80:81], v[86:87], v[78:79]
	v_pk_mul_f32 v[48:49], v[64:65], v[48:49] op_sel_hi:[0,1]
	v_lshlrev_b32_e32 v86, 16, v17
	v_and_b32_e32 v87, 0xffff0000, v17
	v_pk_fma_f32 v[36:37], v[44:45], v[88:89], v[36:37]
	v_pk_mul_f32 v[34:35], v[58:59], v[34:35] op_sel_hi:[0,1]
	v_pk_fma_f32 v[36:37], v[48:49], v[86:87], v[36:37]
	v_lshlrev_b32_e32 v44, 16, v4
	v_mul_f32_e32 v5, 0xbfb8aa3b, v37
	v_exp_f32_e32 v5, v5
	v_and_b32_e32 v45, 0xffff0000, v4
	v_pk_mul_f32 v[38:39], v[60:61], v[38:39] op_sel_hi:[0,1]
	v_pk_mul_f32 v[42:43], v[62:63], v[42:43] op_sel_hi:[0,1]
	v_add_f32_e32 v5, 1.0, v5
	v_rcp_f32_e32 v41, v5
	v_mul_f32_e32 v5, 0xbfb8aa3b, v36
	v_exp_f32_e32 v5, v5
	v_and_b32_e32 v9, 0xffff0000, v12
	v_pk_mul_f32 v[46:47], v[64:65], v[46:47] op_sel_hi:[0,1]
	v_pk_mul_f32 v[20:21], v[58:59], v[20:21] op_sel_hi:[0,1]
	v_add_f32_e32 v5, 1.0, v5
	v_rcp_f32_e32 v40, v5
	v_pk_fma_f32 v[4:5], v[34:35], v[44:45], 0 op_sel_hi:[1,1,0]
	v_lshlrev_b32_e32 v34, 16, v8
	v_and_b32_e32 v35, 0xffff0000, v8
	v_pk_fma_f32 v[4:5], v[38:39], v[34:35], v[4:5]
	v_lshlrev_b32_e32 v8, 16, v12
	v_pk_fma_f32 v[4:5], v[42:43], v[8:9], v[4:5]
	v_lshlrev_b32_e32 v8, 16, v16
	v_and_b32_e32 v9, 0xffff0000, v16
	v_pk_fma_f32 v[8:9], v[46:47], v[8:9], v[4:5]
	v_lshlrev_b32_e32 v38, 16, v3
	v_mul_f32_e32 v4, 0xbfb8aa3b, v9
	v_exp_f32_e32 v4, v4
	v_and_b32_e32 v39, 0xffff0000, v3
	v_pk_mul_f32 v[24:25], v[60:61], v[24:25] op_sel_hi:[0,1]
	v_lshlrev_b32_e32 v34, 16, v7
	v_add_f32_e32 v4, 1.0, v4
	v_rcp_f32_e32 v13, v4
	v_mul_f32_e32 v4, 0xbfb8aa3b, v8
	v_exp_f32_e32 v4, v4
	v_and_b32_e32 v35, 0xffff0000, v7
	v_pk_fma_f32 v[20:21], v[20:21], v[38:39], 0 op_sel_hi:[1,1,0]
	v_pk_mul_f32 v[28:29], v[62:63], v[28:29] op_sel_hi:[0,1]
	v_add_f32_e32 v4, 1.0, v4
	v_rcp_f32_e32 v12, v4
	v_pk_mul_f32 v[4:5], v[64:65], v[32:33] op_sel_hi:[0,1]
	v_lshlrev_b32_e32 v32, 16, v11
	v_and_b32_e32 v33, 0xffff0000, v11
	v_pk_fma_f32 v[20:21], v[24:25], v[34:35], v[20:21]
	v_pk_mul_f32 v[16:17], v[64:65], v[30:31] op_sel_hi:[0,1]
	v_lshlrev_b32_e32 v30, 16, v15
	v_and_b32_e32 v31, 0xffff0000, v15
	v_pk_fma_f32 v[20:21], v[28:29], v[32:33], v[20:21]
	v_pk_mul_f32 v[18:19], v[58:59], v[18:19] op_sel_hi:[0,1]
	v_pk_fma_f32 v[4:5], v[4:5], v[30:31], v[20:21]
	v_lshlrev_b32_e32 v24, 16, v2
	v_mul_f32_e32 v3, 0xbfb8aa3b, v5
	v_exp_f32_e32 v3, v3
	v_and_b32_e32 v25, 0xffff0000, v2
	v_pk_mul_f32 v[22:23], v[60:61], v[22:23] op_sel_hi:[0,1]
	v_pk_mul_f32 v[26:27], v[62:63], v[26:27] op_sel_hi:[0,1]
	v_add_f32_e32 v3, 1.0, v3
	v_rcp_f32_e32 v21, v3
	v_mul_f32_e32 v3, 0xbfb8aa3b, v4
	v_exp_f32_e32 v3, v3
	v_and_b32_e32 v7, 0xffff0000, v10
	v_pk_mul_f32 v[108:109], v[62:63], v[108:109] op_sel_hi:[0,1]
	v_lshlrev_b32_e32 v120, 16, v101
	v_add_f32_e32 v3, 1.0, v3
	v_rcp_f32_e32 v20, v3
	v_pk_fma_f32 v[2:3], v[18:19], v[24:25], 0 op_sel_hi:[1,1,0]
	v_lshlrev_b32_e32 v18, 16, v6
	v_and_b32_e32 v19, 0xffff0000, v6
	v_pk_fma_f32 v[2:3], v[22:23], v[18:19], v[2:3]
; DI void gdn_prep_item(const Params& P, int l, int n, int hh, char* smem) {
;     ...
; #pragma unroll
;         for (int e4 = 0; e4 < 4; ++e4) { f32x4 v = {y[4 * e4], y[4 * e4 + 1], y[4 * e4 + 2], y[4 * e4 + 3]}; *(f32x4*)(vf + t * 128 + part * 16 + 4 * e4) = v; }
;       }
;     }
;     { const int cb = C_AZ + hh * 128 + part * 16; const u32x4 v0 = *(const u32x4*)(proj + (size_t)tabs * DINP + cb), v1 = *(const u32x4*)(proj + (size_t)tabs * DINP + cb + 8);
	v_lshlrev_b32_e32 v6, 16, v10
	v_pk_fma_f32 v[2:3], v[26:27], v[6:7], v[2:3]
	v_lshlrev_b32_e32 v6, 16, v14
	v_and_b32_e32 v7, 0xffff0000, v14
	v_pk_fma_f32 v[2:3], v[16:17], v[6:7], v[2:3]
	v_and_b32_e32 v121, 0xffff0000, v101
	v_pk_mul_f32 v[76:77], v[64:65], v[76:77] op_sel_hi:[0,1]
	v_lshlrev_b32_e32 v100, 16, v111
	v_and_b32_e32 v101, 0xffff0000, v111
	v_mul_f32_e32 v6, 0xbfb8aa3b, v3
	v_pk_mul_f32 v[116:117], v[64:65], v[116:117] op_sel_hi:[0,1]
	v_pk_mul_f32 v[114:115], v[64:65], v[114:115] op_sel_hi:[0,1]
	v_lshlrev_b32_e32 v66, 16, v113
	v_and_b32_e32 v67, 0xffff0000, v113
	v_pk_fma_f32 v[68:69], v[108:109], v[120:121], v[68:69]
	v_lshlrev_b32_e32 v72, 16, v112
	v_and_b32_e32 v73, 0xffff0000, v112
	v_pk_fma_f32 v[74:75], v[76:77], v[100:101], v[74:75]
	v_exp_f32_e32 v6, v6
	v_pk_fma_f32 v[66:67], v[116:117], v[66:67], v[68:69]
	v_pk_fma_f32 v[70:71], v[114:115], v[72:73], v[70:71]
	v_mul_f32_e32 v76, 0xbfb8aa3b, v75
	v_mul_f32_e32 v80, 0xbfb8aa3b, v79
	v_mul_f32_e32 v68, 0xbfb8aa3b, v67
	v_mul_f32_e32 v72, 0xbfb8aa3b, v71
	v_exp_f32_e32 v76, v76
	v_exp_f32_e32 v80, v80
	v_exp_f32_e32 v68, v68
	v_exp_f32_e32 v72, v72
	v_add_f32_e32 v6, 1.0, v6
	v_rcp_f32_e32 v7, v6
	v_mul_f32_e32 v6, 0xbfb8aa3b, v2
	v_add_f32_e32 v76, 1.0, v76
	v_add_f32_e32 v80, 1.0, v80
	v_exp_f32_e32 v6, v6
	v_add_f32_e32 v68, 1.0, v68
	v_add_f32_e32 v72, 1.0, v72
	v_rcp_f32_e32 v77, v76
	v_mul_f32_e32 v76, 0xbfb8aa3b, v74
	v_rcp_f32_e32 v81, v80
	v_mul_f32_e32 v80, 0xbfb8aa3b, v78
	v_rcp_f32_e32 v69, v68
	v_mul_f32_e32 v68, 0xbfb8aa3b, v66
	v_rcp_f32_e32 v73, v72
	v_mul_f32_e32 v72, 0xbfb8aa3b, v70
	v_exp_f32_e32 v76, v76
	v_exp_f32_e32 v80, v80
	v_exp_f32_e32 v68, v68
	v_exp_f32_e32 v72, v72
	v_add_f32_e32 v6, 1.0, v6
	v_rcp_f32_e32 v6, v6
	v_add_f32_e32 v76, 1.0, v76
	v_add_f32_e32 v80, 1.0, v80
	v_add_f32_e32 v68, 1.0, v68
	v_add_f32_e32 v72, 1.0, v72
	v_rcp_f32_e32 v76, v76
	v_rcp_f32_e32 v80, v80
	v_rcp_f32_e32 v68, v68
	v_rcp_f32_e32 v72, v72
	v_pk_mul_f32 v[2:3], v[2:3], v[6:7]
	v_pk_mul_f32 v[4:5], v[4:5], v[20:21]
	ds_write_b128 v83, v[2:5]
	v_pk_mul_f32 v[2:3], v[8:9], v[12:13]
	v_pk_mul_f32 v[4:5], v[36:37], v[40:41]
	ds_write_b128 v83, v[2:5] offset:16
	v_pk_mul_f32 v[2:3], v[78:79], v[80:81]
	v_pk_mul_f32 v[4:5], v[74:75], v[76:77]
	ds_write_b128 v83, v[2:5] offset:32
	v_pk_mul_f32 v[2:3], v[70:71], v[72:73]
	v_pk_mul_f32 v[4:5], v[66:67], v[68:69]
	ds_write_b128 v83, v[2:5] offset:48
	v_mad_i64_i32 v[2:3], s[2:3], v65, s81, v[56:57]
	v_lshl_add_u64 v[2:3], v[2:3], 0, v[0:1]
	v_add_co_u32_e32 v6, vcc, s82, v2
	s_mov_b64 s[2:3], 0x232e8000
	s_nop 0
	v_addc_co_u32_e32 v7, vcc, 0, v3, vcc
	global_load_dwordx4 v[2:5], v[6:7], off offset:2048
	s_nop 0
	global_load_dwordx4 v[6:9], v[6:7], off offset:2064
	v_lshrrev_b32_e32 v28, 2, v82
	v_and_b32_e32 v29, 32, v28
	s_waitcnt vmcnt(0) lgkmcnt(0)
; DI bf16_t f2bf(float x) { return (bf16_t)(pack2(x, 0.f) & 0xffffu); }
; DI void unpack8(const u32x4& v, float* f) { f[0] = bflo(v.x); f[1] = bfhi(v.x); f[2] = bflo(v.y); f[3] = bfhi(v.y); f[4] = bflo(v.z); f[5] = bfhi(v.z); f[6] = bflo(v.w); f[7] = bfhi(v.w); }
; DI float silu_f(float x) { return x * __builtin_amdgcn_rcpf(1.f + __expf(-x)); }
; DI int crow(int r, int h) { return (r & 3) + 8 * (r >> 2) + 4 * h; }
; #define MFMA32(a, b, c) __builtin_amdgcn_mfma_f32_32x32x16_bf16((a), (b), (c), 0, 0, 0)
; DI void gdn_prep_item(const Params& P, int l, int n, int hh, char* smem) {
;     ...
;     { const int cb = C_AZ + hh * 128 + part * 16; const u32x4 v0 = *(const u32x4*)(proj + (size_t)tabs * DINP + cb), v1 = *(const u32x4*)(proj + (size_t)tabs * DINP + cb + 8);
;       float zv[16]; unpack8(v0, zv); unpack8(v1, zv + 8);
; #pragma unroll
;       for (int e = 0; e < 16; ++e) Zt[(part * 16 + e) * 64 + t] = f2bf(silu_f(zv[e])); }
;   }
;   __syncthreads();
;   {
;     const int which = w >> 2, ti = (w >> 1) & 1, tj = w & 1; const char* Ab = which ? qb16 : kb16;
;     f32x16 acc;
; #pragma unroll
;     for (int r = 0; r < 16; ++r) acc[r] = 0.f;
; #pragma unroll
;     for (int s = 0; s < 8; ++s) { const bf16x8 a = *(const bf16x8*)(Ab + (32 * ti + lq) * 272 + (16 * s + 8 * h) * 2), b = *(const bf16x8*)(kb16 + (32 * tj + lq) * 272 + (16 * s + 8 * h) * 2);
;       acc = MFMA32(a, b, acc); }
;     const int j = 32 * tj + lq; const float gj = gcs[j]; const int pj = 32 * (j >> 5) + perm32(j & 31);
; #pragma unroll
;     for (int r = 0; r < 16; ++r) { const int i = 32 * ti + crow(r, h); const float dec = __expf(fminf(gcs[i] - gj, 0.f));
;       if (which == 0) Lm[i * 64 + j] = (j < i) ? gcs[64 + i] * acc[r] * dec : 0.f;
;       else QK[i * 64 + pj] = f2bf((j <= i) ? acc[r] * dec : 0.f); }
	v_lshlrev_b32_e32 v10, 16, v2
	v_and_b32_e32 v11, 0xffff0000, v2
	v_mul_f32_e32 v2, 0xbfb8aa3b, v10
	v_exp_f32_e32 v2, v2
	v_lshlrev_b32_e32 v16, 16, v5
	v_and_b32_e32 v17, 0xffff0000, v5
	v_lshlrev_b32_e32 v22, 16, v8
	v_add_f32_e32 v2, 1.0, v2
	v_rcp_f32_e32 v2, v2
	v_and_b32_e32 v5, 0xffff0000, v8
	v_lshlrev_b32_e32 v12, 16, v3
	v_and_b32_e32 v13, 0xffff0000, v3
	v_mul_f32_e32 v2, v2, v10
	v_cvt_pk_bf16_f32 v8, v2, s0
	v_add_u32_e32 v2, v84, v63
	v_ashrrev_i32_e32 v3, 31, v2
	v_lshlrev_b32_e32 v18, 16, v6
	v_and_b32_e32 v19, 0xffff0000, v6
	v_lshlrev_b32_e32 v20, 16, v7
	v_and_b32_e32 v21, 0xffff0000, v7
	v_lshl_add_u64 v[6:7], v[2:3], 1, v[54:55]
	v_lshl_add_u64 v[2:3], v[6:7], 0, s[2:3]
	s_mov_b32 s2, 0x232e8000
	v_add_co_u32_e32 v6, vcc, s2, v6
	v_lshlrev_b32_e32 v14, 16, v4
	s_nop 0
	v_addc_co_u32_e32 v7, vcc, 0, v7, vcc
	global_store_short v[6:7], v8, off
	v_mul_f32_e32 v6, 0xbfb8aa3b, v11
	v_exp_f32_e32 v6, v6
	v_and_b32_e32 v15, 0xffff0000, v4
	v_lshlrev_b32_e32 v4, 16, v9
	v_and_b32_e32 v0, 0xffff0000, v9
	v_add_f32_e32 v6, 1.0, v6
	v_rcp_f32_e32 v6, v6
	s_movk_i32 s2, 0xff
	v_cmp_lt_u32_e32 vcc, s2, v82
	v_cmp_gt_u32_e64 s[2:3], s97, v82
	v_mul_f32_e32 v6, v6, v11
	v_cvt_pk_bf16_f32 v6, v6, s0
	global_store_short v[2:3], v6, off offset:128
	v_mul_f32_e32 v6, 0xbfb8aa3b, v12
	v_exp_f32_e32 v6, v6
	s_nop 0
	v_add_f32_e32 v6, 1.0, v6
	v_rcp_f32_e32 v6, v6
	s_nop 0
	v_mul_f32_e32 v6, v6, v12
	v_cvt_pk_bf16_f32 v6, v6, s0
	global_store_short v[2:3], v6, off offset:256
	v_mul_f32_e32 v6, 0xbfb8aa3b, v13
	v_exp_f32_e32 v6, v6
	s_nop 0
	v_add_f32_e32 v6, 1.0, v6
	v_rcp_f32_e32 v6, v6
	s_nop 0
	v_mul_f32_e32 v6, v6, v13
	v_cvt_pk_bf16_f32 v6, v6, s0
	global_store_short v[2:3], v6, off offset:384
	v_mul_f32_e32 v6, 0xbfb8aa3b, v14
	v_exp_f32_e32 v6, v6
	s_nop 0
	v_add_f32_e32 v6, 1.0, v6
	v_rcp_f32_e32 v6, v6
	s_nop 0
	v_mul_f32_e32 v6, v6, v14
	v_cvt_pk_bf16_f32 v6, v6, s0
	global_store_short v[2:3], v6, off offset:512
	v_mul_f32_e32 v6, 0xbfb8aa3b, v15
	v_exp_f32_e32 v6, v6
	s_nop 0
	v_add_f32_e32 v6, 1.0, v6
	v_rcp_f32_e32 v6, v6
	s_nop 0
	v_mul_f32_e32 v6, v6, v15
	v_cvt_pk_bf16_f32 v6, v6, s0
	global_store_short v[2:3], v6, off offset:640
	v_mul_f32_e32 v6, 0xbfb8aa3b, v16
	v_exp_f32_e32 v6, v6
	s_nop 0
	v_add_f32_e32 v6, 1.0, v6
	v_rcp_f32_e32 v6, v6
	s_nop 0
	v_mul_f32_e32 v6, v6, v16
	v_cvt_pk_bf16_f32 v6, v6, s0
	global_store_short v[2:3], v6, off offset:768
	v_mul_f32_e32 v6, 0xbfb8aa3b, v17
	v_exp_f32_e32 v6, v6
	s_nop 0
	v_add_f32_e32 v6, 1.0, v6
	v_rcp_f32_e32 v6, v6
	s_nop 0
	v_mul_f32_e32 v6, v6, v17
	v_cvt_pk_bf16_f32 v6, v6, s0
	global_store_short v[2:3], v6, off offset:896
	v_mul_f32_e32 v6, 0xbfb8aa3b, v18
	v_exp_f32_e32 v6, v6
	s_nop 0
	v_add_f32_e32 v6, 1.0, v6
	v_rcp_f32_e32 v6, v6
	s_nop 0
	v_mul_f32_e32 v6, v6, v18
	v_cvt_pk_bf16_f32 v6, v6, s0
	global_store_short v[2:3], v6, off offset:1024
	v_mul_f32_e32 v6, 0xbfb8aa3b, v19
	v_exp_f32_e32 v6, v6
	s_nop 0
	v_add_f32_e32 v6, 1.0, v6
	v_rcp_f32_e32 v6, v6
	s_nop 0
	v_mul_f32_e32 v6, v6, v19
	v_cvt_pk_bf16_f32 v6, v6, s0
	global_store_short v[2:3], v6, off offset:1152
	v_mul_f32_e32 v6, 0xbfb8aa3b, v20
	v_exp_f32_e32 v6, v6
	s_nop 0
	v_add_f32_e32 v6, 1.0, v6
	v_rcp_f32_e32 v6, v6
	s_nop 0
	v_mul_f32_e32 v6, v6, v20
	v_cvt_pk_bf16_f32 v6, v6, s0
	global_store_short v[2:3], v6, off offset:1280
	v_mul_f32_e32 v6, 0xbfb8aa3b, v21
	v_exp_f32_e32 v6, v6
	s_nop 0
	v_add_f32_e32 v6, 1.0, v6
	v_rcp_f32_e32 v6, v6
	s_nop 0
	v_mul_f32_e32 v6, v6, v21
	v_cvt_pk_bf16_f32 v6, v6, s0
	global_store_short v[2:3], v6, off offset:1408
	v_mul_f32_e32 v6, 0xbfb8aa3b, v22
	v_exp_f32_e32 v6, v6
	s_nop 0
	v_add_f32_e32 v6, 1.0, v6
	v_rcp_f32_e32 v6, v6
	s_nop 0
	v_mul_f32_e32 v6, v6, v22
	v_cvt_pk_bf16_f32 v6, v6, s0
	global_store_short v[2:3], v6, off offset:1536
	v_mul_f32_e32 v6, 0xbfb8aa3b, v5
	v_exp_f32_e32 v6, v6
	s_nop 0
	v_add_f32_e32 v6, 1.0, v6
	v_rcp_f32_e32 v6, v6
	s_nop 0
	v_mul_f32_e32 v5, v6, v5
	v_cvt_pk_bf16_f32 v5, v5, s0
	global_store_short v[2:3], v5, off offset:1664
	v_mul_f32_e32 v5, 0xbfb8aa3b, v4
	v_exp_f32_e32 v5, v5
	s_nop 0
	v_add_f32_e32 v5, 1.0, v5
	v_rcp_f32_e32 v5, v5
	s_nop 0
	v_mul_f32_e32 v4, v5, v4
	v_cvt_pk_bf16_f32 v4, v4, s0
	global_store_short v[2:3], v4, off offset:1792
	v_mul_f32_e32 v4, 0xbfb8aa3b, v0
	v_exp_f32_e32 v4, v4
	s_nop 0
	v_add_f32_e32 v4, 1.0, v4
	v_rcp_f32_e32 v4, v4
	s_nop 0
	v_mul_f32_e32 v0, v4, v0
	v_cvt_pk_bf16_f32 v0, v0, s0
	global_store_short v[2:3], v0, off offset:1920
	v_mov_b32_e32 v0, 0x4400
	v_or_b32_e32 v2, v29, v61
	v_lshrrev_b32_e32 v4, 1, v82
	v_cndmask_b32_e64 v0, v0, 0, s[2:3]
	v_mul_u32_u24_e32 v2, 0x110, v2
	v_lshlrev_b32_e32 v3, 4, v59
	v_and_b32_e32 v19, 32, v4
	v_or_b32_e32 v18, v19, v61
	v_add3_u32 v0, v0, v2, v3
	s_waitcnt lgkmcnt(0)
	s_barrier
	v_mad_u32_u24 v30, v18, s11, v3
	ds_read_b128 v[2:5], v0
	ds_read_b128 v[20:23], v0 offset:32
	ds_read_b128 v[6:9], v30
	ds_read_b128 v[24:27], v30 offset:32
	s_waitcnt lgkmcnt(0)
	v_mfma_f32_32x32x16_bf16 v[2:17], v[2:5], v[6:9], 0
	v_mfma_f32_32x32x16_bf16 v[2:17], v[20:23], v[24:27], v[2:17]
	ds_read_b128 v[20:23], v0 offset:64
	ds_read_b128 v[24:27], v30 offset:64
	s_waitcnt lgkmcnt(0)
	v_mfma_f32_32x32x16_bf16 v[2:17], v[20:23], v[24:27], v[2:17]
	ds_read_b128 v[20:23], v0 offset:96
	ds_read_b128 v[24:27], v30 offset:96
	s_waitcnt lgkmcnt(0)
	v_mfma_f32_32x32x16_bf16 v[2:17], v[20:23], v[24:27], v[2:17]
	ds_read_b128 v[20:23], v0 offset:128
	ds_read_b128 v[24:27], v30 offset:128
	s_waitcnt lgkmcnt(0)
	v_mfma_f32_32x32x16_bf16 v[2:17], v[20:23], v[24:27], v[2:17]
	ds_read_b128 v[20:23], v0 offset:160
	ds_read_b128 v[24:27], v30 offset:160
	s_waitcnt lgkmcnt(0)
	v_mfma_f32_32x32x16_bf16 v[2:17], v[20:23], v[24:27], v[2:17]
	ds_read_b128 v[20:23], v0 offset:192
	ds_read_b128 v[24:27], v30 offset:192
	s_waitcnt lgkmcnt(0)
	v_mfma_f32_32x32x16_bf16 v[2:17], v[20:23], v[24:27], v[2:17]
	ds_read_b128 v[20:23], v0 offset:224
	ds_read_b128 v[24:27], v30 offset:224
	s_waitcnt lgkmcnt(0)
	v_mfma_f32_32x32x16_bf16 v[2:17], v[20:23], v[24:27], v[2:17]
	v_lshlrev_b32_e32 v22, 2, v18
	v_or_b32_e32 v0, 0x1c800, v22
	ds_read_b32 v20, v0
	v_lshlrev_b32_e32 v0, 1, v82
	v_and_b32_e32 v0, 24, v0
	v_and_b32_e32 v21, 4, v28
	v_and_b32_e32 v23, 3, v82
	v_or3_b32 v68, v21, v23, v0
	v_lshl_or_b32 v21, v59, 2, v29
	v_lshl_or_b32 v0, v21, 2, v241
	ds_read_b32 v23, v0
	s_waitcnt lgkmcnt(0)
	v_sub_f32_e32 v23, v23, v20
	v_min_f32_e32 v23, 0, v23
	v_mul_f32_e32 v23, 0x3fb8aa3b, v23
	v_exp_f32_e32 v23, v23
	s_and_saveexec_b64 s[2:3], vcc
	s_xor_b64 s[10:11], exec, s[2:3]
	s_cbranch_execz .LBB0_433
	v_mul_f32_e32 v0, v2, v23
	v_cvt_pk_bf16_f32 v0, v0, s0
	v_cmp_le_u32_e64 s[2:3], v18, v21
	s_nop 1
	v_cndmask_b32_e64 v23, 0, v0, s[2:3]
	v_lshlrev_b32_e32 v0, 6, v21
	v_or3_b32 v0, v0, v19, v68
	v_lshlrev_b32_e32 v0, 1, v0
	v_lshl_add_u64 v[24:25], v[52:53], 0, v[0:1]
	global_store_short v[24:25], v23, off

; DI bf16_t f2bf(float x) { return (bf16_t)(pack2(x, 0.f) & 0xffffu); }
; DI int crow(int r, int h) { return (r & 3) + 8 * (r >> 2) + 4 * h; }
; DI void gdn_prep_item(const Params& P, int l, int n, int hh, char* smem) {
;     ...
;     for (int r = 0; r < 16; ++r) { const int i = 32 * ti + crow(r, h); const float dec = __expf(fminf(gcs[i] - gj, 0.f));
;       if (which == 0) Lm[i * 64 + j] = (j < i) ? gcs[64 + i] * acc[r] * dec : 0.f;
;       else QK[i * 64 + pj] = f2bf((j <= i) ? acc[r] * dec : 0.f); }
.LBB0_437:
	s_or_b64 exec, exec, s[10:11]
	v_or_b32_e32 v0, 1, v21
	v_lshl_or_b32 v2, v0, 2, v241
	ds_read_b32 v23, v2
	s_waitcnt lgkmcnt(0)
	v_sub_f32_e32 v23, v23, v20
	v_min_f32_e32 v23, 0, v23
	v_mul_f32_e32 v23, 0x3fb8aa3b, v23
	v_exp_f32_e32 v23, v23
	s_and_saveexec_b64 s[2:3], vcc
	s_xor_b64 s[10:11], exec, s[2:3]
	s_cbranch_execz .LBB0_439
	v_cmp_le_u32_e64 s[2:3], v18, v0
	v_lshlrev_b32_e32 v0, 6, v0
	v_mul_f32_e32 v2, v3, v23
	v_or3_b32 v0, v0, v19, v68
	v_cvt_pk_bf16_f32 v2, v2, s0
	v_lshlrev_b32_e32 v0, 1, v0
	v_cndmask_b32_e64 v2, 0, v2, s[2:3]
	v_lshl_add_u64 v[24:25], v[52:53], 0, v[0:1]
	global_store_short v[24:25], v2, off

; DI bf16_t f2bf(float x) { return (bf16_t)(pack2(x, 0.f) & 0xffffu); }
; DI int crow(int r, int h) { return (r & 3) + 8 * (r >> 2) + 4 * h; }
; DI void gdn_prep_item(const Params& P, int l, int n, int hh, char* smem) {
;     ...
;     for (int r = 0; r < 16; ++r) { const int i = 32 * ti + crow(r, h); const float dec = __expf(fminf(gcs[i] - gj, 0.f));
;       if (which == 0) Lm[i * 64 + j] = (j < i) ? gcs[64 + i] * acc[r] * dec : 0.f;
;       else QK[i * 64 + pj] = f2bf((j <= i) ? acc[r] * dec : 0.f); }
.LBB0_443:
	s_or_b64 exec, exec, s[10:11]
	v_or_b32_e32 v0, 2, v21
	v_lshl_or_b32 v2, v0, 2, v241
	ds_read_b32 v3, v2
	s_waitcnt lgkmcnt(0)
	v_sub_f32_e32 v3, v3, v20
	v_min_f32_e32 v3, 0, v3
	v_mul_f32_e32 v3, 0x3fb8aa3b, v3
	v_exp_f32_e32 v3, v3
	s_and_saveexec_b64 s[2:3], vcc
	s_xor_b64 s[10:11], exec, s[2:3]
	s_cbranch_execz .LBB0_445
	v_cmp_le_u32_e64 s[2:3], v18, v0
	v_lshlrev_b32_e32 v0, 6, v0
	v_mul_f32_e32 v2, v4, v3
	v_or3_b32 v0, v0, v19, v68
	v_cvt_pk_bf16_f32 v2, v2, s0
	v_lshlrev_b32_e32 v0, 1, v0
	v_cndmask_b32_e64 v23, 0, v2, s[2:3]
	v_lshl_add_u64 v[2:3], v[52:53], 0, v[0:1]
	global_store_short v[2:3], v23, off

; DI bf16_t f2bf(float x) { return (bf16_t)(pack2(x, 0.f) & 0xffffu); }
; DI int crow(int r, int h) { return (r & 3) + 8 * (r >> 2) + 4 * h; }
; DI void gdn_prep_item(const Params& P, int l, int n, int hh, char* smem) {
;     ...
;     for (int r = 0; r < 16; ++r) { const int i = 32 * ti + crow(r, h); const float dec = __expf(fminf(gcs[i] - gj, 0.f));
;       if (which == 0) Lm[i * 64 + j] = (j < i) ? gcs[64 + i] * acc[r] * dec : 0.f;
;       else QK[i * 64 + pj] = f2bf((j <= i) ? acc[r] * dec : 0.f); }
.LBB0_449:
	s_or_b64 exec, exec, s[10:11]
	v_or_b32_e32 v0, 3, v21
	v_lshl_or_b32 v2, v0, 2, v241
	ds_read_b32 v3, v2
	s_waitcnt lgkmcnt(0)
	v_sub_f32_e32 v3, v3, v20
	v_min_f32_e32 v3, 0, v3
	v_mul_f32_e32 v3, 0x3fb8aa3b, v3
	v_exp_f32_e32 v3, v3
	s_and_saveexec_b64 s[2:3], vcc
	s_xor_b64 s[10:11], exec, s[2:3]
	s_cbranch_execz .LBB0_451
	v_cmp_le_u32_e64 s[2:3], v18, v0
	v_lshlrev_b32_e32 v0, 6, v0
	v_mul_f32_e32 v2, v5, v3
	v_or3_b32 v0, v0, v19, v68
	v_cvt_pk_bf16_f32 v2, v2, s0
	v_lshlrev_b32_e32 v0, 1, v0
	v_cndmask_b32_e64 v4, 0, v2, s[2:3]
	v_lshl_add_u64 v[2:3], v[52:53], 0, v[0:1]
	global_store_short v[2:3], v4, off

; DI bf16_t f2bf(float x) { return (bf16_t)(pack2(x, 0.f) & 0xffffu); }
; DI int crow(int r, int h) { return (r & 3) + 8 * (r >> 2) + 4 * h; }
; DI void gdn_prep_item(const Params& P, int l, int n, int hh, char* smem) {
;     ...
;     for (int r = 0; r < 16; ++r) { const int i = 32 * ti + crow(r, h); const float dec = __expf(fminf(gcs[i] - gj, 0.f));
;       if (which == 0) Lm[i * 64 + j] = (j < i) ? gcs[64 + i] * acc[r] * dec : 0.f;
;       else QK[i * 64 + pj] = f2bf((j <= i) ? acc[r] * dec : 0.f); }
.LBB0_455:
	s_or_b64 exec, exec, s[10:11]
	v_or_b32_e32 v0, 8, v21
	v_lshl_or_b32 v2, v0, 2, v241
	ds_read_b32 v3, v2
	s_waitcnt lgkmcnt(0)
	v_sub_f32_e32 v3, v3, v20
	v_min_f32_e32 v3, 0, v3
	v_mul_f32_e32 v3, 0x3fb8aa3b, v3
	v_exp_f32_e32 v3, v3
	s_and_saveexec_b64 s[2:3], vcc
	s_xor_b64 s[10:11], exec, s[2:3]
	s_cbranch_execz .LBB0_457
	v_cmp_le_u32_e64 s[2:3], v18, v0
	v_lshlrev_b32_e32 v0, 6, v0
	v_mul_f32_e32 v2, v6, v3
	v_or3_b32 v0, v0, v19, v68
	v_cvt_pk_bf16_f32 v2, v2, s0
	v_lshlrev_b32_e32 v0, 1, v0
	v_cndmask_b32_e64 v4, 0, v2, s[2:3]
	v_lshl_add_u64 v[2:3], v[52:53], 0, v[0:1]
	global_store_short v[2:3], v4, off

; DI bf16_t f2bf(float x) { return (bf16_t)(pack2(x, 0.f) & 0xffffu); }
; DI int crow(int r, int h) { return (r & 3) + 8 * (r >> 2) + 4 * h; }
; DI void gdn_prep_item(const Params& P, int l, int n, int hh, char* smem) {
;     ...
;     for (int r = 0; r < 16; ++r) { const int i = 32 * ti + crow(r, h); const float dec = __expf(fminf(gcs[i] - gj, 0.f));
;       if (which == 0) Lm[i * 64 + j] = (j < i) ? gcs[64 + i] * acc[r] * dec : 0.f;
;       else QK[i * 64 + pj] = f2bf((j <= i) ? acc[r] * dec : 0.f); }
.LBB0_461:
	s_or_b64 exec, exec, s[10:11]
	v_or_b32_e32 v0, 9, v21
	v_lshl_or_b32 v2, v0, 2, v241
	ds_read_b32 v3, v2
	s_waitcnt lgkmcnt(0)
	v_sub_f32_e32 v3, v3, v20
	v_min_f32_e32 v3, 0, v3
	v_mul_f32_e32 v3, 0x3fb8aa3b, v3
	v_exp_f32_e32 v3, v3
	s_and_saveexec_b64 s[2:3], vcc
	s_xor_b64 s[10:11], exec, s[2:3]
	s_cbranch_execz .LBB0_463
	v_cmp_le_u32_e64 s[2:3], v18, v0
	v_lshlrev_b32_e32 v0, 6, v0
	v_mul_f32_e32 v2, v7, v3
	v_or3_b32 v0, v0, v19, v68
	v_cvt_pk_bf16_f32 v2, v2, s0
	v_lshlrev_b32_e32 v0, 1, v0
	v_cndmask_b32_e64 v4, 0, v2, s[2:3]
	v_lshl_add_u64 v[2:3], v[52:53], 0, v[0:1]
	global_store_short v[2:3], v4, off

; DI bf16_t f2bf(float x) { return (bf16_t)(pack2(x, 0.f) & 0xffffu); }
; DI int crow(int r, int h) { return (r & 3) + 8 * (r >> 2) + 4 * h; }
; DI void gdn_prep_item(const Params& P, int l, int n, int hh, char* smem) {
;     ...
;     for (int r = 0; r < 16; ++r) { const int i = 32 * ti + crow(r, h); const float dec = __expf(fminf(gcs[i] - gj, 0.f));
;       if (which == 0) Lm[i * 64 + j] = (j < i) ? gcs[64 + i] * acc[r] * dec : 0.f;
;       else QK[i * 64 + pj] = f2bf((j <= i) ? acc[r] * dec : 0.f); }
.LBB0_467:
	s_or_b64 exec, exec, s[10:11]
	v_or_b32_e32 v0, 10, v21
	v_lshl_or_b32 v2, v0, 2, v241
	ds_read_b32 v3, v2
	s_waitcnt lgkmcnt(0)
	v_sub_f32_e32 v3, v3, v20
	v_min_f32_e32 v3, 0, v3
	v_mul_f32_e32 v3, 0x3fb8aa3b, v3
	v_exp_f32_e32 v3, v3
	s_and_saveexec_b64 s[2:3], vcc
	s_xor_b64 s[10:11], exec, s[2:3]
	s_cbranch_execz .LBB0_469
	v_cmp_le_u32_e64 s[2:3], v18, v0
	v_lshlrev_b32_e32 v0, 6, v0
	v_mul_f32_e32 v2, v8, v3
	v_or3_b32 v0, v0, v19, v68
	v_cvt_pk_bf16_f32 v2, v2, s0
	v_lshlrev_b32_e32 v0, 1, v0
	v_cndmask_b32_e64 v4, 0, v2, s[2:3]
	v_lshl_add_u64 v[2:3], v[52:53], 0, v[0:1]
	global_store_short v[2:3], v4, off

; DI bf16_t f2bf(float x) { return (bf16_t)(pack2(x, 0.f) & 0xffffu); }
; DI int crow(int r, int h) { return (r & 3) + 8 * (r >> 2) + 4 * h; }
; DI void gdn_prep_item(const Params& P, int l, int n, int hh, char* smem) {
;     ...
;     for (int r = 0; r < 16; ++r) { const int i = 32 * ti + crow(r, h); const float dec = __expf(fminf(gcs[i] - gj, 0.f));
;       if (which == 0) Lm[i * 64 + j] = (j < i) ? gcs[64 + i] * acc[r] * dec : 0.f;
;       else QK[i * 64 + pj] = f2bf((j <= i) ? acc[r] * dec : 0.f); }
.LBB0_473:
	s_or_b64 exec, exec, s[10:11]
	v_or_b32_e32 v0, 11, v21
	v_lshl_or_b32 v2, v0, 2, v241
	ds_read_b32 v3, v2
	s_waitcnt lgkmcnt(0)
	v_sub_f32_e32 v3, v3, v20
	v_min_f32_e32 v3, 0, v3
	v_mul_f32_e32 v3, 0x3fb8aa3b, v3
	v_exp_f32_e32 v3, v3
	s_and_saveexec_b64 s[2:3], vcc
	s_xor_b64 s[10:11], exec, s[2:3]
	s_cbranch_execz .LBB0_475
	v_cmp_le_u32_e64 s[2:3], v18, v0
	v_lshlrev_b32_e32 v0, 6, v0
	v_mul_f32_e32 v2, v9, v3
	v_or3_b32 v0, v0, v19, v68
	v_cvt_pk_bf16_f32 v2, v2, s0
	v_lshlrev_b32_e32 v0, 1, v0
	v_cndmask_b32_e64 v4, 0, v2, s[2:3]
	v_lshl_add_u64 v[2:3], v[52:53], 0, v[0:1]
	global_store_short v[2:3], v4, off

; DI bf16_t f2bf(float x) { return (bf16_t)(pack2(x, 0.f) & 0xffffu); }
; DI int crow(int r, int h) { return (r & 3) + 8 * (r >> 2) + 4 * h; }
; DI void gdn_prep_item(const Params& P, int l, int n, int hh, char* smem) {
;     ...
;     for (int r = 0; r < 16; ++r) { const int i = 32 * ti + crow(r, h); const float dec = __expf(fminf(gcs[i] - gj, 0.f));
;       if (which == 0) Lm[i * 64 + j] = (j < i) ? gcs[64 + i] * acc[r] * dec : 0.f;
;       else QK[i * 64 + pj] = f2bf((j <= i) ? acc[r] * dec : 0.f); }
.LBB0_479:
	s_or_b64 exec, exec, s[10:11]
	v_or_b32_e32 v0, 16, v21
	v_lshl_or_b32 v2, v0, 2, v241
	ds_read_b32 v3, v2
	s_waitcnt lgkmcnt(0)
	v_sub_f32_e32 v3, v3, v20
	v_min_f32_e32 v3, 0, v3
	v_mul_f32_e32 v3, 0x3fb8aa3b, v3
	v_exp_f32_e32 v3, v3
	s_and_saveexec_b64 s[2:3], vcc
	s_xor_b64 s[10:11], exec, s[2:3]
	s_cbranch_execz .LBB0_481
	v_cmp_le_u32_e64 s[2:3], v18, v0
	v_lshlrev_b32_e32 v0, 6, v0
	v_mul_f32_e32 v2, v10, v3
	v_or3_b32 v0, v0, v19, v68
	v_cvt_pk_bf16_f32 v2, v2, s0
	v_lshlrev_b32_e32 v0, 1, v0
	v_cndmask_b32_e64 v4, 0, v2, s[2:3]
	v_lshl_add_u64 v[2:3], v[52:53], 0, v[0:1]
	global_store_short v[2:3], v4, off

; DI bf16_t f2bf(float x) { return (bf16_t)(pack2(x, 0.f) & 0xffffu); }
; DI int crow(int r, int h) { return (r & 3) + 8 * (r >> 2) + 4 * h; }
; DI void gdn_prep_item(const Params& P, int l, int n, int hh, char* smem) {
;     ...
;     for (int r = 0; r < 16; ++r) { const int i = 32 * ti + crow(r, h); const float dec = __expf(fminf(gcs[i] - gj, 0.f));
;       if (which == 0) Lm[i * 64 + j] = (j < i) ? gcs[64 + i] * acc[r] * dec : 0.f;
;       else QK[i * 64 + pj] = f2bf((j <= i) ? acc[r] * dec : 0.f); }
.LBB0_485:
	s_or_b64 exec, exec, s[10:11]
	v_or_b32_e32 v0, 17, v21
	v_lshl_or_b32 v2, v0, 2, v241
	ds_read_b32 v3, v2
	s_waitcnt lgkmcnt(0)
	v_sub_f32_e32 v3, v3, v20
	v_min_f32_e32 v3, 0, v3
	v_mul_f32_e32 v3, 0x3fb8aa3b, v3
	v_exp_f32_e32 v3, v3
	s_and_saveexec_b64 s[2:3], vcc
	s_xor_b64 s[10:11], exec, s[2:3]
	s_cbranch_execz .LBB0_487
	v_cmp_le_u32_e64 s[2:3], v18, v0
	v_lshlrev_b32_e32 v0, 6, v0
	v_mul_f32_e32 v2, v11, v3
	v_or3_b32 v0, v0, v19, v68
	v_cvt_pk_bf16_f32 v2, v2, s0
	v_lshlrev_b32_e32 v0, 1, v0
	v_cndmask_b32_e64 v4, 0, v2, s[2:3]
	v_lshl_add_u64 v[2:3], v[52:53], 0, v[0:1]
	global_store_short v[2:3], v4, off

; DI bf16_t f2bf(float x) { return (bf16_t)(pack2(x, 0.f) & 0xffffu); }
; DI int crow(int r, int h) { return (r & 3) + 8 * (r >> 2) + 4 * h; }
; DI void gdn_prep_item(const Params& P, int l, int n, int hh, char* smem) {
;     ...
;     for (int r = 0; r < 16; ++r) { const int i = 32 * ti + crow(r, h); const float dec = __expf(fminf(gcs[i] - gj, 0.f));
;       if (which == 0) Lm[i * 64 + j] = (j < i) ? gcs[64 + i] * acc[r] * dec : 0.f;
;       else QK[i * 64 + pj] = f2bf((j <= i) ? acc[r] * dec : 0.f); }
.LBB0_491:
	s_or_b64 exec, exec, s[10:11]
	v_or_b32_e32 v0, 18, v21
	v_lshl_or_b32 v2, v0, 2, v241
	ds_read_b32 v3, v2
	s_waitcnt lgkmcnt(0)
	v_sub_f32_e32 v3, v3, v20
	v_min_f32_e32 v3, 0, v3
	v_mul_f32_e32 v3, 0x3fb8aa3b, v3
	v_exp_f32_e32 v3, v3
	s_and_saveexec_b64 s[2:3], vcc
	s_xor_b64 s[10:11], exec, s[2:3]
	s_cbranch_execz .LBB0_493
	v_cmp_le_u32_e64 s[2:3], v18, v0
	v_lshlrev_b32_e32 v0, 6, v0
	v_mul_f32_e32 v2, v12, v3
	v_or3_b32 v0, v0, v19, v68
	v_cvt_pk_bf16_f32 v2, v2, s0
	v_lshlrev_b32_e32 v0, 1, v0
	v_cndmask_b32_e64 v4, 0, v2, s[2:3]
	v_lshl_add_u64 v[2:3], v[52:53], 0, v[0:1]
	global_store_short v[2:3], v4, off

; DI bf16_t f2bf(float x) { return (bf16_t)(pack2(x, 0.f) & 0xffffu); }
; DI int crow(int r, int h) { return (r & 3) + 8 * (r >> 2) + 4 * h; }
; DI void gdn_prep_item(const Params& P, int l, int n, int hh, char* smem) {
;     ...
;     for (int r = 0; r < 16; ++r) { const int i = 32 * ti + crow(r, h); const float dec = __expf(fminf(gcs[i] - gj, 0.f));
;       if (which == 0) Lm[i * 64 + j] = (j < i) ? gcs[64 + i] * acc[r] * dec : 0.f;
;       else QK[i * 64 + pj] = f2bf((j <= i) ? acc[r] * dec : 0.f); }
.LBB0_497:
	s_or_b64 exec, exec, s[10:11]
	v_or_b32_e32 v0, 19, v21
	v_lshl_or_b32 v2, v0, 2, v241
	ds_read_b32 v3, v2
	s_waitcnt lgkmcnt(0)
	v_sub_f32_e32 v3, v3, v20
	v_min_f32_e32 v3, 0, v3
	v_mul_f32_e32 v3, 0x3fb8aa3b, v3
	v_exp_f32_e32 v3, v3
	s_and_saveexec_b64 s[2:3], vcc
	s_xor_b64 s[10:11], exec, s[2:3]
	s_cbranch_execz .LBB0_499
	v_cmp_le_u32_e64 s[2:3], v18, v0
	v_lshlrev_b32_e32 v0, 6, v0
	v_mul_f32_e32 v2, v13, v3
	v_or3_b32 v0, v0, v19, v68
	v_cvt_pk_bf16_f32 v2, v2, s0
	v_lshlrev_b32_e32 v0, 1, v0
	v_cndmask_b32_e64 v4, 0, v2, s[2:3]
	v_lshl_add_u64 v[2:3], v[52:53], 0, v[0:1]
	global_store_short v[2:3], v4, off

; DI bf16_t f2bf(float x) { return (bf16_t)(pack2(x, 0.f) & 0xffffu); }
; DI int crow(int r, int h) { return (r & 3) + 8 * (r >> 2) + 4 * h; }
; DI void gdn_prep_item(const Params& P, int l, int n, int hh, char* smem) {
;     ...
;     for (int r = 0; r < 16; ++r) { const int i = 32 * ti + crow(r, h); const float dec = __expf(fminf(gcs[i] - gj, 0.f));
;       if (which == 0) Lm[i * 64 + j] = (j < i) ? gcs[64 + i] * acc[r] * dec : 0.f;
;       else QK[i * 64 + pj] = f2bf((j <= i) ? acc[r] * dec : 0.f); }
.LBB0_503:
	s_or_b64 exec, exec, s[10:11]
	v_or_b32_e32 v0, 24, v21
	v_lshl_or_b32 v2, v0, 2, v241
	ds_read_b32 v3, v2
	s_waitcnt lgkmcnt(0)
	v_sub_f32_e32 v3, v3, v20
	v_min_f32_e32 v3, 0, v3
	v_mul_f32_e32 v3, 0x3fb8aa3b, v3
	v_exp_f32_e32 v3, v3
	s_and_saveexec_b64 s[2:3], vcc
	s_xor_b64 s[10:11], exec, s[2:3]
	s_cbranch_execz .LBB0_505
	v_cmp_le_u32_e64 s[2:3], v18, v0
	v_lshlrev_b32_e32 v0, 6, v0
	v_mul_f32_e32 v2, v14, v3
	v_or3_b32 v0, v0, v19, v68
	v_cvt_pk_bf16_f32 v2, v2, s0
	v_lshlrev_b32_e32 v0, 1, v0
	v_cndmask_b32_e64 v4, 0, v2, s[2:3]
	v_lshl_add_u64 v[2:3], v[52:53], 0, v[0:1]
	global_store_short v[2:3], v4, off

; DI bf16_t f2bf(float x) { return (bf16_t)(pack2(x, 0.f) & 0xffffu); }
; DI int crow(int r, int h) { return (r & 3) + 8 * (r >> 2) + 4 * h; }
; DI void gdn_prep_item(const Params& P, int l, int n, int hh, char* smem) {
;     ...
;     for (int r = 0; r < 16; ++r) { const int i = 32 * ti + crow(r, h); const float dec = __expf(fminf(gcs[i] - gj, 0.f));
;       if (which == 0) Lm[i * 64 + j] = (j < i) ? gcs[64 + i] * acc[r] * dec : 0.f;
;       else QK[i * 64 + pj] = f2bf((j <= i) ? acc[r] * dec : 0.f); }
.LBB0_509:
	s_or_b64 exec, exec, s[10:11]
	v_or_b32_e32 v0, 25, v21
	v_lshl_or_b32 v2, v0, 2, v241
	ds_read_b32 v3, v2
	s_waitcnt lgkmcnt(0)
	v_sub_f32_e32 v3, v3, v20
	v_min_f32_e32 v3, 0, v3
	v_mul_f32_e32 v3, 0x3fb8aa3b, v3
	v_exp_f32_e32 v3, v3
	s_and_saveexec_b64 s[2:3], vcc
	s_xor_b64 s[10:11], exec, s[2:3]
	s_cbranch_execz .LBB0_511
	v_cmp_le_u32_e64 s[2:3], v18, v0
	v_lshlrev_b32_e32 v0, 6, v0
	v_mul_f32_e32 v2, v15, v3
	v_or3_b32 v0, v0, v19, v68
	v_cvt_pk_bf16_f32 v2, v2, s0
	v_lshlrev_b32_e32 v0, 1, v0
	v_cndmask_b32_e64 v4, 0, v2, s[2:3]
	v_lshl_add_u64 v[2:3], v[52:53], 0, v[0:1]
	global_store_short v[2:3], v4, off

; DI bf16_t f2bf(float x) { return (bf16_t)(pack2(x, 0.f) & 0xffffu); }
; DI int crow(int r, int h) { return (r & 3) + 8 * (r >> 2) + 4 * h; }
; DI void gdn_prep_item(const Params& P, int l, int n, int hh, char* smem) {
;     ...
;     for (int r = 0; r < 16; ++r) { const int i = 32 * ti + crow(r, h); const float dec = __expf(fminf(gcs[i] - gj, 0.f));
;       if (which == 0) Lm[i * 64 + j] = (j < i) ? gcs[64 + i] * acc[r] * dec : 0.f;
;       else QK[i * 64 + pj] = f2bf((j <= i) ? acc[r] * dec : 0.f); }
.LBB0_515:
	s_or_b64 exec, exec, s[10:11]
	v_or_b32_e32 v0, 26, v21
	v_lshl_or_b32 v2, v0, 2, v241
	ds_read_b32 v3, v2
	s_waitcnt lgkmcnt(0)
	v_sub_f32_e32 v3, v3, v20
	v_min_f32_e32 v3, 0, v3
	v_mul_f32_e32 v3, 0x3fb8aa3b, v3
	v_exp_f32_e32 v3, v3
	s_and_saveexec_b64 s[2:3], vcc
	s_xor_b64 s[10:11], exec, s[2:3]
	s_cbranch_execz .LBB0_517
	v_cmp_le_u32_e64 s[2:3], v18, v0
	v_lshlrev_b32_e32 v0, 6, v0
	v_mul_f32_e32 v2, v16, v3
	v_or3_b32 v0, v0, v19, v68
	v_cvt_pk_bf16_f32 v2, v2, s0
	v_lshlrev_b32_e32 v0, 1, v0
	v_cndmask_b32_e64 v4, 0, v2, s[2:3]
	v_lshl_add_u64 v[2:3], v[52:53], 0, v[0:1]
	global_store_short v[2:3], v4, off

; DI bf16_t f2bf(float x) { return (bf16_t)(pack2(x, 0.f) & 0xffffu); }
; DI int crow(int r, int h) { return (r & 3) + 8 * (r >> 2) + 4 * h; }
; DI void gdn_prep_item(const Params& P, int l, int n, int hh, char* smem) {
;     ...
;     for (int r = 0; r < 16; ++r) { const int i = 32 * ti + crow(r, h); const float dec = __expf(fminf(gcs[i] - gj, 0.f));
;       if (which == 0) Lm[i * 64 + j] = (j < i) ? gcs[64 + i] * acc[r] * dec : 0.f;
;       else QK[i * 64 + pj] = f2bf((j <= i) ? acc[r] * dec : 0.f); }
.LBB0_521:
	s_or_b64 exec, exec, s[10:11]
	v_or_b32_e32 v0, 27, v21
	v_lshl_or_b32 v21, v0, 2, v241
	ds_read_b32 v2, v21
	s_waitcnt lgkmcnt(0)
	v_sub_f32_e32 v2, v2, v20
	v_min_f32_e32 v2, 0, v2
	v_mul_f32_e32 v2, 0x3fb8aa3b, v2
	v_exp_f32_e32 v2, v2
	s_and_saveexec_b64 s[2:3], vcc
	s_xor_b64 s[2:3], exec, s[2:3]
	s_cbranch_execz .LBB0_523
	v_cmp_le_u32_e32 vcc, v18, v0
	v_lshlrev_b32_e32 v0, 6, v0
	v_mul_f32_e32 v2, v17, v2
	v_or3_b32 v0, v0, v19, v68
	v_cvt_pk_bf16_f32 v2, v2, s0
	v_lshlrev_b32_e32 v0, 1, v0
	v_cndmask_b32_e32 v4, 0, v2, vcc
	v_lshl_add_u64 v[2:3], v[52:53], 0, v[0:1]
	global_store_short v[2:3], v4, off

; DI void gdn_prep_item(const Params& P, int l, int n, int hh, char* smem) {
;     ...
;   if (tid < 256) {
;     const int c = tid; const bool isu = c < 128; const int cc = c & 127;
;     const float* rp = (isu ? vf : kf) + cc; const float* sp = gcs + (isu ? 64 : 192);
;     f32x2 xx[32];
;     f32x4 LA[16], LB[16]; float rh[2];
;     xx[0].x = sp[0] * rp[0];
;     LA[0] = *(const f32x4*)(Lm + 64); rh[1] = sp[1] * rp[128];
; #pragma unroll
;     for (int i = 1; i < 64; ++i) {
;       f32x4 (&CUR)[16] = (i & 1) ? LA : LB; f32x4 (&NXT)[16] = (i & 1) ? LB : LA;
;       if (i + 1 < 64) {
; #pragma unroll
;         for (int c = 0; c < (i + 4) / 4; ++c) NXT[c] = *(const f32x4*)(Lm + (i + 1) * 64 + 4 * c);
;         rh[(i + 1) & 1] = sp[i + 1] * rp[(i + 1) * 128];
;       }
;       __builtin_amdgcn_sched_barrier(0);
;       f32x2 acc = {rh[i & 1], 0.f};
; #pragma unroll
;       for (int p = 0; p < i / 2; ++p) { const f32x2 lp = (p & 1) ? (f32x2){CUR[p >> 1].z, CUR[p >> 1].w} : (f32x2){CUR[p >> 1].x, CUR[p >> 1].y}; acc = acc - lp * xx[p]; }
;       if (i & 1) { const int j = i - 1; const float lj = ((j & 3) == 0) ? CUR[j >> 2].x : CUR[j >> 2].z; acc.x = fmaf(-lj, xx[j >> 1].x, acc.x); }
;       const float xi = acc.x + acc.y;
;       if (i & 1) xx[i >> 1].y = xi; else xx[i >> 1].x = xi;
;       __builtin_amdgcn_sched_barrier(0);
;     }
.LBB0_527:
	s_or_b64 exec, exec, s[2:3]
	v_cmp_gt_i32_e32 vcc, s97, v82
	s_waitcnt lgkmcnt(0)
	s_barrier
	s_and_saveexec_b64 s[2:3], vcc
	s_cbranch_execz .LBB0_418
	v_mov_b32_e32 v0, 0x8800
	v_mov_b32_e32 v2, 0x10800
	v_cmp_gt_i32_e32 vcc, s55, v82
	v_and_b32_e32 v69, 0x7f, v82
	v_mov_b32_e32 v4, 0x18900
	v_cndmask_b32_e32 v0, v0, v2, vcc
	v_lshl_or_b32 v66, v69, 2, v0
	v_mov_b32_e32 v0, 0x300
	v_mov_b32_e32 v2, 0x100
	v_cndmask_b32_e32 v67, v0, v2, vcc
	v_or_b32_e32 v0, 0x1c800, v67
	ds_read2st64_b32 v[2:3], v66 offset1:2
	ds_read_b96 v[8:10], v0
	ds_read_b128 v[4:7], v4
	v_mov_b32_e32 v0, 0x18a00
	s_waitcnt lgkmcnt(0)
	ds_read_b32 v5, v66 offset:1024
	ds_read_b64 v[12:13], v0
	s_movk_i32 s10, 0x7f
	v_mul_f32_e32 v2, v8, v2
	v_mul_f32_e32 v3, v9, v3
	v_cmp_lt_i32_e32 vcc, s10, v82
	s_waitcnt lgkmcnt(0)
	v_mul_f32_e32 v0, v10, v5
	v_fma_f32 v3, -v4, v2, v3
	v_add_f32_e32 v3, 0, v3
	v_or_b32_e32 v4, 0x1c80c, v67
	ds_read_b32 v5, v66 offset:1536
	ds_read_b32 v4, v4
	v_mov_b32_e32 v6, 0x18b00
	ds_read_b128 v[6:9], v6
	s_waitcnt lgkmcnt(0)
	v_mul_f32_e32 v14, v4, v5
	v_pk_fma_f32 v[4:5], v[12:13], v[2:3], v[0:1] neg_lo:[1,0,0] neg_hi:[1,0,0]
	s_nop 0
	v_pk_add_f32 v[4:5], v[4:5], v[4:5] op_sel:[0,1] op_sel_hi:[1,0]
	v_or_b32_e32 v0, 0x1c810, v67
	v_mov_b32_e32 v9, 0x18c00
	ds_read_b32 v5, v66 offset:2048
	ds_read_b32 v0, v0
	ds_read_b128 v[10:13], v9
	s_waitcnt lgkmcnt(0)
	v_mul_f32_e32 v0, v0, v5
	v_mov_b32_e32 v15, v1
	v_pk_fma_f32 v[6:7], v[2:3], v[6:7], v[14:15] neg_lo:[1,0,0] neg_hi:[1,0,0]
	s_nop 0
	v_fma_f32 v5, -v8, v4, v6
	v_add_f32_e32 v5, v7, v5
	v_mov_b32_e32 v6, 0x18d00
	ds_read_b128 v[14:17], v6
	v_mov_b32_e32 v6, 0x18d10
	ds_read_b128 v[18:21], v6
	v_or_b32_e32 v6, 0x1c814, v67
	ds_read_b32 v6, v6
	ds_read_b32 v7, v66 offset:2560
	s_waitcnt lgkmcnt(0)
	v_mul_f32_e32 v20, v6, v7
	v_pk_fma_f32 v[6:7], v[2:3], v[10:11], v[0:1] neg_lo:[1,0,0] neg_hi:[1,0,0]
	s_nop 0
	v_pk_fma_f32 v[6:7], v[12:13], v[4:5], v[6:7] neg_lo:[1,0,0] neg_hi:[1,0,0]
	s_nop 0
	v_pk_add_f32 v[6:7], v[6:7], v[6:7] op_sel:[0,1] op_sel_hi:[1,0]
	v_or_b32_e32 v0, 0x1c818, v67
	v_mov_b32_e32 v8, 0x18e00
	v_mov_b32_e32 v12, 0x18e10
	ds_read_b32 v0, v0
	ds_read_b32 v7, v66 offset:3072
	ds_read_b128 v[8:11], v8
	ds_read_b64 v[22:23], v12
	s_waitcnt lgkmcnt(0)
	v_mul_f32_e32 v0, v0, v7
	v_mov_b32_e32 v21, v1
	v_pk_fma_f32 v[12:13], v[2:3], v[14:15], v[20:21] neg_lo:[1,0,0] neg_hi:[1,0,0]
	s_nop 0
	v_pk_fma_f32 v[12:13], v[4:5], v[16:17], v[12:13] neg_lo:[1,0,0] neg_hi:[1,0,0]
	s_nop 0
	v_fma_f32 v7, -v18, v6, v12
	v_add_f32_e32 v7, v13, v7
	v_or_b32_e32 v12, 0x1c81c, v67
	ds_read_b32 v20, v12
	ds_read_b32 v21, v66 offset:3584
	v_mov_b32_e32 v12, 0x18f00
	v_mov_b32_e32 v16, 0x18f10
	ds_read_b128 v[12:15], v12
	ds_read_b128 v[16:19], v16
	s_waitcnt lgkmcnt(0)
	v_mul_f32_e32 v28, v20, v21
	v_pk_fma_f32 v[8:9], v[2:3], v[8:9], v[0:1] neg_lo:[1,0,0] neg_hi:[1,0,0]
	s_nop 0
	v_pk_fma_f32 v[8:9], v[4:5], v[10:11], v[8:9] neg_lo:[1,0,0] neg_hi:[1,0,0]
	s_nop 0
	v_pk_fma_f32 v[8:9], v[22:23], v[6:7], v[8:9] neg_lo:[1,0,0] neg_hi:[1,0,0]
	s_nop 0
	v_pk_add_f32 v[8:9], v[8:9], v[8:9] op_sel:[0,1] op_sel_hi:[1,0]
	v_or_b32_e32 v0, 0x1c820, v67
	v_mov_b32_e32 v10, 0x19000
	ds_read_b32 v0, v0
	ds_read_b32 v9, v66 offset:4096
	ds_read_b128 v[20:23], v10
	v_mov_b32_e32 v10, 0x19010
	ds_read_b128 v[24:27], v10
	s_waitcnt lgkmcnt(0)
	v_mul_f32_e32 v0, v0, v9
	v_mov_b32_e32 v29, v1
	v_pk_fma_f32 v[10:11], v[2:3], v[12:13], v[28:29] neg_lo:[1,0,0] neg_hi:[1,0,0]
	s_nop 0
	v_pk_fma_f32 v[10:11], v[4:5], v[14:15], v[10:11] neg_lo:[1,0,0] neg_hi:[1,0,0]
	s_nop 0
	v_pk_fma_f32 v[10:11], v[6:7], v[16:17], v[10:11] neg_lo:[1,0,0] neg_hi:[1,0,0]
	s_nop 0
	v_fma_f32 v9, -v18, v8, v10
	v_add_f32_e32 v9, v11, v9
	v_or_b32_e32 v10, 0x1c824, v67
	v_mov_b32_e32 v11, 0x19120
	ds_read_b128 v[12:15], v11
	ds_read_b32 v10, v10
	ds_read_b32 v11, v66 offset:4608
	s_waitcnt lgkmcnt(0)
	v_mov_b32_e32 v13, 0x19100
	ds_read_b128 v[14:17], v13
	v_mov_b32_e32 v13, 0x19110
	ds_read_b128 v[28:31], v13
	v_mul_f32_e32 v32, v10, v11
	v_pk_fma_f32 v[10:11], v[2:3], v[20:21], v[0:1] neg_lo:[1,0,0] neg_hi:[1,0,0]
	s_nop 0
	v_pk_fma_f32 v[10:11], v[4:5], v[22:23], v[10:11] neg_lo:[1,0,0] neg_hi:[1,0,0]
	s_nop 0
	v_pk_fma_f32 v[10:11], v[6:7], v[24:25], v[10:11] neg_lo:[1,0,0] neg_hi:[1,0,0]
	s_nop 0
	v_pk_fma_f32 v[10:11], v[26:27], v[8:9], v[10:11] neg_lo:[1,0,0] neg_hi:[1,0,0]
	s_nop 0
	v_pk_add_f32 v[10:11], v[10:11], v[10:11] op_sel:[0,1] op_sel_hi:[1,0]
	v_or_b32_e32 v0, 0x1c828, v67
	v_mov_b32_e32 v11, 0x19220
	v_mov_b32_e32 v13, 0x19200
	ds_read_b64 v[34:35], v11
	ds_read_b32 v0, v0
	ds_read_b32 v11, v66 offset:5120
	ds_read_b128 v[18:21], v13
	v_mov_b32_e32 v13, 0x19210
	ds_read_b128 v[22:25], v13
	s_waitcnt lgkmcnt(0)
	v_mul_f32_e32 v0, v0, v11
	v_mov_b32_e32 v33, v1
	v_pk_fma_f32 v[14:15], v[2:3], v[14:15], v[32:33] neg_lo:[1,0,0] neg_hi:[1,0,0]
	s_nop 0
	v_pk_fma_f32 v[14:15], v[4:5], v[16:17], v[14:15] neg_lo:[1,0,0] neg_hi:[1,0,0]
	s_nop 0
	v_pk_fma_f32 v[14:15], v[6:7], v[28:29], v[14:15] neg_lo:[1,0,0] neg_hi:[1,0,0]
	s_nop 0
	v_pk_fma_f32 v[14:15], v[8:9], v[30:31], v[14:15] neg_lo:[1,0,0] neg_hi:[1,0,0]
	s_nop 0
	v_fma_f32 v11, -v12, v10, v14
	v_add_f32_e32 v11, v15, v11
	v_or_b32_e32 v12, 0x1c82c, v67
	v_mov_b32_e32 v13, 0x19320
	ds_read_b128 v[14:17], v13
	ds_read_b32 v12, v12
	ds_read_b32 v13, v66 offset:5632
	s_waitcnt lgkmcnt(0)
; DI void gdn_prep_item(const Params& P, int l, int n, int hh, char* smem) {
;     ...
;     for (int i = 1; i < 64; ++i) {
;       f32x4 (&CUR)[16] = (i & 1) ? LA : LB; f32x4 (&NXT)[16] = (i & 1) ? LB : LA;
;       if (i + 1 < 64) {
; #pragma unroll
;         for (int c = 0; c < (i + 4) / 4; ++c) NXT[c] = *(const f32x4*)(Lm + (i + 1) * 64 + 4 * c);
;         rh[(i + 1) & 1] = sp[i + 1] * rp[(i + 1) * 128];
;       }
;       __builtin_amdgcn_sched_barrier(0);
;       f32x2 acc = {rh[i & 1], 0.f};
; #pragma unroll
;       for (int p = 0; p < i / 2; ++p) { const f32x2 lp = (p & 1) ? (f32x2){CUR[p >> 1].z, CUR[p >> 1].w} : (f32x2){CUR[p >> 1].x, CUR[p >> 1].y}; acc = acc - lp * xx[p]; }
;       if (i & 1) { const int j = i - 1; const float lj = ((j & 3) == 0) ? CUR[j >> 2].x : CUR[j >> 2].z; acc.x = fmaf(-lj, xx[j >> 1].x, acc.x); }
;       const float xi = acc.x + acc.y;
;       if (i & 1) xx[i >> 1].y = xi; else xx[i >> 1].x = xi;
;       __builtin_amdgcn_sched_barrier(0);
;     }
	v_mov_b32_e32 v17, 0x19300
	ds_read_b128 v[26:29], v17
	v_mov_b32_e32 v17, 0x19310
	ds_read_b128 v[30:33], v17
	v_mul_f32_e32 v38, v12, v13
	v_pk_fma_f32 v[12:13], v[2:3], v[18:19], v[0:1] neg_lo:[1,0,0] neg_hi:[1,0,0]
	s_nop 0
	v_pk_fma_f32 v[12:13], v[4:5], v[20:21], v[12:13] neg_lo:[1,0,0] neg_hi:[1,0,0]
	s_nop 0
	v_pk_fma_f32 v[12:13], v[6:7], v[22:23], v[12:13] neg_lo:[1,0,0] neg_hi:[1,0,0]
	s_nop 0
	v_pk_fma_f32 v[12:13], v[8:9], v[24:25], v[12:13] neg_lo:[1,0,0] neg_hi:[1,0,0]
	s_nop 0
	v_pk_fma_f32 v[12:13], v[34:35], v[10:11], v[12:13] neg_lo:[1,0,0] neg_hi:[1,0,0]
	s_nop 0
	v_pk_add_f32 v[12:13], v[12:13], v[12:13] op_sel:[0,1] op_sel_hi:[1,0]
	v_or_b32_e32 v0, 0x1c830, v67
	v_mov_b32_e32 v13, 0x19420
	v_mov_b32_e32 v17, 0x19400
	ds_read_b128 v[18:21], v13
	ds_read_b32 v0, v0
	ds_read_b32 v13, v66 offset:6144
	ds_read_b128 v[22:25], v17
	v_mov_b32_e32 v17, 0x19410
	ds_read_b128 v[34:37], v17
	s_waitcnt lgkmcnt(0)
	v_mul_f32_e32 v0, v0, v13
	v_mov_b32_e32 v39, v1
	v_pk_fma_f32 v[26:27], v[2:3], v[26:27], v[38:39] neg_lo:[1,0,0] neg_hi:[1,0,0]
	s_nop 0
	v_pk_fma_f32 v[26:27], v[4:5], v[28:29], v[26:27] neg_lo:[1,0,0] neg_hi:[1,0,0]
	s_nop 0
	v_pk_fma_f32 v[26:27], v[6:7], v[30:31], v[26:27] neg_lo:[1,0,0] neg_hi:[1,0,0]
	s_nop 0
	v_pk_fma_f32 v[26:27], v[8:9], v[32:33], v[26:27] neg_lo:[1,0,0] neg_hi:[1,0,0]
	s_nop 0
	v_pk_fma_f32 v[14:15], v[10:11], v[14:15], v[26:27] neg_lo:[1,0,0] neg_hi:[1,0,0]
	s_nop 0
	v_fma_f32 v13, -v16, v12, v14
	v_add_f32_e32 v13, v15, v13
	v_mov_b32_e32 v14, 0x19500
	ds_read_b128 v[26:29], v14
	v_mov_b32_e32 v14, 0x19510
	ds_read_b128 v[30:33], v14
	v_mov_b32_e32 v14, 0x19520
	ds_read_b128 v[38:41], v14
	v_mov_b32_e32 v14, 0x19530
	ds_read_b128 v[42:45], v14
	v_or_b32_e32 v14, 0x1c834, v67
	ds_read_b32 v14, v14
	ds_read_b32 v15, v66 offset:6656
	s_waitcnt lgkmcnt(0)
	v_mul_f32_e32 v44, v14, v15
	v_pk_fma_f32 v[14:15], v[2:3], v[22:23], v[0:1] neg_lo:[1,0,0] neg_hi:[1,0,0]
	s_nop 0
	v_pk_fma_f32 v[14:15], v[4:5], v[24:25], v[14:15] neg_lo:[1,0,0] neg_hi:[1,0,0]
	s_nop 0
	v_pk_fma_f32 v[14:15], v[6:7], v[34:35], v[14:15] neg_lo:[1,0,0] neg_hi:[1,0,0]
	s_nop 0
	v_pk_fma_f32 v[14:15], v[8:9], v[36:37], v[14:15] neg_lo:[1,0,0] neg_hi:[1,0,0]
	s_nop 0
	v_pk_fma_f32 v[14:15], v[10:11], v[18:19], v[14:15] neg_lo:[1,0,0] neg_hi:[1,0,0]
	s_nop 0
	v_pk_fma_f32 v[14:15], v[20:21], v[12:13], v[14:15] neg_lo:[1,0,0] neg_hi:[1,0,0]
	s_nop 0
	v_pk_add_f32 v[14:15], v[14:15], v[14:15] op_sel:[0,1] op_sel_hi:[1,0]
	v_mov_b32_e32 v0, 0x19600
	ds_read_b128 v[16:19], v0
	v_mov_b32_e32 v0, 0x19610
	ds_read_b128 v[20:23], v0
	v_or_b32_e32 v0, 0x1c838, v67
	v_mov_b32_e32 v24, 0x19620
	ds_read_b32 v0, v0
	ds_read_b32 v15, v66 offset:7168
	ds_read_b128 v[34:37], v24
	v_mov_b32_e32 v24, 0x19630
	ds_read_b64 v[46:47], v24
	s_waitcnt lgkmcnt(0)
	v_mul_f32_e32 v0, v0, v15
	v_mov_b32_e32 v45, v1
	v_pk_fma_f32 v[24:25], v[2:3], v[26:27], v[44:45] neg_lo:[1,0,0] neg_hi:[1,0,0]
	s_nop 0
	v_pk_fma_f32 v[24:25], v[4:5], v[28:29], v[24:25] neg_lo:[1,0,0] neg_hi:[1,0,0]
	s_nop 0
	v_pk_fma_f32 v[24:25], v[6:7], v[30:31], v[24:25] neg_lo:[1,0,0] neg_hi:[1,0,0]
	s_nop 0
	v_pk_fma_f32 v[24:25], v[8:9], v[32:33], v[24:25] neg_lo:[1,0,0] neg_hi:[1,0,0]
	s_nop 0
	v_pk_fma_f32 v[24:25], v[10:11], v[38:39], v[24:25] neg_lo:[1,0,0] neg_hi:[1,0,0]
	s_nop 0
	v_pk_fma_f32 v[24:25], v[12:13], v[40:41], v[24:25] neg_lo:[1,0,0] neg_hi:[1,0,0]
	s_nop 0
	v_fma_f32 v15, -v42, v14, v24
	v_add_f32_e32 v15, v25, v15
	v_mov_b32_e32 v24, 0x19700
	v_mov_b32_e32 v28, 0x19710
	v_or_b32_e32 v32, 0x1c83c, v67
	ds_read_b128 v[24:27], v24
	ds_read_b128 v[28:31], v28
	ds_read_b32 v32, v32
	ds_read_b32 v33, v66 offset:7680
	v_mov_b32_e32 v38, 0x19720
	v_mov_b32_e32 v42, 0x19730
	ds_read_b128 v[38:41], v38
	ds_read_b128 v[42:45], v42
	s_waitcnt lgkmcnt(0)
	v_mul_f32_e32 v56, v32, v33
	v_pk_fma_f32 v[16:17], v[2:3], v[16:17], v[0:1] neg_lo:[1,0,0] neg_hi:[1,0,0]
	s_nop 0
	v_pk_fma_f32 v[16:17], v[4:5], v[18:19], v[16:17] neg_lo:[1,0,0] neg_hi:[1,0,0]
	s_nop 0
	v_pk_fma_f32 v[16:17], v[6:7], v[20:21], v[16:17] neg_lo:[1,0,0] neg_hi:[1,0,0]
	s_nop 0
	v_pk_fma_f32 v[16:17], v[8:9], v[22:23], v[16:17] neg_lo:[1,0,0] neg_hi:[1,0,0]
	s_nop 0
	v_pk_fma_f32 v[16:17], v[10:11], v[34:35], v[16:17] neg_lo:[1,0,0] neg_hi:[1,0,0]
	s_nop 0
	v_pk_fma_f32 v[16:17], v[12:13], v[36:37], v[16:17] neg_lo:[1,0,0] neg_hi:[1,0,0]
	s_nop 0
	v_pk_fma_f32 v[16:17], v[46:47], v[14:15], v[16:17] neg_lo:[1,0,0] neg_hi:[1,0,0]
	s_nop 0
	v_pk_add_f32 v[16:17], v[16:17], v[16:17] op_sel:[0,1] op_sel_hi:[1,0]
	v_mov_b32_e32 v0, 0x19800
	ds_read_b128 v[18:21], v0
	v_mov_b32_e32 v0, 0x19810
	ds_read_b128 v[32:35], v0
	v_or_b32_e32 v0, 0x1c840, v67
	v_mov_b32_e32 v22, 0x19820
	ds_read_b32 v0, v0
	ds_read_b32 v17, v66 offset:8192
	ds_read_b128 v[46:49], v22
	v_mov_b32_e32 v22, 0x19830
	ds_read_b128 v[52:55], v22
	s_waitcnt lgkmcnt(0)
	v_mul_f32_e32 v0, v0, v17
	v_mov_b32_e32 v57, v1
	v_pk_fma_f32 v[22:23], v[2:3], v[24:25], v[56:57] neg_lo:[1,0,0] neg_hi:[1,0,0]
	s_nop 0
	v_pk_fma_f32 v[22:23], v[4:5], v[26:27], v[22:23] neg_lo:[1,0,0] neg_hi:[1,0,0]
	s_nop 0
	v_pk_fma_f32 v[22:23], v[6:7], v[28:29], v[22:23] neg_lo:[1,0,0] neg_hi:[1,0,0]
	s_nop 0
	v_pk_fma_f32 v[22:23], v[8:9], v[30:31], v[22:23] neg_lo:[1,0,0] neg_hi:[1,0,0]
	s_nop 0
	v_pk_fma_f32 v[22:23], v[10:11], v[38:39], v[22:23] neg_lo:[1,0,0] neg_hi:[1,0,0]
	s_nop 0
	v_pk_fma_f32 v[22:23], v[12:13], v[40:41], v[22:23] neg_lo:[1,0,0] neg_hi:[1,0,0]
	s_nop 0
	v_pk_fma_f32 v[22:23], v[14:15], v[42:43], v[22:23] neg_lo:[1,0,0] neg_hi:[1,0,0]
	s_nop 0
	v_fma_f32 v17, -v44, v16, v22
	v_add_f32_e32 v17, v23, v17
	v_mov_b32_e32 v22, 0x19900
	v_mov_b32_e32 v26, 0x19910
	v_or_b32_e32 v30, 0x1c844, v67
	v_mov_b32_e32 v31, 0x19940
	ds_read_b128 v[22:25], v22
	ds_read_b128 v[26:29], v26
	ds_read_b128 v[36:39], v31
	ds_read_b32 v30, v30
	ds_read_b32 v31, v66 offset:8704
	s_waitcnt lgkmcnt(0)
; DI void gdn_prep_item(const Params& P, int l, int n, int hh, char* smem) {
;     ...
;     for (int i = 1; i < 64; ++i) {
;       f32x4 (&CUR)[16] = (i & 1) ? LA : LB; f32x4 (&NXT)[16] = (i & 1) ? LB : LA;
;       if (i + 1 < 64) {
; #pragma unroll
;         for (int c = 0; c < (i + 4) / 4; ++c) NXT[c] = *(const f32x4*)(Lm + (i + 1) * 64 + 4 * c);
;         rh[(i + 1) & 1] = sp[i + 1] * rp[(i + 1) * 128];
;       }
;       __builtin_amdgcn_sched_barrier(0);
;       f32x2 acc = {rh[i & 1], 0.f};
; #pragma unroll
;       for (int p = 0; p < i / 2; ++p) { const f32x2 lp = (p & 1) ? (f32x2){CUR[p >> 1].z, CUR[p >> 1].w} : (f32x2){CUR[p >> 1].x, CUR[p >> 1].y}; acc = acc - lp * xx[p]; }
;       if (i & 1) { const int j = i - 1; const float lj = ((j & 3) == 0) ? CUR[j >> 2].x : CUR[j >> 2].z; acc.x = fmaf(-lj, xx[j >> 1].x, acc.x); }
;       const float xi = acc.x + acc.y;
;       if (i & 1) xx[i >> 1].y = xi; else xx[i >> 1].x = xi;
;       __builtin_amdgcn_sched_barrier(0);
;     }
	v_mov_b32_e32 v37, 0x19920
	ds_read_b128 v[38:41], v37
	v_mov_b32_e32 v37, 0x19930
	ds_read_b128 v[42:45], v37
	v_mul_f32_e32 v60, v30, v31
	v_pk_fma_f32 v[18:19], v[2:3], v[18:19], v[0:1] neg_lo:[1,0,0] neg_hi:[1,0,0]
	s_nop 0
	v_pk_fma_f32 v[18:19], v[4:5], v[20:21], v[18:19] neg_lo:[1,0,0] neg_hi:[1,0,0]
	s_nop 0
	v_pk_fma_f32 v[18:19], v[6:7], v[32:33], v[18:19] neg_lo:[1,0,0] neg_hi:[1,0,0]
	s_nop 0
	v_pk_fma_f32 v[18:19], v[8:9], v[34:35], v[18:19] neg_lo:[1,0,0] neg_hi:[1,0,0]
	s_nop 0
	v_pk_fma_f32 v[18:19], v[10:11], v[46:47], v[18:19] neg_lo:[1,0,0] neg_hi:[1,0,0]
	s_nop 0
	v_pk_fma_f32 v[18:19], v[12:13], v[48:49], v[18:19] neg_lo:[1,0,0] neg_hi:[1,0,0]
	s_nop 0
	v_pk_fma_f32 v[18:19], v[14:15], v[52:53], v[18:19] neg_lo:[1,0,0] neg_hi:[1,0,0]
	s_nop 0
	v_pk_fma_f32 v[18:19], v[54:55], v[16:17], v[18:19] neg_lo:[1,0,0] neg_hi:[1,0,0]
	s_nop 0
	v_pk_add_f32 v[18:19], v[18:19], v[18:19] op_sel:[0,1] op_sel_hi:[1,0]
	v_mov_b32_e32 v0, 0x19a00
	ds_read_b128 v[30:33], v0
	v_mov_b32_e32 v0, 0x19a10
	ds_read_b128 v[46:49], v0
	v_or_b32_e32 v0, 0x1c848, v67
	v_mov_b32_e32 v19, 0x19a40
	v_mov_b32_e32 v34, 0x19a20
	ds_read_b64 v[20:21], v19
	ds_read_b32 v0, v0
	ds_read_b32 v19, v66 offset:9216
	ds_read_b128 v[52:55], v34
	v_mov_b32_e32 v34, 0x19a30
	ds_read_b128 v[56:59], v34
	s_waitcnt lgkmcnt(0)
	v_mul_f32_e32 v0, v0, v19
	v_mov_b32_e32 v61, v1
	v_pk_fma_f32 v[22:23], v[2:3], v[22:23], v[60:61] neg_lo:[1,0,0] neg_hi:[1,0,0]
	s_nop 0
	v_pk_fma_f32 v[22:23], v[4:5], v[24:25], v[22:23] neg_lo:[1,0,0] neg_hi:[1,0,0]
	s_nop 0
	v_pk_fma_f32 v[22:23], v[6:7], v[26:27], v[22:23] neg_lo:[1,0,0] neg_hi:[1,0,0]
	s_nop 0
	v_pk_fma_f32 v[22:23], v[8:9], v[28:29], v[22:23] neg_lo:[1,0,0] neg_hi:[1,0,0]
	s_nop 0
	v_pk_fma_f32 v[22:23], v[10:11], v[38:39], v[22:23] neg_lo:[1,0,0] neg_hi:[1,0,0]
	s_nop 0
	v_pk_fma_f32 v[22:23], v[12:13], v[40:41], v[22:23] neg_lo:[1,0,0] neg_hi:[1,0,0]
	s_nop 0
	v_pk_fma_f32 v[22:23], v[14:15], v[42:43], v[22:23] neg_lo:[1,0,0] neg_hi:[1,0,0]
	s_nop 0
	v_pk_fma_f32 v[22:23], v[16:17], v[44:45], v[22:23] neg_lo:[1,0,0] neg_hi:[1,0,0]
	s_nop 0
	v_fma_f32 v19, -v36, v18, v22
	v_add_f32_e32 v19, v23, v19
	v_mov_b32_e32 v34, 0x19b40
	v_mov_b32_e32 v22, 0x19b00
	v_mov_b32_e32 v26, 0x19b10
	v_or_b32_e32 v38, 0x1c84c, v67
	ds_read_b128 v[34:37], v34
	ds_read_b128 v[22:25], v22
	ds_read_b128 v[26:29], v26
	s_waitcnt lgkmcnt(0)
	ds_read_b32 v37, v38
	ds_read_b32 v60, v66 offset:9728
	v_mov_b32_e32 v38, 0x19b20
	v_mov_b32_e32 v42, 0x19b30
	ds_read_b128 v[38:41], v38
	ds_read_b128 v[42:45], v42
	s_waitcnt lgkmcnt(0)
	v_mul_f32_e32 v64, v37, v60
	v_pk_fma_f32 v[30:31], v[2:3], v[30:31], v[0:1] neg_lo:[1,0,0] neg_hi:[1,0,0]
	s_nop 0
	v_pk_fma_f32 v[30:31], v[4:5], v[32:33], v[30:31] neg_lo:[1,0,0] neg_hi:[1,0,0]
	s_nop 0
	v_pk_fma_f32 v[30:31], v[6:7], v[46:47], v[30:31] neg_lo:[1,0,0] neg_hi:[1,0,0]
	s_nop 0
	v_pk_fma_f32 v[30:31], v[8:9], v[48:49], v[30:31] neg_lo:[1,0,0] neg_hi:[1,0,0]
	s_nop 0
	v_pk_fma_f32 v[30:31], v[10:11], v[52:53], v[30:31] neg_lo:[1,0,0] neg_hi:[1,0,0]
	s_nop 0
	v_pk_fma_f32 v[30:31], v[12:13], v[54:55], v[30:31] neg_lo:[1,0,0] neg_hi:[1,0,0]
	s_nop 0
	v_pk_fma_f32 v[30:31], v[14:15], v[56:57], v[30:31] neg_lo:[1,0,0] neg_hi:[1,0,0]
	s_nop 0
	v_pk_fma_f32 v[30:31], v[16:17], v[58:59], v[30:31] neg_lo:[1,0,0] neg_hi:[1,0,0]
	s_nop 0
	v_pk_fma_f32 v[20:21], v[20:21], v[18:19], v[30:31] neg_lo:[1,0,0] neg_hi:[1,0,0]
	s_nop 0
	v_pk_add_f32 v[20:21], v[20:21], v[20:21] op_sel:[0,1] op_sel_hi:[1,0]
	v_mov_b32_e32 v0, 0x19c00
	ds_read_b128 v[30:33], v0
	v_mov_b32_e32 v0, 0x19c10
	ds_read_b128 v[46:49], v0
	v_or_b32_e32 v0, 0x1c850, v67
	v_mov_b32_e32 v21, 0x19c40
	v_mov_b32_e32 v37, 0x19c20
	ds_read_b128 v[52:55], v21
	ds_read_b32 v0, v0
	ds_read_b32 v21, v66 offset:10240
	ds_read_b128 v[56:59], v37
	v_mov_b32_e32 v37, 0x19c30
	ds_read_b128 v[60:63], v37
	s_waitcnt lgkmcnt(0)
	v_mul_f32_e32 v0, v0, v21
	v_mov_b32_e32 v65, v1
	v_pk_fma_f32 v[22:23], v[2:3], v[22:23], v[64:65] neg_lo:[1,0,0] neg_hi:[1,0,0]
	s_nop 0
	v_pk_fma_f32 v[22:23], v[4:5], v[24:25], v[22:23] neg_lo:[1,0,0] neg_hi:[1,0,0]
	s_nop 0
	v_pk_fma_f32 v[22:23], v[6:7], v[26:27], v[22:23] neg_lo:[1,0,0] neg_hi:[1,0,0]
	s_nop 0
	v_pk_fma_f32 v[22:23], v[8:9], v[28:29], v[22:23] neg_lo:[1,0,0] neg_hi:[1,0,0]
	s_nop 0
	v_pk_fma_f32 v[22:23], v[10:11], v[38:39], v[22:23] neg_lo:[1,0,0] neg_hi:[1,0,0]
	s_nop 0
	v_pk_fma_f32 v[22:23], v[12:13], v[40:41], v[22:23] neg_lo:[1,0,0] neg_hi:[1,0,0]
	s_nop 0
	v_pk_fma_f32 v[22:23], v[14:15], v[42:43], v[22:23] neg_lo:[1,0,0] neg_hi:[1,0,0]
	s_nop 0
	v_pk_fma_f32 v[22:23], v[16:17], v[44:45], v[22:23] neg_lo:[1,0,0] neg_hi:[1,0,0]
	s_nop 0
	v_pk_fma_f32 v[22:23], v[18:19], v[34:35], v[22:23] neg_lo:[1,0,0] neg_hi:[1,0,0]
	s_nop 0
	v_fma_f32 v21, -v36, v20, v22
	v_add_f32_e32 v21, v23, v21
	v_mov_b32_e32 v22, 0x19d00
	ds_read_b128 v[24:27], v22
	v_mov_b32_e32 v22, 0x19d10
	ds_read_b128 v[34:37], v22
	v_mov_b32_e32 v22, 0x19d20
	ds_read_b128 v[38:41], v22
	v_mov_b32_e32 v22, 0x19d30
	ds_read_b128 v[42:45], v22
	v_mov_b32_e32 v22, 0x19d40
	ds_read_b128 v[70:73], v22
	v_mov_b32_e32 v22, 0x19d50
	ds_read_b128 v[74:77], v22
	v_or_b32_e32 v22, 0x1c854, v67
	ds_read_b32 v22, v22
	ds_read_b32 v23, v66 offset:10752
	s_waitcnt lgkmcnt(0)
; DI void gdn_prep_item(const Params& P, int l, int n, int hh, char* smem) {
;     ...
;     for (int i = 1; i < 64; ++i) {
;       f32x4 (&CUR)[16] = (i & 1) ? LA : LB; f32x4 (&NXT)[16] = (i & 1) ? LB : LA;
;       if (i + 1 < 64) {
; #pragma unroll
;         for (int c = 0; c < (i + 4) / 4; ++c) NXT[c] = *(const f32x4*)(Lm + (i + 1) * 64 + 4 * c);
;         rh[(i + 1) & 1] = sp[i + 1] * rp[(i + 1) * 128];
;       }
;       __builtin_amdgcn_sched_barrier(0);
;       f32x2 acc = {rh[i & 1], 0.f};
; #pragma unroll
;       for (int p = 0; p < i / 2; ++p) { const f32x2 lp = (p & 1) ? (f32x2){CUR[p >> 1].z, CUR[p >> 1].w} : (f32x2){CUR[p >> 1].x, CUR[p >> 1].y}; acc = acc - lp * xx[p]; }
;       if (i & 1) { const int j = i - 1; const float lj = ((j & 3) == 0) ? CUR[j >> 2].x : CUR[j >> 2].z; acc.x = fmaf(-lj, xx[j >> 1].x, acc.x); }
;       const float xi = acc.x + acc.y;
;       if (i & 1) xx[i >> 1].y = xi; else xx[i >> 1].x = xi;
;       __builtin_amdgcn_sched_barrier(0);
;     }
	v_mul_f32_e32 v64, v22, v23
	v_pk_fma_f32 v[22:23], v[2:3], v[30:31], v[0:1] neg_lo:[1,0,0] neg_hi:[1,0,0]
	s_nop 0
	v_pk_fma_f32 v[22:23], v[4:5], v[32:33], v[22:23] neg_lo:[1,0,0] neg_hi:[1,0,0]
	s_nop 0
	v_pk_fma_f32 v[22:23], v[6:7], v[46:47], v[22:23] neg_lo:[1,0,0] neg_hi:[1,0,0]
	s_nop 0
	v_pk_fma_f32 v[22:23], v[8:9], v[48:49], v[22:23] neg_lo:[1,0,0] neg_hi:[1,0,0]
	s_nop 0
	v_pk_fma_f32 v[22:23], v[10:11], v[56:57], v[22:23] neg_lo:[1,0,0] neg_hi:[1,0,0]
	s_nop 0
	v_pk_fma_f32 v[22:23], v[12:13], v[58:59], v[22:23] neg_lo:[1,0,0] neg_hi:[1,0,0]
	s_nop 0
	v_pk_fma_f32 v[22:23], v[14:15], v[60:61], v[22:23] neg_lo:[1,0,0] neg_hi:[1,0,0]
	s_nop 0
	v_pk_fma_f32 v[22:23], v[16:17], v[62:63], v[22:23] neg_lo:[1,0,0] neg_hi:[1,0,0]
	s_nop 0
	v_pk_fma_f32 v[22:23], v[18:19], v[52:53], v[22:23] neg_lo:[1,0,0] neg_hi:[1,0,0]
	s_nop 0
	v_pk_fma_f32 v[22:23], v[54:55], v[20:21], v[22:23] neg_lo:[1,0,0] neg_hi:[1,0,0]
	s_nop 0
	v_pk_add_f32 v[22:23], v[22:23], v[22:23] op_sel:[0,1] op_sel_hi:[1,0]
	v_mov_b32_e32 v0, 0x19e00
	ds_read_b128 v[28:31], v0
	v_mov_b32_e32 v0, 0x19e10
	ds_read_b128 v[46:49], v0
	v_mov_b32_e32 v0, 0x19e20
	ds_read_b128 v[52:55], v0
	v_mov_b32_e32 v0, 0x19e30
	ds_read_b128 v[56:59], v0
	v_or_b32_e32 v0, 0x1c858, v67
	v_mov_b32_e32 v32, 0x19e40
	ds_read_b32 v0, v0
	ds_read_b32 v23, v66 offset:11264
	ds_read_b128 v[60:63], v32
	v_mov_b32_e32 v32, 0x19e50
	ds_read_b64 v[84:85], v32
	s_waitcnt lgkmcnt(0)
	v_mul_f32_e32 v0, v0, v23
	v_pk_fma_f32 v[24:25], v[2:3], v[24:25], v[64:65] neg_lo:[1,0,0] neg_hi:[1,0,0]
	s_nop 0
	v_pk_fma_f32 v[24:25], v[4:5], v[26:27], v[24:25] neg_lo:[1,0,0] neg_hi:[1,0,0]
	s_nop 0
	v_pk_fma_f32 v[24:25], v[6:7], v[34:35], v[24:25] neg_lo:[1,0,0] neg_hi:[1,0,0]
	s_nop 0
	v_pk_fma_f32 v[24:25], v[8:9], v[36:37], v[24:25] neg_lo:[1,0,0] neg_hi:[1,0,0]
	s_nop 0
	v_pk_fma_f32 v[24:25], v[10:11], v[38:39], v[24:25] neg_lo:[1,0,0] neg_hi:[1,0,0]
	s_nop 0
	v_pk_fma_f32 v[24:25], v[12:13], v[40:41], v[24:25] neg_lo:[1,0,0] neg_hi:[1,0,0]
	s_nop 0
	v_pk_fma_f32 v[24:25], v[14:15], v[42:43], v[24:25] neg_lo:[1,0,0] neg_hi:[1,0,0]
	s_nop 0
	v_pk_fma_f32 v[24:25], v[16:17], v[44:45], v[24:25] neg_lo:[1,0,0] neg_hi:[1,0,0]
	s_nop 0
	v_pk_fma_f32 v[24:25], v[18:19], v[70:71], v[24:25] neg_lo:[1,0,0] neg_hi:[1,0,0]
	s_nop 0
	v_pk_fma_f32 v[24:25], v[20:21], v[72:73], v[24:25] neg_lo:[1,0,0] neg_hi:[1,0,0]
	s_nop 0
	v_fma_f32 v23, -v74, v22, v24
	v_add_f32_e32 v23, v25, v23
	v_mov_b32_e32 v24, 0x19f00
	ds_read_b128 v[32:35], v24
	v_mov_b32_e32 v24, 0x19f10
	ds_read_b128 v[36:39], v24
	v_mov_b32_e32 v24, 0x19f20
	ds_read_b128 v[40:43], v24
	v_mov_b32_e32 v24, 0x19f30
	ds_read_b128 v[70:73], v24
	v_or_b32_e32 v24, 0x1c85c, v67
	ds_read_b32 v24, v24
	ds_read_b32 v25, v66 offset:11776
	v_mov_b32_e32 v26, 0x19f40
	ds_read_b128 v[74:77], v26
	v_mov_b32_e32 v26, 0x19f50
	ds_read_b128 v[78:81], v26
	s_waitcnt lgkmcnt(0)
	v_mul_f32_e32 v64, v24, v25
	v_pk_fma_f32 v[24:25], v[2:3], v[28:29], v[0:1] neg_lo:[1,0,0] neg_hi:[1,0,0]
	s_nop 0
	v_pk_fma_f32 v[24:25], v[4:5], v[30:31], v[24:25] neg_lo:[1,0,0] neg_hi:[1,0,0]
	s_nop 0
	v_pk_fma_f32 v[24:25], v[6:7], v[46:47], v[24:25] neg_lo:[1,0,0] neg_hi:[1,0,0]
	s_nop 0
	v_pk_fma_f32 v[24:25], v[8:9], v[48:49], v[24:25] neg_lo:[1,0,0] neg_hi:[1,0,0]
	s_nop 0
	v_pk_fma_f32 v[24:25], v[10:11], v[52:53], v[24:25] neg_lo:[1,0,0] neg_hi:[1,0,0]
	s_nop 0
	v_pk_fma_f32 v[24:25], v[12:13], v[54:55], v[24:25] neg_lo:[1,0,0] neg_hi:[1,0,0]
	s_nop 0
	v_pk_fma_f32 v[24:25], v[14:15], v[56:57], v[24:25] neg_lo:[1,0,0] neg_hi:[1,0,0]
	s_nop 0
	v_pk_fma_f32 v[24:25], v[16:17], v[58:59], v[24:25] neg_lo:[1,0,0] neg_hi:[1,0,0]
	s_nop 0
	v_pk_fma_f32 v[24:25], v[18:19], v[60:61], v[24:25] neg_lo:[1,0,0] neg_hi:[1,0,0]
	s_nop 0
	v_pk_fma_f32 v[24:25], v[20:21], v[62:63], v[24:25] neg_lo:[1,0,0] neg_hi:[1,0,0]
	s_nop 0
	v_pk_fma_f32 v[24:25], v[84:85], v[22:23], v[24:25] neg_lo:[1,0,0] neg_hi:[1,0,0]
	s_nop 0
	v_pk_add_f32 v[24:25], v[24:25], v[24:25] op_sel:[0,1] op_sel_hi:[1,0]
	v_mov_b32_e32 v0, 0x1a000
	ds_read_b128 v[26:29], v0
	v_mov_b32_e32 v0, 0x1a010
	ds_read_b128 v[44:47], v0
	v_mov_b32_e32 v0, 0x1a020
	ds_read_b128 v[52:55], v0
	v_mov_b32_e32 v0, 0x1a030
	ds_read_b128 v[56:59], v0
	v_or_b32_e32 v0, 0x1c860, v67
	v_mov_b32_e32 v30, 0x1a040
	ds_read_b32 v0, v0
	ds_read_b32 v25, v66 offset:12288
	ds_read_b128 v[60:63], v30
	v_mov_b32_e32 v30, 0x1a050
	ds_read_b128 v[84:87], v30
	s_waitcnt lgkmcnt(0)
	v_mul_f32_e32 v0, v0, v25
	v_pk_fma_f32 v[30:31], v[2:3], v[32:33], v[64:65] neg_lo:[1,0,0] neg_hi:[1,0,0]
	s_nop 0
	v_pk_fma_f32 v[30:31], v[4:5], v[34:35], v[30:31] neg_lo:[1,0,0] neg_hi:[1,0,0]
	s_nop 0
	v_pk_fma_f32 v[30:31], v[6:7], v[36:37], v[30:31] neg_lo:[1,0,0] neg_hi:[1,0,0]
	s_nop 0
	v_pk_fma_f32 v[30:31], v[8:9], v[38:39], v[30:31] neg_lo:[1,0,0] neg_hi:[1,0,0]
	s_nop 0
	v_pk_fma_f32 v[30:31], v[10:11], v[40:41], v[30:31] neg_lo:[1,0,0] neg_hi:[1,0,0]
	s_nop 0
	v_pk_fma_f32 v[30:31], v[12:13], v[42:43], v[30:31] neg_lo:[1,0,0] neg_hi:[1,0,0]
	s_nop 0
	v_pk_fma_f32 v[30:31], v[14:15], v[70:71], v[30:31] neg_lo:[1,0,0] neg_hi:[1,0,0]
	s_nop 0
	v_pk_fma_f32 v[30:31], v[16:17], v[72:73], v[30:31] neg_lo:[1,0,0] neg_hi:[1,0,0]
	s_nop 0
	v_pk_fma_f32 v[30:31], v[18:19], v[74:75], v[30:31] neg_lo:[1,0,0] neg_hi:[1,0,0]
	s_nop 0
	v_pk_fma_f32 v[30:31], v[20:21], v[76:77], v[30:31] neg_lo:[1,0,0] neg_hi:[1,0,0]
	s_nop 0
	v_pk_fma_f32 v[30:31], v[22:23], v[78:79], v[30:31] neg_lo:[1,0,0] neg_hi:[1,0,0]
	s_nop 0
	v_fma_f32 v25, -v80, v24, v30
	v_add_f32_e32 v25, v31, v25
	v_mov_b32_e32 v38, 0x1a120
	v_mov_b32_e32 v42, 0x1a130
	v_mov_b32_e32 v30, 0x1a100
	v_mov_b32_e32 v34, 0x1a110
	ds_read_b128 v[38:41], v38
	ds_read_b128 v[70:73], v42
	v_or_b32_e32 v42, 0x1c864, v67
	v_mov_b32_e32 v43, 0x1a160
	ds_read_b128 v[30:33], v30
	ds_read_b128 v[34:37], v34
	ds_read_b128 v[74:77], v43
	ds_read_b32 v42, v42
	ds_read_b32 v43, v66 offset:12800
	v_mov_b32_e32 v48, 0x1a140
	s_waitcnt lgkmcnt(0)
; DI void gdn_prep_item(const Params& P, int l, int n, int hh, char* smem) {
;     ...
;     for (int i = 1; i < 64; ++i) {
;       f32x4 (&CUR)[16] = (i & 1) ? LA : LB; f32x4 (&NXT)[16] = (i & 1) ? LB : LA;
;       if (i + 1 < 64) {
; #pragma unroll
;         for (int c = 0; c < (i + 4) / 4; ++c) NXT[c] = *(const f32x4*)(Lm + (i + 1) * 64 + 4 * c);
;         rh[(i + 1) & 1] = sp[i + 1] * rp[(i + 1) * 128];
;       }
;       __builtin_amdgcn_sched_barrier(0);
;       f32x2 acc = {rh[i & 1], 0.f};
; #pragma unroll
;       for (int p = 0; p < i / 2; ++p) { const f32x2 lp = (p & 1) ? (f32x2){CUR[p >> 1].z, CUR[p >> 1].w} : (f32x2){CUR[p >> 1].x, CUR[p >> 1].y}; acc = acc - lp * xx[p]; }
;       if (i & 1) { const int j = i - 1; const float lj = ((j & 3) == 0) ? CUR[j >> 2].x : CUR[j >> 2].z; acc.x = fmaf(-lj, xx[j >> 1].x, acc.x); }
;       const float xi = acc.x + acc.y;
;       if (i & 1) xx[i >> 1].y = xi; else xx[i >> 1].x = xi;
;       __builtin_amdgcn_sched_barrier(0);
;     }
	ds_read_b128 v[76:79], v48
	v_mov_b32_e32 v48, 0x1a150
	ds_read_b128 v[88:91], v48
	v_mul_f32_e32 v64, v42, v43
	v_pk_fma_f32 v[26:27], v[2:3], v[26:27], v[0:1] neg_lo:[1,0,0] neg_hi:[1,0,0]
	s_nop 0
	v_pk_fma_f32 v[26:27], v[4:5], v[28:29], v[26:27] neg_lo:[1,0,0] neg_hi:[1,0,0]
	s_nop 0
	v_pk_fma_f32 v[26:27], v[6:7], v[44:45], v[26:27] neg_lo:[1,0,0] neg_hi:[1,0,0]
	s_nop 0
	v_pk_fma_f32 v[26:27], v[8:9], v[46:47], v[26:27] neg_lo:[1,0,0] neg_hi:[1,0,0]
	s_nop 0
	v_pk_fma_f32 v[26:27], v[10:11], v[52:53], v[26:27] neg_lo:[1,0,0] neg_hi:[1,0,0]
	s_nop 0
	v_pk_fma_f32 v[26:27], v[12:13], v[54:55], v[26:27] neg_lo:[1,0,0] neg_hi:[1,0,0]
	s_nop 0
	v_pk_fma_f32 v[26:27], v[14:15], v[56:57], v[26:27] neg_lo:[1,0,0] neg_hi:[1,0,0]
	s_nop 0
	v_pk_fma_f32 v[26:27], v[16:17], v[58:59], v[26:27] neg_lo:[1,0,0] neg_hi:[1,0,0]
	s_nop 0
	v_pk_fma_f32 v[26:27], v[18:19], v[60:61], v[26:27] neg_lo:[1,0,0] neg_hi:[1,0,0]
	s_nop 0
	v_pk_fma_f32 v[26:27], v[20:21], v[62:63], v[26:27] neg_lo:[1,0,0] neg_hi:[1,0,0]
	s_nop 0
	v_pk_fma_f32 v[26:27], v[22:23], v[84:85], v[26:27] neg_lo:[1,0,0] neg_hi:[1,0,0]
	s_nop 0
	v_pk_fma_f32 v[26:27], v[86:87], v[24:25], v[26:27] neg_lo:[1,0,0] neg_hi:[1,0,0]
	s_nop 0
	v_pk_add_f32 v[26:27], v[26:27], v[26:27] op_sel:[0,1] op_sel_hi:[1,0]
	v_mov_b32_e32 v0, 0x1a200
	ds_read_b128 v[42:45], v0
	v_mov_b32_e32 v0, 0x1a210
	ds_read_b128 v[46:49], v0
	v_mov_b32_e32 v0, 0x1a220
	ds_read_b128 v[52:55], v0
	v_mov_b32_e32 v0, 0x1a230
	ds_read_b128 v[56:59], v0
	v_or_b32_e32 v0, 0x1c868, v67
	v_mov_b32_e32 v27, 0x1a260
	v_mov_b32_e32 v60, 0x1a240
	ds_read_b64 v[28:29], v27
	ds_read_b32 v0, v0
	ds_read_b32 v27, v66 offset:13312
	ds_read_b128 v[60:63], v60
	v_mov_b32_e32 v65, 0x1a250
	ds_read_b128 v[84:87], v65
	s_waitcnt lgkmcnt(0)
	v_mul_f32_e32 v0, v0, v27
	v_mov_b32_e32 v65, v1
	v_pk_fma_f32 v[30:31], v[2:3], v[30:31], v[64:65] neg_lo:[1,0,0] neg_hi:[1,0,0]
	s_nop 0
	v_pk_fma_f32 v[30:31], v[4:5], v[32:33], v[30:31] neg_lo:[1,0,0] neg_hi:[1,0,0]
	s_nop 0
	v_pk_fma_f32 v[30:31], v[6:7], v[34:35], v[30:31] neg_lo:[1,0,0] neg_hi:[1,0,0]
	s_nop 0
	v_pk_fma_f32 v[30:31], v[8:9], v[36:37], v[30:31] neg_lo:[1,0,0] neg_hi:[1,0,0]
	s_nop 0
	v_pk_fma_f32 v[30:31], v[10:11], v[38:39], v[30:31] neg_lo:[1,0,0] neg_hi:[1,0,0]
	s_nop 0
	v_pk_fma_f32 v[30:31], v[12:13], v[40:41], v[30:31] neg_lo:[1,0,0] neg_hi:[1,0,0]
	s_nop 0
	v_pk_fma_f32 v[30:31], v[14:15], v[70:71], v[30:31] neg_lo:[1,0,0] neg_hi:[1,0,0]
	s_nop 0
	v_pk_fma_f32 v[30:31], v[16:17], v[72:73], v[30:31] neg_lo:[1,0,0] neg_hi:[1,0,0]
	s_nop 0
	v_pk_fma_f32 v[30:31], v[18:19], v[76:77], v[30:31] neg_lo:[1,0,0] neg_hi:[1,0,0]
	s_nop 0
	v_pk_fma_f32 v[30:31], v[20:21], v[78:79], v[30:31] neg_lo:[1,0,0] neg_hi:[1,0,0]
	s_nop 0
	v_pk_fma_f32 v[30:31], v[22:23], v[88:89], v[30:31] neg_lo:[1,0,0] neg_hi:[1,0,0]
	s_nop 0
	v_pk_fma_f32 v[30:31], v[24:25], v[90:91], v[30:31] neg_lo:[1,0,0] neg_hi:[1,0,0]
	s_nop 0
	v_fma_f32 v27, -v74, v26, v30
	v_add_f32_e32 v27, v31, v27
	v_mov_b32_e32 v38, 0x1a320
	v_mov_b32_e32 v64, 0x1a330
	v_mov_b32_e32 v30, 0x1a300
	v_mov_b32_e32 v34, 0x1a310
	ds_read_b128 v[38:41], v38
	ds_read_b128 v[70:73], v64
	v_or_b32_e32 v64, 0x1c86c, v67
	v_mov_b32_e32 v65, 0x1a360
	ds_read_b128 v[30:33], v30
	ds_read_b128 v[34:37], v34
	ds_read_b128 v[74:77], v65
	ds_read_b32 v64, v64
	ds_read_b32 v65, v66 offset:13824
	s_waitcnt lgkmcnt(0)
	v_mov_b32_e32 v77, 0x1a340
	ds_read_b128 v[78:81], v77
	v_mov_b32_e32 v77, 0x1a350
	ds_read_b128 v[88:91], v77
	v_mul_f32_e32 v64, v64, v65
	v_pk_fma_f32 v[42:43], v[2:3], v[42:43], v[0:1] neg_lo:[1,0,0] neg_hi:[1,0,0]
	s_nop 0
	v_pk_fma_f32 v[42:43], v[4:5], v[44:45], v[42:43] neg_lo:[1,0,0] neg_hi:[1,0,0]
	s_nop 0
	v_pk_fma_f32 v[42:43], v[6:7], v[46:47], v[42:43] neg_lo:[1,0,0] neg_hi:[1,0,0]
	s_nop 0
	v_pk_fma_f32 v[42:43], v[8:9], v[48:49], v[42:43] neg_lo:[1,0,0] neg_hi:[1,0,0]
	s_nop 0
	v_pk_fma_f32 v[42:43], v[10:11], v[52:53], v[42:43] neg_lo:[1,0,0] neg_hi:[1,0,0]
	s_nop 0
	v_pk_fma_f32 v[42:43], v[12:13], v[54:55], v[42:43] neg_lo:[1,0,0] neg_hi:[1,0,0]
	s_nop 0
	v_pk_fma_f32 v[42:43], v[14:15], v[56:57], v[42:43] neg_lo:[1,0,0] neg_hi:[1,0,0]
	s_nop 0
	v_pk_fma_f32 v[42:43], v[16:17], v[58:59], v[42:43] neg_lo:[1,0,0] neg_hi:[1,0,0]
	s_nop 0
	v_pk_fma_f32 v[42:43], v[18:19], v[60:61], v[42:43] neg_lo:[1,0,0] neg_hi:[1,0,0]
	s_nop 0
	v_pk_fma_f32 v[42:43], v[20:21], v[62:63], v[42:43] neg_lo:[1,0,0] neg_hi:[1,0,0]
	s_nop 0
	v_pk_fma_f32 v[42:43], v[22:23], v[84:85], v[42:43] neg_lo:[1,0,0] neg_hi:[1,0,0]
	s_nop 0
	v_pk_fma_f32 v[42:43], v[24:25], v[86:87], v[42:43] neg_lo:[1,0,0] neg_hi:[1,0,0]
	s_nop 0
	v_pk_fma_f32 v[28:29], v[28:29], v[26:27], v[42:43] neg_lo:[1,0,0] neg_hi:[1,0,0]
	s_nop 0
	v_pk_add_f32 v[28:29], v[28:29], v[28:29] op_sel:[0,1] op_sel_hi:[1,0]
	v_mov_b32_e32 v0, 0x1a400
	ds_read_b128 v[42:45], v0
	v_mov_b32_e32 v0, 0x1a410
	ds_read_b128 v[46:49], v0
	v_mov_b32_e32 v0, 0x1a420
	ds_read_b128 v[52:55], v0
	v_mov_b32_e32 v0, 0x1a430
	ds_read_b128 v[56:59], v0
	v_or_b32_e32 v0, 0x1c870, v67
	v_mov_b32_e32 v29, 0x1a460
	v_mov_b32_e32 v65, 0x1a440
	ds_read_b128 v[60:63], v29
	ds_read_b32 v0, v0
	ds_read_b32 v29, v66 offset:14336
	ds_read_b128 v[84:87], v65
	v_mov_b32_e32 v65, 0x1a450
	ds_read_b128 v[92:95], v65
	s_waitcnt lgkmcnt(0)
; DI void gdn_prep_item(const Params& P, int l, int n, int hh, char* smem) {
;     ...
;     for (int i = 1; i < 64; ++i) {
;       f32x4 (&CUR)[16] = (i & 1) ? LA : LB; f32x4 (&NXT)[16] = (i & 1) ? LB : LA;
;       if (i + 1 < 64) {
; #pragma unroll
;         for (int c = 0; c < (i + 4) / 4; ++c) NXT[c] = *(const f32x4*)(Lm + (i + 1) * 64 + 4 * c);
;         rh[(i + 1) & 1] = sp[i + 1] * rp[(i + 1) * 128];
;       }
;       __builtin_amdgcn_sched_barrier(0);
;       f32x2 acc = {rh[i & 1], 0.f};
; #pragma unroll
;       for (int p = 0; p < i / 2; ++p) { const f32x2 lp = (p & 1) ? (f32x2){CUR[p >> 1].z, CUR[p >> 1].w} : (f32x2){CUR[p >> 1].x, CUR[p >> 1].y}; acc = acc - lp * xx[p]; }
;       if (i & 1) { const int j = i - 1; const float lj = ((j & 3) == 0) ? CUR[j >> 2].x : CUR[j >> 2].z; acc.x = fmaf(-lj, xx[j >> 1].x, acc.x); }
;       const float xi = acc.x + acc.y;
;       if (i & 1) xx[i >> 1].y = xi; else xx[i >> 1].x = xi;
;       __builtin_amdgcn_sched_barrier(0);
;     }
	v_mul_f32_e32 v0, v0, v29
	v_mov_b32_e32 v65, v1
	v_pk_fma_f32 v[30:31], v[2:3], v[30:31], v[64:65] neg_lo:[1,0,0] neg_hi:[1,0,0]
	s_nop 0
	v_pk_fma_f32 v[30:31], v[4:5], v[32:33], v[30:31] neg_lo:[1,0,0] neg_hi:[1,0,0]
	s_nop 0
	v_pk_fma_f32 v[30:31], v[6:7], v[34:35], v[30:31] neg_lo:[1,0,0] neg_hi:[1,0,0]
	s_nop 0
	v_pk_fma_f32 v[30:31], v[8:9], v[36:37], v[30:31] neg_lo:[1,0,0] neg_hi:[1,0,0]
	s_nop 0
	v_pk_fma_f32 v[30:31], v[10:11], v[38:39], v[30:31] neg_lo:[1,0,0] neg_hi:[1,0,0]
	s_nop 0
	v_pk_fma_f32 v[30:31], v[12:13], v[40:41], v[30:31] neg_lo:[1,0,0] neg_hi:[1,0,0]
	s_nop 0
	v_pk_fma_f32 v[30:31], v[14:15], v[70:71], v[30:31] neg_lo:[1,0,0] neg_hi:[1,0,0]
	s_nop 0
	v_pk_fma_f32 v[30:31], v[16:17], v[72:73], v[30:31] neg_lo:[1,0,0] neg_hi:[1,0,0]
	s_nop 0
	v_pk_fma_f32 v[30:31], v[18:19], v[78:79], v[30:31] neg_lo:[1,0,0] neg_hi:[1,0,0]
	s_nop 0
	v_pk_fma_f32 v[30:31], v[20:21], v[80:81], v[30:31] neg_lo:[1,0,0] neg_hi:[1,0,0]
	s_nop 0
	v_pk_fma_f32 v[30:31], v[22:23], v[88:89], v[30:31] neg_lo:[1,0,0] neg_hi:[1,0,0]
	s_nop 0
	v_pk_fma_f32 v[30:31], v[24:25], v[90:91], v[30:31] neg_lo:[1,0,0] neg_hi:[1,0,0]
	s_nop 0
	v_pk_fma_f32 v[30:31], v[26:27], v[74:75], v[30:31] neg_lo:[1,0,0] neg_hi:[1,0,0]
	s_nop 0
	v_fma_f32 v29, -v76, v28, v30
	v_add_f32_e32 v29, v31, v29
	v_mov_b32_e32 v30, 0x1a500
	ds_read_b128 v[32:35], v30
	v_mov_b32_e32 v30, 0x1a510
	ds_read_b128 v[36:39], v30
	v_mov_b32_e32 v30, 0x1a520
	ds_read_b128 v[70:73], v30
	v_mov_b32_e32 v30, 0x1a530
	ds_read_b128 v[74:77], v30
	v_mov_b32_e32 v30, 0x1a540
	ds_read_b128 v[78:81], v30
	v_mov_b32_e32 v30, 0x1a550
	ds_read_b128 v[88:91], v30
	v_mov_b32_e32 v30, 0x1a560
	ds_read_b128 v[96:99], v30
	v_mov_b32_e32 v30, 0x1a570
	ds_read_b128 v[100:103], v30
	v_or_b32_e32 v30, 0x1c874, v67
	ds_read_b32 v30, v30
	ds_read_b32 v31, v66 offset:14848
	s_waitcnt lgkmcnt(0)
	v_mul_f32_e32 v64, v30, v31
	v_pk_fma_f32 v[30:31], v[2:3], v[42:43], v[0:1] neg_lo:[1,0,0] neg_hi:[1,0,0]
	s_nop 0
	v_pk_fma_f32 v[30:31], v[4:5], v[44:45], v[30:31] neg_lo:[1,0,0] neg_hi:[1,0,0]
	s_nop 0
	v_pk_fma_f32 v[30:31], v[6:7], v[46:47], v[30:31] neg_lo:[1,0,0] neg_hi:[1,0,0]
	s_nop 0
	v_pk_fma_f32 v[30:31], v[8:9], v[48:49], v[30:31] neg_lo:[1,0,0] neg_hi:[1,0,0]
	s_nop 0
	v_pk_fma_f32 v[30:31], v[10:11], v[52:53], v[30:31] neg_lo:[1,0,0] neg_hi:[1,0,0]
	s_nop 0
	v_pk_fma_f32 v[30:31], v[12:13], v[54:55], v[30:31] neg_lo:[1,0,0] neg_hi:[1,0,0]
	s_nop 0
	v_pk_fma_f32 v[30:31], v[14:15], v[56:57], v[30:31] neg_lo:[1,0,0] neg_hi:[1,0,0]
	s_nop 0
	v_pk_fma_f32 v[30:31], v[16:17], v[58:59], v[30:31] neg_lo:[1,0,0] neg_hi:[1,0,0]
	s_nop 0
	v_pk_fma_f32 v[30:31], v[18:19], v[84:85], v[30:31] neg_lo:[1,0,0] neg_hi:[1,0,0]
	s_nop 0
	v_pk_fma_f32 v[30:31], v[20:21], v[86:87], v[30:31] neg_lo:[1,0,0] neg_hi:[1,0,0]
	s_nop 0
	v_pk_fma_f32 v[30:31], v[22:23], v[92:93], v[30:31] neg_lo:[1,0,0] neg_hi:[1,0,0]
	s_nop 0
	v_pk_fma_f32 v[30:31], v[24:25], v[94:95], v[30:31] neg_lo:[1,0,0] neg_hi:[1,0,0]
	s_nop 0
	v_pk_fma_f32 v[30:31], v[26:27], v[60:61], v[30:31] neg_lo:[1,0,0] neg_hi:[1,0,0]
	s_nop 0
	v_pk_fma_f32 v[30:31], v[62:63], v[28:29], v[30:31] neg_lo:[1,0,0] neg_hi:[1,0,0]
	s_nop 0
	v_pk_add_f32 v[30:31], v[30:31], v[30:31] op_sel:[0,1] op_sel_hi:[1,0]
	v_mov_b32_e32 v0, 0x1a600
	ds_read_b128 v[40:43], v0
	v_mov_b32_e32 v0, 0x1a610
	ds_read_b128 v[44:47], v0
	v_mov_b32_e32 v0, 0x1a620
	ds_read_b128 v[52:55], v0
	v_mov_b32_e32 v0, 0x1a630
	ds_read_b128 v[56:59], v0
	v_mov_b32_e32 v0, 0x1a640
	ds_read_b128 v[60:63], v0
	v_mov_b32_e32 v0, 0x1a650
	ds_read_b128 v[84:87], v0
	v_or_b32_e32 v0, 0x1c878, v67
	v_mov_b32_e32 v48, 0x1a660
	ds_read_b32 v0, v0
	ds_read_b32 v31, v66 offset:15360
	ds_read_b128 v[92:95], v48
	v_mov_b32_e32 v48, 0x1a670
	ds_read_b64 v[48:49], v48
	s_waitcnt lgkmcnt(0)
	v_mul_f32_e32 v0, v0, v31
	v_pk_fma_f32 v[32:33], v[2:3], v[32:33], v[64:65] neg_lo:[1,0,0] neg_hi:[1,0,0]
	s_nop 0
	v_pk_fma_f32 v[32:33], v[4:5], v[34:35], v[32:33] neg_lo:[1,0,0] neg_hi:[1,0,0]
	s_nop 0
	v_pk_fma_f32 v[32:33], v[6:7], v[36:37], v[32:33] neg_lo:[1,0,0] neg_hi:[1,0,0]
	s_nop 0
	v_pk_fma_f32 v[32:33], v[8:9], v[38:39], v[32:33] neg_lo:[1,0,0] neg_hi:[1,0,0]
	s_nop 0
	v_pk_fma_f32 v[32:33], v[10:11], v[70:71], v[32:33] neg_lo:[1,0,0] neg_hi:[1,0,0]
	s_nop 0
	v_pk_fma_f32 v[32:33], v[12:13], v[72:73], v[32:33] neg_lo:[1,0,0] neg_hi:[1,0,0]
	s_nop 0
	v_pk_fma_f32 v[32:33], v[14:15], v[74:75], v[32:33] neg_lo:[1,0,0] neg_hi:[1,0,0]
	s_nop 0
	v_pk_fma_f32 v[32:33], v[16:17], v[76:77], v[32:33] neg_lo:[1,0,0] neg_hi:[1,0,0]
	s_nop 0
	v_pk_fma_f32 v[32:33], v[18:19], v[78:79], v[32:33] neg_lo:[1,0,0] neg_hi:[1,0,0]
	s_nop 0
	v_pk_fma_f32 v[32:33], v[20:21], v[80:81], v[32:33] neg_lo:[1,0,0] neg_hi:[1,0,0]
	s_nop 0
	v_pk_fma_f32 v[32:33], v[22:23], v[88:89], v[32:33] neg_lo:[1,0,0] neg_hi:[1,0,0]
	s_nop 0
	v_pk_fma_f32 v[32:33], v[24:25], v[90:91], v[32:33] neg_lo:[1,0,0] neg_hi:[1,0,0]
	s_nop 0
	v_pk_fma_f32 v[32:33], v[26:27], v[96:97], v[32:33] neg_lo:[1,0,0] neg_hi:[1,0,0]
	s_nop 0
	v_pk_fma_f32 v[32:33], v[28:29], v[98:99], v[32:33] neg_lo:[1,0,0] neg_hi:[1,0,0]
	s_nop 0
	v_fma_f32 v31, -v100, v30, v32
	v_add_f32_e32 v31, v33, v31
	v_mov_b32_e32 v32, 0x1a700
	ds_read_b128 v[34:37], v32
	v_mov_b32_e32 v32, 0x1a710
	ds_read_b128 v[70:73], v32
	v_mov_b32_e32 v32, 0x1a720
	ds_read_b128 v[74:77], v32
	v_mov_b32_e32 v32, 0x1a730
	ds_read_b128 v[78:81], v32
	v_mov_b32_e32 v32, 0x1a740
	ds_read_b128 v[88:91], v32
	v_mov_b32_e32 v32, 0x1a750
	ds_read_b128 v[96:99], v32
	v_or_b32_e32 v32, 0x1c87c, v67
	ds_read_b32 v32, v32
	ds_read_b32 v33, v66 offset:15872
	v_mov_b32_e32 v38, 0x1a760
	ds_read_b128 v[100:103], v38
	v_mov_b32_e32 v38, 0x1a770
	ds_read_b128 v[104:107], v38
	s_waitcnt lgkmcnt(0)
; DI void gdn_prep_item(const Params& P, int l, int n, int hh, char* smem) {
;     ...
;     for (int i = 1; i < 64; ++i) {
;       f32x4 (&CUR)[16] = (i & 1) ? LA : LB; f32x4 (&NXT)[16] = (i & 1) ? LB : LA;
;       if (i + 1 < 64) {
; #pragma unroll
;         for (int c = 0; c < (i + 4) / 4; ++c) NXT[c] = *(const f32x4*)(Lm + (i + 1) * 64 + 4 * c);
;         rh[(i + 1) & 1] = sp[i + 1] * rp[(i + 1) * 128];
;       }
;       __builtin_amdgcn_sched_barrier(0);
;       f32x2 acc = {rh[i & 1], 0.f};
; #pragma unroll
;       for (int p = 0; p < i / 2; ++p) { const f32x2 lp = (p & 1) ? (f32x2){CUR[p >> 1].z, CUR[p >> 1].w} : (f32x2){CUR[p >> 1].x, CUR[p >> 1].y}; acc = acc - lp * xx[p]; }
;       if (i & 1) { const int j = i - 1; const float lj = ((j & 3) == 0) ? CUR[j >> 2].x : CUR[j >> 2].z; acc.x = fmaf(-lj, xx[j >> 1].x, acc.x); }
;       const float xi = acc.x + acc.y;
;       if (i & 1) xx[i >> 1].y = xi; else xx[i >> 1].x = xi;
;       __builtin_amdgcn_sched_barrier(0);
;     }
	v_mul_f32_e32 v64, v32, v33
	v_pk_fma_f32 v[32:33], v[2:3], v[40:41], v[0:1] neg_lo:[1,0,0] neg_hi:[1,0,0]
	s_nop 0
	v_pk_fma_f32 v[32:33], v[4:5], v[42:43], v[32:33] neg_lo:[1,0,0] neg_hi:[1,0,0]
	s_nop 0
	v_pk_fma_f32 v[32:33], v[6:7], v[44:45], v[32:33] neg_lo:[1,0,0] neg_hi:[1,0,0]
	s_nop 0
	v_pk_fma_f32 v[32:33], v[8:9], v[46:47], v[32:33] neg_lo:[1,0,0] neg_hi:[1,0,0]
	s_nop 0
	v_pk_fma_f32 v[32:33], v[10:11], v[52:53], v[32:33] neg_lo:[1,0,0] neg_hi:[1,0,0]
	s_nop 0
	v_pk_fma_f32 v[32:33], v[12:13], v[54:55], v[32:33] neg_lo:[1,0,0] neg_hi:[1,0,0]
	s_nop 0
	v_pk_fma_f32 v[32:33], v[14:15], v[56:57], v[32:33] neg_lo:[1,0,0] neg_hi:[1,0,0]
	s_nop 0
	v_pk_fma_f32 v[32:33], v[16:17], v[58:59], v[32:33] neg_lo:[1,0,0] neg_hi:[1,0,0]
	s_nop 0
	v_pk_fma_f32 v[32:33], v[18:19], v[60:61], v[32:33] neg_lo:[1,0,0] neg_hi:[1,0,0]
	s_nop 0
	v_pk_fma_f32 v[32:33], v[20:21], v[62:63], v[32:33] neg_lo:[1,0,0] neg_hi:[1,0,0]
	s_nop 0
	v_pk_fma_f32 v[32:33], v[22:23], v[84:85], v[32:33] neg_lo:[1,0,0] neg_hi:[1,0,0]
	s_nop 0
	v_pk_fma_f32 v[32:33], v[24:25], v[86:87], v[32:33] neg_lo:[1,0,0] neg_hi:[1,0,0]
	s_nop 0
	v_pk_fma_f32 v[32:33], v[26:27], v[92:93], v[32:33] neg_lo:[1,0,0] neg_hi:[1,0,0]
	s_nop 0
	v_pk_fma_f32 v[32:33], v[28:29], v[94:95], v[32:33] neg_lo:[1,0,0] neg_hi:[1,0,0]
	s_nop 0
	v_pk_fma_f32 v[32:33], v[48:49], v[30:31], v[32:33] neg_lo:[1,0,0] neg_hi:[1,0,0]
	s_nop 0
	v_pk_add_f32 v[32:33], v[32:33], v[32:33] op_sel:[0,1] op_sel_hi:[1,0]
	v_mov_b32_e32 v0, 0x1a800
	ds_read_b128 v[38:41], v0
	v_mov_b32_e32 v0, 0x1a810
	ds_read_b128 v[42:45], v0
	v_mov_b32_e32 v0, 0x1a820
	ds_read_b128 v[46:49], v0
	v_mov_b32_e32 v0, 0x1a830
	ds_read_b128 v[52:55], v0
	v_mov_b32_e32 v0, 0x1a840
	ds_read_b128 v[56:59], v0
	v_mov_b32_e32 v0, 0x1a850
	ds_read_b128 v[60:63], v0
	v_or_b32_e32 v0, 0x1c880, v67
	v_mov_b32_e32 v65, 0x1a860
	ds_read_b32 v0, v0
	ds_read_b32 v33, v66 offset:16384
	ds_read_b128 v[84:87], v65
	v_mov_b32_e32 v65, 0x1a870
	ds_read_b128 v[92:95], v65
	s_waitcnt lgkmcnt(0)
	v_mul_f32_e32 v0, v0, v33
	v_mov_b32_e32 v65, v1
	v_pk_fma_f32 v[34:35], v[2:3], v[34:35], v[64:65] neg_lo:[1,0,0] neg_hi:[1,0,0]
	s_nop 0
	v_pk_fma_f32 v[34:35], v[4:5], v[36:37], v[34:35] neg_lo:[1,0,0] neg_hi:[1,0,0]
	s_nop 0
	v_pk_fma_f32 v[34:35], v[6:7], v[70:71], v[34:35] neg_lo:[1,0,0] neg_hi:[1,0,0]
	s_nop 0
	v_pk_fma_f32 v[34:35], v[8:9], v[72:73], v[34:35] neg_lo:[1,0,0] neg_hi:[1,0,0]
	s_nop 0
	v_pk_fma_f32 v[34:35], v[10:11], v[74:75], v[34:35] neg_lo:[1,0,0] neg_hi:[1,0,0]
	s_nop 0
	v_pk_fma_f32 v[34:35], v[12:13], v[76:77], v[34:35] neg_lo:[1,0,0] neg_hi:[1,0,0]
	s_nop 0
	v_pk_fma_f32 v[34:35], v[14:15], v[78:79], v[34:35] neg_lo:[1,0,0] neg_hi:[1,0,0]
	s_nop 0
	v_pk_fma_f32 v[34:35], v[16:17], v[80:81], v[34:35] neg_lo:[1,0,0] neg_hi:[1,0,0]
	s_nop 0
	v_pk_fma_f32 v[34:35], v[18:19], v[88:89], v[34:35] neg_lo:[1,0,0] neg_hi:[1,0,0]
	s_nop 0
	v_pk_fma_f32 v[34:35], v[20:21], v[90:91], v[34:35] neg_lo:[1,0,0] neg_hi:[1,0,0]
	s_nop 0
	v_pk_fma_f32 v[34:35], v[22:23], v[96:97], v[34:35] neg_lo:[1,0,0] neg_hi:[1,0,0]
	s_nop 0
	v_pk_fma_f32 v[34:35], v[24:25], v[98:99], v[34:35] neg_lo:[1,0,0] neg_hi:[1,0,0]
	s_nop 0
	v_pk_fma_f32 v[34:35], v[26:27], v[100:101], v[34:35] neg_lo:[1,0,0] neg_hi:[1,0,0]
	s_nop 0
	v_pk_fma_f32 v[34:35], v[28:29], v[102:103], v[34:35] neg_lo:[1,0,0] neg_hi:[1,0,0]
	s_nop 0
	v_pk_fma_f32 v[34:35], v[30:31], v[104:105], v[34:35] neg_lo:[1,0,0] neg_hi:[1,0,0]
	s_nop 0
	v_fma_f32 v33, -v106, v32, v34
	v_add_f32_e32 v33, v35, v33
	v_mov_b32_e32 v34, 0x1a900
	ds_read_b128 v[70:73], v34
	v_mov_b32_e32 v34, 0x1a910
	ds_read_b128 v[74:77], v34
	v_mov_b32_e32 v34, 0x1a920
	ds_read_b128 v[78:81], v34
	v_mov_b32_e32 v34, 0x1a930
	ds_read_b128 v[88:91], v34
	v_mov_b32_e32 v34, 0x1a940
	ds_read_b128 v[96:99], v34
	v_mov_b32_e32 v34, 0x1a950
	ds_read_b128 v[100:103], v34
	v_or_b32_e32 v34, 0x1c884, v67
	v_mov_b32_e32 v35, 0x1a980
	ds_read_b128 v[104:107], v35
	ds_read_b32 v34, v34
	ds_read_b32 v35, v66 offset:16896
	v_mov_b32_e32 v36, 0x1a960
	s_waitcnt lgkmcnt(0)
	ds_read_b128 v[106:109], v36
	v_mov_b32_e32 v36, 0x1a970
	ds_read_b128 v[110:113], v36
	v_mul_f32_e32 v64, v34, v35
	v_pk_fma_f32 v[34:35], v[2:3], v[38:39], v[0:1] neg_lo:[1,0,0] neg_hi:[1,0,0]
	s_nop 0
	v_pk_fma_f32 v[34:35], v[4:5], v[40:41], v[34:35] neg_lo:[1,0,0] neg_hi:[1,0,0]
	s_nop 0
	v_pk_fma_f32 v[34:35], v[6:7], v[42:43], v[34:35] neg_lo:[1,0,0] neg_hi:[1,0,0]
	s_nop 0
	v_pk_fma_f32 v[34:35], v[8:9], v[44:45], v[34:35] neg_lo:[1,0,0] neg_hi:[1,0,0]
	s_nop 0
	v_pk_fma_f32 v[34:35], v[10:11], v[46:47], v[34:35] neg_lo:[1,0,0] neg_hi:[1,0,0]
	s_nop 0
	v_pk_fma_f32 v[34:35], v[12:13], v[48:49], v[34:35] neg_lo:[1,0,0] neg_hi:[1,0,0]
	s_nop 0
	v_pk_fma_f32 v[34:35], v[14:15], v[52:53], v[34:35] neg_lo:[1,0,0] neg_hi:[1,0,0]
	s_nop 0
	v_pk_fma_f32 v[34:35], v[16:17], v[54:55], v[34:35] neg_lo:[1,0,0] neg_hi:[1,0,0]
	s_nop 0
	v_pk_fma_f32 v[34:35], v[18:19], v[56:57], v[34:35] neg_lo:[1,0,0] neg_hi:[1,0,0]
	s_nop 0
	v_pk_fma_f32 v[34:35], v[20:21], v[58:59], v[34:35] neg_lo:[1,0,0] neg_hi:[1,0,0]
	s_nop 0
	v_pk_fma_f32 v[34:35], v[22:23], v[60:61], v[34:35] neg_lo:[1,0,0] neg_hi:[1,0,0]
	s_nop 0
	v_pk_fma_f32 v[34:35], v[24:25], v[62:63], v[34:35] neg_lo:[1,0,0] neg_hi:[1,0,0]
	s_nop 0
	v_pk_fma_f32 v[34:35], v[26:27], v[84:85], v[34:35] neg_lo:[1,0,0] neg_hi:[1,0,0]
	s_nop 0
	v_pk_fma_f32 v[34:35], v[28:29], v[86:87], v[34:35] neg_lo:[1,0,0] neg_hi:[1,0,0]
	s_nop 0
	v_pk_fma_f32 v[34:35], v[30:31], v[92:93], v[34:35] neg_lo:[1,0,0] neg_hi:[1,0,0]
	s_nop 0
	v_pk_fma_f32 v[34:35], v[94:95], v[32:33], v[34:35] neg_lo:[1,0,0] neg_hi:[1,0,0]
	s_nop 0
	v_pk_add_f32 v[34:35], v[34:35], v[34:35] op_sel:[0,1] op_sel_hi:[1,0]
	v_mov_b32_e32 v0, 0x1aa00
	ds_read_b128 v[36:39], v0
	v_mov_b32_e32 v0, 0x1aa10
	ds_read_b128 v[40:43], v0
	v_mov_b32_e32 v0, 0x1aa20
	ds_read_b128 v[44:47], v0
	v_mov_b32_e32 v0, 0x1aa30
	ds_read_b128 v[52:55], v0
	v_mov_b32_e32 v0, 0x1aa40
	ds_read_b128 v[56:59], v0
	v_mov_b32_e32 v0, 0x1aa50
	ds_read_b128 v[60:63], v0
	v_or_b32_e32 v0, 0x1c888, v67
	v_mov_b32_e32 v35, 0x1aa80
	v_mov_b32_e32 v65, 0x1aa60
	ds_read_b64 v[48:49], v35
	ds_read_b32 v0, v0
	ds_read_b32 v35, v66 offset:17408
	ds_read_b128 v[84:87], v65
	v_mov_b32_e32 v65, 0x1aa70
	ds_read_b128 v[92:95], v65
	s_waitcnt lgkmcnt(0)
; DI void gdn_prep_item(const Params& P, int l, int n, int hh, char* smem) {
;     ...
;     for (int i = 1; i < 64; ++i) {
;       f32x4 (&CUR)[16] = (i & 1) ? LA : LB; f32x4 (&NXT)[16] = (i & 1) ? LB : LA;
;       if (i + 1 < 64) {
; #pragma unroll
;         for (int c = 0; c < (i + 4) / 4; ++c) NXT[c] = *(const f32x4*)(Lm + (i + 1) * 64 + 4 * c);
;         rh[(i + 1) & 1] = sp[i + 1] * rp[(i + 1) * 128];
;       }
;       __builtin_amdgcn_sched_barrier(0);
;       f32x2 acc = {rh[i & 1], 0.f};
; #pragma unroll
;       for (int p = 0; p < i / 2; ++p) { const f32x2 lp = (p & 1) ? (f32x2){CUR[p >> 1].z, CUR[p >> 1].w} : (f32x2){CUR[p >> 1].x, CUR[p >> 1].y}; acc = acc - lp * xx[p]; }
;       if (i & 1) { const int j = i - 1; const float lj = ((j & 3) == 0) ? CUR[j >> 2].x : CUR[j >> 2].z; acc.x = fmaf(-lj, xx[j >> 1].x, acc.x); }
;       const float xi = acc.x + acc.y;
;       if (i & 1) xx[i >> 1].y = xi; else xx[i >> 1].x = xi;
;       __builtin_amdgcn_sched_barrier(0);
;     }
	v_mul_f32_e32 v0, v0, v35
	v_mov_b32_e32 v65, v1
	v_pk_fma_f32 v[64:65], v[2:3], v[70:71], v[64:65] neg_lo:[1,0,0] neg_hi:[1,0,0]
	s_nop 0
	v_pk_fma_f32 v[64:65], v[4:5], v[72:73], v[64:65] neg_lo:[1,0,0] neg_hi:[1,0,0]
	s_nop 0
	v_pk_fma_f32 v[64:65], v[6:7], v[74:75], v[64:65] neg_lo:[1,0,0] neg_hi:[1,0,0]
	s_nop 0
	v_pk_fma_f32 v[64:65], v[8:9], v[76:77], v[64:65] neg_lo:[1,0,0] neg_hi:[1,0,0]
	s_nop 0
	v_pk_fma_f32 v[64:65], v[10:11], v[78:79], v[64:65] neg_lo:[1,0,0] neg_hi:[1,0,0]
	s_nop 0
	v_pk_fma_f32 v[64:65], v[12:13], v[80:81], v[64:65] neg_lo:[1,0,0] neg_hi:[1,0,0]
	s_nop 0
	v_pk_fma_f32 v[64:65], v[14:15], v[88:89], v[64:65] neg_lo:[1,0,0] neg_hi:[1,0,0]
	s_nop 0
	v_pk_fma_f32 v[64:65], v[16:17], v[90:91], v[64:65] neg_lo:[1,0,0] neg_hi:[1,0,0]
	s_nop 0
	v_pk_fma_f32 v[64:65], v[18:19], v[96:97], v[64:65] neg_lo:[1,0,0] neg_hi:[1,0,0]
	s_nop 0
	v_pk_fma_f32 v[64:65], v[20:21], v[98:99], v[64:65] neg_lo:[1,0,0] neg_hi:[1,0,0]
	s_nop 0
	v_pk_fma_f32 v[64:65], v[22:23], v[100:101], v[64:65] neg_lo:[1,0,0] neg_hi:[1,0,0]
	s_nop 0
	v_pk_fma_f32 v[64:65], v[24:25], v[102:103], v[64:65] neg_lo:[1,0,0] neg_hi:[1,0,0]
	s_nop 0
	v_pk_fma_f32 v[64:65], v[26:27], v[106:107], v[64:65] neg_lo:[1,0,0] neg_hi:[1,0,0]
	s_nop 0
	v_pk_fma_f32 v[64:65], v[28:29], v[108:109], v[64:65] neg_lo:[1,0,0] neg_hi:[1,0,0]
	s_nop 0
	v_pk_fma_f32 v[64:65], v[30:31], v[110:111], v[64:65] neg_lo:[1,0,0] neg_hi:[1,0,0]
	s_nop 0
	v_pk_fma_f32 v[64:65], v[32:33], v[112:113], v[64:65] neg_lo:[1,0,0] neg_hi:[1,0,0]
	s_nop 0
	v_fma_f32 v35, -v104, v34, v64
	v_add_f32_e32 v35, v65, v35
	v_mov_b32_e32 v64, 0x1ab00
	ds_read_b128 v[70:73], v64
	v_mov_b32_e32 v64, 0x1ab10
	ds_read_b128 v[74:77], v64
	v_mov_b32_e32 v64, 0x1ab20
	ds_read_b128 v[78:81], v64
	v_mov_b32_e32 v64, 0x1ab30
	ds_read_b128 v[88:91], v64
	v_mov_b32_e32 v64, 0x1ab40
	ds_read_b128 v[96:99], v64
	v_mov_b32_e32 v64, 0x1ab50
	ds_read_b128 v[100:103], v64
	v_or_b32_e32 v64, 0x1c88c, v67
	v_mov_b32_e32 v65, 0x1ab80
	ds_read_b128 v[104:107], v65
	ds_read_b32 v64, v64
	ds_read_b32 v65, v66 offset:17920
	v_mov_b32_e32 v83, 0x1ab60
	ds_read_b128 v[108:111], v83
	v_mov_b32_e32 v83, 0x1ab70
	ds_read_b128 v[112:115], v83
	s_waitcnt lgkmcnt(0)
	v_mul_f32_e32 v64, v64, v65
	v_pk_fma_f32 v[36:37], v[2:3], v[36:37], v[0:1] neg_lo:[1,0,0] neg_hi:[1,0,0]
	s_nop 0
	v_pk_fma_f32 v[36:37], v[4:5], v[38:39], v[36:37] neg_lo:[1,0,0] neg_hi:[1,0,0]
	s_nop 0
	v_pk_fma_f32 v[36:37], v[6:7], v[40:41], v[36:37] neg_lo:[1,0,0] neg_hi:[1,0,0]
	s_nop 0
	v_pk_fma_f32 v[36:37], v[8:9], v[42:43], v[36:37] neg_lo:[1,0,0] neg_hi:[1,0,0]
	s_nop 0
	v_pk_fma_f32 v[36:37], v[10:11], v[44:45], v[36:37] neg_lo:[1,0,0] neg_hi:[1,0,0]
	s_nop 0
	v_pk_fma_f32 v[36:37], v[12:13], v[46:47], v[36:37] neg_lo:[1,0,0] neg_hi:[1,0,0]
	s_nop 0
	v_pk_fma_f32 v[36:37], v[14:15], v[52:53], v[36:37] neg_lo:[1,0,0] neg_hi:[1,0,0]
	s_nop 0
	v_pk_fma_f32 v[36:37], v[16:17], v[54:55], v[36:37] neg_lo:[1,0,0] neg_hi:[1,0,0]
	s_nop 0
	v_pk_fma_f32 v[36:37], v[18:19], v[56:57], v[36:37] neg_lo:[1,0,0] neg_hi:[1,0,0]
	s_nop 0
	v_pk_fma_f32 v[36:37], v[20:21], v[58:59], v[36:37] neg_lo:[1,0,0] neg_hi:[1,0,0]
	s_nop 0
	v_pk_fma_f32 v[36:37], v[22:23], v[60:61], v[36:37] neg_lo:[1,0,0] neg_hi:[1,0,0]
	s_nop 0
	v_pk_fma_f32 v[36:37], v[24:25], v[62:63], v[36:37] neg_lo:[1,0,0] neg_hi:[1,0,0]
	s_nop 0
	v_pk_fma_f32 v[36:37], v[26:27], v[84:85], v[36:37] neg_lo:[1,0,0] neg_hi:[1,0,0]
	s_nop 0
	v_pk_fma_f32 v[36:37], v[28:29], v[86:87], v[36:37] neg_lo:[1,0,0] neg_hi:[1,0,0]
	s_nop 0
	v_pk_fma_f32 v[36:37], v[30:31], v[92:93], v[36:37] neg_lo:[1,0,0] neg_hi:[1,0,0]
	s_nop 0
	v_pk_fma_f32 v[36:37], v[32:33], v[94:95], v[36:37] neg_lo:[1,0,0] neg_hi:[1,0,0]
	s_nop 0
	v_pk_fma_f32 v[36:37], v[48:49], v[34:35], v[36:37] neg_lo:[1,0,0] neg_hi:[1,0,0]
	s_nop 0
	v_pk_add_f32 v[36:37], v[36:37], v[36:37] op_sel:[0,1] op_sel_hi:[1,0]
	v_mov_b32_e32 v0, 0x1ac00
	ds_read_b128 v[38:41], v0
	v_mov_b32_e32 v0, 0x1ac10
	ds_read_b128 v[42:45], v0
	v_mov_b32_e32 v0, 0x1ac20
	ds_read_b128 v[46:49], v0
	v_mov_b32_e32 v0, 0x1ac30
	ds_read_b128 v[52:55], v0
	v_mov_b32_e32 v0, 0x1ac40
	ds_read_b128 v[56:59], v0
	v_mov_b32_e32 v0, 0x1ac50
	ds_read_b128 v[60:63], v0
	v_or_b32_e32 v0, 0x1c890, v67
	v_mov_b32_e32 v37, 0x1ac80
	v_mov_b32_e32 v65, 0x1ac60
	ds_read_b128 v[84:87], v37
	ds_read_b32 v0, v0
	ds_read_b32 v37, v66 offset:18432
	ds_read_b128 v[92:95], v65
	v_mov_b32_e32 v65, 0x1ac70
	ds_read_b128 v[116:119], v65
	s_waitcnt lgkmcnt(0)
; DI void gdn_prep_item(const Params& P, int l, int n, int hh, char* smem) {
;     ...
;     for (int i = 1; i < 64; ++i) {
;       f32x4 (&CUR)[16] = (i & 1) ? LA : LB; f32x4 (&NXT)[16] = (i & 1) ? LB : LA;
;       if (i + 1 < 64) {
; #pragma unroll
;         for (int c = 0; c < (i + 4) / 4; ++c) NXT[c] = *(const f32x4*)(Lm + (i + 1) * 64 + 4 * c);
;         rh[(i + 1) & 1] = sp[i + 1] * rp[(i + 1) * 128];
;       }
;       __builtin_amdgcn_sched_barrier(0);
;       f32x2 acc = {rh[i & 1], 0.f};
; #pragma unroll
;       for (int p = 0; p < i / 2; ++p) { const f32x2 lp = (p & 1) ? (f32x2){CUR[p >> 1].z, CUR[p >> 1].w} : (f32x2){CUR[p >> 1].x, CUR[p >> 1].y}; acc = acc - lp * xx[p]; }
;       if (i & 1) { const int j = i - 1; const float lj = ((j & 3) == 0) ? CUR[j >> 2].x : CUR[j >> 2].z; acc.x = fmaf(-lj, xx[j >> 1].x, acc.x); }
;       const float xi = acc.x + acc.y;
;       if (i & 1) xx[i >> 1].y = xi; else xx[i >> 1].x = xi;
;       __builtin_amdgcn_sched_barrier(0);
;     }
	v_mul_f32_e32 v0, v0, v37
	v_mov_b32_e32 v65, v1
	v_pk_fma_f32 v[64:65], v[2:3], v[70:71], v[64:65] neg_lo:[1,0,0] neg_hi:[1,0,0]
	s_nop 0
	v_pk_fma_f32 v[64:65], v[4:5], v[72:73], v[64:65] neg_lo:[1,0,0] neg_hi:[1,0,0]
	s_nop 0
	v_pk_fma_f32 v[64:65], v[6:7], v[74:75], v[64:65] neg_lo:[1,0,0] neg_hi:[1,0,0]
	s_nop 0
	v_pk_fma_f32 v[64:65], v[8:9], v[76:77], v[64:65] neg_lo:[1,0,0] neg_hi:[1,0,0]
	s_nop 0
	v_pk_fma_f32 v[64:65], v[10:11], v[78:79], v[64:65] neg_lo:[1,0,0] neg_hi:[1,0,0]
	s_nop 0
	v_pk_fma_f32 v[64:65], v[12:13], v[80:81], v[64:65] neg_lo:[1,0,0] neg_hi:[1,0,0]
	s_nop 0
	v_pk_fma_f32 v[64:65], v[14:15], v[88:89], v[64:65] neg_lo:[1,0,0] neg_hi:[1,0,0]
	s_nop 0
	v_pk_fma_f32 v[64:65], v[16:17], v[90:91], v[64:65] neg_lo:[1,0,0] neg_hi:[1,0,0]
	s_nop 0
	v_pk_fma_f32 v[64:65], v[18:19], v[96:97], v[64:65] neg_lo:[1,0,0] neg_hi:[1,0,0]
	s_nop 0
	v_pk_fma_f32 v[64:65], v[20:21], v[98:99], v[64:65] neg_lo:[1,0,0] neg_hi:[1,0,0]
	s_nop 0
	v_pk_fma_f32 v[64:65], v[22:23], v[100:101], v[64:65] neg_lo:[1,0,0] neg_hi:[1,0,0]
	s_nop 0
	v_pk_fma_f32 v[64:65], v[24:25], v[102:103], v[64:65] neg_lo:[1,0,0] neg_hi:[1,0,0]
	s_nop 0
	v_pk_fma_f32 v[64:65], v[26:27], v[108:109], v[64:65] neg_lo:[1,0,0] neg_hi:[1,0,0]
	s_nop 0
	v_pk_fma_f32 v[64:65], v[28:29], v[110:111], v[64:65] neg_lo:[1,0,0] neg_hi:[1,0,0]
	s_nop 0
	v_pk_fma_f32 v[64:65], v[30:31], v[112:113], v[64:65] neg_lo:[1,0,0] neg_hi:[1,0,0]
	s_nop 0
	v_pk_fma_f32 v[64:65], v[32:33], v[114:115], v[64:65] neg_lo:[1,0,0] neg_hi:[1,0,0]
	s_nop 0
	v_pk_fma_f32 v[64:65], v[34:35], v[104:105], v[64:65] neg_lo:[1,0,0] neg_hi:[1,0,0]
	s_nop 0
	v_fma_f32 v37, -v106, v36, v64
	v_add_f32_e32 v37, v65, v37
	v_mov_b32_e32 v64, 0x1ad00
	ds_read_b128 v[70:73], v64
	v_mov_b32_e32 v64, 0x1ad10
	ds_read_b128 v[74:77], v64
	v_mov_b32_e32 v64, 0x1ad20
	ds_read_b128 v[78:81], v64
	v_mov_b32_e32 v64, 0x1ad30
	ds_read_b128 v[88:91], v64
	v_mov_b32_e32 v64, 0x1ad40
	ds_read_b128 v[96:99], v64
	v_mov_b32_e32 v64, 0x1ad50
	ds_read_b128 v[100:103], v64
	v_mov_b32_e32 v64, 0x1ad60
	ds_read_b128 v[104:107], v64
	v_mov_b32_e32 v64, 0x1ad70
	ds_read_b128 v[108:111], v64
	v_mov_b32_e32 v64, 0x1ad80
	ds_read_b128 v[112:115], v64
	v_mov_b32_e32 v64, 0x1ad90
	ds_read_b128 v[120:123], v64
	v_or_b32_e32 v64, 0x1c894, v67
	ds_read_b32 v64, v64
	ds_read_b32 v65, v66 offset:18944
	s_waitcnt lgkmcnt(0)
	v_mul_f32_e32 v64, v64, v65
	v_pk_fma_f32 v[38:39], v[2:3], v[38:39], v[0:1] neg_lo:[1,0,0] neg_hi:[1,0,0]
	s_nop 0
	v_pk_fma_f32 v[38:39], v[4:5], v[40:41], v[38:39] neg_lo:[1,0,0] neg_hi:[1,0,0]
	s_nop 0
	v_pk_fma_f32 v[38:39], v[6:7], v[42:43], v[38:39] neg_lo:[1,0,0] neg_hi:[1,0,0]
	s_nop 0
	v_pk_fma_f32 v[38:39], v[8:9], v[44:45], v[38:39] neg_lo:[1,0,0] neg_hi:[1,0,0]
	s_nop 0
	v_pk_fma_f32 v[38:39], v[10:11], v[46:47], v[38:39] neg_lo:[1,0,0] neg_hi:[1,0,0]
	s_nop 0
	v_pk_fma_f32 v[38:39], v[12:13], v[48:49], v[38:39] neg_lo:[1,0,0] neg_hi:[1,0,0]
	s_nop 0
	v_pk_fma_f32 v[38:39], v[14:15], v[52:53], v[38:39] neg_lo:[1,0,0] neg_hi:[1,0,0]
	s_nop 0
	v_pk_fma_f32 v[38:39], v[16:17], v[54:55], v[38:39] neg_lo:[1,0,0] neg_hi:[1,0,0]
	s_nop 0
	v_pk_fma_f32 v[38:39], v[18:19], v[56:57], v[38:39] neg_lo:[1,0,0] neg_hi:[1,0,0]
	s_nop 0
	v_pk_fma_f32 v[38:39], v[20:21], v[58:59], v[38:39] neg_lo:[1,0,0] neg_hi:[1,0,0]
	s_nop 0
	v_pk_fma_f32 v[38:39], v[22:23], v[60:61], v[38:39] neg_lo:[1,0,0] neg_hi:[1,0,0]
	s_nop 0
	v_pk_fma_f32 v[38:39], v[24:25], v[62:63], v[38:39] neg_lo:[1,0,0] neg_hi:[1,0,0]
	s_nop 0
	v_pk_fma_f32 v[38:39], v[26:27], v[92:93], v[38:39] neg_lo:[1,0,0] neg_hi:[1,0,0]
	s_nop 0
	v_pk_fma_f32 v[38:39], v[28:29], v[94:95], v[38:39] neg_lo:[1,0,0] neg_hi:[1,0,0]
	s_nop 0
	v_pk_fma_f32 v[38:39], v[30:31], v[116:117], v[38:39] neg_lo:[1,0,0] neg_hi:[1,0,0]
	s_nop 0
	v_pk_fma_f32 v[38:39], v[32:33], v[118:119], v[38:39] neg_lo:[1,0,0] neg_hi:[1,0,0]
	s_nop 0
	v_pk_fma_f32 v[38:39], v[34:35], v[84:85], v[38:39] neg_lo:[1,0,0] neg_hi:[1,0,0]
	s_nop 0
	v_pk_fma_f32 v[38:39], v[86:87], v[36:37], v[38:39] neg_lo:[1,0,0] neg_hi:[1,0,0]
	s_nop 0
	v_pk_add_f32 v[38:39], v[38:39], v[38:39] op_sel:[0,1] op_sel_hi:[1,0]
	v_mov_b32_e32 v0, 0x1ae00
	ds_read_b128 v[40:43], v0
	v_mov_b32_e32 v0, 0x1ae10
	ds_read_b128 v[44:47], v0
	v_mov_b32_e32 v0, 0x1ae20
	ds_read_b128 v[52:55], v0
	v_mov_b32_e32 v0, 0x1ae30
	ds_read_b128 v[56:59], v0
	v_mov_b32_e32 v0, 0x1ae40
	ds_read_b128 v[60:63], v0
	v_mov_b32_e32 v0, 0x1ae50
	ds_read_b128 v[84:87], v0
	v_mov_b32_e32 v0, 0x1ae60
	ds_read_b128 v[92:95], v0
	v_mov_b32_e32 v0, 0x1ae70
	ds_read_b128 v[116:119], v0
	v_or_b32_e32 v0, 0x1c898, v67
	v_mov_b32_e32 v48, 0x1ae80
	ds_read_b32 v0, v0
	ds_read_b32 v39, v66 offset:19456
	ds_read_b128 v[122:125], v48
	v_mov_b32_e32 v48, 0x1ae90
	ds_read_b64 v[48:49], v48
	s_waitcnt lgkmcnt(0)
; DI void gdn_prep_item(const Params& P, int l, int n, int hh, char* smem) {
;     ...
;     for (int i = 1; i < 64; ++i) {
;       f32x4 (&CUR)[16] = (i & 1) ? LA : LB; f32x4 (&NXT)[16] = (i & 1) ? LB : LA;
;       if (i + 1 < 64) {
; #pragma unroll
;         for (int c = 0; c < (i + 4) / 4; ++c) NXT[c] = *(const f32x4*)(Lm + (i + 1) * 64 + 4 * c);
;         rh[(i + 1) & 1] = sp[i + 1] * rp[(i + 1) * 128];
;       }
;       __builtin_amdgcn_sched_barrier(0);
;       f32x2 acc = {rh[i & 1], 0.f};
; #pragma unroll
;       for (int p = 0; p < i / 2; ++p) { const f32x2 lp = (p & 1) ? (f32x2){CUR[p >> 1].z, CUR[p >> 1].w} : (f32x2){CUR[p >> 1].x, CUR[p >> 1].y}; acc = acc - lp * xx[p]; }
;       if (i & 1) { const int j = i - 1; const float lj = ((j & 3) == 0) ? CUR[j >> 2].x : CUR[j >> 2].z; acc.x = fmaf(-lj, xx[j >> 1].x, acc.x); }
;       const float xi = acc.x + acc.y;
;       if (i & 1) xx[i >> 1].y = xi; else xx[i >> 1].x = xi;
;       __builtin_amdgcn_sched_barrier(0);
;     }
	v_mul_f32_e32 v0, v0, v39
	v_mov_b32_e32 v65, v1
	v_pk_fma_f32 v[64:65], v[2:3], v[70:71], v[64:65] neg_lo:[1,0,0] neg_hi:[1,0,0]
	s_nop 0
	v_pk_fma_f32 v[64:65], v[4:5], v[72:73], v[64:65] neg_lo:[1,0,0] neg_hi:[1,0,0]
	s_nop 0
	v_pk_fma_f32 v[64:65], v[6:7], v[74:75], v[64:65] neg_lo:[1,0,0] neg_hi:[1,0,0]
	s_nop 0
	v_pk_fma_f32 v[64:65], v[8:9], v[76:77], v[64:65] neg_lo:[1,0,0] neg_hi:[1,0,0]
	s_nop 0
	v_pk_fma_f32 v[64:65], v[10:11], v[78:79], v[64:65] neg_lo:[1,0,0] neg_hi:[1,0,0]
	s_nop 0
	v_pk_fma_f32 v[64:65], v[12:13], v[80:81], v[64:65] neg_lo:[1,0,0] neg_hi:[1,0,0]
	s_nop 0
	v_pk_fma_f32 v[64:65], v[14:15], v[88:89], v[64:65] neg_lo:[1,0,0] neg_hi:[1,0,0]
	s_nop 0
	v_pk_fma_f32 v[64:65], v[16:17], v[90:91], v[64:65] neg_lo:[1,0,0] neg_hi:[1,0,0]
	s_nop 0
	v_pk_fma_f32 v[64:65], v[18:19], v[96:97], v[64:65] neg_lo:[1,0,0] neg_hi:[1,0,0]
	s_nop 0
	v_pk_fma_f32 v[64:65], v[20:21], v[98:99], v[64:65] neg_lo:[1,0,0] neg_hi:[1,0,0]
	s_nop 0
	v_pk_fma_f32 v[64:65], v[22:23], v[100:101], v[64:65] neg_lo:[1,0,0] neg_hi:[1,0,0]
	s_nop 0
	v_pk_fma_f32 v[64:65], v[24:25], v[102:103], v[64:65] neg_lo:[1,0,0] neg_hi:[1,0,0]
	s_nop 0
	v_pk_fma_f32 v[64:65], v[26:27], v[104:105], v[64:65] neg_lo:[1,0,0] neg_hi:[1,0,0]
	s_nop 0
	v_pk_fma_f32 v[64:65], v[28:29], v[106:107], v[64:65] neg_lo:[1,0,0] neg_hi:[1,0,0]
	s_nop 0
	v_pk_fma_f32 v[64:65], v[30:31], v[108:109], v[64:65] neg_lo:[1,0,0] neg_hi:[1,0,0]
	s_nop 0
	v_pk_fma_f32 v[64:65], v[32:33], v[110:111], v[64:65] neg_lo:[1,0,0] neg_hi:[1,0,0]
	s_nop 0
	v_pk_fma_f32 v[64:65], v[34:35], v[112:113], v[64:65] neg_lo:[1,0,0] neg_hi:[1,0,0]
	s_nop 0
	v_pk_fma_f32 v[64:65], v[36:37], v[114:115], v[64:65] neg_lo:[1,0,0] neg_hi:[1,0,0]
	s_nop 0
	v_fma_f32 v39, -v120, v38, v64
	v_add_f32_e32 v39, v65, v39
	v_mov_b32_e32 v64, 0x1af00
	ds_read_b128 v[70:73], v64
	v_mov_b32_e32 v64, 0x1af10
	ds_read_b128 v[74:77], v64
	v_mov_b32_e32 v64, 0x1af20
	ds_read_b128 v[78:81], v64
	v_mov_b32_e32 v64, 0x1af30
	ds_read_b128 v[88:91], v64
	v_mov_b32_e32 v64, 0x1af40
	ds_read_b128 v[96:99], v64
	v_mov_b32_e32 v64, 0x1af50
	ds_read_b128 v[100:103], v64
	v_mov_b32_e32 v64, 0x1af60
	ds_read_b128 v[104:107], v64
	v_mov_b32_e32 v64, 0x1af70
	ds_read_b128 v[108:111], v64
	v_or_b32_e32 v64, 0x1c89c, v67
	ds_read_b32 v64, v64
	ds_read_b32 v65, v66 offset:19968
	v_mov_b32_e32 v83, 0x1af80
	ds_read_b128 v[112:115], v83
	v_mov_b32_e32 v83, 0x1af90
	ds_read_b128 v[126:129], v83
	s_waitcnt lgkmcnt(0)
	v_mul_f32_e32 v64, v64, v65
	v_pk_fma_f32 v[40:41], v[2:3], v[40:41], v[0:1] neg_lo:[1,0,0] neg_hi:[1,0,0]
	s_nop 0
	v_pk_fma_f32 v[40:41], v[4:5], v[42:43], v[40:41] neg_lo:[1,0,0] neg_hi:[1,0,0]
	s_nop 0
	v_pk_fma_f32 v[40:41], v[6:7], v[44:45], v[40:41] neg_lo:[1,0,0] neg_hi:[1,0,0]
	s_nop 0
	v_pk_fma_f32 v[40:41], v[8:9], v[46:47], v[40:41] neg_lo:[1,0,0] neg_hi:[1,0,0]
	s_nop 0
	v_pk_fma_f32 v[40:41], v[10:11], v[52:53], v[40:41] neg_lo:[1,0,0] neg_hi:[1,0,0]
	s_nop 0
	v_pk_fma_f32 v[40:41], v[12:13], v[54:55], v[40:41] neg_lo:[1,0,0] neg_hi:[1,0,0]
	s_nop 0
	v_pk_fma_f32 v[40:41], v[14:15], v[56:57], v[40:41] neg_lo:[1,0,0] neg_hi:[1,0,0]
	s_nop 0
	v_pk_fma_f32 v[40:41], v[16:17], v[58:59], v[40:41] neg_lo:[1,0,0] neg_hi:[1,0,0]
	s_nop 0
	v_pk_fma_f32 v[40:41], v[18:19], v[60:61], v[40:41] neg_lo:[1,0,0] neg_hi:[1,0,0]
	s_nop 0
	v_pk_fma_f32 v[40:41], v[20:21], v[62:63], v[40:41] neg_lo:[1,0,0] neg_hi:[1,0,0]
	s_nop 0
	v_pk_fma_f32 v[40:41], v[22:23], v[84:85], v[40:41] neg_lo:[1,0,0] neg_hi:[1,0,0]
	s_nop 0
	v_pk_fma_f32 v[40:41], v[24:25], v[86:87], v[40:41] neg_lo:[1,0,0] neg_hi:[1,0,0]
	s_nop 0
	v_pk_fma_f32 v[40:41], v[26:27], v[92:93], v[40:41] neg_lo:[1,0,0] neg_hi:[1,0,0]
	s_nop 0
	v_pk_fma_f32 v[40:41], v[28:29], v[94:95], v[40:41] neg_lo:[1,0,0] neg_hi:[1,0,0]
	s_nop 0
	v_pk_fma_f32 v[40:41], v[30:31], v[116:117], v[40:41] neg_lo:[1,0,0] neg_hi:[1,0,0]
	s_nop 0
	v_pk_fma_f32 v[40:41], v[32:33], v[118:119], v[40:41] neg_lo:[1,0,0] neg_hi:[1,0,0]
	s_nop 0
	v_pk_fma_f32 v[40:41], v[34:35], v[122:123], v[40:41] neg_lo:[1,0,0] neg_hi:[1,0,0]
	s_nop 0
	v_pk_fma_f32 v[40:41], v[36:37], v[124:125], v[40:41] neg_lo:[1,0,0] neg_hi:[1,0,0]
	s_nop 0
	v_pk_fma_f32 v[40:41], v[48:49], v[38:39], v[40:41] neg_lo:[1,0,0] neg_hi:[1,0,0]
	s_nop 0
	v_pk_add_f32 v[40:41], v[40:41], v[40:41] op_sel:[0,1] op_sel_hi:[1,0]
	v_mov_b32_e32 v0, 0x1b000
	ds_read_b128 v[42:45], v0
	v_mov_b32_e32 v0, 0x1b010
	ds_read_b128 v[46:49], v0
	v_mov_b32_e32 v0, 0x1b020
	ds_read_b128 v[52:55], v0
	v_mov_b32_e32 v0, 0x1b030
	ds_read_b128 v[56:59], v0
	v_mov_b32_e32 v0, 0x1b040
	ds_read_b128 v[60:63], v0
	v_mov_b32_e32 v0, 0x1b050
	ds_read_b128 v[84:87], v0
	v_mov_b32_e32 v0, 0x1b060
	ds_read_b128 v[92:95], v0
	v_mov_b32_e32 v0, 0x1b070
	ds_read_b128 v[116:119], v0
	v_or_b32_e32 v0, 0x1c8a0, v67
	v_mov_b32_e32 v65, 0x1b080
	ds_read_b32 v0, v0
	ds_read_b32 v41, v66 offset:20480
	ds_read_b128 v[120:123], v65
	v_mov_b32_e32 v65, 0x1b090
	ds_read_b128 v[130:133], v65
	s_waitcnt lgkmcnt(0)
; DI void gdn_prep_item(const Params& P, int l, int n, int hh, char* smem) {
;     ...
;     for (int i = 1; i < 64; ++i) {
;       f32x4 (&CUR)[16] = (i & 1) ? LA : LB; f32x4 (&NXT)[16] = (i & 1) ? LB : LA;
;       if (i + 1 < 64) {
; #pragma unroll
;         for (int c = 0; c < (i + 4) / 4; ++c) NXT[c] = *(const f32x4*)(Lm + (i + 1) * 64 + 4 * c);
;         rh[(i + 1) & 1] = sp[i + 1] * rp[(i + 1) * 128];
;       }
;       __builtin_amdgcn_sched_barrier(0);
;       f32x2 acc = {rh[i & 1], 0.f};
; #pragma unroll
;       for (int p = 0; p < i / 2; ++p) { const f32x2 lp = (p & 1) ? (f32x2){CUR[p >> 1].z, CUR[p >> 1].w} : (f32x2){CUR[p >> 1].x, CUR[p >> 1].y}; acc = acc - lp * xx[p]; }
;       if (i & 1) { const int j = i - 1; const float lj = ((j & 3) == 0) ? CUR[j >> 2].x : CUR[j >> 2].z; acc.x = fmaf(-lj, xx[j >> 1].x, acc.x); }
;       const float xi = acc.x + acc.y;
;       if (i & 1) xx[i >> 1].y = xi; else xx[i >> 1].x = xi;
;       __builtin_amdgcn_sched_barrier(0);
;     }
	v_mul_f32_e32 v0, v0, v41
	v_mov_b32_e32 v65, v1
	v_pk_fma_f32 v[64:65], v[2:3], v[70:71], v[64:65] neg_lo:[1,0,0] neg_hi:[1,0,0]
	s_nop 0
	v_pk_fma_f32 v[64:65], v[4:5], v[72:73], v[64:65] neg_lo:[1,0,0] neg_hi:[1,0,0]
	s_nop 0
	v_pk_fma_f32 v[64:65], v[6:7], v[74:75], v[64:65] neg_lo:[1,0,0] neg_hi:[1,0,0]
	s_nop 0
	v_pk_fma_f32 v[64:65], v[8:9], v[76:77], v[64:65] neg_lo:[1,0,0] neg_hi:[1,0,0]
	s_nop 0
	v_pk_fma_f32 v[64:65], v[10:11], v[78:79], v[64:65] neg_lo:[1,0,0] neg_hi:[1,0,0]
	s_nop 0
	v_pk_fma_f32 v[64:65], v[12:13], v[80:81], v[64:65] neg_lo:[1,0,0] neg_hi:[1,0,0]
	s_nop 0
	v_pk_fma_f32 v[64:65], v[14:15], v[88:89], v[64:65] neg_lo:[1,0,0] neg_hi:[1,0,0]
	s_nop 0
	v_pk_fma_f32 v[64:65], v[16:17], v[90:91], v[64:65] neg_lo:[1,0,0] neg_hi:[1,0,0]
	s_nop 0
	v_pk_fma_f32 v[64:65], v[18:19], v[96:97], v[64:65] neg_lo:[1,0,0] neg_hi:[1,0,0]
	s_nop 0
	v_pk_fma_f32 v[64:65], v[20:21], v[98:99], v[64:65] neg_lo:[1,0,0] neg_hi:[1,0,0]
	s_nop 0
	v_pk_fma_f32 v[64:65], v[22:23], v[100:101], v[64:65] neg_lo:[1,0,0] neg_hi:[1,0,0]
	s_nop 0
	v_pk_fma_f32 v[64:65], v[24:25], v[102:103], v[64:65] neg_lo:[1,0,0] neg_hi:[1,0,0]
	s_nop 0
	v_pk_fma_f32 v[64:65], v[26:27], v[104:105], v[64:65] neg_lo:[1,0,0] neg_hi:[1,0,0]
	s_nop 0
	v_pk_fma_f32 v[64:65], v[28:29], v[106:107], v[64:65] neg_lo:[1,0,0] neg_hi:[1,0,0]
	s_nop 0
	v_pk_fma_f32 v[64:65], v[30:31], v[108:109], v[64:65] neg_lo:[1,0,0] neg_hi:[1,0,0]
	s_nop 0
	v_pk_fma_f32 v[64:65], v[32:33], v[110:111], v[64:65] neg_lo:[1,0,0] neg_hi:[1,0,0]
	s_nop 0
	v_pk_fma_f32 v[64:65], v[34:35], v[112:113], v[64:65] neg_lo:[1,0,0] neg_hi:[1,0,0]
	s_nop 0
	v_pk_fma_f32 v[64:65], v[36:37], v[114:115], v[64:65] neg_lo:[1,0,0] neg_hi:[1,0,0]
	s_nop 0
	v_pk_fma_f32 v[64:65], v[38:39], v[126:127], v[64:65] neg_lo:[1,0,0] neg_hi:[1,0,0]
	s_nop 0
	v_fma_f32 v41, -v128, v40, v64
	v_add_f32_e32 v41, v65, v41
	v_mov_b32_e32 v64, 0x1b100
	ds_read_b128 v[70:73], v64
	v_mov_b32_e32 v64, 0x1b110
	ds_read_b128 v[74:77], v64
	v_mov_b32_e32 v64, 0x1b120
	ds_read_b128 v[78:81], v64
	v_mov_b32_e32 v64, 0x1b130
	ds_read_b128 v[88:91], v64
	v_mov_b32_e32 v64, 0x1b140
	ds_read_b128 v[96:99], v64
	v_mov_b32_e32 v64, 0x1b150
	ds_read_b128 v[100:103], v64
	v_mov_b32_e32 v64, 0x1b160
	ds_read_b128 v[104:107], v64
	v_mov_b32_e32 v64, 0x1b170
	ds_read_b128 v[108:111], v64
	v_or_b32_e32 v64, 0x1c8a4, v67
	v_mov_b32_e32 v65, 0x1b1a0
	ds_read_b128 v[112:115], v65
	ds_read_b32 v64, v64
	ds_read_b32 v65, v66 offset:20992
	v_mov_b32_e32 v83, 0x1b180
	ds_read_b128 v[124:127], v83
	v_mov_b32_e32 v83, 0x1b190
	ds_read_b128 v[134:137], v83
	s_waitcnt lgkmcnt(0)
	v_mul_f32_e32 v64, v64, v65
	v_pk_fma_f32 v[42:43], v[2:3], v[42:43], v[0:1] neg_lo:[1,0,0] neg_hi:[1,0,0]
	s_nop 0
	v_pk_fma_f32 v[42:43], v[4:5], v[44:45], v[42:43] neg_lo:[1,0,0] neg_hi:[1,0,0]
	s_nop 0
	v_pk_fma_f32 v[42:43], v[6:7], v[46:47], v[42:43] neg_lo:[1,0,0] neg_hi:[1,0,0]
	s_nop 0
	v_pk_fma_f32 v[42:43], v[8:9], v[48:49], v[42:43] neg_lo:[1,0,0] neg_hi:[1,0,0]
	s_nop 0
	v_pk_fma_f32 v[42:43], v[10:11], v[52:53], v[42:43] neg_lo:[1,0,0] neg_hi:[1,0,0]
	s_nop 0
	v_pk_fma_f32 v[42:43], v[12:13], v[54:55], v[42:43] neg_lo:[1,0,0] neg_hi:[1,0,0]
	s_nop 0
	v_pk_fma_f32 v[42:43], v[14:15], v[56:57], v[42:43] neg_lo:[1,0,0] neg_hi:[1,0,0]
	s_nop 0
	v_pk_fma_f32 v[42:43], v[16:17], v[58:59], v[42:43] neg_lo:[1,0,0] neg_hi:[1,0,0]
	s_nop 0
	v_pk_fma_f32 v[42:43], v[18:19], v[60:61], v[42:43] neg_lo:[1,0,0] neg_hi:[1,0,0]
	s_nop 0
	v_pk_fma_f32 v[42:43], v[20:21], v[62:63], v[42:43] neg_lo:[1,0,0] neg_hi:[1,0,0]
	s_nop 0
	v_pk_fma_f32 v[42:43], v[22:23], v[84:85], v[42:43] neg_lo:[1,0,0] neg_hi:[1,0,0]
	s_nop 0
	v_pk_fma_f32 v[42:43], v[24:25], v[86:87], v[42:43] neg_lo:[1,0,0] neg_hi:[1,0,0]
	s_nop 0
	v_pk_fma_f32 v[42:43], v[26:27], v[92:93], v[42:43] neg_lo:[1,0,0] neg_hi:[1,0,0]
	s_nop 0
	v_pk_fma_f32 v[42:43], v[28:29], v[94:95], v[42:43] neg_lo:[1,0,0] neg_hi:[1,0,0]
	s_nop 0
	v_pk_fma_f32 v[42:43], v[30:31], v[116:117], v[42:43] neg_lo:[1,0,0] neg_hi:[1,0,0]
	s_nop 0
	v_pk_fma_f32 v[42:43], v[32:33], v[118:119], v[42:43] neg_lo:[1,0,0] neg_hi:[1,0,0]
	s_nop 0
	v_pk_fma_f32 v[42:43], v[34:35], v[120:121], v[42:43] neg_lo:[1,0,0] neg_hi:[1,0,0]
	s_nop 0
	v_pk_fma_f32 v[42:43], v[36:37], v[122:123], v[42:43] neg_lo:[1,0,0] neg_hi:[1,0,0]
	s_nop 0
	v_pk_fma_f32 v[42:43], v[38:39], v[130:131], v[42:43] neg_lo:[1,0,0] neg_hi:[1,0,0]
	s_nop 0
	v_pk_fma_f32 v[42:43], v[132:133], v[40:41], v[42:43] neg_lo:[1,0,0] neg_hi:[1,0,0]
	s_nop 0
	v_pk_add_f32 v[42:43], v[42:43], v[42:43] op_sel:[0,1] op_sel_hi:[1,0]
	v_mov_b32_e32 v0, 0x1b200
	ds_read_b128 v[44:47], v0
	v_mov_b32_e32 v0, 0x1b210
	ds_read_b128 v[52:55], v0
	v_mov_b32_e32 v0, 0x1b220
	ds_read_b128 v[56:59], v0
	v_mov_b32_e32 v0, 0x1b230
	ds_read_b128 v[60:63], v0
	v_mov_b32_e32 v0, 0x1b240
	ds_read_b128 v[84:87], v0
	v_mov_b32_e32 v0, 0x1b250
	ds_read_b128 v[92:95], v0
	v_mov_b32_e32 v0, 0x1b260
	ds_read_b128 v[114:117], v0
	v_mov_b32_e32 v0, 0x1b270
	ds_read_b128 v[118:121], v0
	v_or_b32_e32 v0, 0x1c8a8, v67
	v_mov_b32_e32 v43, 0x1b2a0
	v_mov_b32_e32 v65, 0x1b280
	ds_read_b64 v[48:49], v43
	ds_read_b32 v0, v0
	ds_read_b32 v43, v66 offset:21504
	ds_read_b128 v[128:131], v65
	v_mov_b32_e32 v65, 0x1b290
	ds_read_b128 v[138:141], v65
	s_waitcnt lgkmcnt(0)
; DI void gdn_prep_item(const Params& P, int l, int n, int hh, char* smem) {
;     ...
;     for (int i = 1; i < 64; ++i) {
;       f32x4 (&CUR)[16] = (i & 1) ? LA : LB; f32x4 (&NXT)[16] = (i & 1) ? LB : LA;
;       if (i + 1 < 64) {
; #pragma unroll
;         for (int c = 0; c < (i + 4) / 4; ++c) NXT[c] = *(const f32x4*)(Lm + (i + 1) * 64 + 4 * c);
;         rh[(i + 1) & 1] = sp[i + 1] * rp[(i + 1) * 128];
;       }
;       __builtin_amdgcn_sched_barrier(0);
;       f32x2 acc = {rh[i & 1], 0.f};
; #pragma unroll
;       for (int p = 0; p < i / 2; ++p) { const f32x2 lp = (p & 1) ? (f32x2){CUR[p >> 1].z, CUR[p >> 1].w} : (f32x2){CUR[p >> 1].x, CUR[p >> 1].y}; acc = acc - lp * xx[p]; }
;       if (i & 1) { const int j = i - 1; const float lj = ((j & 3) == 0) ? CUR[j >> 2].x : CUR[j >> 2].z; acc.x = fmaf(-lj, xx[j >> 1].x, acc.x); }
;       const float xi = acc.x + acc.y;
;       if (i & 1) xx[i >> 1].y = xi; else xx[i >> 1].x = xi;
;       __builtin_amdgcn_sched_barrier(0);
;     }
	v_mul_f32_e32 v0, v0, v43
	v_mov_b32_e32 v65, v1
	v_pk_fma_f32 v[64:65], v[2:3], v[70:71], v[64:65] neg_lo:[1,0,0] neg_hi:[1,0,0]
	s_nop 0
	v_pk_fma_f32 v[64:65], v[4:5], v[72:73], v[64:65] neg_lo:[1,0,0] neg_hi:[1,0,0]
	s_nop 0
	v_pk_fma_f32 v[64:65], v[6:7], v[74:75], v[64:65] neg_lo:[1,0,0] neg_hi:[1,0,0]
	s_nop 0
	v_pk_fma_f32 v[64:65], v[8:9], v[76:77], v[64:65] neg_lo:[1,0,0] neg_hi:[1,0,0]
	s_nop 0
	v_pk_fma_f32 v[64:65], v[10:11], v[78:79], v[64:65] neg_lo:[1,0,0] neg_hi:[1,0,0]
	s_nop 0
	v_pk_fma_f32 v[64:65], v[12:13], v[80:81], v[64:65] neg_lo:[1,0,0] neg_hi:[1,0,0]
	s_nop 0
	v_pk_fma_f32 v[64:65], v[14:15], v[88:89], v[64:65] neg_lo:[1,0,0] neg_hi:[1,0,0]
	s_nop 0
	v_pk_fma_f32 v[64:65], v[16:17], v[90:91], v[64:65] neg_lo:[1,0,0] neg_hi:[1,0,0]
	s_nop 0
	v_pk_fma_f32 v[64:65], v[18:19], v[96:97], v[64:65] neg_lo:[1,0,0] neg_hi:[1,0,0]
	s_nop 0
	v_pk_fma_f32 v[64:65], v[20:21], v[98:99], v[64:65] neg_lo:[1,0,0] neg_hi:[1,0,0]
	s_nop 0
	v_pk_fma_f32 v[64:65], v[22:23], v[100:101], v[64:65] neg_lo:[1,0,0] neg_hi:[1,0,0]
	s_nop 0
	v_pk_fma_f32 v[64:65], v[24:25], v[102:103], v[64:65] neg_lo:[1,0,0] neg_hi:[1,0,0]
	s_nop 0
	v_pk_fma_f32 v[64:65], v[26:27], v[104:105], v[64:65] neg_lo:[1,0,0] neg_hi:[1,0,0]
	s_nop 0
	v_pk_fma_f32 v[64:65], v[28:29], v[106:107], v[64:65] neg_lo:[1,0,0] neg_hi:[1,0,0]
	s_nop 0
	v_pk_fma_f32 v[64:65], v[30:31], v[108:109], v[64:65] neg_lo:[1,0,0] neg_hi:[1,0,0]
	s_nop 0
	v_pk_fma_f32 v[64:65], v[32:33], v[110:111], v[64:65] neg_lo:[1,0,0] neg_hi:[1,0,0]
	s_nop 0
	v_pk_fma_f32 v[64:65], v[34:35], v[124:125], v[64:65] neg_lo:[1,0,0] neg_hi:[1,0,0]
	s_nop 0
	v_pk_fma_f32 v[64:65], v[36:37], v[126:127], v[64:65] neg_lo:[1,0,0] neg_hi:[1,0,0]
	s_nop 0
	v_pk_fma_f32 v[64:65], v[38:39], v[134:135], v[64:65] neg_lo:[1,0,0] neg_hi:[1,0,0]
	s_nop 0
	v_pk_fma_f32 v[64:65], v[40:41], v[136:137], v[64:65] neg_lo:[1,0,0] neg_hi:[1,0,0]
	s_nop 0
	v_fma_f32 v43, -v112, v42, v64
	v_add_f32_e32 v43, v65, v43
	v_mov_b32_e32 v64, 0x1b300
	ds_read_b128 v[70:73], v64
	v_mov_b32_e32 v64, 0x1b310
	ds_read_b128 v[74:77], v64
	v_mov_b32_e32 v64, 0x1b320
	ds_read_b128 v[78:81], v64
	v_mov_b32_e32 v64, 0x1b330
	ds_read_b128 v[88:91], v64
	v_mov_b32_e32 v64, 0x1b340
	ds_read_b128 v[96:99], v64
	v_mov_b32_e32 v64, 0x1b350
	ds_read_b128 v[100:103], v64
	v_mov_b32_e32 v64, 0x1b360
	ds_read_b128 v[104:107], v64
	v_mov_b32_e32 v64, 0x1b370
	ds_read_b128 v[108:111], v64
	v_or_b32_e32 v64, 0x1c8ac, v67
	v_mov_b32_e32 v65, 0x1b3a0
	ds_read_b128 v[122:125], v65
	ds_read_b32 v64, v64
	ds_read_b32 v65, v66 offset:22016
	v_mov_b32_e32 v83, 0x1b380
	ds_read_b128 v[132:135], v83
	v_mov_b32_e32 v83, 0x1b390
	ds_read_b128 v[142:145], v83
	s_waitcnt lgkmcnt(0)
	v_mul_f32_e32 v64, v64, v65
	v_pk_fma_f32 v[44:45], v[2:3], v[44:45], v[0:1] neg_lo:[1,0,0] neg_hi:[1,0,0]
	s_nop 0
	v_pk_fma_f32 v[44:45], v[4:5], v[46:47], v[44:45] neg_lo:[1,0,0] neg_hi:[1,0,0]
	s_nop 0
	v_pk_fma_f32 v[44:45], v[6:7], v[52:53], v[44:45] neg_lo:[1,0,0] neg_hi:[1,0,0]
	s_nop 0
	v_pk_fma_f32 v[44:45], v[8:9], v[54:55], v[44:45] neg_lo:[1,0,0] neg_hi:[1,0,0]
	s_nop 0
	v_pk_fma_f32 v[44:45], v[10:11], v[56:57], v[44:45] neg_lo:[1,0,0] neg_hi:[1,0,0]
	s_nop 0
	v_pk_fma_f32 v[44:45], v[12:13], v[58:59], v[44:45] neg_lo:[1,0,0] neg_hi:[1,0,0]
	s_nop 0
	v_pk_fma_f32 v[44:45], v[14:15], v[60:61], v[44:45] neg_lo:[1,0,0] neg_hi:[1,0,0]
	s_nop 0
	v_pk_fma_f32 v[44:45], v[16:17], v[62:63], v[44:45] neg_lo:[1,0,0] neg_hi:[1,0,0]
	s_nop 0
	v_pk_fma_f32 v[44:45], v[18:19], v[84:85], v[44:45] neg_lo:[1,0,0] neg_hi:[1,0,0]
	s_nop 0
	v_pk_fma_f32 v[44:45], v[20:21], v[86:87], v[44:45] neg_lo:[1,0,0] neg_hi:[1,0,0]
	s_nop 0
	v_pk_fma_f32 v[44:45], v[22:23], v[92:93], v[44:45] neg_lo:[1,0,0] neg_hi:[1,0,0]
	s_nop 0
	v_pk_fma_f32 v[44:45], v[24:25], v[94:95], v[44:45] neg_lo:[1,0,0] neg_hi:[1,0,0]
	s_nop 0
	v_pk_fma_f32 v[44:45], v[26:27], v[114:115], v[44:45] neg_lo:[1,0,0] neg_hi:[1,0,0]
	s_nop 0
	v_pk_fma_f32 v[44:45], v[28:29], v[116:117], v[44:45] neg_lo:[1,0,0] neg_hi:[1,0,0]
	s_nop 0
	v_pk_fma_f32 v[44:45], v[30:31], v[118:119], v[44:45] neg_lo:[1,0,0] neg_hi:[1,0,0]
	s_nop 0
	v_pk_fma_f32 v[44:45], v[32:33], v[120:121], v[44:45] neg_lo:[1,0,0] neg_hi:[1,0,0]
	s_nop 0
	v_pk_fma_f32 v[44:45], v[34:35], v[128:129], v[44:45] neg_lo:[1,0,0] neg_hi:[1,0,0]
	s_nop 0
	v_pk_fma_f32 v[44:45], v[36:37], v[130:131], v[44:45] neg_lo:[1,0,0] neg_hi:[1,0,0]
	s_nop 0
	v_pk_fma_f32 v[44:45], v[38:39], v[138:139], v[44:45] neg_lo:[1,0,0] neg_hi:[1,0,0]
	s_nop 0
	v_pk_fma_f32 v[44:45], v[40:41], v[140:141], v[44:45] neg_lo:[1,0,0] neg_hi:[1,0,0]
	s_nop 0
	v_pk_fma_f32 v[44:45], v[48:49], v[42:43], v[44:45] neg_lo:[1,0,0] neg_hi:[1,0,0]
	s_nop 0
	v_pk_add_f32 v[44:45], v[44:45], v[44:45] op_sel:[0,1] op_sel_hi:[1,0]
	v_mov_b32_e32 v0, 0x1b400
	ds_read_b128 v[46:49], v0
	v_mov_b32_e32 v0, 0x1b410
	ds_read_b128 v[52:55], v0
	v_mov_b32_e32 v0, 0x1b420
	ds_read_b128 v[56:59], v0
	v_mov_b32_e32 v0, 0x1b430
	ds_read_b128 v[60:63], v0
	v_mov_b32_e32 v0, 0x1b440
	ds_read_b128 v[84:87], v0
	v_mov_b32_e32 v0, 0x1b450
	ds_read_b128 v[92:95], v0
	v_mov_b32_e32 v0, 0x1b460
	ds_read_b128 v[112:115], v0
	v_mov_b32_e32 v0, 0x1b470
	ds_read_b128 v[116:119], v0
	v_or_b32_e32 v0, 0x1c8b0, v67
	v_mov_b32_e32 v45, 0x1b4a0
	v_mov_b32_e32 v65, 0x1b480
	ds_read_b128 v[126:129], v45
	ds_read_b32 v0, v0
	ds_read_b32 v45, v66 offset:22528
	ds_read_b128 v[136:139], v65
	v_mov_b32_e32 v65, 0x1b490
	ds_read_b128 v[146:149], v65
	s_waitcnt lgkmcnt(0)
; DI void gdn_prep_item(const Params& P, int l, int n, int hh, char* smem) {
;     ...
;     for (int i = 1; i < 64; ++i) {
;       f32x4 (&CUR)[16] = (i & 1) ? LA : LB; f32x4 (&NXT)[16] = (i & 1) ? LB : LA;
;       if (i + 1 < 64) {
; #pragma unroll
;         for (int c = 0; c < (i + 4) / 4; ++c) NXT[c] = *(const f32x4*)(Lm + (i + 1) * 64 + 4 * c);
;         rh[(i + 1) & 1] = sp[i + 1] * rp[(i + 1) * 128];
;       }
;       __builtin_amdgcn_sched_barrier(0);
;       f32x2 acc = {rh[i & 1], 0.f};
; #pragma unroll
;       for (int p = 0; p < i / 2; ++p) { const f32x2 lp = (p & 1) ? (f32x2){CUR[p >> 1].z, CUR[p >> 1].w} : (f32x2){CUR[p >> 1].x, CUR[p >> 1].y}; acc = acc - lp * xx[p]; }
;       if (i & 1) { const int j = i - 1; const float lj = ((j & 3) == 0) ? CUR[j >> 2].x : CUR[j >> 2].z; acc.x = fmaf(-lj, xx[j >> 1].x, acc.x); }
;       const float xi = acc.x + acc.y;
;       if (i & 1) xx[i >> 1].y = xi; else xx[i >> 1].x = xi;
;       __builtin_amdgcn_sched_barrier(0);
;     }
	v_mul_f32_e32 v0, v0, v45
	v_mov_b32_e32 v65, v1
	v_pk_fma_f32 v[64:65], v[2:3], v[70:71], v[64:65] neg_lo:[1,0,0] neg_hi:[1,0,0]
	s_nop 0
	v_pk_fma_f32 v[64:65], v[4:5], v[72:73], v[64:65] neg_lo:[1,0,0] neg_hi:[1,0,0]
	s_nop 0
	v_pk_fma_f32 v[64:65], v[6:7], v[74:75], v[64:65] neg_lo:[1,0,0] neg_hi:[1,0,0]
	s_nop 0
	v_pk_fma_f32 v[64:65], v[8:9], v[76:77], v[64:65] neg_lo:[1,0,0] neg_hi:[1,0,0]
	s_nop 0
	v_pk_fma_f32 v[64:65], v[10:11], v[78:79], v[64:65] neg_lo:[1,0,0] neg_hi:[1,0,0]
	s_nop 0
	v_pk_fma_f32 v[64:65], v[12:13], v[80:81], v[64:65] neg_lo:[1,0,0] neg_hi:[1,0,0]
	s_nop 0
	v_pk_fma_f32 v[64:65], v[14:15], v[88:89], v[64:65] neg_lo:[1,0,0] neg_hi:[1,0,0]
	s_nop 0
	v_pk_fma_f32 v[64:65], v[16:17], v[90:91], v[64:65] neg_lo:[1,0,0] neg_hi:[1,0,0]
	s_nop 0
	v_pk_fma_f32 v[64:65], v[18:19], v[96:97], v[64:65] neg_lo:[1,0,0] neg_hi:[1,0,0]
	s_nop 0
	v_pk_fma_f32 v[64:65], v[20:21], v[98:99], v[64:65] neg_lo:[1,0,0] neg_hi:[1,0,0]
	s_nop 0
	v_pk_fma_f32 v[64:65], v[22:23], v[100:101], v[64:65] neg_lo:[1,0,0] neg_hi:[1,0,0]
	s_nop 0
	v_pk_fma_f32 v[64:65], v[24:25], v[102:103], v[64:65] neg_lo:[1,0,0] neg_hi:[1,0,0]
	s_nop 0
	v_pk_fma_f32 v[64:65], v[26:27], v[104:105], v[64:65] neg_lo:[1,0,0] neg_hi:[1,0,0]
	s_nop 0
	v_pk_fma_f32 v[64:65], v[28:29], v[106:107], v[64:65] neg_lo:[1,0,0] neg_hi:[1,0,0]
	s_nop 0
	v_pk_fma_f32 v[64:65], v[30:31], v[108:109], v[64:65] neg_lo:[1,0,0] neg_hi:[1,0,0]
	s_nop 0
	v_pk_fma_f32 v[64:65], v[32:33], v[110:111], v[64:65] neg_lo:[1,0,0] neg_hi:[1,0,0]
	s_nop 0
	v_pk_fma_f32 v[64:65], v[34:35], v[132:133], v[64:65] neg_lo:[1,0,0] neg_hi:[1,0,0]
	s_nop 0
	v_pk_fma_f32 v[64:65], v[36:37], v[134:135], v[64:65] neg_lo:[1,0,0] neg_hi:[1,0,0]
	s_nop 0
	v_pk_fma_f32 v[64:65], v[38:39], v[142:143], v[64:65] neg_lo:[1,0,0] neg_hi:[1,0,0]
	s_nop 0
	v_pk_fma_f32 v[64:65], v[40:41], v[144:145], v[64:65] neg_lo:[1,0,0] neg_hi:[1,0,0]
	s_nop 0
	v_pk_fma_f32 v[64:65], v[42:43], v[122:123], v[64:65] neg_lo:[1,0,0] neg_hi:[1,0,0]
	s_nop 0
	v_fma_f32 v45, -v124, v44, v64
	v_add_f32_e32 v45, v65, v45
	v_mov_b32_e32 v64, 0x1b500
	ds_read_b128 v[70:73], v64
	v_mov_b32_e32 v64, 0x1b510
	ds_read_b128 v[74:77], v64
	v_mov_b32_e32 v64, 0x1b520
	ds_read_b128 v[78:81], v64
	v_mov_b32_e32 v64, 0x1b530
	ds_read_b128 v[88:91], v64
	v_mov_b32_e32 v64, 0x1b540
	ds_read_b128 v[96:99], v64
	v_mov_b32_e32 v64, 0x1b550
	ds_read_b128 v[100:103], v64
	v_mov_b32_e32 v64, 0x1b560
	ds_read_b128 v[104:107], v64
	v_mov_b32_e32 v64, 0x1b570
	ds_read_b128 v[108:111], v64
	v_mov_b32_e32 v64, 0x1b580
	ds_read_b128 v[120:123], v64
	v_mov_b32_e32 v64, 0x1b590
	ds_read_b128 v[130:133], v64
	v_mov_b32_e32 v64, 0x1b5a0
	ds_read_b128 v[140:143], v64
	v_mov_b32_e32 v64, 0x1b5b0
	ds_read_b128 v[150:153], v64
	v_or_b32_e32 v64, 0x1c8b4, v67
	ds_read_b32 v64, v64
	ds_read_b32 v65, v66 offset:23040
	s_waitcnt lgkmcnt(0)
	v_mul_f32_e32 v64, v64, v65
	v_pk_fma_f32 v[46:47], v[2:3], v[46:47], v[0:1] neg_lo:[1,0,0] neg_hi:[1,0,0]
	s_nop 0
	v_pk_fma_f32 v[46:47], v[4:5], v[48:49], v[46:47] neg_lo:[1,0,0] neg_hi:[1,0,0]
	s_nop 0
	v_pk_fma_f32 v[46:47], v[6:7], v[52:53], v[46:47] neg_lo:[1,0,0] neg_hi:[1,0,0]
	s_nop 0
	v_pk_fma_f32 v[46:47], v[8:9], v[54:55], v[46:47] neg_lo:[1,0,0] neg_hi:[1,0,0]
	s_nop 0
	v_pk_fma_f32 v[46:47], v[10:11], v[56:57], v[46:47] neg_lo:[1,0,0] neg_hi:[1,0,0]
	s_nop 0
	v_pk_fma_f32 v[46:47], v[12:13], v[58:59], v[46:47] neg_lo:[1,0,0] neg_hi:[1,0,0]
	s_nop 0
	v_pk_fma_f32 v[46:47], v[14:15], v[60:61], v[46:47] neg_lo:[1,0,0] neg_hi:[1,0,0]
	s_nop 0
	v_pk_fma_f32 v[46:47], v[16:17], v[62:63], v[46:47] neg_lo:[1,0,0] neg_hi:[1,0,0]
	s_nop 0
	v_pk_fma_f32 v[46:47], v[18:19], v[84:85], v[46:47] neg_lo:[1,0,0] neg_hi:[1,0,0]
	s_nop 0
	v_pk_fma_f32 v[46:47], v[20:21], v[86:87], v[46:47] neg_lo:[1,0,0] neg_hi:[1,0,0]
	s_nop 0
	v_pk_fma_f32 v[46:47], v[22:23], v[92:93], v[46:47] neg_lo:[1,0,0] neg_hi:[1,0,0]
	s_nop 0
	v_pk_fma_f32 v[46:47], v[24:25], v[94:95], v[46:47] neg_lo:[1,0,0] neg_hi:[1,0,0]
	s_nop 0
	v_pk_fma_f32 v[46:47], v[26:27], v[112:113], v[46:47] neg_lo:[1,0,0] neg_hi:[1,0,0]
	s_nop 0
	v_pk_fma_f32 v[46:47], v[28:29], v[114:115], v[46:47] neg_lo:[1,0,0] neg_hi:[1,0,0]
	s_nop 0
	v_pk_fma_f32 v[46:47], v[30:31], v[116:117], v[46:47] neg_lo:[1,0,0] neg_hi:[1,0,0]
	s_nop 0
	v_pk_fma_f32 v[46:47], v[32:33], v[118:119], v[46:47] neg_lo:[1,0,0] neg_hi:[1,0,0]
	s_nop 0
	v_pk_fma_f32 v[46:47], v[34:35], v[136:137], v[46:47] neg_lo:[1,0,0] neg_hi:[1,0,0]
	s_nop 0
	v_pk_fma_f32 v[46:47], v[36:37], v[138:139], v[46:47] neg_lo:[1,0,0] neg_hi:[1,0,0]
	s_nop 0
	v_pk_fma_f32 v[46:47], v[38:39], v[146:147], v[46:47] neg_lo:[1,0,0] neg_hi:[1,0,0]
	s_nop 0
	v_pk_fma_f32 v[46:47], v[40:41], v[148:149], v[46:47] neg_lo:[1,0,0] neg_hi:[1,0,0]
	s_nop 0
	v_pk_fma_f32 v[46:47], v[42:43], v[126:127], v[46:47] neg_lo:[1,0,0] neg_hi:[1,0,0]
	s_nop 0
	v_pk_fma_f32 v[46:47], v[128:129], v[44:45], v[46:47] neg_lo:[1,0,0] neg_hi:[1,0,0]
	s_nop 0
	v_pk_add_f32 v[46:47], v[46:47], v[46:47] op_sel:[0,1] op_sel_hi:[1,0]
	v_mov_b32_e32 v0, 0x1b600
	ds_read_b128 v[52:55], v0
	v_mov_b32_e32 v0, 0x1b610
	ds_read_b128 v[56:59], v0
	v_mov_b32_e32 v0, 0x1b620
	ds_read_b128 v[60:63], v0
	v_mov_b32_e32 v0, 0x1b630
	ds_read_b128 v[84:87], v0
	v_mov_b32_e32 v0, 0x1b640
	ds_read_b128 v[92:95], v0
	v_mov_b32_e32 v0, 0x1b650
	ds_read_b128 v[112:115], v0
	v_mov_b32_e32 v0, 0x1b660
	ds_read_b128 v[116:119], v0
	v_mov_b32_e32 v0, 0x1b670
	ds_read_b128 v[124:127], v0
	v_mov_b32_e32 v0, 0x1b680
	ds_read_b128 v[134:137], v0
	v_mov_b32_e32 v0, 0x1b690
	ds_read_b128 v[144:147], v0
	v_or_b32_e32 v0, 0x1c8b8, v67
	v_mov_b32_e32 v48, 0x1b6a0
	ds_read_b32 v0, v0
	ds_read_b32 v47, v66 offset:23552
	ds_read_b128 v[152:155], v48
	v_mov_b32_e32 v48, 0x1b6b0
	ds_read_b64 v[48:49], v48
	s_waitcnt lgkmcnt(0)
; DI void gdn_prep_item(const Params& P, int l, int n, int hh, char* smem) {
;     ...
;     for (int i = 1; i < 64; ++i) {
;       f32x4 (&CUR)[16] = (i & 1) ? LA : LB; f32x4 (&NXT)[16] = (i & 1) ? LB : LA;
;       if (i + 1 < 64) {
; #pragma unroll
;         for (int c = 0; c < (i + 4) / 4; ++c) NXT[c] = *(const f32x4*)(Lm + (i + 1) * 64 + 4 * c);
;         rh[(i + 1) & 1] = sp[i + 1] * rp[(i + 1) * 128];
;       }
;       __builtin_amdgcn_sched_barrier(0);
;       f32x2 acc = {rh[i & 1], 0.f};
; #pragma unroll
;       for (int p = 0; p < i / 2; ++p) { const f32x2 lp = (p & 1) ? (f32x2){CUR[p >> 1].z, CUR[p >> 1].w} : (f32x2){CUR[p >> 1].x, CUR[p >> 1].y}; acc = acc - lp * xx[p]; }
;       if (i & 1) { const int j = i - 1; const float lj = ((j & 3) == 0) ? CUR[j >> 2].x : CUR[j >> 2].z; acc.x = fmaf(-lj, xx[j >> 1].x, acc.x); }
;       const float xi = acc.x + acc.y;
;       if (i & 1) xx[i >> 1].y = xi; else xx[i >> 1].x = xi;
;       __builtin_amdgcn_sched_barrier(0);
;     }
	v_mul_f32_e32 v0, v0, v47
	v_mov_b32_e32 v65, v1
	v_pk_fma_f32 v[64:65], v[2:3], v[70:71], v[64:65] neg_lo:[1,0,0] neg_hi:[1,0,0]
	s_nop 0
	v_pk_fma_f32 v[64:65], v[4:5], v[72:73], v[64:65] neg_lo:[1,0,0] neg_hi:[1,0,0]
	s_nop 0
	v_pk_fma_f32 v[64:65], v[6:7], v[74:75], v[64:65] neg_lo:[1,0,0] neg_hi:[1,0,0]
	s_nop 0
	v_pk_fma_f32 v[64:65], v[8:9], v[76:77], v[64:65] neg_lo:[1,0,0] neg_hi:[1,0,0]
	s_nop 0
	v_pk_fma_f32 v[64:65], v[10:11], v[78:79], v[64:65] neg_lo:[1,0,0] neg_hi:[1,0,0]
	s_nop 0
	v_pk_fma_f32 v[64:65], v[12:13], v[80:81], v[64:65] neg_lo:[1,0,0] neg_hi:[1,0,0]
	s_nop 0
	v_pk_fma_f32 v[64:65], v[14:15], v[88:89], v[64:65] neg_lo:[1,0,0] neg_hi:[1,0,0]
	s_nop 0
	v_pk_fma_f32 v[64:65], v[16:17], v[90:91], v[64:65] neg_lo:[1,0,0] neg_hi:[1,0,0]
	s_nop 0
	v_pk_fma_f32 v[64:65], v[18:19], v[96:97], v[64:65] neg_lo:[1,0,0] neg_hi:[1,0,0]
	s_nop 0
	v_pk_fma_f32 v[64:65], v[20:21], v[98:99], v[64:65] neg_lo:[1,0,0] neg_hi:[1,0,0]
	s_nop 0
	v_pk_fma_f32 v[64:65], v[22:23], v[100:101], v[64:65] neg_lo:[1,0,0] neg_hi:[1,0,0]
	s_nop 0
	v_pk_fma_f32 v[64:65], v[24:25], v[102:103], v[64:65] neg_lo:[1,0,0] neg_hi:[1,0,0]
	s_nop 0
	v_pk_fma_f32 v[64:65], v[26:27], v[104:105], v[64:65] neg_lo:[1,0,0] neg_hi:[1,0,0]
	s_nop 0
	v_pk_fma_f32 v[64:65], v[28:29], v[106:107], v[64:65] neg_lo:[1,0,0] neg_hi:[1,0,0]
	s_nop 0
	v_pk_fma_f32 v[64:65], v[30:31], v[108:109], v[64:65] neg_lo:[1,0,0] neg_hi:[1,0,0]
	s_nop 0
	v_pk_fma_f32 v[64:65], v[32:33], v[110:111], v[64:65] neg_lo:[1,0,0] neg_hi:[1,0,0]
	s_nop 0
	v_pk_fma_f32 v[64:65], v[34:35], v[120:121], v[64:65] neg_lo:[1,0,0] neg_hi:[1,0,0]
	s_nop 0
	v_pk_fma_f32 v[64:65], v[36:37], v[122:123], v[64:65] neg_lo:[1,0,0] neg_hi:[1,0,0]
	s_nop 0
	v_pk_fma_f32 v[64:65], v[38:39], v[130:131], v[64:65] neg_lo:[1,0,0] neg_hi:[1,0,0]
	s_nop 0
	v_pk_fma_f32 v[64:65], v[40:41], v[132:133], v[64:65] neg_lo:[1,0,0] neg_hi:[1,0,0]
	s_nop 0
	v_pk_fma_f32 v[64:65], v[42:43], v[140:141], v[64:65] neg_lo:[1,0,0] neg_hi:[1,0,0]
	s_nop 0
	v_pk_fma_f32 v[64:65], v[44:45], v[142:143], v[64:65] neg_lo:[1,0,0] neg_hi:[1,0,0]
	s_nop 0
	v_fma_f32 v47, -v150, v46, v64
	v_add_f32_e32 v47, v65, v47
	v_mov_b32_e32 v64, 0x1b700
	ds_read_b128 v[70:73], v64
	v_mov_b32_e32 v64, 0x1b710
	ds_read_b128 v[74:77], v64
	v_mov_b32_e32 v64, 0x1b720
	ds_read_b128 v[78:81], v64
	v_mov_b32_e32 v64, 0x1b730
	ds_read_b128 v[88:91], v64
	v_mov_b32_e32 v64, 0x1b740
	ds_read_b128 v[96:99], v64
	v_mov_b32_e32 v64, 0x1b750
	ds_read_b128 v[100:103], v64
	v_mov_b32_e32 v64, 0x1b760
	ds_read_b128 v[104:107], v64
	v_mov_b32_e32 v64, 0x1b770
	ds_read_b128 v[108:111], v64
	v_mov_b32_e32 v64, 0x1b780
	ds_read_b128 v[120:123], v64
	v_mov_b32_e32 v64, 0x1b790
	ds_read_b128 v[128:131], v64
	v_or_b32_e32 v64, 0x1c8bc, v67
	ds_read_b32 v64, v64
	ds_read_b32 v65, v66 offset:24064
	v_mov_b32_e32 v83, 0x1b7a0
	ds_read_b128 v[138:141], v83
	v_mov_b32_e32 v83, 0x1b7b0
	ds_read_b128 v[148:151], v83
	s_waitcnt lgkmcnt(0)
	v_mul_f32_e32 v64, v64, v65
	v_pk_fma_f32 v[52:53], v[2:3], v[52:53], v[0:1] neg_lo:[1,0,0] neg_hi:[1,0,0]
	s_nop 0
	v_pk_fma_f32 v[52:53], v[4:5], v[54:55], v[52:53] neg_lo:[1,0,0] neg_hi:[1,0,0]
	s_nop 0
	v_pk_fma_f32 v[52:53], v[6:7], v[56:57], v[52:53] neg_lo:[1,0,0] neg_hi:[1,0,0]
	s_nop 0
	v_pk_fma_f32 v[52:53], v[8:9], v[58:59], v[52:53] neg_lo:[1,0,0] neg_hi:[1,0,0]
	s_nop 0
	v_pk_fma_f32 v[52:53], v[10:11], v[60:61], v[52:53] neg_lo:[1,0,0] neg_hi:[1,0,0]
	s_nop 0
	v_pk_fma_f32 v[52:53], v[12:13], v[62:63], v[52:53] neg_lo:[1,0,0] neg_hi:[1,0,0]
	s_nop 0
	v_pk_fma_f32 v[52:53], v[14:15], v[84:85], v[52:53] neg_lo:[1,0,0] neg_hi:[1,0,0]
	s_nop 0
	v_pk_fma_f32 v[52:53], v[16:17], v[86:87], v[52:53] neg_lo:[1,0,0] neg_hi:[1,0,0]
	s_nop 0
	v_pk_fma_f32 v[52:53], v[18:19], v[92:93], v[52:53] neg_lo:[1,0,0] neg_hi:[1,0,0]
	s_nop 0
	v_pk_fma_f32 v[52:53], v[20:21], v[94:95], v[52:53] neg_lo:[1,0,0] neg_hi:[1,0,0]
	s_nop 0
	v_pk_fma_f32 v[52:53], v[22:23], v[112:113], v[52:53] neg_lo:[1,0,0] neg_hi:[1,0,0]
	s_nop 0
	v_pk_fma_f32 v[52:53], v[24:25], v[114:115], v[52:53] neg_lo:[1,0,0] neg_hi:[1,0,0]
	s_nop 0
	v_pk_fma_f32 v[52:53], v[26:27], v[116:117], v[52:53] neg_lo:[1,0,0] neg_hi:[1,0,0]
	s_nop 0
	v_pk_fma_f32 v[52:53], v[28:29], v[118:119], v[52:53] neg_lo:[1,0,0] neg_hi:[1,0,0]
	s_nop 0
	v_pk_fma_f32 v[52:53], v[30:31], v[124:125], v[52:53] neg_lo:[1,0,0] neg_hi:[1,0,0]
	s_nop 0
	v_pk_fma_f32 v[52:53], v[32:33], v[126:127], v[52:53] neg_lo:[1,0,0] neg_hi:[1,0,0]
	s_nop 0
	v_pk_fma_f32 v[52:53], v[34:35], v[134:135], v[52:53] neg_lo:[1,0,0] neg_hi:[1,0,0]
	s_nop 0
	v_pk_fma_f32 v[52:53], v[36:37], v[136:137], v[52:53] neg_lo:[1,0,0] neg_hi:[1,0,0]
	s_nop 0
	v_pk_fma_f32 v[52:53], v[38:39], v[144:145], v[52:53] neg_lo:[1,0,0] neg_hi:[1,0,0]
	s_nop 0
	v_pk_fma_f32 v[52:53], v[40:41], v[146:147], v[52:53] neg_lo:[1,0,0] neg_hi:[1,0,0]
	s_nop 0
	v_pk_fma_f32 v[52:53], v[42:43], v[152:153], v[52:53] neg_lo:[1,0,0] neg_hi:[1,0,0]
	s_nop 0
	v_pk_fma_f32 v[52:53], v[44:45], v[154:155], v[52:53] neg_lo:[1,0,0] neg_hi:[1,0,0]
	s_nop 0
	v_pk_fma_f32 v[48:49], v[48:49], v[46:47], v[52:53] neg_lo:[1,0,0] neg_hi:[1,0,0]
	s_nop 0
	v_pk_add_f32 v[48:49], v[48:49], v[48:49] op_sel:[0,1] op_sel_hi:[1,0]
	v_mov_b32_e32 v0, 0x1b800
	ds_read_b128 v[52:55], v0
	v_mov_b32_e32 v0, 0x1b810
	ds_read_b128 v[56:59], v0
	v_mov_b32_e32 v0, 0x1b820
	ds_read_b128 v[60:63], v0
	v_mov_b32_e32 v0, 0x1b830
	ds_read_b128 v[84:87], v0
	v_mov_b32_e32 v0, 0x1b840
	ds_read_b128 v[92:95], v0
	v_mov_b32_e32 v0, 0x1b850
	ds_read_b128 v[112:115], v0
	v_mov_b32_e32 v0, 0x1b860
	ds_read_b128 v[116:119], v0
	v_mov_b32_e32 v0, 0x1b870
	ds_read_b128 v[124:127], v0
	v_mov_b32_e32 v0, 0x1b880
	ds_read_b128 v[132:135], v0
	v_mov_b32_e32 v0, 0x1b890
	ds_read_b128 v[142:145], v0
	v_or_b32_e32 v0, 0x1c8c0, v67
	v_mov_b32_e32 v65, 0x1b8a0
	ds_read_b32 v0, v0
	ds_read_b32 v49, v66 offset:24576
	ds_read_b128 v[152:155], v65
	v_mov_b32_e32 v65, 0x1b8b0
	ds_read_b128 v[156:159], v65
	s_waitcnt lgkmcnt(0)
; DI void gdn_prep_item(const Params& P, int l, int n, int hh, char* smem) {
;     ...
;     for (int i = 1; i < 64; ++i) {
;       f32x4 (&CUR)[16] = (i & 1) ? LA : LB; f32x4 (&NXT)[16] = (i & 1) ? LB : LA;
;       if (i + 1 < 64) {
; #pragma unroll
;         for (int c = 0; c < (i + 4) / 4; ++c) NXT[c] = *(const f32x4*)(Lm + (i + 1) * 64 + 4 * c);
;         rh[(i + 1) & 1] = sp[i + 1] * rp[(i + 1) * 128];
;       }
;       __builtin_amdgcn_sched_barrier(0);
;       f32x2 acc = {rh[i & 1], 0.f};
; #pragma unroll
;       for (int p = 0; p < i / 2; ++p) { const f32x2 lp = (p & 1) ? (f32x2){CUR[p >> 1].z, CUR[p >> 1].w} : (f32x2){CUR[p >> 1].x, CUR[p >> 1].y}; acc = acc - lp * xx[p]; }
;       if (i & 1) { const int j = i - 1; const float lj = ((j & 3) == 0) ? CUR[j >> 2].x : CUR[j >> 2].z; acc.x = fmaf(-lj, xx[j >> 1].x, acc.x); }
;       const float xi = acc.x + acc.y;
;       if (i & 1) xx[i >> 1].y = xi; else xx[i >> 1].x = xi;
;       __builtin_amdgcn_sched_barrier(0);
;     }
	v_mul_f32_e32 v0, v0, v49
	v_mov_b32_e32 v65, v1
	v_pk_fma_f32 v[64:65], v[2:3], v[70:71], v[64:65] neg_lo:[1,0,0] neg_hi:[1,0,0]
	s_nop 0
	v_pk_fma_f32 v[64:65], v[4:5], v[72:73], v[64:65] neg_lo:[1,0,0] neg_hi:[1,0,0]
	s_nop 0
	v_pk_fma_f32 v[64:65], v[6:7], v[74:75], v[64:65] neg_lo:[1,0,0] neg_hi:[1,0,0]
	s_nop 0
	v_pk_fma_f32 v[64:65], v[8:9], v[76:77], v[64:65] neg_lo:[1,0,0] neg_hi:[1,0,0]
	s_nop 0
	v_pk_fma_f32 v[64:65], v[10:11], v[78:79], v[64:65] neg_lo:[1,0,0] neg_hi:[1,0,0]
	s_nop 0
	v_pk_fma_f32 v[64:65], v[12:13], v[80:81], v[64:65] neg_lo:[1,0,0] neg_hi:[1,0,0]
	s_nop 0
	v_pk_fma_f32 v[64:65], v[14:15], v[88:89], v[64:65] neg_lo:[1,0,0] neg_hi:[1,0,0]
	s_nop 0
	v_pk_fma_f32 v[64:65], v[16:17], v[90:91], v[64:65] neg_lo:[1,0,0] neg_hi:[1,0,0]
	s_nop 0
	v_pk_fma_f32 v[64:65], v[18:19], v[96:97], v[64:65] neg_lo:[1,0,0] neg_hi:[1,0,0]
	s_nop 0
	v_pk_fma_f32 v[64:65], v[20:21], v[98:99], v[64:65] neg_lo:[1,0,0] neg_hi:[1,0,0]
	s_nop 0
	v_pk_fma_f32 v[64:65], v[22:23], v[100:101], v[64:65] neg_lo:[1,0,0] neg_hi:[1,0,0]
	s_nop 0
	v_pk_fma_f32 v[64:65], v[24:25], v[102:103], v[64:65] neg_lo:[1,0,0] neg_hi:[1,0,0]
	s_nop 0
	v_pk_fma_f32 v[64:65], v[26:27], v[104:105], v[64:65] neg_lo:[1,0,0] neg_hi:[1,0,0]
	s_nop 0
	v_pk_fma_f32 v[64:65], v[28:29], v[106:107], v[64:65] neg_lo:[1,0,0] neg_hi:[1,0,0]
	s_nop 0
	v_pk_fma_f32 v[64:65], v[30:31], v[108:109], v[64:65] neg_lo:[1,0,0] neg_hi:[1,0,0]
	s_nop 0
	v_pk_fma_f32 v[64:65], v[32:33], v[110:111], v[64:65] neg_lo:[1,0,0] neg_hi:[1,0,0]
	s_nop 0
	v_pk_fma_f32 v[64:65], v[34:35], v[120:121], v[64:65] neg_lo:[1,0,0] neg_hi:[1,0,0]
	s_nop 0
	v_pk_fma_f32 v[64:65], v[36:37], v[122:123], v[64:65] neg_lo:[1,0,0] neg_hi:[1,0,0]
	s_nop 0
	v_pk_fma_f32 v[64:65], v[38:39], v[128:129], v[64:65] neg_lo:[1,0,0] neg_hi:[1,0,0]
	s_nop 0
	v_pk_fma_f32 v[64:65], v[40:41], v[130:131], v[64:65] neg_lo:[1,0,0] neg_hi:[1,0,0]
	s_nop 0
	v_pk_fma_f32 v[64:65], v[42:43], v[138:139], v[64:65] neg_lo:[1,0,0] neg_hi:[1,0,0]
	s_nop 0
	v_pk_fma_f32 v[64:65], v[44:45], v[140:141], v[64:65] neg_lo:[1,0,0] neg_hi:[1,0,0]
	s_nop 0
	v_pk_fma_f32 v[64:65], v[46:47], v[148:149], v[64:65] neg_lo:[1,0,0] neg_hi:[1,0,0]
	s_nop 0
	v_fma_f32 v49, -v150, v48, v64
	v_add_f32_e32 v49, v65, v49
	v_mov_b32_e32 v64, 0x1b900
	ds_read_b128 v[70:73], v64
	v_mov_b32_e32 v64, 0x1b910
	ds_read_b128 v[74:77], v64
	v_mov_b32_e32 v64, 0x1b920
	ds_read_b128 v[78:81], v64
	v_mov_b32_e32 v64, 0x1b930
	ds_read_b128 v[88:91], v64
	v_mov_b32_e32 v64, 0x1b940
	ds_read_b128 v[96:99], v64
	v_mov_b32_e32 v64, 0x1b950
	ds_read_b128 v[100:103], v64
	v_mov_b32_e32 v64, 0x1b960
	ds_read_b128 v[104:107], v64
	v_mov_b32_e32 v64, 0x1b970
	ds_read_b128 v[108:111], v64
	v_mov_b32_e32 v64, 0x1b980
	ds_read_b128 v[120:123], v64
	v_mov_b32_e32 v64, 0x1b990
	ds_read_b128 v[128:131], v64
	v_or_b32_e32 v64, 0x1c8c4, v67
	v_mov_b32_e32 v65, 0x1b9c0
	ds_read_b128 v[136:139], v65
	ds_read_b32 v64, v64
	ds_read_b32 v65, v66 offset:25088
	v_mov_b32_e32 v83, 0x1b9a0
	s_waitcnt lgkmcnt(0)
	ds_read_b128 v[138:141], v83
	v_mov_b32_e32 v83, 0x1b9b0
	ds_read_b128 v[146:149], v83
	v_mul_f32_e32 v160, v64, v65
	v_pk_fma_f32 v[52:53], v[2:3], v[52:53], v[0:1] neg_lo:[1,0,0] neg_hi:[1,0,0]
	s_nop 0
	v_pk_fma_f32 v[52:53], v[4:5], v[54:55], v[52:53] neg_lo:[1,0,0] neg_hi:[1,0,0]
	s_nop 0
	v_pk_fma_f32 v[52:53], v[6:7], v[56:57], v[52:53] neg_lo:[1,0,0] neg_hi:[1,0,0]
	s_nop 0
	v_pk_fma_f32 v[52:53], v[8:9], v[58:59], v[52:53] neg_lo:[1,0,0] neg_hi:[1,0,0]
	s_nop 0
	v_pk_fma_f32 v[52:53], v[10:11], v[60:61], v[52:53] neg_lo:[1,0,0] neg_hi:[1,0,0]
	s_nop 0
	v_pk_fma_f32 v[52:53], v[12:13], v[62:63], v[52:53] neg_lo:[1,0,0] neg_hi:[1,0,0]
	s_nop 0
	v_pk_fma_f32 v[52:53], v[14:15], v[84:85], v[52:53] neg_lo:[1,0,0] neg_hi:[1,0,0]
	s_nop 0
	v_pk_fma_f32 v[52:53], v[16:17], v[86:87], v[52:53] neg_lo:[1,0,0] neg_hi:[1,0,0]
	s_nop 0
	v_pk_fma_f32 v[52:53], v[18:19], v[92:93], v[52:53] neg_lo:[1,0,0] neg_hi:[1,0,0]
	s_nop 0
	v_pk_fma_f32 v[52:53], v[20:21], v[94:95], v[52:53] neg_lo:[1,0,0] neg_hi:[1,0,0]
	s_nop 0
	v_pk_fma_f32 v[52:53], v[22:23], v[112:113], v[52:53] neg_lo:[1,0,0] neg_hi:[1,0,0]
	s_nop 0
	v_pk_fma_f32 v[52:53], v[24:25], v[114:115], v[52:53] neg_lo:[1,0,0] neg_hi:[1,0,0]
	s_nop 0
	v_pk_fma_f32 v[52:53], v[26:27], v[116:117], v[52:53] neg_lo:[1,0,0] neg_hi:[1,0,0]
	s_nop 0
	v_pk_fma_f32 v[52:53], v[28:29], v[118:119], v[52:53] neg_lo:[1,0,0] neg_hi:[1,0,0]
	s_nop 0
	v_pk_fma_f32 v[52:53], v[30:31], v[124:125], v[52:53] neg_lo:[1,0,0] neg_hi:[1,0,0]
	s_nop 0
	v_pk_fma_f32 v[52:53], v[32:33], v[126:127], v[52:53] neg_lo:[1,0,0] neg_hi:[1,0,0]
	s_nop 0
	v_pk_fma_f32 v[52:53], v[34:35], v[132:133], v[52:53] neg_lo:[1,0,0] neg_hi:[1,0,0]
	s_nop 0
	v_pk_fma_f32 v[52:53], v[36:37], v[134:135], v[52:53] neg_lo:[1,0,0] neg_hi:[1,0,0]
	s_nop 0
	v_pk_fma_f32 v[52:53], v[38:39], v[142:143], v[52:53] neg_lo:[1,0,0] neg_hi:[1,0,0]
	s_nop 0
	v_pk_fma_f32 v[52:53], v[40:41], v[144:145], v[52:53] neg_lo:[1,0,0] neg_hi:[1,0,0]
	s_nop 0
	v_pk_fma_f32 v[52:53], v[42:43], v[152:153], v[52:53] neg_lo:[1,0,0] neg_hi:[1,0,0]
	s_nop 0
	v_pk_fma_f32 v[52:53], v[44:45], v[154:155], v[52:53] neg_lo:[1,0,0] neg_hi:[1,0,0]
	s_nop 0
	v_pk_fma_f32 v[52:53], v[46:47], v[156:157], v[52:53] neg_lo:[1,0,0] neg_hi:[1,0,0]
	s_nop 0
	v_pk_fma_f32 v[52:53], v[158:159], v[48:49], v[52:53] neg_lo:[1,0,0] neg_hi:[1,0,0]
	s_nop 0
	v_pk_add_f32 v[52:53], v[52:53], v[52:53] op_sel:[0,1] op_sel_hi:[1,0]
	v_mov_b32_e32 v0, 0x1ba00
	ds_read_b128 v[54:57], v0
	v_mov_b32_e32 v0, 0x1ba10
	ds_read_b128 v[58:61], v0
	v_mov_b32_e32 v0, 0x1ba20
	ds_read_b128 v[62:65], v0
	v_mov_b32_e32 v0, 0x1ba30
	ds_read_b128 v[84:87], v0
	v_mov_b32_e32 v0, 0x1ba40
	ds_read_b128 v[92:95], v0
	v_mov_b32_e32 v0, 0x1ba50
	ds_read_b128 v[112:115], v0
	v_mov_b32_e32 v0, 0x1ba60
	ds_read_b128 v[116:119], v0
	v_mov_b32_e32 v0, 0x1ba70
	ds_read_b128 v[124:127], v0
	v_mov_b32_e32 v0, 0x1ba80
	ds_read_b128 v[132:135], v0
	v_mov_b32_e32 v0, 0x1ba90
	ds_read_b128 v[142:145], v0
	v_or_b32_e32 v0, 0x1c8c8, v67
	v_mov_b32_e32 v53, 0x1bac0
	v_mov_b32_e32 v83, 0x1baa0
	ds_read_b64 v[162:163], v53
	ds_read_b32 v0, v0
	ds_read_b32 v53, v66 offset:25600
	ds_read_b128 v[150:153], v83
	v_mov_b32_e32 v83, 0x1bab0
	ds_read_b128 v[154:157], v83
	s_waitcnt lgkmcnt(0)
; DI void gdn_prep_item(const Params& P, int l, int n, int hh, char* smem) {
;     ...
;     for (int i = 1; i < 64; ++i) {
;       f32x4 (&CUR)[16] = (i & 1) ? LA : LB; f32x4 (&NXT)[16] = (i & 1) ? LB : LA;
;       if (i + 1 < 64) {
; #pragma unroll
;         for (int c = 0; c < (i + 4) / 4; ++c) NXT[c] = *(const f32x4*)(Lm + (i + 1) * 64 + 4 * c);
;         rh[(i + 1) & 1] = sp[i + 1] * rp[(i + 1) * 128];
;       }
;       __builtin_amdgcn_sched_barrier(0);
;       f32x2 acc = {rh[i & 1], 0.f};
; #pragma unroll
;       for (int p = 0; p < i / 2; ++p) { const f32x2 lp = (p & 1) ? (f32x2){CUR[p >> 1].z, CUR[p >> 1].w} : (f32x2){CUR[p >> 1].x, CUR[p >> 1].y}; acc = acc - lp * xx[p]; }
;       if (i & 1) { const int j = i - 1; const float lj = ((j & 3) == 0) ? CUR[j >> 2].x : CUR[j >> 2].z; acc.x = fmaf(-lj, xx[j >> 1].x, acc.x); }
;       const float xi = acc.x + acc.y;
;       if (i & 1) xx[i >> 1].y = xi; else xx[i >> 1].x = xi;
;       __builtin_amdgcn_sched_barrier(0);
;     }
	v_mul_f32_e32 v0, v0, v53
	v_mov_b32_e32 v161, v1
	v_pk_fma_f32 v[70:71], v[2:3], v[70:71], v[160:161] neg_lo:[1,0,0] neg_hi:[1,0,0]
	s_nop 0
	v_pk_fma_f32 v[70:71], v[4:5], v[72:73], v[70:71] neg_lo:[1,0,0] neg_hi:[1,0,0]
	s_nop 0
	v_pk_fma_f32 v[70:71], v[6:7], v[74:75], v[70:71] neg_lo:[1,0,0] neg_hi:[1,0,0]
	s_nop 0
	v_pk_fma_f32 v[70:71], v[8:9], v[76:77], v[70:71] neg_lo:[1,0,0] neg_hi:[1,0,0]
	s_nop 0
	v_pk_fma_f32 v[70:71], v[10:11], v[78:79], v[70:71] neg_lo:[1,0,0] neg_hi:[1,0,0]
	s_nop 0
	v_pk_fma_f32 v[70:71], v[12:13], v[80:81], v[70:71] neg_lo:[1,0,0] neg_hi:[1,0,0]
	s_nop 0
	v_pk_fma_f32 v[70:71], v[14:15], v[88:89], v[70:71] neg_lo:[1,0,0] neg_hi:[1,0,0]
	s_nop 0
	v_pk_fma_f32 v[70:71], v[16:17], v[90:91], v[70:71] neg_lo:[1,0,0] neg_hi:[1,0,0]
	s_nop 0
	v_pk_fma_f32 v[70:71], v[18:19], v[96:97], v[70:71] neg_lo:[1,0,0] neg_hi:[1,0,0]
	s_nop 0
	v_pk_fma_f32 v[70:71], v[20:21], v[98:99], v[70:71] neg_lo:[1,0,0] neg_hi:[1,0,0]
	s_nop 0
	v_pk_fma_f32 v[70:71], v[22:23], v[100:101], v[70:71] neg_lo:[1,0,0] neg_hi:[1,0,0]
	s_nop 0
	v_pk_fma_f32 v[70:71], v[24:25], v[102:103], v[70:71] neg_lo:[1,0,0] neg_hi:[1,0,0]
	s_nop 0
	v_pk_fma_f32 v[70:71], v[26:27], v[104:105], v[70:71] neg_lo:[1,0,0] neg_hi:[1,0,0]
	s_nop 0
	v_pk_fma_f32 v[70:71], v[28:29], v[106:107], v[70:71] neg_lo:[1,0,0] neg_hi:[1,0,0]
	s_nop 0
	v_pk_fma_f32 v[70:71], v[30:31], v[108:109], v[70:71] neg_lo:[1,0,0] neg_hi:[1,0,0]
	s_nop 0
	v_pk_fma_f32 v[70:71], v[32:33], v[110:111], v[70:71] neg_lo:[1,0,0] neg_hi:[1,0,0]
	s_nop 0
	v_pk_fma_f32 v[70:71], v[34:35], v[120:121], v[70:71] neg_lo:[1,0,0] neg_hi:[1,0,0]
	s_nop 0
	v_pk_fma_f32 v[70:71], v[36:37], v[122:123], v[70:71] neg_lo:[1,0,0] neg_hi:[1,0,0]
	s_nop 0
	v_pk_fma_f32 v[70:71], v[38:39], v[128:129], v[70:71] neg_lo:[1,0,0] neg_hi:[1,0,0]
	s_nop 0
	v_pk_fma_f32 v[70:71], v[40:41], v[130:131], v[70:71] neg_lo:[1,0,0] neg_hi:[1,0,0]
	s_nop 0
	v_pk_fma_f32 v[70:71], v[42:43], v[138:139], v[70:71] neg_lo:[1,0,0] neg_hi:[1,0,0]
	s_nop 0
	v_pk_fma_f32 v[70:71], v[44:45], v[140:141], v[70:71] neg_lo:[1,0,0] neg_hi:[1,0,0]
	s_nop 0
	v_pk_fma_f32 v[70:71], v[46:47], v[146:147], v[70:71] neg_lo:[1,0,0] neg_hi:[1,0,0]
	s_nop 0
	v_pk_fma_f32 v[70:71], v[48:49], v[148:149], v[70:71] neg_lo:[1,0,0] neg_hi:[1,0,0]
	s_nop 0
	v_fma_f32 v53, -v136, v52, v70
	v_add_f32_e32 v53, v71, v53
	v_mov_b32_e32 v78, 0x1bb20
	v_mov_b32_e32 v83, 0x1bb30
	ds_read_b128 v[78:81], v78
	ds_read_b128 v[88:91], v83
	v_mov_b32_e32 v83, 0x1bb40
	ds_read_b128 v[96:99], v83
	v_mov_b32_e32 v83, 0x1bb50
	ds_read_b128 v[100:103], v83
	v_mov_b32_e32 v83, 0x1bb60
	ds_read_b128 v[104:107], v83
	v_mov_b32_e32 v83, 0x1bb70
	ds_read_b128 v[108:111], v83
	v_mov_b32_e32 v83, 0x1bb80
	ds_read_b128 v[120:123], v83
	v_mov_b32_e32 v83, 0x1bb90
	v_mov_b32_e32 v70, 0x1bb00
	v_mov_b32_e32 v74, 0x1bb10
	ds_read_b128 v[128:131], v83
	v_or_b32_e32 v83, 0x1c8cc, v67
	v_mov_b32_e32 v136, 0x1bbc0
	ds_read_b128 v[70:73], v70
	ds_read_b128 v[74:77], v74
	ds_read_b128 v[136:139], v136
	ds_read_b32 v83, v83
	v_mov_b32_e32 v140, 0x1bba0
	s_waitcnt lgkmcnt(0)
	ds_read_b32 v139, v66 offset:26112
	ds_read_b128 v[146:149], v140
	v_mov_b32_e32 v140, 0x1bbb0
	ds_read_b128 v[158:161], v140
	s_waitcnt lgkmcnt(0)
	v_mul_f32_e32 v170, v83, v139
	v_pk_fma_f32 v[54:55], v[2:3], v[54:55], v[0:1] neg_lo:[1,0,0] neg_hi:[1,0,0]
	s_nop 0
	v_pk_fma_f32 v[54:55], v[4:5], v[56:57], v[54:55] neg_lo:[1,0,0] neg_hi:[1,0,0]
	s_nop 0
	v_pk_fma_f32 v[54:55], v[6:7], v[58:59], v[54:55] neg_lo:[1,0,0] neg_hi:[1,0,0]
	s_nop 0
	v_pk_fma_f32 v[54:55], v[8:9], v[60:61], v[54:55] neg_lo:[1,0,0] neg_hi:[1,0,0]
	s_nop 0
	v_pk_fma_f32 v[54:55], v[10:11], v[62:63], v[54:55] neg_lo:[1,0,0] neg_hi:[1,0,0]
	s_nop 0
	v_pk_fma_f32 v[54:55], v[12:13], v[64:65], v[54:55] neg_lo:[1,0,0] neg_hi:[1,0,0]
	s_nop 0
	v_pk_fma_f32 v[54:55], v[14:15], v[84:85], v[54:55] neg_lo:[1,0,0] neg_hi:[1,0,0]
	s_nop 0
	v_pk_fma_f32 v[54:55], v[16:17], v[86:87], v[54:55] neg_lo:[1,0,0] neg_hi:[1,0,0]
	s_nop 0
	v_pk_fma_f32 v[54:55], v[18:19], v[92:93], v[54:55] neg_lo:[1,0,0] neg_hi:[1,0,0]
	s_nop 0
	v_pk_fma_f32 v[54:55], v[20:21], v[94:95], v[54:55] neg_lo:[1,0,0] neg_hi:[1,0,0]
	s_nop 0
	v_pk_fma_f32 v[54:55], v[22:23], v[112:113], v[54:55] neg_lo:[1,0,0] neg_hi:[1,0,0]
	s_nop 0
	v_pk_fma_f32 v[54:55], v[24:25], v[114:115], v[54:55] neg_lo:[1,0,0] neg_hi:[1,0,0]
	s_nop 0
	v_pk_fma_f32 v[54:55], v[26:27], v[116:117], v[54:55] neg_lo:[1,0,0] neg_hi:[1,0,0]
	s_nop 0
	v_pk_fma_f32 v[54:55], v[28:29], v[118:119], v[54:55] neg_lo:[1,0,0] neg_hi:[1,0,0]
	s_nop 0
	v_pk_fma_f32 v[54:55], v[30:31], v[124:125], v[54:55] neg_lo:[1,0,0] neg_hi:[1,0,0]
	s_nop 0
	v_pk_fma_f32 v[54:55], v[32:33], v[126:127], v[54:55] neg_lo:[1,0,0] neg_hi:[1,0,0]
	s_nop 0
	v_pk_fma_f32 v[54:55], v[34:35], v[132:133], v[54:55] neg_lo:[1,0,0] neg_hi:[1,0,0]
	s_nop 0
	v_pk_fma_f32 v[54:55], v[36:37], v[134:135], v[54:55] neg_lo:[1,0,0] neg_hi:[1,0,0]
	s_nop 0
	v_pk_fma_f32 v[54:55], v[38:39], v[142:143], v[54:55] neg_lo:[1,0,0] neg_hi:[1,0,0]
	s_nop 0
	v_pk_fma_f32 v[54:55], v[40:41], v[144:145], v[54:55] neg_lo:[1,0,0] neg_hi:[1,0,0]
	s_nop 0
	v_pk_fma_f32 v[54:55], v[42:43], v[150:151], v[54:55] neg_lo:[1,0,0] neg_hi:[1,0,0]
	s_nop 0
	v_pk_fma_f32 v[54:55], v[44:45], v[152:153], v[54:55] neg_lo:[1,0,0] neg_hi:[1,0,0]
	s_nop 0
	v_pk_fma_f32 v[54:55], v[46:47], v[154:155], v[54:55] neg_lo:[1,0,0] neg_hi:[1,0,0]
	s_nop 0
	v_pk_fma_f32 v[54:55], v[48:49], v[156:157], v[54:55] neg_lo:[1,0,0] neg_hi:[1,0,0]
	s_nop 0
	v_pk_fma_f32 v[54:55], v[162:163], v[52:53], v[54:55] neg_lo:[1,0,0] neg_hi:[1,0,0]
	s_nop 0
	v_pk_add_f32 v[54:55], v[54:55], v[54:55] op_sel:[0,1] op_sel_hi:[1,0]
	v_mov_b32_e32 v0, 0x1bc00
	ds_read_b128 v[56:59], v0
	v_mov_b32_e32 v0, 0x1bc10
	ds_read_b128 v[60:63], v0
	v_mov_b32_e32 v0, 0x1bc20
	ds_read_b128 v[84:87], v0
	v_mov_b32_e32 v0, 0x1bc30
	ds_read_b128 v[92:95], v0
	v_mov_b32_e32 v0, 0x1bc40
	ds_read_b128 v[112:115], v0
	v_mov_b32_e32 v0, 0x1bc50
	ds_read_b128 v[116:119], v0
	v_mov_b32_e32 v0, 0x1bc60
	ds_read_b128 v[124:127], v0
	v_mov_b32_e32 v0, 0x1bc70
	ds_read_b128 v[132:135], v0
	v_mov_b32_e32 v0, 0x1bc80
	ds_read_b128 v[140:143], v0
	v_mov_b32_e32 v0, 0x1bc90
	ds_read_b128 v[150:153], v0
	v_or_b32_e32 v0, 0x1c8d0, v67
	v_mov_b32_e32 v55, 0x1bcc0
	v_mov_b32_e32 v64, 0x1bca0
	ds_read_b128 v[154:157], v55
	ds_read_b32 v0, v0
	ds_read_b32 v55, v66 offset:26624
	ds_read_b128 v[162:165], v64
	v_mov_b32_e32 v64, 0x1bcb0
	ds_read_b128 v[166:169], v64
	s_waitcnt lgkmcnt(0)
; DI void gdn_prep_item(const Params& P, int l, int n, int hh, char* smem) {
;     ...
;     for (int i = 1; i < 64; ++i) {
;       f32x4 (&CUR)[16] = (i & 1) ? LA : LB; f32x4 (&NXT)[16] = (i & 1) ? LB : LA;
;       if (i + 1 < 64) {
; #pragma unroll
;         for (int c = 0; c < (i + 4) / 4; ++c) NXT[c] = *(const f32x4*)(Lm + (i + 1) * 64 + 4 * c);
;         rh[(i + 1) & 1] = sp[i + 1] * rp[(i + 1) * 128];
;       }
;       __builtin_amdgcn_sched_barrier(0);
;       f32x2 acc = {rh[i & 1], 0.f};
; #pragma unroll
;       for (int p = 0; p < i / 2; ++p) { const f32x2 lp = (p & 1) ? (f32x2){CUR[p >> 1].z, CUR[p >> 1].w} : (f32x2){CUR[p >> 1].x, CUR[p >> 1].y}; acc = acc - lp * xx[p]; }
;       if (i & 1) { const int j = i - 1; const float lj = ((j & 3) == 0) ? CUR[j >> 2].x : CUR[j >> 2].z; acc.x = fmaf(-lj, xx[j >> 1].x, acc.x); }
;       const float xi = acc.x + acc.y;
;       if (i & 1) xx[i >> 1].y = xi; else xx[i >> 1].x = xi;
;       __builtin_amdgcn_sched_barrier(0);
;     }
	v_mul_f32_e32 v0, v0, v55
	v_mov_b32_e32 v171, v1
	v_pk_fma_f32 v[64:65], v[2:3], v[70:71], v[170:171] neg_lo:[1,0,0] neg_hi:[1,0,0]
	s_nop 0
	v_pk_fma_f32 v[64:65], v[4:5], v[72:73], v[64:65] neg_lo:[1,0,0] neg_hi:[1,0,0]
	s_nop 0
	v_pk_fma_f32 v[64:65], v[6:7], v[74:75], v[64:65] neg_lo:[1,0,0] neg_hi:[1,0,0]
	s_nop 0
	v_pk_fma_f32 v[64:65], v[8:9], v[76:77], v[64:65] neg_lo:[1,0,0] neg_hi:[1,0,0]
	s_nop 0
	v_pk_fma_f32 v[64:65], v[10:11], v[78:79], v[64:65] neg_lo:[1,0,0] neg_hi:[1,0,0]
	s_nop 0
	v_pk_fma_f32 v[64:65], v[12:13], v[80:81], v[64:65] neg_lo:[1,0,0] neg_hi:[1,0,0]
	s_nop 0
	v_pk_fma_f32 v[64:65], v[14:15], v[88:89], v[64:65] neg_lo:[1,0,0] neg_hi:[1,0,0]
	s_nop 0
	v_pk_fma_f32 v[64:65], v[16:17], v[90:91], v[64:65] neg_lo:[1,0,0] neg_hi:[1,0,0]
	s_nop 0
	v_pk_fma_f32 v[64:65], v[18:19], v[96:97], v[64:65] neg_lo:[1,0,0] neg_hi:[1,0,0]
	s_nop 0
	v_pk_fma_f32 v[64:65], v[20:21], v[98:99], v[64:65] neg_lo:[1,0,0] neg_hi:[1,0,0]
	s_nop 0
	v_pk_fma_f32 v[64:65], v[22:23], v[100:101], v[64:65] neg_lo:[1,0,0] neg_hi:[1,0,0]
	s_nop 0
	v_pk_fma_f32 v[64:65], v[24:25], v[102:103], v[64:65] neg_lo:[1,0,0] neg_hi:[1,0,0]
	s_nop 0
	v_pk_fma_f32 v[64:65], v[26:27], v[104:105], v[64:65] neg_lo:[1,0,0] neg_hi:[1,0,0]
	s_nop 0
	v_pk_fma_f32 v[64:65], v[28:29], v[106:107], v[64:65] neg_lo:[1,0,0] neg_hi:[1,0,0]
	s_nop 0
	v_pk_fma_f32 v[64:65], v[30:31], v[108:109], v[64:65] neg_lo:[1,0,0] neg_hi:[1,0,0]
	s_nop 0
	v_pk_fma_f32 v[64:65], v[32:33], v[110:111], v[64:65] neg_lo:[1,0,0] neg_hi:[1,0,0]
	s_nop 0
	v_pk_fma_f32 v[64:65], v[34:35], v[120:121], v[64:65] neg_lo:[1,0,0] neg_hi:[1,0,0]
	s_nop 0
	v_pk_fma_f32 v[64:65], v[36:37], v[122:123], v[64:65] neg_lo:[1,0,0] neg_hi:[1,0,0]
	s_nop 0
	v_pk_fma_f32 v[64:65], v[38:39], v[128:129], v[64:65] neg_lo:[1,0,0] neg_hi:[1,0,0]
	s_nop 0
	v_pk_fma_f32 v[64:65], v[40:41], v[130:131], v[64:65] neg_lo:[1,0,0] neg_hi:[1,0,0]
	s_nop 0
	v_pk_fma_f32 v[64:65], v[42:43], v[146:147], v[64:65] neg_lo:[1,0,0] neg_hi:[1,0,0]
	s_nop 0
	v_pk_fma_f32 v[64:65], v[44:45], v[148:149], v[64:65] neg_lo:[1,0,0] neg_hi:[1,0,0]
	s_nop 0
	v_pk_fma_f32 v[64:65], v[46:47], v[158:159], v[64:65] neg_lo:[1,0,0] neg_hi:[1,0,0]
	s_nop 0
	v_pk_fma_f32 v[64:65], v[48:49], v[160:161], v[64:65] neg_lo:[1,0,0] neg_hi:[1,0,0]
	s_nop 0
	v_pk_fma_f32 v[64:65], v[52:53], v[136:137], v[64:65] neg_lo:[1,0,0] neg_hi:[1,0,0]
	s_nop 0
	v_fma_f32 v55, -v138, v54, v64
	v_add_f32_e32 v55, v65, v55
	v_mov_b32_e32 v64, 0x1bd00
	ds_read_b128 v[70:73], v64
	v_mov_b32_e32 v64, 0x1bd10
	ds_read_b128 v[74:77], v64
	v_mov_b32_e32 v64, 0x1bd20
	ds_read_b128 v[78:81], v64
	v_mov_b32_e32 v64, 0x1bd30
	ds_read_b128 v[88:91], v64
	v_mov_b32_e32 v64, 0x1bd40
	ds_read_b128 v[96:99], v64
	v_mov_b32_e32 v64, 0x1bd50
	ds_read_b128 v[100:103], v64
	v_mov_b32_e32 v64, 0x1bd60
	ds_read_b128 v[104:107], v64
	v_mov_b32_e32 v64, 0x1bd70
	ds_read_b128 v[108:111], v64
	v_mov_b32_e32 v64, 0x1bd80
	ds_read_b128 v[120:123], v64
	v_mov_b32_e32 v64, 0x1bd90
	ds_read_b128 v[128:131], v64
	v_mov_b32_e32 v64, 0x1bda0
	ds_read_b128 v[136:139], v64
	v_mov_b32_e32 v64, 0x1bdb0
	ds_read_b128 v[144:147], v64
	v_mov_b32_e32 v64, 0x1bdc0
	ds_read_b128 v[158:161], v64
	v_mov_b32_e32 v64, 0x1bdd0
	ds_read_b128 v[170:173], v64
	v_or_b32_e32 v64, 0x1c8d4, v67
	ds_read_b32 v64, v64
	ds_read_b32 v65, v66 offset:27136
	s_waitcnt lgkmcnt(0)
	v_mul_f32_e32 v172, v64, v65
	v_pk_fma_f32 v[56:57], v[2:3], v[56:57], v[0:1] neg_lo:[1,0,0] neg_hi:[1,0,0]
	s_nop 0
	v_pk_fma_f32 v[56:57], v[4:5], v[58:59], v[56:57] neg_lo:[1,0,0] neg_hi:[1,0,0]
	s_nop 0
	v_pk_fma_f32 v[56:57], v[6:7], v[60:61], v[56:57] neg_lo:[1,0,0] neg_hi:[1,0,0]
	s_nop 0
	v_pk_fma_f32 v[56:57], v[8:9], v[62:63], v[56:57] neg_lo:[1,0,0] neg_hi:[1,0,0]
	s_nop 0
	v_pk_fma_f32 v[56:57], v[10:11], v[84:85], v[56:57] neg_lo:[1,0,0] neg_hi:[1,0,0]
	s_nop 0
	v_pk_fma_f32 v[56:57], v[12:13], v[86:87], v[56:57] neg_lo:[1,0,0] neg_hi:[1,0,0]
	s_nop 0
	v_pk_fma_f32 v[56:57], v[14:15], v[92:93], v[56:57] neg_lo:[1,0,0] neg_hi:[1,0,0]
	s_nop 0
	v_pk_fma_f32 v[56:57], v[16:17], v[94:95], v[56:57] neg_lo:[1,0,0] neg_hi:[1,0,0]
	s_nop 0
	v_pk_fma_f32 v[56:57], v[18:19], v[112:113], v[56:57] neg_lo:[1,0,0] neg_hi:[1,0,0]
	s_nop 0
	v_pk_fma_f32 v[56:57], v[20:21], v[114:115], v[56:57] neg_lo:[1,0,0] neg_hi:[1,0,0]
	s_nop 0
	v_pk_fma_f32 v[56:57], v[22:23], v[116:117], v[56:57] neg_lo:[1,0,0] neg_hi:[1,0,0]
	s_nop 0
	v_pk_fma_f32 v[56:57], v[24:25], v[118:119], v[56:57] neg_lo:[1,0,0] neg_hi:[1,0,0]
	s_nop 0
	v_pk_fma_f32 v[56:57], v[26:27], v[124:125], v[56:57] neg_lo:[1,0,0] neg_hi:[1,0,0]
	s_nop 0
	v_pk_fma_f32 v[56:57], v[28:29], v[126:127], v[56:57] neg_lo:[1,0,0] neg_hi:[1,0,0]
	s_nop 0
	v_pk_fma_f32 v[56:57], v[30:31], v[132:133], v[56:57] neg_lo:[1,0,0] neg_hi:[1,0,0]
	s_nop 0
	v_pk_fma_f32 v[56:57], v[32:33], v[134:135], v[56:57] neg_lo:[1,0,0] neg_hi:[1,0,0]
	s_nop 0
	v_pk_fma_f32 v[56:57], v[34:35], v[140:141], v[56:57] neg_lo:[1,0,0] neg_hi:[1,0,0]
	s_nop 0
	v_pk_fma_f32 v[56:57], v[36:37], v[142:143], v[56:57] neg_lo:[1,0,0] neg_hi:[1,0,0]
	s_nop 0
	v_pk_fma_f32 v[56:57], v[38:39], v[150:151], v[56:57] neg_lo:[1,0,0] neg_hi:[1,0,0]
	s_nop 0
	v_pk_fma_f32 v[56:57], v[40:41], v[152:153], v[56:57] neg_lo:[1,0,0] neg_hi:[1,0,0]
	s_nop 0
	v_pk_fma_f32 v[56:57], v[42:43], v[162:163], v[56:57] neg_lo:[1,0,0] neg_hi:[1,0,0]
	s_nop 0
	v_pk_fma_f32 v[56:57], v[44:45], v[164:165], v[56:57] neg_lo:[1,0,0] neg_hi:[1,0,0]
	s_nop 0
	v_pk_fma_f32 v[56:57], v[46:47], v[166:167], v[56:57] neg_lo:[1,0,0] neg_hi:[1,0,0]
	s_nop 0
	v_pk_fma_f32 v[56:57], v[48:49], v[168:169], v[56:57] neg_lo:[1,0,0] neg_hi:[1,0,0]
	s_nop 0
	v_pk_fma_f32 v[56:57], v[52:53], v[154:155], v[56:57] neg_lo:[1,0,0] neg_hi:[1,0,0]
	s_nop 0
	v_pk_fma_f32 v[56:57], v[156:157], v[54:55], v[56:57] neg_lo:[1,0,0] neg_hi:[1,0,0]
	s_nop 0
	v_pk_add_f32 v[56:57], v[56:57], v[56:57] op_sel:[0,1] op_sel_hi:[1,0]
	v_mov_b32_e32 v0, 0x1be00
	ds_read_b128 v[58:61], v0
	v_mov_b32_e32 v0, 0x1be10
	ds_read_b128 v[62:65], v0
	v_mov_b32_e32 v0, 0x1be20
	ds_read_b128 v[84:87], v0
	v_mov_b32_e32 v0, 0x1be30
	ds_read_b128 v[92:95], v0
	v_mov_b32_e32 v0, 0x1be40
	ds_read_b128 v[112:115], v0
	v_mov_b32_e32 v0, 0x1be50
	ds_read_b128 v[116:119], v0
	v_mov_b32_e32 v0, 0x1be60
	ds_read_b128 v[124:127], v0
	v_mov_b32_e32 v0, 0x1be70
	ds_read_b128 v[132:135], v0
	v_mov_b32_e32 v0, 0x1be80
	ds_read_b128 v[140:143], v0
	v_mov_b32_e32 v0, 0x1be90
	ds_read_b128 v[148:151], v0
	v_mov_b32_e32 v0, 0x1bea0
	ds_read_b128 v[152:155], v0
	v_mov_b32_e32 v0, 0x1beb0
	ds_read_b128 v[162:165], v0
	v_or_b32_e32 v0, 0x1c8d8, v67
	v_mov_b32_e32 v83, 0x1bec0
	ds_read_b32 v0, v0
	ds_read_b32 v57, v66 offset:27648
	ds_read_b128 v[166:169], v83
	v_mov_b32_e32 v83, 0x1bed0
	ds_read_b64 v[174:175], v83
	s_waitcnt lgkmcnt(0)
; DI void gdn_prep_item(const Params& P, int l, int n, int hh, char* smem) {
;     ...
;     for (int i = 1; i < 64; ++i) {
;       f32x4 (&CUR)[16] = (i & 1) ? LA : LB; f32x4 (&NXT)[16] = (i & 1) ? LB : LA;
;       if (i + 1 < 64) {
; #pragma unroll
;         for (int c = 0; c < (i + 4) / 4; ++c) NXT[c] = *(const f32x4*)(Lm + (i + 1) * 64 + 4 * c);
;         rh[(i + 1) & 1] = sp[i + 1] * rp[(i + 1) * 128];
;       }
;       __builtin_amdgcn_sched_barrier(0);
;       f32x2 acc = {rh[i & 1], 0.f};
; #pragma unroll
;       for (int p = 0; p < i / 2; ++p) { const f32x2 lp = (p & 1) ? (f32x2){CUR[p >> 1].z, CUR[p >> 1].w} : (f32x2){CUR[p >> 1].x, CUR[p >> 1].y}; acc = acc - lp * xx[p]; }
;       if (i & 1) { const int j = i - 1; const float lj = ((j & 3) == 0) ? CUR[j >> 2].x : CUR[j >> 2].z; acc.x = fmaf(-lj, xx[j >> 1].x, acc.x); }
;       const float xi = acc.x + acc.y;
;       if (i & 1) xx[i >> 1].y = xi; else xx[i >> 1].x = xi;
;       __builtin_amdgcn_sched_barrier(0);
;     }
	v_mul_f32_e32 v0, v0, v57
	v_mov_b32_e32 v173, v1
	v_pk_fma_f32 v[70:71], v[2:3], v[70:71], v[172:173] neg_lo:[1,0,0] neg_hi:[1,0,0]
	s_nop 0
	v_pk_fma_f32 v[70:71], v[4:5], v[72:73], v[70:71] neg_lo:[1,0,0] neg_hi:[1,0,0]
	s_nop 0
	v_pk_fma_f32 v[70:71], v[6:7], v[74:75], v[70:71] neg_lo:[1,0,0] neg_hi:[1,0,0]
	s_nop 0
	v_pk_fma_f32 v[70:71], v[8:9], v[76:77], v[70:71] neg_lo:[1,0,0] neg_hi:[1,0,0]
	s_nop 0
	v_pk_fma_f32 v[70:71], v[10:11], v[78:79], v[70:71] neg_lo:[1,0,0] neg_hi:[1,0,0]
	s_nop 0
	v_pk_fma_f32 v[70:71], v[12:13], v[80:81], v[70:71] neg_lo:[1,0,0] neg_hi:[1,0,0]
	s_nop 0
	v_pk_fma_f32 v[70:71], v[14:15], v[88:89], v[70:71] neg_lo:[1,0,0] neg_hi:[1,0,0]
	s_nop 0
	v_pk_fma_f32 v[70:71], v[16:17], v[90:91], v[70:71] neg_lo:[1,0,0] neg_hi:[1,0,0]
	s_nop 0
	v_pk_fma_f32 v[70:71], v[18:19], v[96:97], v[70:71] neg_lo:[1,0,0] neg_hi:[1,0,0]
	s_nop 0
	v_pk_fma_f32 v[70:71], v[20:21], v[98:99], v[70:71] neg_lo:[1,0,0] neg_hi:[1,0,0]
	s_nop 0
	v_pk_fma_f32 v[70:71], v[22:23], v[100:101], v[70:71] neg_lo:[1,0,0] neg_hi:[1,0,0]
	s_nop 0
	v_pk_fma_f32 v[70:71], v[24:25], v[102:103], v[70:71] neg_lo:[1,0,0] neg_hi:[1,0,0]
	s_nop 0
	v_pk_fma_f32 v[70:71], v[26:27], v[104:105], v[70:71] neg_lo:[1,0,0] neg_hi:[1,0,0]
	s_nop 0
	v_pk_fma_f32 v[70:71], v[28:29], v[106:107], v[70:71] neg_lo:[1,0,0] neg_hi:[1,0,0]
	s_nop 0
	v_pk_fma_f32 v[70:71], v[30:31], v[108:109], v[70:71] neg_lo:[1,0,0] neg_hi:[1,0,0]
	s_nop 0
	v_pk_fma_f32 v[70:71], v[32:33], v[110:111], v[70:71] neg_lo:[1,0,0] neg_hi:[1,0,0]
	s_nop 0
	v_pk_fma_f32 v[70:71], v[34:35], v[120:121], v[70:71] neg_lo:[1,0,0] neg_hi:[1,0,0]
	s_nop 0
	v_pk_fma_f32 v[70:71], v[36:37], v[122:123], v[70:71] neg_lo:[1,0,0] neg_hi:[1,0,0]
	s_nop 0
	v_pk_fma_f32 v[70:71], v[38:39], v[128:129], v[70:71] neg_lo:[1,0,0] neg_hi:[1,0,0]
	s_nop 0
	v_pk_fma_f32 v[70:71], v[40:41], v[130:131], v[70:71] neg_lo:[1,0,0] neg_hi:[1,0,0]
	s_nop 0
	v_pk_fma_f32 v[70:71], v[42:43], v[136:137], v[70:71] neg_lo:[1,0,0] neg_hi:[1,0,0]
	s_nop 0
	v_pk_fma_f32 v[70:71], v[44:45], v[138:139], v[70:71] neg_lo:[1,0,0] neg_hi:[1,0,0]
	s_nop 0
	v_pk_fma_f32 v[70:71], v[46:47], v[144:145], v[70:71] neg_lo:[1,0,0] neg_hi:[1,0,0]
	s_nop 0
	v_pk_fma_f32 v[70:71], v[48:49], v[146:147], v[70:71] neg_lo:[1,0,0] neg_hi:[1,0,0]
	s_nop 0
	v_pk_fma_f32 v[70:71], v[52:53], v[158:159], v[70:71] neg_lo:[1,0,0] neg_hi:[1,0,0]
	s_nop 0
	v_pk_fma_f32 v[70:71], v[54:55], v[160:161], v[70:71] neg_lo:[1,0,0] neg_hi:[1,0,0]
	s_nop 0
	v_fma_f32 v57, -v170, v56, v70
	v_add_f32_e32 v57, v71, v57
	v_mov_b32_e32 v78, 0x1bf20
	v_mov_b32_e32 v83, 0x1bf30
	ds_read_b128 v[78:81], v78
	ds_read_b128 v[88:91], v83
	v_mov_b32_e32 v83, 0x1bf40
	ds_read_b128 v[96:99], v83
	v_mov_b32_e32 v83, 0x1bf50
	ds_read_b128 v[100:103], v83
	v_mov_b32_e32 v83, 0x1bf60
	ds_read_b128 v[104:107], v83
	v_mov_b32_e32 v83, 0x1bf70
	ds_read_b128 v[108:111], v83
	v_mov_b32_e32 v83, 0x1bf80
	ds_read_b128 v[120:123], v83
	v_mov_b32_e32 v83, 0x1bf90
	ds_read_b128 v[128:131], v83
	v_mov_b32_e32 v83, 0x1bfa0
	ds_read_b128 v[136:139], v83
	v_mov_b32_e32 v83, 0x1bfb0
	v_mov_b32_e32 v70, 0x1bf00
	v_mov_b32_e32 v74, 0x1bf10
	ds_read_b128 v[144:147], v83
	v_or_b32_e32 v83, 0x1c8dc, v67
	ds_read_b128 v[70:73], v70
	ds_read_b128 v[74:77], v74
	ds_read_b32 v83, v83
	ds_read_b32 v160, v66 offset:28160
	v_mov_b32_e32 v156, 0x1bfc0
	v_mov_b32_e32 v161, 0x1bfd0
	ds_read_b128 v[156:159], v156
	ds_read_b128 v[170:173], v161
	s_waitcnt lgkmcnt(0)
	v_mul_f32_e32 v182, v83, v160
	v_pk_fma_f32 v[58:59], v[2:3], v[58:59], v[0:1] neg_lo:[1,0,0] neg_hi:[1,0,0]
	s_nop 0
	v_pk_fma_f32 v[58:59], v[4:5], v[60:61], v[58:59] neg_lo:[1,0,0] neg_hi:[1,0,0]
	s_nop 0
	v_pk_fma_f32 v[58:59], v[6:7], v[62:63], v[58:59] neg_lo:[1,0,0] neg_hi:[1,0,0]
	s_nop 0
	v_pk_fma_f32 v[58:59], v[8:9], v[64:65], v[58:59] neg_lo:[1,0,0] neg_hi:[1,0,0]
	s_nop 0
	v_pk_fma_f32 v[58:59], v[10:11], v[84:85], v[58:59] neg_lo:[1,0,0] neg_hi:[1,0,0]
	s_nop 0
	v_pk_fma_f32 v[58:59], v[12:13], v[86:87], v[58:59] neg_lo:[1,0,0] neg_hi:[1,0,0]
	s_nop 0
	v_pk_fma_f32 v[58:59], v[14:15], v[92:93], v[58:59] neg_lo:[1,0,0] neg_hi:[1,0,0]
	s_nop 0
	v_pk_fma_f32 v[58:59], v[16:17], v[94:95], v[58:59] neg_lo:[1,0,0] neg_hi:[1,0,0]
	s_nop 0
	v_pk_fma_f32 v[58:59], v[18:19], v[112:113], v[58:59] neg_lo:[1,0,0] neg_hi:[1,0,0]
	s_nop 0
	v_pk_fma_f32 v[58:59], v[20:21], v[114:115], v[58:59] neg_lo:[1,0,0] neg_hi:[1,0,0]
	s_nop 0
	v_pk_fma_f32 v[58:59], v[22:23], v[116:117], v[58:59] neg_lo:[1,0,0] neg_hi:[1,0,0]
	s_nop 0
	v_pk_fma_f32 v[58:59], v[24:25], v[118:119], v[58:59] neg_lo:[1,0,0] neg_hi:[1,0,0]
	s_nop 0
	v_pk_fma_f32 v[58:59], v[26:27], v[124:125], v[58:59] neg_lo:[1,0,0] neg_hi:[1,0,0]
	s_nop 0
	v_pk_fma_f32 v[58:59], v[28:29], v[126:127], v[58:59] neg_lo:[1,0,0] neg_hi:[1,0,0]
	s_nop 0
	v_pk_fma_f32 v[58:59], v[30:31], v[132:133], v[58:59] neg_lo:[1,0,0] neg_hi:[1,0,0]
	s_nop 0
	v_pk_fma_f32 v[58:59], v[32:33], v[134:135], v[58:59] neg_lo:[1,0,0] neg_hi:[1,0,0]
	s_nop 0
	v_pk_fma_f32 v[58:59], v[34:35], v[140:141], v[58:59] neg_lo:[1,0,0] neg_hi:[1,0,0]
	s_nop 0
	v_pk_fma_f32 v[58:59], v[36:37], v[142:143], v[58:59] neg_lo:[1,0,0] neg_hi:[1,0,0]
	s_nop 0
	v_pk_fma_f32 v[58:59], v[38:39], v[148:149], v[58:59] neg_lo:[1,0,0] neg_hi:[1,0,0]
	s_nop 0
	v_pk_fma_f32 v[58:59], v[40:41], v[150:151], v[58:59] neg_lo:[1,0,0] neg_hi:[1,0,0]
	s_nop 0
	v_pk_fma_f32 v[58:59], v[42:43], v[152:153], v[58:59] neg_lo:[1,0,0] neg_hi:[1,0,0]
	s_nop 0
	v_pk_fma_f32 v[58:59], v[44:45], v[154:155], v[58:59] neg_lo:[1,0,0] neg_hi:[1,0,0]
	s_nop 0
	v_pk_fma_f32 v[58:59], v[46:47], v[162:163], v[58:59] neg_lo:[1,0,0] neg_hi:[1,0,0]
	s_nop 0
	v_pk_fma_f32 v[58:59], v[48:49], v[164:165], v[58:59] neg_lo:[1,0,0] neg_hi:[1,0,0]
	s_nop 0
	v_pk_fma_f32 v[58:59], v[52:53], v[166:167], v[58:59] neg_lo:[1,0,0] neg_hi:[1,0,0]
	s_nop 0
	v_pk_fma_f32 v[58:59], v[54:55], v[168:169], v[58:59] neg_lo:[1,0,0] neg_hi:[1,0,0]
	s_nop 0
	v_pk_fma_f32 v[58:59], v[174:175], v[56:57], v[58:59] neg_lo:[1,0,0] neg_hi:[1,0,0]
	s_nop 0
	v_pk_add_f32 v[58:59], v[58:59], v[58:59] op_sel:[0,1] op_sel_hi:[1,0]
	v_mov_b32_e32 v0, 0x1c000
	ds_read_b128 v[60:63], v0
	v_mov_b32_e32 v0, 0x1c010
	ds_read_b128 v[84:87], v0
	v_mov_b32_e32 v0, 0x1c020
	ds_read_b128 v[92:95], v0
	v_mov_b32_e32 v0, 0x1c030
	ds_read_b128 v[112:115], v0
	v_mov_b32_e32 v0, 0x1c040
	ds_read_b128 v[116:119], v0
	v_mov_b32_e32 v0, 0x1c050
	ds_read_b128 v[124:127], v0
	v_mov_b32_e32 v0, 0x1c060
	ds_read_b128 v[132:135], v0
	v_mov_b32_e32 v0, 0x1c070
	ds_read_b128 v[140:143], v0
	v_mov_b32_e32 v0, 0x1c080
	ds_read_b128 v[148:151], v0
	v_mov_b32_e32 v0, 0x1c090
	ds_read_b128 v[152:155], v0
	v_mov_b32_e32 v0, 0x1c0a0
	ds_read_b128 v[160:163], v0
	v_mov_b32_e32 v0, 0x1c0b0
	ds_read_b128 v[164:167], v0
	v_or_b32_e32 v0, 0x1c8e0, v67
	v_mov_b32_e32 v64, 0x1c0c0
	ds_read_b32 v0, v0
	ds_read_b32 v59, v66 offset:28672
	ds_read_b128 v[174:177], v64
	v_mov_b32_e32 v64, 0x1c0d0
	ds_read_b128 v[178:181], v64
	s_waitcnt lgkmcnt(0)
; DI void gdn_prep_item(const Params& P, int l, int n, int hh, char* smem) {
;     ...
;     for (int i = 1; i < 64; ++i) {
;       f32x4 (&CUR)[16] = (i & 1) ? LA : LB; f32x4 (&NXT)[16] = (i & 1) ? LB : LA;
;       if (i + 1 < 64) {
; #pragma unroll
;         for (int c = 0; c < (i + 4) / 4; ++c) NXT[c] = *(const f32x4*)(Lm + (i + 1) * 64 + 4 * c);
;         rh[(i + 1) & 1] = sp[i + 1] * rp[(i + 1) * 128];
;       }
;       __builtin_amdgcn_sched_barrier(0);
;       f32x2 acc = {rh[i & 1], 0.f};
; #pragma unroll
;       for (int p = 0; p < i / 2; ++p) { const f32x2 lp = (p & 1) ? (f32x2){CUR[p >> 1].z, CUR[p >> 1].w} : (f32x2){CUR[p >> 1].x, CUR[p >> 1].y}; acc = acc - lp * xx[p]; }
;       if (i & 1) { const int j = i - 1; const float lj = ((j & 3) == 0) ? CUR[j >> 2].x : CUR[j >> 2].z; acc.x = fmaf(-lj, xx[j >> 1].x, acc.x); }
;       const float xi = acc.x + acc.y;
;       if (i & 1) xx[i >> 1].y = xi; else xx[i >> 1].x = xi;
;       __builtin_amdgcn_sched_barrier(0);
;     }
	v_mul_f32_e32 v0, v0, v59
	v_mov_b32_e32 v183, v1
	v_pk_fma_f32 v[64:65], v[2:3], v[70:71], v[182:183] neg_lo:[1,0,0] neg_hi:[1,0,0]
	s_nop 0
	v_pk_fma_f32 v[64:65], v[4:5], v[72:73], v[64:65] neg_lo:[1,0,0] neg_hi:[1,0,0]
	s_nop 0
	v_pk_fma_f32 v[64:65], v[6:7], v[74:75], v[64:65] neg_lo:[1,0,0] neg_hi:[1,0,0]
	s_nop 0
	v_pk_fma_f32 v[64:65], v[8:9], v[76:77], v[64:65] neg_lo:[1,0,0] neg_hi:[1,0,0]
	s_nop 0
	v_pk_fma_f32 v[64:65], v[10:11], v[78:79], v[64:65] neg_lo:[1,0,0] neg_hi:[1,0,0]
	s_nop 0
	v_pk_fma_f32 v[64:65], v[12:13], v[80:81], v[64:65] neg_lo:[1,0,0] neg_hi:[1,0,0]
	s_nop 0
	v_pk_fma_f32 v[64:65], v[14:15], v[88:89], v[64:65] neg_lo:[1,0,0] neg_hi:[1,0,0]
	s_nop 0
	v_pk_fma_f32 v[64:65], v[16:17], v[90:91], v[64:65] neg_lo:[1,0,0] neg_hi:[1,0,0]
	s_nop 0
	v_pk_fma_f32 v[64:65], v[18:19], v[96:97], v[64:65] neg_lo:[1,0,0] neg_hi:[1,0,0]
	s_nop 0
	v_pk_fma_f32 v[64:65], v[20:21], v[98:99], v[64:65] neg_lo:[1,0,0] neg_hi:[1,0,0]
	s_nop 0
	v_pk_fma_f32 v[64:65], v[22:23], v[100:101], v[64:65] neg_lo:[1,0,0] neg_hi:[1,0,0]
	s_nop 0
	v_pk_fma_f32 v[64:65], v[24:25], v[102:103], v[64:65] neg_lo:[1,0,0] neg_hi:[1,0,0]
	s_nop 0
	v_pk_fma_f32 v[64:65], v[26:27], v[104:105], v[64:65] neg_lo:[1,0,0] neg_hi:[1,0,0]
	s_nop 0
	v_pk_fma_f32 v[64:65], v[28:29], v[106:107], v[64:65] neg_lo:[1,0,0] neg_hi:[1,0,0]
	s_nop 0
	v_pk_fma_f32 v[64:65], v[30:31], v[108:109], v[64:65] neg_lo:[1,0,0] neg_hi:[1,0,0]
	s_nop 0
	v_pk_fma_f32 v[64:65], v[32:33], v[110:111], v[64:65] neg_lo:[1,0,0] neg_hi:[1,0,0]
	s_nop 0
	v_pk_fma_f32 v[64:65], v[34:35], v[120:121], v[64:65] neg_lo:[1,0,0] neg_hi:[1,0,0]
	s_nop 0
	v_pk_fma_f32 v[64:65], v[36:37], v[122:123], v[64:65] neg_lo:[1,0,0] neg_hi:[1,0,0]
	s_nop 0
	v_pk_fma_f32 v[64:65], v[38:39], v[128:129], v[64:65] neg_lo:[1,0,0] neg_hi:[1,0,0]
	s_nop 0
	v_pk_fma_f32 v[64:65], v[40:41], v[130:131], v[64:65] neg_lo:[1,0,0] neg_hi:[1,0,0]
	s_nop 0
	v_pk_fma_f32 v[64:65], v[42:43], v[136:137], v[64:65] neg_lo:[1,0,0] neg_hi:[1,0,0]
	s_nop 0
	v_pk_fma_f32 v[64:65], v[44:45], v[138:139], v[64:65] neg_lo:[1,0,0] neg_hi:[1,0,0]
	s_nop 0
	v_pk_fma_f32 v[64:65], v[46:47], v[144:145], v[64:65] neg_lo:[1,0,0] neg_hi:[1,0,0]
	s_nop 0
	v_pk_fma_f32 v[64:65], v[48:49], v[146:147], v[64:65] neg_lo:[1,0,0] neg_hi:[1,0,0]
	s_nop 0
	v_pk_fma_f32 v[64:65], v[52:53], v[156:157], v[64:65] neg_lo:[1,0,0] neg_hi:[1,0,0]
	s_nop 0
	v_pk_fma_f32 v[64:65], v[54:55], v[158:159], v[64:65] neg_lo:[1,0,0] neg_hi:[1,0,0]
	s_nop 0
	v_pk_fma_f32 v[64:65], v[56:57], v[170:171], v[64:65] neg_lo:[1,0,0] neg_hi:[1,0,0]
	s_nop 0
	v_fma_f32 v59, -v172, v58, v64
	v_add_f32_e32 v59, v65, v59
	v_mov_b32_e32 v64, 0x1c100
	ds_read_b128 v[70:73], v64
	v_mov_b32_e32 v64, 0x1c110
	ds_read_b128 v[74:77], v64
	v_mov_b32_e32 v64, 0x1c120
	ds_read_b128 v[78:81], v64
	v_mov_b32_e32 v64, 0x1c130
	ds_read_b128 v[88:91], v64
	v_mov_b32_e32 v64, 0x1c140
	ds_read_b128 v[96:99], v64
	v_mov_b32_e32 v64, 0x1c150
	ds_read_b128 v[100:103], v64
	v_mov_b32_e32 v64, 0x1c160
	ds_read_b128 v[104:107], v64
	v_mov_b32_e32 v64, 0x1c170
	ds_read_b128 v[108:111], v64
	v_mov_b32_e32 v64, 0x1c180
	ds_read_b128 v[120:123], v64
	v_mov_b32_e32 v64, 0x1c190
	ds_read_b128 v[128:131], v64
	v_mov_b32_e32 v64, 0x1c1a0
	ds_read_b128 v[136:139], v64
	v_mov_b32_e32 v64, 0x1c1b0
	ds_read_b128 v[144:147], v64
	v_or_b32_e32 v64, 0x1c8e4, v67
	v_mov_b32_e32 v65, 0x1c1e0
	v_mov_b32_e32 v83, 0x1c1c0
	ds_read_b128 v[156:159], v65
	ds_read_b32 v64, v64
	ds_read_b32 v65, v66 offset:29184
	ds_read_b128 v[168:171], v83
	v_mov_b32_e32 v83, 0x1c1d0
	ds_read_b128 v[182:185], v83
	s_waitcnt lgkmcnt(0)
	v_mul_f32_e32 v186, v64, v65
	v_pk_fma_f32 v[60:61], v[2:3], v[60:61], v[0:1] neg_lo:[1,0,0] neg_hi:[1,0,0]
	s_nop 0
	v_pk_fma_f32 v[60:61], v[4:5], v[62:63], v[60:61] neg_lo:[1,0,0] neg_hi:[1,0,0]
	s_nop 0
	v_pk_fma_f32 v[60:61], v[6:7], v[84:85], v[60:61] neg_lo:[1,0,0] neg_hi:[1,0,0]
	s_nop 0
	v_pk_fma_f32 v[60:61], v[8:9], v[86:87], v[60:61] neg_lo:[1,0,0] neg_hi:[1,0,0]
	s_nop 0
	v_pk_fma_f32 v[60:61], v[10:11], v[92:93], v[60:61] neg_lo:[1,0,0] neg_hi:[1,0,0]
	s_nop 0
	v_pk_fma_f32 v[60:61], v[12:13], v[94:95], v[60:61] neg_lo:[1,0,0] neg_hi:[1,0,0]
	s_nop 0
	v_pk_fma_f32 v[60:61], v[14:15], v[112:113], v[60:61] neg_lo:[1,0,0] neg_hi:[1,0,0]
	s_nop 0
	v_pk_fma_f32 v[60:61], v[16:17], v[114:115], v[60:61] neg_lo:[1,0,0] neg_hi:[1,0,0]
	s_nop 0
	v_pk_fma_f32 v[60:61], v[18:19], v[116:117], v[60:61] neg_lo:[1,0,0] neg_hi:[1,0,0]
	s_nop 0
	v_pk_fma_f32 v[60:61], v[20:21], v[118:119], v[60:61] neg_lo:[1,0,0] neg_hi:[1,0,0]
	s_nop 0
	v_pk_fma_f32 v[60:61], v[22:23], v[124:125], v[60:61] neg_lo:[1,0,0] neg_hi:[1,0,0]
	s_nop 0
	v_pk_fma_f32 v[60:61], v[24:25], v[126:127], v[60:61] neg_lo:[1,0,0] neg_hi:[1,0,0]
	s_nop 0
	v_pk_fma_f32 v[60:61], v[26:27], v[132:133], v[60:61] neg_lo:[1,0,0] neg_hi:[1,0,0]
	s_nop 0
	v_pk_fma_f32 v[60:61], v[28:29], v[134:135], v[60:61] neg_lo:[1,0,0] neg_hi:[1,0,0]
	s_nop 0
	v_pk_fma_f32 v[60:61], v[30:31], v[140:141], v[60:61] neg_lo:[1,0,0] neg_hi:[1,0,0]
	s_nop 0
	v_pk_fma_f32 v[60:61], v[32:33], v[142:143], v[60:61] neg_lo:[1,0,0] neg_hi:[1,0,0]
	s_nop 0
	v_pk_fma_f32 v[60:61], v[34:35], v[148:149], v[60:61] neg_lo:[1,0,0] neg_hi:[1,0,0]
	s_nop 0
	v_pk_fma_f32 v[60:61], v[36:37], v[150:151], v[60:61] neg_lo:[1,0,0] neg_hi:[1,0,0]
	s_nop 0
	v_pk_fma_f32 v[60:61], v[38:39], v[152:153], v[60:61] neg_lo:[1,0,0] neg_hi:[1,0,0]
	s_nop 0
	v_pk_fma_f32 v[60:61], v[40:41], v[154:155], v[60:61] neg_lo:[1,0,0] neg_hi:[1,0,0]
	s_nop 0
	v_pk_fma_f32 v[60:61], v[42:43], v[160:161], v[60:61] neg_lo:[1,0,0] neg_hi:[1,0,0]
	s_nop 0
	v_pk_fma_f32 v[60:61], v[44:45], v[162:163], v[60:61] neg_lo:[1,0,0] neg_hi:[1,0,0]
; DI void gdn_prep_item(const Params& P, int l, int n, int hh, char* smem) {
;     ...
;     for (int i = 1; i < 64; ++i) {
;       f32x4 (&CUR)[16] = (i & 1) ? LA : LB; f32x4 (&NXT)[16] = (i & 1) ? LB : LA;
;       if (i + 1 < 64) {
; #pragma unroll
;         for (int c = 0; c < (i + 4) / 4; ++c) NXT[c] = *(const f32x4*)(Lm + (i + 1) * 64 + 4 * c);
;         rh[(i + 1) & 1] = sp[i + 1] * rp[(i + 1) * 128];
;       }
;       __builtin_amdgcn_sched_barrier(0);
;       f32x2 acc = {rh[i & 1], 0.f};
; #pragma unroll
;       for (int p = 0; p < i / 2; ++p) { const f32x2 lp = (p & 1) ? (f32x2){CUR[p >> 1].z, CUR[p >> 1].w} : (f32x2){CUR[p >> 1].x, CUR[p >> 1].y}; acc = acc - lp * xx[p]; }
;       if (i & 1) { const int j = i - 1; const float lj = ((j & 3) == 0) ? CUR[j >> 2].x : CUR[j >> 2].z; acc.x = fmaf(-lj, xx[j >> 1].x, acc.x); }
;       const float xi = acc.x + acc.y;
;       if (i & 1) xx[i >> 1].y = xi; else xx[i >> 1].x = xi;
;       __builtin_amdgcn_sched_barrier(0);
;     }
	s_nop 0
	v_pk_fma_f32 v[60:61], v[46:47], v[164:165], v[60:61] neg_lo:[1,0,0] neg_hi:[1,0,0]
	s_nop 0
	v_pk_fma_f32 v[60:61], v[48:49], v[166:167], v[60:61] neg_lo:[1,0,0] neg_hi:[1,0,0]
	s_nop 0
	v_pk_fma_f32 v[60:61], v[52:53], v[174:175], v[60:61] neg_lo:[1,0,0] neg_hi:[1,0,0]
	s_nop 0
	v_pk_fma_f32 v[60:61], v[54:55], v[176:177], v[60:61] neg_lo:[1,0,0] neg_hi:[1,0,0]
	s_nop 0
	v_pk_fma_f32 v[60:61], v[56:57], v[178:179], v[60:61] neg_lo:[1,0,0] neg_hi:[1,0,0]
	s_nop 0
	v_pk_fma_f32 v[60:61], v[180:181], v[58:59], v[60:61] neg_lo:[1,0,0] neg_hi:[1,0,0]
	s_nop 0
	v_pk_add_f32 v[60:61], v[60:61], v[60:61] op_sel:[0,1] op_sel_hi:[1,0]
	v_mov_b32_e32 v0, 0x1c200
	ds_read_b128 v[62:65], v0
	v_mov_b32_e32 v0, 0x1c210
	ds_read_b128 v[84:87], v0
	v_mov_b32_e32 v0, 0x1c220
	ds_read_b128 v[92:95], v0
	v_mov_b32_e32 v0, 0x1c230
	ds_read_b128 v[112:115], v0
	v_mov_b32_e32 v0, 0x1c240
	ds_read_b128 v[116:119], v0
	v_mov_b32_e32 v0, 0x1c250
	ds_read_b128 v[124:127], v0
	v_mov_b32_e32 v0, 0x1c260
	ds_read_b128 v[132:135], v0
	v_mov_b32_e32 v0, 0x1c270
	ds_read_b128 v[140:143], v0
	v_mov_b32_e32 v0, 0x1c280
	ds_read_b128 v[148:151], v0
	v_mov_b32_e32 v0, 0x1c290
	ds_read_b128 v[152:155], v0
	v_mov_b32_e32 v0, 0x1c2a0
	ds_read_b128 v[158:161], v0
	v_mov_b32_e32 v0, 0x1c2b0
	ds_read_b128 v[162:165], v0
	v_or_b32_e32 v0, 0x1c8e8, v67
	v_mov_b32_e32 v61, 0x1c2e0
	v_mov_b32_e32 v83, 0x1c2c0
	ds_read_b64 v[188:189], v61
	ds_read_b32 v0, v0
	ds_read_b32 v61, v66 offset:29696
	ds_read_b128 v[172:175], v83
	v_mov_b32_e32 v83, 0x1c2d0
	ds_read_b128 v[176:179], v83
	s_waitcnt lgkmcnt(0)
	v_mul_f32_e32 v0, v0, v61
	v_mov_b32_e32 v187, v1
	v_pk_fma_f32 v[70:71], v[2:3], v[70:71], v[186:187] neg_lo:[1,0,0] neg_hi:[1,0,0]
	s_nop 0
	v_pk_fma_f32 v[70:71], v[4:5], v[72:73], v[70:71] neg_lo:[1,0,0] neg_hi:[1,0,0]
	s_nop 0
	v_pk_fma_f32 v[70:71], v[6:7], v[74:75], v[70:71] neg_lo:[1,0,0] neg_hi:[1,0,0]
	s_nop 0
	v_pk_fma_f32 v[70:71], v[8:9], v[76:77], v[70:71] neg_lo:[1,0,0] neg_hi:[1,0,0]
	s_nop 0
	v_pk_fma_f32 v[70:71], v[10:11], v[78:79], v[70:71] neg_lo:[1,0,0] neg_hi:[1,0,0]
	s_nop 0
	v_pk_fma_f32 v[70:71], v[12:13], v[80:81], v[70:71] neg_lo:[1,0,0] neg_hi:[1,0,0]
	s_nop 0
	v_pk_fma_f32 v[70:71], v[14:15], v[88:89], v[70:71] neg_lo:[1,0,0] neg_hi:[1,0,0]
	s_nop 0
	v_pk_fma_f32 v[70:71], v[16:17], v[90:91], v[70:71] neg_lo:[1,0,0] neg_hi:[1,0,0]
	s_nop 0
	v_pk_fma_f32 v[70:71], v[18:19], v[96:97], v[70:71] neg_lo:[1,0,0] neg_hi:[1,0,0]
	s_nop 0
	v_pk_fma_f32 v[70:71], v[20:21], v[98:99], v[70:71] neg_lo:[1,0,0] neg_hi:[1,0,0]
	s_nop 0
	v_pk_fma_f32 v[70:71], v[22:23], v[100:101], v[70:71] neg_lo:[1,0,0] neg_hi:[1,0,0]
	s_nop 0
	v_pk_fma_f32 v[70:71], v[24:25], v[102:103], v[70:71] neg_lo:[1,0,0] neg_hi:[1,0,0]
	s_nop 0
	v_pk_fma_f32 v[70:71], v[26:27], v[104:105], v[70:71] neg_lo:[1,0,0] neg_hi:[1,0,0]
	s_nop 0
	v_pk_fma_f32 v[70:71], v[28:29], v[106:107], v[70:71] neg_lo:[1,0,0] neg_hi:[1,0,0]
	s_nop 0
	v_pk_fma_f32 v[70:71], v[30:31], v[108:109], v[70:71] neg_lo:[1,0,0] neg_hi:[1,0,0]
	s_nop 0
	v_pk_fma_f32 v[70:71], v[32:33], v[110:111], v[70:71] neg_lo:[1,0,0] neg_hi:[1,0,0]
	s_nop 0
	v_pk_fma_f32 v[70:71], v[34:35], v[120:121], v[70:71] neg_lo:[1,0,0] neg_hi:[1,0,0]
	s_nop 0
	v_pk_fma_f32 v[70:71], v[36:37], v[122:123], v[70:71] neg_lo:[1,0,0] neg_hi:[1,0,0]
	s_nop 0
	v_pk_fma_f32 v[70:71], v[38:39], v[128:129], v[70:71] neg_lo:[1,0,0] neg_hi:[1,0,0]
	s_nop 0
	v_pk_fma_f32 v[70:71], v[40:41], v[130:131], v[70:71] neg_lo:[1,0,0] neg_hi:[1,0,0]
	s_nop 0
	v_pk_fma_f32 v[70:71], v[42:43], v[136:137], v[70:71] neg_lo:[1,0,0] neg_hi:[1,0,0]
	s_nop 0
	v_pk_fma_f32 v[70:71], v[44:45], v[138:139], v[70:71] neg_lo:[1,0,0] neg_hi:[1,0,0]
	s_nop 0
	v_pk_fma_f32 v[70:71], v[46:47], v[144:145], v[70:71] neg_lo:[1,0,0] neg_hi:[1,0,0]
	s_nop 0
	v_pk_fma_f32 v[70:71], v[48:49], v[146:147], v[70:71] neg_lo:[1,0,0] neg_hi:[1,0,0]
	s_nop 0
	v_pk_fma_f32 v[70:71], v[52:53], v[168:169], v[70:71] neg_lo:[1,0,0] neg_hi:[1,0,0]
	s_nop 0
	v_pk_fma_f32 v[70:71], v[54:55], v[170:171], v[70:71] neg_lo:[1,0,0] neg_hi:[1,0,0]
	s_nop 0
	v_pk_fma_f32 v[70:71], v[56:57], v[182:183], v[70:71] neg_lo:[1,0,0] neg_hi:[1,0,0]
	s_nop 0
	v_pk_fma_f32 v[70:71], v[58:59], v[184:185], v[70:71] neg_lo:[1,0,0] neg_hi:[1,0,0]
	s_nop 0
	v_fma_f32 v61, -v156, v60, v70
	v_add_f32_e32 v61, v71, v61
	v_mov_b32_e32 v78, 0x1c320
	v_mov_b32_e32 v83, 0x1c330
	ds_read_b128 v[78:81], v78
	ds_read_b128 v[88:91], v83
	v_mov_b32_e32 v83, 0x1c340
	ds_read_b128 v[96:99], v83
	v_mov_b32_e32 v83, 0x1c350
	ds_read_b128 v[100:103], v83
	v_mov_b32_e32 v83, 0x1c360
	ds_read_b128 v[104:107], v83
	v_mov_b32_e32 v83, 0x1c370
	ds_read_b128 v[108:111], v83
	v_mov_b32_e32 v83, 0x1c380
	ds_read_b128 v[120:123], v83
	v_mov_b32_e32 v83, 0x1c390
	ds_read_b128 v[128:131], v83
	v_mov_b32_e32 v83, 0x1c3a0
	ds_read_b128 v[136:139], v83
	v_mov_b32_e32 v83, 0x1c3b0
	v_mov_b32_e32 v70, 0x1c300
	v_mov_b32_e32 v74, 0x1c310
	ds_read_b128 v[144:147], v83
	v_or_b32_e32 v83, 0x1c8ec, v67
	v_mov_b32_e32 v156, 0x1c3e0
	v_mov_b32_e32 v157, 0x1c3c0
	ds_read_b128 v[70:73], v70
	ds_read_b128 v[74:77], v74
	ds_read_b128 v[166:169], v156
	ds_read_b32 v83, v83
	ds_read_b32 v156, v66 offset:30208
	ds_read_b128 v[180:183], v157
	v_mov_b32_e32 v157, 0x1c3d0
	ds_read_b128 v[184:187], v157
	s_waitcnt lgkmcnt(0)
; DI void gdn_prep_item(const Params& P, int l, int n, int hh, char* smem) {
;     ...
;     for (int i = 1; i < 64; ++i) {
;       f32x4 (&CUR)[16] = (i & 1) ? LA : LB; f32x4 (&NXT)[16] = (i & 1) ? LB : LA;
;       if (i + 1 < 64) {
; #pragma unroll
;         for (int c = 0; c < (i + 4) / 4; ++c) NXT[c] = *(const f32x4*)(Lm + (i + 1) * 64 + 4 * c);
;         rh[(i + 1) & 1] = sp[i + 1] * rp[(i + 1) * 128];
;       }
;       __builtin_amdgcn_sched_barrier(0);
;       f32x2 acc = {rh[i & 1], 0.f};
; #pragma unroll
;       for (int p = 0; p < i / 2; ++p) { const f32x2 lp = (p & 1) ? (f32x2){CUR[p >> 1].z, CUR[p >> 1].w} : (f32x2){CUR[p >> 1].x, CUR[p >> 1].y}; acc = acc - lp * xx[p]; }
;       if (i & 1) { const int j = i - 1; const float lj = ((j & 3) == 0) ? CUR[j >> 2].x : CUR[j >> 2].z; acc.x = fmaf(-lj, xx[j >> 1].x, acc.x); }
;       const float xi = acc.x + acc.y;
;       if (i & 1) xx[i >> 1].y = xi; else xx[i >> 1].x = xi;
;       __builtin_amdgcn_sched_barrier(0);
;     }
	v_mul_f32_e32 v196, v83, v156
	v_pk_fma_f32 v[62:63], v[2:3], v[62:63], v[0:1] neg_lo:[1,0,0] neg_hi:[1,0,0]
	s_nop 0
	v_pk_fma_f32 v[62:63], v[4:5], v[64:65], v[62:63] neg_lo:[1,0,0] neg_hi:[1,0,0]
	s_nop 0
	v_pk_fma_f32 v[62:63], v[6:7], v[84:85], v[62:63] neg_lo:[1,0,0] neg_hi:[1,0,0]
	s_nop 0
	v_pk_fma_f32 v[62:63], v[8:9], v[86:87], v[62:63] neg_lo:[1,0,0] neg_hi:[1,0,0]
	s_nop 0
	v_pk_fma_f32 v[62:63], v[10:11], v[92:93], v[62:63] neg_lo:[1,0,0] neg_hi:[1,0,0]
	s_nop 0
	v_pk_fma_f32 v[62:63], v[12:13], v[94:95], v[62:63] neg_lo:[1,0,0] neg_hi:[1,0,0]
	s_nop 0
	v_pk_fma_f32 v[62:63], v[14:15], v[112:113], v[62:63] neg_lo:[1,0,0] neg_hi:[1,0,0]
	s_nop 0
	v_pk_fma_f32 v[62:63], v[16:17], v[114:115], v[62:63] neg_lo:[1,0,0] neg_hi:[1,0,0]
	s_nop 0
	v_pk_fma_f32 v[62:63], v[18:19], v[116:117], v[62:63] neg_lo:[1,0,0] neg_hi:[1,0,0]
	s_nop 0
	v_pk_fma_f32 v[62:63], v[20:21], v[118:119], v[62:63] neg_lo:[1,0,0] neg_hi:[1,0,0]
	s_nop 0
	v_pk_fma_f32 v[62:63], v[22:23], v[124:125], v[62:63] neg_lo:[1,0,0] neg_hi:[1,0,0]
	s_nop 0
	v_pk_fma_f32 v[62:63], v[24:25], v[126:127], v[62:63] neg_lo:[1,0,0] neg_hi:[1,0,0]
	s_nop 0
	v_pk_fma_f32 v[62:63], v[26:27], v[132:133], v[62:63] neg_lo:[1,0,0] neg_hi:[1,0,0]
	s_nop 0
	v_pk_fma_f32 v[62:63], v[28:29], v[134:135], v[62:63] neg_lo:[1,0,0] neg_hi:[1,0,0]
	s_nop 0
	v_pk_fma_f32 v[62:63], v[30:31], v[140:141], v[62:63] neg_lo:[1,0,0] neg_hi:[1,0,0]
	s_nop 0
	v_pk_fma_f32 v[62:63], v[32:33], v[142:143], v[62:63] neg_lo:[1,0,0] neg_hi:[1,0,0]
	s_nop 0
	v_pk_fma_f32 v[62:63], v[34:35], v[148:149], v[62:63] neg_lo:[1,0,0] neg_hi:[1,0,0]
	s_nop 0
	v_pk_fma_f32 v[62:63], v[36:37], v[150:151], v[62:63] neg_lo:[1,0,0] neg_hi:[1,0,0]
	s_nop 0
	v_pk_fma_f32 v[62:63], v[38:39], v[152:153], v[62:63] neg_lo:[1,0,0] neg_hi:[1,0,0]
	s_nop 0
	v_pk_fma_f32 v[62:63], v[40:41], v[154:155], v[62:63] neg_lo:[1,0,0] neg_hi:[1,0,0]
	s_nop 0
	v_pk_fma_f32 v[62:63], v[42:43], v[158:159], v[62:63] neg_lo:[1,0,0] neg_hi:[1,0,0]
	s_nop 0
	v_pk_fma_f32 v[62:63], v[44:45], v[160:161], v[62:63] neg_lo:[1,0,0] neg_hi:[1,0,0]
	s_nop 0
	v_pk_fma_f32 v[62:63], v[46:47], v[162:163], v[62:63] neg_lo:[1,0,0] neg_hi:[1,0,0]
	s_nop 0
	v_pk_fma_f32 v[62:63], v[48:49], v[164:165], v[62:63] neg_lo:[1,0,0] neg_hi:[1,0,0]
	s_nop 0
	v_pk_fma_f32 v[62:63], v[52:53], v[172:173], v[62:63] neg_lo:[1,0,0] neg_hi:[1,0,0]
	s_nop 0
	v_pk_fma_f32 v[62:63], v[54:55], v[174:175], v[62:63] neg_lo:[1,0,0] neg_hi:[1,0,0]
	s_nop 0
	v_pk_fma_f32 v[62:63], v[56:57], v[176:177], v[62:63] neg_lo:[1,0,0] neg_hi:[1,0,0]
	s_nop 0
	v_pk_fma_f32 v[62:63], v[58:59], v[178:179], v[62:63] neg_lo:[1,0,0] neg_hi:[1,0,0]
	s_nop 0
	v_pk_fma_f32 v[62:63], v[188:189], v[60:61], v[62:63] neg_lo:[1,0,0] neg_hi:[1,0,0]
	s_nop 0
	v_pk_add_f32 v[62:63], v[62:63], v[62:63] op_sel:[0,1] op_sel_hi:[1,0]
	v_mov_b32_e32 v0, 0x1c400
	ds_read_b128 v[84:87], v0
	v_mov_b32_e32 v0, 0x1c410
	ds_read_b128 v[92:95], v0
	v_mov_b32_e32 v0, 0x1c420
	ds_read_b128 v[112:115], v0
	v_mov_b32_e32 v0, 0x1c430
	ds_read_b128 v[116:119], v0
	v_mov_b32_e32 v0, 0x1c440
	ds_read_b128 v[124:127], v0
	v_mov_b32_e32 v0, 0x1c450
	ds_read_b128 v[132:135], v0
	v_mov_b32_e32 v0, 0x1c460
	ds_read_b128 v[140:143], v0
	v_mov_b32_e32 v0, 0x1c470
	ds_read_b128 v[148:151], v0
	v_mov_b32_e32 v0, 0x1c480
	ds_read_b128 v[152:155], v0
	v_mov_b32_e32 v0, 0x1c490
	ds_read_b128 v[156:159], v0
	v_mov_b32_e32 v0, 0x1c4a0
	ds_read_b128 v[160:163], v0
	v_mov_b32_e32 v0, 0x1c4b0
	ds_read_b128 v[170:173], v0
	v_or_b32_e32 v0, 0x1c8f0, v67
	v_mov_b32_e32 v63, 0x1c4e0
	v_mov_b32_e32 v64, 0x1c4c0
	ds_read_b128 v[174:177], v63
	ds_read_b32 v0, v0
	ds_read_b32 v63, v66 offset:30720
	ds_read_b128 v[188:191], v64
	v_mov_b32_e32 v64, 0x1c4d0
	ds_read_b128 v[192:195], v64
	s_waitcnt lgkmcnt(0)
	v_mul_f32_e32 v0, v0, v63
	v_mov_b32_e32 v197, v1
	v_pk_fma_f32 v[64:65], v[2:3], v[70:71], v[196:197] neg_lo:[1,0,0] neg_hi:[1,0,0]
	s_nop 0
	v_pk_fma_f32 v[64:65], v[4:5], v[72:73], v[64:65] neg_lo:[1,0,0] neg_hi:[1,0,0]
	s_nop 0
	v_pk_fma_f32 v[64:65], v[6:7], v[74:75], v[64:65] neg_lo:[1,0,0] neg_hi:[1,0,0]
	s_nop 0
	v_pk_fma_f32 v[64:65], v[8:9], v[76:77], v[64:65] neg_lo:[1,0,0] neg_hi:[1,0,0]
	s_nop 0
	v_pk_fma_f32 v[64:65], v[10:11], v[78:79], v[64:65] neg_lo:[1,0,0] neg_hi:[1,0,0]
	s_nop 0
	v_pk_fma_f32 v[64:65], v[12:13], v[80:81], v[64:65] neg_lo:[1,0,0] neg_hi:[1,0,0]
	s_nop 0
	v_pk_fma_f32 v[64:65], v[14:15], v[88:89], v[64:65] neg_lo:[1,0,0] neg_hi:[1,0,0]
	s_nop 0
	v_pk_fma_f32 v[64:65], v[16:17], v[90:91], v[64:65] neg_lo:[1,0,0] neg_hi:[1,0,0]
	s_nop 0
	v_pk_fma_f32 v[64:65], v[18:19], v[96:97], v[64:65] neg_lo:[1,0,0] neg_hi:[1,0,0]
	s_nop 0
	v_pk_fma_f32 v[64:65], v[20:21], v[98:99], v[64:65] neg_lo:[1,0,0] neg_hi:[1,0,0]
	s_nop 0
	v_pk_fma_f32 v[64:65], v[22:23], v[100:101], v[64:65] neg_lo:[1,0,0] neg_hi:[1,0,0]
	s_nop 0
	v_pk_fma_f32 v[64:65], v[24:25], v[102:103], v[64:65] neg_lo:[1,0,0] neg_hi:[1,0,0]
	s_nop 0
	v_pk_fma_f32 v[64:65], v[26:27], v[104:105], v[64:65] neg_lo:[1,0,0] neg_hi:[1,0,0]
	s_nop 0
	v_pk_fma_f32 v[64:65], v[28:29], v[106:107], v[64:65] neg_lo:[1,0,0] neg_hi:[1,0,0]
	s_nop 0
	v_pk_fma_f32 v[64:65], v[30:31], v[108:109], v[64:65] neg_lo:[1,0,0] neg_hi:[1,0,0]
	s_nop 0
	v_pk_fma_f32 v[64:65], v[32:33], v[110:111], v[64:65] neg_lo:[1,0,0] neg_hi:[1,0,0]
	s_nop 0
	v_pk_fma_f32 v[64:65], v[34:35], v[120:121], v[64:65] neg_lo:[1,0,0] neg_hi:[1,0,0]
	s_nop 0
	v_pk_fma_f32 v[64:65], v[36:37], v[122:123], v[64:65] neg_lo:[1,0,0] neg_hi:[1,0,0]
	s_nop 0
	v_pk_fma_f32 v[64:65], v[38:39], v[128:129], v[64:65] neg_lo:[1,0,0] neg_hi:[1,0,0]
	s_nop 0
	v_pk_fma_f32 v[64:65], v[40:41], v[130:131], v[64:65] neg_lo:[1,0,0] neg_hi:[1,0,0]
; DI void gdn_prep_item(const Params& P, int l, int n, int hh, char* smem) {
;     ...
;     for (int i = 1; i < 64; ++i) {
;       f32x4 (&CUR)[16] = (i & 1) ? LA : LB; f32x4 (&NXT)[16] = (i & 1) ? LB : LA;
;       if (i + 1 < 64) {
; #pragma unroll
;         for (int c = 0; c < (i + 4) / 4; ++c) NXT[c] = *(const f32x4*)(Lm + (i + 1) * 64 + 4 * c);
;         rh[(i + 1) & 1] = sp[i + 1] * rp[(i + 1) * 128];
;       }
;       __builtin_amdgcn_sched_barrier(0);
;       f32x2 acc = {rh[i & 1], 0.f};
; #pragma unroll
;       for (int p = 0; p < i / 2; ++p) { const f32x2 lp = (p & 1) ? (f32x2){CUR[p >> 1].z, CUR[p >> 1].w} : (f32x2){CUR[p >> 1].x, CUR[p >> 1].y}; acc = acc - lp * xx[p]; }
;       if (i & 1) { const int j = i - 1; const float lj = ((j & 3) == 0) ? CUR[j >> 2].x : CUR[j >> 2].z; acc.x = fmaf(-lj, xx[j >> 1].x, acc.x); }
;       const float xi = acc.x + acc.y;
;       if (i & 1) xx[i >> 1].y = xi; else xx[i >> 1].x = xi;
;       __builtin_amdgcn_sched_barrier(0);
;     }
	s_nop 0
	v_pk_fma_f32 v[64:65], v[42:43], v[136:137], v[64:65] neg_lo:[1,0,0] neg_hi:[1,0,0]
	s_nop 0
	v_pk_fma_f32 v[64:65], v[44:45], v[138:139], v[64:65] neg_lo:[1,0,0] neg_hi:[1,0,0]
	s_nop 0
	v_pk_fma_f32 v[64:65], v[46:47], v[144:145], v[64:65] neg_lo:[1,0,0] neg_hi:[1,0,0]
	s_nop 0
	v_pk_fma_f32 v[64:65], v[48:49], v[146:147], v[64:65] neg_lo:[1,0,0] neg_hi:[1,0,0]
	s_nop 0
	v_pk_fma_f32 v[64:65], v[52:53], v[180:181], v[64:65] neg_lo:[1,0,0] neg_hi:[1,0,0]
	s_nop 0
	v_pk_fma_f32 v[64:65], v[54:55], v[182:183], v[64:65] neg_lo:[1,0,0] neg_hi:[1,0,0]
	s_nop 0
	v_pk_fma_f32 v[64:65], v[56:57], v[184:185], v[64:65] neg_lo:[1,0,0] neg_hi:[1,0,0]
	s_nop 0
	v_pk_fma_f32 v[64:65], v[58:59], v[186:187], v[64:65] neg_lo:[1,0,0] neg_hi:[1,0,0]
	s_nop 0
	v_pk_fma_f32 v[64:65], v[60:61], v[166:167], v[64:65] neg_lo:[1,0,0] neg_hi:[1,0,0]
	s_nop 0
	v_fma_f32 v63, -v168, v62, v64
	v_add_f32_e32 v63, v65, v63
	v_mov_b32_e32 v64, 0x1c500
	ds_read_b128 v[70:73], v64
	v_mov_b32_e32 v64, 0x1c510
	ds_read_b128 v[74:77], v64
	v_mov_b32_e32 v64, 0x1c520
	ds_read_b128 v[78:81], v64
	v_mov_b32_e32 v64, 0x1c530
	ds_read_b128 v[88:91], v64
	v_mov_b32_e32 v64, 0x1c540
	ds_read_b128 v[96:99], v64
	v_mov_b32_e32 v64, 0x1c550
	ds_read_b128 v[100:103], v64
	v_mov_b32_e32 v64, 0x1c560
	ds_read_b128 v[104:107], v64
	v_mov_b32_e32 v64, 0x1c570
	ds_read_b128 v[108:111], v64
	v_mov_b32_e32 v64, 0x1c580
	ds_read_b128 v[120:123], v64
	v_mov_b32_e32 v64, 0x1c590
	ds_read_b128 v[128:131], v64
	v_mov_b32_e32 v64, 0x1c5a0
	ds_read_b128 v[136:139], v64
	v_mov_b32_e32 v64, 0x1c5b0
	ds_read_b128 v[144:147], v64
	v_mov_b32_e32 v64, 0x1c5c0
	ds_read_b128 v[164:167], v64
	v_mov_b32_e32 v64, 0x1c5d0
	ds_read_b128 v[178:181], v64
	v_mov_b32_e32 v64, 0x1c5e0
	ds_read_b128 v[182:185], v64
	v_mov_b32_e32 v64, 0x1c5f0
	ds_read_b128 v[196:199], v64
	v_or_b32_e32 v64, 0x1c8f4, v67
	ds_read_b32 v64, v64
	ds_read_b32 v65, v66 offset:31232
	s_waitcnt lgkmcnt(0)
	v_mul_f32_e32 v198, v64, v65
	v_pk_fma_f32 v[64:65], v[2:3], v[84:85], v[0:1] neg_lo:[1,0,0] neg_hi:[1,0,0]
	s_nop 0
	v_pk_fma_f32 v[64:65], v[4:5], v[86:87], v[64:65] neg_lo:[1,0,0] neg_hi:[1,0,0]
	s_nop 0
	v_pk_fma_f32 v[64:65], v[6:7], v[92:93], v[64:65] neg_lo:[1,0,0] neg_hi:[1,0,0]
	s_nop 0
	v_pk_fma_f32 v[64:65], v[8:9], v[94:95], v[64:65] neg_lo:[1,0,0] neg_hi:[1,0,0]
	s_nop 0
	v_pk_fma_f32 v[64:65], v[10:11], v[112:113], v[64:65] neg_lo:[1,0,0] neg_hi:[1,0,0]
	s_nop 0
	v_pk_fma_f32 v[64:65], v[12:13], v[114:115], v[64:65] neg_lo:[1,0,0] neg_hi:[1,0,0]
	s_nop 0
	v_pk_fma_f32 v[64:65], v[14:15], v[116:117], v[64:65] neg_lo:[1,0,0] neg_hi:[1,0,0]
	s_nop 0
	v_pk_fma_f32 v[64:65], v[16:17], v[118:119], v[64:65] neg_lo:[1,0,0] neg_hi:[1,0,0]
	s_nop 0
	v_pk_fma_f32 v[64:65], v[18:19], v[124:125], v[64:65] neg_lo:[1,0,0] neg_hi:[1,0,0]
	s_nop 0
	v_pk_fma_f32 v[64:65], v[20:21], v[126:127], v[64:65] neg_lo:[1,0,0] neg_hi:[1,0,0]
	s_nop 0
	v_pk_fma_f32 v[64:65], v[22:23], v[132:133], v[64:65] neg_lo:[1,0,0] neg_hi:[1,0,0]
	s_nop 0
	v_pk_fma_f32 v[64:65], v[24:25], v[134:135], v[64:65] neg_lo:[1,0,0] neg_hi:[1,0,0]
	s_nop 0
	v_pk_fma_f32 v[64:65], v[26:27], v[140:141], v[64:65] neg_lo:[1,0,0] neg_hi:[1,0,0]
	s_nop 0
	v_pk_fma_f32 v[64:65], v[28:29], v[142:143], v[64:65] neg_lo:[1,0,0] neg_hi:[1,0,0]
	s_nop 0
	v_pk_fma_f32 v[64:65], v[30:31], v[148:149], v[64:65] neg_lo:[1,0,0] neg_hi:[1,0,0]
	s_nop 0
	v_pk_fma_f32 v[64:65], v[32:33], v[150:151], v[64:65] neg_lo:[1,0,0] neg_hi:[1,0,0]
	s_nop 0
	v_pk_fma_f32 v[64:65], v[34:35], v[152:153], v[64:65] neg_lo:[1,0,0] neg_hi:[1,0,0]
	s_nop 0
	v_pk_fma_f32 v[64:65], v[36:37], v[154:155], v[64:65] neg_lo:[1,0,0] neg_hi:[1,0,0]
	s_nop 0
	v_pk_fma_f32 v[64:65], v[38:39], v[156:157], v[64:65] neg_lo:[1,0,0] neg_hi:[1,0,0]
	s_nop 0
	v_pk_fma_f32 v[64:65], v[40:41], v[158:159], v[64:65] neg_lo:[1,0,0] neg_hi:[1,0,0]
	s_nop 0
	v_pk_fma_f32 v[64:65], v[42:43], v[160:161], v[64:65] neg_lo:[1,0,0] neg_hi:[1,0,0]
	s_nop 0
	v_pk_fma_f32 v[64:65], v[44:45], v[162:163], v[64:65] neg_lo:[1,0,0] neg_hi:[1,0,0]
	s_nop 0
	v_pk_fma_f32 v[64:65], v[46:47], v[170:171], v[64:65] neg_lo:[1,0,0] neg_hi:[1,0,0]
	s_nop 0
	v_pk_fma_f32 v[64:65], v[48:49], v[172:173], v[64:65] neg_lo:[1,0,0] neg_hi:[1,0,0]
	s_nop 0
	v_pk_fma_f32 v[64:65], v[52:53], v[188:189], v[64:65] neg_lo:[1,0,0] neg_hi:[1,0,0]
	s_nop 0
	v_pk_fma_f32 v[64:65], v[54:55], v[190:191], v[64:65] neg_lo:[1,0,0] neg_hi:[1,0,0]
	s_nop 0
	v_pk_fma_f32 v[64:65], v[56:57], v[192:193], v[64:65] neg_lo:[1,0,0] neg_hi:[1,0,0]
	s_nop 0
	v_pk_fma_f32 v[64:65], v[58:59], v[194:195], v[64:65] neg_lo:[1,0,0] neg_hi:[1,0,0]
	s_nop 0
	v_pk_fma_f32 v[64:65], v[60:61], v[174:175], v[64:65] neg_lo:[1,0,0] neg_hi:[1,0,0]
	s_nop 0
	v_pk_fma_f32 v[64:65], v[176:177], v[62:63], v[64:65] neg_lo:[1,0,0] neg_hi:[1,0,0]
	s_nop 0
	v_pk_add_f32 v[64:65], v[64:65], v[64:65] op_sel:[0,1] op_sel_hi:[1,0]
	v_mov_b32_e32 v0, 0x1c600
	ds_read_b128 v[84:87], v0
	v_mov_b32_e32 v0, 0x1c610
	ds_read_b128 v[92:95], v0
	v_mov_b32_e32 v0, 0x1c620
	ds_read_b128 v[112:115], v0
	v_mov_b32_e32 v0, 0x1c630
	ds_read_b128 v[116:119], v0
	v_mov_b32_e32 v0, 0x1c640
	ds_read_b128 v[124:127], v0
	v_mov_b32_e32 v0, 0x1c650
	ds_read_b128 v[132:135], v0
	v_mov_b32_e32 v0, 0x1c660
	ds_read_b128 v[140:143], v0
	v_mov_b32_e32 v0, 0x1c670
	ds_read_b128 v[148:151], v0
	v_mov_b32_e32 v0, 0x1c680
	ds_read_b128 v[152:155], v0
	v_mov_b32_e32 v0, 0x1c690
	ds_read_b128 v[156:159], v0
	v_mov_b32_e32 v0, 0x1c6a0
	ds_read_b128 v[160:163], v0
	v_mov_b32_e32 v0, 0x1c6b0
	ds_read_b128 v[168:171], v0
	v_mov_b32_e32 v0, 0x1c6c0
	ds_read_b128 v[172:175], v0
	v_mov_b32_e32 v0, 0x1c6d0
	ds_read_b128 v[186:189], v0
	v_or_b32_e32 v0, 0x1c8f8, v67
	v_mov_b32_e32 v83, 0x1c6e0
	ds_read_b32 v0, v0
	ds_read_b32 v65, v66 offset:31744
	ds_read_b128 v[190:193], v83
	v_mov_b32_e32 v83, 0x1c6f0
	ds_read_b64 v[200:201], v83
	s_waitcnt lgkmcnt(0)
; DI void gdn_prep_item(const Params& P, int l, int n, int hh, char* smem) {
;     ...
;     for (int i = 1; i < 64; ++i) {
;       f32x4 (&CUR)[16] = (i & 1) ? LA : LB; f32x4 (&NXT)[16] = (i & 1) ? LB : LA;
;       if (i + 1 < 64) {
; #pragma unroll
;         for (int c = 0; c < (i + 4) / 4; ++c) NXT[c] = *(const f32x4*)(Lm + (i + 1) * 64 + 4 * c);
;         rh[(i + 1) & 1] = sp[i + 1] * rp[(i + 1) * 128];
;       }
;       __builtin_amdgcn_sched_barrier(0);
;       f32x2 acc = {rh[i & 1], 0.f};
; #pragma unroll
;       for (int p = 0; p < i / 2; ++p) { const f32x2 lp = (p & 1) ? (f32x2){CUR[p >> 1].z, CUR[p >> 1].w} : (f32x2){CUR[p >> 1].x, CUR[p >> 1].y}; acc = acc - lp * xx[p]; }
;       if (i & 1) { const int j = i - 1; const float lj = ((j & 3) == 0) ? CUR[j >> 2].x : CUR[j >> 2].z; acc.x = fmaf(-lj, xx[j >> 1].x, acc.x); }
;       const float xi = acc.x + acc.y;
;       if (i & 1) xx[i >> 1].y = xi; else xx[i >> 1].x = xi;
;       __builtin_amdgcn_sched_barrier(0);
;     }
	v_mul_f32_e32 v0, v0, v65
	v_mov_b32_e32 v199, v1
	v_pk_fma_f32 v[70:71], v[2:3], v[70:71], v[198:199] neg_lo:[1,0,0] neg_hi:[1,0,0]
	s_nop 0
	v_pk_fma_f32 v[70:71], v[4:5], v[72:73], v[70:71] neg_lo:[1,0,0] neg_hi:[1,0,0]
	s_nop 0
	v_pk_fma_f32 v[70:71], v[6:7], v[74:75], v[70:71] neg_lo:[1,0,0] neg_hi:[1,0,0]
	s_nop 0
	v_pk_fma_f32 v[70:71], v[8:9], v[76:77], v[70:71] neg_lo:[1,0,0] neg_hi:[1,0,0]
	s_nop 0
	v_pk_fma_f32 v[70:71], v[10:11], v[78:79], v[70:71] neg_lo:[1,0,0] neg_hi:[1,0,0]
	s_nop 0
	v_pk_fma_f32 v[70:71], v[12:13], v[80:81], v[70:71] neg_lo:[1,0,0] neg_hi:[1,0,0]
	s_nop 0
	v_pk_fma_f32 v[70:71], v[14:15], v[88:89], v[70:71] neg_lo:[1,0,0] neg_hi:[1,0,0]
	s_nop 0
	v_pk_fma_f32 v[70:71], v[16:17], v[90:91], v[70:71] neg_lo:[1,0,0] neg_hi:[1,0,0]
	s_nop 0
	v_pk_fma_f32 v[70:71], v[18:19], v[96:97], v[70:71] neg_lo:[1,0,0] neg_hi:[1,0,0]
	s_nop 0
	v_pk_fma_f32 v[70:71], v[20:21], v[98:99], v[70:71] neg_lo:[1,0,0] neg_hi:[1,0,0]
	s_nop 0
	v_pk_fma_f32 v[70:71], v[22:23], v[100:101], v[70:71] neg_lo:[1,0,0] neg_hi:[1,0,0]
	s_nop 0
	v_pk_fma_f32 v[70:71], v[24:25], v[102:103], v[70:71] neg_lo:[1,0,0] neg_hi:[1,0,0]
	s_nop 0
	v_pk_fma_f32 v[70:71], v[26:27], v[104:105], v[70:71] neg_lo:[1,0,0] neg_hi:[1,0,0]
	s_nop 0
	v_pk_fma_f32 v[70:71], v[28:29], v[106:107], v[70:71] neg_lo:[1,0,0] neg_hi:[1,0,0]
	s_nop 0
	v_pk_fma_f32 v[70:71], v[30:31], v[108:109], v[70:71] neg_lo:[1,0,0] neg_hi:[1,0,0]
	s_nop 0
	v_pk_fma_f32 v[70:71], v[32:33], v[110:111], v[70:71] neg_lo:[1,0,0] neg_hi:[1,0,0]
	s_nop 0
	v_pk_fma_f32 v[70:71], v[34:35], v[120:121], v[70:71] neg_lo:[1,0,0] neg_hi:[1,0,0]
	s_nop 0
	v_pk_fma_f32 v[70:71], v[36:37], v[122:123], v[70:71] neg_lo:[1,0,0] neg_hi:[1,0,0]
	s_nop 0
	v_pk_fma_f32 v[70:71], v[38:39], v[128:129], v[70:71] neg_lo:[1,0,0] neg_hi:[1,0,0]
	s_nop 0
	v_pk_fma_f32 v[70:71], v[40:41], v[130:131], v[70:71] neg_lo:[1,0,0] neg_hi:[1,0,0]
	s_nop 0
	v_pk_fma_f32 v[70:71], v[42:43], v[136:137], v[70:71] neg_lo:[1,0,0] neg_hi:[1,0,0]
	s_nop 0
	v_pk_fma_f32 v[70:71], v[44:45], v[138:139], v[70:71] neg_lo:[1,0,0] neg_hi:[1,0,0]
	s_nop 0
	v_pk_fma_f32 v[70:71], v[46:47], v[144:145], v[70:71] neg_lo:[1,0,0] neg_hi:[1,0,0]
	s_nop 0
	v_pk_fma_f32 v[70:71], v[48:49], v[146:147], v[70:71] neg_lo:[1,0,0] neg_hi:[1,0,0]
	s_nop 0
	v_pk_fma_f32 v[70:71], v[52:53], v[164:165], v[70:71] neg_lo:[1,0,0] neg_hi:[1,0,0]
	s_nop 0
	v_pk_fma_f32 v[70:71], v[54:55], v[166:167], v[70:71] neg_lo:[1,0,0] neg_hi:[1,0,0]
	s_nop 0
	v_pk_fma_f32 v[70:71], v[56:57], v[178:179], v[70:71] neg_lo:[1,0,0] neg_hi:[1,0,0]
	s_nop 0
	v_pk_fma_f32 v[70:71], v[58:59], v[180:181], v[70:71] neg_lo:[1,0,0] neg_hi:[1,0,0]
	s_nop 0
	v_pk_fma_f32 v[70:71], v[60:61], v[182:183], v[70:71] neg_lo:[1,0,0] neg_hi:[1,0,0]
	s_nop 0
	v_pk_fma_f32 v[70:71], v[62:63], v[184:185], v[70:71] neg_lo:[1,0,0] neg_hi:[1,0,0]
	s_nop 0
	v_fma_f32 v65, -v196, v64, v70
	v_add_f32_e32 v65, v71, v65
	v_mov_b32_e32 v78, 0x1c720
	v_mov_b32_e32 v83, 0x1c730
	ds_read_b128 v[78:81], v78
	ds_read_b128 v[88:91], v83
	v_mov_b32_e32 v83, 0x1c740
	ds_read_b128 v[96:99], v83
	v_mov_b32_e32 v83, 0x1c750
	ds_read_b128 v[100:103], v83
	v_mov_b32_e32 v83, 0x1c760
	ds_read_b128 v[104:107], v83
	v_mov_b32_e32 v83, 0x1c770
	ds_read_b128 v[108:111], v83
	v_mov_b32_e32 v83, 0x1c780
	ds_read_b128 v[120:123], v83
	v_mov_b32_e32 v83, 0x1c790
	ds_read_b128 v[128:131], v83
	v_mov_b32_e32 v83, 0x1c7a0
	ds_read_b128 v[136:139], v83
	v_mov_b32_e32 v83, 0x1c7b0
	ds_read_b128 v[144:147], v83
	v_mov_b32_e32 v83, 0x1c7c0
	ds_read_b128 v[164:167], v83
	v_mov_b32_e32 v83, 0x1c7d0
	v_mov_b32_e32 v70, 0x1c700
	v_mov_b32_e32 v74, 0x1c710
	ds_read_b128 v[176:179], v83
	v_or_b32_e32 v67, 0x1c8fc, v67
	v_mov_b32_e32 v83, 0x1c7e0
	ds_read_b128 v[70:73], v70
	ds_read_b128 v[74:77], v74
	ds_read_b32 v67, v67
	ds_read_b32 v66, v66 offset:32256
	ds_read_b128 v[180:183], v83
	v_mov_b32_e32 v83, 0x1c7f0
	ds_read_b128 v[194:197], v83
	s_waitcnt lgkmcnt(0)
	v_mul_f32_e32 v184, v67, v66
	v_pk_fma_f32 v[66:67], v[2:3], v[84:85], v[0:1] neg_lo:[1,0,0] neg_hi:[1,0,0]
	s_nop 0
	v_pk_fma_f32 v[66:67], v[4:5], v[86:87], v[66:67] neg_lo:[1,0,0] neg_hi:[1,0,0]
	s_nop 0
	v_pk_fma_f32 v[66:67], v[6:7], v[92:93], v[66:67] neg_lo:[1,0,0] neg_hi:[1,0,0]
	s_nop 0
	v_pk_fma_f32 v[66:67], v[8:9], v[94:95], v[66:67] neg_lo:[1,0,0] neg_hi:[1,0,0]
	s_nop 0
	v_pk_fma_f32 v[66:67], v[10:11], v[112:113], v[66:67] neg_lo:[1,0,0] neg_hi:[1,0,0]
	s_nop 0
	v_pk_fma_f32 v[66:67], v[12:13], v[114:115], v[66:67] neg_lo:[1,0,0] neg_hi:[1,0,0]
	s_nop 0
	v_pk_fma_f32 v[66:67], v[14:15], v[116:117], v[66:67] neg_lo:[1,0,0] neg_hi:[1,0,0]
	s_nop 0
	v_pk_fma_f32 v[66:67], v[16:17], v[118:119], v[66:67] neg_lo:[1,0,0] neg_hi:[1,0,0]
	s_nop 0
	v_pk_fma_f32 v[66:67], v[18:19], v[124:125], v[66:67] neg_lo:[1,0,0] neg_hi:[1,0,0]
	s_nop 0
	v_pk_fma_f32 v[66:67], v[20:21], v[126:127], v[66:67] neg_lo:[1,0,0] neg_hi:[1,0,0]
	s_nop 0
	v_pk_fma_f32 v[66:67], v[22:23], v[132:133], v[66:67] neg_lo:[1,0,0] neg_hi:[1,0,0]
	s_nop 0
	v_pk_fma_f32 v[66:67], v[24:25], v[134:135], v[66:67] neg_lo:[1,0,0] neg_hi:[1,0,0]
	s_nop 0
	v_pk_fma_f32 v[66:67], v[26:27], v[140:141], v[66:67] neg_lo:[1,0,0] neg_hi:[1,0,0]
	s_nop 0
	v_pk_fma_f32 v[66:67], v[28:29], v[142:143], v[66:67] neg_lo:[1,0,0] neg_hi:[1,0,0]
	s_nop 0
	v_pk_fma_f32 v[66:67], v[30:31], v[148:149], v[66:67] neg_lo:[1,0,0] neg_hi:[1,0,0]
	s_nop 0
	v_pk_fma_f32 v[66:67], v[32:33], v[150:151], v[66:67] neg_lo:[1,0,0] neg_hi:[1,0,0]
	s_nop 0
	v_pk_fma_f32 v[66:67], v[34:35], v[152:153], v[66:67] neg_lo:[1,0,0] neg_hi:[1,0,0]
	s_nop 0
	v_pk_fma_f32 v[66:67], v[36:37], v[154:155], v[66:67] neg_lo:[1,0,0] neg_hi:[1,0,0]
	s_nop 0
; DI void gdn_prep_item(const Params& P, int l, int n, int hh, char* smem) {
;     ...
;     for (int i = 1; i < 64; ++i) {
;       f32x4 (&CUR)[16] = (i & 1) ? LA : LB; f32x4 (&NXT)[16] = (i & 1) ? LB : LA;
;       if (i + 1 < 64) {
; #pragma unroll
;         for (int c = 0; c < (i + 4) / 4; ++c) NXT[c] = *(const f32x4*)(Lm + (i + 1) * 64 + 4 * c);
;         rh[(i + 1) & 1] = sp[i + 1] * rp[(i + 1) * 128];
;       }
;       __builtin_amdgcn_sched_barrier(0);
;       f32x2 acc = {rh[i & 1], 0.f};
; #pragma unroll
;       for (int p = 0; p < i / 2; ++p) { const f32x2 lp = (p & 1) ? (f32x2){CUR[p >> 1].z, CUR[p >> 1].w} : (f32x2){CUR[p >> 1].x, CUR[p >> 1].y}; acc = acc - lp * xx[p]; }
;       if (i & 1) { const int j = i - 1; const float lj = ((j & 3) == 0) ? CUR[j >> 2].x : CUR[j >> 2].z; acc.x = fmaf(-lj, xx[j >> 1].x, acc.x); }
;       const float xi = acc.x + acc.y;
;       if (i & 1) xx[i >> 1].y = xi; else xx[i >> 1].x = xi;
;       __builtin_amdgcn_sched_barrier(0);
;     }
;     float x[64];
; #pragma unroll
;     for (int p = 0; p < 32; ++p) { x[2 * p] = xx[p].x; x[2 * p + 1] = xx[p].y; }
;     if (isu) {
	v_pk_fma_f32 v[66:67], v[38:39], v[156:157], v[66:67] neg_lo:[1,0,0] neg_hi:[1,0,0]
	s_nop 0
	v_pk_fma_f32 v[66:67], v[40:41], v[158:159], v[66:67] neg_lo:[1,0,0] neg_hi:[1,0,0]
	s_nop 0
	v_pk_fma_f32 v[66:67], v[42:43], v[160:161], v[66:67] neg_lo:[1,0,0] neg_hi:[1,0,0]
	s_nop 0
	v_pk_fma_f32 v[66:67], v[44:45], v[162:163], v[66:67] neg_lo:[1,0,0] neg_hi:[1,0,0]
	s_nop 0
	v_pk_fma_f32 v[66:67], v[46:47], v[168:169], v[66:67] neg_lo:[1,0,0] neg_hi:[1,0,0]
	s_nop 0
	v_pk_fma_f32 v[66:67], v[48:49], v[170:171], v[66:67] neg_lo:[1,0,0] neg_hi:[1,0,0]
	s_nop 0
	v_pk_fma_f32 v[66:67], v[52:53], v[172:173], v[66:67] neg_lo:[1,0,0] neg_hi:[1,0,0]
	s_nop 0
	v_pk_fma_f32 v[66:67], v[54:55], v[174:175], v[66:67] neg_lo:[1,0,0] neg_hi:[1,0,0]
	s_nop 0
	v_pk_fma_f32 v[66:67], v[56:57], v[186:187], v[66:67] neg_lo:[1,0,0] neg_hi:[1,0,0]
	s_nop 0
	v_pk_fma_f32 v[66:67], v[58:59], v[188:189], v[66:67] neg_lo:[1,0,0] neg_hi:[1,0,0]
	s_nop 0
	v_pk_fma_f32 v[66:67], v[60:61], v[190:191], v[66:67] neg_lo:[1,0,0] neg_hi:[1,0,0]
	s_nop 0
	v_pk_fma_f32 v[66:67], v[62:63], v[192:193], v[66:67] neg_lo:[1,0,0] neg_hi:[1,0,0]
	s_nop 0
	v_pk_fma_f32 v[66:67], v[200:201], v[64:65], v[66:67] neg_lo:[1,0,0] neg_hi:[1,0,0]
	s_nop 0
	v_pk_add_f32 v[66:67], v[66:67], v[66:67] op_sel:[0,1] op_sel_hi:[1,0]
	v_mov_b32_e32 v185, v1
	v_pk_fma_f32 v[70:71], v[2:3], v[70:71], v[184:185] neg_lo:[1,0,0] neg_hi:[1,0,0]
	s_nop 0
	v_pk_fma_f32 v[70:71], v[4:5], v[72:73], v[70:71] neg_lo:[1,0,0] neg_hi:[1,0,0]
	s_nop 0
	v_pk_fma_f32 v[70:71], v[6:7], v[74:75], v[70:71] neg_lo:[1,0,0] neg_hi:[1,0,0]
	s_nop 0
	v_pk_fma_f32 v[70:71], v[8:9], v[76:77], v[70:71] neg_lo:[1,0,0] neg_hi:[1,0,0]
	s_nop 0
	v_pk_fma_f32 v[70:71], v[10:11], v[78:79], v[70:71] neg_lo:[1,0,0] neg_hi:[1,0,0]
	s_nop 0
	v_pk_fma_f32 v[70:71], v[12:13], v[80:81], v[70:71] neg_lo:[1,0,0] neg_hi:[1,0,0]
	s_nop 0
	v_pk_fma_f32 v[70:71], v[14:15], v[88:89], v[70:71] neg_lo:[1,0,0] neg_hi:[1,0,0]
	s_nop 0
	v_pk_fma_f32 v[70:71], v[16:17], v[90:91], v[70:71] neg_lo:[1,0,0] neg_hi:[1,0,0]
	s_nop 0
	v_pk_fma_f32 v[70:71], v[18:19], v[96:97], v[70:71] neg_lo:[1,0,0] neg_hi:[1,0,0]
	s_nop 0
	v_pk_fma_f32 v[70:71], v[20:21], v[98:99], v[70:71] neg_lo:[1,0,0] neg_hi:[1,0,0]
	s_nop 0
	v_pk_fma_f32 v[70:71], v[22:23], v[100:101], v[70:71] neg_lo:[1,0,0] neg_hi:[1,0,0]
	s_nop 0
	v_pk_fma_f32 v[70:71], v[24:25], v[102:103], v[70:71] neg_lo:[1,0,0] neg_hi:[1,0,0]
	s_nop 0
	v_pk_fma_f32 v[70:71], v[26:27], v[104:105], v[70:71] neg_lo:[1,0,0] neg_hi:[1,0,0]
	s_nop 0
	v_pk_fma_f32 v[70:71], v[28:29], v[106:107], v[70:71] neg_lo:[1,0,0] neg_hi:[1,0,0]
	s_nop 0
	v_pk_fma_f32 v[70:71], v[30:31], v[108:109], v[70:71] neg_lo:[1,0,0] neg_hi:[1,0,0]
	s_nop 0
	v_pk_fma_f32 v[70:71], v[32:33], v[110:111], v[70:71] neg_lo:[1,0,0] neg_hi:[1,0,0]
	s_nop 0
	v_pk_fma_f32 v[70:71], v[34:35], v[120:121], v[70:71] neg_lo:[1,0,0] neg_hi:[1,0,0]
	s_nop 0
	v_pk_fma_f32 v[70:71], v[36:37], v[122:123], v[70:71] neg_lo:[1,0,0] neg_hi:[1,0,0]
	s_nop 0
	v_pk_fma_f32 v[70:71], v[38:39], v[128:129], v[70:71] neg_lo:[1,0,0] neg_hi:[1,0,0]
	s_nop 0
	v_pk_fma_f32 v[70:71], v[40:41], v[130:131], v[70:71] neg_lo:[1,0,0] neg_hi:[1,0,0]
	s_nop 0
	v_pk_fma_f32 v[70:71], v[42:43], v[136:137], v[70:71] neg_lo:[1,0,0] neg_hi:[1,0,0]
	s_nop 0
	v_pk_fma_f32 v[70:71], v[44:45], v[138:139], v[70:71] neg_lo:[1,0,0] neg_hi:[1,0,0]
	s_nop 0
	v_pk_fma_f32 v[70:71], v[46:47], v[144:145], v[70:71] neg_lo:[1,0,0] neg_hi:[1,0,0]
	s_nop 0
	v_pk_fma_f32 v[70:71], v[48:49], v[146:147], v[70:71] neg_lo:[1,0,0] neg_hi:[1,0,0]
	s_nop 0
	v_pk_fma_f32 v[70:71], v[52:53], v[164:165], v[70:71] neg_lo:[1,0,0] neg_hi:[1,0,0]
	s_nop 0
	v_pk_fma_f32 v[70:71], v[54:55], v[166:167], v[70:71] neg_lo:[1,0,0] neg_hi:[1,0,0]
	s_nop 0
	v_pk_fma_f32 v[70:71], v[56:57], v[176:177], v[70:71] neg_lo:[1,0,0] neg_hi:[1,0,0]
	s_nop 0
	v_pk_fma_f32 v[70:71], v[58:59], v[178:179], v[70:71] neg_lo:[1,0,0] neg_hi:[1,0,0]
	s_nop 0
	v_pk_fma_f32 v[70:71], v[60:61], v[180:181], v[70:71] neg_lo:[1,0,0] neg_hi:[1,0,0]
	s_nop 0
	v_pk_fma_f32 v[70:71], v[62:63], v[182:183], v[70:71] neg_lo:[1,0,0] neg_hi:[1,0,0]
	s_nop 0
	v_pk_fma_f32 v[70:71], v[64:65], v[194:195], v[70:71] neg_lo:[1,0,0] neg_hi:[1,0,0]
	s_nop 0
	v_fma_f32 v0, -v196, v66, v70
	v_add_f32_e32 v67, v71, v0
	s_and_saveexec_b64 s[10:11], vcc
	s_xor_b64 s[10:11], exec, s[10:11]
	s_cbranch_execz .LBB0_530
; DI bf16_t f2bf(float x) { return (bf16_t)(pack2(x, 0.f) & 0xffffu); }
; DI void gdn_prep_item(const Params& P, int l, int n, int hh, char* smem) {
;     ...
;     } else {
;       const int pp = 32 * (cc >> 5) + perm32(cc & 31);
; #pragma unroll
;       for (int i = 0; i < 64; ++i) Wp[i * 128 + pp] = f2bf(x[i]);
;     }
	s_lshl_b64 s[12:13], s[8:9], 1
	v_lshl_add_u64 v[50:51], v[50:51], 0, s[12:13]
	s_movk_i32 s12, 0x60
	v_and_or_b32 v0, v82, s12, v68
	v_lshlrev_b32_e32 v0, 1, v0
	v_lshl_add_u64 v[50:51], v[50:51], 0, v[0:1]
	s_mov_b64 s[12:13], 0x1d2e8000
	v_lshl_add_u64 v[68:69], v[50:51], 0, s[12:13]
	v_cvt_pk_bf16_f32 v0, v3, s0
	global_store_short v[68:69], v0, off offset:256
	v_cvt_pk_bf16_f32 v0, v4, s0
	global_store_short v[68:69], v0, off offset:512
	v_cvt_pk_bf16_f32 v0, v5, s0
	global_store_short v[68:69], v0, off offset:768
	v_cvt_pk_bf16_f32 v0, v6, s0
	global_store_short v[68:69], v0, off offset:1024
	v_cvt_pk_bf16_f32 v0, v7, s0
	global_store_short v[68:69], v0, off offset:1280
	v_cvt_pk_bf16_f32 v0, v8, s0
	global_store_short v[68:69], v0, off offset:1536
	v_cvt_pk_bf16_f32 v0, v9, s0
	global_store_short v[68:69], v0, off offset:1792
	v_cvt_pk_bf16_f32 v0, v10, s0
	global_store_short v[68:69], v0, off offset:2048
	v_cvt_pk_bf16_f32 v0, v11, s0
	global_store_short v[68:69], v0, off offset:2304
	v_cvt_pk_bf16_f32 v0, v12, s0
	global_store_short v[68:69], v0, off offset:2560
	v_cvt_pk_bf16_f32 v0, v13, s0
	global_store_short v[68:69], v0, off offset:2816
	v_cvt_pk_bf16_f32 v0, v14, s0
	v_add_co_u32_e32 v70, vcc, 0x1d2e8000, v50
	global_store_short v[68:69], v0, off offset:3072
	v_cvt_pk_bf16_f32 v0, v15, s0
	v_cvt_pk_bf16_f32 v2, v2, s0
	v_addc_co_u32_e32 v71, vcc, 0, v51, vcc
	global_store_short v[68:69], v0, off offset:3328
	v_cvt_pk_bf16_f32 v0, v16, s0
	s_mov_b32 s12, 0x1d2e9000
	global_store_short v[70:71], v2, off
	global_store_short v[68:69], v0, off offset:3584
	v_cvt_pk_bf16_f32 v0, v17, s0
	v_add_co_u32_e32 v2, vcc, s12, v50
	global_store_short v[68:69], v0, off offset:3840
	v_cvt_pk_bf16_f32 v0, v18, s0
	v_addc_co_u32_e32 v3, vcc, 0, v51, vcc
	global_store_short v[2:3], v0, off
	v_cvt_pk_bf16_f32 v0, v19, s0
	global_store_short v[2:3], v0, off offset:256
	v_cvt_pk_bf16_f32 v0, v20, s0
	global_store_short v[2:3], v0, off offset:512
	v_cvt_pk_bf16_f32 v0, v21, s0
	global_store_short v[2:3], v0, off offset:768
	v_cvt_pk_bf16_f32 v0, v22, s0
	global_store_short v[2:3], v0, off offset:1024
	v_cvt_pk_bf16_f32 v0, v23, s0
	global_store_short v[2:3], v0, off offset:1280
	v_cvt_pk_bf16_f32 v0, v24, s0
	global_store_short v[2:3], v0, off offset:1536
	v_cvt_pk_bf16_f32 v0, v25, s0
	global_store_short v[2:3], v0, off offset:1792
	v_cvt_pk_bf16_f32 v0, v26, s0
	global_store_short v[2:3], v0, off offset:2048
	v_cvt_pk_bf16_f32 v0, v27, s0
	global_store_short v[2:3], v0, off offset:2304
	v_cvt_pk_bf16_f32 v0, v28, s0
	global_store_short v[2:3], v0, off offset:2560
	v_cvt_pk_bf16_f32 v0, v29, s0
	global_store_short v[2:3], v0, off offset:2816
	v_cvt_pk_bf16_f32 v0, v30, s0
	global_store_short v[2:3], v0, off offset:3072
	v_cvt_pk_bf16_f32 v0, v31, s0
	global_store_short v[2:3], v0, off offset:3328
	v_cvt_pk_bf16_f32 v0, v32, s0
	global_store_short v[2:3], v0, off offset:3584
	v_cvt_pk_bf16_f32 v0, v33, s0
	s_mov_b32 s12, 0x1d2ea000
	global_store_short v[2:3], v0, off offset:3840
	v_add_co_u32_e32 v2, vcc, s12, v50
	v_cvt_pk_bf16_f32 v0, v34, s0
	s_nop 0
	v_addc_co_u32_e32 v3, vcc, 0, v51, vcc
	global_store_short v[2:3], v0, off
	v_cvt_pk_bf16_f32 v0, v35, s0
	global_store_short v[2:3], v0, off offset:256
	v_cvt_pk_bf16_f32 v0, v36, s0
	global_store_short v[2:3], v0, off offset:512
	v_cvt_pk_bf16_f32 v0, v37, s0
	global_store_short v[2:3], v0, off offset:768
	v_cvt_pk_bf16_f32 v0, v38, s0
	global_store_short v[2:3], v0, off offset:1024
	v_cvt_pk_bf16_f32 v0, v39, s0
	global_store_short v[2:3], v0, off offset:1280
	v_cvt_pk_bf16_f32 v0, v40, s0
	global_store_short v[2:3], v0, off offset:1536
	v_cvt_pk_bf16_f32 v0, v41, s0
	global_store_short v[2:3], v0, off offset:1792
	v_cvt_pk_bf16_f32 v0, v42, s0
	global_store_short v[2:3], v0, off offset:2048
	v_cvt_pk_bf16_f32 v0, v43, s0
	global_store_short v[2:3], v0, off offset:2304
	v_cvt_pk_bf16_f32 v0, v44, s0
	global_store_short v[2:3], v0, off offset:2560
	v_cvt_pk_bf16_f32 v0, v45, s0
	global_store_short v[2:3], v0, off offset:2816
	v_cvt_pk_bf16_f32 v0, v46, s0
	global_store_short v[2:3], v0, off offset:3072
	v_cvt_pk_bf16_f32 v0, v47, s0
	global_store_short v[2:3], v0, off offset:3328
	v_cvt_pk_bf16_f32 v0, v48, s0
	global_store_short v[2:3], v0, off offset:3584
	v_cvt_pk_bf16_f32 v0, v49, s0
	s_mov_b32 s12, 0x1d2eb000
	global_store_short v[2:3], v0, off offset:3840
	v_add_co_u32_e32 v2, vcc, s12, v50
	v_cvt_pk_bf16_f32 v0, v52, s0
	s_nop 0
	v_addc_co_u32_e32 v3, vcc, 0, v51, vcc
	global_store_short v[2:3], v0, off
	v_cvt_pk_bf16_f32 v0, v53, s0
	global_store_short v[2:3], v0, off offset:256
	v_cvt_pk_bf16_f32 v0, v54, s0
	global_store_short v[2:3], v0, off offset:512
	v_cvt_pk_bf16_f32 v0, v55, s0
	global_store_short v[2:3], v0, off offset:768
	v_cvt_pk_bf16_f32 v0, v56, s0
	global_store_short v[2:3], v0, off offset:1024
	v_cvt_pk_bf16_f32 v0, v57, s0
	global_store_short v[2:3], v0, off offset:1280
	v_cvt_pk_bf16_f32 v0, v58, s0
	global_store_short v[2:3], v0, off offset:1536
	v_cvt_pk_bf16_f32 v0, v59, s0
	global_store_short v[2:3], v0, off offset:1792
	v_cvt_pk_bf16_f32 v0, v60, s0
	global_store_short v[2:3], v0, off offset:2048
	v_cvt_pk_bf16_f32 v0, v61, s0
	global_store_short v[2:3], v0, off offset:2304
	v_cvt_pk_bf16_f32 v0, v62, s0
	global_store_short v[2:3], v0, off offset:2560
	v_cvt_pk_bf16_f32 v0, v63, s0
	global_store_short v[2:3], v0, off offset:2816
	v_cvt_pk_bf16_f32 v0, v64, s0
	global_store_short v[2:3], v0, off offset:3072
	v_cvt_pk_bf16_f32 v0, v65, s0
	global_store_short v[2:3], v0, off offset:3328
	v_cvt_pk_bf16_f32 v0, v66, s0
	global_store_short v[2:3], v0, off offset:3584
	v_cvt_pk_bf16_f32 v0, v67, s0
	global_store_short v[2:3], v0, off offset:3840
; DI unsigned pack2(float lo, float hi) { f32x2 v = {lo, hi}; bf2_t b = __builtin_convertvector(v, bf2_t); return __builtin_bit_cast(unsigned, b); }
; DI void gdn_prep_item(const Params& P, int l, int n, int hh, char* smem) {
;     ...
;     if (isu) {
; #pragma unroll
;       for (int i8 = 0; i8 < 8; ++i8) { u32x4 v = {pack2(x[8 * i8], x[8 * i8 + 1]), pack2(x[8 * i8 + 2], x[8 * i8 + 3]), pack2(x[8 * i8 + 4], x[8 * i8 + 5]), pack2(x[8 * i8 + 6], x[8 * i8 + 7])}; *(u32x4*)(Ut + cc * 64 + 8 * i8) = v; }
.LBB0_530:
	s_andn2_saveexec_b64 s[10:11], s[10:11]
	s_cbranch_execz .LBB0_418
	s_lshl_b64 s[8:9], s[8:9], 1
	v_lshl_add_u64 v[50:51], v[50:51], 0, s[8:9]
	v_lshlrev_b32_e32 v0, 7, v69
	v_lshl_add_u64 v[50:51], v[50:51], 0, v[0:1]
	s_mov_b64 s[8:9], 0x282e8000
	v_lshl_add_u64 v[68:69], v[50:51], 0, s[8:9]
	s_mov_b32 s8, 0x282e8000
	v_cvt_pk_bf16_f32 v2, v2, v3
	v_cvt_pk_bf16_f32 v3, v4, v5
	v_cvt_pk_bf16_f32 v4, v6, v7
	v_add_co_u32_e32 v6, vcc, s8, v50
	v_cvt_pk_bf16_f32 v5, v8, v9
	s_nop 0
	v_addc_co_u32_e32 v7, vcc, 0, v51, vcc
	global_store_dwordx4 v[6:7], v[2:5], off
	s_nop 1
	v_cvt_pk_bf16_f32 v2, v10, v11
	v_cvt_pk_bf16_f32 v3, v12, v13
	v_cvt_pk_bf16_f32 v4, v14, v15
	v_cvt_pk_bf16_f32 v5, v16, v17
	global_store_dwordx4 v[68:69], v[2:5], off offset:16
	s_nop 1
	v_cvt_pk_bf16_f32 v2, v18, v19
	v_cvt_pk_bf16_f32 v3, v20, v21
	v_cvt_pk_bf16_f32 v4, v22, v23
	v_cvt_pk_bf16_f32 v5, v24, v25
	global_store_dwordx4 v[68:69], v[2:5], off offset:32
	s_nop 1
	v_cvt_pk_bf16_f32 v2, v26, v27
	v_cvt_pk_bf16_f32 v3, v28, v29
	v_cvt_pk_bf16_f32 v4, v30, v31
	v_cvt_pk_bf16_f32 v5, v32, v33
	global_store_dwordx4 v[68:69], v[2:5], off offset:48
	s_nop 1
	v_cvt_pk_bf16_f32 v2, v34, v35
	v_cvt_pk_bf16_f32 v3, v36, v37
	v_cvt_pk_bf16_f32 v4, v38, v39
	v_cvt_pk_bf16_f32 v5, v40, v41
	global_store_dwordx4 v[68:69], v[2:5], off offset:64
	s_nop 1
	v_cvt_pk_bf16_f32 v2, v42, v43
	v_cvt_pk_bf16_f32 v3, v44, v45
	v_cvt_pk_bf16_f32 v4, v46, v47
	v_cvt_pk_bf16_f32 v5, v48, v49
	global_store_dwordx4 v[68:69], v[2:5], off offset:80
	s_nop 1
	v_cvt_pk_bf16_f32 v2, v52, v53
	v_cvt_pk_bf16_f32 v3, v54, v55
	v_cvt_pk_bf16_f32 v4, v56, v57
	v_cvt_pk_bf16_f32 v5, v58, v59
	global_store_dwordx4 v[68:69], v[2:5], off offset:96
	s_nop 1
	v_cvt_pk_bf16_f32 v2, v60, v61
	v_cvt_pk_bf16_f32 v3, v62, v63
	v_cvt_pk_bf16_f32 v4, v64, v65
	v_cvt_pk_bf16_f32 v5, v66, v67
	global_store_dwordx4 v[68:69], v[2:5], off offset:112
	s_branch .LBB0_418

; DI int opaque_tid() { int t = threadIdx.x; asm volatile("" : "+v"(t)); return t; }
; DI void swa_item(const Params& P, int l, int n, int hk2, char* smem) {
;   const int tid = opaque_tid(), lane = tid & 63, w = tid >> 6, lq = lane & 31, h = lane >> 5;
;   const bf16_t* proj = (const bf16_t*)(P.ws + OFF_PROJ); bf16_t* mixin = (bf16_t*)(P.ws + OFF_H);
;   bf16_t* sVt = (bf16_t*)smem;
; #pragma unroll
;   for (int i = 0; i < 4; ++i) { const int id = tid + NT * i, key = id >> 3, dc = id & 7; const int kp = 128 * (n - 1) + key;
;     u32x4 v = {0u, 0u, 0u, 0u}; if (kp >= 0) v = *(const u32x4*)(proj + (size_t)kp * DINP + C_CV + hk2 * 64 + dc * 8);
;     sVt[(8 * dc + 0) * 264 + key] = (bf16_t)(v.x & 0xffff); sVt[(8 * dc + 1) * 264 + key] = (bf16_t)(v.x >> 16);
;     sVt[(8 * dc + 2) * 264 + key] = (bf16_t)(v.y & 0xffff); sVt[(8 * dc + 3) * 264 + key] = (bf16_t)(v.y >> 16);
;     sVt[(8 * dc + 4) * 264 + key] = (bf16_t)(v.z & 0xffff); sVt[(8 * dc + 5) * 264 + key] = (bf16_t)(v.z >> 16);
;     sVt[(8 * dc + 6) * 264 + key] = (bf16_t)(v.w & 0xffff); sVt[(8 * dc + 7) * 264 + key] = (bf16_t)(v.w >> 16); }
;   __syncthreads();
;   const int g = w >> 1, hq = hk2 * 4 + g;
;   const float slope = exp2f(-(float)(hq + 1)) * LOG2E, sinkv = P.swa_sinks[l * 8 + hq] * LOG2E;
; #pragma unroll 1
;   for (int jj = 0; jj < 2; ++jj) {
;     const int j = 2 * (w & 1) + jj; const int qrow = 128 * n + 32 * j + lq;
; __global__ void __launch_bounds__(NT) fwd_megakernel(Params P0) {
;     ...
;         if (tid == 0) *sitem = atomicAdd(ctrl + 16 * l, 1);
;         __syncthreads(); const int item = *sitem; __syncthreads();
;         if (item >= 16 + 512 + 256) break;
;         if (item < 16) gdn_scan_item(P, l, item >> 1, item & 1, smem);
;         else if (item < 528) { const int idx = item - 16; mla_attn_item(P, idx & 3, 127 - (idx >> 2), smem); }
;         else { const int idx = item - 528; swa_item(P, l, idx >> 1, idx & 1, smem); }
.LBB0_593:
	s_or_b64 exec, exec, s[2:3]
	s_waitcnt lgkmcnt(0)
	s_barrier
	ds_read_b32 v0, v238
	s_movk_i32 s2, 0x30f
	s_waitcnt lgkmcnt(0)
	s_barrier
	v_cmp_lt_i32_e32 vcc, s2, v0
	v_readfirstlane_b32 s96, v0
	s_mov_b64 s[2:3], -1
	s_cbranch_vccnz .LBB0_588
	s_cmp_gt_i32 s96, 15
	s_cbranch_scc0 .LBB0_661
	s_cmpk_gt_u32 s96, 0x20f
	s_cbranch_scc0 .LBB0_640
	v_mov_b32_e32 v8, v206
	global_load_dwordx2 v[102:103], v1, s[40:41] offset:1224
	s_add_i32 s4, s96, 0xfffffdf0
	s_lshl_b32 s2, s4, 6
	s_and_b32 s8, s2, 0x7fffff80
	v_and_b32_e32 v9, 7, v8
	v_ashrrev_i32_e32 v3, 3, v8
	s_add_i32 s11, s8, 0xffffff80
	s_and_b32 s5, s96, 1
	v_lshlrev_b32_e32 v0, 3, v9
	v_add_u32_e32 v10, s11, v3
	v_mov_b32_e32 v2, 0
	v_mov_b32_e32 v4, 0
	v_mov_b32_e32 v5, 0
	v_mov_b32_e32 v6, 0
	s_lshl_b32 s10, s5, 6
	v_lshlrev_b32_e32 v0, 1, v0
	v_cmp_lt_i32_e32 vcc, -1, v10
	v_mov_b32_e32 v7, 0
	s_waitcnt vmcnt(0)
	v_lshl_add_u64 v[104:105], v[102:103], 0, s[30:31]
	s_and_saveexec_b64 s[2:3], vcc
	s_cbranch_execz .LBB0_598
	v_mad_u64_u32 v[4:5], s[12:13], v10, s81, v[104:105]
	s_lshl_b32 s62, s10, 1
	v_lshl_add_u64 v[4:5], v[4:5], 0, s[62:63]
	v_lshl_add_u64 v[4:5], v[4:5], 0, v[0:1]
	v_add_co_u32_e32 v4, vcc, 0x2000, v4
	s_nop 1
	v_addc_co_u32_e32 v5, vcc, 0, v5, vcc
	global_load_dwordx4 v[4:7], v[4:5], off offset:2592
.LBB0_598:
	s_or_b64 exec, exec, s[2:3]
	v_lshlrev_b32_e32 v3, 1, v3
	s_movk_i32 s2, 0x1080
	v_mad_u32_u24 v3, v9, s2, v3
	s_waitcnt vmcnt(0) lgkmcnt(0)
	ds_write_b16 v3, v4
	ds_write_b16_d16_hi v3, v4 offset:528
	ds_write_b16 v3, v5 offset:1056
	ds_write_b16_d16_hi v3, v5 offset:1584
	ds_write_b16 v3, v6 offset:2112
	ds_write_b16_d16_hi v3, v6 offset:2640
	ds_write_b16 v3, v7 offset:3168
	ds_write_b16_d16_hi v3, v7 offset:3696
	v_add_u32_e32 v3, 0x200, v8
	v_ashrrev_i32_e32 v6, 3, v3
	v_add_u32_e32 v7, s11, v6
	v_cmp_lt_i32_e32 vcc, -1, v7
	v_mov_b32_e32 v3, 0
	v_mov_b32_e32 v4, 0
	v_mov_b32_e32 v5, 0
	s_and_saveexec_b64 s[2:3], vcc
	s_cbranch_execz .LBB0_600
	v_mad_u64_u32 v[2:3], s[12:13], v7, s81, v[104:105]
	s_lshl_b32 s62, s10, 1
	v_lshl_add_u64 v[2:3], v[2:3], 0, s[62:63]
	v_lshl_add_u64 v[2:3], v[2:3], 0, v[0:1]
	v_add_co_u32_e32 v2, vcc, 0x2000, v2
	s_nop 1
	v_addc_co_u32_e32 v3, vcc, 0, v3, vcc
	global_load_dwordx4 v[2:5], v[2:3], off offset:2592
.LBB0_600:
	s_or_b64 exec, exec, s[2:3]
	v_mul_u32_u24_e32 v9, 0x1080, v9
	v_lshl_add_u32 v6, v6, 1, v9
	s_waitcnt vmcnt(0) lgkmcnt(0)
	ds_write_b16 v6, v2
	ds_write_b16_d16_hi v6, v2 offset:528
	ds_write_b16 v6, v3 offset:1056
	ds_write_b16_d16_hi v6, v3 offset:1584
	ds_write_b16 v6, v4 offset:2112
	ds_write_b16_d16_hi v6, v4 offset:2640
	ds_write_b16 v6, v5 offset:3168
	ds_write_b16_d16_hi v6, v5 offset:3696
	v_add_u32_e32 v2, 0x400, v8
	v_ashrrev_i32_e32 v3, 3, v2
	v_add_u32_e32 v10, s11, v3
	v_cmp_lt_i32_e32 vcc, -1, v10
	v_mov_b32_e32 v2, 0
	v_mov_b32_e32 v4, 0
	v_mov_b32_e32 v5, 0
	v_mov_b32_e32 v6, 0
	v_mov_b32_e32 v7, 0
	s_and_saveexec_b64 s[2:3], vcc
	s_cbranch_execz .LBB0_602
	v_mad_u64_u32 v[4:5], s[12:13], v10, s81, v[104:105]
	s_lshl_b32 s62, s10, 1
	v_lshl_add_u64 v[4:5], v[4:5], 0, s[62:63]
	v_lshl_add_u64 v[4:5], v[4:5], 0, v[0:1]
	v_add_co_u32_e32 v4, vcc, 0x2000, v4
	s_nop 1
	v_addc_co_u32_e32 v5, vcc, 0, v5, vcc
	global_load_dwordx4 v[4:7], v[4:5], off offset:2592
.LBB0_602:
	s_or_b64 exec, exec, s[2:3]
	v_lshl_add_u32 v3, v3, 1, v9
	s_waitcnt vmcnt(0) lgkmcnt(0)
	ds_write_b16 v3, v4
	ds_write_b16_d16_hi v3, v4 offset:528
	ds_write_b16 v3, v5 offset:1056
	ds_write_b16_d16_hi v3, v5 offset:1584
	ds_write_b16 v3, v6 offset:2112
	ds_write_b16_d16_hi v3, v6 offset:2640
	ds_write_b16 v3, v7 offset:3168
	ds_write_b16_d16_hi v3, v7 offset:3696
	v_add_u32_e32 v3, 0x600, v8
	v_ashrrev_i32_e32 v6, 3, v3
	v_add_u32_e32 v7, s11, v6
	v_cmp_lt_i32_e32 vcc, -1, v7
	s_mov_b32 s15, 0
	v_mov_b32_e32 v3, 0
	v_mov_b32_e32 v4, 0
	v_mov_b32_e32 v5, 0
	s_and_saveexec_b64 s[2:3], vcc
	s_cbranch_execz .LBB0_604
	v_mad_u64_u32 v[2:3], s[12:13], v7, s81, v[104:105]
	s_lshl_b32 s62, s10, 1
	v_lshl_add_u64 v[2:3], v[2:3], 0, s[62:63]
	v_lshl_add_u64 v[2:3], v[2:3], 0, v[0:1]
	v_add_co_u32_e32 v2, vcc, 0x2000, v2
	s_nop 1
	v_addc_co_u32_e32 v3, vcc, 0, v3, vcc
	global_load_dwordx4 v[2:5], v[2:3], off offset:2592
.LBB0_604:
	s_or_b64 exec, exec, s[2:3]
	v_lshl_add_u32 v6, v6, 1, v9
	s_waitcnt vmcnt(0) lgkmcnt(0)
	ds_write_b16 v6, v2
	ds_write_b16_d16_hi v6, v2 offset:528
	ds_write_b16 v6, v3 offset:1056
	ds_write_b16_d16_hi v6, v3 offset:1584
	ds_write_b16 v6, v4 offset:2112
	ds_write_b16_d16_hi v6, v4 offset:2640
	ds_write_b16 v6, v5 offset:3168
	ds_write_b16_d16_hi v6, v5 offset:3696
	v_ashrrev_i32_e32 v2, 7, v8
	v_lshl_add_u32 v7, s5, 2, v2
	v_add_u32_e32 v2, 1, v7
	v_cvt_f32_i32_e32 v2, v2
	s_mov_b32 s2, 0x42fc0000
	s_waitcnt lgkmcnt(0)
	s_barrier
	v_cmp_lt_f32_e32 vcc, s2, v2
	v_readlane_b32 s2, v255, 52
	s_nop 0
	v_cndmask_b32_e32 v3, 0, v242, vcc
	v_sub_f32_e32 v2, v3, v2
	v_exp_f32_e32 v2, v2
	v_cndmask_b32_e32 v3, 0, v243, vcc
	v_add_u32_e32 v4, s2, v7
	v_ashrrev_i32_e32 v5, 31, v4
	v_ldexp_f32 v2, v2, v3
	v_mul_f32_e32 v107, 0x3fb8aa3b, v2
	global_load_dwordx2 v[2:3], v1, s[40:41] offset:1160
	v_and_b32_e32 v111, 31, v8
	v_bfe_u32 v6, v8, 5, 1
	v_lshrrev_b32_e32 v0, 5, v8
	v_lshlrev_b32_e32 v110, 2, v6
	v_and_b32_e32 v115, 2, v0
	v_lshlrev_b32_e32 v108, 6, v7
	v_lshlrev_b32_e32 v0, 3, v6
	s_cmp_gt_u32 s4, 1
	v_or_b32_e32 v116, s8, v111
	v_ashrrev_i32_e32 v109, 31, v108
	s_cselect_b64 s[4:5], -1, 0
	s_add_i32 s12, s8, 0xffffffa0
	s_sub_i32 s13, s8, 64
	s_sub_i32 s14, s8, 32
	s_mov_b64 s[8:9], -1
	v_lshlrev_b32_e32 v112, 1, v0
	s_waitcnt vmcnt(0)
	v_lshl_add_u64 v[2:3], v[4:5], 2, v[2:3]
	global_load_dword v2, v[2:3], off
	s_waitcnt vmcnt(0) lgkmcnt(0)
	v_mul_f32_e32 v114, 0x3fb8aa3b, v2
	v_or_b32_e32 v2, 0x80, v111
	v_sub_u32_e32 v117, v2, v110
	v_mul_u32_u24_e32 v2, 0x210, v111
	v_or_b32_e32 v118, v0, v2
	s_branch .LBB0_606
; #define MFMA32(a, b, c) __builtin_amdgcn_mfma_f32_32x32x16_bf16((a), (b), (c), 0, 0, 0)
; DI void swa_item(const Params& P, int l, int n, int hk2, char* smem) {
;     ...
; #pragma unroll
;     for (int tt = 0; tt < 5; ++tt) {
;       if (tt + 1 < 5) { const int kp = 128 * (n - 1) + 32 * (j + tt + 1) + lq;
; #pragma unroll
;         for (int s = 0; s < 4; ++s) { kf[(tt + 1) & 1][s] = (bf16x8){0, 0, 0, 0, 0, 0, 0, 0}; if (kp >= 0) kf[(tt + 1) & 1][s] = *(const bf16x8*)(proj + (size_t)kp * DINP + C_CK + hk2 * 64 + 16 * s + 8 * h); } }
;       __builtin_amdgcn_sched_barrier(0);
; #pragma unroll
;       for (int r = 0; r < 16; ++r) st[tt][r] = 0.f;
; #pragma unroll
;       for (int s = 0; s < 4; ++s) st[tt] = MFMA32(kf[tt & 1][s], qf[s], st[tt]);
;       __builtin_amdgcn_sched_barrier(0);
;     }
;     float mx = sinkv;
;     int dbase = 128 + lq - 4 * h, kbase = 128 * (n - 1) + 32 * j + 4 * h;
;     asm volatile("" : "+v"(dbase), "+v"(kbase));
; #pragma unroll
;     for (int tt = 0; tt < 5; ++tt)
; #pragma unroll
;       for (int r = 0; r < 16; ++r) { const int cst = 32 * tt + (r & 3) + 8 * (r >> 2); const int dist = dbase - cst; const int kpos = kbase + cst;
;         const bool valid = (dist >= 0) && (dist < 128) && (kpos >= 0);
;         const float sv = valid ? st[tt][r] * (0.125f * LOG2E) - slope * (float)dist : -1e30f; st[tt][r] = sv; mx = fmaxf(mx, sv); }
.LBB0_605:
	s_or_b64 exec, exec, s[2:3]
	s_xor_b64 s[8:9], s[8:9], -1
	s_waitcnt vmcnt(0) lgkmcnt(0)
	v_mfma_f32_32x32x16_bf16 v[34:49], v[10:13], v[2:5], 0
	v_mfma_f32_32x32x16_bf16 v[34:49], v[6:9], v[90:93], v[34:49]
	v_mfma_f32_32x32x16_bf16 v[34:49], v[26:29], v[82:85], v[34:49]
	v_mfma_f32_32x32x16_bf16 v[34:49], v[22:25], v[86:89], v[34:49]
	v_mul_lo_u32 v0, v119, s81
	v_lshl_add_u64 v[6:7], v[104:105], 0, v[0:1]
	v_lshl_add_u64 v[6:7], v[6:7], 0, s[62:63]
	v_mov_b32_e32 v113, v1
	v_lshl_add_u64 v[6:7], v[6:7], 0, v[112:113]
	v_lshl_add_u64 v[10:11], v[6:7], 0, s[58:59]
	v_add_co_u32_e32 v6, vcc, s83, v6
	s_mov_b32 s15, 1
	s_nop 0
	v_addc_co_u32_e32 v7, vcc, 0, v7, vcc
	global_load_dwordx4 v[122:125], v[10:11], off offset:32
	global_load_dwordx4 v[126:129], v[10:11], off offset:64
	s_nop 0
	global_load_dwordx4 v[6:9], v[6:7], off offset:2336
	s_nop 0
	global_load_dwordx4 v[130:133], v[10:11], off offset:96
	v_mfma_f32_32x32x16_bf16 v[18:33], v[18:21], v[2:5], 0
	v_mfma_f32_32x32x16_bf16 v[18:33], v[14:17], v[90:93], v[18:33]
	v_mfma_f32_32x32x16_bf16 v[18:33], v[98:101], v[82:85], v[18:33]
	v_mfma_f32_32x32x16_bf16 v[18:33], v[94:97], v[86:89], v[18:33]
	s_waitcnt vmcnt(0) lgkmcnt(0)
	v_mfma_f32_32x32x16_bf16 v[2:17], v[6:9], v[2:5], 0
	v_mfma_f32_32x32x16_bf16 v[2:17], v[122:125], v[90:93], v[2:17]
	v_mfma_f32_32x32x16_bf16 v[2:17], v[126:129], v[82:85], v[2:17]
	v_mfma_f32_32x32x16_bf16 v[2:17], v[130:133], v[86:89], v[2:17]
	v_or_b32_e32 v0, v106, v110
	v_mov_b32_e32 v82, v117
	v_mov_b32_e32 v106, v66
	v_cvt_f32_i32_e32 v209, v82
	v_subrev_co_u32_e32 v83, vcc, s55, v82
	v_cmp_lt_i32_e64 s[2:3], -1, v0
	v_pk_mul_f32 v[84:85], v[106:107], v[208:209]
	s_and_b64 vcc, vcc, s[2:3]
	v_sub_f32_e32 v66, v84, v85
	v_add_u32_e32 v84, -1, v82
	v_cvt_f32_i32_e32 v209, v84
	v_mov_b32_e32 v106, v67
	v_cndmask_b32_e32 v66, v244, v66, vcc
	v_cmp_gt_u32_e32 vcc, s55, v84
	v_pk_mul_f32 v[84:85], v[106:107], v[208:209]
	v_cmp_lt_i32_e64 s[2:3], -2, v0
	v_sub_f32_e32 v67, v84, v85
	v_add_u32_e32 v84, -2, v82
	v_cvt_f32_i32_e32 v209, v84
	s_and_b64 vcc, vcc, s[2:3]
	v_mov_b32_e32 v106, v68
	v_cndmask_b32_e32 v67, v244, v67, vcc
	v_cmp_gt_u32_e32 vcc, s55, v84
	v_pk_mul_f32 v[84:85], v[106:107], v[208:209]
	v_cmp_lt_i32_e64 s[2:3], -3, v0
	v_sub_f32_e32 v68, v84, v85
	v_add_u32_e32 v84, -3, v82
	v_cvt_f32_i32_e32 v209, v84
	s_and_b64 vcc, vcc, s[2:3]
	v_mov_b32_e32 v106, v69
	v_cndmask_b32_e32 v68, v244, v68, vcc
	v_cmp_gt_u32_e32 vcc, s55, v84
	v_pk_mul_f32 v[84:85], v[106:107], v[208:209]
	v_cmp_lt_i32_e64 s[2:3], -4, v0
	v_sub_f32_e32 v69, v84, v85
	v_add_u32_e32 v84, -8, v82
	v_cvt_f32_i32_e32 v209, v84
	s_and_b64 vcc, vcc, s[2:3]
	v_mov_b32_e32 v106, v70
	v_cndmask_b32_e32 v69, v244, v69, vcc
	v_cmp_gt_u32_e32 vcc, s55, v84
	v_pk_mul_f32 v[84:85], v[106:107], v[208:209]
	v_cmp_lt_i32_e64 s[2:3], -9, v0
	v_sub_f32_e32 v70, v84, v85
	v_add_u32_e32 v84, -9, v82
	v_cvt_f32_i32_e32 v209, v84
	s_and_b64 vcc, vcc, s[2:3]
	v_mov_b32_e32 v106, v71
	v_cndmask_b32_e32 v70, v244, v70, vcc
	v_cmp_gt_u32_e32 vcc, s55, v84
	v_pk_mul_f32 v[84:85], v[106:107], v[208:209]
	v_cmp_lt_i32_e64 s[2:3], -10, v0
	v_sub_f32_e32 v71, v84, v85
	v_add_u32_e32 v84, -10, v82
	v_cvt_f32_i32_e32 v209, v84
	s_and_b64 vcc, vcc, s[2:3]
	v_mov_b32_e32 v106, v72
	v_cndmask_b32_e32 v71, v244, v71, vcc
	v_cmp_gt_u32_e32 vcc, s55, v84
	v_pk_mul_f32 v[84:85], v[106:107], v[208:209]
	v_cmp_lt_i32_e64 s[2:3], -11, v0
	v_sub_f32_e32 v72, v84, v85
	v_add_u32_e32 v84, -11, v82
	v_cvt_f32_i32_e32 v209, v84
	s_and_b64 vcc, vcc, s[2:3]
	v_mov_b32_e32 v106, v73
	v_cndmask_b32_e32 v72, v244, v72, vcc
	v_cmp_gt_u32_e32 vcc, s55, v84
	v_pk_mul_f32 v[84:85], v[106:107], v[208:209]
	v_cmp_lt_i32_e64 s[2:3], -12, v0
	v_sub_f32_e32 v73, v84, v85
	v_add_u32_e32 v84, -16, v82
	v_cvt_f32_i32_e32 v209, v84
	s_and_b64 vcc, vcc, s[2:3]
	v_mov_b32_e32 v106, v74
	v_cndmask_b32_e32 v73, v244, v73, vcc
	v_cmp_gt_u32_e32 vcc, s55, v84
	v_pk_mul_f32 v[84:85], v[106:107], v[208:209]
	s_movk_i32 s2, 0xffef
	v_sub_f32_e32 v74, v84, v85
	v_subrev_u32_e32 v84, 17, v82
	v_cvt_f32_i32_e32 v209, v84
	v_cmp_lt_i32_e64 s[2:3], s2, v0
	s_and_b64 vcc, vcc, s[2:3]
	v_mov_b32_e32 v106, v75
	v_cndmask_b32_e32 v74, v244, v74, vcc
	v_cmp_gt_u32_e32 vcc, s55, v84
	v_pk_mul_f32 v[84:85], v[106:107], v[208:209]
	s_movk_i32 s2, 0xffee
	v_sub_f32_e32 v75, v84, v85
	v_subrev_u32_e32 v84, 18, v82
	v_cvt_f32_i32_e32 v209, v84
	v_cmp_lt_i32_e64 s[2:3], s2, v0
	s_and_b64 vcc, vcc, s[2:3]
	v_mov_b32_e32 v106, v76
	v_cndmask_b32_e32 v75, v244, v75, vcc
	v_cmp_gt_u32_e32 vcc, s55, v84
	v_pk_mul_f32 v[84:85], v[106:107], v[208:209]
	s_movk_i32 s2, 0xffed
	v_sub_f32_e32 v76, v84, v85
	v_subrev_u32_e32 v84, 19, v82
	v_cvt_f32_i32_e32 v209, v84
	v_cmp_lt_i32_e64 s[2:3], s2, v0
	s_and_b64 vcc, vcc, s[2:3]
	v_mov_b32_e32 v106, v77
	v_cndmask_b32_e32 v76, v244, v76, vcc
	v_cmp_gt_u32_e32 vcc, s55, v84
	v_pk_mul_f32 v[84:85], v[106:107], v[208:209]
	s_movk_i32 s2, 0xffec
	v_sub_f32_e32 v77, v84, v85
	v_subrev_u32_e32 v84, 24, v82
	v_cvt_f32_i32_e32 v209, v84
	v_cmp_lt_i32_e64 s[2:3], s2, v0
	s_and_b64 vcc, vcc, s[2:3]
	v_mov_b32_e32 v106, v78
	v_cndmask_b32_e32 v77, v244, v77, vcc
	v_cmp_gt_u32_e32 vcc, s55, v84
	v_pk_mul_f32 v[84:85], v[106:107], v[208:209]
	s_movk_i32 s2, 0xffe7
	v_sub_f32_e32 v78, v84, v85
	v_subrev_u32_e32 v84, 25, v82
	v_cvt_f32_i32_e32 v209, v84
	v_cmp_lt_i32_e64 s[2:3], s2, v0
	s_and_b64 vcc, vcc, s[2:3]
	v_mov_b32_e32 v106, v79
	v_cndmask_b32_e32 v78, v244, v78, vcc
	v_cmp_gt_u32_e32 vcc, s55, v84
	v_pk_mul_f32 v[84:85], v[106:107], v[208:209]
	s_movk_i32 s2, 0xffe6
	v_sub_f32_e32 v79, v84, v85
	v_subrev_u32_e32 v84, 26, v82
; DI void swa_item(const Params& P, int l, int n, int hk2, char* smem) {
;     ...
; #pragma unroll
;     for (int tt = 0; tt < 5; ++tt)
; #pragma unroll
;       for (int r = 0; r < 16; ++r) { const int cst = 32 * tt + (r & 3) + 8 * (r >> 2); const int dist = dbase - cst; const int kpos = kbase + cst;
;         const bool valid = (dist >= 0) && (dist < 128) && (kpos >= 0);
;         const float sv = valid ? st[tt][r] * (0.125f * LOG2E) - slope * (float)dist : -1e30f; st[tt][r] = sv; mx = fmaxf(mx, sv); }
	v_cvt_f32_i32_e32 v209, v84
	v_cmp_lt_i32_e64 s[2:3], s2, v0
	s_and_b64 vcc, vcc, s[2:3]
	v_mov_b32_e32 v106, v80
	v_cndmask_b32_e32 v79, v244, v79, vcc
	v_cmp_gt_u32_e32 vcc, s55, v84
	v_pk_mul_f32 v[84:85], v[106:107], v[208:209]
	s_movk_i32 s2, 0xffe5
	v_sub_f32_e32 v80, v84, v85
	v_subrev_u32_e32 v84, 27, v82
	v_cvt_f32_i32_e32 v209, v84
	v_cmp_lt_i32_e64 s[2:3], s2, v0
	s_and_b64 vcc, vcc, s[2:3]
	v_mov_b32_e32 v106, v81
	v_cndmask_b32_e32 v80, v244, v80, vcc
	v_cmp_gt_u32_e32 vcc, s55, v84
	v_pk_mul_f32 v[84:85], v[106:107], v[208:209]
	s_movk_i32 s2, 0xffe4
	v_sub_f32_e32 v81, v84, v85
	v_subrev_u32_e32 v84, 32, v82
	v_cvt_f32_i32_e32 v209, v84
	v_cmp_lt_i32_e64 s[2:3], s2, v0
	s_and_b64 vcc, vcc, s[2:3]
	v_mov_b32_e32 v106, v50
	v_cndmask_b32_e32 v81, v244, v81, vcc
	v_cmp_gt_u32_e32 vcc, s55, v84
	v_pk_mul_f32 v[84:85], v[106:107], v[208:209]
	s_movk_i32 s2, 0xffdf
	v_sub_f32_e32 v50, v84, v85
	v_subrev_u32_e32 v84, 33, v82
	v_cvt_f32_i32_e32 v209, v84
	v_cmp_lt_i32_e64 s[2:3], s2, v0
	s_and_b64 vcc, vcc, s[2:3]
	v_mov_b32_e32 v106, v51
	v_cndmask_b32_e32 v50, v244, v50, vcc
	v_cmp_gt_u32_e32 vcc, s55, v84
	v_pk_mul_f32 v[84:85], v[106:107], v[208:209]
	s_movk_i32 s2, 0xffde
	v_sub_f32_e32 v51, v84, v85
	v_subrev_u32_e32 v84, 34, v82
	v_cvt_f32_i32_e32 v209, v84
	v_cmp_lt_i32_e64 s[2:3], s2, v0
	s_and_b64 vcc, vcc, s[2:3]
	v_mov_b32_e32 v106, v52
	v_cndmask_b32_e32 v51, v244, v51, vcc
	v_cmp_gt_u32_e32 vcc, s55, v84
	v_pk_mul_f32 v[84:85], v[106:107], v[208:209]
	s_movk_i32 s2, 0xffdd
	v_sub_f32_e32 v52, v84, v85
	v_subrev_u32_e32 v84, 35, v82
	v_cvt_f32_i32_e32 v209, v84
	v_cmp_lt_i32_e64 s[2:3], s2, v0
	s_and_b64 vcc, vcc, s[2:3]
	v_mov_b32_e32 v106, v53
	v_cndmask_b32_e32 v52, v244, v52, vcc
	v_cmp_gt_u32_e32 vcc, s55, v84
	v_pk_mul_f32 v[84:85], v[106:107], v[208:209]
	s_movk_i32 s2, 0xffdc
	v_sub_f32_e32 v53, v84, v85
	v_subrev_u32_e32 v84, 40, v82
	v_cvt_f32_i32_e32 v209, v84
	v_cmp_lt_i32_e64 s[2:3], s2, v0
	s_and_b64 vcc, vcc, s[2:3]
	v_mov_b32_e32 v106, v54
	v_cndmask_b32_e32 v53, v244, v53, vcc
	v_cmp_gt_u32_e32 vcc, s55, v84
	v_pk_mul_f32 v[84:85], v[106:107], v[208:209]
	s_movk_i32 s2, 0xffd7
	v_sub_f32_e32 v54, v84, v85
	v_subrev_u32_e32 v84, 41, v82
	v_cvt_f32_i32_e32 v209, v84
	v_cmp_lt_i32_e64 s[2:3], s2, v0
	s_and_b64 vcc, vcc, s[2:3]
	v_mov_b32_e32 v106, v55
	v_cndmask_b32_e32 v54, v244, v54, vcc
	v_cmp_gt_u32_e32 vcc, s55, v84
	v_pk_mul_f32 v[84:85], v[106:107], v[208:209]
	s_movk_i32 s2, 0xffd6
	v_sub_f32_e32 v55, v84, v85
	v_subrev_u32_e32 v84, 42, v82
	v_cvt_f32_i32_e32 v209, v84
	v_cmp_lt_i32_e64 s[2:3], s2, v0
	s_and_b64 vcc, vcc, s[2:3]
	v_mov_b32_e32 v106, v56
	v_cndmask_b32_e32 v55, v244, v55, vcc
	v_cmp_gt_u32_e32 vcc, s55, v84
	v_pk_mul_f32 v[84:85], v[106:107], v[208:209]
	s_movk_i32 s2, 0xffd5
	v_sub_f32_e32 v56, v84, v85
	v_subrev_u32_e32 v84, 43, v82
	v_cvt_f32_i32_e32 v209, v84
	v_cmp_lt_i32_e64 s[2:3], s2, v0
	s_and_b64 vcc, vcc, s[2:3]
	v_mov_b32_e32 v106, v57
	v_cndmask_b32_e32 v56, v244, v56, vcc
	v_cmp_gt_u32_e32 vcc, s55, v84
	v_pk_mul_f32 v[84:85], v[106:107], v[208:209]
	s_movk_i32 s2, 0xffd4
	v_sub_f32_e32 v57, v84, v85
	v_subrev_u32_e32 v84, 48, v82
	v_cvt_f32_i32_e32 v209, v84
	v_cmp_lt_i32_e64 s[2:3], s2, v0
	s_and_b64 vcc, vcc, s[2:3]
	v_mov_b32_e32 v106, v58
	v_cndmask_b32_e32 v57, v244, v57, vcc
	v_cmp_gt_u32_e32 vcc, s55, v84
	v_pk_mul_f32 v[84:85], v[106:107], v[208:209]
	s_movk_i32 s2, 0xffcf
	v_sub_f32_e32 v58, v84, v85
	v_subrev_u32_e32 v84, 49, v82
	v_cvt_f32_i32_e32 v209, v84
	v_cmp_lt_i32_e64 s[2:3], s2, v0
	s_and_b64 vcc, vcc, s[2:3]
	v_mov_b32_e32 v106, v59
	v_cndmask_b32_e32 v58, v244, v58, vcc
	v_cmp_gt_u32_e32 vcc, s55, v84
	v_pk_mul_f32 v[84:85], v[106:107], v[208:209]
	s_movk_i32 s2, 0xffce
	v_sub_f32_e32 v59, v84, v85
	v_subrev_u32_e32 v84, 50, v82
	v_cvt_f32_i32_e32 v209, v84
	v_cmp_lt_i32_e64 s[2:3], s2, v0
	s_and_b64 vcc, vcc, s[2:3]
	v_mov_b32_e32 v106, v60
	v_cndmask_b32_e32 v59, v244, v59, vcc
	v_cmp_gt_u32_e32 vcc, s55, v84
	v_pk_mul_f32 v[84:85], v[106:107], v[208:209]
	s_movk_i32 s2, 0xffcd
	v_sub_f32_e32 v60, v84, v85
	v_subrev_u32_e32 v84, 51, v82
	v_cvt_f32_i32_e32 v209, v84
	v_cmp_lt_i32_e64 s[2:3], s2, v0
	s_and_b64 vcc, vcc, s[2:3]
	v_mov_b32_e32 v106, v61
	v_cndmask_b32_e32 v60, v244, v60, vcc
	v_cmp_gt_u32_e32 vcc, s55, v84
	v_pk_mul_f32 v[84:85], v[106:107], v[208:209]
	s_movk_i32 s2, 0xffcc
	v_sub_f32_e32 v61, v84, v85
	v_subrev_u32_e32 v84, 56, v82
	v_cvt_f32_i32_e32 v209, v84
	v_cmp_lt_i32_e64 s[2:3], s2, v0
	s_and_b64 vcc, vcc, s[2:3]
	v_mov_b32_e32 v106, v62
	v_cndmask_b32_e32 v61, v244, v61, vcc
	v_cmp_gt_u32_e32 vcc, s55, v84
	v_pk_mul_f32 v[84:85], v[106:107], v[208:209]
	s_movk_i32 s2, 0xffc7
	v_sub_f32_e32 v62, v84, v85
	v_subrev_u32_e32 v84, 57, v82
	v_cvt_f32_i32_e32 v209, v84
	v_cmp_lt_i32_e64 s[2:3], s2, v0
	s_and_b64 vcc, vcc, s[2:3]
	v_mov_b32_e32 v106, v63
	v_cndmask_b32_e32 v62, v244, v62, vcc
	v_cmp_gt_u32_e32 vcc, s55, v84
	v_pk_mul_f32 v[84:85], v[106:107], v[208:209]
	s_movk_i32 s2, 0xffc6
	v_sub_f32_e32 v63, v84, v85
	v_subrev_u32_e32 v84, 58, v82
	v_cvt_f32_i32_e32 v209, v84
	v_cmp_lt_i32_e64 s[2:3], s2, v0
	s_and_b64 vcc, vcc, s[2:3]
	v_mov_b32_e32 v106, v64
	v_cndmask_b32_e32 v63, v244, v63, vcc
	v_cmp_gt_u32_e32 vcc, s55, v84
	v_pk_mul_f32 v[84:85], v[106:107], v[208:209]
	s_movk_i32 s2, 0xffc5
	v_sub_f32_e32 v64, v84, v85
	v_subrev_u32_e32 v84, 59, v82
	v_cvt_f32_i32_e32 v209, v84
	v_cmp_lt_i32_e64 s[2:3], s2, v0
	s_and_b64 vcc, vcc, s[2:3]
	v_mov_b32_e32 v106, v65
	v_cndmask_b32_e32 v64, v244, v64, vcc
	v_cmp_gt_u32_e32 vcc, s55, v84
	v_pk_mul_f32 v[84:85], v[106:107], v[208:209]
	s_movk_i32 s2, 0xffc4
; DI void swa_item(const Params& P, int l, int n, int hk2, char* smem) {
;     ...
; #pragma unroll
;     for (int tt = 0; tt < 5; ++tt)
; #pragma unroll
;       for (int r = 0; r < 16; ++r) { const int cst = 32 * tt + (r & 3) + 8 * (r >> 2); const int dist = dbase - cst; const int kpos = kbase + cst;
;         const bool valid = (dist >= 0) && (dist < 128) && (kpos >= 0);
;         const float sv = valid ? st[tt][r] * (0.125f * LOG2E) - slope * (float)dist : -1e30f; st[tt][r] = sv; mx = fmaxf(mx, sv); }
	v_sub_f32_e32 v65, v84, v85
	v_subrev_u32_e32 v84, 64, v82
	v_cvt_f32_i32_e32 v209, v84
	v_cmp_lt_i32_e64 s[2:3], s2, v0
	s_and_b64 vcc, vcc, s[2:3]
	v_mov_b32_e32 v106, v34
	v_cndmask_b32_e32 v65, v244, v65, vcc
	v_cmp_gt_u32_e32 vcc, s55, v84
	v_pk_mul_f32 v[84:85], v[106:107], v[208:209]
	s_movk_i32 s2, 0xffbf
	v_sub_f32_e32 v34, v84, v85
	v_add_u32_e32 v84, 0xffffffbf, v82
	v_cvt_f32_i32_e32 v209, v84
	v_cmp_lt_i32_e64 s[2:3], s2, v0
	s_and_b64 vcc, vcc, s[2:3]
	v_mov_b32_e32 v106, v35
	v_cndmask_b32_e32 v34, v244, v34, vcc
	v_cmp_gt_u32_e32 vcc, s55, v84
	v_pk_mul_f32 v[84:85], v[106:107], v[208:209]
	s_movk_i32 s2, 0xffbe
	v_sub_f32_e32 v35, v84, v85
	v_add_u32_e32 v84, 0xffffffbe, v82
	v_cvt_f32_i32_e32 v209, v84
	v_cmp_lt_i32_e64 s[2:3], s2, v0
	s_and_b64 vcc, vcc, s[2:3]
	v_mov_b32_e32 v106, v36
	v_cndmask_b32_e32 v35, v244, v35, vcc
	v_cmp_gt_u32_e32 vcc, s55, v84
	v_pk_mul_f32 v[84:85], v[106:107], v[208:209]
	s_movk_i32 s2, 0xffbd
	v_sub_f32_e32 v36, v84, v85
	v_add_u32_e32 v84, 0xffffffbd, v82
	v_cvt_f32_i32_e32 v209, v84
	v_cmp_lt_i32_e64 s[2:3], s2, v0
	s_and_b64 vcc, vcc, s[2:3]
	v_mov_b32_e32 v106, v37
	v_cndmask_b32_e32 v36, v244, v36, vcc
	v_cmp_gt_u32_e32 vcc, s55, v84
	v_pk_mul_f32 v[84:85], v[106:107], v[208:209]
	s_movk_i32 s2, 0xffbc
	v_sub_f32_e32 v37, v84, v85
	v_add_u32_e32 v84, 0xffffffb8, v82
	v_cvt_f32_i32_e32 v209, v84
	v_cmp_lt_i32_e64 s[2:3], s2, v0
	s_and_b64 vcc, vcc, s[2:3]
	v_mov_b32_e32 v106, v38
	v_cndmask_b32_e32 v37, v244, v37, vcc
	v_cmp_gt_u32_e32 vcc, s55, v84
	v_pk_mul_f32 v[84:85], v[106:107], v[208:209]
	s_movk_i32 s2, 0xffb7
	v_sub_f32_e32 v38, v84, v85
	v_add_u32_e32 v84, 0xffffffb7, v82
	v_cvt_f32_i32_e32 v209, v84
	v_cmp_lt_i32_e64 s[2:3], s2, v0
	s_and_b64 vcc, vcc, s[2:3]
	v_mov_b32_e32 v106, v39
	v_cndmask_b32_e32 v38, v244, v38, vcc
	v_cmp_gt_u32_e32 vcc, s55, v84
	v_pk_mul_f32 v[84:85], v[106:107], v[208:209]
	s_movk_i32 s2, 0xffb6
	v_sub_f32_e32 v39, v84, v85
	v_add_u32_e32 v84, 0xffffffb6, v82
	v_cvt_f32_i32_e32 v209, v84
	v_cmp_lt_i32_e64 s[2:3], s2, v0
	s_and_b64 vcc, vcc, s[2:3]
	v_mov_b32_e32 v106, v40
	v_cndmask_b32_e32 v39, v244, v39, vcc
	v_cmp_gt_u32_e32 vcc, s55, v84
	v_pk_mul_f32 v[84:85], v[106:107], v[208:209]
	s_movk_i32 s2, 0xffb5
	v_sub_f32_e32 v40, v84, v85
	v_add_u32_e32 v84, 0xffffffb5, v82
	v_cvt_f32_i32_e32 v209, v84
	v_cmp_lt_i32_e64 s[2:3], s2, v0
	s_and_b64 vcc, vcc, s[2:3]
	v_mov_b32_e32 v106, v41
	v_cndmask_b32_e32 v40, v244, v40, vcc
	v_cmp_gt_u32_e32 vcc, s55, v84
	v_pk_mul_f32 v[84:85], v[106:107], v[208:209]
	s_movk_i32 s2, 0xffb4
	v_sub_f32_e32 v41, v84, v85
	v_add_u32_e32 v84, 0xffffffb0, v82
	v_cvt_f32_i32_e32 v209, v84
	v_cmp_lt_i32_e64 s[2:3], s2, v0
	s_and_b64 vcc, vcc, s[2:3]
	v_mov_b32_e32 v106, v42
	v_cndmask_b32_e32 v41, v244, v41, vcc
	v_cmp_gt_u32_e32 vcc, s55, v84
	v_pk_mul_f32 v[84:85], v[106:107], v[208:209]
	s_movk_i32 s2, 0xffaf
	v_sub_f32_e32 v42, v84, v85
	v_add_u32_e32 v84, 0xffffffaf, v82
	v_cvt_f32_i32_e32 v209, v84
	v_cmp_lt_i32_e64 s[2:3], s2, v0
	s_and_b64 vcc, vcc, s[2:3]
	v_mov_b32_e32 v106, v43
	v_cndmask_b32_e32 v42, v244, v42, vcc
	v_cmp_gt_u32_e32 vcc, s55, v84
	v_pk_mul_f32 v[84:85], v[106:107], v[208:209]
	s_movk_i32 s2, 0xffae
	v_sub_f32_e32 v43, v84, v85
	v_add_u32_e32 v84, 0xffffffae, v82
	v_cvt_f32_i32_e32 v209, v84
	v_cmp_lt_i32_e64 s[2:3], s2, v0
	s_and_b64 vcc, vcc, s[2:3]
	v_mov_b32_e32 v106, v44
	v_cndmask_b32_e32 v43, v244, v43, vcc
	v_cmp_gt_u32_e32 vcc, s55, v84
	v_pk_mul_f32 v[84:85], v[106:107], v[208:209]
	s_movk_i32 s2, 0xffad
	v_sub_f32_e32 v44, v84, v85
	v_add_u32_e32 v84, 0xffffffad, v82
	v_cvt_f32_i32_e32 v209, v84
	v_cmp_lt_i32_e64 s[2:3], s2, v0
	s_and_b64 vcc, vcc, s[2:3]
	v_mov_b32_e32 v106, v45
	v_cndmask_b32_e32 v44, v244, v44, vcc
	v_cmp_gt_u32_e32 vcc, s55, v84
	v_pk_mul_f32 v[84:85], v[106:107], v[208:209]
	s_movk_i32 s2, 0xffac
	v_sub_f32_e32 v45, v84, v85
	v_add_u32_e32 v84, 0xffffffa8, v82
	v_cvt_f32_i32_e32 v209, v84
	v_cmp_lt_i32_e64 s[2:3], s2, v0
	s_and_b64 vcc, vcc, s[2:3]
	v_mov_b32_e32 v106, v46
	v_cndmask_b32_e32 v45, v244, v45, vcc
	v_cmp_gt_u32_e32 vcc, s55, v84
	v_pk_mul_f32 v[84:85], v[106:107], v[208:209]
	s_movk_i32 s2, 0xffa7
	v_sub_f32_e32 v46, v84, v85
	v_add_u32_e32 v84, 0xffffffa7, v82
	v_cvt_f32_i32_e32 v209, v84
	v_cmp_lt_i32_e64 s[2:3], s2, v0
	s_and_b64 vcc, vcc, s[2:3]
	v_mov_b32_e32 v106, v47
	v_cndmask_b32_e32 v46, v244, v46, vcc
	v_cmp_gt_u32_e32 vcc, s55, v84
	v_pk_mul_f32 v[84:85], v[106:107], v[208:209]
	s_movk_i32 s2, 0xffa6
	v_sub_f32_e32 v47, v84, v85
	v_add_u32_e32 v84, 0xffffffa6, v82
	v_cvt_f32_i32_e32 v209, v84
	v_cmp_lt_i32_e64 s[2:3], s2, v0
	s_and_b64 vcc, vcc, s[2:3]
	v_mov_b32_e32 v106, v48
	v_cndmask_b32_e32 v47, v244, v47, vcc
	v_cmp_gt_u32_e32 vcc, s55, v84
	v_pk_mul_f32 v[84:85], v[106:107], v[208:209]
	s_movk_i32 s2, 0xffa5
	v_sub_f32_e32 v48, v84, v85
	v_add_u32_e32 v84, 0xffffffa5, v82
	v_cvt_f32_i32_e32 v209, v84
	v_cmp_lt_i32_e64 s[2:3], s2, v0
	s_and_b64 vcc, vcc, s[2:3]
	v_mov_b32_e32 v106, v49
	v_cndmask_b32_e32 v48, v244, v48, vcc
	v_cmp_gt_u32_e32 vcc, s55, v84
	v_pk_mul_f32 v[84:85], v[106:107], v[208:209]
	s_movk_i32 s2, 0xffa4
	v_sub_f32_e32 v49, v84, v85
	v_add_u32_e32 v84, 0xffffffa0, v82
	v_cvt_f32_i32_e32 v209, v84
	v_cmp_lt_i32_e64 s[2:3], s2, v0
	s_and_b64 vcc, vcc, s[2:3]
	v_mov_b32_e32 v106, v18
	v_cndmask_b32_e32 v49, v244, v49, vcc
	v_cmp_gt_u32_e32 vcc, s55, v84
	v_pk_mul_f32 v[84:85], v[106:107], v[208:209]
	s_movk_i32 s2, 0xff9f
	v_sub_f32_e32 v18, v84, v85
	v_add_u32_e32 v84, 0xffffff9f, v82
	v_cvt_f32_i32_e32 v209, v84
	v_cmp_lt_i32_e64 s[2:3], s2, v0
	s_and_b64 vcc, vcc, s[2:3]
	v_mov_b32_e32 v106, v19
; DI void swa_item(const Params& P, int l, int n, int hk2, char* smem) {
;     ...
; #pragma unroll
;     for (int tt = 0; tt < 5; ++tt)
; #pragma unroll
;       for (int r = 0; r < 16; ++r) { const int cst = 32 * tt + (r & 3) + 8 * (r >> 2); const int dist = dbase - cst; const int kpos = kbase + cst;
;         const bool valid = (dist >= 0) && (dist < 128) && (kpos >= 0);
;         const float sv = valid ? st[tt][r] * (0.125f * LOG2E) - slope * (float)dist : -1e30f; st[tt][r] = sv; mx = fmaxf(mx, sv); }
	v_cndmask_b32_e32 v18, v244, v18, vcc
	v_cmp_gt_u32_e32 vcc, s55, v84
	v_pk_mul_f32 v[84:85], v[106:107], v[208:209]
	s_movk_i32 s2, 0xff9e
	v_sub_f32_e32 v19, v84, v85
	v_add_u32_e32 v84, 0xffffff9e, v82
	v_cvt_f32_i32_e32 v209, v84
	v_cmp_lt_i32_e64 s[2:3], s2, v0
	s_and_b64 vcc, vcc, s[2:3]
	v_mov_b32_e32 v106, v20
	v_cndmask_b32_e32 v19, v244, v19, vcc
	v_cmp_gt_u32_e32 vcc, s55, v84
	v_pk_mul_f32 v[84:85], v[106:107], v[208:209]
	s_movk_i32 s2, 0xff9d
	v_sub_f32_e32 v20, v84, v85
	v_add_u32_e32 v84, 0xffffff9d, v82
	v_cvt_f32_i32_e32 v209, v84
	v_cmp_lt_i32_e64 s[2:3], s2, v0
	s_and_b64 vcc, vcc, s[2:3]
	v_mov_b32_e32 v106, v21
	v_cndmask_b32_e32 v20, v244, v20, vcc
	v_cmp_gt_u32_e32 vcc, s55, v84
	v_pk_mul_f32 v[84:85], v[106:107], v[208:209]
	s_movk_i32 s2, 0xff9c
	v_sub_f32_e32 v21, v84, v85
	v_add_u32_e32 v84, 0xffffff98, v82
	v_cvt_f32_i32_e32 v209, v84
	v_cmp_lt_i32_e64 s[2:3], s2, v0
	s_and_b64 vcc, vcc, s[2:3]
	v_mov_b32_e32 v106, v22
	v_cndmask_b32_e32 v21, v244, v21, vcc
	v_cmp_gt_u32_e32 vcc, s55, v84
	v_pk_mul_f32 v[84:85], v[106:107], v[208:209]
	s_movk_i32 s2, 0xff97
	v_sub_f32_e32 v22, v84, v85
	v_add_u32_e32 v84, 0xffffff97, v82
	v_cvt_f32_i32_e32 v209, v84
	v_cmp_lt_i32_e64 s[2:3], s2, v0
	s_and_b64 vcc, vcc, s[2:3]
	v_mov_b32_e32 v106, v23
	v_cndmask_b32_e32 v22, v244, v22, vcc
	v_cmp_gt_u32_e32 vcc, s55, v84
	v_pk_mul_f32 v[84:85], v[106:107], v[208:209]
	s_movk_i32 s2, 0xff96
	v_sub_f32_e32 v23, v84, v85
	v_add_u32_e32 v84, 0xffffff96, v82
	v_cvt_f32_i32_e32 v209, v84
	v_cmp_lt_i32_e64 s[2:3], s2, v0
	s_and_b64 vcc, vcc, s[2:3]
	v_mov_b32_e32 v106, v24
	v_cndmask_b32_e32 v23, v244, v23, vcc
	v_cmp_gt_u32_e32 vcc, s55, v84
	v_pk_mul_f32 v[84:85], v[106:107], v[208:209]
	s_movk_i32 s2, 0xff95
	v_sub_f32_e32 v24, v84, v85
	v_add_u32_e32 v84, 0xffffff95, v82
	v_cvt_f32_i32_e32 v209, v84
	v_cmp_lt_i32_e64 s[2:3], s2, v0
	s_and_b64 vcc, vcc, s[2:3]
	v_mov_b32_e32 v106, v25
	v_cndmask_b32_e32 v24, v244, v24, vcc
	v_cmp_gt_u32_e32 vcc, s55, v84
	v_pk_mul_f32 v[84:85], v[106:107], v[208:209]
	s_movk_i32 s2, 0xff94
	v_sub_f32_e32 v25, v84, v85
	v_add_u32_e32 v84, 0xffffff90, v82
	v_cvt_f32_i32_e32 v209, v84
	v_cmp_lt_i32_e64 s[2:3], s2, v0
	s_and_b64 vcc, vcc, s[2:3]
	v_mov_b32_e32 v106, v26
	v_cndmask_b32_e32 v25, v244, v25, vcc
	v_cmp_gt_u32_e32 vcc, s55, v84
	v_pk_mul_f32 v[84:85], v[106:107], v[208:209]
	s_movk_i32 s2, 0xff8f
	v_sub_f32_e32 v26, v84, v85
	v_add_u32_e32 v84, 0xffffff8f, v82
	v_cvt_f32_i32_e32 v209, v84
	v_cmp_lt_i32_e64 s[2:3], s2, v0
	s_and_b64 vcc, vcc, s[2:3]
	v_mov_b32_e32 v106, v27
	v_cndmask_b32_e32 v26, v244, v26, vcc
	v_cmp_gt_u32_e32 vcc, s55, v84
	v_pk_mul_f32 v[84:85], v[106:107], v[208:209]
	s_movk_i32 s2, 0xff8e
	v_sub_f32_e32 v27, v84, v85
	v_add_u32_e32 v84, 0xffffff8e, v82
	v_cvt_f32_i32_e32 v209, v84
	v_cmp_lt_i32_e64 s[2:3], s2, v0
	s_and_b64 vcc, vcc, s[2:3]
	v_mov_b32_e32 v106, v28
	v_cndmask_b32_e32 v27, v244, v27, vcc
	v_cmp_gt_u32_e32 vcc, s55, v84
	v_pk_mul_f32 v[84:85], v[106:107], v[208:209]
	s_movk_i32 s2, 0xff8d
	v_sub_f32_e32 v28, v84, v85
	v_add_u32_e32 v84, 0xffffff8d, v82
	v_cvt_f32_i32_e32 v209, v84
	v_cmp_lt_i32_e64 s[2:3], s2, v0
	s_and_b64 vcc, vcc, s[2:3]
	v_mov_b32_e32 v106, v29
	v_cndmask_b32_e32 v28, v244, v28, vcc
	v_cmp_gt_u32_e32 vcc, s55, v84
	v_pk_mul_f32 v[84:85], v[106:107], v[208:209]
	s_movk_i32 s2, 0xff8c
	v_sub_f32_e32 v29, v84, v85
	v_add_u32_e32 v84, 0xffffff88, v82
	v_cvt_f32_i32_e32 v209, v84
	v_cmp_lt_i32_e64 s[2:3], s2, v0
	s_and_b64 vcc, vcc, s[2:3]
	v_mov_b32_e32 v106, v30
	v_cndmask_b32_e32 v29, v244, v29, vcc
	v_cmp_gt_u32_e32 vcc, s55, v84
	v_pk_mul_f32 v[84:85], v[106:107], v[208:209]
	s_movk_i32 s2, 0xff87
	v_sub_f32_e32 v30, v84, v85
	v_add_u32_e32 v84, 0xffffff87, v82
	v_cvt_f32_i32_e32 v209, v84
	v_cmp_lt_i32_e64 s[2:3], s2, v0
	s_and_b64 vcc, vcc, s[2:3]
	v_mov_b32_e32 v106, v31
	v_cndmask_b32_e32 v30, v244, v30, vcc
	v_cmp_gt_u32_e32 vcc, s55, v84
	v_pk_mul_f32 v[84:85], v[106:107], v[208:209]
	s_movk_i32 s2, 0xff86
	v_sub_f32_e32 v31, v84, v85
	v_add_u32_e32 v84, 0xffffff86, v82
	v_cvt_f32_i32_e32 v209, v84
	v_cmp_lt_i32_e64 s[2:3], s2, v0
	s_and_b64 vcc, vcc, s[2:3]
	v_mov_b32_e32 v106, v32
	v_cndmask_b32_e32 v31, v244, v31, vcc
	v_cmp_gt_u32_e32 vcc, s55, v84
	v_pk_mul_f32 v[84:85], v[106:107], v[208:209]
	s_movk_i32 s2, 0xff85
	v_sub_f32_e32 v32, v84, v85
	v_add_u32_e32 v84, 0xffffff85, v82
	v_cvt_f32_i32_e32 v209, v84
	v_cmp_lt_i32_e64 s[2:3], s2, v0
	s_and_b64 vcc, vcc, s[2:3]
	v_mov_b32_e32 v106, v33
	v_cndmask_b32_e32 v32, v244, v32, vcc
	v_cmp_gt_u32_e32 vcc, s55, v84
	s_movk_i32 s2, 0xff84
	v_pk_mul_f32 v[84:85], v[106:107], v[208:209]
	v_cvt_f32_i32_e32 v209, v83
	v_cmp_lt_i32_e64 s[2:3], s2, v0
	v_sub_f32_e32 v33, v84, v85
	s_and_b64 vcc, vcc, s[2:3]
	v_cndmask_b32_e32 v33, v244, v33, vcc
	v_cmp_gt_u32_e32 vcc, s55, v83
	v_mov_b32_e32 v106, v2
	v_add_u32_e32 v83, 0xffffff7f, v82
	v_pk_mul_f32 v[84:85], v[106:107], v[208:209]
	v_cvt_f32_i32_e32 v209, v83
	v_mov_b32_e32 v106, v3
	v_sub_f32_e32 v2, v84, v85
	s_movk_i32 s2, 0xff7f
	v_pk_mul_f32 v[84:85], v[106:107], v[208:209]
	v_cmp_lt_i32_e64 s[2:3], s2, v0
	v_sub_f32_e32 v3, v84, v85
	v_add_u32_e32 v84, 0xffffff7e, v82
	v_cvt_f32_i32_e32 v209, v84
	s_and_b64 vcc, vcc, s[2:3]
	s_movk_i32 s2, 0xff7e
	v_cndmask_b32_e32 v2, v244, v2, vcc
	v_cmp_gt_u32_e32 vcc, s55, v83
	v_cmp_lt_i32_e64 s[2:3], s2, v0
	s_and_b64 vcc, vcc, s[2:3]
	v_mov_b32_e32 v106, v4
	v_cndmask_b32_e32 v3, v244, v3, vcc
	v_cmp_gt_u32_e32 vcc, s55, v84
	v_pk_mul_f32 v[84:85], v[106:107], v[208:209]
	s_movk_i32 s2, 0xff7d
	v_sub_f32_e32 v4, v84, v85
	v_add_u32_e32 v84, 0xffffff7d, v82
	v_cvt_f32_i32_e32 v209, v84
; DI void swa_item(const Params& P, int l, int n, int hk2, char* smem) {
;     ...
; #pragma unroll
;     for (int tt = 0; tt < 5; ++tt)
; #pragma unroll
;       for (int r = 0; r < 16; ++r) { const int cst = 32 * tt + (r & 3) + 8 * (r >> 2); const int dist = dbase - cst; const int kpos = kbase + cst;
;         const bool valid = (dist >= 0) && (dist < 128) && (kpos >= 0);
;         const float sv = valid ? st[tt][r] * (0.125f * LOG2E) - slope * (float)dist : -1e30f; st[tt][r] = sv; mx = fmaxf(mx, sv); }
;     mx = fmaxf(mx, __shfl_xor(mx, 32));
	v_cmp_lt_i32_e64 s[2:3], s2, v0
	s_and_b64 vcc, vcc, s[2:3]
	v_mov_b32_e32 v106, v5
	v_cndmask_b32_e32 v4, v244, v4, vcc
	v_cmp_gt_u32_e32 vcc, s55, v84
	v_pk_mul_f32 v[84:85], v[106:107], v[208:209]
	s_movk_i32 s2, 0xff7c
	v_sub_f32_e32 v5, v84, v85
	v_add_u32_e32 v84, 0xffffff78, v82
	v_cvt_f32_i32_e32 v209, v84
	v_cmp_lt_i32_e64 s[2:3], s2, v0
	s_and_b64 vcc, vcc, s[2:3]
	v_mov_b32_e32 v106, v6
	v_cndmask_b32_e32 v5, v244, v5, vcc
	v_cmp_gt_u32_e32 vcc, s55, v84
	v_pk_mul_f32 v[84:85], v[106:107], v[208:209]
	s_movk_i32 s2, 0xff77
	v_sub_f32_e32 v6, v84, v85
	v_add_u32_e32 v84, 0xffffff77, v82
	v_cvt_f32_i32_e32 v209, v84
	v_cmp_lt_i32_e64 s[2:3], s2, v0
	s_and_b64 vcc, vcc, s[2:3]
	v_mov_b32_e32 v106, v7
	v_cndmask_b32_e32 v6, v244, v6, vcc
	v_cmp_gt_u32_e32 vcc, s55, v84
	v_pk_mul_f32 v[84:85], v[106:107], v[208:209]
	s_movk_i32 s2, 0xff76
	v_sub_f32_e32 v7, v84, v85
	v_add_u32_e32 v84, 0xffffff76, v82
	v_cvt_f32_i32_e32 v209, v84
	v_cmp_lt_i32_e64 s[2:3], s2, v0
	s_and_b64 vcc, vcc, s[2:3]
	v_mov_b32_e32 v106, v8
	v_cndmask_b32_e32 v7, v244, v7, vcc
	v_cmp_gt_u32_e32 vcc, s55, v84
	v_pk_mul_f32 v[84:85], v[106:107], v[208:209]
	s_movk_i32 s2, 0xff75
	v_sub_f32_e32 v8, v84, v85
	v_add_u32_e32 v84, 0xffffff75, v82
	v_cvt_f32_i32_e32 v209, v84
	v_cmp_lt_i32_e64 s[2:3], s2, v0
	s_and_b64 vcc, vcc, s[2:3]
	v_mov_b32_e32 v106, v9
	v_cndmask_b32_e32 v8, v244, v8, vcc
	v_cmp_gt_u32_e32 vcc, s55, v84
	v_pk_mul_f32 v[84:85], v[106:107], v[208:209]
	v_max3_f32 v86, v114, v66, v67
	v_sub_f32_e32 v9, v84, v85
	v_add_u32_e32 v84, 0xffffff70, v82
	v_max3_f32 v86, v86, v68, v69
	v_cvt_f32_i32_e32 v209, v84
	v_max3_f32 v86, v86, v70, v71
	s_movk_i32 s2, 0xff74
	v_max3_f32 v86, v86, v72, v73
	v_cmp_lt_i32_e64 s[2:3], s2, v0
	v_max3_f32 v86, v86, v74, v75
	s_and_b64 vcc, vcc, s[2:3]
	v_mov_b32_e32 v106, v10
	v_max3_f32 v86, v86, v76, v77
	v_cndmask_b32_e32 v9, v244, v9, vcc
	v_cmp_gt_u32_e32 vcc, s55, v84
	v_pk_mul_f32 v[84:85], v[106:107], v[208:209]
	v_max3_f32 v86, v86, v78, v79
	v_sub_f32_e32 v10, v84, v85
	v_add_u32_e32 v84, 0xffffff6f, v82
	v_max3_f32 v86, v86, v80, v81
	v_cvt_f32_i32_e32 v209, v84
	v_max3_f32 v86, v86, v50, v51
	s_movk_i32 s2, 0xff6f
	v_max3_f32 v86, v86, v52, v53
	v_cmp_lt_i32_e64 s[2:3], s2, v0
	v_max3_f32 v86, v86, v54, v55
	s_and_b64 vcc, vcc, s[2:3]
	v_mov_b32_e32 v106, v11
	v_max3_f32 v86, v86, v56, v57
	v_cndmask_b32_e32 v10, v244, v10, vcc
	v_cmp_gt_u32_e32 vcc, s55, v84
	v_pk_mul_f32 v[84:85], v[106:107], v[208:209]
	v_max3_f32 v86, v86, v58, v59
	v_sub_f32_e32 v11, v84, v85
	v_add_u32_e32 v84, 0xffffff6e, v82
	v_max3_f32 v86, v86, v60, v61
	v_cvt_f32_i32_e32 v209, v84
	v_max3_f32 v86, v86, v62, v63
	s_movk_i32 s2, 0xff6e
	v_max3_f32 v86, v86, v64, v65
	v_cmp_lt_i32_e64 s[2:3], s2, v0
	v_max3_f32 v86, v86, v34, v35
	s_and_b64 vcc, vcc, s[2:3]
	v_mov_b32_e32 v106, v12
	v_max3_f32 v86, v86, v36, v37
	v_cndmask_b32_e32 v11, v244, v11, vcc
	v_cmp_gt_u32_e32 vcc, s55, v84
	v_pk_mul_f32 v[84:85], v[106:107], v[208:209]
	v_max3_f32 v86, v86, v38, v39
	v_sub_f32_e32 v12, v84, v85
	v_add_u32_e32 v84, 0xffffff6d, v82
	v_max3_f32 v86, v86, v40, v41
	v_cvt_f32_i32_e32 v209, v84
	v_max3_f32 v86, v86, v42, v43
	s_movk_i32 s2, 0xff6d
	v_max3_f32 v86, v86, v44, v45
	v_cmp_lt_i32_e64 s[2:3], s2, v0
	v_max3_f32 v86, v86, v46, v47
	s_and_b64 vcc, vcc, s[2:3]
	v_mov_b32_e32 v106, v13
	v_max3_f32 v86, v86, v48, v49
	v_cndmask_b32_e32 v12, v244, v12, vcc
	v_cmp_gt_u32_e32 vcc, s55, v84
	v_pk_mul_f32 v[84:85], v[106:107], v[208:209]
	v_max3_f32 v86, v86, v18, v19
	v_sub_f32_e32 v13, v84, v85
	v_add_u32_e32 v84, 0xffffff68, v82
	v_max3_f32 v86, v86, v20, v21
	v_cvt_f32_i32_e32 v209, v84
	v_max3_f32 v86, v86, v22, v23
	s_movk_i32 s2, 0xff6c
	v_max3_f32 v86, v86, v24, v25
	v_cmp_lt_i32_e64 s[2:3], s2, v0
	v_max3_f32 v86, v86, v26, v27
	s_and_b64 vcc, vcc, s[2:3]
	v_mov_b32_e32 v106, v14
	v_max3_f32 v86, v86, v28, v29
	v_cndmask_b32_e32 v13, v244, v13, vcc
	v_cmp_gt_u32_e32 vcc, s55, v84
	v_pk_mul_f32 v[84:85], v[106:107], v[208:209]
	v_max3_f32 v86, v86, v30, v31
	v_sub_f32_e32 v14, v84, v85
	v_add_u32_e32 v84, 0xffffff67, v82
	v_max3_f32 v86, v86, v32, v33
	v_cvt_f32_i32_e32 v209, v84
	v_max3_f32 v83, v86, v2, v3
	s_movk_i32 s2, 0xff67
	v_max3_f32 v83, v83, v4, v5
	v_cmp_lt_i32_e64 s[2:3], s2, v0
	v_max3_f32 v83, v83, v6, v7
	s_and_b64 vcc, vcc, s[2:3]
	s_movk_i32 s2, 0xff66
	v_mov_b32_e32 v106, v15
	v_max3_f32 v83, v83, v8, v9
	v_cndmask_b32_e32 v14, v244, v14, vcc
	v_cmp_gt_u32_e32 vcc, s55, v84
	v_cmp_lt_i32_e64 s[2:3], s2, v0
	v_pk_mul_f32 v[84:85], v[106:107], v[208:209]
	v_max3_f32 v83, v83, v10, v11
	v_sub_f32_e32 v15, v84, v85
	s_and_b64 vcc, vcc, s[2:3]
	v_max3_f32 v83, v83, v12, v13
	v_cndmask_b32_e32 v15, v244, v15, vcc
	v_max3_f32 v86, v83, v14, v15
	v_add_u32_e32 v83, 0xffffff66, v82
	v_cvt_f32_i32_e32 v209, v83
	v_mov_b32_e32 v106, v16
	v_add_u32_e32 v82, 0xffffff65, v82
	s_movk_i32 s2, 0xff65
	v_pk_mul_f32 v[84:85], v[106:107], v[208:209]
	v_cvt_f32_i32_e32 v209, v82
	v_cmp_gt_u32_e32 vcc, s55, v83
	v_cmp_lt_i32_e64 s[2:3], s2, v0
	v_sub_f32_e32 v16, v84, v85
	s_and_b64 vcc, vcc, s[2:3]
	v_mov_b32_e32 v106, v17
	v_cndmask_b32_e32 v16, v244, v16, vcc
	v_cmp_gt_u32_e32 vcc, s55, v82
	s_movk_i32 s2, 0xff64
	v_pk_mul_f32 v[82:83], v[106:107], v[208:209]
	v_cmp_lt_i32_e64 s[2:3], s2, v0
	v_sub_f32_e32 v0, v82, v83
	v_and_b32_e32 v82, 64, v239
	s_and_b64 vcc, vcc, s[2:3]
	v_xor_b32_e32 v17, 32, v239
	v_add_u32_e32 v82, 64, v82
	v_cndmask_b32_e32 v84, v244, v0, vcc
	v_cmp_lt_i32_e32 vcc, v17, v82
	v_max3_f32 v0, v86, v16, v84
	s_nop 0
	v_cndmask_b32_e32 v17, v239, v17, vcc
	v_lshlrev_b32_e32 v82, 2, v17
	ds_bpermute_b32 v17, v82, v0
	s_waitcnt lgkmcnt(0)
; DI void swa_item(const Params& P, int l, int n, int hk2, char* smem) {
;     ...
;     float den = 0.f;
; #pragma unroll
;     for (int tt = 0; tt < 5; ++tt)
; #pragma unroll
;       for (int r = 0; r < 16; ++r) { const float p = exp2f(st[tt][r] - mx); st[tt][r] = p; den += p; }
;     den += __shfl_xor(den, 32); den += exp2f(sinkv - mx);
	v_max_f32_e32 v17, v17, v17
	v_max_f32_e32 v83, v0, v17
	v_sub_f32_e32 v0, v66, v83
	v_cmp_gt_f32_e32 vcc, s91, v0
	v_sub_f32_e32 v69, v69, v83
	v_sub_f32_e32 v71, v71, v83
	v_cndmask_b32_e32 v17, 0, v242, vcc
	v_add_f32_e32 v0, v0, v17
	v_sub_f32_e32 v17, v67, v83
	v_cmp_gt_f32_e64 s[2:3], s91, v17
	v_exp_f32_e32 v0, v0
	v_sub_f32_e32 v73, v73, v83
	v_cndmask_b32_e64 v66, 0, v242, s[2:3]
	v_add_f32_e32 v17, v17, v66
	v_exp_f32_e32 v17, v17
	v_cndmask_b32_e32 v66, 0, v243, vcc
	v_ldexp_f32 v0, v0, v66
	v_cndmask_b32_e64 v66, 0, v243, s[2:3]
	v_ldexp_f32 v17, v17, v66
	v_sub_f32_e32 v66, v68, v83
	v_cmp_gt_f32_e32 vcc, s91, v66
	v_add_f32_e32 v67, v0, v17
	v_sub_f32_e32 v75, v75, v83
	v_cndmask_b32_e32 v68, 0, v242, vcc
	v_add_f32_e32 v66, v66, v68
	v_cndmask_b32_e32 v68, 0, v243, vcc
	v_cmp_gt_f32_e32 vcc, s91, v69
	v_exp_f32_e32 v66, v66
	v_sub_f32_e32 v77, v77, v83
	v_cndmask_b32_e32 v85, 0, v242, vcc
	v_add_f32_e32 v69, v69, v85
	v_exp_f32_e32 v69, v69
	v_ldexp_f32 v66, v66, v68
	v_add_f32_e32 v68, v66, v67
	v_cndmask_b32_e32 v67, 0, v243, vcc
	v_ldexp_f32 v67, v69, v67
	v_add_f32_e32 v69, v67, v68
	v_sub_f32_e32 v68, v70, v83
	v_cmp_gt_f32_e32 vcc, s91, v68
	v_sub_f32_e32 v79, v79, v83
	v_sub_f32_e32 v81, v81, v83
	v_cndmask_b32_e32 v70, 0, v242, vcc
	v_add_f32_e32 v68, v68, v70
	v_cndmask_b32_e32 v70, 0, v243, vcc
	v_cmp_gt_f32_e32 vcc, s91, v71
	v_exp_f32_e32 v68, v68
	v_sub_f32_e32 v50, v50, v83
	v_cndmask_b32_e32 v85, 0, v242, vcc
	v_add_f32_e32 v71, v71, v85
	v_exp_f32_e32 v71, v71
	v_ldexp_f32 v68, v68, v70
	v_add_f32_e32 v70, v68, v69
	v_cndmask_b32_e32 v69, 0, v243, vcc
	v_ldexp_f32 v69, v71, v69
	v_sub_f32_e32 v71, v72, v83
	v_cmp_gt_f32_e32 vcc, s91, v71
	v_add_f32_e32 v70, v69, v70
	v_sub_f32_e32 v51, v51, v83
	v_cndmask_b32_e32 v72, 0, v242, vcc
	v_add_f32_e32 v71, v71, v72
	v_cndmask_b32_e32 v72, 0, v243, vcc
	v_cmp_gt_f32_e32 vcc, s91, v73
	v_exp_f32_e32 v71, v71
	v_sub_f32_e32 v52, v52, v83
	v_cndmask_b32_e32 v85, 0, v242, vcc
	v_add_f32_e32 v73, v73, v85
	v_exp_f32_e32 v73, v73
	v_ldexp_f32 v72, v71, v72
	v_cndmask_b32_e32 v71, 0, v243, vcc
	v_add_f32_e32 v70, v72, v70
	v_ldexp_f32 v73, v73, v71
	v_add_f32_e32 v71, v73, v70
	v_sub_f32_e32 v70, v74, v83
	v_cmp_gt_f32_e32 vcc, s91, v70
	v_sub_f32_e32 v53, v53, v83
	v_sub_f32_e32 v55, v55, v83
	v_cndmask_b32_e32 v74, 0, v242, vcc
	v_add_f32_e32 v70, v70, v74
	v_cndmask_b32_e32 v74, 0, v243, vcc
	v_cmp_gt_f32_e32 vcc, s91, v75
	v_exp_f32_e32 v70, v70
	v_sub_f32_e32 v34, v34, v83
	v_cndmask_b32_e32 v85, 0, v242, vcc
	v_add_f32_e32 v75, v75, v85
	v_exp_f32_e32 v75, v75
	v_ldexp_f32 v70, v70, v74
	v_add_f32_e32 v74, v70, v71
	v_cndmask_b32_e32 v71, 0, v243, vcc
	v_ldexp_f32 v71, v75, v71
	v_add_f32_e32 v75, v71, v74
	v_sub_f32_e32 v74, v76, v83
	v_cmp_gt_f32_e32 vcc, s91, v74
	v_sub_f32_e32 v35, v35, v83
	v_sub_f32_e32 v36, v36, v83
	v_cndmask_b32_e32 v76, 0, v242, vcc
	v_add_f32_e32 v74, v74, v76
	v_cndmask_b32_e32 v76, 0, v243, vcc
	v_cmp_gt_f32_e32 vcc, s91, v77
	v_exp_f32_e32 v74, v74
	v_sub_f32_e32 v37, v37, v83
	v_cndmask_b32_e32 v85, 0, v242, vcc
	v_add_f32_e32 v77, v77, v85
	v_exp_f32_e32 v77, v77
	v_ldexp_f32 v74, v74, v76
	v_add_f32_e32 v76, v74, v75
	v_cndmask_b32_e32 v75, 0, v243, vcc
	v_ldexp_f32 v75, v77, v75
	v_sub_f32_e32 v77, v78, v83
	v_cmp_gt_f32_e32 vcc, s91, v77
	v_add_f32_e32 v76, v75, v76
	v_sub_f32_e32 v39, v39, v83
	v_cndmask_b32_e32 v78, 0, v242, vcc
	v_add_f32_e32 v77, v77, v78
	v_cndmask_b32_e32 v78, 0, v243, vcc
	v_cmp_gt_f32_e32 vcc, s91, v79
	v_exp_f32_e32 v77, v77
	v_sub_f32_e32 v18, v18, v83
	v_cndmask_b32_e32 v85, 0, v242, vcc
	v_add_f32_e32 v79, v79, v85
	v_exp_f32_e32 v79, v79
	v_ldexp_f32 v78, v77, v78
	v_cndmask_b32_e32 v77, 0, v243, vcc
	v_add_f32_e32 v76, v78, v76
	v_ldexp_f32 v79, v79, v77
	v_sub_f32_e32 v77, v80, v83
	v_cmp_gt_f32_e32 vcc, s91, v77
	v_add_f32_e32 v76, v79, v76
	v_sub_f32_e32 v19, v19, v83
	v_cndmask_b32_e32 v80, 0, v242, vcc
	v_add_f32_e32 v77, v77, v80
	v_cndmask_b32_e32 v80, 0, v243, vcc
	v_cmp_gt_f32_e32 vcc, s91, v81
	v_exp_f32_e32 v77, v77
	v_sub_f32_e32 v21, v21, v83
	v_cndmask_b32_e32 v85, 0, v242, vcc
	v_add_f32_e32 v81, v81, v85
	v_exp_f32_e32 v81, v81
	v_ldexp_f32 v85, v77, v80
	v_cndmask_b32_e32 v77, 0, v243, vcc
	v_cmp_gt_f32_e32 vcc, s91, v50
	v_ldexp_f32 v86, v81, v77
	v_add_f32_e32 v76, v85, v76
	v_cndmask_b32_e32 v77, 0, v242, vcc
	v_add_f32_e32 v50, v50, v77
	v_cndmask_b32_e32 v77, 0, v243, vcc
	v_cmp_gt_f32_e32 vcc, s91, v51
	v_exp_f32_e32 v50, v50
	v_add_f32_e32 v76, v86, v76
	v_cndmask_b32_e32 v80, 0, v242, vcc
	v_add_f32_e32 v51, v51, v80
	v_exp_f32_e32 v51, v51
	v_ldexp_f32 v50, v50, v77
	v_cndmask_b32_e32 v77, 0, v243, vcc
	v_add_f32_e32 v76, v50, v76
	v_ldexp_f32 v51, v51, v77
	v_cmp_gt_f32_e32 vcc, s91, v52
	v_add_f32_e32 v77, v51, v76
	v_sub_f32_e32 v2, v2, v83
	v_cndmask_b32_e32 v76, 0, v242, vcc
	v_add_f32_e32 v52, v52, v76
	v_cndmask_b32_e32 v76, 0, v243, vcc
	v_cmp_gt_f32_e32 vcc, s91, v53
	v_exp_f32_e32 v52, v52
	v_sub_f32_e32 v3, v3, v83
	v_cndmask_b32_e32 v80, 0, v242, vcc
	v_add_f32_e32 v53, v53, v80
	v_exp_f32_e32 v53, v53
	v_ldexp_f32 v76, v52, v76
	v_add_f32_e32 v52, v76, v77
	v_cndmask_b32_e32 v77, 0, v243, vcc
	v_ldexp_f32 v77, v53, v77
	v_sub_f32_e32 v53, v54, v83
	v_cmp_gt_f32_e32 vcc, s91, v53
	v_add_f32_e32 v52, v77, v52
	v_sub_f32_e32 v5, v5, v83
	v_cndmask_b32_e32 v54, 0, v242, vcc
	v_add_f32_e32 v53, v53, v54
	v_cndmask_b32_e32 v54, 0, v243, vcc
	v_cmp_gt_f32_e32 vcc, s91, v55
	v_exp_f32_e32 v53, v53
	s_nop 0
	v_cndmask_b32_e32 v80, 0, v242, vcc
	v_add_f32_e32 v55, v55, v80
	v_exp_f32_e32 v55, v55
	v_ldexp_f32 v80, v53, v54
	v_cndmask_b32_e32 v53, 0, v243, vcc
; DI void swa_item(const Params& P, int l, int n, int hk2, char* smem) {
;     ...
;     float den = 0.f;
; #pragma unroll
;     for (int tt = 0; tt < 5; ++tt)
; #pragma unroll
;       for (int r = 0; r < 16; ++r) { const float p = exp2f(st[tt][r] - mx); st[tt][r] = p; den += p; }
;     den += __shfl_xor(den, 32); den += exp2f(sinkv - mx);
	v_add_f32_e32 v52, v80, v52
	v_ldexp_f32 v81, v55, v53
	v_sub_f32_e32 v53, v56, v83
	v_cmp_gt_f32_e32 vcc, s91, v53
	v_sub_f32_e32 v55, v57, v83
	v_add_f32_e32 v52, v81, v52
	v_cndmask_b32_e32 v54, 0, v242, vcc
	v_add_f32_e32 v53, v53, v54
	v_cndmask_b32_e32 v54, 0, v243, vcc
	v_cmp_gt_f32_e32 vcc, s91, v55
	v_exp_f32_e32 v53, v53
	v_sub_f32_e32 v57, v61, v83
	v_cndmask_b32_e32 v56, 0, v242, vcc
	v_add_f32_e32 v55, v55, v56
	v_exp_f32_e32 v55, v55
	v_ldexp_f32 v87, v53, v54
	v_cndmask_b32_e32 v53, 0, v243, vcc
	v_add_f32_e32 v52, v87, v52
	v_ldexp_f32 v88, v55, v53
	v_add_f32_e32 v53, v88, v52
	v_sub_f32_e32 v52, v58, v83
	v_cmp_gt_f32_e32 vcc, s91, v52
	v_sub_f32_e32 v55, v59, v83
	v_sub_f32_e32 v59, v63, v83
	v_cndmask_b32_e32 v54, 0, v242, vcc
	v_add_f32_e32 v52, v52, v54
	v_cndmask_b32_e32 v54, 0, v243, vcc
	v_cmp_gt_f32_e32 vcc, s91, v55
	v_exp_f32_e32 v52, v52
	v_sub_f32_e32 v61, v65, v83
	v_cndmask_b32_e32 v56, 0, v242, vcc
	v_add_f32_e32 v55, v55, v56
	v_exp_f32_e32 v55, v55
	v_ldexp_f32 v52, v52, v54
	v_add_f32_e32 v54, v52, v53
	v_cndmask_b32_e32 v53, 0, v243, vcc
	v_ldexp_f32 v53, v55, v53
	v_add_f32_e32 v55, v53, v54
	v_sub_f32_e32 v54, v60, v83
	v_cmp_gt_f32_e32 vcc, s91, v54
	s_nop 1
	v_cndmask_b32_e32 v56, 0, v242, vcc
	v_add_f32_e32 v54, v54, v56
	v_cndmask_b32_e32 v56, 0, v243, vcc
	v_cmp_gt_f32_e32 vcc, s91, v57
	v_exp_f32_e32 v54, v54
	s_nop 0
	v_cndmask_b32_e32 v58, 0, v242, vcc
	v_add_f32_e32 v57, v57, v58
	v_exp_f32_e32 v57, v57
	v_ldexp_f32 v54, v54, v56
	v_add_f32_e32 v56, v54, v55
	v_cndmask_b32_e32 v55, 0, v243, vcc
	v_ldexp_f32 v55, v57, v55
	v_sub_f32_e32 v57, v62, v83
	v_cmp_gt_f32_e32 vcc, s91, v57
	v_add_f32_e32 v56, v55, v56
	s_nop 0
	v_cndmask_b32_e32 v58, 0, v242, vcc
	v_add_f32_e32 v57, v57, v58
	v_cndmask_b32_e32 v58, 0, v243, vcc
	v_cmp_gt_f32_e32 vcc, s91, v59
	v_exp_f32_e32 v57, v57
	s_nop 0
	v_cndmask_b32_e32 v60, 0, v242, vcc
	v_add_f32_e32 v59, v59, v60
	v_exp_f32_e32 v59, v59
	v_ldexp_f32 v58, v57, v58
	v_cndmask_b32_e32 v57, 0, v243, vcc
	v_add_f32_e32 v56, v58, v56
	v_ldexp_f32 v59, v59, v57
	v_sub_f32_e32 v57, v64, v83
	v_cmp_gt_f32_e32 vcc, s91, v57
	v_add_f32_e32 v56, v59, v56
	s_nop 0
	v_cndmask_b32_e32 v60, 0, v242, vcc
	v_add_f32_e32 v57, v57, v60
	v_cndmask_b32_e32 v60, 0, v243, vcc
	v_cmp_gt_f32_e32 vcc, s91, v61
	v_exp_f32_e32 v57, v57
	s_nop 0
	v_cndmask_b32_e32 v62, 0, v242, vcc
	v_add_f32_e32 v61, v61, v62
	v_exp_f32_e32 v61, v61
	v_ldexp_f32 v62, v57, v60
	v_cndmask_b32_e32 v57, 0, v243, vcc
	v_cmp_gt_f32_e32 vcc, s91, v34
	v_ldexp_f32 v63, v61, v57
	v_add_f32_e32 v56, v62, v56
	v_cndmask_b32_e32 v57, 0, v242, vcc
	v_add_f32_e32 v34, v34, v57
	v_cndmask_b32_e32 v57, 0, v243, vcc
	v_cmp_gt_f32_e32 vcc, s91, v35
	v_exp_f32_e32 v34, v34
	v_add_f32_e32 v56, v63, v56
	v_cndmask_b32_e32 v60, 0, v242, vcc
	v_add_f32_e32 v35, v35, v60
	v_exp_f32_e32 v35, v35
	v_ldexp_f32 v34, v34, v57
	v_cndmask_b32_e32 v57, 0, v243, vcc
	v_add_f32_e32 v56, v34, v56
	v_ldexp_f32 v35, v35, v57
	v_cmp_gt_f32_e32 vcc, s91, v36
	v_add_f32_e32 v57, v35, v56
	s_nop 0
	v_cndmask_b32_e32 v56, 0, v242, vcc
	v_add_f32_e32 v36, v36, v56
	v_cndmask_b32_e32 v56, 0, v243, vcc
	v_cmp_gt_f32_e32 vcc, s91, v37
	v_exp_f32_e32 v36, v36
	s_nop 0
	v_cndmask_b32_e32 v60, 0, v242, vcc
	v_add_f32_e32 v37, v37, v60
	v_exp_f32_e32 v37, v37
	v_ldexp_f32 v56, v36, v56
	v_add_f32_e32 v36, v56, v57
	v_cndmask_b32_e32 v57, 0, v243, vcc
	v_ldexp_f32 v57, v37, v57
	v_sub_f32_e32 v37, v38, v83
	v_cmp_gt_f32_e32 vcc, s91, v37
	v_add_f32_e32 v36, v57, v36
	s_nop 0
	v_cndmask_b32_e32 v38, 0, v242, vcc
	v_add_f32_e32 v37, v37, v38
	v_cndmask_b32_e32 v38, 0, v243, vcc
	v_cmp_gt_f32_e32 vcc, s91, v39
	v_exp_f32_e32 v37, v37
	s_nop 0
	v_cndmask_b32_e32 v60, 0, v242, vcc
	v_add_f32_e32 v39, v39, v60
	v_exp_f32_e32 v39, v39
	v_ldexp_f32 v60, v37, v38
	v_cndmask_b32_e32 v37, 0, v243, vcc
	v_add_f32_e32 v36, v60, v36
	v_ldexp_f32 v61, v39, v37
	v_sub_f32_e32 v37, v40, v83
	v_cmp_gt_f32_e32 vcc, s91, v37
	v_sub_f32_e32 v39, v41, v83
	v_add_f32_e32 v36, v61, v36
	v_cndmask_b32_e32 v38, 0, v242, vcc
	v_add_f32_e32 v37, v37, v38
	v_cndmask_b32_e32 v38, 0, v243, vcc
	v_cmp_gt_f32_e32 vcc, s91, v39
	v_exp_f32_e32 v37, v37
	v_sub_f32_e32 v41, v45, v83
	v_cndmask_b32_e32 v40, 0, v242, vcc
	v_add_f32_e32 v39, v39, v40
	v_exp_f32_e32 v39, v39
	v_ldexp_f32 v64, v37, v38
	v_cndmask_b32_e32 v37, 0, v243, vcc
	v_add_f32_e32 v36, v64, v36
	v_ldexp_f32 v65, v39, v37
	v_add_f32_e32 v37, v65, v36
	v_sub_f32_e32 v36, v42, v83
	v_cmp_gt_f32_e32 vcc, s91, v36
	v_sub_f32_e32 v39, v43, v83
	v_sub_f32_e32 v43, v47, v83
	v_cndmask_b32_e32 v38, 0, v242, vcc
	v_add_f32_e32 v36, v36, v38
	v_cndmask_b32_e32 v38, 0, v243, vcc
	v_cmp_gt_f32_e32 vcc, s91, v39
	v_exp_f32_e32 v36, v36
	s_nop 0
	v_cndmask_b32_e32 v40, 0, v242, vcc
	v_add_f32_e32 v39, v39, v40
	v_exp_f32_e32 v39, v39
	v_ldexp_f32 v36, v36, v38
	v_add_f32_e32 v38, v36, v37
	v_cndmask_b32_e32 v37, 0, v243, vcc
	v_ldexp_f32 v37, v39, v37
	v_sub_f32_e32 v39, v44, v83
	v_cmp_gt_f32_e32 vcc, s91, v39
	v_add_f32_e32 v38, v37, v38
	s_nop 0
	v_cndmask_b32_e32 v40, 0, v242, vcc
	v_add_f32_e32 v39, v39, v40
	v_cndmask_b32_e32 v40, 0, v243, vcc
	v_cmp_gt_f32_e32 vcc, s91, v41
	v_exp_f32_e32 v39, v39
	s_nop 0
	v_cndmask_b32_e32 v42, 0, v242, vcc
	v_add_f32_e32 v41, v41, v42
	v_exp_f32_e32 v41, v41
	v_ldexp_f32 v40, v39, v40
	v_cndmask_b32_e32 v39, 0, v243, vcc
	v_add_f32_e32 v38, v40, v38
	v_ldexp_f32 v41, v41, v39
	v_sub_f32_e32 v39, v46, v83
	v_cmp_gt_f32_e32 vcc, s91, v39
	v_add_f32_e32 v38, v41, v38
	s_nop 0
	v_cndmask_b32_e32 v42, 0, v242, vcc
	v_add_f32_e32 v39, v39, v42
	v_cndmask_b32_e32 v42, 0, v243, vcc
; DI void swa_item(const Params& P, int l, int n, int hk2, char* smem) {
;     ...
;     float den = 0.f;
; #pragma unroll
;     for (int tt = 0; tt < 5; ++tt)
; #pragma unroll
;       for (int r = 0; r < 16; ++r) { const float p = exp2f(st[tt][r] - mx); st[tt][r] = p; den += p; }
;     den += __shfl_xor(den, 32); den += exp2f(sinkv - mx);
	v_cmp_gt_f32_e32 vcc, s91, v43
	v_exp_f32_e32 v39, v39
	s_nop 0
	v_cndmask_b32_e32 v44, 0, v242, vcc
	v_add_f32_e32 v43, v43, v44
	v_exp_f32_e32 v43, v43
	v_ldexp_f32 v46, v39, v42
	v_cndmask_b32_e32 v39, 0, v243, vcc
	v_add_f32_e32 v38, v46, v38
	v_ldexp_f32 v47, v43, v39
	v_sub_f32_e32 v39, v48, v83
	v_cmp_gt_f32_e32 vcc, s91, v39
	v_sub_f32_e32 v43, v49, v83
	v_add_f32_e32 v38, v47, v38
	v_cndmask_b32_e32 v42, 0, v242, vcc
	v_add_f32_e32 v39, v39, v42
	v_cndmask_b32_e32 v42, 0, v243, vcc
	v_cmp_gt_f32_e32 vcc, s91, v43
	v_exp_f32_e32 v39, v39
	s_nop 0
	v_cndmask_b32_e32 v44, 0, v242, vcc
	v_add_f32_e32 v43, v43, v44
	v_exp_f32_e32 v43, v43
	v_ldexp_f32 v93, v39, v42
	v_cndmask_b32_e32 v39, 0, v243, vcc
	v_add_f32_e32 v38, v93, v38
	v_ldexp_f32 v95, v43, v39
	v_cmp_gt_f32_e32 vcc, s91, v18
	v_add_f32_e32 v39, v95, v38
	s_nop 0
	v_cndmask_b32_e32 v38, 0, v242, vcc
	v_add_f32_e32 v18, v18, v38
	v_cndmask_b32_e32 v38, 0, v243, vcc
	v_cmp_gt_f32_e32 vcc, s91, v19
	v_exp_f32_e32 v18, v18
	s_nop 0
	v_cndmask_b32_e32 v42, 0, v242, vcc
	v_add_f32_e32 v19, v19, v42
	v_exp_f32_e32 v19, v19
	v_ldexp_f32 v38, v18, v38
	v_add_f32_e32 v18, v38, v39
	v_cndmask_b32_e32 v39, 0, v243, vcc
	v_ldexp_f32 v39, v19, v39
	v_sub_f32_e32 v19, v20, v83
	v_cmp_gt_f32_e32 vcc, s91, v19
	v_add_f32_e32 v18, v39, v18
	s_nop 0
	v_cndmask_b32_e32 v20, 0, v242, vcc
	v_add_f32_e32 v19, v19, v20
	v_cndmask_b32_e32 v20, 0, v243, vcc
	v_cmp_gt_f32_e32 vcc, s91, v21
	v_exp_f32_e32 v19, v19
	s_nop 0
	v_cndmask_b32_e32 v42, 0, v242, vcc
	v_add_f32_e32 v21, v21, v42
	v_exp_f32_e32 v21, v21
	v_ldexp_f32 v44, v19, v20
	v_cndmask_b32_e32 v19, 0, v243, vcc
	v_add_f32_e32 v18, v44, v18
	v_ldexp_f32 v45, v21, v19
	v_sub_f32_e32 v19, v22, v83
	v_cmp_gt_f32_e32 vcc, s91, v19
	v_sub_f32_e32 v21, v23, v83
	v_add_f32_e32 v18, v45, v18
	v_cndmask_b32_e32 v20, 0, v242, vcc
	v_add_f32_e32 v19, v19, v20
	v_cndmask_b32_e32 v20, 0, v243, vcc
	v_cmp_gt_f32_e32 vcc, s91, v21
	v_exp_f32_e32 v19, v19
	s_nop 0
	v_cndmask_b32_e32 v22, 0, v242, vcc
	v_add_f32_e32 v21, v21, v22
	v_exp_f32_e32 v21, v21
	v_ldexp_f32 v91, v19, v20
	v_cndmask_b32_e32 v19, 0, v243, vcc
	v_add_f32_e32 v18, v91, v18
	v_ldexp_f32 v92, v21, v19
	v_sub_f32_e32 v19, v24, v83
	v_cmp_gt_f32_e32 vcc, s91, v19
	v_sub_f32_e32 v21, v25, v83
	v_add_f32_e32 v18, v92, v18
	v_cndmask_b32_e32 v20, 0, v242, vcc
	v_add_f32_e32 v19, v19, v20
	v_cndmask_b32_e32 v20, 0, v243, vcc
	v_cmp_gt_f32_e32 vcc, s91, v21
	v_exp_f32_e32 v19, v19
	s_nop 0
	v_cndmask_b32_e32 v22, 0, v242, vcc
	v_add_f32_e32 v21, v21, v22
	v_exp_f32_e32 v21, v21
	v_ldexp_f32 v101, v19, v20
	v_cndmask_b32_e32 v19, 0, v243, vcc
	v_add_f32_e32 v18, v101, v18
	v_ldexp_f32 v106, v21, v19
	v_sub_f32_e32 v19, v26, v83
	v_cmp_gt_f32_e32 vcc, s91, v19
	v_sub_f32_e32 v21, v27, v83
	v_add_f32_e32 v18, v106, v18
	v_cndmask_b32_e32 v20, 0, v242, vcc
	v_add_f32_e32 v19, v19, v20
	v_cndmask_b32_e32 v20, 0, v243, vcc
	v_cmp_gt_f32_e32 vcc, s91, v21
	v_exp_f32_e32 v19, v19
	s_nop 0
	v_cndmask_b32_e32 v22, 0, v242, vcc
	v_add_f32_e32 v21, v21, v22
	v_exp_f32_e32 v21, v21
	v_ldexp_f32 v42, v19, v20
	v_cndmask_b32_e32 v19, 0, v243, vcc
	v_add_f32_e32 v18, v42, v18
	v_ldexp_f32 v43, v21, v19
	v_sub_f32_e32 v19, v28, v83
	v_cmp_gt_f32_e32 vcc, s91, v19
	v_sub_f32_e32 v21, v29, v83
	v_add_f32_e32 v18, v43, v18
	v_cndmask_b32_e32 v20, 0, v242, vcc
	v_add_f32_e32 v19, v19, v20
	v_cndmask_b32_e32 v20, 0, v243, vcc
	v_cmp_gt_f32_e32 vcc, s91, v21
	v_exp_f32_e32 v19, v19
	s_nop 0
	v_cndmask_b32_e32 v22, 0, v242, vcc
	v_add_f32_e32 v21, v21, v22
	v_exp_f32_e32 v21, v21
	v_ldexp_f32 v89, v19, v20
	v_cndmask_b32_e32 v19, 0, v243, vcc
	v_add_f32_e32 v18, v89, v18
	v_ldexp_f32 v90, v21, v19
	v_sub_f32_e32 v19, v30, v83
	v_cmp_gt_f32_e32 vcc, s91, v19
	v_sub_f32_e32 v21, v31, v83
	v_add_f32_e32 v18, v90, v18
	v_cndmask_b32_e32 v20, 0, v242, vcc
	v_add_f32_e32 v19, v19, v20
	v_cndmask_b32_e32 v20, 0, v243, vcc
	v_cmp_gt_f32_e32 vcc, s91, v21
	v_exp_f32_e32 v19, v19
	s_nop 0
	v_cndmask_b32_e32 v22, 0, v242, vcc
	v_add_f32_e32 v21, v21, v22
	v_exp_f32_e32 v21, v21
	v_ldexp_f32 v99, v19, v20
	v_cndmask_b32_e32 v19, 0, v243, vcc
	v_add_f32_e32 v18, v99, v18
	v_ldexp_f32 v100, v21, v19
	v_sub_f32_e32 v19, v32, v83
	v_cmp_gt_f32_e32 vcc, s91, v19
	v_sub_f32_e32 v21, v33, v83
	v_add_f32_e32 v18, v100, v18
	v_cndmask_b32_e32 v20, 0, v242, vcc
	v_add_f32_e32 v19, v19, v20
	v_cndmask_b32_e32 v20, 0, v243, vcc
	v_cmp_gt_f32_e32 vcc, s91, v21
	v_exp_f32_e32 v19, v19
	s_nop 0
	v_cndmask_b32_e32 v22, 0, v242, vcc
	v_add_f32_e32 v21, v21, v22
	v_exp_f32_e32 v21, v21
	v_ldexp_f32 v124, v19, v20
	v_cndmask_b32_e32 v19, 0, v243, vcc
	v_cmp_gt_f32_e32 vcc, s91, v2
	v_ldexp_f32 v125, v21, v19
	v_add_f32_e32 v18, v124, v18
	v_cndmask_b32_e32 v19, 0, v242, vcc
	v_add_f32_e32 v2, v2, v19
	v_cndmask_b32_e32 v19, 0, v243, vcc
	v_cmp_gt_f32_e32 vcc, s91, v3
	v_exp_f32_e32 v2, v2
	v_add_f32_e32 v18, v125, v18
	v_cndmask_b32_e32 v20, 0, v242, vcc
	v_add_f32_e32 v3, v3, v20
	v_exp_f32_e32 v3, v3
	v_ldexp_f32 v48, v2, v19
	v_add_f32_e32 v2, v48, v18
	v_cndmask_b32_e32 v18, 0, v243, vcc
	v_ldexp_f32 v49, v3, v18
	v_sub_f32_e32 v3, v4, v83
	v_cmp_gt_f32_e32 vcc, s91, v3
	v_add_f32_e32 v2, v49, v2
	s_nop 0
	v_cndmask_b32_e32 v4, 0, v242, vcc
	v_add_f32_e32 v3, v3, v4
	v_cndmask_b32_e32 v4, 0, v243, vcc
	v_cmp_gt_f32_e32 vcc, s91, v5
	v_exp_f32_e32 v3, v3
	s_nop 0
	v_cndmask_b32_e32 v18, 0, v242, vcc
	v_add_f32_e32 v5, v5, v18
	v_exp_f32_e32 v5, v5
	v_ldexp_f32 v97, v3, v4
	v_cndmask_b32_e32 v3, 0, v243, vcc
	v_add_f32_e32 v2, v97, v2
	v_ldexp_f32 v98, v5, v3
	v_sub_f32_e32 v3, v6, v83
	v_cmp_gt_f32_e32 vcc, s91, v3
	v_sub_f32_e32 v5, v7, v83
; #define MFMA32(a, b, c) __builtin_amdgcn_mfma_f32_32x32x16_bf16((a), (b), (c), 0, 0, 0)
; DI void swa_item(const Params& P, int l, int n, int hk2, char* smem) {
;     ...
;     float den = 0.f;
; #pragma unroll
;     for (int tt = 0; tt < 5; ++tt)
; #pragma unroll
;       for (int r = 0; r < 16; ++r) { const float p = exp2f(st[tt][r] - mx); st[tt][r] = p; den += p; }
;     den += __shfl_xor(den, 32); den += exp2f(sinkv - mx);
;     f32x16 O[2];
; #pragma unroll
;     for (int i = 0; i < 2; ++i)
; #pragma unroll
;       for (int r = 0; r < 16; ++r) O[i][r] = 0.f;
; #pragma unroll
;     for (int tt = 0; tt < 5; ++tt)
; #pragma unroll
;       for (int s = 0; s < 2; ++s) { const bf16x8 pf = pack8(st[tt][8 * s], st[tt][8 * s + 1], st[tt][8 * s + 2], st[tt][8 * s + 3], st[tt][8 * s + 4], st[tt][8 * s + 5], st[tt][8 * s + 6], st[tt][8 * s + 7]);
; #pragma unroll
;         for (int i = 0; i < 2; ++i) { const char* vp = (const char*)sVt + (32 * i + lq) * 528 + (32 * (j + tt) + 16 * s + 4 * h) * 2;
;           const u32x2 lo = *(const u32x2*)vp, hi = *(const u32x2*)(vp + 16); u32x4 vv = {lo.x, lo.y, hi.x, hi.y};
;           O[i] = MFMA32(__builtin_bit_cast(bf16x8, vv), pf, O[i]); }
;         __builtin_amdgcn_sched_barrier(0); }
	v_add_f32_e32 v2, v98, v2
	v_cndmask_b32_e32 v4, 0, v242, vcc
	v_add_f32_e32 v3, v3, v4
	v_cndmask_b32_e32 v4, 0, v243, vcc
	v_cmp_gt_f32_e32 vcc, s91, v5
	v_exp_f32_e32 v3, v3
	v_cvt_pk_bf16_f32 v7, v66, v67
	v_cndmask_b32_e32 v6, 0, v242, vcc
	v_add_f32_e32 v5, v5, v6
	v_exp_f32_e32 v5, v5
	v_ldexp_f32 v122, v3, v4
	v_cndmask_b32_e32 v3, 0, v243, vcc
	v_add_f32_e32 v2, v122, v2
	v_ldexp_f32 v123, v5, v3
	v_sub_f32_e32 v3, v8, v83
	v_cmp_gt_f32_e32 vcc, s91, v3
	v_sub_f32_e32 v5, v9, v83
	v_add_f32_e32 v2, v123, v2
	v_cndmask_b32_e32 v4, 0, v242, vcc
	v_add_f32_e32 v3, v3, v4
	v_cndmask_b32_e32 v4, 0, v243, vcc
	v_cmp_gt_f32_e32 vcc, s91, v5
	v_exp_f32_e32 v3, v3
	v_cvt_pk_bf16_f32 v8, v68, v69
	v_cndmask_b32_e32 v6, 0, v242, vcc
	v_add_f32_e32 v5, v5, v6
	v_exp_f32_e32 v5, v5
	v_ldexp_f32 v128, v3, v4
	v_cndmask_b32_e32 v3, 0, v243, vcc
	v_add_f32_e32 v2, v128, v2
	v_ldexp_f32 v129, v5, v3
	v_sub_f32_e32 v3, v10, v83
	v_cmp_gt_f32_e32 vcc, s91, v3
	v_sub_f32_e32 v5, v11, v83
	v_add_f32_e32 v2, v129, v2
	v_cndmask_b32_e32 v4, 0, v242, vcc
	v_add_f32_e32 v3, v3, v4
	v_cndmask_b32_e32 v4, 0, v243, vcc
	v_cmp_gt_f32_e32 vcc, s91, v5
	v_exp_f32_e32 v3, v3
	v_cvt_pk_bf16_f32 v9, v72, v73
	v_cndmask_b32_e32 v6, 0, v242, vcc
	v_add_f32_e32 v5, v5, v6
	v_exp_f32_e32 v5, v5
	v_ldexp_f32 v94, v3, v4
	v_cndmask_b32_e32 v3, 0, v243, vcc
	v_add_f32_e32 v2, v94, v2
	v_ldexp_f32 v96, v5, v3
	v_sub_f32_e32 v3, v12, v83
	v_cmp_gt_f32_e32 vcc, s91, v3
	v_sub_f32_e32 v5, v13, v83
	v_add_f32_e32 v2, v96, v2
	v_cndmask_b32_e32 v4, 0, v242, vcc
	v_add_f32_e32 v3, v3, v4
	v_cndmask_b32_e32 v4, 0, v243, vcc
	v_cmp_gt_f32_e32 vcc, s91, v5
	v_exp_f32_e32 v3, v3
	s_nop 0
	v_cndmask_b32_e32 v6, 0, v242, vcc
	v_add_f32_e32 v5, v5, v6
	v_exp_f32_e32 v5, v5
	v_ldexp_f32 v113, v3, v4
	v_cndmask_b32_e32 v3, 0, v243, vcc
	v_add_f32_e32 v2, v113, v2
	v_ldexp_f32 v121, v5, v3
	v_sub_f32_e32 v3, v14, v83
	v_cmp_gt_f32_e32 vcc, s91, v3
	v_sub_f32_e32 v5, v15, v83
	v_add_f32_e32 v2, v121, v2
	v_cndmask_b32_e32 v4, 0, v242, vcc
	v_add_f32_e32 v3, v3, v4
	v_cndmask_b32_e32 v4, 0, v243, vcc
	v_cmp_gt_f32_e32 vcc, s91, v5
	v_exp_f32_e32 v3, v3
	s_nop 0
	v_cndmask_b32_e32 v6, 0, v242, vcc
	v_add_f32_e32 v5, v5, v6
	v_exp_f32_e32 v5, v5
	v_ldexp_f32 v126, v3, v4
	v_cndmask_b32_e32 v3, 0, v243, vcc
	v_add_f32_e32 v2, v126, v2
	v_ldexp_f32 v127, v5, v3
	v_sub_f32_e32 v3, v16, v83
	v_cmp_gt_f32_e32 vcc, s91, v3
	v_sub_f32_e32 v5, v84, v83
	v_add_f32_e32 v2, v127, v2
	v_cndmask_b32_e32 v4, 0, v242, vcc
	v_add_f32_e32 v3, v3, v4
	v_cndmask_b32_e32 v4, 0, v243, vcc
	v_cmp_gt_f32_e32 vcc, s91, v5
	v_exp_f32_e32 v3, v3
	v_sub_f32_e32 v16, v114, v83
	v_cndmask_b32_e32 v6, 0, v242, vcc
	v_add_f32_e32 v5, v5, v6
	v_exp_f32_e32 v5, v5
	v_ldexp_f32 v84, v3, v4
	v_cndmask_b32_e32 v3, 0, v243, vcc
	v_add_f32_e32 v2, v84, v2
	v_ldexp_f32 v130, v5, v3
	v_add_f32_e32 v14, v130, v2
	ds_bpermute_b32 v15, v82, v14
	v_lshl_add_u32 v82, v120, 6, v118
	ds_read2_b64 v[2:5], v82 offset1:2
	v_add_u32_e32 v67, 0x4000, v82
	ds_read2_b64 v[10:13], v67 offset0:64 offset1:66
	v_cmp_gt_f32_e32 vcc, s91, v16
	v_cvt_pk_bf16_f32 v6, v0, v17
	s_waitcnt lgkmcnt(2)
	v_add_f32_e32 v66, v14, v15
	v_cndmask_b32_e32 v83, 0, v242, vcc
	v_add_f32_e32 v0, v16, v83
	v_exp_f32_e32 v0, v0
	s_waitcnt lgkmcnt(1)
	v_mfma_f32_32x32x16_bf16 v[18:33], v[2:5], v[6:9], 0
	v_cndmask_b32_e32 v2, 0, v243, vcc
	v_ldexp_f32 v0, v0, v2
	s_waitcnt lgkmcnt(0)
	v_mfma_f32_32x32x16_bf16 v[2:17], v[10:13], v[6:9], 0
	v_cvt_pk_bf16_f32 v69, v74, v75
	ds_read2_b64 v[72:75], v82 offset0:4 offset1:6
	v_cvt_pk_bf16_f32 v68, v70, v71
	v_cvt_pk_bf16_f32 v70, v78, v79
	v_cvt_pk_bf16_f32 v71, v85, v86
	s_waitcnt lgkmcnt(0)
	s_nop 0
	v_mfma_f32_32x32x16_bf16 v[18:33], v[72:75], v[68:71], v[18:33]
	ds_read2_b64 v[72:75], v67 offset0:68 offset1:70
	s_waitcnt lgkmcnt(0)
	v_mfma_f32_32x32x16_bf16 v[2:17], v[72:75], v[68:71], v[2:17]
	ds_read2_b64 v[72:75], v82 offset0:8 offset1:10
	v_cvt_pk_bf16_f32 v68, v50, v51
	v_cvt_pk_bf16_f32 v69, v76, v77
	v_cvt_pk_bf16_f32 v70, v80, v81
	v_cvt_pk_bf16_f32 v71, v87, v88
	s_waitcnt lgkmcnt(0)
	s_nop 0
	v_mfma_f32_32x32x16_bf16 v[18:33], v[72:75], v[68:71], v[18:33]
	ds_read2_b64 v[72:75], v67 offset0:72 offset1:74
	s_waitcnt lgkmcnt(0)
	v_mfma_f32_32x32x16_bf16 v[2:17], v[72:75], v[68:71], v[2:17]
	ds_read2_b64 v[68:71], v82 offset0:12 offset1:14
	v_cvt_pk_bf16_f32 v50, v52, v53
	v_cvt_pk_bf16_f32 v51, v54, v55
	v_cvt_pk_bf16_f32 v52, v58, v59
	v_cvt_pk_bf16_f32 v53, v62, v63
	s_waitcnt lgkmcnt(0)
	s_nop 0
	v_mfma_f32_32x32x16_bf16 v[18:33], v[68:71], v[50:53], v[18:33]
	ds_read2_b64 v[68:71], v67 offset0:76 offset1:78
	s_waitcnt lgkmcnt(0)
	v_mfma_f32_32x32x16_bf16 v[2:17], v[68:71], v[50:53], v[2:17]
	v_cvt_pk_bf16_f32 v51, v56, v57
	ds_read2_b64 v[54:57], v82 offset0:16 offset1:18
	v_cvt_pk_bf16_f32 v50, v34, v35
	v_cvt_pk_bf16_f32 v52, v60, v61
	v_cvt_pk_bf16_f32 v53, v64, v65
	s_waitcnt lgkmcnt(0)
	s_nop 0
	v_mfma_f32_32x32x16_bf16 v[18:33], v[54:57], v[50:53], v[18:33]
	ds_read2_b64 v[54:57], v67 offset0:80 offset1:82
	s_waitcnt lgkmcnt(0)
	v_mfma_f32_32x32x16_bf16 v[2:17], v[54:57], v[50:53], v[2:17]
	ds_read2_b64 v[50:53], v82 offset0:20 offset1:22
	v_cvt_pk_bf16_f32 v34, v36, v37
	v_cvt_pk_bf16_f32 v35, v40, v41
	v_cvt_pk_bf16_f32 v36, v46, v47
	v_cvt_pk_bf16_f32 v37, v93, v95
	s_waitcnt lgkmcnt(0)
	s_nop 0
	v_mfma_f32_32x32x16_bf16 v[18:33], v[50:53], v[34:37], v[18:33]
	ds_read2_b64 v[50:53], v67 offset0:84 offset1:86
	s_waitcnt lgkmcnt(0)
; DI unsigned pack2(float lo, float hi) { f32x2 v = {lo, hi}; bf2_t b = __builtin_convertvector(v, bf2_t); return __builtin_bit_cast(unsigned, b); }
; #define MFMA32(a, b, c) __builtin_amdgcn_mfma_f32_32x32x16_bf16((a), (b), (c), 0, 0, 0)
; DI void swa_item(const Params& P, int l, int n, int hk2, char* smem) {
;     ...
;   for (int jj = 0; jj < 2; ++jj) {
;     const int j = 2 * (w & 1) + jj; const int qrow = 128 * n + 32 * j + lq;
;     bf16x8 qf[4];
; #pragma unroll
;     for (int s = 0; s < 4; ++s) qf[s] = *(const bf16x8*)(proj + (size_t)qrow * DINP + C_CQ + hq * 64 + 16 * s + 8 * h);
;     f32x16 st[5];
;     bf16x8 kf[2][4];
;     { const int kp = 128 * (n - 1) + 32 * j + lq;
; #pragma unroll
;       for (int s = 0; s < 4; ++s) { kf[0][s] = (bf16x8){0, 0, 0, 0, 0, 0, 0, 0}; if (kp >= 0) kf[0][s] = *(const bf16x8*)(proj + (size_t)kp * DINP + C_CK + hk2 * 64 + 16 * s + 8 * h); } }
;     ...
; #pragma unroll
;     for (int tt = 0; tt < 5; ++tt)
; #pragma unroll
;       for (int s = 0; s < 2; ++s) { const bf16x8 pf = pack8(st[tt][8 * s], st[tt][8 * s + 1], st[tt][8 * s + 2], st[tt][8 * s + 3], st[tt][8 * s + 4], st[tt][8 * s + 5], st[tt][8 * s + 6], st[tt][8 * s + 7]);
; #pragma unroll
;         for (int i = 0; i < 2; ++i) { const char* vp = (const char*)sVt + (32 * i + lq) * 528 + (32 * (j + tt) + 16 * s + 4 * h) * 2;
;           const u32x2 lo = *(const u32x2*)vp, hi = *(const u32x2*)(vp + 16); u32x4 vv = {lo.x, lo.y, hi.x, hi.y};
;           O[i] = MFMA32(__builtin_bit_cast(bf16x8, vv), pf, O[i]); }
;         __builtin_amdgcn_sched_barrier(0); }
;     const float inv = 1.f / den;
;     bf16_t* op = mixin + (size_t)qrow * 2048 + 1536 + hq * 64;
; #pragma unroll
;     for (int i = 0; i < 2; ++i)
; #pragma unroll
;       for (int rg = 0; rg < 4; ++rg) { u32x2 pk = {pack2(O[i][4 * rg] * inv, O[i][4 * rg + 1] * inv), pack2(O[i][4 * rg + 2] * inv, O[i][4 * rg + 3] * inv)};
;         *(u32x2*)(op + 32 * i + 8 * rg + 4 * h) = pk; }
	v_mfma_f32_32x32x16_bf16 v[2:17], v[50:53], v[34:37], v[2:17]
	v_cvt_pk_bf16_f32 v34, v38, v39
	ds_read2_b64 v[38:41], v82 offset0:24 offset1:26
	v_cvt_pk_bf16_f32 v35, v44, v45
	v_cvt_pk_bf16_f32 v36, v91, v92
	v_cvt_pk_bf16_f32 v37, v101, v106
	s_waitcnt lgkmcnt(0)
	s_nop 0
	v_mfma_f32_32x32x16_bf16 v[18:33], v[38:41], v[34:37], v[18:33]
	ds_read2_b64 v[38:41], v67 offset0:88 offset1:90
	s_waitcnt lgkmcnt(0)
	v_mfma_f32_32x32x16_bf16 v[2:17], v[38:41], v[34:37], v[2:17]
	ds_read2_b64 v[38:41], v82 offset0:28 offset1:30
	v_cvt_pk_bf16_f32 v34, v42, v43
	v_cvt_pk_bf16_f32 v35, v89, v90
	v_cvt_pk_bf16_f32 v36, v99, v100
	v_cvt_pk_bf16_f32 v37, v124, v125
	s_waitcnt lgkmcnt(0)
	s_nop 0
	v_mfma_f32_32x32x16_bf16 v[18:33], v[38:41], v[34:37], v[18:33]
	ds_read2_b64 v[38:41], v67 offset0:92 offset1:94
	s_waitcnt lgkmcnt(0)
	v_mfma_f32_32x32x16_bf16 v[2:17], v[38:41], v[34:37], v[2:17]
	ds_read2_b64 v[38:41], v82 offset0:32 offset1:34
	v_cvt_pk_bf16_f32 v34, v48, v49
	v_cvt_pk_bf16_f32 v35, v97, v98
	v_cvt_pk_bf16_f32 v36, v122, v123
	v_cvt_pk_bf16_f32 v37, v128, v129
	s_waitcnt lgkmcnt(0)
	s_nop 0
	v_mfma_f32_32x32x16_bf16 v[18:33], v[38:41], v[34:37], v[18:33]
	ds_read2_b64 v[38:41], v67 offset0:96 offset1:98
	s_waitcnt lgkmcnt(0)
	v_mfma_f32_32x32x16_bf16 v[2:17], v[38:41], v[34:37], v[2:17]
	ds_read2_b64 v[38:41], v82 offset0:36 offset1:38
	v_cvt_pk_bf16_f32 v34, v94, v96
	v_cvt_pk_bf16_f32 v35, v113, v121
	v_cvt_pk_bf16_f32 v36, v126, v127
	v_cvt_pk_bf16_f32 v37, v84, v130
	s_waitcnt lgkmcnt(0)
	s_nop 0
	v_mfma_f32_32x32x16_bf16 v[18:33], v[38:41], v[34:37], v[18:33]
	ds_read2_b64 v[38:41], v67 offset0:100 offset1:102
	s_waitcnt lgkmcnt(0)
	v_mfma_f32_32x32x16_bf16 v[2:17], v[38:41], v[34:37], v[2:17]
	v_add_f32_e32 v0, v0, v66
	v_div_scale_f32 v34, s[2:3], v0, v0, 1.0
	v_rcp_f32_e32 v35, v34
	v_div_scale_f32 v36, vcc, 1.0, v0, 1.0
	s_mov_b64 s[2:3], 0x62e8c00
	v_fma_f32 v37, -v34, v35, 1.0
	v_fmac_f32_e32 v35, v37, v35
	v_mul_f32_e32 v37, v36, v35
	v_fma_f32 v38, -v34, v37, v36
	v_fmac_f32_e32 v37, v38, v35
	v_fma_f32 v34, -v34, v37, v36
	v_div_fmas_f32 v34, v34, v35, v37
	v_div_fixup_f32 v34, v34, v0, 1.0
	v_lshlrev_b32_e32 v0, 12, v119
	v_lshl_add_u64 v[36:37], v[102:103], 0, v[0:1]
	v_lshl_add_u64 v[36:37], v[108:109], 1, v[36:37]
	v_lshlrev_b32_e32 v0, 1, v110
	v_lshl_add_u64 v[36:37], v[36:37], 0, v[0:1]
	v_pk_mul_f32 v[18:19], v[18:19], v[34:35] op_sel_hi:[1,0]
	v_pk_mul_f32 v[20:21], v[20:21], v[34:35] op_sel_hi:[1,0]
	v_cvt_pk_bf16_f32 v18, v18, v19
	v_cvt_pk_bf16_f32 v19, v20, v21
	v_add_co_u32_e32 v20, vcc, s92, v36
	v_pk_mul_f32 v[2:3], v[2:3], v[34:35] op_sel_hi:[1,0]
	v_pk_mul_f32 v[4:5], v[4:5], v[34:35] op_sel_hi:[1,0]
	v_lshl_add_u64 v[38:39], v[36:37], 0, s[2:3]
	v_addc_co_u32_e32 v21, vcc, 0, v37, vcc
	v_cvt_pk_bf16_f32 v2, v2, v3
	v_cvt_pk_bf16_f32 v3, v4, v5
	global_store_dwordx2 v[20:21], v[18:19], off offset:3072
	v_pk_mul_f32 v[18:19], v[22:23], v[34:35] op_sel_hi:[1,0]
	v_pk_mul_f32 v[20:21], v[24:25], v[34:35] op_sel_hi:[1,0]
	global_store_dwordx2 v[38:39], v[2:3], off offset:64
	v_pk_mul_f32 v[2:3], v[6:7], v[34:35] op_sel_hi:[1,0]
	v_pk_mul_f32 v[4:5], v[8:9], v[34:35] op_sel_hi:[1,0]
	v_cvt_pk_bf16_f32 v18, v18, v19
	v_cvt_pk_bf16_f32 v19, v20, v21
	v_cvt_pk_bf16_f32 v2, v2, v3
	v_cvt_pk_bf16_f32 v3, v4, v5
	global_store_dwordx2 v[38:39], v[18:19], off offset:16
	v_pk_mul_f32 v[18:19], v[26:27], v[34:35] op_sel_hi:[1,0]
	v_pk_mul_f32 v[20:21], v[28:29], v[34:35] op_sel_hi:[1,0]
	global_store_dwordx2 v[38:39], v[2:3], off offset:80
	v_pk_mul_f32 v[2:3], v[10:11], v[34:35] op_sel_hi:[1,0]
	v_pk_mul_f32 v[4:5], v[12:13], v[34:35] op_sel_hi:[1,0]
	v_cvt_pk_bf16_f32 v18, v18, v19
	v_cvt_pk_bf16_f32 v19, v20, v21
	v_cvt_pk_bf16_f32 v2, v2, v3
	v_cvt_pk_bf16_f32 v3, v4, v5
	global_store_dwordx2 v[38:39], v[18:19], off offset:32
	v_pk_mul_f32 v[18:19], v[30:31], v[34:35] op_sel_hi:[1,0]
	v_pk_mul_f32 v[20:21], v[32:33], v[34:35] op_sel_hi:[1,0]
	global_store_dwordx2 v[38:39], v[2:3], off offset:96
	v_pk_mul_f32 v[2:3], v[14:15], v[34:35] op_sel_hi:[1,0]
	v_pk_mul_f32 v[4:5], v[16:17], v[34:35] op_sel_hi:[1,0]
	v_cvt_pk_bf16_f32 v18, v18, v19
	v_cvt_pk_bf16_f32 v19, v20, v21
	v_cvt_pk_bf16_f32 v2, v2, v3
	v_cvt_pk_bf16_f32 v3, v4, v5
	s_andn2_b64 vcc, exec, s[8:9]
	s_mov_b64 s[8:9], 0
	global_store_dwordx2 v[38:39], v[18:19], off offset:48
	global_store_dwordx2 v[38:39], v[2:3], off offset:112
	s_cbranch_vccz .LBB0_639
.LBB0_606:
	v_or_b32_e32 v120, s15, v115
	v_lshlrev_b32_e32 v40, 5, v120
	v_or_b32_e32 v119, v116, v40
	v_mul_lo_u32 v0, v119, s90
	v_lshl_add_u64 v[2:3], v[0:1], 1, v[104:105]
	v_lshl_add_u64 v[2:3], v[108:109], 1, v[2:3]
	v_mov_b32_e32 v113, v1
	v_lshl_add_u64 v[2:3], v[2:3], 0, v[112:113]
	s_mov_b64 s[2:3], 0x2520
	v_lshl_add_u64 v[6:7], v[2:3], 0, s[2:3]
	v_add_co_u32_e32 v2, vcc, 0x2000, v2
	v_or_b32_e32 v106, s11, v40
	s_nop 0
	v_addc_co_u32_e32 v3, vcc, 0, v3, vcc
	global_load_dwordx4 v[90:93], v[6:7], off offset:32
	global_load_dwordx4 v[82:85], v[6:7], off offset:64
	s_nop 0
	global_load_dwordx4 v[2:5], v[2:3], off offset:1312
	s_nop 0
	global_load_dwordx4 v[86:89], v[6:7], off offset:96
	v_or_b32_e32 v0, v106, v111
	v_mad_u64_u32 v[6:7], s[2:3], v0, s81, v[104:105]
	s_lshl_b32 s62, s10, 1
	v_lshl_add_u64 v[6:7], v[6:7], 0, s[62:63]
	v_lshl_add_u64 v[6:7], v[6:7], 0, v[112:113]
	v_cndmask_b32_e64 v0, 0, 1, s[4:5]
	v_cmp_ne_u32_e64 s[2:3], 1, v0
	s_andn2_b64 vcc, exec, s[4:5]
	v_lshl_add_u64 v[14:15], v[6:7], 0, s[58:59]
	s_cbranch_vccnz .LBB0_611
	global_load_dwordx4 v[6:9], v[14:15], off
	s_and_b64 vcc, exec, s[2:3]
	s_cbranch_vccz .LBB0_612

; #define MFMA32(a, b, c) __builtin_amdgcn_mfma_f32_32x32x16_bf16((a), (b), (c), 0, 0, 0)
; DI void swa_item(const Params& P, int l, int n, int hk2, char* smem) {
;     ...
;     { const int kp = 128 * (n - 1) + 32 * j + lq;
; #pragma unroll
;       for (int s = 0; s < 4; ++s) { kf[0][s] = (bf16x8){0, 0, 0, 0, 0, 0, 0, 0}; if (kp >= 0) kf[0][s] = *(const bf16x8*)(proj + (size_t)kp * DINP + C_CK + hk2 * 64 + 16 * s + 8 * h); } }
; #pragma unroll
;     for (int tt = 0; tt < 5; ++tt) {
;       if (tt + 1 < 5) { const int kp = 128 * (n - 1) + 32 * (j + tt + 1) + lq;
; #pragma unroll
;         for (int s = 0; s < 4; ++s) { kf[(tt + 1) & 1][s] = (bf16x8){0, 0, 0, 0, 0, 0, 0, 0}; if (kp >= 0) kf[(tt + 1) & 1][s] = *(const bf16x8*)(proj + (size_t)kp * DINP + C_CK + hk2 * 64 + 16 * s + 8 * h); } }
;       __builtin_amdgcn_sched_barrier(0);
; #pragma unroll
;       for (int r = 0; r < 16; ++r) st[tt][r] = 0.f;
; #pragma unroll
;       for (int s = 0; s < 4; ++s) st[tt] = MFMA32(kf[tt & 1][s], qf[s], st[tt]);
;       __builtin_amdgcn_sched_barrier(0);
;     }
.LBB0_612:
	global_load_dwordx4 v[10:13], v[14:15], off offset:32
	s_and_b64 vcc, exec, s[2:3]
	s_cbranch_vccnz .LBB0_609
.LBB0_613:
	global_load_dwordx4 v[22:25], v[14:15], off offset:64
	s_and_b64 vcc, exec, s[2:3]
	s_cbranch_vccnz .LBB0_610
.LBB0_614:
	global_load_dwordx4 v[26:29], v[14:15], off offset:96
.LBB0_615:
	v_add_u32_e32 v0, s12, v40
	v_or_b32_e32 v14, v0, v111
	v_mad_u64_u32 v[14:15], s[2:3], v14, s81, v[104:105]
	v_lshl_add_u64 v[14:15], v[14:15], 0, s[62:63]
	v_mov_b32_e32 v113, v1
	v_lshl_add_u64 v[14:15], v[14:15], 0, v[112:113]
	v_cmp_lt_i32_e32 vcc, -1, v0
	v_lshl_add_u64 v[38:39], v[14:15], 0, s[58:59]
	v_mov_b32_e32 v14, 0
	v_mov_b32_e32 v18, 0
	v_mov_b32_e32 v19, 0
	v_mov_b32_e32 v20, 0
	v_mov_b32_e32 v21, 0
	s_and_saveexec_b64 s[2:3], vcc
	s_cbranch_execz .LBB0_617
	global_load_dwordx4 v[18:21], v[38:39], off
.LBB0_617:
	s_or_b64 exec, exec, s[2:3]
	v_mov_b32_e32 v15, 0
	v_mov_b32_e32 v16, 0
	v_mov_b32_e32 v17, 0
	s_and_saveexec_b64 s[2:3], vcc
	s_cbranch_execz .LBB0_619
	global_load_dwordx4 v[14:17], v[38:39], off offset:32
.LBB0_619:
	s_or_b64 exec, exec, s[2:3]
	v_mov_b32_e32 v30, 0
	v_mov_b32_e32 v34, 0
	v_mov_b32_e32 v35, 0
	v_mov_b32_e32 v36, 0
	v_mov_b32_e32 v37, 0
	s_and_saveexec_b64 s[2:3], vcc
	s_cbranch_execz .LBB0_621
	global_load_dwordx4 v[34:37], v[38:39], off offset:64
.LBB0_621:
	s_or_b64 exec, exec, s[2:3]
	v_mov_b32_e32 v31, 0
	v_mov_b32_e32 v32, 0
	v_mov_b32_e32 v33, 0
	s_and_saveexec_b64 s[2:3], vcc
	s_cbranch_execz .LBB0_623
	global_load_dwordx4 v[30:33], v[38:39], off offset:96
.LBB0_623:
	s_or_b64 exec, exec, s[2:3]
	s_waitcnt vmcnt(0) lgkmcnt(0)
	v_mfma_f32_32x32x16_bf16 v[66:81], v[6:9], v[2:5], 0
	v_mfma_f32_32x32x16_bf16 v[66:81], v[10:13], v[90:93], v[66:81]
	v_mfma_f32_32x32x16_bf16 v[66:81], v[22:25], v[82:85], v[66:81]
	v_mfma_f32_32x32x16_bf16 v[66:81], v[26:29], v[86:89], v[66:81]
	v_add_u32_e32 v0, s13, v40
	v_or_b32_e32 v6, v0, v111
	v_mad_u64_u32 v[6:7], s[2:3], v6, s81, v[104:105]
	v_lshl_add_u64 v[6:7], v[6:7], 0, s[62:63]
	v_mov_b32_e32 v113, v1
	v_lshl_add_u64 v[6:7], v[6:7], 0, v[112:113]
	v_cmp_lt_i32_e32 vcc, -1, v0
	v_lshl_add_u64 v[38:39], v[6:7], 0, s[58:59]
	v_mov_b32_e32 v6, 0
	v_mov_b32_e32 v10, 0
	v_mov_b32_e32 v11, 0
	v_mov_b32_e32 v12, 0
	v_mov_b32_e32 v13, 0
	s_and_saveexec_b64 s[2:3], vcc
	s_cbranch_execz .LBB0_625
	global_load_dwordx4 v[10:13], v[38:39], off
.LBB0_625:
	s_or_b64 exec, exec, s[2:3]
	v_mov_b32_e32 v7, 0
	v_mov_b32_e32 v8, 0
	v_mov_b32_e32 v9, 0
	s_and_saveexec_b64 s[2:3], vcc
	s_cbranch_execz .LBB0_627
	global_load_dwordx4 v[6:9], v[38:39], off offset:32
.LBB0_627:
	s_or_b64 exec, exec, s[2:3]
	v_mov_b32_e32 v22, 0
	v_mov_b32_e32 v26, 0
	v_mov_b32_e32 v27, 0
	v_mov_b32_e32 v28, 0
	v_mov_b32_e32 v29, 0
	s_and_saveexec_b64 s[2:3], vcc
	s_cbranch_execz .LBB0_629
	global_load_dwordx4 v[26:29], v[38:39], off offset:64
.LBB0_629:
	s_or_b64 exec, exec, s[2:3]
	v_mov_b32_e32 v23, 0
	v_mov_b32_e32 v24, 0
	v_mov_b32_e32 v25, 0
	s_and_saveexec_b64 s[2:3], vcc
	s_cbranch_execz .LBB0_631
	global_load_dwordx4 v[22:25], v[38:39], off offset:96
.LBB0_631:
	s_or_b64 exec, exec, s[2:3]
	v_mfma_f32_32x32x16_bf16 v[50:65], v[18:21], v[2:5], 0
	v_mfma_f32_32x32x16_bf16 v[50:65], v[14:17], v[90:93], v[50:65]
	v_mfma_f32_32x32x16_bf16 v[50:65], v[34:37], v[82:85], v[50:65]
	v_mfma_f32_32x32x16_bf16 v[50:65], v[30:33], v[86:89], v[50:65]
	v_add_u32_e32 v0, s14, v40
	v_or_b32_e32 v14, v0, v111
	v_mad_u64_u32 v[14:15], s[2:3], v14, s81, v[104:105]
	v_lshl_add_u64 v[14:15], v[14:15], 0, s[62:63]
	v_mov_b32_e32 v113, v1
	v_lshl_add_u64 v[14:15], v[14:15], 0, v[112:113]
	v_cmp_lt_i32_e32 vcc, -1, v0
	v_lshl_add_u64 v[30:31], v[14:15], 0, s[58:59]
	v_mov_b32_e32 v14, 0
	v_mov_b32_e32 v18, 0
	v_mov_b32_e32 v19, 0
	v_mov_b32_e32 v20, 0
	v_mov_b32_e32 v21, 0
	s_and_saveexec_b64 s[2:3], vcc
	s_cbranch_execz .LBB0_633
	global_load_dwordx4 v[18:21], v[30:31], off
.LBB0_633:
	s_or_b64 exec, exec, s[2:3]
	v_mov_b32_e32 v15, 0
	v_mov_b32_e32 v16, 0
	v_mov_b32_e32 v17, 0
	s_and_saveexec_b64 s[2:3], vcc
	s_cbranch_execz .LBB0_635
	global_load_dwordx4 v[14:17], v[30:31], off offset:32
.LBB0_635:
	s_or_b64 exec, exec, s[2:3]
	v_mov_b32_e32 v94, 0
	v_mov_b32_e32 v98, 0
	v_mov_b32_e32 v99, 0
	v_mov_b32_e32 v100, 0
	v_mov_b32_e32 v101, 0
	s_and_saveexec_b64 s[2:3], vcc
	s_cbranch_execz .LBB0_637
	global_load_dwordx4 v[98:101], v[30:31], off offset:64
.LBB0_637:
	s_or_b64 exec, exec, s[2:3]
	v_mov_b32_e32 v95, 0
	v_mov_b32_e32 v96, 0
	v_mov_b32_e32 v97, 0
	s_and_saveexec_b64 s[2:3], vcc
	s_cbranch_execz .LBB0_605
	global_load_dwordx4 v[94:97], v[30:31], off offset:96
	s_branch .LBB0_605

; DI void mla_attn_item(const Params& P, int hd, int b, char* smem) {
;     ...
;   const int q = 128 * b + 32 * wq + lq;
;   bf16x8 qf[12];
;   {
;     const float* qp = qraw + (size_t)q * 768 + hd * 192 + 8 * h;
;     const float sc = 0.07216878364870322f * LOG2E;
; #pragma unroll
;     for (int s = 0; s < 8; ++s) { const f32x4 a = *(const f32x4*)(qp + 16 * s), c = *(const f32x4*)(qp + 16 * s + 4);
;       qf[s] = pack8(a.x * sc, a.y * sc, a.z * sc, a.w * sc, c.x * sc, c.y * sc, c.z * sc, c.w * sc); }
;     const double pq = (double)P.pos[q];
; #pragma unroll
;     for (int s2 = 0; s2 < 2; ++s2) {
;       const f32x4 a0 = *(const f32x4*)(qp + 128 + 16 * s2), a1 = *(const f32x4*)(qp + 128 + 16 * s2 + 4);
;       const f32x4 b0 = *(const f32x4*)(qp + 160 + 16 * s2), b1 = *(const f32x4*)(qp + 160 + 16 * s2 + 4);
;       float x1[8] = {a0.x, a0.y, a0.z, a0.w, a1.x, a1.y, a1.z, a1.w}, x2[8] = {b0.x, b0.y, b0.z, b0.w, b1.x, b1.y, b1.z, b1.w}, o1[8], o2[8];
; #pragma unroll
;       for (int j = 0; j < 8; ++j) { double fr = pq * kInvFreq2Pi[16 * s2 + 8 * h + j]; fr -= floor(fr); const float ff = (float)fr;
;         const float sn = __builtin_amdgcn_sinf(ff), cs = __builtin_amdgcn_cosf(ff);
;         o1[j] = (x1[j] * cs - x2[j] * sn) * sc; o2[j] = (x2[j] * cs + x1[j] * sn) * sc; }
;       qf[8 + s2] = pack8(o1[0], o1[1], o1[2], o1[3], o1[4], o1[5], o1[6], o1[7]);
;       qf[10 + s2] = pack8(o2[0], o2[1], o2[2], o2[3], o2[4], o2[5], o2[6], o2[7]);
;     }
.LBB0_640:
	s_and_b64 vcc, exec, s[2:3]
	s_cbranch_vccz .LBB0_660
	v_mov_b32_e32 v187, v206
	global_load_dwordx2 v[184:185], v1, s[40:41] offset:1224
	global_load_dwordx2 v[2:3], v1, s[40:41] offset:1040
	s_add_i32 s2, s96, -16
	s_lshr_b32 s8, s2, 2
	v_bfe_u32 v209, v187, 6, 2
	s_sub_i32 s9, 0x7f, s8
	v_lshlrev_b32_e32 v39, 5, v209
	v_and_b32_e32 v38, 31, v187
	v_lshl_or_b32 v213, s9, 7, v39
	s_and_b32 s97, s96, 3
	v_or_b32_e32 v186, v213, v38
	s_movk_i32 s4, 0xc00
	s_mov_b32 s3, s63
	s_mul_i32 s2, s97, 0x300
	v_and_b32_e32 v0, 32, v187
	v_bfe_u32 v40, v187, 5, 1
	v_lshlrev_b32_e32 v41, 6, v40
	s_mul_i32 s62, s97, 0x600000
	v_ashrrev_i32_e32 v221, 8, v187
	v_lshlrev_b32_e32 v216, 2, v40
	v_lshlrev_b32_e32 v222, 6, v221
	s_movk_i32 s61, 0x100
	v_and_b32_e32 v215, 63, v187
	v_lshrrev_b32_e32 v214, 6, v187
	v_mov_b32_e32 v229, 0xf149f2ca
	v_mov_b32_e32 v212, 0
	s_mov_b32 s60, -2
	s_waitcnt vmcnt(0)
	v_mad_u64_u32 v[4:5], s[4:5], v186, s4, v[184:185]
	v_lshl_add_u64 v[4:5], v[4:5], 0, s[2:3]
	v_lshl_add_u64 v[4:5], v[4:5], 0, v[0:1]
	s_mov_b32 s2, 0xa2e8000
	v_add_co_u32_e32 v6, vcc, s2, v4
	s_mov_b64 s[2:3], 0xa2e8000
	v_lshlrev_b32_e32 v0, 2, v186
	v_addc_co_u32_e32 v7, vcc, 0, v5, vcc
	v_lshl_add_u64 v[18:19], v[4:5], 0, s[2:3]
	v_lshl_add_u64 v[2:3], v[2:3], 0, v[0:1]
	global_load_dwordx4 v[20:23], v[6:7], off
	global_load_dwordx4 v[24:27], v[18:19], off offset:16
	global_load_dwordx4 v[28:31], v[18:19], off offset:64
	global_load_dwordx4 v[32:35], v[18:19], off offset:80
	global_load_dwordx4 v[42:45], v[18:19], off offset:128
	global_load_dwordx4 v[46:49], v[18:19], off offset:144
	global_load_dwordx4 v[50:53], v[18:19], off offset:192
	global_load_dwordx4 v[54:57], v[18:19], off offset:208
	global_load_dwordx4 v[58:61], v[18:19], off offset:256
	global_load_dwordx4 v[62:65], v[18:19], off offset:272
	global_load_dwordx4 v[66:69], v[18:19], off offset:320
	global_load_dwordx4 v[70:73], v[18:19], off offset:336
	global_load_dwordx4 v[74:77], v[18:19], off offset:384
	global_load_dwordx4 v[78:81], v[18:19], off offset:400
	global_load_dwordx4 v[82:85], v[18:19], off offset:448
	global_load_dword v0, v[2:3], off
	s_getpc_b64 s[4:5]
	s_add_u32 s4, s4, kInvFreq2Pi@rel32@lo+4
	s_addc_u32 s5, s5, kInvFreq2Pi@rel32@hi+12
	global_load_dwordx4 v[86:89], v[18:19], off offset:464
	global_load_dwordx4 v[90:93], v41, s[4:5] offset:16
	global_load_dwordx4 v[128:131], v41, s[4:5]
	s_getpc_b64 s[2:3]
	s_add_u32 s2, s2, kInvFreq2Pi@rel32@lo+132
	s_addc_u32 s3, s3, kInvFreq2Pi@rel32@hi+140
	global_load_dwordx4 v[132:135], v41, s[4:5] offset:48
	global_load_dwordx4 v[136:139], v41, s[4:5] offset:32
	global_load_dwordx4 v[10:13], v41, s[2:3] offset:16
	global_load_dwordx4 v[14:17], v41, s[2:3]
	global_load_dwordx4 v[140:143], v[18:19], off offset:512
	global_load_dwordx4 v[144:147], v[18:19], off offset:528
	global_load_dwordx4 v[148:151], v[18:19], off offset:656
	global_load_dwordx4 v[152:155], v[18:19], off offset:640
	global_load_dwordx4 v[2:5], v[18:19], off offset:592
	global_load_dwordx4 v[6:9], v[18:19], off offset:720
	v_lshl_add_u64 v[36:37], v[184:185], 0, s[62:63]
	s_lshl_b32 s62, s97, 22
	s_mov_b64 s[4:5], 0xd2e8000
	v_lshl_add_u64 v[188:189], v[36:37], 0, s[4:5]
	s_lshl_b32 s56, s9, 1
	s_or_b32 s57, s56, 1
	s_waitcnt vmcnt(0) lgkmcnt(0)
	v_pk_mul_f32 v[24:25], v[24:25], s[54:55] op_sel_hi:[1,0]
	v_pk_mul_f32 v[26:27], v[26:27], s[54:55] op_sel_hi:[1,0]
	v_pk_mul_f32 v[94:95], v[34:35], s[54:55] op_sel_hi:[1,0]
	v_pk_mul_f32 v[28:29], v[28:29], s[54:55] op_sel_hi:[1,0]
	v_pk_mul_f32 v[30:31], v[30:31], s[54:55] op_sel_hi:[1,0]
	v_cvt_pk_bf16_f32 v98, v24, v25
	v_cvt_pk_bf16_f32 v99, v26, v27
	v_cvt_pk_bf16_f32 v100, v28, v29
	v_cvt_pk_bf16_f32 v101, v30, v31
	v_pk_mul_f32 v[46:47], v[46:47], s[54:55] op_sel_hi:[1,0]
	v_pk_mul_f32 v[32:33], v[32:33], s[54:55] op_sel_hi:[1,0]
	v_cvt_pk_bf16_f32 v106, v46, v47
	v_pk_mul_f32 v[20:21], v[20:21], s[54:55] op_sel_hi:[1,0]
	v_pk_mul_f32 v[22:23], v[22:23], s[54:55] op_sel_hi:[1,0]
	v_cvt_f64_i32_e32 v[34:35], v0
	v_cvt_pk_bf16_f32 v96, v20, v21
	v_cvt_pk_bf16_f32 v97, v22, v23
	v_mul_f64 v[20:21], v[128:129], v[34:35]
	v_mul_f64 v[22:23], v[130:131], v[34:35]
	v_mul_f64 v[24:25], v[90:91], v[34:35]
	v_mul_f64 v[26:27], v[92:93], v[34:35]
	v_mul_f64 v[28:29], v[136:137], v[34:35]
	v_mul_f64 v[30:31], v[138:139], v[34:35]
	v_floor_f64_e32 v[20:21], v[20:21]
	v_floor_f64_e32 v[22:23], v[22:23]
	v_floor_f64_e32 v[24:25], v[24:25]
	v_floor_f64_e32 v[26:27], v[26:27]
	v_floor_f64_e32 v[28:29], v[28:29]
	v_floor_f64_e32 v[30:31], v[30:31]
	v_fma_f64 v[20:21], v[128:129], v[34:35], -v[20:21]
	v_fma_f64 v[22:23], v[130:131], v[34:35], -v[22:23]
	v_fma_f64 v[24:25], v[90:91], v[34:35], -v[24:25]
	v_fma_f64 v[26:27], v[92:93], v[34:35], -v[26:27]
	v_fma_f64 v[28:29], v[136:137], v[34:35], -v[28:29]
	v_fma_f64 v[30:31], v[138:139], v[34:35], -v[30:31]
	v_cvt_f32_f64_e32 v0, v[20:21]
	v_cvt_f32_f64_e32 v23, v[22:23]
	v_cvt_f32_f64_e32 v25, v[24:25]
	v_cvt_f32_f64_e32 v27, v[26:27]
	v_cvt_f32_f64_e32 v46, v[28:29]
	v_cvt_f32_f64_e32 v47, v[30:31]
	v_sin_f32_e32 v20, v0
	v_sin_f32_e32 v21, v23
	v_sin_f32_e32 v24, v25
	v_cos_f32_e32 v26, v25
	v_sin_f32_e32 v25, v27
	v_cos_f32_e32 v22, v0
	v_cos_f32_e32 v23, v23
	v_cos_f32_e32 v27, v27
	v_sin_f32_e32 v30, v46
	v_sin_f32_e32 v31, v47
	v_cos_f32_e32 v46, v46
	v_cos_f32_e32 v47, v47
	v_pk_mul_f32 v[48:49], v[48:49], s[54:55] op_sel_hi:[1,0]
	v_cvt_pk_bf16_f32 v102, v32, v33
	v_pk_mul_f32 v[28:29], v[152:153], v[20:21]
	v_pk_mul_f32 v[20:21], v[140:141], v[20:21]
	v_pk_mul_f32 v[32:33], v[154:155], v[24:25]
	v_pk_mul_f32 v[24:25], v[142:143], v[24:25]
; #define AT_LOAD(RK, RV, T) { const size_t ko_ = (size_t)(T) * 64 * 192; const int vo_ = (T) * 64; \
;     _Pragma("unroll") for (int i = 0; i < 3; ++i) { const int id = tid + NT * i, row = id / 24, cc = id % 24; RK[i] = *(const u32x4*)(Kg + ko_ + row * 192 + cc * 8); } \
;     _Pragma("unroll") for (int i = 0; i < 2; ++i) RV[i] = *(const u32x4*)(Vg + (size_t)(vrow + 64 * i) * S_ + vo_ + vcc * 8); }
; DI void mla_attn_item(const Params& P, int hd, int b, char* smem) {
;     ...
;     const double pq = (double)P.pos[q];
; #pragma unroll
;     for (int s2 = 0; s2 < 2; ++s2) {
;       const f32x4 a0 = *(const f32x4*)(qp + 128 + 16 * s2), a1 = *(const f32x4*)(qp + 128 + 16 * s2 + 4);
;       const f32x4 b0 = *(const f32x4*)(qp + 160 + 16 * s2), b1 = *(const f32x4*)(qp + 160 + 16 * s2 + 4);
;       float x1[8] = {a0.x, a0.y, a0.z, a0.w, a1.x, a1.y, a1.z, a1.w}, x2[8] = {b0.x, b0.y, b0.z, b0.w, b1.x, b1.y, b1.z, b1.w}, o1[8], o2[8];
; #pragma unroll
;       for (int j = 0; j < 8; ++j) { double fr = pq * kInvFreq2Pi[16 * s2 + 8 * h + j]; fr -= floor(fr); const float ff = (float)fr;
;         const float sn = __builtin_amdgcn_sinf(ff), cs = __builtin_amdgcn_cosf(ff);
;         o1[j] = (x1[j] * cs - x2[j] * sn) * sc; o2[j] = (x2[j] * cs + x1[j] * sn) * sc; }
;       qf[8 + s2] = pack8(o1[0], o1[1], o1[2], o1[3], o1[4], o1[5], o1[6], o1[7]);
;       qf[10 + s2] = pack8(o2[0], o2[1], o2[2], o2[3], o2[4], o2[5], o2[6], o2[7]);
;     }
;   }
;   constexpr int KST = 64 * 400, VST = 128 * 144, STG = KST + VST;
;   f32x16 O[4];
; #pragma unroll
;   for (int i = 0; i < 4; ++i)
; #pragma unroll
;     for (int r = 0; r < 16; ++r) O[i][r] = 0.f;
;   float m_i = -1e30f, l_i = 0.f;
;   const int nt = 2 * b + 2;
;   u32x4 rk0[3], rv0[2], rk1[3], rv1[2];
;   const int vrow = tid >> 3, vcc = tid & 7;
;   const int ntl = nt - 1;
;     ...
;   AT_LOAD(rk0, rv0, 0);
;   AT_LOAD(rk1, rv1, 1);
	v_pk_mul_f32 v[42:43], v[42:43], s[54:55] op_sel_hi:[1,0]
	v_pk_mul_f32 v[44:45], v[44:45], s[54:55] op_sel_hi:[1,0]
	v_cvt_pk_bf16_f32 v107, v48, v49
	v_pk_fma_f32 v[28:29], v[140:141], v[22:23], v[28:29] neg_lo:[0,0,1] neg_hi:[0,0,1]
	v_pk_fma_f32 v[20:21], v[152:153], v[22:23], v[20:21]
	v_pk_fma_f32 v[22:23], v[142:143], v[26:27], v[32:33] neg_lo:[0,0,1] neg_hi:[0,0,1]
	v_pk_fma_f32 v[24:25], v[154:155], v[26:27], v[24:25]
	v_pk_mul_f32 v[48:49], v[148:149], v[30:31]
	v_pk_mul_f32 v[52:53], v[52:53], s[54:55] op_sel_hi:[1,0]
	v_cvt_pk_bf16_f32 v104, v42, v43
	v_cvt_pk_bf16_f32 v105, v44, v45
	v_pk_mul_f32 v[32:33], v[28:29], s[54:55] op_sel_hi:[1,0]
	v_pk_mul_f32 v[42:43], v[22:23], s[54:55] op_sel_hi:[1,0]
	v_pk_mul_f32 v[44:45], v[24:25], s[54:55] op_sel_hi:[1,0]
	global_load_dwordx4 v[22:25], v[18:19], off offset:704
	global_load_dwordx4 v[26:29], v[18:19], off offset:576
	v_pk_fma_f32 v[18:19], v[144:145], v[46:47], v[48:49] neg_lo:[0,0,1] neg_hi:[0,0,1]
	v_mul_f64 v[48:49], v[132:133], v[34:35]
	v_cvt_pk_bf16_f32 v109, v52, v53
	v_floor_f64_e32 v[48:49], v[48:49]
	v_mul_f64 v[52:53], v[134:135], v[34:35]
	v_fma_f64 v[48:49], v[132:133], v[34:35], -v[48:49]
	v_floor_f64_e32 v[52:53], v[52:53]
	v_pk_mul_f32 v[50:51], v[50:51], s[54:55] op_sel_hi:[1,0]
	v_cvt_f32_f64_e32 v0, v[48:49]
	v_fma_f64 v[52:53], v[134:135], v[34:35], -v[52:53]
	v_cvt_pk_bf16_f32 v108, v50, v51
	v_sin_f32_e32 v48, v0
	v_cos_f32_e32 v50, v0
	v_cvt_f32_f64_e32 v0, v[52:53]
	v_sin_f32_e32 v49, v0
	v_cos_f32_e32 v51, v0
	v_pk_mul_f32 v[30:31], v[144:145], v[30:31]
	v_pk_mul_f32 v[62:63], v[62:63], s[54:55] op_sel_hi:[1,0]
	v_pk_fma_f32 v[30:31], v[148:149], v[46:47], v[30:31]
	v_cvt_pk_bf16_f32 v114, v62, v63
	v_pk_mul_f32 v[62:63], v[30:31], s[54:55] op_sel_hi:[1,0]
	v_pk_mul_f32 v[30:31], v[150:151], v[48:49]
	v_pk_mul_f32 v[66:67], v[66:67], s[54:55] op_sel_hi:[1,0]
	v_pk_fma_f32 v[30:31], v[146:147], v[50:51], v[30:31] neg_lo:[0,0,1] neg_hi:[0,0,1]
	v_pk_mul_f32 v[20:21], v[20:21], s[54:55] op_sel_hi:[1,0]
	v_pk_mul_f32 v[18:19], v[18:19], s[54:55] op_sel_hi:[1,0]
	v_pk_mul_f32 v[30:31], v[30:31], s[54:55] op_sel_hi:[1,0]
	v_cvt_pk_bf16_f32 v129, v42, v43
	v_mul_f64 v[42:43], v[14:15], v[34:35]
	v_pk_mul_f32 v[68:69], v[68:69], s[54:55] op_sel_hi:[1,0]
	v_cvt_pk_bf16_f32 v116, v66, v67
	v_cvt_pk_bf16_f32 v128, v32, v33
	v_cvt_pk_bf16_f32 v130, v18, v19
	v_cvt_pk_bf16_f32 v131, v30, v31
	v_cvt_pk_bf16_f32 v132, v20, v21
	global_load_dwordx4 v[18:21], v41, s[2:3] offset:48
	global_load_dwordx4 v[30:33], v41, s[2:3] offset:32
	v_floor_f64_e32 v[66:67], v[42:43]
	v_lshl_add_u64 v[42:43], v[184:185], 0, s[62:63]
	s_mov_b64 s[2:3], 0xeae8000
	v_cvt_pk_bf16_f32 v117, v68, v69
	v_lshl_add_u64 v[68:69], v[42:43], 0, s[2:3]
	s_mov_b32 s3, 0x2aaaaaab
	v_mul_hi_i32 v0, v187, s3
	v_lshrrev_b32_e32 v41, 31, v0
	v_ashrrev_i32_e32 v0, 2, v0
	v_add_u32_e32 v41, v0, v41
	v_pk_mul_f32 v[86:87], v[86:87], s[54:55] op_sel_hi:[1,0]
	v_mul_lo_u32 v0, v41, 24
	v_cvt_pk_bf16_f32 v126, v86, v87
	v_sub_u32_e32 v86, v187, v0
	v_add_u32_e32 v0, 0x200, v187
	v_cvt_pk_bf16_f32 v133, v44, v45
	v_mul_hi_i32 v44, v0, s3
	v_lshrrev_b32_e32 v45, 31, v44
	v_ashrrev_i32_e32 v44, 2, v44
	v_add_u32_e32 v87, v44, v45
	v_pk_mul_f32 v[88:89], v[88:89], s[54:55] op_sel_hi:[1,0]
	v_mul_lo_u32 v44, v87, 24
	v_cvt_pk_bf16_f32 v127, v88, v89
	v_pk_mul_f32 v[46:47], v[146:147], v[48:49]
	v_sub_u32_e32 v88, v0, v44
	v_add_u32_e32 v0, 0x400, v187
	v_pk_fma_f32 v[46:47], v[150:151], v[50:51], v[46:47]
	v_mul_hi_i32 v50, v0, s3
	v_lshrrev_b32_e32 v51, 31, v50
	v_ashrrev_i32_e32 v50, 2, v50
	v_add_u32_e32 v89, v50, v51
	s_movk_i32 s2, 0xc0
	v_mul_lo_u32 v50, v89, 24
	v_pk_mul_f32 v[82:83], v[82:83], s[54:55] op_sel_hi:[1,0]
	v_mul_lo_u32 v190, v41, s2
	v_mul_lo_u32 v194, v87, s2
	v_sub_u32_e32 v90, v0, v50
	v_mul_lo_u32 v198, v89, s2
	v_pk_mul_f32 v[70:71], v[70:71], s[54:55] op_sel_hi:[1,0]
	v_pk_mul_f32 v[74:75], v[74:75], s[54:55] op_sel_hi:[1,0]
	v_pk_mul_f32 v[78:79], v[78:79], s[54:55] op_sel_hi:[1,0]
	v_cvt_pk_bf16_f32 v124, v82, v83
	v_ashrrev_i32_e32 v191, 31, v190
	v_lshlrev_b32_e32 v192, 3, v86
	v_ashrrev_i32_e32 v195, 31, v194
	v_lshlrev_b32_e32 v196, 3, v88
	v_ashrrev_i32_e32 v199, 31, v198
	v_lshlrev_b32_e32 v200, 3, v90
	v_ashrrev_i32_e32 v82, 3, v187
	v_lshlrev_b32_e32 v0, 4, v187
	v_pk_mul_f32 v[72:73], v[72:73], s[54:55] op_sel_hi:[1,0]
	v_pk_mul_f32 v[76:77], v[76:77], s[54:55] op_sel_hi:[1,0]
	v_pk_mul_f32 v[80:81], v[80:81], s[54:55] op_sel_hi:[1,0]
	v_cvt_pk_bf16_f32 v118, v70, v71
	v_cvt_pk_bf16_f32 v120, v74, v75
	v_cvt_pk_bf16_f32 v122, v78, v79
	v_lshlrev_b64 v[70:71], 1, v[190:191]
	v_ashrrev_i32_e32 v193, 31, v192
	v_lshlrev_b64 v[74:75], 1, v[194:195]
	v_ashrrev_i32_e32 v197, 31, v196
	v_lshlrev_b64 v[78:79], 1, v[198:199]
	v_ashrrev_i32_e32 v201, 31, v200
	v_and_b32_e32 v0, 0x70, v0
	v_ashrrev_i32_e32 v83, 31, v82
	v_pk_mul_f32 v[54:55], v[54:55], s[54:55] op_sel_hi:[1,0]
	v_pk_mul_f32 v[64:65], v[64:65], s[54:55] op_sel_hi:[1,0]
	v_cvt_pk_bf16_f32 v119, v72, v73
	v_cvt_pk_bf16_f32 v121, v76, v77
	v_cvt_pk_bf16_f32 v123, v80, v81
	v_lshl_add_u64 v[42:43], v[188:189], 0, v[70:71]
	v_lshlrev_b64 v[72:73], 1, v[192:193]
	v_lshl_add_u64 v[44:45], v[188:189], 0, v[74:75]
	v_lshlrev_b64 v[76:77], 1, v[196:197]
	v_lshl_add_u64 v[50:51], v[188:189], 0, v[78:79]
	v_lshlrev_b64 v[80:81], 1, v[200:201]
	v_lshl_add_u64 v[202:203], v[68:69], 0, v[0:1]
	v_lshlrev_b64 v[204:205], 15, v[82:83]
	s_mov_b64 s[2:3], 0x200000
	v_pk_mul_f32 v[56:57], v[56:57], s[54:55] op_sel_hi:[1,0]
	v_pk_mul_f32 v[58:59], v[58:59], s[54:55] op_sel_hi:[1,0]
	v_cvt_pk_bf16_f32 v110, v54, v55
	v_cvt_pk_bf16_f32 v115, v64, v65
	v_pk_mul_f32 v[64:65], v[46:47], s[54:55] op_sel_hi:[1,0]
	v_lshl_add_u64 v[42:43], v[42:43], 0, v[72:73]
	v_lshl_add_u64 v[46:47], v[44:45], 0, v[76:77]
	v_lshl_add_u64 v[50:51], v[50:51], 0, v[80:81]
	v_lshl_add_u64 v[54:55], v[202:203], 0, v[204:205]
	v_lshl_add_u64 v[210:211], v[204:205], 0, s[2:3]
	v_pk_mul_f32 v[60:61], v[60:61], s[54:55] op_sel_hi:[1,0]
	v_cvt_pk_bf16_f32 v111, v56, v57
	v_cvt_pk_bf16_f32 v112, v58, v59
	global_load_dwordx4 v[42:45], v[42:43], off
	s_nop 0
	global_load_dwordx4 v[46:49], v[46:47], off
	s_nop 0
	global_load_dwordx4 v[50:53], v[50:51], off
	s_nop 0
	global_load_dwordx4 v[54:57], v[54:55], off
	v_lshl_add_u64 v[58:59], v[202:203], 0, v[210:211]
	v_cvt_pk_bf16_f32 v113, v60, v61
	global_load_dwordx4 v[58:61], v[58:59], off
	v_pk_mul_f32 v[84:85], v[84:85], s[54:55] op_sel_hi:[1,0]
	v_fma_f64 v[14:15], v[14:15], v[34:35], -v[66:67]
	v_cvt_pk_bf16_f32 v125, v84, v85
	v_mul_f64 v[84:85], v[16:17], v[34:35]
	v_floor_f64_e32 v[84:85], v[84:85]
	v_fma_f64 v[16:17], v[16:17], v[34:35], -v[84:85]
	v_cvt_f32_f64_e32 v15, v[14:15]
	v_cvt_f32_f64_e32 v16, v[16:17]
	v_sin_f32_e32 v14, v15
	v_cos_f32_e32 v66, v15
	v_sin_f32_e32 v15, v16
	v_cos_f32_e32 v67, v16
	v_cvt_pk_bf16_f32 v134, v62, v63
	v_mul_f64 v[62:63], v[12:13], v[34:35]
	s_waitcnt vmcnt(0) lgkmcnt(0)
; #define AT_LOAD(RK, RV, T) { const size_t ko_ = (size_t)(T) * 64 * 192; const int vo_ = (T) * 64; \
;     _Pragma("unroll") for (int i = 0; i < 3; ++i) { const int id = tid + NT * i, row = id / 24, cc = id % 24; RK[i] = *(const u32x4*)(Kg + ko_ + row * 192 + cc * 8); } \
;     _Pragma("unroll") for (int i = 0; i < 2; ++i) RV[i] = *(const u32x4*)(Vg + (size_t)(vrow + 64 * i) * S_ + vo_ + vcc * 8); }
; #define AT_WRITE(RK, RV, ST) { char* dK = smem + (ST) * STG; \
;     _Pragma("unroll") for (int i = 0; i < 3; ++i) { const int id = tid + NT * i, row = id / 24, cc = id % 24; *(u32x4*)(dK + row * 400 + cc * 16) = RK[i]; } \
;     _Pragma("unroll") for (int i = 0; i < 2; ++i) *(u32x4*)(dK + KST + (vrow + 64 * i) * 144 + vcc * 16) = RV[i]; }
; DI void mla_attn_item(const Params& P, int hd, int b, char* smem) {
;     ...
;   constexpr int KST = 64 * 400, VST = 128 * 144, STG = KST + VST;
;   f32x16 O[4];
; #pragma unroll
;   for (int i = 0; i < 4; ++i)
; #pragma unroll
;     for (int r = 0; r < 16; ++r) O[i][r] = 0.f;
;   float m_i = -1e30f, l_i = 0.f;
;   const int nt = 2 * b + 2;
;   u32x4 rk0[3], rv0[2], rk1[3], rv1[2];
;   const int vrow = tid >> 3, vcc = tid & 7;
;   const int ntl = nt - 1;
;     ...
;   AT_LOAD(rk0, rv0, 0);
;   AT_LOAD(rk1, rv1, 1);
;   AT_WRITE(rk0, rv0, 0);
;   AT_LOAD(rk0, rv0, (2 < ntl ? 2 : ntl));
;   __syncthreads();
	v_pk_mul_f32 v[16:17], v[22:23], v[14:15]
	v_pk_mul_f32 v[14:15], v[26:27], v[14:15]
	v_pk_fma_f32 v[16:17], v[26:27], v[66:67], v[16:17] neg_lo:[0,0,1] neg_hi:[0,0,1]
	v_mul_f64 v[26:27], v[10:11], v[34:35]
	v_floor_f64_e32 v[26:27], v[26:27]
	v_floor_f64_e32 v[62:63], v[62:63]
	v_fma_f64 v[10:11], v[10:11], v[34:35], -v[26:27]
	v_fma_f64 v[12:13], v[12:13], v[34:35], -v[62:63]
	v_cvt_f32_f64_e32 v11, v[10:11]
	v_cvt_f32_f64_e32 v12, v[12:13]
	v_sin_f32_e32 v10, v11
	v_cos_f32_e32 v26, v11
	v_sin_f32_e32 v11, v12
	v_cos_f32_e32 v27, v12
	v_pk_fma_f32 v[12:13], v[22:23], v[66:67], v[14:15]
	s_mov_b64 s[2:3], 0xd2ee000
	v_pk_mul_f32 v[14:15], v[24:25], v[10:11]
	v_pk_mul_f32 v[10:11], v[28:29], v[10:11]
	v_pk_fma_f32 v[14:15], v[28:29], v[26:27], v[14:15] neg_lo:[0,0,1] neg_hi:[0,0,1]
	v_pk_fma_f32 v[10:11], v[24:25], v[26:27], v[10:11]
	v_mul_f64 v[26:27], v[32:33], v[34:35]
	v_floor_f64_e32 v[26:27], v[26:27]
	v_fma_f64 v[26:27], v[32:33], v[34:35], -v[26:27]
	v_cvt_f32_f64_e32 v25, v[26:27]
	v_lshl_add_u64 v[26:27], v[36:37], 0, s[2:3]
	v_lshl_add_u64 v[28:29], v[26:27], 0, v[70:71]
	v_lshl_add_u64 v[28:29], v[28:29], 0, v[72:73]
	global_load_dwordx4 v[136:139], v[28:29], off
	v_lshl_add_u64 v[28:29], v[26:27], 0, v[74:75]
	v_lshl_add_u64 v[26:27], v[26:27], 0, v[78:79]
	v_lshl_add_u64 v[28:29], v[28:29], 0, v[76:77]
	v_lshl_add_u64 v[26:27], v[26:27], 0, v[80:81]
	global_load_dwordx4 v[140:143], v[28:29], off
	global_load_dwordx4 v[144:147], v[26:27], off
	v_lshl_add_u64 v[26:27], v[68:69], 0, v[204:205]
	v_lshl_add_u64 v[26:27], v[26:27], 0, v[0:1]
	v_lshl_add_u64 v[28:29], v[68:69], 0, v[210:211]
	s_movk_i32 s3, 0x190
	v_lshl_add_u64 v[28:29], v[28:29], 0, v[0:1]
	global_load_dwordx4 v[148:151], v[26:27], off offset:128
	global_load_dwordx4 v[152:155], v[28:29], off offset:128
	v_mul_lo_u32 v26, v41, s3
	v_lshlrev_b32_e32 v27, 4, v86
	s_movk_i32 s2, 0x90
	v_add_u32_e32 v217, v26, v27
	v_mul_lo_u32 v26, v87, s3
	v_lshlrev_b32_e32 v27, 4, v88
	v_mul_lo_u32 v32, v82, s2
	s_min_u32 s2, s57, 2
	v_add_u32_e32 v218, v26, v27
	v_mul_lo_u32 v26, v89, s3
	v_lshlrev_b32_e32 v27, 4, v90
	s_mul_i32 s62, s2, 0x6000
	v_mul_f64 v[22:23], v[30:31], v[34:35]
	v_add_u32_e32 v219, v26, v27
	v_lshl_add_u64 v[26:27], v[188:189], 0, s[62:63]
	v_floor_f64_e32 v[22:23], v[22:23]
	v_add_u32_e32 v220, v0, v32
	v_lshl_add_u64 v[28:29], v[26:27], 0, v[70:71]
	v_fma_f64 v[22:23], v[30:31], v[34:35], -v[22:23]
	v_lshl_add_u64 v[28:29], v[28:29], 0, v[72:73]
	v_lshl_add_u64 v[30:31], v[26:27], 0, v[74:75]
	ds_write_b128 v217, v[42:45]
	ds_write_b128 v218, v[46:49]
	ds_write_b128 v219, v[50:53]
	ds_write_b128 v220, v[54:57] offset:25600
	ds_write_b128 v220, v[58:61] offset:34816
	s_lshl_b32 s62, s2, 7
	v_lshl_add_u64 v[30:31], v[30:31], 0, v[76:77]
	global_load_dwordx4 v[156:159], v[28:29], off
	global_load_dwordx4 v[160:163], v[30:31], off
	v_lshl_add_u64 v[26:27], v[26:27], 0, v[78:79]
	v_lshl_add_u64 v[28:29], v[68:69], 0, s[62:63]
	v_lshl_add_u64 v[26:27], v[26:27], 0, v[80:81]
	v_lshl_add_u64 v[28:29], v[28:29], 0, v[0:1]
	v_lshl_add_u64 v[30:31], v[28:29], 0, v[204:205]
	global_load_dwordx4 v[164:167], v[26:27], off
	global_load_dwordx4 v[168:171], v[30:31], off
	v_lshl_add_u64 v[26:27], v[28:29], 0, v[210:211]
	global_load_dwordx4 v[172:175], v[26:27], off
	v_cvt_f32_f64_e32 v23, v[22:23]
	v_sin_f32_e32 v22, v23
	v_cos_f32_e32 v24, v23
	v_sin_f32_e32 v23, v25
	v_cos_f32_e32 v25, v25
	v_mul_f64 v[28:29], v[20:21], v[34:35]
	v_floor_f64_e32 v[28:29], v[28:29]
	v_pk_mul_f32 v[26:27], v[6:7], v[22:23]
	v_fma_f64 v[20:21], v[20:21], v[34:35], -v[28:29]
	v_pk_fma_f32 v[26:27], v[2:3], v[24:25], v[26:27] neg_lo:[0,0,1] neg_hi:[0,0,1]
	v_pk_mul_f32 v[2:3], v[2:3], v[22:23]
	v_mul_f64 v[22:23], v[18:19], v[34:35]
	v_floor_f64_e32 v[22:23], v[22:23]
	v_fma_f64 v[18:19], v[18:19], v[34:35], -v[22:23]
	v_cvt_f32_f64_e32 v19, v[18:19]
	v_cvt_f32_f64_e32 v20, v[20:21]
	v_pk_mul_f32 v[16:17], v[16:17], s[54:55] op_sel_hi:[1,0]
	v_sin_f32_e32 v18, v19
	v_cos_f32_e32 v22, v19
	v_sin_f32_e32 v19, v20
	v_pk_fma_f32 v[2:3], v[6:7], v[24:25], v[2:3]
	v_cos_f32_e32 v23, v20
	v_pk_mul_f32 v[2:3], v[2:3], s[54:55] op_sel_hi:[1,0]
	v_cvt_pk_bf16_f32 v176, v16, v17
	v_or_b32_e32 v16, 0x11000, v0
	v_lshlrev_b32_e32 v0, 5, v221
	v_cvt_pk_bf16_f32 v182, v2, v3
	v_or_b32_e32 v2, v0, v38
	v_mul_lo_u32 v17, v2, s3
	v_mul_u32_u24_e32 v2, 0x90, v38
	v_pk_mul_f32 v[6:7], v[8:9], v[18:19]
	v_lshl_or_b32 v223, v40, 3, v2
	v_or_b32_e32 v2, v39, v38
	v_pk_fma_f32 v[6:7], v[4:5], v[22:23], v[6:7] neg_lo:[0,0,1] neg_hi:[0,0,1]
	v_pk_mul_f32 v[4:5], v[4:5], v[18:19]
	v_sub_u32_e32 v2, v2, v216
	v_pk_mul_f32 v[14:15], v[14:15], s[54:55] op_sel_hi:[1,0]
	v_pk_fma_f32 v[4:5], v[8:9], v[22:23], v[4:5]
	v_add_u32_e32 v224, 0x5f, v0
	v_sub_u32_e32 v0, v2, v0
	s_lshl_b32 s2, s8, 7
	v_pk_mul_f32 v[12:13], v[12:13], s[54:55] op_sel_hi:[1,0]
	v_pk_mul_f32 v[10:11], v[10:11], s[54:55] op_sel_hi:[1,0]
	v_pk_mul_f32 v[26:27], v[26:27], s[54:55] op_sel_hi:[1,0]
	v_pk_mul_f32 v[6:7], v[6:7], s[54:55] op_sel_hi:[1,0]
	v_pk_mul_f32 v[4:5], v[4:5], s[54:55] op_sel_hi:[1,0]
	v_cvt_pk_bf16_f32 v177, v14, v15
	v_lshlrev_b32_e32 v18, 4, v40
	v_add_u32_e32 v19, 0x11000, v223
	v_subrev_u32_e32 v0, s2, v0
	v_mov_b32_e32 v14, v1
	v_mov_b32_e32 v15, v1
	v_cvt_pk_bf16_f32 v135, v64, v65
	v_cvt_pk_bf16_f32 v178, v26, v27
	v_cvt_pk_bf16_f32 v179, v6, v7
	v_cvt_pk_bf16_f32 v180, v12, v13
	v_cvt_pk_bf16_f32 v181, v10, v11
	v_cvt_pk_bf16_f32 v183, v4, v5
	v_add_u32_e32 v225, 0x3f40, v0
	v_mov_b32_e32 v0, v1
	v_mov_b32_e32 v2, v1
	v_mov_b32_e32 v3, v1
	v_mov_b32_e32 v4, v1
	v_mov_b32_e32 v5, v1
	v_mov_b32_e32 v6, v1
	v_mov_b32_e32 v7, v1
	v_mov_b32_e32 v8, v1
	v_mov_b32_e32 v9, v1
	v_mov_b32_e32 v10, v1
	v_mov_b32_e32 v11, v1
	v_mov_b32_e32 v12, v1
	v_mov_b32_e32 v13, v1
	v_add_u32_e32 v226, v16, v32
	v_add_u32_e32 v227, v19, v222
	v_add_u32_e32 v228, v17, v18
	v_mov_b64_e32 v[30:31], v[14:15]
	v_mov_b64_e32 v[46:47], v[14:15]
	v_mov_b64_e32 v[62:63], v[14:15]
	v_mov_b64_e32 v[78:79], v[14:15]
	v_cvt_pk_bf16_f32 v103, v94, v95
	v_mov_b64_e32 v[28:29], v[12:13]
	v_mov_b64_e32 v[26:27], v[10:11]
	v_mov_b64_e32 v[24:25], v[8:9]
	v_mov_b64_e32 v[22:23], v[6:7]
	v_mov_b64_e32 v[20:21], v[4:5]
	v_mov_b64_e32 v[18:19], v[2:3]
	v_mov_b64_e32 v[16:17], v[0:1]
	v_mov_b64_e32 v[44:45], v[12:13]
	v_mov_b64_e32 v[42:43], v[10:11]
	v_mov_b64_e32 v[40:41], v[8:9]
	v_mov_b64_e32 v[38:39], v[6:7]
	v_mov_b64_e32 v[36:37], v[4:5]
	v_mov_b64_e32 v[34:35], v[2:3]
	v_mov_b64_e32 v[32:33], v[0:1]
	v_mov_b64_e32 v[60:61], v[12:13]
	v_mov_b64_e32 v[58:59], v[10:11]
	v_mov_b64_e32 v[56:57], v[8:9]
	v_mov_b64_e32 v[54:55], v[6:7]
	v_mov_b64_e32 v[52:53], v[4:5]
	v_mov_b64_e32 v[50:51], v[2:3]
	v_mov_b64_e32 v[48:49], v[0:1]
	v_mov_b64_e32 v[76:77], v[12:13]
	v_mov_b64_e32 v[74:75], v[10:11]
	v_mov_b64_e32 v[72:73], v[8:9]
	v_mov_b64_e32 v[70:71], v[6:7]
	v_mov_b64_e32 v[68:69], v[4:5]
	v_mov_b64_e32 v[66:67], v[2:3]
	v_mov_b64_e32 v[64:65], v[0:1]
	s_waitcnt lgkmcnt(0)
	s_barrier
	s_branch .LBB0_644

; DI unsigned pack2(float lo, float hi) { f32x2 v = {lo, hi}; bf2_t b = __builtin_convertvector(v, bf2_t); return __builtin_bit_cast(unsigned, b); }
; DI void mla_attn_item(const Params& P, int hd, int b, char* smem) {
;     ...
;   float* cO = (float*)smem; float* cm = cO + 4 * 4096; float* cl = cm + 256;
;   if (hk == 1) {
; #pragma unroll
;     for (int i = 0; i < 4; ++i)
; #pragma unroll
;       for (int r = 0; r < 16; ++r) cO[wq * 4096 + (i * 16 + r) * 64 + lane] = O[i][r];
;     cm[wq * 64 + lane] = m_i; cl[wq * 64 + lane] = l_i;
;   }
;   __syncthreads();
;   if (hk == 0) {
;     const float m1 = cm[wq * 64 + lane], l1 = cl[wq * 64 + lane];
;     const float m = fmaxf(m_i, m1), a0 = exp2f(m_i - m), a1 = exp2f(m1 - m);
;     float lt = l_i * a0 + l1 * a1; lt += __shfl_xor(lt, 32);
;     const float inv = 1.f / lt;
;     bf16_t* op = mixin + (size_t)q * 2048 + 1024 + hd * 128;
; #pragma unroll
;     for (int i = 0; i < 4; ++i)
; #pragma unroll
;       for (int rg = 0; rg < 4; ++rg) { float v[4];
; #pragma unroll
;         for (int e = 0; e < 4; ++e) v[e] = (O[i][4 * rg + e] * a0 + cO[wq * 4096 + (i * 16 + 4 * rg + e) * 64 + lane] * a1) * inv;
;         u32x2 pk = {pack2(v[0], v[1]), pack2(v[2], v[3])}; *(u32x2*)(op + 32 * i + 8 * rg + 4 * h) = pk; }
;   }
;   __syncthreads();
.LBB0_657:
	s_or_b64 exec, exec, s[2:3]
	v_cmp_gt_u32_e32 vcc, s61, v187
	s_waitcnt lgkmcnt(0)
	s_barrier
	s_and_saveexec_b64 s[2:3], vcc
	v_readlane_b32 s28, v254, 4
	v_readlane_b32 s60, v255, 56
	v_readlane_b32 s29, v254, 5
	v_readlane_b32 s61, v255, 57
	s_mov_b64 s[30:31], 0x122e8000
	v_readlane_b32 s56, v255, 58
	s_cbranch_execz .LBB0_659
	v_add_u32_e32 v2, 0x10000, v0
	ds_read_b32 v3, v2
	v_add_u32_e32 v0, 0x10400, v0
	ds_read_b32 v213, v0
	v_max_f32_e32 v2, v229, v229
	v_lshl_or_b32 v5, v214, 14, v5
	s_waitcnt lgkmcnt(0)
	v_max_f32_e32 v0, v3, v3
	v_max_f32_e32 v0, v2, v0
	v_sub_f32_e32 v2, v229, v0
	v_cmp_gt_f32_e32 vcc, s91, v2
	v_sub_f32_e32 v0, v3, v0
	ds_read2st64_b32 v[10:11], v5 offset1:1
	ds_read2st64_b32 v[12:13], v5 offset0:2 offset1:3
	v_cndmask_b32_e32 v4, 0, v242, vcc
	v_add_f32_e32 v2, v2, v4
	v_cndmask_b32_e32 v4, 0, v243, vcc
	v_cmp_gt_f32_e32 vcc, s91, v0
	v_exp_f32_e32 v2, v2
	s_lshl_b32 s62, s97, 8
	v_cndmask_b32_e32 v3, 0, v242, vcc
	v_add_f32_e32 v0, v0, v3
	v_exp_f32_e32 v0, v0
	v_cndmask_b32_e32 v3, 0, v243, vcc
	v_ldexp_f32 v2, v2, v4
	v_xor_b32_e32 v4, 32, v239
	v_ldexp_f32 v3, v0, v3
	v_pk_mul_f32 v[6:7], v[212:213], v[2:3]
	s_nop 0
	v_add_f32_e32 v0, v6, v7
	v_and_b32_e32 v6, 64, v239
	v_add_u32_e32 v6, 64, v6
	v_cmp_lt_i32_e32 vcc, v4, v6
	s_nop 1
	v_cndmask_b32_e32 v4, v239, v4, vcc
	v_lshlrev_b32_e32 v4, 2, v4
	ds_bpermute_b32 v4, v4, v0
	s_waitcnt lgkmcnt(0)
	v_add_f32_e32 v0, v0, v4
	v_div_scale_f32 v4, s[4:5], v0, v0, 1.0
	v_rcp_f32_e32 v6, v4
	s_mov_b64 s[4:5], 0x62e8800
	v_fma_f32 v7, -v4, v6, 1.0
	v_fmac_f32_e32 v6, v7, v6
	v_div_scale_f32 v7, vcc, 1.0, v0, 1.0
	v_mul_f32_e32 v8, v7, v6
	v_fma_f32 v9, -v4, v8, v7
	v_fmac_f32_e32 v8, v9, v6
	v_fma_f32 v4, -v4, v8, v7
	v_div_fmas_f32 v4, v4, v6, v8
	v_div_fixup_f32 v4, v4, v0, 1.0
	v_lshlrev_b32_e32 v0, 12, v186
	v_lshl_add_u64 v[6:7], v[184:185], 0, v[0:1]
	v_lshl_add_u64 v[6:7], v[6:7], 0, s[62:63]
	v_lshlrev_b32_e32 v0, 1, v216
	v_lshl_add_u64 v[8:9], v[6:7], 0, v[0:1]
	v_mov_b32_e32 v0, v3
	v_pk_mul_f32 v[10:11], v[0:1], v[10:11] op_sel_hi:[0,1]
	v_pk_mul_f32 v[12:13], v[0:1], v[12:13] op_sel_hi:[0,1]
	v_pk_fma_f32 v[10:11], v[64:65], v[2:3], v[10:11] op_sel_hi:[1,0,1]
	v_pk_fma_f32 v[12:13], v[66:67], v[2:3], v[12:13] op_sel_hi:[1,0,1]
	v_lshl_add_u64 v[6:7], v[8:9], 0, s[4:5]
	v_pk_mul_f32 v[10:11], v[4:5], v[10:11] op_sel_hi:[0,1]
	v_pk_mul_f32 v[12:13], v[4:5], v[12:13] op_sel_hi:[0,1]
	v_add_co_u32_e32 v8, vcc, s92, v8
	v_cvt_pk_bf16_f32 v10, v10, v11
	v_cvt_pk_bf16_f32 v11, v12, v13
	v_addc_co_u32_e32 v9, vcc, 0, v9, vcc
	global_store_dwordx2 v[8:9], v[10:11], off offset:2048
	ds_read2st64_b32 v[8:9], v5 offset0:4 offset1:5
	ds_read2st64_b32 v[10:11], v5 offset0:6 offset1:7
	s_waitcnt lgkmcnt(0)
	v_pk_mul_f32 v[8:9], v[0:1], v[8:9] op_sel_hi:[0,1]
	v_pk_mul_f32 v[10:11], v[0:1], v[10:11] op_sel_hi:[0,1]
	v_pk_fma_f32 v[8:9], v[68:69], v[2:3], v[8:9] op_sel_hi:[1,0,1]
	v_pk_fma_f32 v[10:11], v[70:71], v[2:3], v[10:11] op_sel_hi:[1,0,1]
	v_pk_mul_f32 v[8:9], v[4:5], v[8:9] op_sel_hi:[0,1]
	v_pk_mul_f32 v[10:11], v[4:5], v[10:11] op_sel_hi:[0,1]
	v_cvt_pk_bf16_f32 v8, v8, v9
	v_cvt_pk_bf16_f32 v9, v10, v11
	global_store_dwordx2 v[6:7], v[8:9], off offset:16
	ds_read2st64_b32 v[8:9], v5 offset0:8 offset1:9
	ds_read2st64_b32 v[10:11], v5 offset0:10 offset1:11
	s_waitcnt lgkmcnt(0)
	v_pk_mul_f32 v[8:9], v[0:1], v[8:9] op_sel_hi:[0,1]
	v_pk_mul_f32 v[10:11], v[0:1], v[10:11] op_sel_hi:[0,1]
	v_pk_fma_f32 v[8:9], v[72:73], v[2:3], v[8:9] op_sel_hi:[1,0,1]
	v_pk_fma_f32 v[10:11], v[74:75], v[2:3], v[10:11] op_sel_hi:[1,0,1]
	v_pk_mul_f32 v[8:9], v[4:5], v[8:9] op_sel_hi:[0,1]
	v_pk_mul_f32 v[10:11], v[4:5], v[10:11] op_sel_hi:[0,1]
	v_cvt_pk_bf16_f32 v8, v8, v9
	v_cvt_pk_bf16_f32 v9, v10, v11
	global_store_dwordx2 v[6:7], v[8:9], off offset:32
	ds_read2st64_b32 v[8:9], v5 offset0:12 offset1:13
	ds_read2st64_b32 v[10:11], v5 offset0:14 offset1:15
	s_waitcnt lgkmcnt(0)
	v_pk_mul_f32 v[8:9], v[0:1], v[8:9] op_sel_hi:[0,1]
	v_pk_mul_f32 v[10:11], v[0:1], v[10:11] op_sel_hi:[0,1]
	v_pk_fma_f32 v[8:9], v[76:77], v[2:3], v[8:9] op_sel_hi:[1,0,1]
	v_pk_fma_f32 v[10:11], v[78:79], v[2:3], v[10:11] op_sel_hi:[1,0,1]
	v_pk_mul_f32 v[8:9], v[4:5], v[8:9] op_sel_hi:[0,1]
	v_pk_mul_f32 v[10:11], v[4:5], v[10:11] op_sel_hi:[0,1]
	v_cvt_pk_bf16_f32 v8, v8, v9
	v_cvt_pk_bf16_f32 v9, v10, v11
	global_store_dwordx2 v[6:7], v[8:9], off offset:48
	ds_read2st64_b32 v[8:9], v5 offset0:16 offset1:17
	ds_read2st64_b32 v[10:11], v5 offset0:18 offset1:19
	s_waitcnt lgkmcnt(0)
	v_pk_mul_f32 v[8:9], v[0:1], v[8:9] op_sel_hi:[0,1]
	v_pk_mul_f32 v[10:11], v[0:1], v[10:11] op_sel_hi:[0,1]
	v_pk_fma_f32 v[8:9], v[48:49], v[2:3], v[8:9] op_sel_hi:[1,0,1]
	v_pk_fma_f32 v[10:11], v[50:51], v[2:3], v[10:11] op_sel_hi:[1,0,1]
	v_pk_mul_f32 v[8:9], v[4:5], v[8:9] op_sel_hi:[0,1]
	v_pk_mul_f32 v[10:11], v[4:5], v[10:11] op_sel_hi:[0,1]
	v_cvt_pk_bf16_f32 v8, v8, v9
	v_cvt_pk_bf16_f32 v9, v10, v11
	global_store_dwordx2 v[6:7], v[8:9], off offset:64
	ds_read2st64_b32 v[8:9], v5 offset0:20 offset1:21
	ds_read2st64_b32 v[10:11], v5 offset0:22 offset1:23
	s_waitcnt lgkmcnt(0)
	v_pk_mul_f32 v[8:9], v[0:1], v[8:9] op_sel_hi:[0,1]
	v_pk_mul_f32 v[10:11], v[0:1], v[10:11] op_sel_hi:[0,1]
	v_pk_fma_f32 v[8:9], v[52:53], v[2:3], v[8:9] op_sel_hi:[1,0,1]
	v_pk_fma_f32 v[10:11], v[54:55], v[2:3], v[10:11] op_sel_hi:[1,0,1]
	v_pk_mul_f32 v[8:9], v[4:5], v[8:9] op_sel_hi:[0,1]
	v_pk_mul_f32 v[10:11], v[4:5], v[10:11] op_sel_hi:[0,1]
	v_cvt_pk_bf16_f32 v8, v8, v9
	v_cvt_pk_bf16_f32 v9, v10, v11
	global_store_dwordx2 v[6:7], v[8:9], off offset:80
	ds_read2st64_b32 v[8:9], v5 offset0:24 offset1:25
	ds_read2st64_b32 v[10:11], v5 offset0:26 offset1:27
	s_waitcnt lgkmcnt(0)
; DI unsigned pack2(float lo, float hi) { f32x2 v = {lo, hi}; bf2_t b = __builtin_convertvector(v, bf2_t); return __builtin_bit_cast(unsigned, b); }
; DI void mla_attn_item(const Params& P, int hd, int b, char* smem) {
;     ...
;     bf16_t* op = mixin + (size_t)q * 2048 + 1024 + hd * 128;
; #pragma unroll
;     for (int i = 0; i < 4; ++i)
; #pragma unroll
;       for (int rg = 0; rg < 4; ++rg) { float v[4];
; #pragma unroll
;         for (int e = 0; e < 4; ++e) v[e] = (O[i][4 * rg + e] * a0 + cO[wq * 4096 + (i * 16 + 4 * rg + e) * 64 + lane] * a1) * inv;
;         u32x2 pk = {pack2(v[0], v[1]), pack2(v[2], v[3])}; *(u32x2*)(op + 32 * i + 8 * rg + 4 * h) = pk; }
;   }
	v_pk_mul_f32 v[8:9], v[0:1], v[8:9] op_sel_hi:[0,1]
	v_pk_mul_f32 v[10:11], v[0:1], v[10:11] op_sel_hi:[0,1]
	v_pk_fma_f32 v[8:9], v[56:57], v[2:3], v[8:9] op_sel_hi:[1,0,1]
	v_pk_fma_f32 v[10:11], v[58:59], v[2:3], v[10:11] op_sel_hi:[1,0,1]
	v_pk_mul_f32 v[8:9], v[4:5], v[8:9] op_sel_hi:[0,1]
	v_pk_mul_f32 v[10:11], v[4:5], v[10:11] op_sel_hi:[0,1]
	v_cvt_pk_bf16_f32 v8, v8, v9
	v_cvt_pk_bf16_f32 v9, v10, v11
	global_store_dwordx2 v[6:7], v[8:9], off offset:96
	ds_read2st64_b32 v[8:9], v5 offset0:28 offset1:29
	ds_read2st64_b32 v[10:11], v5 offset0:30 offset1:31
	s_waitcnt lgkmcnt(0)
	v_pk_mul_f32 v[8:9], v[0:1], v[8:9] op_sel_hi:[0,1]
	v_pk_mul_f32 v[10:11], v[0:1], v[10:11] op_sel_hi:[0,1]
	v_pk_fma_f32 v[8:9], v[60:61], v[2:3], v[8:9] op_sel_hi:[1,0,1]
	v_pk_fma_f32 v[10:11], v[62:63], v[2:3], v[10:11] op_sel_hi:[1,0,1]
	v_pk_mul_f32 v[8:9], v[4:5], v[8:9] op_sel_hi:[0,1]
	v_pk_mul_f32 v[10:11], v[4:5], v[10:11] op_sel_hi:[0,1]
	v_cvt_pk_bf16_f32 v8, v8, v9
	v_cvt_pk_bf16_f32 v9, v10, v11
	global_store_dwordx2 v[6:7], v[8:9], off offset:112
	ds_read2st64_b32 v[8:9], v5 offset0:32 offset1:33
	ds_read2st64_b32 v[10:11], v5 offset0:34 offset1:35
	s_waitcnt lgkmcnt(0)
	v_pk_mul_f32 v[8:9], v[0:1], v[8:9] op_sel_hi:[0,1]
	v_pk_mul_f32 v[10:11], v[0:1], v[10:11] op_sel_hi:[0,1]
	v_pk_fma_f32 v[8:9], v[32:33], v[2:3], v[8:9] op_sel_hi:[1,0,1]
	v_pk_fma_f32 v[10:11], v[34:35], v[2:3], v[10:11] op_sel_hi:[1,0,1]
	v_pk_mul_f32 v[8:9], v[4:5], v[8:9] op_sel_hi:[0,1]
	v_pk_mul_f32 v[10:11], v[4:5], v[10:11] op_sel_hi:[0,1]
	v_cvt_pk_bf16_f32 v8, v8, v9
	v_cvt_pk_bf16_f32 v9, v10, v11
	global_store_dwordx2 v[6:7], v[8:9], off offset:128
	ds_read2st64_b32 v[8:9], v5 offset0:36 offset1:37
	ds_read2st64_b32 v[10:11], v5 offset0:38 offset1:39
	s_waitcnt lgkmcnt(0)
	v_pk_mul_f32 v[8:9], v[0:1], v[8:9] op_sel_hi:[0,1]
	v_pk_mul_f32 v[10:11], v[0:1], v[10:11] op_sel_hi:[0,1]
	v_pk_fma_f32 v[8:9], v[36:37], v[2:3], v[8:9] op_sel_hi:[1,0,1]
	v_pk_fma_f32 v[10:11], v[38:39], v[2:3], v[10:11] op_sel_hi:[1,0,1]
	v_pk_mul_f32 v[8:9], v[4:5], v[8:9] op_sel_hi:[0,1]
	v_pk_mul_f32 v[10:11], v[4:5], v[10:11] op_sel_hi:[0,1]
	v_cvt_pk_bf16_f32 v8, v8, v9
	v_cvt_pk_bf16_f32 v9, v10, v11
	global_store_dwordx2 v[6:7], v[8:9], off offset:144
	ds_read2st64_b32 v[8:9], v5 offset0:40 offset1:41
	ds_read2st64_b32 v[10:11], v5 offset0:42 offset1:43
	s_waitcnt lgkmcnt(0)
	v_pk_mul_f32 v[8:9], v[0:1], v[8:9] op_sel_hi:[0,1]
	v_pk_mul_f32 v[10:11], v[0:1], v[10:11] op_sel_hi:[0,1]
	v_pk_fma_f32 v[8:9], v[40:41], v[2:3], v[8:9] op_sel_hi:[1,0,1]
	v_pk_fma_f32 v[10:11], v[42:43], v[2:3], v[10:11] op_sel_hi:[1,0,1]
	v_pk_mul_f32 v[8:9], v[4:5], v[8:9] op_sel_hi:[0,1]
	v_pk_mul_f32 v[10:11], v[4:5], v[10:11] op_sel_hi:[0,1]
	v_cvt_pk_bf16_f32 v8, v8, v9
	v_cvt_pk_bf16_f32 v9, v10, v11
	global_store_dwordx2 v[6:7], v[8:9], off offset:160
	ds_read2st64_b32 v[8:9], v5 offset0:44 offset1:45
	ds_read2st64_b32 v[10:11], v5 offset0:46 offset1:47
	s_waitcnt lgkmcnt(0)
	v_pk_mul_f32 v[8:9], v[0:1], v[8:9] op_sel_hi:[0,1]
	v_pk_mul_f32 v[10:11], v[0:1], v[10:11] op_sel_hi:[0,1]
	v_pk_fma_f32 v[8:9], v[44:45], v[2:3], v[8:9] op_sel_hi:[1,0,1]
	v_pk_fma_f32 v[10:11], v[46:47], v[2:3], v[10:11] op_sel_hi:[1,0,1]
	v_pk_mul_f32 v[8:9], v[4:5], v[8:9] op_sel_hi:[0,1]
	v_pk_mul_f32 v[10:11], v[4:5], v[10:11] op_sel_hi:[0,1]
	v_cvt_pk_bf16_f32 v8, v8, v9
	v_cvt_pk_bf16_f32 v9, v10, v11
	global_store_dwordx2 v[6:7], v[8:9], off offset:176
	ds_read2st64_b32 v[8:9], v5 offset0:48 offset1:49
	ds_read2st64_b32 v[10:11], v5 offset0:50 offset1:51
	s_waitcnt lgkmcnt(0)
	v_pk_mul_f32 v[8:9], v[0:1], v[8:9] op_sel_hi:[0,1]
	v_pk_mul_f32 v[10:11], v[0:1], v[10:11] op_sel_hi:[0,1]
	v_pk_fma_f32 v[8:9], v[16:17], v[2:3], v[8:9] op_sel_hi:[1,0,1]
	v_pk_fma_f32 v[10:11], v[18:19], v[2:3], v[10:11] op_sel_hi:[1,0,1]
	v_pk_mul_f32 v[8:9], v[4:5], v[8:9] op_sel_hi:[0,1]
	v_pk_mul_f32 v[10:11], v[4:5], v[10:11] op_sel_hi:[0,1]
	v_cvt_pk_bf16_f32 v8, v8, v9
	v_cvt_pk_bf16_f32 v9, v10, v11
	global_store_dwordx2 v[6:7], v[8:9], off offset:192
	ds_read2st64_b32 v[8:9], v5 offset0:52 offset1:53
	ds_read2st64_b32 v[10:11], v5 offset0:54 offset1:55
	s_waitcnt lgkmcnt(0)
	v_pk_mul_f32 v[8:9], v[0:1], v[8:9] op_sel_hi:[0,1]
	v_pk_mul_f32 v[10:11], v[0:1], v[10:11] op_sel_hi:[0,1]
	v_pk_fma_f32 v[8:9], v[20:21], v[2:3], v[8:9] op_sel_hi:[1,0,1]
	v_pk_fma_f32 v[10:11], v[22:23], v[2:3], v[10:11] op_sel_hi:[1,0,1]
	v_pk_mul_f32 v[8:9], v[4:5], v[8:9] op_sel_hi:[0,1]
	v_pk_mul_f32 v[10:11], v[4:5], v[10:11] op_sel_hi:[0,1]
	v_cvt_pk_bf16_f32 v8, v8, v9
	v_cvt_pk_bf16_f32 v9, v10, v11
	global_store_dwordx2 v[6:7], v[8:9], off offset:208
	ds_read2st64_b32 v[8:9], v5 offset0:56 offset1:57
	ds_read2st64_b32 v[10:11], v5 offset0:58 offset1:59
	s_waitcnt lgkmcnt(0)
	v_pk_mul_f32 v[8:9], v[0:1], v[8:9] op_sel_hi:[0,1]
	v_pk_mul_f32 v[10:11], v[0:1], v[10:11] op_sel_hi:[0,1]
	v_pk_fma_f32 v[8:9], v[24:25], v[2:3], v[8:9] op_sel_hi:[1,0,1]
	v_pk_fma_f32 v[10:11], v[26:27], v[2:3], v[10:11] op_sel_hi:[1,0,1]
	v_pk_mul_f32 v[8:9], v[4:5], v[8:9] op_sel_hi:[0,1]
	v_pk_mul_f32 v[10:11], v[4:5], v[10:11] op_sel_hi:[0,1]
	v_cvt_pk_bf16_f32 v8, v8, v9
	v_cvt_pk_bf16_f32 v9, v10, v11
	global_store_dwordx2 v[6:7], v[8:9], off offset:224
	ds_read2st64_b32 v[8:9], v5 offset0:60 offset1:61
	ds_read2st64_b32 v[10:11], v5 offset0:62 offset1:63
	s_waitcnt lgkmcnt(0)
	v_pk_mul_f32 v[8:9], v[0:1], v[8:9] op_sel_hi:[0,1]
	v_pk_mul_f32 v[10:11], v[0:1], v[10:11] op_sel_hi:[0,1]
	v_pk_fma_f32 v[8:9], v[28:29], v[2:3], v[8:9] op_sel_hi:[1,0,1]
	v_pk_fma_f32 v[2:3], v[30:31], v[2:3], v[10:11] op_sel_hi:[1,0,1]
	v_pk_mul_f32 v[8:9], v[4:5], v[8:9] op_sel_hi:[0,1]
	v_pk_mul_f32 v[2:3], v[4:5], v[2:3] op_sel_hi:[0,1]
	v_cvt_pk_bf16_f32 v4, v8, v9
	v_cvt_pk_bf16_f32 v5, v2, v3
	global_store_dwordx2 v[6:7], v[4:5], off offset:240

; DI void gdn_scan_item(const Params& P, int l, int hh, int half, char* smem) {
;     ...
;   } else {
;     const int dvc = 64 * half + 16 * w + l15;
;     const int uoff = dvc * 64 + 4 * q4;
;     float* ssqp = (float*)(P.ws + OFF_SSQP) + (size_t)(half * 4 + w) * S_ * 8;
;     f32x4 St[8];
; #pragma unroll
;     for (int t = 0; t < 8; ++t) St[t] = (f32x4){0.f, 0.f, 0.f, 0.f};
;     u32x2 uc[4], un[4]; float gcur, gn = 0.f;
; #pragma unroll
;     for (int it = 0; it < 4; ++it) { uc[it] = *(const u32x2*)(Ut + uoff + 16 * it); un[it] = uc[it]; }
;     gcur = gt[0];
;     ...
;     __syncthreads();
.LBB0_661:
	s_andn2_b64 vcc, exec, s[2:3]
	s_cbranch_vccnz .LBB0_587
	v_mov_b32_e32 v79, v206
	global_load_dwordx2 v[114:115], v1, s[40:41] offset:1224
	s_ashr_i32 s4, s96, 1
	v_and_b32_e32 v63, 63, v79
	v_ashrrev_i32_e32 v0, 6, v79
	v_bfe_u32 v135, v79, 4, 2
	s_ashr_i32 s5, s4, 31
	s_and_b32 s16, s96, 1
	v_and_b32_e32 v134, 15, v79
	s_lshl_b64 s[2:3], s[4:5], 21
	v_cmp_gt_i32_e32 vcc, 4, v0
	v_lshlrev_b32_e32 v106, 2, v135
	s_waitcnt vmcnt(0)
	v_lshlrev_b32_e32 v158, 3, v63
	s_and_saveexec_b64 s[8:9], vcc
	s_xor_b64 s[8:9], exec, s[8:9]
	s_cbranch_execz .LBB0_672
	s_lshl_b32 s17, s16, 6
	v_lshl_add_u32 v6, v0, 4, s17
	v_or_b32_e32 v6, v6, v134
	v_lshl_or_b32 v6, v6, 6, v106
	s_lshl_b64 s[12:13], s[2:3], 1
	v_ashrrev_i32_e32 v7, 31, v6
	v_lshl_add_u64 v[4:5], v[114:115], 0, s[12:13]
	v_lshlrev_b64 v[6:7], 1, v[6:7]
	v_lshl_add_u64 v[4:5], v[4:5], 0, v[6:7]
	s_mov_b64 s[12:13], 0x282e8000
	v_lshl_add_u64 v[8:9], v[4:5], 0, s[12:13]
	s_mov_b32 s12, 0x282e8000
	s_lshl_b64 s[10:11], s[4:5], 10
	v_add_co_u32_e32 v4, vcc, s12, v4
	v_lshl_add_u64 v[2:3], v[114:115], 0, s[10:11]
	s_nop 0
	v_addc_co_u32_e32 v5, vcc, 0, v5, vcc
	global_load_dwordx2 v[88:89], v[4:5], off
	global_load_dwordx2 v[86:87], v[8:9], off offset:32
	global_load_dwordx2 v[84:85], v[8:9], off offset:64
	global_load_dwordx2 v[82:83], v[8:9], off offset:96
	v_add_co_u32_e32 v2, vcc, s89, v2
	s_mov_b64 s[12:13], 0x263ea000
	s_nop 0
	v_addc_co_u32_e32 v3, vcc, 0, v3, vcc
	global_load_dword v78, v[2:3], off
	v_lshl_add_u32 v2, s16, 2, v0
	v_ashrrev_i32_e32 v3, 31, v2
	v_lshlrev_b64 v[2:3], 19, v[2:3]
	v_lshl_add_u64 v[2:3], v[114:115], 0, v[2:3]
	v_lshl_add_u64 v[64:65], v[2:3], 0, s[12:13]
	v_mov_b32_e32 v2, 0x1e800
	v_lshl_add_u32 v0, v0, 11, v2
	v_and_b32_e32 v2, 7, v79
	s_mov_b32 s14, 0x3fffffc0
	v_lshlrev_b32_e32 v62, 4, v2
	v_and_or_b32 v2, v79, s14, v63
	v_mov_b32_e32 v3, 0x26800
	v_and_b32_e32 v109, 48, v79
	v_lshl_add_u32 v81, v2, 2, v3
	s_movk_i32 s14, 0x110
	v_add_u32_e32 v2, 0x100, v79
	v_mad_u32_u24 v110, v134, s14, v109
	v_ashrrev_i32_e32 v66, 3, v2
	s_lshl_b64 s[14:15], s[4:5], 22
	s_lshl_b32 s12, s4, 7
	v_lshl_add_u64 v[72:73], s[14:15], 0, v[6:7]
	v_ashrrev_i32_e32 v67, 31, v66
	s_lshl_b32 s14, s96, 7
	s_ashr_i32 s13, s12, 31
	v_ashrrev_i32_e32 v68, 3, v79
	v_lshlrev_b64 v[2:3], 12, v[66:67]
	s_and_b32 s14, s14, 0x80
	v_or3_b32 v2, v2, s14, v62
	s_lshl_b64 s[12:13], s[12:13], 1
	v_ashrrev_i32_e32 v69, 31, v68
	v_lshl_add_u64 v[74:75], v[2:3], 0, s[12:13]
	v_lshlrev_b64 v[2:3], 12, v[68:69]
	v_or3_b32 v2, v2, s14, v62
	v_mul_u32_u24_e32 v111, 0x90, v134
	v_or_b32_e32 v4, 0x1c400, v109
	v_or_b32_e32 v5, 0x17c00, v109
	v_lshl_add_u64 v[76:77], v[2:3], 0, s[12:13]
	v_mov_b32_e32 v2, 0
	s_mov_b32 s18, 0
	v_lshl_add_u64 v[70:71], s[4:5], 2, v[64:65]
	v_or_b32_e32 v108, 0x22800, v62
	v_lshlrev_b32_e32 v107, 7, v68
	v_lshlrev_b32_e32 v106, 7, v66
	v_add_u32_e32 v112, 0x1100, v110
	v_add_u32_e32 v113, 0x2200, v110
	v_add_u32_e32 v116, 0x3300, v110
	v_add_u32_e32 v117, v4, v111
	v_add_u32_e32 v118, v5, v111
	v_add_u32_e32 v119, v0, v158
	v_mov_b32_e32 v3, v2
	v_mov_b32_e32 v4, v2
	v_mov_b32_e32 v5, v2
	v_mov_b32_e32 v6, v2
	v_mov_b32_e32 v7, v2
	v_mov_b32_e32 v8, v2
	v_mov_b32_e32 v9, v2
	v_mov_b32_e32 v10, v2
	v_mov_b32_e32 v11, v2
	v_mov_b32_e32 v12, v2
	v_mov_b32_e32 v13, v2
	v_mov_b32_e32 v18, v2
	v_mov_b32_e32 v19, v2
	v_mov_b32_e32 v20, v2
	v_mov_b32_e32 v21, v2
	v_mov_b32_e32 v22, v2
	v_mov_b32_e32 v23, v2
	v_mov_b32_e32 v24, v2
	v_mov_b32_e32 v25, v2
	v_mov_b32_e32 v26, v2
	v_mov_b32_e32 v27, v2
	v_mov_b32_e32 v28, v2
	v_mov_b32_e32 v29, v2
	v_mov_b32_e32 v30, v2
	v_mov_b32_e32 v31, v2
	v_mov_b32_e32 v32, v2
	v_mov_b32_e32 v33, v2
	v_mov_b32_e32 v14, v2
	v_mov_b32_e32 v15, v2
	v_mov_b32_e32 v16, v2
	v_mov_b32_e32 v17, v2
	s_waitcnt lgkmcnt(0)
	s_barrier
	s_branch .LBB0_665

; DI void gdn_scan_item(const Params& P, int l, int hh, int half, char* smem) {
;     ...
;   if (w >= 4) {
;     const int lt = tid - 256, wl = w - 4;
;     const int dvc = 64 * half + 16 * wl + l15; const float nw = P.gdn_norm[l * 128 + dvc];
;     const int uoff = dvc * 64 + 4 * q4;
;     const int g256 = (lt >> 4) * 128 + (lt & 15) * 8, l256 = (lt >> 4) * 272 + (lt & 15) * 16;
;     const int g128 = (lt >> 3) * 64 + (lt & 7) * 8, l128 = (lt >> 3) * 144 + (lt & 7) * 16;
;     u32x4 pwA[4], pqA[4], pkA[4], pqkA[2], pwB[4], pqB[4], pkB[4], pqkB[2]; u32x2 zA[4], zB[4];
;     ...
;     LD_LOAD(pwA, pqA, pkA, pqkA, 0);
.LBB0_671:
	v_lshl_add_u64 v[2:3], v[114:115], 0, s[12:13]
	s_lshl_b32 s62, s17, 1
	v_lshl_add_u64 v[2:3], v[2:3], 0, s[62:63]
	v_mov_b32_e32 v63, v1
	v_lshl_add_u64 v[2:3], v[2:3], 0, v[62:63]
	s_mov_b64 s[10:11], 0x62e8000
	v_add_u32_e32 v0, v108, v107
	v_lshl_add_u64 v[6:7], v[2:3], 0, s[10:11]
	ds_read_b128 v[2:5], v0
	v_lshlrev_b64 v[8:9], 12, v[68:69]
	v_lshl_add_u64 v[8:9], v[6:7], 0, v[8:9]
	v_add_co_u32_e32 v10, vcc, 0x3f80000, v8
	v_add_u32_e32 v0, v108, v106
	s_nop 0
	v_addc_co_u32_e32 v11, vcc, 0, v9, vcc
	s_waitcnt lgkmcnt(0)
	global_store_dwordx4 v[10:11], v[2:5], off
	ds_read_b128 v[2:5], v0
	v_lshlrev_b64 v[10:11], 12, v[66:67]
	v_lshl_add_u64 v[6:7], v[6:7], 0, v[10:11]
	v_add_co_u32_e32 v10, vcc, 0x3f80000, v6
	v_mov_b32_e32 v0, 0x26800
	s_nop 0
	v_addc_co_u32_e32 v11, vcc, 0, v7, vcc
	s_waitcnt lgkmcnt(0)
	global_store_dwordx4 v[10:11], v[2:5], off
	v_lshl_add_u32 v0, v79, 2, v0
	ds_read_b32 v4, v0
	v_lshlrev_b32_e32 v0, 2, v158
	v_lshl_add_u64 v[2:3], v[64:65], 0, v[0:1]
	v_lshl_add_u64 v[2:3], s[4:5], 2, v[2:3]
	v_add_co_u32_e32 v10, vcc, 0x7f000, v2
	v_or_b32_e32 v0, 0x24800, v62
	s_nop 0
	v_addc_co_u32_e32 v11, vcc, 0, v3, vcc
	v_add_u32_e32 v2, v0, v107
	s_waitcnt lgkmcnt(0)
	global_store_dword v[10:11], v4, off
	s_waitcnt lgkmcnt(0)
	s_barrier
	ds_read_b128 v[2:5], v2
	v_add_co_u32_e32 v8, vcc, 0x3fc0000, v8
	v_add_u32_e32 v0, v0, v106
	s_nop 0
	v_addc_co_u32_e32 v9, vcc, 0, v9, vcc
	s_waitcnt lgkmcnt(0)
	global_store_dwordx4 v[8:9], v[2:5], off
	ds_read_b128 v[2:5], v0
	v_add_co_u32_e32 v6, vcc, 0x3fc0000, v6
	s_nop 1
	v_addc_co_u32_e32 v7, vcc, 0, v7, vcc
	s_waitcnt lgkmcnt(0)
	global_store_dwordx4 v[6:7], v[2:5], off
	ds_read_b32 v0, v81 offset:1024
	s_waitcnt lgkmcnt(0)
	global_store_dword v[10:11], v0, off offset:2048
.LBB0_672:
	s_andn2_saveexec_b64 s[8:9], s[8:9]
	s_cbranch_execz .LBB0_586
	global_load_dwordx2 v[2:3], v1, s[40:41] offset:1120
	s_lshl_b64 s[10:11], s[2:3], 1
	v_lshl_add_u64 v[4:5], v[114:115], 0, s[2:3]
	v_add_u32_e32 v136, -4, v0
	s_lshl_b32 s2, s16, 6
	v_lshl_add_u32 v7, v136, 4, s2
	v_add_u32_e32 v6, 0xffffff00, v79
	v_lshlrev_b32_e32 v0, 4, v79
	v_or_b32_e32 v107, v7, v134
	v_readlane_b32 s2, v255, 61
	v_lshlrev_b32_e32 v18, 4, v134
	v_lshrrev_b32_e32 v19, 4, v6
	v_and_b32_e32 v62, 0x70, v0
	v_add_u32_e32 v0, s2, v107
	v_lshl_add_u64 v[60:61], v[114:115], 0, s[10:11]
	s_mov_b32 s2, 0x1d2e8000
	v_lshrrev_b32_e32 v63, 3, v6
	v_lshl_or_b32 v142, v107, 6, v106
	s_lshl_b64 s[4:5], s[4:5], 22
	v_lshlrev_b32_e32 v163, 9, v135
	v_lshl_add_u64 v[114:115], v[114:115], 0, s[4:5]
	v_or_b32_e32 v162, 0x800, v163
	v_or_b32_e32 v161, 0x1000, v163
	v_or_b32_e32 v159, 0x1800, v163
	s_mov_b32 s12, -2
	s_mov_b64 s[4:5], 0
	s_waitcnt vmcnt(0)
	v_lshl_add_u64 v[64:65], v[0:1], 2, v[2:3]
	v_lshl_or_b32 v0, v19, 8, v18
	v_lshl_add_u64 v[122:123], v[60:61], 0, v[0:1]
	v_add_co_u32_e32 v2, vcc, s2, v122
	s_mov_b32 s2, 0x1f2e8000
	s_nop 0
	v_addc_co_u32_e32 v3, vcc, 0, v123, vcc
	v_add_co_u32_e32 v6, vcc, s2, v122
	s_mov_b32 s2, 0x1d2e9000
	s_nop 0
	v_addc_co_u32_e32 v7, vcc, 0, v123, vcc
	v_add_co_u32_e32 v24, vcc, s2, v122
	s_mov_b32 s2, 0x1f2e9000
	s_nop 0
	v_addc_co_u32_e32 v25, vcc, 0, v123, vcc
	v_add_co_u32_e32 v28, vcc, s2, v122
	s_mov_b32 s2, 0x1d2ea000
	s_nop 0
	v_addc_co_u32_e32 v29, vcc, 0, v123, vcc
	v_add_co_u32_e32 v10, vcc, s2, v122
	s_mov_b32 s2, 0x1f2ea000
	s_nop 0
	v_addc_co_u32_e32 v11, vcc, 0, v123, vcc
	v_add_co_u32_e32 v14, vcc, s2, v122
	s_mov_b32 s2, 0x1d2eb000
	s_nop 0
	v_addc_co_u32_e32 v15, vcc, 0, v123, vcc
	v_add_co_u32_e32 v40, vcc, s2, v122
	s_mov_b32 s2, 0x1f2eb000
	s_nop 0
	v_addc_co_u32_e32 v41, vcc, 0, v123, vcc
	v_lshl_or_b32 v0, v63, 7, v62
	v_add_co_u32_e32 v44, vcc, s2, v122
	v_lshl_add_u64 v[128:129], v[60:61], 0, v[0:1]
	s_nop 0
	v_addc_co_u32_e32 v45, vcc, 0, v123, vcc
	s_mov_b32 s2, 0x212e8000
	v_add_co_u32_e32 v20, vcc, s2, v128
	s_mov_b32 s2, 0x212e9000
	s_nop 0
	v_addc_co_u32_e32 v21, vcc, 0, v129, vcc
	v_add_co_u32_e32 v32, vcc, s2, v128
	s_mov_b32 s2, 0x212ea000
	s_nop 0
	v_addc_co_u32_e32 v33, vcc, 0, v129, vcc
	v_add_co_u32_e32 v36, vcc, s2, v128
	s_mov_b32 s2, 0x212eb000
	s_nop 0
	v_addc_co_u32_e32 v37, vcc, 0, v129, vcc
	v_add_co_u32_e32 v48, vcc, s2, v128
	v_lshl_add_u64 v[130:131], v[4:5], 0, v[0:1]
	s_nop 0
	v_addc_co_u32_e32 v49, vcc, 0, v129, vcc
	s_mov_b32 s2, 0x252e8000
	v_add_co_u32_e32 v52, vcc, s2, v130
	s_mov_b32 s2, 0x252e9000
	s_nop 0
	v_addc_co_u32_e32 v53, vcc, 0, v131, vcc
	v_add_co_u32_e32 v56, vcc, s2, v130
	global_load_dwordx4 v[2:5], v[2:3], off nt
	s_nop 0
	global_load_dwordx4 v[6:9], v[6:7], off nt
	v_addc_co_u32_e32 v57, vcc, 0, v131, vcc
	global_load_dwordx4 v[10:13], v[10:11], off nt
	s_nop 0
	global_load_dwordx4 v[14:17], v[14:15], off nt
	s_nop 0
	global_load_dwordx4 v[20:23], v[20:21], off nt
	s_nop 0
	global_load_dwordx4 v[24:27], v[24:25], off nt
	s_nop 0
	global_load_dwordx4 v[28:31], v[28:29], off nt
	s_nop 0
	global_load_dwordx4 v[32:35], v[32:33], off nt
	s_nop 0
	global_load_dwordx4 v[36:39], v[36:37], off nt
	s_nop 0
	global_load_dwordx4 v[40:43], v[40:41], off nt
	s_nop 0
	global_load_dwordx4 v[44:47], v[44:45], off nt
	s_nop 0
	global_load_dwordx4 v[48:51], v[48:49], off nt
	s_nop 0
	global_load_dwordx4 v[52:55], v[52:53], off nt
	s_nop 0
	global_load_dwordx4 v[56:59], v[56:57], off nt
	s_mov_b64 s[2:3], 0x232e8000
	v_lshl_add_u64 v[116:117], v[60:61], 0, s[2:3]
	s_movk_i32 s2, 0x110
	v_mad_u64_u32 v[118:119], s[2:3], v19, s2, v[18:19]
	s_movk_i32 s2, 0x90
	s_nop 0
	v_mad_u64_u32 v[120:121], s[2:3], v63, s2, v[62:63]
	s_mov_b32 s2, 0x1d2ec000
	s_nop 0
	v_add_co_u32_e32 v18, vcc, s2, v122
	s_mov_b32 s2, 0x1f2ec000
	s_nop 0
	v_addc_co_u32_e32 v19, vcc, 0, v123, vcc
	v_add_co_u32_e32 v60, vcc, s2, v122
	s_mov_b32 s2, 0x1d2ed000
	s_nop 0
	v_addc_co_u32_e32 v61, vcc, 0, v123, vcc
	v_add_co_u32_e32 v62, vcc, s2, v122
	s_mov_b32 s2, 0x1f2ed000
	s_nop 0
	v_addc_co_u32_e32 v63, vcc, 0, v123, vcc
	global_load_dword v119, v[64:65], off
	v_add_co_u32_e32 v64, vcc, s2, v122
	s_mov_b32 s2, 0x1d2ee000
	s_nop 0
	v_addc_co_u32_e32 v65, vcc, 0, v123, vcc
	v_add_co_u32_e32 v66, vcc, s2, v122
	s_mov_b32 s2, 0x1f2ee000
	s_nop 0
	v_addc_co_u32_e32 v67, vcc, 0, v123, vcc
	v_add_co_u32_e32 v68, vcc, s2, v122
	s_mov_b32 s2, 0x1d2ef000
	s_nop 0
	v_addc_co_u32_e32 v69, vcc, 0, v123, vcc
	v_add_co_u32_e32 v70, vcc, s2, v122
	s_mov_b32 s2, 0x1f2ef000
	s_nop 0
	v_addc_co_u32_e32 v71, vcc, 0, v123, vcc
	v_add_co_u32_e32 v72, vcc, s2, v122
	s_mov_b32 s2, 0x212ec000
	s_nop 0
	v_addc_co_u32_e32 v73, vcc, 0, v123, vcc
	v_add_co_u32_e32 v74, vcc, s2, v128
	s_mov_b32 s2, 0x212ed000
	s_nop 0
	v_addc_co_u32_e32 v75, vcc, 0, v129, vcc
	v_add_co_u32_e32 v76, vcc, s2, v128
	s_mov_b32 s2, 0x212ee000
	s_nop 0
	v_addc_co_u32_e32 v77, vcc, 0, v129, vcc
	v_add_co_u32_e32 v78, vcc, s2, v128
	s_mov_b32 s2, 0x212ef000
	s_nop 0
	v_addc_co_u32_e32 v79, vcc, 0, v129, vcc
	s_waitcnt vmcnt(0) lgkmcnt(0)
; #define LZ_LOAD(Z, N) { const int n__ = (N) < 255 ? (N) : 255; _Pragma("unroll") for (int it = 0; it < 4; ++it) Z[it] = __builtin_nontemporal_load((const u32x2*)(Zt + (size_t)n__ * 8192 + uoff + 16 * it)); }
; #define LD_STAGE(PW, PQ, PK, PQK, NB) { char* nb_ = (NB); \
;     _Pragma("unroll") for (int i = 0; i < 4; ++i) { *(u32x4*)(nb_ + l256 + i * 4352) = PW[i]; *(u32x4*)(nb_ + 17408 + l256 + i * 4352) = PQ[i]; *(u32x4*)(nb_ + 34816 + l128 + i * 4608) = PK[i]; } \
;     _Pragma("unroll") for (int i = 0; i < 2; ++i) *(u32x4*)(nb_ + 53248 + l128 + i * 4608) = PQK[i]; }
; DI void gdn_scan_item(const Params& P, int l, int hh, int half, char* smem) {
;     ...
;     LD_LOAD(pwA, pqA, pkA, pqkA, 0);
;     LD_STAGE(pwA, pqA, pkA, pqkA, smem);
;     LD_LOAD(pwA, pqA, pkA, pqkA, 1);
;     LD_LOAD(pwB, pqB, pkB, pqkB, 2);
;     LZ_LOAD(zB, 0);
;     LZ_LOAD(zA, 0);
;     __syncthreads();
	ds_write_b128 v118, v[2:5]
	ds_write_b128 v118, v[6:9] offset:17408
	ds_write_b128 v120, v[20:23] offset:34816
	ds_write_b128 v118, v[24:27] offset:4352
	ds_write_b128 v118, v[28:31] offset:21760
	ds_write_b128 v120, v[32:35] offset:39424
	ds_write_b128 v118, v[10:13] offset:8704
	ds_write_b128 v118, v[14:17] offset:26112
	ds_write_b128 v120, v[36:39] offset:44032
	ds_write_b128 v118, v[40:43] offset:13056
	ds_write_b128 v118, v[44:47] offset:30464
	ds_write_b128 v120, v[48:51] offset:48640
	ds_write_b128 v120, v[52:55] offset:53248
	ds_write_b128 v120, v[56:59] offset:57856
	v_add_co_u32_e32 v42, vcc, s2, v128
	s_mov_b32 s2, 0x252ea000
	s_nop 0
	v_addc_co_u32_e32 v43, vcc, 0, v129, vcc
	global_load_dwordx4 v[6:9], v[18:19], off nt
	global_load_dwordx4 v[2:5], v[60:61], off nt
	global_load_dwordx4 v[10:13], v[74:75], off nt
	global_load_dwordx4 v[14:17], v[62:63], off nt
	s_nop 0
	global_load_dwordx4 v[18:21], v[64:65], off nt
	global_load_dwordx4 v[22:25], v[76:77], off nt
	global_load_dwordx4 v[26:29], v[66:67], off nt
	global_load_dwordx4 v[30:33], v[68:69], off nt
	global_load_dwordx4 v[34:37], v[78:79], off nt
	global_load_dwordx4 v[38:41], v[70:71], off nt
	global_load_dwordx4 v[58:61], v[72:73], off nt
	global_load_dwordx4 v[62:65], v[42:43], off nt
	v_add_co_u32_e32 v42, vcc, s2, v130
	s_mov_b32 s2, 0x252eb000
	s_nop 0
	v_addc_co_u32_e32 v43, vcc, 0, v131, vcc
	v_add_co_u32_e32 v44, vcc, s2, v130
	s_mov_b32 s2, 0x1d2f0000
	s_nop 0
	v_addc_co_u32_e32 v45, vcc, 0, v131, vcc
	global_load_dwordx4 v[74:77], v[42:43], off nt
	global_load_dwordx4 v[78:81], v[44:45], off nt
	v_add_co_u32_e32 v42, vcc, s2, v122
	s_mov_b32 s2, 0x1f2f0000
	s_nop 0
	v_addc_co_u32_e32 v43, vcc, 0, v123, vcc
	v_add_co_u32_e32 v46, vcc, s2, v122
	s_mov_b32 s2, 0x212f0000
	s_nop 0
	v_addc_co_u32_e32 v47, vcc, 0, v123, vcc
	v_add_co_u32_e32 v50, vcc, s2, v128
	s_mov_b32 s2, 0x1d2f1000
	s_nop 0
	v_addc_co_u32_e32 v51, vcc, 0, v129, vcc
	v_add_co_u32_e32 v54, vcc, s2, v122
	s_mov_b32 s2, 0x1f2f1000
	s_nop 0
	v_addc_co_u32_e32 v55, vcc, 0, v123, vcc
	v_add_co_u32_e32 v66, vcc, s2, v122
	s_mov_b32 s2, 0x212f1000
	s_nop 0
	v_addc_co_u32_e32 v67, vcc, 0, v123, vcc
	v_add_co_u32_e32 v70, vcc, s2, v128
	s_mov_b32 s2, 0x1d2f2000
	s_nop 0
	v_addc_co_u32_e32 v71, vcc, 0, v129, vcc
	v_add_co_u32_e32 v82, vcc, s2, v122
	s_mov_b32 s2, 0x1f2f2000
	s_nop 0
	v_addc_co_u32_e32 v83, vcc, 0, v123, vcc
	v_add_co_u32_e32 v86, vcc, s2, v122
	s_mov_b32 s2, 0x212f2000
	s_nop 0
	v_addc_co_u32_e32 v87, vcc, 0, v123, vcc
	v_add_co_u32_e32 v90, vcc, s2, v128
	s_mov_b32 s2, 0x1d2f3000
	s_nop 0
	v_addc_co_u32_e32 v91, vcc, 0, v129, vcc
	v_add_co_u32_e32 v94, vcc, s2, v122
	s_mov_b32 s2, 0x1f2f3000
	s_nop 0
	v_addc_co_u32_e32 v95, vcc, 0, v123, vcc
	v_add_co_u32_e32 v98, vcc, s2, v122
	s_mov_b32 s2, 0x212f3000
	s_nop 0
	v_addc_co_u32_e32 v99, vcc, 0, v123, vcc
	v_add_co_u32_e32 v102, vcc, s2, v128
	s_mov_b32 s2, 0x252ec000
	s_nop 0
	v_addc_co_u32_e32 v103, vcc, 0, v129, vcc
	v_add_co_u32_e32 v108, vcc, s2, v130
	v_lshlrev_b32_e32 v0, 1, v142
	s_nop 0
	v_addc_co_u32_e32 v109, vcc, 0, v131, vcc
	v_lshl_add_u64 v[106:107], v[116:117], 0, v[0:1]
	s_mov_b32 s2, 0x252ed000
	global_load_dwordx4 v[42:45], v[42:43], off nt
	s_nop 0
	global_load_dwordx4 v[46:49], v[46:47], off nt
	s_nop 0
	global_load_dwordx4 v[50:53], v[50:51], off nt
	s_nop 0
	global_load_dwordx4 v[54:57], v[54:55], off nt
	s_nop 0
	global_load_dwordx4 v[66:69], v[66:67], off nt
	s_nop 0
	global_load_dwordx4 v[70:73], v[70:71], off nt
	s_nop 0
	global_load_dwordx4 v[82:85], v[82:83], off nt
	s_nop 0
	global_load_dwordx4 v[86:89], v[86:87], off nt
	s_nop 0
	global_load_dwordx4 v[90:93], v[90:91], off nt
	s_nop 0
	global_load_dwordx4 v[94:97], v[94:95], off nt
	s_nop 0
	global_load_dwordx4 v[98:101], v[98:99], off nt
	s_nop 0
	global_load_dwordx4 v[102:105], v[102:103], off nt
	s_nop 0
	global_load_dwordx2 v[144:145], v[106:107], off nt
	global_load_dwordx2 v[140:141], v[106:107], off offset:32 nt
	global_load_dwordx2 v[138:139], v[106:107], off offset:64 nt
	v_add_co_u32_e32 v110, vcc, s2, v130
	s_mov_b64 s[2:3], 0x1d2e8000
	s_nop 0
	v_addc_co_u32_e32 v111, vcc, 0, v131, vcc
	global_load_dwordx2 v[132:133], v[106:107], off offset:96 nt
	s_nop 0
	global_load_dwordx4 v[106:109], v[108:109], off nt
	s_nop 0
	global_load_dwordx4 v[110:113], v[110:111], off nt
	v_lshl_add_u64 v[124:125], v[122:123], 0, s[2:3]
	s_mov_b64 s[2:3], 0x1f2e8000
	v_lshl_add_u64 v[126:127], v[122:123], 0, s[2:3]
	s_mov_b64 s[2:3], 0x212e8000
	v_lshl_add_u64 v[128:129], v[128:129], 0, s[2:3]
	s_mov_b64 s[2:3], 0x252e8000
	v_lshl_add_u64 v[130:131], v[130:131], 0, s[2:3]
	v_lshlrev_b32_e32 v121, 11, v136
	v_lshlrev_b32_e32 v123, 4, v135
	v_cmp_eq_u32_e64 s[2:3], 0, v134
	v_lshlrev_b32_e32 v134, 1, v134
	v_add_u32_e32 v122, 0x1e800, v121
	v_lshl_or_b32 v123, v136, 8, v123
	v_lshl_or_b32 v134, v136, 5, v134
	v_add_u32_e32 v164, 0xf400, v118
	v_add_u32_e32 v166, 0x22800, v134
	v_add_u32_e32 v165, 0x20800, v121
	v_add_u32_e32 v121, 0x24800, v134
	v_add_u32_e32 v160, 0x26c00, v123
	v_add_u32_e32 v167, 0x26800, v123
	v_lshl_add_u64 v[134:135], v[114:115], 0, v[0:1]
	v_lshlrev_b32_e32 v0, 1, v142
	v_add_u32_e32 v168, v122, v158
	s_waitcnt lgkmcnt(0)
	s_barrier
	s_waitcnt vmcnt(0)
	v_mov_b32_e32 v142, v144
	v_mov_b32_e32 v143, v145
	v_mov_b32_e32 v136, v140
	v_mov_b32_e32 v137, v141
	v_mov_b32_e32 v122, v138
	v_mov_b32_e32 v123, v139
	v_mov_b32_e32 v114, v132
	v_mov_b32_e32 v115, v133
	s_branch .LBB0_675

; DI unsigned pack2(float lo, float hi) { f32x2 v = {lo, hi}; bf2_t b = __builtin_convertvector(v, bf2_t); return __builtin_bit_cast(unsigned, b); }
; DI void unpack8(const u32x4& v, float* f) { f[0] = bflo(v.x); f[1] = bfhi(v.x); f[2] = bflo(v.y); f[3] = bfhi(v.y); f[4] = bflo(v.z); f[5] = bfhi(v.z); f[6] = bflo(v.w); f[7] = bfhi(v.w); }
; DI int opaque_tid() { int t = threadIdx.x; asm volatile("" : "+v"(t)); return t; }
; DI float row16_sum(float v) { v += dppf<0xB1>(v); v += dppf<0x4E>(v); v += dppf<0x141>(v); v += dppf<0x140>(v); return v; }
; DI void gdn_fix_phase(const Params& P) {
;   const int tid = opaque_tid();
;   bf16_t* mixin = (bf16_t*)(P.ws + OFF_H); const float* ssqp = (const float*)(P.ws + OFF_SSQP);
;   for (int idx = blockIdx.x * NT + tid; idx < S_ * 128; idx += gridDim.x * NT) {
;     const int t = idx >> 7, ck = idx & 127, h = ck >> 4;
;     const int p = (tid & 15) >> 1;
;     float sq = ((tid & 1) == 0) ? ssqp[((size_t)p * S_ + t) * 8 + h] : 0.f;
;     sq = row16_sum(sq);
;     const float r = rsqrtf(sq * (1.f / 128.f) + EPS);
;     u32x4* pp = (u32x4*)(mixin + (size_t)t * 2048 + ck * 8); const u32x4 v = *pp; float f[8]; unpack8(v, f);
;     u32x4 o = {pack2(f[0] * r, f[1] * r), pack2(f[2] * r, f[3] * r), pack2(f[4] * r, f[5] * r), pack2(f[6] * r, f[7] * r)}; *pp = o;
;   }
.LBB0_755:
	s_or_b64 exec, exec, s[2:3]
	s_waitcnt vmcnt(0) lgkmcnt(0)
	v_add_f32_dpp v9, v9, v9 quad_perm:[1,0,3,2] row_mask:0xf bank_mask:0xf bound_ctrl:1
	v_lshlrev_b64 v[6:7], 12, v[6:7]
	v_lshl_add_u64 v[6:7], v[4:5], 0, v[6:7]
	v_add_f32_dpp v9, v9, v9 quad_perm:[2,3,0,1] row_mask:0xf bank_mask:0xf bound_ctrl:1
	s_nop 1
	v_add_f32_dpp v9, v9, v9 row_half_mirror row_mask:0xf bank_mask:0xf bound_ctrl:1
	s_nop 1
	v_add_f32_dpp v9, v9, v9 row_mirror row_mask:0xf bank_mask:0xf bound_ctrl:1
	v_fmamk_f32 v9, v9, 0x3c000000, v245
	v_cmp_gt_f32_e64 s[2:3], s84, v9
	v_mul_f32_e32 v10, 0x4b800000, v9
	s_nop 0
	v_cndmask_b32_e64 v9, v9, v10, s[2:3]
	v_rsq_f32_e32 v9, v9
	s_nop 0
	v_mul_f32_e32 v10, 0x45800000, v9
	v_cndmask_b32_e64 v14, v9, v10, s[2:3]
	global_load_dwordx4 v[10:13], v[6:7], off
	v_readlane_b32 s2, v254, 60
	s_waitcnt vmcnt(0) lgkmcnt(0)
	v_lshlrev_b32_e32 v16, 16, v10
	v_and_b32_e32 v17, 0xffff0000, v10
	v_pk_mul_f32 v[16:17], v[14:15], v[16:17] op_sel_hi:[0,1]
	v_cvt_pk_bf16_f32 v10, v16, v17
	v_lshlrev_b32_e32 v16, 16, v11
	v_and_b32_e32 v17, 0xffff0000, v11
	v_pk_mul_f32 v[16:17], v[14:15], v[16:17] op_sel_hi:[0,1]
	v_cvt_pk_bf16_f32 v11, v16, v17
	v_lshlrev_b32_e32 v16, 16, v12
	v_and_b32_e32 v17, 0xffff0000, v12
	v_pk_mul_f32 v[16:17], v[14:15], v[16:17] op_sel_hi:[0,1]
	v_cvt_pk_bf16_f32 v12, v16, v17
	v_lshlrev_b32_e32 v16, 16, v13
	v_and_b32_e32 v17, 0xffff0000, v13
	v_add_u32_e32 v8, s2, v8
	s_mov_b32 s2, 0x1fffff
	v_pk_mul_f32 v[14:15], v[14:15], v[16:17] op_sel_hi:[0,1]
	v_cmp_lt_i32_e64 s[2:3], s2, v8
	v_cvt_pk_bf16_f32 v13, v14, v15
	s_or_b64 s[4:5], s[2:3], s[4:5]
	global_store_dwordx4 v[6:7], v[10:13], off
	s_andn2_b64 exec, exec, s[4:5]
	s_cbranch_execz .LBB0_758
.LBB0_756:
	v_ashrrev_i32_e32 v6, 7, v8
	v_ashrrev_i32_e32 v7, 31, v6
	v_mov_b32_e32 v9, 0
	s_and_saveexec_b64 s[2:3], vcc
	s_cbranch_execz .LBB0_755
	v_lshl_add_u64 v[10:11], v[6:7], 0, v[0:1]
	v_lshlrev_b64 v[10:11], 5, v[10:11]
	v_lshl_add_u64 v[10:11], v[2:3], 0, v[10:11]
	global_load_dword v9, v[10:11], off
	s_branch .LBB0_755

; DI float bflo(unsigned u) { return __uint_as_float(u << 16); }
; DI float bfhi(unsigned u) { return __uint_as_float(u & 0xffff0000u); }
; DI float wave_sum(float v) { v += __shfl_xor(v, 32); v += __shfl_xor(v, 16); v += __shfl_xor(v, 8); v += __shfl_xor(v, 4); v += __shfl_xor(v, 2); v += __shfl_xor(v, 1); return v; }
; DI void rownorm_phase(const Params& P, const float* xin, const bf16_t* yin, float* xout, bf16_t* hout, int lg, int gate_idx, const float* w_post,
;                       int lh, int scale_idx, int shift_idx, const float* w_pre, char* smem) {
;     ...
;     f32x4 xv[8];
; #pragma unroll
;     for (int j = 0; j < 8; ++j) xv[j] = __builtin_nontemporal_load((const f32x4*)(xin + (size_t)row * 2048 + (j * 64 + lane) * 4));
;     if (yin) {
;       f32x4 yv[8]; float ss = 0.f;
; #pragma unroll
;       for (int j = 0; j < 8; ++j) { const u32x2 yb = __builtin_nontemporal_load((const u32x2*)(yin + (size_t)row * 2048 + (j * 64 + lane) * 4)); yv[j] = (f32x4){bflo(yb.x), bfhi(yb.x), bflo(yb.y), bfhi(yb.y)};
;         ss += yv[j].x * yv[j].x + yv[j].y * yv[j].y + yv[j].z * yv[j].z + yv[j].w * yv[j].w; }
;       ss = wave_sum(ss); const float r = rsqrtf(ss * (1.f / 2048.f) + EPS);
; #pragma unroll
;       for (int j = 0; j < 8; ++j) { const f32x4 a = *(const f32x4*)(A1 + (j * 64 + lane) * 4); xv[j] += a * (yv[j] * r); }
;     }
;     if (yin || xout != xin) {
; #pragma unroll
;       for (int j = 0; j < 8; ++j) __builtin_nontemporal_store(xv[j], (f32x4*)(xout + (size_t)row * 2048 + (j * 64 + lane) * 4));
;     }
;     if (hout) {
;       float ss = 0.f;
; #pragma unroll
;       for (int j = 0; j < 8; ++j) ss += xv[j].x * xv[j].x + xv[j].y * xv[j].y + xv[j].z * xv[j].z + xv[j].w * xv[j].w;
.LBB0_889:
	v_ashrrev_i32_e32 v37, 31, v36
	v_lshlrev_b64 v[2:3], 13, v[36:37]
	s_waitcnt vmcnt(0)
	v_lshl_add_u64 v[2:3], v[34:35], 0, v[2:3]
	v_lshlrev_b64 v[50:51], 12, v[36:37]
	v_lshl_add_u64 v[52:53], v[2:3], 0, v[0:1]
	v_lshl_add_u64 v[86:87], v[38:39], 0, v[50:51]
	global_load_dwordx4 v[30:33], v[52:53], off nt
	global_load_dwordx4 v[26:29], v[52:53], off offset:1024 nt
	global_load_dwordx4 v[22:25], v[52:53], off offset:2048 nt
	global_load_dwordx4 v[18:21], v[52:53], off offset:3072 nt
	global_load_dwordx2 v[62:63], v[86:87], off nt
	v_mov_b32_e32 v43, v1
	v_mov_b32_e32 v45, v1
	v_mov_b32_e32 v47, v1
	v_mov_b32_e32 v49, v1
	v_lshl_add_u64 v[54:55], v[2:3], 0, v[42:43]
	v_lshl_add_u64 v[56:57], v[2:3], 0, v[44:45]
	v_lshl_add_u64 v[58:59], v[2:3], 0, v[46:47]
	v_lshl_add_u64 v[60:61], v[2:3], 0, v[48:49]
	s_waitcnt vmcnt(0)
	global_load_dwordx4 v[14:17], v[54:55], off nt
	global_load_dwordx4 v[10:13], v[56:57], off nt
	global_load_dwordx4 v[6:9], v[58:59], off nt
	global_load_dwordx4 v[2:5], v[60:61], off nt
	v_add_u32_e32 v36, s79, v36
	v_lshlrev_b32_e32 v70, 16, v62
	v_and_b32_e32 v71, 0xffff0000, v62
	v_lshlrev_b32_e32 v72, 16, v63
	v_and_b32_e32 v73, 0xffff0000, v63
	global_load_dwordx2 v[62:63], v[86:87], off offset:512 nt
	v_mul_f32_e32 v37, v71, v71
	v_fmac_f32_e32 v37, v70, v70
	v_fmac_f32_e32 v37, v72, v72
	v_fmac_f32_e32 v37, v73, v73
	s_waitcnt vmcnt(0)
	v_lshlrev_b32_e32 v74, 16, v62
	v_and_b32_e32 v75, 0xffff0000, v62
	v_lshlrev_b32_e32 v76, 16, v63
	v_and_b32_e32 v77, 0xffff0000, v63
	global_load_dwordx2 v[62:63], v[86:87], off offset:1024 nt
	v_mul_f32_e32 v43, v75, v75
	v_fmac_f32_e32 v43, v74, v74
	v_fmac_f32_e32 v43, v76, v76
	v_fmac_f32_e32 v43, v77, v77
	v_add_f32_e32 v37, v37, v43
	s_waitcnt vmcnt(0)
	v_lshlrev_b32_e32 v78, 16, v62
	v_and_b32_e32 v79, 0xffff0000, v62
	v_lshlrev_b32_e32 v80, 16, v63
	v_and_b32_e32 v81, 0xffff0000, v63
	global_load_dwordx2 v[62:63], v[86:87], off offset:1536 nt
	global_load_dwordx2 v[88:89], v[86:87], off offset:2048 nt
	global_load_dwordx2 v[66:67], v[86:87], off offset:2560 nt
	global_load_dwordx2 v[102:103], v[86:87], off offset:3072 nt
	global_load_dwordx2 v[92:93], v[86:87], off offset:3584 nt
	v_mul_f32_e32 v43, v79, v79
	v_fmac_f32_e32 v43, v78, v78
	v_fmac_f32_e32 v43, v80, v80
	v_fmac_f32_e32 v43, v81, v81
	v_add_f32_e32 v37, v37, v43
	s_waitcnt vmcnt(0)
	v_lshlrev_b32_e32 v64, 16, v88
	v_and_b32_e32 v83, 0xffff0000, v62
	v_lshlrev_b32_e32 v82, 16, v62
	v_lshlrev_b32_e32 v84, 16, v63
	v_and_b32_e32 v85, 0xffff0000, v63
	v_mul_f32_e32 v43, v83, v83
	v_and_b32_e32 v63, 0xffff0000, v66
	v_and_b32_e32 v62, 0xffff0000, v88
	v_fmac_f32_e32 v43, v82, v82
	v_lshlrev_b32_e32 v65, 16, v66
	v_lshlrev_b32_e32 v68, 16, v89
	v_and_b32_e32 v66, 0xffff0000, v89
	v_pk_mul_f32 v[88:89], v[62:63], v[62:63]
	v_fmac_f32_e32 v43, v84, v84
	v_lshlrev_b32_e32 v69, 16, v67
	v_pk_fma_f32 v[88:89], v[64:65], v[64:65], v[88:89]
	v_fmac_f32_e32 v43, v85, v85
	v_and_b32_e32 v67, 0xffff0000, v67
	v_pk_fma_f32 v[88:89], v[68:69], v[68:69], v[88:89]
	v_add_f32_e32 v37, v37, v43
	v_pk_fma_f32 v[88:89], v[66:67], v[66:67], v[88:89]
	v_lshlrev_b32_e32 v87, 16, v92
	v_add_f32_e32 v37, v37, v88
	v_add_f32_e32 v37, v37, v89
	v_and_b32_e32 v89, 0xffff0000, v92
	v_and_b32_e32 v88, 0xffff0000, v102
	v_lshlrev_b32_e32 v86, 16, v102
	v_lshlrev_b32_e32 v90, 16, v103
	v_and_b32_e32 v92, 0xffff0000, v103
	v_pk_mul_f32 v[102:103], v[88:89], v[88:89]
	v_lshlrev_b32_e32 v91, 16, v93
	v_pk_fma_f32 v[102:103], v[86:87], v[86:87], v[102:103]
	v_and_b32_e32 v93, 0xffff0000, v93
	v_pk_fma_f32 v[102:103], v[90:91], v[90:91], v[102:103]
	s_nop 0
	v_pk_fma_f32 v[102:103], v[92:93], v[92:93], v[102:103]
	s_nop 0
	v_add_f32_e32 v37, v37, v102
	v_add_f32_e32 v37, v37, v103
	ds_bpermute_b32 v43, v96, v37
	ds_read_b128 v[102:105], v95
	s_waitcnt lgkmcnt(0)
	v_add_f32_e32 v37, v37, v43
	ds_bpermute_b32 v43, v97, v37
	s_waitcnt lgkmcnt(0)
	v_add_f32_e32 v37, v37, v43
	ds_bpermute_b32 v43, v98, v37
	s_waitcnt lgkmcnt(0)
	v_add_f32_e32 v37, v37, v43
	ds_bpermute_b32 v43, v99, v37
	s_waitcnt lgkmcnt(0)
	v_add_f32_e32 v37, v37, v43
	ds_bpermute_b32 v43, v100, v37
	s_waitcnt lgkmcnt(0)
	v_add_f32_e32 v37, v37, v43
	ds_bpermute_b32 v43, v101, v37
	s_waitcnt lgkmcnt(0)
	v_add_f32_e32 v37, v37, v43
	v_fmamk_f32 v37, v37, 0x3a000000, v245
	v_cmp_gt_f32_e32 vcc, s84, v37
	v_mul_f32_e32 v43, 0x4b800000, v37
	s_nop 0
	v_cndmask_b32_e32 v37, v37, v43, vcc
	v_rsq_f32_e32 v37, v37
	s_nop 0
	v_mul_f32_e32 v43, 0x45800000, v37
	v_cndmask_b32_e32 v94, v37, v43, vcc
	v_pk_mul_f32 v[70:71], v[70:71], v[94:95] op_sel_hi:[1,0]
	v_pk_mul_f32 v[72:73], v[72:73], v[94:95] op_sel_hi:[1,0]
	v_pk_fma_f32 v[30:31], v[102:103], v[70:71], v[30:31]
	v_pk_fma_f32 v[32:33], v[104:105], v[72:73], v[32:33]
	ds_read_b128 v[70:73], v95 offset:1024
	v_pk_mul_f32 v[74:75], v[74:75], v[94:95] op_sel_hi:[1,0]
	v_pk_mul_f32 v[76:77], v[76:77], v[94:95] op_sel_hi:[1,0]
	v_mul_f32_e32 v37, v31, v31
	v_fmac_f32_e32 v37, v30, v30
	s_waitcnt lgkmcnt(0)
	v_pk_fma_f32 v[28:29], v[72:73], v[76:77], v[28:29]
	v_pk_fma_f32 v[26:27], v[70:71], v[74:75], v[26:27]
	ds_read_b128 v[70:73], v95 offset:2048
	v_pk_mul_f32 v[74:75], v[78:79], v[94:95] op_sel_hi:[1,0]
	v_pk_mul_f32 v[76:77], v[80:81], v[94:95] op_sel_hi:[1,0]
	v_mul_f32_e32 v43, v27, v27
	v_fmac_f32_e32 v43, v26, v26
	s_waitcnt lgkmcnt(0)
	v_pk_fma_f32 v[24:25], v[72:73], v[76:77], v[24:25]
	v_pk_fma_f32 v[22:23], v[70:71], v[74:75], v[22:23]
	ds_read_b128 v[70:73], v95 offset:3072
	v_pk_mul_f32 v[74:75], v[82:83], v[94:95] op_sel_hi:[1,0]
	v_pk_mul_f32 v[76:77], v[84:85], v[94:95] op_sel_hi:[1,0]
	v_fmac_f32_e32 v37, v32, v32
	v_fmac_f32_e32 v43, v28, v28
	s_waitcnt lgkmcnt(0)
; DI float wave_sum(float v) { v += __shfl_xor(v, 32); v += __shfl_xor(v, 16); v += __shfl_xor(v, 8); v += __shfl_xor(v, 4); v += __shfl_xor(v, 2); v += __shfl_xor(v, 1); return v; }
; DI void rownorm_phase(const Params& P, const float* xin, const bf16_t* yin, float* xout, bf16_t* hout, int lg, int gate_idx, const float* w_post,
;                       int lh, int scale_idx, int shift_idx, const float* w_pre, char* smem) {
;     ...
;       for (int j = 0; j < 8; ++j) { const f32x4 a = *(const f32x4*)(A1 + (j * 64 + lane) * 4); xv[j] += a * (yv[j] * r); }
;     }
;     if (yin || xout != xin) {
; #pragma unroll
;       for (int j = 0; j < 8; ++j) __builtin_nontemporal_store(xv[j], (f32x4*)(xout + (size_t)row * 2048 + (j * 64 + lane) * 4));
;     }
;     if (hout) {
;       float ss = 0.f;
; #pragma unroll
;       for (int j = 0; j < 8; ++j) ss += xv[j].x * xv[j].x + xv[j].y * xv[j].y + xv[j].z * xv[j].z + xv[j].w * xv[j].w;
;       ss = wave_sum(ss); const float r = rsqrtf(ss * (1.f / 2048.f) + EPS);
	v_pk_fma_f32 v[20:21], v[72:73], v[76:77], v[20:21]
	v_pk_fma_f32 v[18:19], v[70:71], v[74:75], v[18:19]
	ds_read_b128 v[70:73], v95 offset:4096
	v_mov_b32_e32 v74, v64
	v_mov_b32_e32 v75, v62
	v_mov_b32_e32 v76, v68
	v_mov_b32_e32 v77, v66
	v_pk_mul_f32 v[74:75], v[74:75], v[94:95] op_sel_hi:[1,0]
	v_pk_mul_f32 v[76:77], v[76:77], v[94:95] op_sel_hi:[1,0]
	s_waitcnt lgkmcnt(0)
	v_pk_fma_f32 v[14:15], v[70:71], v[74:75], v[14:15]
	v_pk_fma_f32 v[16:17], v[72:73], v[76:77], v[16:17]
	ds_read_b128 v[70:73], v95 offset:5120
	v_mov_b32_e32 v62, v65
	v_mov_b32_e32 v66, v69
	v_pk_mul_f32 v[62:63], v[62:63], v[94:95] op_sel_hi:[1,0]
	v_pk_mul_f32 v[64:65], v[66:67], v[94:95] op_sel_hi:[1,0]
	s_waitcnt lgkmcnt(0)
	v_pk_fma_f32 v[10:11], v[70:71], v[62:63], v[10:11]
	v_pk_fma_f32 v[12:13], v[72:73], v[64:65], v[12:13]
	ds_read_b128 v[62:65], v95 offset:6144
	v_mov_b32_e32 v66, v86
	v_mov_b32_e32 v67, v88
	v_mov_b32_e32 v68, v90
	v_mov_b32_e32 v69, v92
	v_pk_mul_f32 v[66:67], v[66:67], v[94:95] op_sel_hi:[1,0]
	v_pk_mul_f32 v[68:69], v[68:69], v[94:95] op_sel_hi:[1,0]
	s_waitcnt lgkmcnt(0)
	v_pk_fma_f32 v[6:7], v[62:63], v[66:67], v[6:7]
	v_pk_fma_f32 v[8:9], v[64:65], v[68:69], v[8:9]
	ds_read_b128 v[62:65], v95 offset:7168
	v_fmac_f32_e32 v37, v33, v33
	v_fmac_f32_e32 v43, v29, v29
	v_add_f32_e32 v37, v37, v43
	v_mul_f32_e32 v43, v23, v23
	v_fmac_f32_e32 v43, v22, v22
	v_mov_b32_e32 v88, v87
	v_mov_b32_e32 v92, v91
	v_fmac_f32_e32 v43, v24, v24
	v_pk_mul_f32 v[66:67], v[88:89], v[94:95] op_sel_hi:[1,0]
	v_pk_mul_f32 v[68:69], v[92:93], v[94:95] op_sel_hi:[1,0]
	v_fmac_f32_e32 v43, v25, v25
	s_waitcnt lgkmcnt(0)
	v_pk_fma_f32 v[4:5], v[64:65], v[68:69], v[4:5]
	v_pk_fma_f32 v[2:3], v[62:63], v[66:67], v[2:3]
	global_store_dwordx4 v[52:53], v[30:33], off nt
	global_store_dwordx4 v[52:53], v[26:29], off offset:1024 nt
	global_store_dwordx4 v[52:53], v[22:25], off offset:2048 nt
	global_store_dwordx4 v[52:53], v[18:21], off offset:3072 nt
	global_store_dwordx4 v[54:55], v[14:17], off nt
	global_store_dwordx4 v[56:57], v[10:13], off nt
	global_store_dwordx4 v[58:59], v[6:9], off nt
	global_store_dwordx4 v[60:61], v[2:5], off nt
	v_add_f32_e32 v37, v43, v37
	v_mul_f32_e32 v43, v19, v19
	v_mov_b32_e32 v54, v11
	v_mov_b32_e32 v55, v15
	v_fmac_f32_e32 v43, v18, v18
	v_mov_b32_e32 v52, v10
	v_mov_b32_e32 v53, v14
	v_pk_mul_f32 v[54:55], v[54:55], v[54:55]
	v_fmac_f32_e32 v43, v20, v20
	v_pk_fma_f32 v[52:53], v[52:53], v[52:53], v[54:55]
	v_mov_b32_e32 v54, v12
	v_mov_b32_e32 v55, v16
	v_fmac_f32_e32 v43, v21, v21
	v_pk_fma_f32 v[52:53], v[54:55], v[54:55], v[52:53]
	v_mov_b32_e32 v54, v13
	v_mov_b32_e32 v55, v17
	v_add_f32_e32 v37, v43, v37
	v_pk_fma_f32 v[52:53], v[54:55], v[54:55], v[52:53]
	v_mov_b32_e32 v54, v3
	v_add_f32_e32 v37, v53, v37
	v_mov_b32_e32 v55, v7
	v_add_f32_e32 v37, v52, v37
	v_mov_b32_e32 v52, v2
	v_mov_b32_e32 v53, v6
	v_pk_mul_f32 v[54:55], v[54:55], v[54:55]
	s_nop 0
	v_pk_fma_f32 v[52:53], v[52:53], v[52:53], v[54:55]
	v_mov_b32_e32 v54, v4
	v_mov_b32_e32 v55, v8
	v_pk_fma_f32 v[52:53], v[54:55], v[54:55], v[52:53]
	v_mov_b32_e32 v54, v5
	v_mov_b32_e32 v55, v9
	v_pk_fma_f32 v[52:53], v[54:55], v[54:55], v[52:53]
	ds_read_b128 v[54:57], v95 offset:8192
	ds_read_b128 v[58:61], v95 offset:16384
	v_add_f32_e32 v37, v53, v37
	v_add_f32_e32 v37, v52, v37
	ds_bpermute_b32 v43, v96, v37
	s_waitcnt lgkmcnt(0)
	v_add_f32_e32 v37, v37, v43
	ds_bpermute_b32 v43, v97, v37
	s_waitcnt lgkmcnt(0)
	v_add_f32_e32 v37, v37, v43
	ds_bpermute_b32 v43, v98, v37
	s_waitcnt lgkmcnt(0)
	v_add_f32_e32 v37, v37, v43
	ds_bpermute_b32 v43, v99, v37
	s_waitcnt lgkmcnt(0)
	v_add_f32_e32 v37, v37, v43
	ds_bpermute_b32 v43, v100, v37
	s_waitcnt lgkmcnt(0)
	v_add_f32_e32 v37, v37, v43
	ds_bpermute_b32 v43, v101, v37
	s_waitcnt lgkmcnt(0)
; DI unsigned pack2(float lo, float hi) { f32x2 v = {lo, hi}; bf2_t b = __builtin_convertvector(v, bf2_t); return __builtin_bit_cast(unsigned, b); }
; DI float wave_sum(float v) { v += __shfl_xor(v, 32); v += __shfl_xor(v, 16); v += __shfl_xor(v, 8); v += __shfl_xor(v, 4); v += __shfl_xor(v, 2); v += __shfl_xor(v, 1); return v; }
; DI void rownorm_phase(const Params& P, const float* xin, const bf16_t* yin, float* xout, bf16_t* hout, int lg, int gate_idx, const float* w_post,
;                       int lh, int scale_idx, int shift_idx, const float* w_pre, char* smem) {
;     ...
;       ss = wave_sum(ss); const float r = rsqrtf(ss * (1.f / 2048.f) + EPS);
; #pragma unroll
;       for (int j = 0; j < 8; ++j) { const f32x4 a = *(const f32x4*)(A2 + (j * 64 + lane) * 4), b = *(const f32x4*)(B2 + (j * 64 + lane) * 4);
;         const f32x4 hv = xv[j] * r * a + b; u32x2 pk = {pack2(hv.x, hv.y), pack2(hv.z, hv.w)};
;         *(u32x2*)(hout + (size_t)row * 2048 + (j * 64 + lane) * 4) = pk; }
	v_add_f32_e32 v37, v37, v43
	v_fmamk_f32 v37, v37, 0x3a000000, v245
	v_cmp_gt_f32_e32 vcc, s84, v37
	v_mul_f32_e32 v43, 0x4b800000, v37
	s_nop 0
	v_cndmask_b32_e32 v37, v37, v43, vcc
	v_rsq_f32_e32 v37, v37
	s_nop 0
	v_mul_f32_e32 v43, 0x45800000, v37
	v_cndmask_b32_e32 v52, v37, v43, vcc
	v_pk_mul_f32 v[30:31], v[30:31], v[52:53] op_sel_hi:[1,0]
	v_pk_mul_f32 v[32:33], v[32:33], v[52:53] op_sel_hi:[1,0]
	v_pk_fma_f32 v[30:31], v[54:55], v[30:31], v[58:59]
	v_pk_fma_f32 v[32:33], v[56:57], v[32:33], v[60:61]
	v_cvt_pk_bf16_f32 v54, v30, v31
	v_cvt_pk_bf16_f32 v55, v32, v33
	v_lshl_add_u64 v[30:31], v[40:41], 0, v[50:51]
	global_store_dwordx2 v[30:31], v[54:55], off
	ds_read_b128 v[54:57], v95 offset:9216
	ds_read_b128 v[58:61], v95 offset:17408
	v_pk_mul_f32 v[26:27], v[26:27], v[52:53] op_sel_hi:[1,0]
	v_pk_mul_f32 v[28:29], v[28:29], v[52:53] op_sel_hi:[1,0]
	v_pk_mul_f32 v[22:23], v[22:23], v[52:53] op_sel_hi:[1,0]
	v_pk_mul_f32 v[24:25], v[24:25], v[52:53] op_sel_hi:[1,0]
	s_waitcnt lgkmcnt(0)
	v_pk_fma_f32 v[28:29], v[56:57], v[28:29], v[60:61]
	v_pk_fma_f32 v[26:27], v[54:55], v[26:27], v[58:59]
	v_pk_mul_f32 v[18:19], v[18:19], v[52:53] op_sel_hi:[1,0]
	v_cvt_pk_bf16_f32 v26, v26, v27
	v_cvt_pk_bf16_f32 v27, v28, v29
	global_store_dwordx2 v[30:31], v[26:27], off offset:512
	ds_read_b128 v[26:29], v95 offset:10240
	ds_read_b128 v[54:57], v95 offset:18432
	v_pk_mul_f32 v[20:21], v[20:21], v[52:53] op_sel_hi:[1,0]
	v_pk_mul_f32 v[14:15], v[14:15], v[52:53] op_sel_hi:[1,0]
	v_pk_mul_f32 v[16:17], v[16:17], v[52:53] op_sel_hi:[1,0]
	v_pk_mul_f32 v[10:11], v[10:11], v[52:53] op_sel_hi:[1,0]
	s_waitcnt lgkmcnt(0)
	v_pk_fma_f32 v[24:25], v[28:29], v[24:25], v[56:57]
	v_pk_fma_f32 v[22:23], v[26:27], v[22:23], v[54:55]
	v_pk_mul_f32 v[12:13], v[12:13], v[52:53] op_sel_hi:[1,0]
	v_cvt_pk_bf16_f32 v22, v22, v23
	v_cvt_pk_bf16_f32 v23, v24, v25
	global_store_dwordx2 v[30:31], v[22:23], off offset:1024
	ds_read_b128 v[22:25], v95 offset:11264
	ds_read_b128 v[26:29], v95 offset:19456
	v_pk_mul_f32 v[6:7], v[6:7], v[52:53] op_sel_hi:[1,0]
	v_pk_mul_f32 v[8:9], v[8:9], v[52:53] op_sel_hi:[1,0]
	v_pk_mul_f32 v[2:3], v[2:3], v[52:53] op_sel_hi:[1,0]
	v_pk_mul_f32 v[4:5], v[4:5], v[52:53] op_sel_hi:[1,0]
	s_waitcnt lgkmcnt(0)
	v_pk_fma_f32 v[20:21], v[24:25], v[20:21], v[28:29]
	v_pk_fma_f32 v[18:19], v[22:23], v[18:19], v[26:27]
	v_cmp_lt_i32_e32 vcc, s10, v36
	v_cvt_pk_bf16_f32 v18, v18, v19
	v_cvt_pk_bf16_f32 v19, v20, v21
	global_store_dwordx2 v[30:31], v[18:19], off offset:1536
	ds_read_b128 v[18:21], v95 offset:12288
	ds_read_b128 v[22:25], v95 offset:20480
	s_or_b64 s[8:9], vcc, s[8:9]
	s_waitcnt lgkmcnt(0)
	v_pk_fma_f32 v[16:17], v[20:21], v[16:17], v[24:25]
	v_pk_fma_f32 v[14:15], v[18:19], v[14:15], v[22:23]
	s_nop 0
	v_cvt_pk_bf16_f32 v14, v14, v15
	v_cvt_pk_bf16_f32 v15, v16, v17
	global_store_dwordx2 v[30:31], v[14:15], off offset:2048
	ds_read_b128 v[14:17], v95 offset:13312
	ds_read_b128 v[18:21], v95 offset:21504
	s_waitcnt lgkmcnt(0)
	v_pk_fma_f32 v[12:13], v[16:17], v[12:13], v[20:21]
	v_pk_fma_f32 v[10:11], v[14:15], v[10:11], v[18:19]
	s_nop 0
	v_cvt_pk_bf16_f32 v10, v10, v11
	v_cvt_pk_bf16_f32 v11, v12, v13
	global_store_dwordx2 v[30:31], v[10:11], off offset:2560
	ds_read_b128 v[10:13], v95 offset:14336
	ds_read_b128 v[14:17], v95 offset:22528
	s_waitcnt lgkmcnt(0)
	v_pk_fma_f32 v[8:9], v[12:13], v[8:9], v[16:17]
	v_pk_fma_f32 v[6:7], v[10:11], v[6:7], v[14:15]
	s_nop 0
	v_cvt_pk_bf16_f32 v6, v6, v7
	v_cvt_pk_bf16_f32 v7, v8, v9
	global_store_dwordx2 v[30:31], v[6:7], off offset:3072
	ds_read_b128 v[6:9], v95 offset:15360
	ds_read_b128 v[10:13], v95 offset:23552
	s_waitcnt lgkmcnt(0)
	v_pk_fma_f32 v[4:5], v[8:9], v[4:5], v[12:13]
	v_pk_fma_f32 v[2:3], v[6:7], v[2:3], v[10:11]
	s_nop 0
	v_cvt_pk_bf16_f32 v2, v2, v3
	v_cvt_pk_bf16_f32 v3, v4, v5
	global_store_dwordx2 v[30:31], v[2:3], off offset:3584
	s_andn2_b64 exec, exec, s[8:9]
	s_cbranch_execnz .LBB0_889

; DI void unpack8(const u32x4& v, float* f) { f[0] = bflo(v.x); f[1] = bfhi(v.x); f[2] = bflo(v.y); f[3] = bfhi(v.y); f[4] = bflo(v.z); f[5] = bfhi(v.z); f[6] = bflo(v.w); f[7] = bfhi(v.w); }
; DI void ffn_act_phase(const Params& P, int l) {
;     ...
;   for (int item = blockIdx.x * 8 + w; item < 512 * 11; item += gridDim.x * 8) {
;     const int cbk = item % 11, rr = item / 11; const int ch = cbk * 512 + lane * 8, r0 = rr * 32;
;     float wg[3][8], wu[3][8], bg[8], bu[8];
; #pragma unroll
;     for (int j = 0; j < 3; ++j)
; #pragma unroll
;       for (int e4 = 0; e4 < 2; ++e4) { const f32x4 a = *(const f32x4*)(cw + (size_t)j * DFF2 + ch + 4 * e4), b = *(const f32x4*)(cw + (size_t)j * DFF2 + DFF + ch + 4 * e4);
;         wg[j][4 * e4] = a.x; wg[j][4 * e4 + 1] = a.y; wg[j][4 * e4 + 2] = a.z; wg[j][4 * e4 + 3] = a.w; wu[j][4 * e4] = b.x; wu[j][4 * e4 + 1] = b.y; wu[j][4 * e4 + 2] = b.z; wu[j][4 * e4 + 3] = b.w; }
; #pragma unroll
;     for (int e4 = 0; e4 < 2; ++e4) { const f32x4 a = *(const f32x4*)(cb + ch + 4 * e4), b = *(const f32x4*)(cb + DFF + ch + 4 * e4);
;       bg[4 * e4] = a.x; bg[4 * e4 + 1] = a.y; bg[4 * e4 + 2] = a.z; bg[4 * e4 + 3] = a.w; bu[4 * e4] = b.x; bu[4 * e4 + 1] = b.y; bu[4 * e4 + 2] = b.z; bu[4 * e4 + 3] = b.w; }
;     float g2[8], g1[8], u2[8], u1[8];
; #pragma unroll
;     for (int e = 0; e < 8; ++e) { g2[e] = 0.f; g1[e] = 0.f; u2[e] = 0.f; u1[e] = 0.f; }
;     if (r0 >= 2) { unpack8(*(const u32x4*)(u + (size_t)(r0 - 2) * DFF2 + ch), g2); unpack8(*(const u32x4*)(u + (size_t)(r0 - 2) * DFF2 + DFF + ch), u2);
;       unpack8(*(const u32x4*)(u + (size_t)(r0 - 1) * DFF2 + ch), g1); unpack8(*(const u32x4*)(u + (size_t)(r0 - 1) * DFF2 + DFF + ch), u1); }
.LBB0_1018:
	s_mov_b32 s22, 0x2e8ba2e9
	v_mul_hi_i32 v0, v209, s22
	v_lshrrev_b32_e32 v2, 31, v0
	v_ashrrev_i32_e32 v0, 1, v0
	v_add_u32_e32 v0, v0, v2
	v_mul_lo_u32 v2, v0, 11
	v_sub_u32_e32 v2, v209, v2
	v_lshl_or_b32 v68, v2, 9, v246
	v_ashrrev_i32_e32 v69, 31, v68
	v_lshlrev_b64 v[50:51], 2, v[68:69]
	v_lshl_add_u64 v[6:7], s[8:9], 0, v[50:51]
	v_lshl_add_u64 v[14:15], s[10:11], 0, v[50:51]
	v_lshl_add_u64 v[22:23], s[12:13], 0, v[50:51]
	v_lshl_add_u64 v[30:31], s[14:15], 0, v[50:51]
	v_lshl_add_u64 v[38:39], s[16:17], 0, v[50:51]
	v_lshl_add_u64 v[46:47], s[18:19], 0, v[50:51]
	v_lshl_add_u64 v[54:55], v[134:135], 0, v[50:51]
	v_lshl_add_u64 v[62:63], v[136:137], 0, v[50:51]
	global_load_dwordx4 v[2:5], v[6:7], off
	s_nop 0
	global_load_dwordx4 v[6:9], v[6:7], off offset:16
	s_nop 0
	global_load_dwordx4 v[10:13], v[14:15], off
	s_nop 0
	global_load_dwordx4 v[14:17], v[14:15], off offset:16
	s_nop 0
	global_load_dwordx4 v[18:21], v[22:23], off
	s_nop 0
	global_load_dwordx4 v[22:25], v[22:23], off offset:16
	s_nop 0
	global_load_dwordx4 v[26:29], v[30:31], off
	s_nop 0
	global_load_dwordx4 v[30:33], v[30:31], off offset:16
	s_nop 0
	global_load_dwordx4 v[34:37], v[38:39], off
	s_nop 0
	global_load_dwordx4 v[38:41], v[38:39], off offset:16
	s_nop 0
	global_load_dwordx4 v[42:45], v[46:47], off
	s_nop 0
	global_load_dwordx4 v[46:49], v[46:47], off offset:16
	s_nop 0
	global_load_dwordx4 v[50:53], v[54:55], off
	s_nop 0
	global_load_dwordx4 v[54:57], v[54:55], off offset:16
	s_nop 0
	global_load_dwordx4 v[58:61], v[62:63], off
	s_nop 0
	global_load_dwordx4 v[62:65], v[62:63], off offset:16
	v_lshlrev_b32_e32 v66, 5, v0
	v_mov_b32_e32 v0, v1
	v_cmp_lt_i32_e32 vcc, 10, v209
	v_mov_b32_e32 v159, 0
	v_lshlrev_b64 v[138:139], 1, v[68:69]
	v_mov_b64_e32 v[140:141], v[0:1]
	v_mov_b64_e32 v[164:165], v[0:1]
	v_mov_b64_e32 v[172:173], v[0:1]
	v_mov_b64_e32 v[170:171], v[0:1]
	v_mov_b64_e32 v[178:179], v[0:1]
	v_mov_b64_e32 v[150:151], v[0:1]
	v_mov_b64_e32 v[154:155], v[0:1]
	v_mov_b64_e32 v[142:143], v[0:1]
	v_mov_b64_e32 v[174:175], v[0:1]
	v_mov_b64_e32 v[144:145], v[0:1]
	v_mov_b64_e32 v[152:153], v[0:1]
	v_mov_b64_e32 v[148:149], v[0:1]
	v_mov_b64_e32 v[168:169], v[0:1]
	v_mov_b64_e32 v[146:147], v[0:1]
	v_mov_b64_e32 v[166:167], v[0:1]
	v_mov_b32_e32 v157, 0
	s_and_saveexec_b64 s[22:23], vcc
	s_cbranch_execz .LBB0_1020
	v_add_u32_e32 v0, -2, v66
	s_movk_i32 s26, 0x5800
	v_mad_u64_u32 v[68:69], s[24:25], v0, s26, v[132:133]
	v_add_u32_e32 v0, -1, v66
	v_mad_u64_u32 v[72:73], s[24:25], v0, s26, v[132:133]
	v_lshl_add_u64 v[76:77], v[68:69], 0, v[138:139]
	v_lshl_add_u64 v[80:81], v[72:73], 0, v[138:139]
	global_load_dwordx4 v[68:71], v[76:77], off
	global_load_dwordx4 v[72:75], v[80:81], off
	v_add_co_u32_e32 v76, vcc, s83, v76
	s_waitcnt vmcnt(0) lgkmcnt(0)
	v_lshlrev_b32_e32 v166, 16, v68
	v_addc_co_u32_e32 v77, vcc, 0, v77, vcc
	v_add_co_u32_e32 v80, vcc, s83, v80
	global_load_dwordx4 v[76:79], v[76:77], off offset:3072
	s_nop 0
	v_addc_co_u32_e32 v81, vcc, 0, v81, vcc
	global_load_dwordx4 v[80:83], v[80:81], off offset:3072
	v_and_b32_e32 v167, 0xffff0000, v68
	v_lshlrev_b32_e32 v168, 16, v69
	v_and_b32_e32 v169, 0xffff0000, v69
	v_lshlrev_b32_e32 v174, 16, v70
	v_and_b32_e32 v175, 0xffff0000, v70
	v_lshlrev_b32_e32 v178, 16, v71
	v_and_b32_e32 v179, 0xffff0000, v71
	v_lshlrev_b32_e32 v148, 16, v73
	v_and_b32_e32 v149, 0xffff0000, v73
	v_lshlrev_b32_e32 v142, 16, v74
	v_and_b32_e32 v143, 0xffff0000, v74
	v_lshlrev_b32_e32 v170, 16, v75
	v_and_b32_e32 v171, 0xffff0000, v75
	v_lshlrev_b32_e32 v141, 16, v72
	v_and_b32_e32 v157, 0xffff0000, v72
	s_waitcnt vmcnt(0) lgkmcnt(0)
	v_lshlrev_b32_e32 v146, 16, v76
	v_and_b32_e32 v147, 0xffff0000, v76
	v_lshlrev_b32_e32 v144, 16, v77
	v_lshlrev_b32_e32 v140, 16, v80
	v_and_b32_e32 v159, 0xffff0000, v80
	v_and_b32_e32 v145, 0xffff0000, v77
	v_lshlrev_b32_e32 v152, 16, v81
	v_and_b32_e32 v153, 0xffff0000, v81
	v_lshlrev_b32_e32 v150, 16, v78
	v_and_b32_e32 v151, 0xffff0000, v78
	v_lshlrev_b32_e32 v154, 16, v82
	v_and_b32_e32 v155, 0xffff0000, v82
	v_lshlrev_b32_e32 v164, 16, v79
	v_and_b32_e32 v165, 0xffff0000, v79
	v_lshlrev_b32_e32 v172, 16, v83
	v_and_b32_e32 v173, 0xffff0000, v83

; DI unsigned pack2(float lo, float hi) { f32x2 v = {lo, hi}; bf2_t b = __builtin_convertvector(v, bf2_t); return __builtin_bit_cast(unsigned, b); }
; DI void unpack8(const u32x4& v, float* f) { f[0] = bflo(v.x); f[1] = bfhi(v.x); f[2] = bflo(v.y); f[3] = bfhi(v.y); f[4] = bflo(v.z); f[5] = bfhi(v.z); f[6] = bflo(v.w); f[7] = bfhi(v.w); }
; DI float gelu_tanh(float x) { const float y = 0.7978845608028654f * (x + 0.044715f * x * x * x); const float t = 1.f - 2.f * __builtin_amdgcn_rcpf(1.f + __expf(2.f * y)); return 0.5f * x * (1.f + t); }
; DI void ffn_act_phase(const Params& P, int l) {
;     ...
;     for (int rb = 0; rb < 4; ++rb) {
;       u32x4 G[8], U[8];
; #pragma unroll
;       for (int i = 0; i < 8; ++i) { const size_t ro = (size_t)(r0 + rb * 8 + i) * DFF2 + ch; G[i] = __builtin_nontemporal_load((const u32x4*)(u + ro)); U[i] = __builtin_nontemporal_load((const u32x4*)(u + ro + DFF)); }
; #pragma unroll
;       for (int i = 0; i < 8; ++i) {
;         float g0[8], u0[8]; unpack8(G[i], g0); unpack8(U[i], u0);
;         float o[8];
; #pragma unroll
;         for (int e = 0; e < 8; ++e) { const float yg = wg[0][e] * g2[e] + wg[1][e] * g1[e] + wg[2][e] * g0[e] + bg[e]; const float yu = wu[0][e] * u2[e] + wu[1][e] * u1[e] + wu[2][e] * u0[e] + bu[e];
;           o[e] = gelu_tanh(yg) * yu; g2[e] = g1[e]; g1[e] = g0[e]; u2[e] = u1[e]; u1[e] = u0[e]; }
;         u32x4 pk = {pack2(o[0], o[1]), pack2(o[2], o[3]), pack2(o[4], o[5]), pack2(o[6], o[7])};
;         *(u32x4*)(act + (size_t)(r0 + rb * 8 + i) * DFF + ch) = pk;
;       }
.LBB0_1021:
	v_lshl_add_u64 v[70:71], v[162:163], 0, v[138:139]
	s_mov_b32 s23, 0x122e8000
	v_add_co_u32_e32 v66, vcc, s23, v70
	s_mov_b32 s23, 0x122ed000
	s_nop 0
	v_addc_co_u32_e32 v67, vcc, 0, v71, vcc
	global_load_dwordx4 v[82:85], v[66:67], off nt
	v_add_co_u32_e32 v66, vcc, s85, v70
	s_waitcnt vmcnt(0) lgkmcnt(0)
	v_pk_mul_f32 v[192:193], v[4:5], v[168:169]
	v_addc_co_u32_e32 v67, vcc, 0, v71, vcc
	global_load_dwordx4 v[86:89], v[66:67], off offset:3072 nt
	v_add_co_u32_e32 v66, vcc, s23, v70
	s_mov_b32 s23, 0x122f0000
	s_nop 0
	v_addc_co_u32_e32 v67, vcc, 0, v71, vcc
	global_load_dwordx4 v[106:109], v[66:67], off offset:2048 nt
	v_add_co_u32_e32 v66, vcc, s23, v70
	s_mov_b32 s23, 0x122f3000
	s_nop 0
	v_addc_co_u32_e32 v67, vcc, 0, v71, vcc
	global_load_dwordx4 v[110:113], v[66:67], off offset:1024 nt
	v_add_co_u32_e32 v66, vcc, s23, v70
	s_mov_b32 s23, 0x122f5000
	s_nop 0
	v_addc_co_u32_e32 v67, vcc, 0, v71, vcc
	global_load_dwordx4 v[114:117], v[66:67], off nt
	v_add_co_u32_e32 v66, vcc, s23, v70
	s_mov_b32 s23, 0x122f8000
	s_nop 0
	v_addc_co_u32_e32 v67, vcc, 0, v71, vcc
	global_load_dwordx4 v[118:121], v[66:67], off offset:3072 nt
	v_add_co_u32_e32 v66, vcc, s23, v70
	s_mov_b32 s23, 0x122fb000
	s_nop 0
	v_addc_co_u32_e32 v67, vcc, 0, v71, vcc
	global_load_dwordx4 v[122:125], v[66:67], off offset:2048 nt
	v_add_co_u32_e32 v66, vcc, s23, v70
	v_pk_mul_f32 v[200:201], v[2:3], v[166:167]
	s_nop 0
	v_addc_co_u32_e32 v67, vcc, 0, v71, vcc
	global_load_dwordx4 v[126:129], v[66:67], off offset:1024 nt
	s_mov_b32 s23, 0x122fe000
	v_add_co_u32_e32 v66, vcc, s23, v70
	s_mov_b32 s23, 0x12300000
	s_nop 0
	v_addc_co_u32_e32 v67, vcc, 0, v71, vcc
	global_load_dwordx4 v[98:101], v[66:67], off nt
	v_add_co_u32_e32 v66, vcc, s23, v70
	s_mov_b32 s23, 0x12303000
	s_nop 0
	v_addc_co_u32_e32 v67, vcc, 0, v71, vcc
	global_load_dwordx4 v[102:105], v[66:67], off offset:3072 nt
	v_add_co_u32_e32 v66, vcc, s23, v70
	s_mov_b32 s23, 0x12306000
	s_nop 0
	v_addc_co_u32_e32 v67, vcc, 0, v71, vcc
	global_load_dwordx4 v[90:93], v[66:67], off offset:2048 nt
	v_add_co_u32_e32 v66, vcc, s23, v70
	s_mov_b32 s23, 0x12309000
	s_nop 0
	v_addc_co_u32_e32 v67, vcc, 0, v71, vcc
	global_load_dwordx4 v[94:97], v[66:67], off offset:1024 nt
	v_add_co_u32_e32 v66, vcc, s23, v70
	s_mov_b32 s23, 0x1230b000
	s_nop 0
	v_addc_co_u32_e32 v67, vcc, 0, v71, vcc
	global_load_dwordx4 v[74:77], v[66:67], off nt
	v_add_co_u32_e32 v66, vcc, s23, v70
	s_mov_b32 s23, 0x1230e000
	s_nop 0
	v_addc_co_u32_e32 v67, vcc, 0, v71, vcc
	global_load_dwordx4 v[78:81], v[66:67], off offset:3072 nt
	v_add_co_u32_e32 v66, vcc, s23, v70
	s_mov_b32 s23, 0x12311000
	s_nop 0
	v_addc_co_u32_e32 v67, vcc, 0, v71, vcc
	v_add_co_u32_e32 v70, vcc, s23, v70
	v_lshl_add_u64 v[176:177], v[160:161], 0, v[138:139]
	s_nop 0
	v_addc_co_u32_e32 v71, vcc, 0, v71, vcc
	s_mov_b32 s23, 0x62f0000
	global_load_dwordx4 v[66:69], v[66:67], off offset:2048 nt
	s_waitcnt vmcnt(0) lgkmcnt(0)
	v_lshlrev_b32_e32 v194, 16, v106
	v_and_b32_e32 v195, 0xffff0000, v106
	global_load_dwordx4 v[70:73], v[70:71], off offset:1024 nt
	v_mov_b32_e32 v156, v141
	v_mov_b32_e32 v141, v159
	v_pk_fma_f32 v[192:193], v[20:21], v[148:149], v[192:193]
	v_lshlrev_b32_e32 v198, 16, v110
	v_and_b32_e32 v199, 0xffff0000, v110
	v_lshlrev_b32_e32 v190, 16, v111
	v_and_b32_e32 v191, 0xffff0000, v111
	v_pk_mul_f32 v[186:187], v[28:29], v[152:153]
	v_pk_mul_f32 v[182:183], v[6:7], v[174:175]
	v_lshlrev_b32_e32 v196, 16, v114
	v_and_b32_e32 v197, 0xffff0000, v114
	v_pk_mul_f32 v[168:169], v[18:19], v[196:197]
	v_pk_fma_f32 v[144:145], v[12:13], v[144:145], v[186:187]
	v_pk_fma_f32 v[168:169], v[2:3], v[194:195], v[168:169]
	v_pk_mul_f32 v[174:175], v[30:31], v[154:155]
	v_lshlrev_b32_e32 v166, 16, v118
	v_and_b32_e32 v167, 0xffff0000, v118
	v_pk_mul_f32 v[188:189], v[26:27], v[166:167]
	v_lshlrev_b32_e32 v118, 16, v108
	v_pk_fma_f32 v[188:189], v[10:11], v[198:199], v[188:189]
	v_pk_mul_f32 v[180:181], v[8:9], v[178:179]
	v_lshlrev_b32_e32 v212, 16, v122
	v_and_b32_e32 v213, 0xffff0000, v122
	v_pk_fma_f32 v[168:169], v[34:35], v[212:213], v[168:169]
	v_lshlrev_b32_e32 v224, 16, v123
	v_pk_add_f32 v[168:169], v[50:51], v[168:169]
	v_and_b32_e32 v225, 0xffff0000, v123
	v_mul_f32_e32 v0, 0x3d372713, v168
	v_mul_f32_e32 v0, v168, v0
	v_fma_f32 v0, v168, v0, v168
	v_mul_f32_e32 v0, 0x3f4c422a, v0
	v_add_f32_e32 v0, v0, v0
	v_mul_f32_e32 v0, 0x3fb8aa3b, v0
	v_exp_f32_e32 v0, v0
	v_lshlrev_b32_e32 v202, 16, v126
	v_and_b32_e32 v203, 0xffff0000, v126
	v_pk_fma_f32 v[188:189], v[42:43], v[202:203], v[188:189]
	v_add_f32_e32 v0, 1.0, v0
	v_rcp_f32_e32 v184, v0
	v_mul_f32_e32 v0, 0x3d372713, v169
	v_mul_f32_e32 v0, v169, v0
	v_fma_f32 v0, v169, v0, v169
	v_mul_f32_e32 v0, 0x3f4c422a, v0
	v_add_f32_e32 v0, v0, v0
	v_mul_f32_e32 v0, 0x3fb8aa3b, v0
	v_exp_f32_e32 v0, v0
	v_pk_mul_f32 v[168:169], v[168:169], 0.5 op_sel_hi:[1,0]
	v_pk_add_f32 v[188:189], v[58:59], v[188:189]
	v_lshlrev_b32_e32 v220, 16, v127
	v_add_f32_e32 v0, 1.0, v0
	v_rcp_f32_e32 v185, v0
	v_and_b32_e32 v221, 0xffff0000, v127
	v_lshlrev_b32_e32 v122, 16, v116
	v_and_b32_e32 v123, 0xffff0000, v116
	v_pk_fma_f32 v[184:185], v[184:185], 2.0, 1.0 op_sel_hi:[1,0,0] neg_lo:[1,0,0] neg_hi:[1,0,0]
	v_lshlrev_b32_e32 v228, 16, v124
	v_pk_add_f32 v[184:185], v[184:185], 1.0 op_sel_hi:[1,0]
	v_and_b32_e32 v229, 0xffff0000, v124
	v_pk_mul_f32 v[168:169], v[168:169], v[184:185]
	v_lshlrev_b32_e32 v184, 16, v107
	v_pk_mul_f32 v[204:205], v[188:189], v[168:169]
	v_lshlrev_b32_e32 v188, 16, v115
	v_and_b32_e32 v189, 0xffff0000, v115
	v_and_b32_e32 v185, 0xffff0000, v107
	v_pk_mul_f32 v[106:107], v[20:21], v[188:189]
; DI unsigned pack2(float lo, float hi) { f32x2 v = {lo, hi}; bf2_t b = __builtin_convertvector(v, bf2_t); return __builtin_bit_cast(unsigned, b); }
; DI void unpack8(const u32x4& v, float* f) { f[0] = bflo(v.x); f[1] = bfhi(v.x); f[2] = bflo(v.y); f[3] = bfhi(v.y); f[4] = bflo(v.z); f[5] = bfhi(v.z); f[6] = bflo(v.w); f[7] = bfhi(v.w); }
; DI float gelu_tanh(float x) { const float y = 0.7978845608028654f * (x + 0.044715f * x * x * x); const float t = 1.f - 2.f * __builtin_amdgcn_rcpf(1.f + __expf(2.f * y)); return 0.5f * x * (1.f + t); }
; DI void ffn_act_phase(const Params& P, int l) {
;     ...
;     for (int rb = 0; rb < 4; ++rb) {
;       u32x4 G[8], U[8];
; #pragma unroll
;       for (int i = 0; i < 8; ++i) { const size_t ro = (size_t)(r0 + rb * 8 + i) * DFF2 + ch; G[i] = __builtin_nontemporal_load((const u32x4*)(u + ro)); U[i] = __builtin_nontemporal_load((const u32x4*)(u + ro + DFF)); }
; #pragma unroll
;       for (int i = 0; i < 8; ++i) {
;         float g0[8], u0[8]; unpack8(G[i], g0); unpack8(U[i], u0);
;         float o[8];
; #pragma unroll
;         for (int e = 0; e < 8; ++e) { const float yg = wg[0][e] * g2[e] + wg[1][e] * g1[e] + wg[2][e] * g0[e] + bg[e]; const float yu = wu[0][e] * u2[e] + wu[1][e] * u1[e] + wu[2][e] * u0[e] + bu[e];
;           o[e] = gelu_tanh(yg) * yu; g2[e] = g1[e]; g1[e] = g0[e]; u2[e] = u1[e]; u1[e] = u0[e]; }
;         u32x4 pk = {pack2(o[0], o[1]), pack2(o[2], o[3]), pack2(o[4], o[5]), pack2(o[6], o[7])};
;         *(u32x4*)(act + (size_t)(r0 + rb * 8 + i) * DFF + ch) = pk;
;       }
	v_lshlrev_b32_e32 v168, 16, v119
	v_pk_fma_f32 v[106:107], v[4:5], v[184:185], v[106:107]
	v_and_b32_e32 v169, 0xffff0000, v119
	v_pk_fma_f32 v[106:107], v[36:37], v[224:225], v[106:107]
	v_pk_mul_f32 v[114:115], v[28:29], v[168:169]
	v_pk_add_f32 v[106:107], v[52:53], v[106:107]
	v_pk_fma_f32 v[114:115], v[12:13], v[190:191], v[114:115]
	v_mul_f32_e32 v0, 0x3d372713, v106
	v_mul_f32_e32 v0, v106, v0
	v_fma_f32 v0, v106, v0, v106
	v_mul_f32_e32 v0, 0x3f4c422a, v0
	v_add_f32_e32 v0, v0, v0
	v_mul_f32_e32 v0, 0x3fb8aa3b, v0
	v_exp_f32_e32 v0, v0
	v_pk_fma_f32 v[114:115], v[44:45], v[220:221], v[114:115]
	v_and_b32_e32 v119, 0xffff0000, v108
	v_pk_add_f32 v[114:115], v[60:61], v[114:115]
	v_add_f32_e32 v0, 1.0, v0
	v_rcp_f32_e32 v110, v0
	v_mul_f32_e32 v0, 0x3d372713, v107
	v_mul_f32_e32 v0, v107, v0
	v_fma_f32 v0, v107, v0, v107
	v_mul_f32_e32 v0, 0x3f4c422a, v0
	v_add_f32_e32 v0, v0, v0
	v_mul_f32_e32 v0, 0x3fb8aa3b, v0
	v_exp_f32_e32 v0, v0
	v_pk_mul_f32 v[106:107], v[106:107], 0.5 op_sel_hi:[1,0]
	v_lshlrev_b32_e32 v108, 16, v109
	v_and_b32_e32 v109, 0xffff0000, v109
	v_add_f32_e32 v0, 1.0, v0
	v_rcp_f32_e32 v111, v0
	v_lshlrev_b32_e32 v230, 16, v125
	v_and_b32_e32 v231, 0xffff0000, v125
	v_lshlrev_b32_e32 v126, 16, v112
	v_pk_fma_f32 v[110:111], v[110:111], 2.0, 1.0 op_sel_hi:[1,0,0] neg_lo:[1,0,0] neg_hi:[1,0,0]
	v_and_b32_e32 v127, 0xffff0000, v112
	v_pk_add_f32 v[110:111], v[110:111], 1.0 op_sel_hi:[1,0]
	v_lshlrev_b32_e32 v222, 16, v128
	v_pk_mul_f32 v[106:107], v[106:107], v[110:111]
	v_and_b32_e32 v223, 0xffff0000, v128
	v_pk_mul_f32 v[210:211], v[114:115], v[106:107]
	v_pk_mul_f32 v[106:107], v[22:23], v[122:123]
	v_lshlrev_b32_e32 v114, 16, v120
	v_pk_fma_f32 v[106:107], v[6:7], v[118:119], v[106:107]
	v_and_b32_e32 v115, 0xffff0000, v120
	v_pk_fma_f32 v[106:107], v[38:39], v[228:229], v[106:107]
	v_pk_mul_f32 v[214:215], v[30:31], v[114:115]
	v_pk_add_f32 v[106:107], v[54:55], v[106:107]
	v_pk_fma_f32 v[214:215], v[14:15], v[126:127], v[214:215]
	v_mul_f32_e32 v0, 0x3d372713, v106
	v_mul_f32_e32 v0, v106, v0
	v_fma_f32 v0, v106, v0, v106
	v_mul_f32_e32 v0, 0x3f4c422a, v0
	v_add_f32_e32 v0, v0, v0
	v_mul_f32_e32 v0, 0x3fb8aa3b, v0
	v_exp_f32_e32 v0, v0
	v_pk_fma_f32 v[214:215], v[46:47], v[222:223], v[214:215]
	v_lshlrev_b32_e32 v112, 16, v113
	v_pk_add_f32 v[214:215], v[62:63], v[214:215]
	v_add_f32_e32 v0, 1.0, v0
	v_rcp_f32_e32 v110, v0
	v_mul_f32_e32 v0, 0x3d372713, v107
	v_mul_f32_e32 v0, v107, v0
	v_fma_f32 v0, v107, v0, v107
	v_mul_f32_e32 v0, 0x3f4c422a, v0
	v_add_f32_e32 v0, v0, v0
	v_mul_f32_e32 v0, 0x3fb8aa3b, v0
	v_exp_f32_e32 v0, v0
	v_pk_mul_f32 v[106:107], v[106:107], 0.5 op_sel_hi:[1,0]
	v_and_b32_e32 v113, 0xffff0000, v113
	v_lshlrev_b32_e32 v226, 16, v129
	v_add_f32_e32 v0, 1.0, v0
	v_rcp_f32_e32 v111, v0
	v_and_b32_e32 v227, 0xffff0000, v129
	v_lshlrev_b32_e32 v128, 16, v99
	v_and_b32_e32 v129, 0xffff0000, v99
	v_pk_fma_f32 v[110:111], v[110:111], 2.0, 1.0 op_sel_hi:[1,0,0] neg_lo:[1,0,0] neg_hi:[1,0,0]
	v_pk_mul_f32 v[218:219], v[30:31], v[222:223]
	v_pk_add_f32 v[110:111], v[110:111], 1.0 op_sel_hi:[1,0]
	v_pk_fma_f32 v[218:219], v[14:15], v[114:115], v[218:219]
	v_pk_mul_f32 v[106:107], v[106:107], v[110:111]
	v_lshlrev_b32_e32 v110, 16, v117
	v_and_b32_e32 v111, 0xffff0000, v117
	v_pk_mul_f32 v[116:117], v[24:25], v[110:111]
	v_pk_mul_f32 v[216:217], v[214:215], v[106:107]
	v_pk_fma_f32 v[116:117], v[8:9], v[108:109], v[116:117]
	v_lshlrev_b32_e32 v106, 16, v121
	v_pk_fma_f32 v[116:117], v[40:41], v[230:231], v[116:117]
	v_and_b32_e32 v107, 0xffff0000, v121
	v_pk_add_f32 v[116:117], v[56:57], v[116:117]
	v_pk_mul_f32 v[124:125], v[32:33], v[106:107]
	v_mul_f32_e32 v0, 0x3d372713, v116
	v_mul_f32_e32 v0, v116, v0
	v_fma_f32 v0, v116, v0, v116
	v_mul_f32_e32 v0, 0x3f4c422a, v0
	v_add_f32_e32 v0, v0, v0
	v_mul_f32_e32 v0, 0x3fb8aa3b, v0
	v_exp_f32_e32 v0, v0
	v_pk_fma_f32 v[124:125], v[16:17], v[112:113], v[124:125]
	v_cvt_pk_bf16_f32 v216, v216, v217
	v_pk_fma_f32 v[124:125], v[48:49], v[226:227], v[124:125]
	v_add_f32_e32 v0, 1.0, v0
	v_rcp_f32_e32 v120, v0
	v_mul_f32_e32 v0, 0x3d372713, v117
	v_mul_f32_e32 v0, v117, v0
	v_fma_f32 v0, v117, v0, v117
	v_mul_f32_e32 v0, 0x3f4c422a, v0
	v_add_f32_e32 v0, v0, v0
	v_mul_f32_e32 v0, 0x3fb8aa3b, v0
	v_exp_f32_e32 v0, v0
	v_pk_mul_f32 v[116:117], v[116:117], 0.5 op_sel_hi:[1,0]
	v_pk_add_f32 v[124:125], v[64:65], v[124:125]
	v_cvt_pk_bf16_f32 v214, v204, v205
	v_add_f32_e32 v0, 1.0, v0
	v_rcp_f32_e32 v121, v0
	v_cvt_pk_bf16_f32 v215, v210, v211
	v_lshlrev_b32_e32 v210, 16, v98
	v_and_b32_e32 v211, 0xffff0000, v98
	v_pk_fma_f32 v[120:121], v[120:121], 2.0, 1.0 op_sel_hi:[1,0,0] neg_lo:[1,0,0] neg_hi:[1,0,0]
	v_pk_mul_f32 v[98:99], v[20:21], v[224:225]
	v_pk_add_f32 v[120:121], v[120:121], 1.0 op_sel_hi:[1,0]
	v_pk_fma_f32 v[98:99], v[4:5], v[188:189], v[98:99]
	v_pk_mul_f32 v[116:117], v[116:117], v[120:121]
	v_pk_fma_f32 v[98:99], v[36:37], v[128:129], v[98:99]
	v_pk_mul_f32 v[116:117], v[124:125], v[116:117]
	v_pk_add_f32 v[98:99], v[52:53], v[98:99]
	v_cvt_pk_bf16_f32 v217, v116, v117
	v_add_co_u32_e32 v116, vcc, s23, v176
	v_lshlrev_b32_e32 v204, 16, v102
	s_nop 0
	v_addc_co_u32_e32 v117, vcc, 0, v177, vcc
	global_store_dwordx4 v[116:117], v[214:217], off offset:1024
	v_pk_mul_f32 v[116:117], v[18:19], v[212:213]
	v_and_b32_e32 v205, 0xffff0000, v102
	v_pk_fma_f32 v[116:117], v[2:3], v[196:197], v[116:117]
	v_pk_mul_f32 v[124:125], v[26:27], v[202:203]
	v_pk_fma_f32 v[116:117], v[34:35], v[210:211], v[116:117]
	v_pk_fma_f32 v[124:125], v[10:11], v[166:167], v[124:125]
	v_pk_add_f32 v[116:117], v[50:51], v[116:117]
	v_pk_fma_f32 v[124:125], v[42:43], v[204:205], v[124:125]
; DI unsigned pack2(float lo, float hi) { f32x2 v = {lo, hi}; bf2_t b = __builtin_convertvector(v, bf2_t); return __builtin_bit_cast(unsigned, b); }
; DI void unpack8(const u32x4& v, float* f) { f[0] = bflo(v.x); f[1] = bfhi(v.x); f[2] = bflo(v.y); f[3] = bfhi(v.y); f[4] = bflo(v.z); f[5] = bfhi(v.z); f[6] = bflo(v.w); f[7] = bfhi(v.w); }
; DI float gelu_tanh(float x) { const float y = 0.7978845608028654f * (x + 0.044715f * x * x * x); const float t = 1.f - 2.f * __builtin_amdgcn_rcpf(1.f + __expf(2.f * y)); return 0.5f * x * (1.f + t); }
; DI void ffn_act_phase(const Params& P, int l) {
;     ...
;     for (int rb = 0; rb < 4; ++rb) {
;       u32x4 G[8], U[8];
; #pragma unroll
;       for (int i = 0; i < 8; ++i) { const size_t ro = (size_t)(r0 + rb * 8 + i) * DFF2 + ch; G[i] = __builtin_nontemporal_load((const u32x4*)(u + ro)); U[i] = __builtin_nontemporal_load((const u32x4*)(u + ro + DFF)); }
; #pragma unroll
;       for (int i = 0; i < 8; ++i) {
;         float g0[8], u0[8]; unpack8(G[i], g0); unpack8(U[i], u0);
;         float o[8];
; #pragma unroll
;         for (int e = 0; e < 8; ++e) { const float yg = wg[0][e] * g2[e] + wg[1][e] * g1[e] + wg[2][e] * g0[e] + bg[e]; const float yu = wu[0][e] * u2[e] + wu[1][e] * u1[e] + wu[2][e] * u0[e] + bu[e];
;           o[e] = gelu_tanh(yg) * yu; g2[e] = g1[e]; g1[e] = g0[e]; u2[e] = u1[e]; u1[e] = u0[e]; }
;         u32x4 pk = {pack2(o[0], o[1]), pack2(o[2], o[3]), pack2(o[4], o[5]), pack2(o[6], o[7])};
;         *(u32x4*)(act + (size_t)(r0 + rb * 8 + i) * DFF + ch) = pk;
;       }
	v_mul_f32_e32 v0, 0x3d372713, v116
	v_mul_f32_e32 v0, v116, v0
	v_fma_f32 v0, v116, v0, v116
	v_mul_f32_e32 v0, 0x3f4c422a, v0
	v_add_f32_e32 v0, v0, v0
	v_mul_f32_e32 v0, 0x3fb8aa3b, v0
	v_exp_f32_e32 v0, v0
	v_pk_add_f32 v[124:125], v[58:59], v[124:125]
	v_pk_mul_f32 v[232:233], v[32:33], v[226:227]
	s_mov_b32 s23, 0x62f3000
	v_add_f32_e32 v0, 1.0, v0
	v_rcp_f32_e32 v120, v0
	v_mul_f32_e32 v0, 0x3d372713, v117
	v_mul_f32_e32 v0, v117, v0
	v_fma_f32 v0, v117, v0, v117
	v_mul_f32_e32 v0, 0x3f4c422a, v0
	v_add_f32_e32 v0, v0, v0
	v_mul_f32_e32 v0, 0x3fb8aa3b, v0
	v_exp_f32_e32 v0, v0
	v_pk_mul_f32 v[116:117], v[116:117], 0.5 op_sel_hi:[1,0]
	v_pk_fma_f32 v[232:233], v[16:17], v[106:107], v[232:233]
	v_pk_mul_f32 v[178:179], v[32:33], v[172:173]
	v_add_f32_e32 v0, 1.0, v0
	v_rcp_f32_e32 v121, v0
	v_mul_f32_e32 v0, 0x3d372713, v98
	v_mul_f32_e32 v0, v98, v0
	v_fma_f32 v0, v98, v0, v98
	v_mul_f32_e32 v0, 0x3f4c422a, v0
	v_add_f32_e32 v0, v0, v0
	v_mul_f32_e32 v0, 0x3fb8aa3b, v0
	v_exp_f32_e32 v0, v0
	v_pk_fma_f32 v[120:121], v[120:121], 2.0, 1.0 op_sel_hi:[1,0,0] neg_lo:[1,0,0] neg_hi:[1,0,0]
	s_mov_b64 s[24:25], 0x16000
	v_pk_add_f32 v[120:121], v[120:121], 1.0 op_sel_hi:[1,0]
	v_add_f32_e32 v0, 1.0, v0
	v_rcp_f32_e32 v102, v0
	v_mul_f32_e32 v0, 0x3d372713, v99
	v_mul_f32_e32 v0, v99, v0
	v_fma_f32 v0, v99, v0, v99
	v_mul_f32_e32 v0, 0x3f4c422a, v0
	v_add_f32_e32 v0, v0, v0
	v_mul_f32_e32 v0, 0x3fb8aa3b, v0
	v_exp_f32_e32 v0, v0
	v_pk_mul_f32 v[116:117], v[116:117], v[120:121]
	v_pk_mul_f32 v[98:99], v[98:99], 0.5 op_sel_hi:[1,0]
	v_pk_mul_f32 v[214:215], v[124:125], v[116:117]
	v_add_f32_e32 v0, 1.0, v0
	v_lshlrev_b32_e32 v124, 16, v103
	v_and_b32_e32 v125, 0xffff0000, v103
	v_rcp_f32_e32 v103, v0
	v_lshlrev_b32_e32 v120, 16, v100
	v_and_b32_e32 v121, 0xffff0000, v100
	v_pk_mul_f32 v[116:117], v[28:29], v[220:221]
	v_pk_fma_f32 v[102:103], v[102:103], 2.0, 1.0 op_sel_hi:[1,0,0] neg_lo:[1,0,0] neg_hi:[1,0,0]
	v_pk_fma_f32 v[116:117], v[12:13], v[168:169], v[116:117]
	v_pk_add_f32 v[102:103], v[102:103], 1.0 op_sel_hi:[1,0]
	v_pk_fma_f32 v[116:117], v[44:45], v[124:125], v[116:117]
	v_pk_mul_f32 v[98:99], v[98:99], v[102:103]
	v_pk_mul_f32 v[102:103], v[22:23], v[228:229]
	v_pk_add_f32 v[116:117], v[60:61], v[116:117]
	v_pk_fma_f32 v[102:103], v[6:7], v[122:123], v[102:103]
	v_pk_mul_f32 v[98:99], v[116:117], v[98:99]
	v_pk_fma_f32 v[102:103], v[38:39], v[120:121], v[102:103]
	v_lshlrev_b32_e32 v116, 16, v104
	v_pk_add_f32 v[102:103], v[54:55], v[102:103]
	v_and_b32_e32 v117, 0xffff0000, v104
	v_mul_f32_e32 v0, 0x3d372713, v102
	v_mul_f32_e32 v0, v102, v0
	v_fma_f32 v0, v102, v0, v102
	v_mul_f32_e32 v0, 0x3f4c422a, v0
	v_add_f32_e32 v0, v0, v0
	v_mul_f32_e32 v0, 0x3fb8aa3b, v0
	v_exp_f32_e32 v0, v0
	v_pk_fma_f32 v[218:219], v[46:47], v[116:117], v[218:219]
	v_lshlrev_b32_e32 v100, 16, v105
	v_pk_add_f32 v[218:219], v[62:63], v[218:219]
	v_add_f32_e32 v0, 1.0, v0
	v_rcp_f32_e32 v216, v0
	v_mul_f32_e32 v0, 0x3d372713, v103
	v_mul_f32_e32 v0, v103, v0
	v_fma_f32 v0, v103, v0, v103
	v_mul_f32_e32 v0, 0x3f4c422a, v0
	v_add_f32_e32 v0, v0, v0
	v_mul_f32_e32 v0, 0x3fb8aa3b, v0
	v_exp_f32_e32 v0, v0
	v_pk_mul_f32 v[102:103], v[102:103], 0.5 op_sel_hi:[1,0]
	v_cvt_pk_bf16_f32 v214, v214, v215
	v_cvt_pk_bf16_f32 v215, v98, v99
	v_add_f32_e32 v0, 1.0, v0
	v_rcp_f32_e32 v217, v0
	v_add_co_u32_e32 v98, vcc, s23, v176
	s_mov_b32 s23, 0x62f5000
	v_pk_fma_f32 v[216:217], v[216:217], 2.0, 1.0 op_sel_hi:[1,0,0] neg_lo:[1,0,0] neg_hi:[1,0,0]
	v_addc_co_u32_e32 v99, vcc, 0, v177, vcc
	v_pk_add_f32 v[216:217], v[216:217], 1.0 op_sel_hi:[1,0]
	s_add_i32 s22, s22, -1
	v_pk_mul_f32 v[102:103], v[102:103], v[216:217]
	v_lshl_add_u64 v[160:161], v[160:161], 0, s[24:25]
	v_pk_mul_f32 v[216:217], v[218:219], v[102:103]
	v_lshlrev_b32_e32 v102, 16, v101
	v_and_b32_e32 v103, 0xffff0000, v101
	v_and_b32_e32 v101, 0xffff0000, v105
	v_pk_mul_f32 v[104:105], v[24:25], v[230:231]
	v_pk_fma_f32 v[232:233], v[48:49], v[100:101], v[232:233]
	v_pk_fma_f32 v[104:105], v[8:9], v[110:111], v[104:105]
	v_pk_add_f32 v[232:233], v[64:65], v[232:233]
	v_pk_fma_f32 v[104:105], v[40:41], v[102:103], v[104:105]
	v_cvt_pk_bf16_f32 v216, v216, v217
	v_pk_add_f32 v[104:105], v[56:57], v[104:105]
	s_mov_b64 s[24:25], 0x2c000
	v_mul_f32_e32 v0, 0x3d372713, v104
	v_mul_f32_e32 v0, v104, v0
	v_fma_f32 v0, v104, v0, v104
	v_mul_f32_e32 v0, 0x3f4c422a, v0
	v_add_f32_e32 v0, v0, v0
	v_mul_f32_e32 v0, 0x3fb8aa3b, v0
	v_exp_f32_e32 v0, v0
	v_lshl_add_u64 v[162:163], v[162:163], 0, s[24:25]
	s_cmp_eq_u32 s22, 0
	v_add_f32_e32 v0, 1.0, v0
	v_rcp_f32_e32 v218, v0
	v_mul_f32_e32 v0, 0x3d372713, v105
	v_mul_f32_e32 v0, v105, v0
	v_fma_f32 v0, v105, v0, v105
	v_mul_f32_e32 v0, 0x3f4c422a, v0
	v_add_f32_e32 v0, v0, v0
	v_mul_f32_e32 v0, 0x3fb8aa3b, v0
	v_exp_f32_e32 v0, v0
	v_pk_mul_f32 v[104:105], v[104:105], 0.5 op_sel_hi:[1,0]
	v_add_f32_e32 v0, 1.0, v0
	v_rcp_f32_e32 v219, v0
	s_nop 0
	v_pk_fma_f32 v[218:219], v[218:219], 2.0, 1.0 op_sel_hi:[1,0,0] neg_lo:[1,0,0] neg_hi:[1,0,0]
	s_nop 0
	v_pk_add_f32 v[218:219], v[218:219], 1.0 op_sel_hi:[1,0]
	s_nop 0
	v_pk_mul_f32 v[104:105], v[104:105], v[218:219]
	v_lshlrev_b32_e32 v218, 16, v90
	v_pk_mul_f32 v[104:105], v[232:233], v[104:105]
	v_and_b32_e32 v219, 0xffff0000, v90
	v_cvt_pk_bf16_f32 v217, v104, v105
	global_store_dwordx4 v[98:99], v[214:217], off
	v_pk_mul_f32 v[98:99], v[18:19], v[210:211]
	s_nop 0
	v_pk_fma_f32 v[98:99], v[2:3], v[212:213], v[98:99]
	v_lshlrev_b32_e32 v214, 16, v91
	v_pk_fma_f32 v[98:99], v[34:35], v[218:219], v[98:99]
	v_and_b32_e32 v215, 0xffff0000, v91
	v_pk_add_f32 v[98:99], v[50:51], v[98:99]
	v_pk_mul_f32 v[90:91], v[20:21], v[128:129]
; DI unsigned pack2(float lo, float hi) { f32x2 v = {lo, hi}; bf2_t b = __builtin_convertvector(v, bf2_t); return __builtin_bit_cast(unsigned, b); }
; DI void unpack8(const u32x4& v, float* f) { f[0] = bflo(v.x); f[1] = bfhi(v.x); f[2] = bflo(v.y); f[3] = bfhi(v.y); f[4] = bflo(v.z); f[5] = bfhi(v.z); f[6] = bflo(v.w); f[7] = bfhi(v.w); }
; DI float gelu_tanh(float x) { const float y = 0.7978845608028654f * (x + 0.044715f * x * x * x); const float t = 1.f - 2.f * __builtin_amdgcn_rcpf(1.f + __expf(2.f * y)); return 0.5f * x * (1.f + t); }
; DI void ffn_act_phase(const Params& P, int l) {
;     ...
;     for (int rb = 0; rb < 4; ++rb) {
;       u32x4 G[8], U[8];
; #pragma unroll
;       for (int i = 0; i < 8; ++i) { const size_t ro = (size_t)(r0 + rb * 8 + i) * DFF2 + ch; G[i] = __builtin_nontemporal_load((const u32x4*)(u + ro)); U[i] = __builtin_nontemporal_load((const u32x4*)(u + ro + DFF)); }
; #pragma unroll
;       for (int i = 0; i < 8; ++i) {
;         float g0[8], u0[8]; unpack8(G[i], g0); unpack8(U[i], u0);
;         float o[8];
; #pragma unroll
;         for (int e = 0; e < 8; ++e) { const float yg = wg[0][e] * g2[e] + wg[1][e] * g1[e] + wg[2][e] * g0[e] + bg[e]; const float yu = wu[0][e] * u2[e] + wu[1][e] * u1[e] + wu[2][e] * u0[e] + bu[e];
;           o[e] = gelu_tanh(yg) * yu; g2[e] = g1[e]; g1[e] = g0[e]; u2[e] = u1[e]; u1[e] = u0[e]; }
;         u32x4 pk = {pack2(o[0], o[1]), pack2(o[2], o[3]), pack2(o[4], o[5]), pack2(o[6], o[7])};
;         *(u32x4*)(act + (size_t)(r0 + rb * 8 + i) * DFF + ch) = pk;
;       }
	v_mul_f32_e32 v0, 0x3d372713, v98
	v_mul_f32_e32 v0, v98, v0
	v_fma_f32 v0, v98, v0, v98
	v_mul_f32_e32 v0, 0x3f4c422a, v0
	v_add_f32_e32 v0, v0, v0
	v_mul_f32_e32 v0, 0x3fb8aa3b, v0
	v_exp_f32_e32 v0, v0
	v_pk_fma_f32 v[90:91], v[4:5], v[224:225], v[90:91]
	v_lshlrev_b32_e32 v216, 16, v94
	v_pk_fma_f32 v[90:91], v[36:37], v[214:215], v[90:91]
	v_add_f32_e32 v0, 1.0, v0
	v_rcp_f32_e32 v104, v0
	v_mul_f32_e32 v0, 0x3d372713, v99
	v_mul_f32_e32 v0, v99, v0
	v_fma_f32 v0, v99, v0, v99
	v_mul_f32_e32 v0, 0x3f4c422a, v0
	v_add_f32_e32 v0, v0, v0
	v_mul_f32_e32 v0, 0x3fb8aa3b, v0
	v_exp_f32_e32 v0, v0
	v_pk_add_f32 v[90:91], v[52:53], v[90:91]
	v_and_b32_e32 v217, 0xffff0000, v94
	v_pk_mul_f32 v[212:213], v[26:27], v[204:205]
	v_add_f32_e32 v0, 1.0, v0
	v_rcp_f32_e32 v105, v0
	v_mul_f32_e32 v0, 0x3d372713, v90
	v_mul_f32_e32 v0, v90, v0
	v_fma_f32 v0, v90, v0, v90
	v_mul_f32_e32 v0, 0x3f4c422a, v0
	v_add_f32_e32 v0, v0, v0
	v_mul_f32_e32 v0, 0x3fb8aa3b, v0
	v_exp_f32_e32 v0, v0
	v_pk_fma_f32 v[202:203], v[10:11], v[202:203], v[212:213]
	v_pk_fma_f32 v[104:105], v[104:105], 2.0, 1.0 op_sel_hi:[1,0,0] neg_lo:[1,0,0] neg_hi:[1,0,0]
	v_lshlrev_b32_e32 v212, 16, v95
	v_add_f32_e32 v0, 1.0, v0
	v_rcp_f32_e32 v94, v0
	v_mul_f32_e32 v0, 0x3d372713, v91
	v_mul_f32_e32 v0, v91, v0
	v_fma_f32 v0, v91, v0, v91
	v_mul_f32_e32 v0, 0x3f4c422a, v0
	v_add_f32_e32 v0, v0, v0
	v_mul_f32_e32 v0, 0x3fb8aa3b, v0
	v_exp_f32_e32 v0, v0
	v_and_b32_e32 v213, 0xffff0000, v95
	v_pk_fma_f32 v[202:203], v[42:43], v[216:217], v[202:203]
	v_pk_mul_f32 v[98:99], v[98:99], 0.5 op_sel_hi:[1,0]
	v_add_f32_e32 v0, 1.0, v0
	v_rcp_f32_e32 v95, v0
	v_pk_add_f32 v[104:105], v[104:105], 1.0 op_sel_hi:[1,0]
	v_pk_add_f32 v[202:203], v[58:59], v[202:203]
	v_pk_mul_f32 v[98:99], v[98:99], v[104:105]
	v_pk_fma_f32 v[94:95], v[94:95], 2.0, 1.0 op_sel_hi:[1,0,0] neg_lo:[1,0,0] neg_hi:[1,0,0]
	v_pk_mul_f32 v[232:233], v[202:203], v[98:99]
	v_pk_mul_f32 v[98:99], v[28:29], v[124:125]
	v_pk_mul_f32 v[90:91], v[90:91], 0.5 op_sel_hi:[1,0]
	v_pk_fma_f32 v[98:99], v[12:13], v[220:221], v[98:99]
	v_pk_add_f32 v[94:95], v[94:95], 1.0 op_sel_hi:[1,0]
	v_pk_fma_f32 v[98:99], v[44:45], v[212:213], v[98:99]
	v_pk_mul_f32 v[90:91], v[90:91], v[94:95]
	v_pk_add_f32 v[98:99], v[60:61], v[98:99]
	v_lshlrev_b32_e32 v202, 16, v92
	v_pk_mul_f32 v[220:221], v[98:99], v[90:91]
	v_pk_mul_f32 v[90:91], v[22:23], v[120:121]
	v_and_b32_e32 v203, 0xffff0000, v92
	v_pk_fma_f32 v[90:91], v[6:7], v[228:229], v[90:91]
	v_pk_mul_f32 v[98:99], v[30:31], v[116:117]
	v_pk_fma_f32 v[90:91], v[38:39], v[202:203], v[90:91]
	v_lshlrev_b32_e32 v104, 16, v96
	v_pk_add_f32 v[90:91], v[54:55], v[90:91]
	v_and_b32_e32 v105, 0xffff0000, v96
	v_mul_f32_e32 v0, 0x3d372713, v90
	v_mul_f32_e32 v0, v90, v0
	v_fma_f32 v0, v90, v0, v90
	v_mul_f32_e32 v0, 0x3f4c422a, v0
	v_add_f32_e32 v0, v0, v0
	v_mul_f32_e32 v0, 0x3fb8aa3b, v0
	v_exp_f32_e32 v0, v0
	v_pk_fma_f32 v[98:99], v[14:15], v[222:223], v[98:99]
	v_add_f32_e32 v0, 1.0, v0
	v_rcp_f32_e32 v94, v0
	v_mul_f32_e32 v0, 0x3d372713, v91
	v_mul_f32_e32 v0, v91, v0
	v_fma_f32 v0, v91, v0, v91
	v_mul_f32_e32 v0, 0x3f4c422a, v0
	v_add_f32_e32 v0, v0, v0
	v_mul_f32_e32 v0, 0x3fb8aa3b, v0
	v_exp_f32_e32 v0, v0
	v_pk_fma_f32 v[98:99], v[46:47], v[104:105], v[98:99]
	v_pk_mul_f32 v[90:91], v[90:91], 0.5 op_sel_hi:[1,0]
	v_pk_add_f32 v[98:99], v[62:63], v[98:99]
	v_add_f32_e32 v0, 1.0, v0
	v_rcp_f32_e32 v95, v0
	s_nop 0
	v_pk_fma_f32 v[94:95], v[94:95], 2.0, 1.0 op_sel_hi:[1,0,0] neg_lo:[1,0,0] neg_hi:[1,0,0]
	s_nop 0
	v_pk_add_f32 v[94:95], v[94:95], 1.0 op_sel_hi:[1,0]
	s_nop 0
	v_pk_mul_f32 v[90:91], v[90:91], v[94:95]
	v_lshlrev_b32_e32 v94, 16, v97
	v_pk_mul_f32 v[222:223], v[98:99], v[90:91]
	v_pk_mul_f32 v[90:91], v[24:25], v[102:103]
	v_lshlrev_b32_e32 v98, 16, v93
	v_and_b32_e32 v99, 0xffff0000, v93
	v_pk_fma_f32 v[90:91], v[8:9], v[230:231], v[90:91]
	v_and_b32_e32 v95, 0xffff0000, v97
	v_pk_fma_f32 v[90:91], v[40:41], v[98:99], v[90:91]
	v_pk_mul_f32 v[96:97], v[32:33], v[100:101]
	v_pk_add_f32 v[90:91], v[56:57], v[90:91]
	v_pk_fma_f32 v[96:97], v[16:17], v[226:227], v[96:97]
	v_mul_f32_e32 v0, 0x3d372713, v90
	v_mul_f32_e32 v0, v90, v0
	v_fma_f32 v0, v90, v0, v90
	v_mul_f32_e32 v0, 0x3f4c422a, v0
	v_add_f32_e32 v0, v0, v0
	v_mul_f32_e32 v0, 0x3fb8aa3b, v0
	v_exp_f32_e32 v0, v0
	v_pk_fma_f32 v[96:97], v[48:49], v[94:95], v[96:97]
	v_add_f32_e32 v0, 1.0, v0
	v_rcp_f32_e32 v92, v0
	v_mul_f32_e32 v0, 0x3d372713, v91
	v_mul_f32_e32 v0, v91, v0
	v_fma_f32 v0, v91, v0, v91
	v_mul_f32_e32 v0, 0x3f4c422a, v0
	v_add_f32_e32 v0, v0, v0
	v_mul_f32_e32 v0, 0x3fb8aa3b, v0
	v_exp_f32_e32 v0, v0
	v_pk_mul_f32 v[90:91], v[90:91], 0.5 op_sel_hi:[1,0]
	v_pk_add_f32 v[96:97], v[64:65], v[96:97]
	v_add_f32_e32 v0, 1.0, v0
	v_rcp_f32_e32 v93, v0
	s_nop 0
	v_pk_fma_f32 v[92:93], v[92:93], 2.0, 1.0 op_sel_hi:[1,0,0] neg_lo:[1,0,0] neg_hi:[1,0,0]
	s_nop 0
	v_pk_add_f32 v[92:93], v[92:93], 1.0 op_sel_hi:[1,0]
	s_nop 0
	v_pk_mul_f32 v[90:91], v[90:91], v[92:93]
	v_cvt_pk_bf16_f32 v92, v222, v223
	v_pk_mul_f32 v[96:97], v[96:97], v[90:91]
	v_cvt_pk_bf16_f32 v90, v232, v233
	v_cvt_pk_bf16_f32 v93, v96, v97
	v_add_co_u32_e32 v96, vcc, s23, v176
	v_cvt_pk_bf16_f32 v91, v220, v221
	s_nop 0
	v_addc_co_u32_e32 v97, vcc, 0, v177, vcc
	global_store_dwordx4 v[96:97], v[90:93], off offset:3072
	v_lshlrev_b32_e32 v96, 16, v82
	v_and_b32_e32 v97, 0xffff0000, v82
	v_pk_fma_f32 v[90:91], v[18:19], v[156:157], v[200:201]
	v_pk_mul_f32 v[200:201], v[26:27], v[140:141]
	v_pk_fma_f32 v[90:91], v[34:35], v[96:97], v[90:91]
	v_lshlrev_b32_e32 v92, 16, v86
	v_pk_add_f32 v[90:91], v[50:51], v[90:91]
	v_and_b32_e32 v93, 0xffff0000, v86
; DI unsigned pack2(float lo, float hi) { f32x2 v = {lo, hi}; bf2_t b = __builtin_convertvector(v, bf2_t); return __builtin_bit_cast(unsigned, b); }
; DI void unpack8(const u32x4& v, float* f) { f[0] = bflo(v.x); f[1] = bfhi(v.x); f[2] = bflo(v.y); f[3] = bfhi(v.y); f[4] = bflo(v.z); f[5] = bfhi(v.z); f[6] = bflo(v.w); f[7] = bfhi(v.w); }
; DI float gelu_tanh(float x) { const float y = 0.7978845608028654f * (x + 0.044715f * x * x * x); const float t = 1.f - 2.f * __builtin_amdgcn_rcpf(1.f + __expf(2.f * y)); return 0.5f * x * (1.f + t); }
; DI void ffn_act_phase(const Params& P, int l) {
;     ...
;     for (int rb = 0; rb < 4; ++rb) {
;       u32x4 G[8], U[8];
; #pragma unroll
;       for (int i = 0; i < 8; ++i) { const size_t ro = (size_t)(r0 + rb * 8 + i) * DFF2 + ch; G[i] = __builtin_nontemporal_load((const u32x4*)(u + ro)); U[i] = __builtin_nontemporal_load((const u32x4*)(u + ro + DFF)); }
; #pragma unroll
;       for (int i = 0; i < 8; ++i) {
;         float g0[8], u0[8]; unpack8(G[i], g0); unpack8(U[i], u0);
;         float o[8];
; #pragma unroll
;         for (int e = 0; e < 8; ++e) { const float yg = wg[0][e] * g2[e] + wg[1][e] * g1[e] + wg[2][e] * g0[e] + bg[e]; const float yu = wu[0][e] * u2[e] + wu[1][e] * u1[e] + wu[2][e] * u0[e] + bu[e];
;           o[e] = gelu_tanh(yg) * yu; g2[e] = g1[e]; g1[e] = g0[e]; u2[e] = u1[e]; u1[e] = u0[e]; }
;         u32x4 pk = {pack2(o[0], o[1]), pack2(o[2], o[3]), pack2(o[4], o[5]), pack2(o[6], o[7])};
;         *(u32x4*)(act + (size_t)(r0 + rb * 8 + i) * DFF + ch) = pk;
;       }
	v_mul_f32_e32 v0, 0x3d372713, v90
	v_mul_f32_e32 v0, v90, v0
	v_fma_f32 v0, v90, v0, v90
	v_mul_f32_e32 v0, 0x3f4c422a, v0
	v_add_f32_e32 v0, v0, v0
	v_mul_f32_e32 v0, 0x3fb8aa3b, v0
	v_exp_f32_e32 v0, v0
	v_pk_fma_f32 v[146:147], v[10:11], v[146:147], v[200:201]
	s_mov_b32 s23, 0x62ea000
	v_pk_fma_f32 v[146:147], v[42:43], v[92:93], v[146:147]
	v_add_f32_e32 v0, 1.0, v0
	v_rcp_f32_e32 v158, v0
	v_mul_f32_e32 v0, 0x3d372713, v91
	v_mul_f32_e32 v0, v91, v0
	v_fma_f32 v0, v91, v0, v91
	v_mul_f32_e32 v0, 0x3f4c422a, v0
	v_add_f32_e32 v0, v0, v0
	v_mul_f32_e32 v0, 0x3fb8aa3b, v0
	v_exp_f32_e32 v0, v0
	v_pk_mul_f32 v[90:91], v[90:91], 0.5 op_sel_hi:[1,0]
	v_pk_add_f32 v[146:147], v[58:59], v[146:147]
	v_add_f32_e32 v0, 1.0, v0
	v_rcp_f32_e32 v159, v0
	s_nop 0
	v_pk_fma_f32 v[158:159], v[158:159], 2.0, 1.0 op_sel_hi:[1,0,0] neg_lo:[1,0,0] neg_hi:[1,0,0]
	s_nop 0
	v_pk_add_f32 v[158:159], v[158:159], 1.0 op_sel_hi:[1,0]
	s_nop 0
	v_pk_mul_f32 v[90:91], v[90:91], v[158:159]
	v_pk_mul_f32 v[158:159], v[26:27], v[92:93]
	v_pk_mul_f32 v[90:91], v[146:147], v[90:91]
	v_pk_mul_f32 v[146:147], v[18:19], v[96:97]
	v_pk_fma_f32 v[140:141], v[10:11], v[140:141], v[158:159]
	v_pk_fma_f32 v[146:147], v[2:3], v[156:157], v[146:147]
	v_pk_fma_f32 v[140:141], v[42:43], v[198:199], v[140:141]
	v_pk_fma_f32 v[146:147], v[34:35], v[194:195], v[146:147]
	v_pk_add_f32 v[140:141], v[58:59], v[140:141]
	v_pk_add_f32 v[146:147], v[50:51], v[146:147]
	s_waitcnt vmcnt(0) lgkmcnt(0)
	v_and_b32_e32 v159, 0xffff0000, v70
	v_mul_f32_e32 v0, 0x3d372713, v146
	v_mul_f32_e32 v0, v146, v0
	v_fma_f32 v0, v146, v0, v146
	v_mul_f32_e32 v0, 0x3f4c422a, v0
	v_add_f32_e32 v0, v0, v0
	v_mul_f32_e32 v0, 0x3fb8aa3b, v0
	v_exp_f32_e32 v0, v0
	v_cvt_pk_bf16_f32 v90, v90, v91
	v_add_f32_e32 v0, 1.0, v0
	v_rcp_f32_e32 v156, v0
	v_mul_f32_e32 v0, 0x3d372713, v147
	v_mul_f32_e32 v0, v147, v0
	v_fma_f32 v0, v147, v0, v147
	v_mul_f32_e32 v0, 0x3f4c422a, v0
	v_add_f32_e32 v0, v0, v0
	v_mul_f32_e32 v0, 0x3fb8aa3b, v0
	v_exp_f32_e32 v0, v0
	v_pk_mul_f32 v[146:147], v[146:147], 0.5 op_sel_hi:[1,0]
	v_add_f32_e32 v0, 1.0, v0
	v_rcp_f32_e32 v157, v0
	s_nop 0
	v_pk_fma_f32 v[156:157], v[156:157], 2.0, 1.0 op_sel_hi:[1,0,0] neg_lo:[1,0,0] neg_hi:[1,0,0]
	s_nop 0
	v_pk_add_f32 v[156:157], v[156:157], 1.0 op_sel_hi:[1,0]
	s_nop 0
	v_pk_mul_f32 v[146:147], v[146:147], v[156:157]
	v_and_b32_e32 v157, 0xffff0000, v66
	v_pk_mul_f32 v[140:141], v[140:141], v[146:147]
	v_pk_mul_f32 v[146:147], v[26:27], v[198:199]
	v_cvt_pk_bf16_f32 v86, v140, v141
	v_pk_mul_f32 v[140:141], v[18:19], v[194:195]
	v_pk_fma_f32 v[92:93], v[10:11], v[92:93], v[146:147]
	v_pk_fma_f32 v[96:97], v[2:3], v[96:97], v[140:141]
	v_pk_fma_f32 v[92:93], v[42:43], v[166:167], v[92:93]
	v_pk_fma_f32 v[96:97], v[34:35], v[196:197], v[96:97]
	v_pk_add_f32 v[92:93], v[58:59], v[92:93]
	v_pk_add_f32 v[96:97], v[50:51], v[96:97]
	v_lshlrev_b32_e32 v166, 16, v74
	v_mul_f32_e32 v0, 0x3d372713, v96
	v_mul_f32_e32 v0, v96, v0
	v_fma_f32 v0, v96, v0, v96
	v_mul_f32_e32 v0, 0x3f4c422a, v0
	v_add_f32_e32 v0, v0, v0
	v_mul_f32_e32 v0, 0x3fb8aa3b, v0
	v_exp_f32_e32 v0, v0
	v_and_b32_e32 v167, 0xffff0000, v74
	v_lshlrev_b32_e32 v146, 16, v78
	v_and_b32_e32 v147, 0xffff0000, v78
	v_add_f32_e32 v0, 1.0, v0
	v_rcp_f32_e32 v140, v0
	v_mul_f32_e32 v0, 0x3d372713, v97
	v_mul_f32_e32 v0, v97, v0
	v_fma_f32 v0, v97, v0, v97
	v_mul_f32_e32 v0, 0x3f4c422a, v0
	v_add_f32_e32 v0, v0, v0
	v_mul_f32_e32 v0, 0x3fb8aa3b, v0
	v_exp_f32_e32 v0, v0
	v_pk_mul_f32 v[96:97], v[96:97], 0.5 op_sel_hi:[1,0]
	v_pk_mul_f32 v[194:195], v[26:27], v[146:147]
	v_add_f32_e32 v0, 1.0, v0
	v_rcp_f32_e32 v141, v0
	v_pk_fma_f32 v[194:195], v[10:11], v[216:217], v[194:195]
	v_pk_fma_f32 v[140:141], v[140:141], 2.0, 1.0 op_sel_hi:[1,0,0] neg_lo:[1,0,0] neg_hi:[1,0,0]
	s_nop 0
	v_pk_add_f32 v[140:141], v[140:141], 1.0 op_sel_hi:[1,0]
	s_nop 0
	v_pk_mul_f32 v[96:97], v[96:97], v[140:141]
	s_nop 0
	v_pk_mul_f32 v[92:93], v[92:93], v[96:97]
	v_pk_mul_f32 v[96:97], v[26:27], v[216:217]
	v_cvt_pk_bf16_f32 v82, v92, v93
	v_pk_mul_f32 v[92:93], v[18:19], v[218:219]
	v_pk_fma_f32 v[96:97], v[10:11], v[204:205], v[96:97]
	v_pk_fma_f32 v[92:93], v[2:3], v[210:211], v[92:93]
	v_pk_fma_f32 v[96:97], v[42:43], v[146:147], v[96:97]
	v_pk_fma_f32 v[92:93], v[34:35], v[166:167], v[92:93]
	v_pk_add_f32 v[96:97], v[58:59], v[96:97]
	v_pk_add_f32 v[92:93], v[50:51], v[92:93]
	s_nop 0
	v_mul_f32_e32 v0, 0x3d372713, v92
	v_mul_f32_e32 v0, v92, v0
	v_fma_f32 v0, v92, v0, v92
	v_mul_f32_e32 v0, 0x3f4c422a, v0
	v_add_f32_e32 v0, v0, v0
	v_mul_f32_e32 v0, 0x3fb8aa3b, v0
	v_exp_f32_e32 v0, v0
	s_nop 0
	v_add_f32_e32 v0, 1.0, v0
	v_rcp_f32_e32 v140, v0
	v_mul_f32_e32 v0, 0x3d372713, v93
	v_mul_f32_e32 v0, v93, v0
	v_fma_f32 v0, v93, v0, v93
	v_mul_f32_e32 v0, 0x3f4c422a, v0
	v_add_f32_e32 v0, v0, v0
	v_mul_f32_e32 v0, 0x3fb8aa3b, v0
	v_exp_f32_e32 v0, v0
	v_pk_mul_f32 v[92:93], v[92:93], 0.5 op_sel_hi:[1,0]
	v_add_f32_e32 v0, 1.0, v0
	v_rcp_f32_e32 v141, v0
	s_nop 0
	v_pk_fma_f32 v[140:141], v[140:141], 2.0, 1.0 op_sel_hi:[1,0,0] neg_lo:[1,0,0] neg_hi:[1,0,0]
	s_nop 0
	v_pk_add_f32 v[140:141], v[140:141], 1.0 op_sel_hi:[1,0]
	s_nop 0
	v_pk_mul_f32 v[92:93], v[92:93], v[140:141]
	v_lshlrev_b32_e32 v141, 16, v66
	v_pk_mul_f32 v[92:93], v[96:97], v[92:93]
	v_mov_b32_e32 v156, v141
	v_cvt_pk_bf16_f32 v74, v92, v93
	v_pk_mul_f32 v[92:93], v[18:19], v[166:167]
	v_lshlrev_b32_e32 v140, 16, v70
	v_pk_fma_f32 v[92:93], v[2:3], v[218:219], v[92:93]
	v_mov_b32_e32 v158, v140
	v_pk_fma_f32 v[92:93], v[34:35], v[156:157], v[92:93]
	v_pk_fma_f32 v[194:195], v[42:43], v[158:159], v[194:195]
	v_pk_add_f32 v[92:93], v[50:51], v[92:93]
; DI unsigned pack2(float lo, float hi) { f32x2 v = {lo, hi}; bf2_t b = __builtin_convertvector(v, bf2_t); return __builtin_bit_cast(unsigned, b); }
; DI void unpack8(const u32x4& v, float* f) { f[0] = bflo(v.x); f[1] = bfhi(v.x); f[2] = bflo(v.y); f[3] = bfhi(v.y); f[4] = bflo(v.z); f[5] = bfhi(v.z); f[6] = bflo(v.w); f[7] = bfhi(v.w); }
; DI float gelu_tanh(float x) { const float y = 0.7978845608028654f * (x + 0.044715f * x * x * x); const float t = 1.f - 2.f * __builtin_amdgcn_rcpf(1.f + __expf(2.f * y)); return 0.5f * x * (1.f + t); }
; DI void ffn_act_phase(const Params& P, int l) {
;     ...
;     for (int rb = 0; rb < 4; ++rb) {
;       u32x4 G[8], U[8];
; #pragma unroll
;       for (int i = 0; i < 8; ++i) { const size_t ro = (size_t)(r0 + rb * 8 + i) * DFF2 + ch; G[i] = __builtin_nontemporal_load((const u32x4*)(u + ro)); U[i] = __builtin_nontemporal_load((const u32x4*)(u + ro + DFF)); }
; #pragma unroll
;       for (int i = 0; i < 8; ++i) {
;         float g0[8], u0[8]; unpack8(G[i], g0); unpack8(U[i], u0);
;         float o[8];
; #pragma unroll
;         for (int e = 0; e < 8; ++e) { const float yg = wg[0][e] * g2[e] + wg[1][e] * g1[e] + wg[2][e] * g0[e] + bg[e]; const float yu = wu[0][e] * u2[e] + wu[1][e] * u1[e] + wu[2][e] * u0[e] + bu[e];
;           o[e] = gelu_tanh(yg) * yu; g2[e] = g1[e]; g1[e] = g0[e]; u2[e] = u1[e]; u1[e] = u0[e]; }
;         u32x4 pk = {pack2(o[0], o[1]), pack2(o[2], o[3]), pack2(o[4], o[5]), pack2(o[6], o[7])};
;         *(u32x4*)(act + (size_t)(r0 + rb * 8 + i) * DFF + ch) = pk;
;       }
	v_pk_add_f32 v[194:195], v[58:59], v[194:195]
	v_mul_f32_e32 v0, 0x3d372713, v92
	v_mul_f32_e32 v0, v92, v0
	v_fma_f32 v0, v92, v0, v92
	v_mul_f32_e32 v0, 0x3f4c422a, v0
	v_add_f32_e32 v0, v0, v0
	v_mul_f32_e32 v0, 0x3fb8aa3b, v0
	v_exp_f32_e32 v0, v0
	s_nop 0
	v_add_f32_e32 v0, 1.0, v0
	v_rcp_f32_e32 v96, v0
	v_mul_f32_e32 v0, 0x3d372713, v93
	v_mul_f32_e32 v0, v93, v0
	v_fma_f32 v0, v93, v0, v93
	v_mul_f32_e32 v0, 0x3f4c422a, v0
	v_add_f32_e32 v0, v0, v0
	v_mul_f32_e32 v0, 0x3fb8aa3b, v0
	v_exp_f32_e32 v0, v0
	v_pk_mul_f32 v[92:93], v[92:93], 0.5 op_sel_hi:[1,0]
	v_add_f32_e32 v0, 1.0, v0
	v_rcp_f32_e32 v97, v0
	s_nop 0
	v_pk_fma_f32 v[96:97], v[96:97], 2.0, 1.0 op_sel_hi:[1,0,0] neg_lo:[1,0,0] neg_hi:[1,0,0]
	s_nop 0
	v_pk_add_f32 v[96:97], v[96:97], 1.0 op_sel_hi:[1,0]
	s_nop 0
	v_pk_mul_f32 v[92:93], v[92:93], v[96:97]
	s_nop 0
	v_pk_mul_f32 v[96:97], v[194:195], v[92:93]
	v_lshlrev_b32_e32 v92, 16, v83
	v_and_b32_e32 v93, 0xffff0000, v83
	v_pk_fma_f32 v[192:193], v[36:37], v[92:93], v[192:193]
	v_lshlrev_b32_e32 v194, 16, v87
	v_pk_add_f32 v[192:193], v[52:53], v[192:193]
	v_and_b32_e32 v195, 0xffff0000, v87
	v_mul_f32_e32 v0, 0x3d372713, v192
	v_mul_f32_e32 v0, v192, v0
	v_fma_f32 v0, v192, v0, v192
	v_mul_f32_e32 v0, 0x3f4c422a, v0
	v_add_f32_e32 v0, v0, v0
	v_mul_f32_e32 v0, 0x3fb8aa3b, v0
	v_exp_f32_e32 v0, v0
	v_pk_fma_f32 v[144:145], v[44:45], v[194:195], v[144:145]
	v_add_f32_e32 v0, 1.0, v0
	v_rcp_f32_e32 v196, v0
	v_mul_f32_e32 v0, 0x3d372713, v193
	v_mul_f32_e32 v0, v193, v0
	v_fma_f32 v0, v193, v0, v193
	v_mul_f32_e32 v0, 0x3f4c422a, v0
	v_add_f32_e32 v0, v0, v0
	v_mul_f32_e32 v0, 0x3fb8aa3b, v0
	v_exp_f32_e32 v0, v0
	v_pk_mul_f32 v[192:193], v[192:193], 0.5 op_sel_hi:[1,0]
	v_pk_add_f32 v[144:145], v[60:61], v[144:145]
	v_add_f32_e32 v0, 1.0, v0
	v_rcp_f32_e32 v197, v0
	s_nop 0
	v_pk_fma_f32 v[186:187], v[196:197], 2.0, 1.0 op_sel_hi:[1,0,0] neg_lo:[1,0,0] neg_hi:[1,0,0]
	s_nop 0
	v_pk_add_f32 v[186:187], v[186:187], 1.0 op_sel_hi:[1,0]
	s_nop 0
	v_pk_mul_f32 v[186:187], v[192:193], v[186:187]
	s_nop 0
	v_pk_mul_f32 v[144:145], v[144:145], v[186:187]
	v_pk_mul_f32 v[186:187], v[28:29], v[194:195]
	v_cvt_pk_bf16_f32 v91, v144, v145
	v_pk_mul_f32 v[144:145], v[20:21], v[92:93]
	v_pk_fma_f32 v[152:153], v[12:13], v[152:153], v[186:187]
	v_pk_fma_f32 v[144:145], v[4:5], v[148:149], v[144:145]
	v_pk_fma_f32 v[152:153], v[44:45], v[190:191], v[152:153]
	v_pk_fma_f32 v[144:145], v[36:37], v[184:185], v[144:145]
	v_pk_add_f32 v[152:153], v[60:61], v[152:153]
	v_pk_add_f32 v[144:145], v[52:53], v[144:145]
	s_nop 0
	v_mul_f32_e32 v0, 0x3d372713, v144
	v_mul_f32_e32 v0, v144, v0
	v_fma_f32 v0, v144, v0, v144
	v_mul_f32_e32 v0, 0x3f4c422a, v0
	v_add_f32_e32 v0, v0, v0
	v_mul_f32_e32 v0, 0x3fb8aa3b, v0
	v_exp_f32_e32 v0, v0
	s_nop 0
	v_add_f32_e32 v0, 1.0, v0
	v_rcp_f32_e32 v148, v0
	v_mul_f32_e32 v0, 0x3d372713, v145
	v_mul_f32_e32 v0, v145, v0
	v_fma_f32 v0, v145, v0, v145
	v_mul_f32_e32 v0, 0x3f4c422a, v0
	v_add_f32_e32 v0, v0, v0
	v_mul_f32_e32 v0, 0x3fb8aa3b, v0
	v_exp_f32_e32 v0, v0
	v_pk_mul_f32 v[144:145], v[144:145], 0.5 op_sel_hi:[1,0]
	v_add_f32_e32 v0, 1.0, v0
	v_rcp_f32_e32 v149, v0
	s_nop 0
	v_pk_fma_f32 v[148:149], v[148:149], 2.0, 1.0 op_sel_hi:[1,0,0] neg_lo:[1,0,0] neg_hi:[1,0,0]
	s_nop 0
	v_pk_add_f32 v[148:149], v[148:149], 1.0 op_sel_hi:[1,0]
	s_nop 0
	v_pk_mul_f32 v[144:145], v[144:145], v[148:149]
	v_pk_mul_f32 v[148:149], v[28:29], v[190:191]
	v_pk_mul_f32 v[144:145], v[152:153], v[144:145]
	v_pk_fma_f32 v[148:149], v[12:13], v[194:195], v[148:149]
	v_cvt_pk_bf16_f32 v87, v144, v145
	v_pk_mul_f32 v[144:145], v[20:21], v[184:185]
	v_pk_fma_f32 v[148:149], v[44:45], v[168:169], v[148:149]
	v_pk_fma_f32 v[92:93], v[4:5], v[92:93], v[144:145]
	v_lshlrev_b32_e32 v168, 16, v75
	v_pk_fma_f32 v[92:93], v[36:37], v[188:189], v[92:93]
	v_and_b32_e32 v169, 0xffff0000, v75
	v_pk_add_f32 v[92:93], v[52:53], v[92:93]
	v_pk_add_f32 v[148:149], v[60:61], v[148:149]
	v_mul_f32_e32 v0, 0x3d372713, v92
	v_mul_f32_e32 v0, v92, v0
	v_fma_f32 v0, v92, v0, v92
	v_mul_f32_e32 v0, 0x3f4c422a, v0
	v_add_f32_e32 v0, v0, v0
	v_mul_f32_e32 v0, 0x3fb8aa3b, v0
	v_exp_f32_e32 v0, v0
	v_lshlrev_b32_e32 v152, 16, v71
	v_and_b32_e32 v153, 0xffff0000, v71
	v_add_f32_e32 v0, 1.0, v0
	v_rcp_f32_e32 v144, v0
	v_mul_f32_e32 v0, 0x3d372713, v93
	v_mul_f32_e32 v0, v93, v0
	v_fma_f32 v0, v93, v0, v93
	v_mul_f32_e32 v0, 0x3f4c422a, v0
	v_add_f32_e32 v0, v0, v0
	v_mul_f32_e32 v0, 0x3fb8aa3b, v0
	v_exp_f32_e32 v0, v0
	v_pk_mul_f32 v[92:93], v[92:93], 0.5 op_sel_hi:[1,0]
	v_add_f32_e32 v0, 1.0, v0
	v_rcp_f32_e32 v145, v0
	s_nop 0
	v_pk_fma_f32 v[144:145], v[144:145], 2.0, 1.0 op_sel_hi:[1,0,0] neg_lo:[1,0,0] neg_hi:[1,0,0]
	s_nop 0
	v_pk_add_f32 v[144:145], v[144:145], 1.0 op_sel_hi:[1,0]
	s_nop 0
	v_pk_mul_f32 v[92:93], v[92:93], v[144:145]
	v_lshlrev_b32_e32 v144, 16, v79
	v_and_b32_e32 v145, 0xffff0000, v79
	v_pk_mul_f32 v[78:79], v[20:21], v[214:215]
	v_pk_mul_f32 v[92:93], v[148:149], v[92:93]
	v_pk_fma_f32 v[78:79], v[4:5], v[128:129], v[78:79]
	v_cvt_pk_bf16_f32 v83, v92, v93
	v_pk_fma_f32 v[78:79], v[36:37], v[168:169], v[78:79]
	v_pk_mul_f32 v[92:93], v[28:29], v[212:213]
	v_pk_add_f32 v[78:79], v[52:53], v[78:79]
	v_pk_fma_f32 v[92:93], v[12:13], v[124:125], v[92:93]
	v_mul_f32_e32 v0, 0x3d372713, v78
	v_mul_f32_e32 v0, v78, v0
	v_fma_f32 v0, v78, v0, v78
	v_mul_f32_e32 v0, 0x3f4c422a, v0
	v_add_f32_e32 v0, v0, v0
	v_mul_f32_e32 v0, 0x3fb8aa3b, v0
	v_exp_f32_e32 v0, v0
	v_lshlrev_b32_e32 v148, 16, v67
	v_and_b32_e32 v149, 0xffff0000, v67
	v_pk_mul_f32 v[66:67], v[20:21], v[168:169]
	v_add_f32_e32 v0, 1.0, v0
	v_rcp_f32_e32 v124, v0
; DI unsigned pack2(float lo, float hi) { f32x2 v = {lo, hi}; bf2_t b = __builtin_convertvector(v, bf2_t); return __builtin_bit_cast(unsigned, b); }
; DI void unpack8(const u32x4& v, float* f) { f[0] = bflo(v.x); f[1] = bfhi(v.x); f[2] = bflo(v.y); f[3] = bfhi(v.y); f[4] = bflo(v.z); f[5] = bfhi(v.z); f[6] = bflo(v.w); f[7] = bfhi(v.w); }
; DI float gelu_tanh(float x) { const float y = 0.7978845608028654f * (x + 0.044715f * x * x * x); const float t = 1.f - 2.f * __builtin_amdgcn_rcpf(1.f + __expf(2.f * y)); return 0.5f * x * (1.f + t); }
; DI void ffn_act_phase(const Params& P, int l) {
;     ...
;     for (int rb = 0; rb < 4; ++rb) {
;       u32x4 G[8], U[8];
; #pragma unroll
;       for (int i = 0; i < 8; ++i) { const size_t ro = (size_t)(r0 + rb * 8 + i) * DFF2 + ch; G[i] = __builtin_nontemporal_load((const u32x4*)(u + ro)); U[i] = __builtin_nontemporal_load((const u32x4*)(u + ro + DFF)); }
; #pragma unroll
;       for (int i = 0; i < 8; ++i) {
;         float g0[8], u0[8]; unpack8(G[i], g0); unpack8(U[i], u0);
;         float o[8];
; #pragma unroll
;         for (int e = 0; e < 8; ++e) { const float yg = wg[0][e] * g2[e] + wg[1][e] * g1[e] + wg[2][e] * g0[e] + bg[e]; const float yu = wu[0][e] * u2[e] + wu[1][e] * u1[e] + wu[2][e] * u0[e] + bu[e];
;           o[e] = gelu_tanh(yg) * yu; g2[e] = g1[e]; g1[e] = g0[e]; u2[e] = u1[e]; u1[e] = u0[e]; }
;         u32x4 pk = {pack2(o[0], o[1]), pack2(o[2], o[3]), pack2(o[4], o[5]), pack2(o[6], o[7])};
;         *(u32x4*)(act + (size_t)(r0 + rb * 8 + i) * DFF + ch) = pk;
;       }
	v_mul_f32_e32 v0, 0x3d372713, v79
	v_mul_f32_e32 v0, v79, v0
	v_fma_f32 v0, v79, v0, v79
	v_mul_f32_e32 v0, 0x3f4c422a, v0
	v_add_f32_e32 v0, v0, v0
	v_mul_f32_e32 v0, 0x3fb8aa3b, v0
	v_exp_f32_e32 v0, v0
	v_pk_fma_f32 v[66:67], v[4:5], v[214:215], v[66:67]
	v_pk_fma_f32 v[92:93], v[44:45], v[144:145], v[92:93]
	v_pk_fma_f32 v[66:67], v[36:37], v[148:149], v[66:67]
	v_add_f32_e32 v0, 1.0, v0
	v_pk_add_f32 v[66:67], v[52:53], v[66:67]
	v_rcp_f32_e32 v125, v0
	v_mul_f32_e32 v0, 0x3d372713, v66
	v_mul_f32_e32 v0, v66, v0
	v_fma_f32 v0, v66, v0, v66
	v_mul_f32_e32 v0, 0x3f4c422a, v0
	v_add_f32_e32 v0, v0, v0
	v_mul_f32_e32 v0, 0x3fb8aa3b, v0
	v_exp_f32_e32 v0, v0
	v_pk_fma_f32 v[124:125], v[124:125], 2.0, 1.0 op_sel_hi:[1,0,0] neg_lo:[1,0,0] neg_hi:[1,0,0]
	v_pk_mul_f32 v[78:79], v[78:79], 0.5 op_sel_hi:[1,0]
	v_pk_add_f32 v[124:125], v[124:125], 1.0 op_sel_hi:[1,0]
	v_add_f32_e32 v0, 1.0, v0
	v_rcp_f32_e32 v70, v0
	v_mul_f32_e32 v0, 0x3d372713, v67
	v_mul_f32_e32 v0, v67, v0
	v_fma_f32 v0, v67, v0, v67
	v_mul_f32_e32 v0, 0x3f4c422a, v0
	v_add_f32_e32 v0, v0, v0
	v_mul_f32_e32 v0, 0x3fb8aa3b, v0
	v_exp_f32_e32 v0, v0
	v_pk_add_f32 v[92:93], v[60:61], v[92:93]
	v_pk_mul_f32 v[78:79], v[78:79], v[124:125]
	v_pk_mul_f32 v[66:67], v[66:67], 0.5 op_sel_hi:[1,0]
	v_add_f32_e32 v0, 1.0, v0
	v_rcp_f32_e32 v71, v0
	v_pk_mul_f32 v[78:79], v[92:93], v[78:79]
	v_pk_fma_f32 v[92:93], v[22:23], v[142:143], v[182:183]
	v_cvt_pk_bf16_f32 v75, v78, v79
	v_pk_mul_f32 v[78:79], v[28:29], v[144:145]
	v_pk_fma_f32 v[70:71], v[70:71], 2.0, 1.0 op_sel_hi:[1,0,0] neg_lo:[1,0,0] neg_hi:[1,0,0]
	v_pk_fma_f32 v[78:79], v[12:13], v[212:213], v[78:79]
	v_pk_add_f32 v[70:71], v[70:71], 1.0 op_sel_hi:[1,0]
	v_pk_fma_f32 v[78:79], v[44:45], v[152:153], v[78:79]
	v_pk_mul_f32 v[66:67], v[66:67], v[70:71]
	v_pk_add_f32 v[78:79], v[60:61], v[78:79]
	v_pk_fma_f32 v[128:129], v[14:15], v[150:151], v[174:175]
	v_pk_mul_f32 v[70:71], v[78:79], v[66:67]
	v_lshlrev_b32_e32 v66, 16, v84
	v_and_b32_e32 v67, 0xffff0000, v84
	v_pk_fma_f32 v[92:93], v[38:39], v[66:67], v[92:93]
	v_lshlrev_b32_e32 v78, 16, v88
	v_pk_add_f32 v[92:93], v[54:55], v[92:93]
	v_and_b32_e32 v79, 0xffff0000, v88
	v_mul_f32_e32 v0, 0x3d372713, v92
	v_mul_f32_e32 v0, v92, v0
	v_fma_f32 v0, v92, v0, v92
	v_mul_f32_e32 v0, 0x3f4c422a, v0
	v_add_f32_e32 v0, v0, v0
	v_mul_f32_e32 v0, 0x3fb8aa3b, v0
	v_exp_f32_e32 v0, v0
	v_pk_fma_f32 v[128:129], v[46:47], v[78:79], v[128:129]
	v_lshlrev_b32_e32 v174, 16, v76
	v_pk_add_f32 v[128:129], v[62:63], v[128:129]
	v_add_f32_e32 v0, 1.0, v0
	v_rcp_f32_e32 v124, v0
	v_mul_f32_e32 v0, 0x3d372713, v93
	v_mul_f32_e32 v0, v93, v0
	v_fma_f32 v0, v93, v0, v93
	v_mul_f32_e32 v0, 0x3f4c422a, v0
	v_add_f32_e32 v0, v0, v0
	v_mul_f32_e32 v0, 0x3fb8aa3b, v0
	v_exp_f32_e32 v0, v0
	v_pk_mul_f32 v[92:93], v[92:93], 0.5 op_sel_hi:[1,0]
	v_and_b32_e32 v175, 0xffff0000, v76
	v_lshlrev_b32_e32 v150, 16, v80
	v_add_f32_e32 v0, 1.0, v0
	v_rcp_f32_e32 v125, v0
	v_and_b32_e32 v151, 0xffff0000, v80
	v_pk_fma_f32 v[124:125], v[124:125], 2.0, 1.0 op_sel_hi:[1,0,0] neg_lo:[1,0,0] neg_hi:[1,0,0]
	s_nop 0
	v_pk_add_f32 v[124:125], v[124:125], 1.0 op_sel_hi:[1,0]
	s_nop 0
	v_pk_mul_f32 v[92:93], v[92:93], v[124:125]
	v_pk_mul_f32 v[124:125], v[22:23], v[66:67]
	v_pk_mul_f32 v[92:93], v[128:129], v[92:93]
	v_pk_fma_f32 v[124:125], v[6:7], v[142:143], v[124:125]
	v_pk_mul_f32 v[142:143], v[30:31], v[78:79]
	v_pk_fma_f32 v[124:125], v[38:39], v[118:119], v[124:125]
	v_pk_mul_f32 v[118:119], v[22:23], v[118:119]
	v_pk_add_f32 v[124:125], v[54:55], v[124:125]
	v_pk_fma_f32 v[66:67], v[6:7], v[66:67], v[118:119]
	v_mul_f32_e32 v0, 0x3d372713, v124
	v_mul_f32_e32 v0, v124, v0
	v_fma_f32 v0, v124, v0, v124
	v_mul_f32_e32 v0, 0x3f4c422a, v0
	v_add_f32_e32 v0, v0, v0
	v_mul_f32_e32 v0, 0x3fb8aa3b, v0
	v_exp_f32_e32 v0, v0
	v_pk_fma_f32 v[66:67], v[38:39], v[122:123], v[66:67]
	v_pk_fma_f32 v[142:143], v[14:15], v[154:155], v[142:143]
	v_pk_add_f32 v[66:67], v[54:55], v[66:67]
	v_add_f32_e32 v0, 1.0, v0
	v_rcp_f32_e32 v128, v0
	v_mul_f32_e32 v0, 0x3d372713, v125
	v_mul_f32_e32 v0, v125, v0
	v_fma_f32 v0, v125, v0, v125
	v_mul_f32_e32 v0, 0x3f4c422a, v0
	v_add_f32_e32 v0, v0, v0
	v_mul_f32_e32 v0, 0x3fb8aa3b, v0
	v_exp_f32_e32 v0, v0
	v_pk_fma_f32 v[142:143], v[46:47], v[126:127], v[142:143]
	v_pk_mul_f32 v[124:125], v[124:125], 0.5 op_sel_hi:[1,0]
	v_pk_add_f32 v[142:143], v[62:63], v[142:143]
	v_add_f32_e32 v0, 1.0, v0
	v_rcp_f32_e32 v129, v0
	v_mul_f32_e32 v0, 0x3d372713, v66
	v_mul_f32_e32 v0, v66, v0
	v_fma_f32 v0, v66, v0, v66
	v_mul_f32_e32 v0, 0x3f4c422a, v0
	v_add_f32_e32 v0, v0, v0
	v_mul_f32_e32 v0, 0x3fb8aa3b, v0
	v_exp_f32_e32 v0, v0
	v_pk_fma_f32 v[128:129], v[128:129], 2.0, 1.0 op_sel_hi:[1,0,0] neg_lo:[1,0,0] neg_hi:[1,0,0]
	v_lshlrev_b32_e32 v154, 16, v72
	v_pk_add_f32 v[128:129], v[128:129], 1.0 op_sel_hi:[1,0]
	v_add_f32_e32 v0, 1.0, v0
	v_rcp_f32_e32 v118, v0
	v_mul_f32_e32 v0, 0x3d372713, v67
	v_mul_f32_e32 v0, v67, v0
	v_fma_f32 v0, v67, v0, v67
	v_mul_f32_e32 v0, 0x3f4c422a, v0
	v_add_f32_e32 v0, v0, v0
	v_mul_f32_e32 v0, 0x3fb8aa3b, v0
	v_exp_f32_e32 v0, v0
	v_pk_mul_f32 v[124:125], v[124:125], v[128:129]
	v_pk_mul_f32 v[66:67], v[66:67], 0.5 op_sel_hi:[1,0]
	v_pk_mul_f32 v[124:125], v[142:143], v[124:125]
	v_add_f32_e32 v0, 1.0, v0
	v_rcp_f32_e32 v119, v0
	v_cvt_pk_bf16_f32 v88, v124, v125
	v_pk_mul_f32 v[124:125], v[30:31], v[126:127]
	v_lshlrev_b32_e32 v142, 16, v68
	v_pk_fma_f32 v[78:79], v[14:15], v[78:79], v[124:125]
	v_and_b32_e32 v143, 0xffff0000, v68
	v_pk_fma_f32 v[78:79], v[46:47], v[114:115], v[78:79]
	v_pk_fma_f32 v[114:115], v[118:119], 2.0, 1.0 op_sel_hi:[1,0,0] neg_lo:[1,0,0] neg_hi:[1,0,0]
; DI unsigned pack2(float lo, float hi) { f32x2 v = {lo, hi}; bf2_t b = __builtin_convertvector(v, bf2_t); return __builtin_bit_cast(unsigned, b); }
; DI void unpack8(const u32x4& v, float* f) { f[0] = bflo(v.x); f[1] = bfhi(v.x); f[2] = bflo(v.y); f[3] = bfhi(v.y); f[4] = bflo(v.z); f[5] = bfhi(v.z); f[6] = bflo(v.w); f[7] = bfhi(v.w); }
; DI float gelu_tanh(float x) { const float y = 0.7978845608028654f * (x + 0.044715f * x * x * x); const float t = 1.f - 2.f * __builtin_amdgcn_rcpf(1.f + __expf(2.f * y)); return 0.5f * x * (1.f + t); }
; DI void ffn_act_phase(const Params& P, int l) {
;     ...
;     for (int rb = 0; rb < 4; ++rb) {
;       u32x4 G[8], U[8];
; #pragma unroll
;       for (int i = 0; i < 8; ++i) { const size_t ro = (size_t)(r0 + rb * 8 + i) * DFF2 + ch; G[i] = __builtin_nontemporal_load((const u32x4*)(u + ro)); U[i] = __builtin_nontemporal_load((const u32x4*)(u + ro + DFF)); }
; #pragma unroll
;       for (int i = 0; i < 8; ++i) {
;         float g0[8], u0[8]; unpack8(G[i], g0); unpack8(U[i], u0);
;         float o[8];
; #pragma unroll
;         for (int e = 0; e < 8; ++e) { const float yg = wg[0][e] * g2[e] + wg[1][e] * g1[e] + wg[2][e] * g0[e] + bg[e]; const float yu = wu[0][e] * u2[e] + wu[1][e] * u1[e] + wu[2][e] * u0[e] + bu[e];
;           o[e] = gelu_tanh(yg) * yu; g2[e] = g1[e]; g1[e] = g0[e]; u2[e] = u1[e]; u1[e] = u0[e]; }
;         u32x4 pk = {pack2(o[0], o[1]), pack2(o[2], o[3]), pack2(o[4], o[5]), pack2(o[6], o[7])};
;         *(u32x4*)(act + (size_t)(r0 + rb * 8 + i) * DFF + ch) = pk;
;       }
	v_pk_add_f32 v[78:79], v[62:63], v[78:79]
	v_pk_add_f32 v[114:115], v[114:115], 1.0 op_sel_hi:[1,0]
	v_and_b32_e32 v155, 0xffff0000, v72
	v_pk_mul_f32 v[66:67], v[66:67], v[114:115]
	v_pk_fma_f32 v[118:119], v[16:17], v[164:165], v[178:179]
	v_pk_mul_f32 v[66:67], v[78:79], v[66:67]
	v_pk_mul_f32 v[78:79], v[30:31], v[104:105]
	v_cvt_pk_bf16_f32 v84, v66, v67
	v_pk_mul_f32 v[66:67], v[22:23], v[202:203]
	v_pk_fma_f32 v[78:79], v[14:15], v[116:117], v[78:79]
	v_pk_fma_f32 v[66:67], v[6:7], v[120:121], v[66:67]
	v_pk_fma_f32 v[78:79], v[46:47], v[150:151], v[78:79]
	v_pk_fma_f32 v[66:67], v[38:39], v[174:175], v[66:67]
	v_pk_add_f32 v[78:79], v[62:63], v[78:79]
	v_pk_add_f32 v[66:67], v[54:55], v[66:67]
	v_cvt_pk_bf16_f32 v92, v92, v93
	v_mul_f32_e32 v0, 0x3d372713, v66
	v_mul_f32_e32 v0, v66, v0
	v_fma_f32 v0, v66, v0, v66
	v_mul_f32_e32 v0, 0x3f4c422a, v0
	v_add_f32_e32 v0, v0, v0
	v_mul_f32_e32 v0, 0x3fb8aa3b, v0
	v_exp_f32_e32 v0, v0
	v_lshlrev_b32_e32 v178, 16, v77
	v_and_b32_e32 v179, 0xffff0000, v77
	v_lshlrev_b32_e32 v164, 16, v81
	v_add_f32_e32 v0, 1.0, v0
	v_rcp_f32_e32 v114, v0
	v_mul_f32_e32 v0, 0x3d372713, v67
	v_mul_f32_e32 v0, v67, v0
	v_fma_f32 v0, v67, v0, v67
	v_mul_f32_e32 v0, 0x3f4c422a, v0
	v_add_f32_e32 v0, v0, v0
	v_mul_f32_e32 v0, 0x3fb8aa3b, v0
	v_exp_f32_e32 v0, v0
	v_pk_mul_f32 v[66:67], v[66:67], 0.5 op_sel_hi:[1,0]
	v_and_b32_e32 v165, 0xffff0000, v81
	v_pk_mul_f32 v[80:81], v[32:33], v[94:95]
	v_add_f32_e32 v0, 1.0, v0
	v_rcp_f32_e32 v115, v0
	v_pk_fma_f32 v[80:81], v[16:17], v[100:101], v[80:81]
	v_pk_fma_f32 v[114:115], v[114:115], 2.0, 1.0 op_sel_hi:[1,0,0] neg_lo:[1,0,0] neg_hi:[1,0,0]
	s_nop 0
	v_pk_add_f32 v[114:115], v[114:115], 1.0 op_sel_hi:[1,0]
	v_pk_fma_f32 v[80:81], v[48:49], v[164:165], v[80:81]
	v_pk_mul_f32 v[66:67], v[66:67], v[114:115]
	v_pk_mul_f32 v[114:115], v[30:31], v[150:151]
	v_pk_mul_f32 v[66:67], v[78:79], v[66:67]
	v_pk_fma_f32 v[104:105], v[14:15], v[104:105], v[114:115]
	v_cvt_pk_bf16_f32 v76, v66, v67
	v_pk_mul_f32 v[66:67], v[22:23], v[174:175]
	v_pk_fma_f32 v[104:105], v[46:47], v[154:155], v[104:105]
	v_pk_fma_f32 v[66:67], v[6:7], v[202:203], v[66:67]
	v_pk_add_f32 v[104:105], v[62:63], v[104:105]
	v_pk_fma_f32 v[66:67], v[38:39], v[142:143], v[66:67]
	v_pk_fma_f32 v[114:115], v[24:25], v[170:171], v[180:181]
	v_pk_add_f32 v[66:67], v[54:55], v[66:67]
	v_pk_add_f32 v[80:81], v[64:65], v[80:81]
	v_mul_f32_e32 v0, 0x3d372713, v66
	v_mul_f32_e32 v0, v66, v0
	v_fma_f32 v0, v66, v0, v66
	v_mul_f32_e32 v0, 0x3f4c422a, v0
	v_add_f32_e32 v0, v0, v0
	v_mul_f32_e32 v0, 0x3fb8aa3b, v0
	v_exp_f32_e32 v0, v0
	s_nop 0
	v_add_f32_e32 v0, 1.0, v0
	v_rcp_f32_e32 v78, v0
	v_mul_f32_e32 v0, 0x3d372713, v67
	v_mul_f32_e32 v0, v67, v0
	v_fma_f32 v0, v67, v0, v67
	v_mul_f32_e32 v0, 0x3f4c422a, v0
	v_add_f32_e32 v0, v0, v0
	v_mul_f32_e32 v0, 0x3fb8aa3b, v0
	v_exp_f32_e32 v0, v0
	v_pk_mul_f32 v[66:67], v[66:67], 0.5 op_sel_hi:[1,0]
	v_add_f32_e32 v0, 1.0, v0
	v_rcp_f32_e32 v79, v0
	s_nop 0
	v_pk_fma_f32 v[78:79], v[78:79], 2.0, 1.0 op_sel_hi:[1,0,0] neg_lo:[1,0,0] neg_hi:[1,0,0]
	s_nop 0
	v_pk_add_f32 v[78:79], v[78:79], 1.0 op_sel_hi:[1,0]
	s_nop 0
	v_pk_mul_f32 v[66:67], v[66:67], v[78:79]
	s_nop 0
	v_pk_mul_f32 v[78:79], v[104:105], v[66:67]
	v_lshlrev_b32_e32 v104, 16, v85
	v_and_b32_e32 v105, 0xffff0000, v85
	v_pk_fma_f32 v[114:115], v[40:41], v[104:105], v[114:115]
	v_lshlrev_b32_e32 v66, 16, v89
	v_pk_add_f32 v[114:115], v[56:57], v[114:115]
	v_and_b32_e32 v67, 0xffff0000, v89
	v_mul_f32_e32 v0, 0x3d372713, v114
	v_mul_f32_e32 v0, v114, v0
	v_fma_f32 v0, v114, v0, v114
	v_mul_f32_e32 v0, 0x3f4c422a, v0
	v_add_f32_e32 v0, v0, v0
	v_mul_f32_e32 v0, 0x3fb8aa3b, v0
	v_exp_f32_e32 v0, v0
	v_pk_fma_f32 v[118:119], v[48:49], v[66:67], v[118:119]
	v_add_f32_e32 v0, 1.0, v0
	v_rcp_f32_e32 v116, v0
	v_mul_f32_e32 v0, 0x3d372713, v115
	v_mul_f32_e32 v0, v115, v0
	v_fma_f32 v0, v115, v0, v115
	v_mul_f32_e32 v0, 0x3f4c422a, v0
	v_add_f32_e32 v0, v0, v0
	v_mul_f32_e32 v0, 0x3fb8aa3b, v0
	v_exp_f32_e32 v0, v0
	v_pk_mul_f32 v[114:115], v[114:115], 0.5 op_sel_hi:[1,0]
	v_pk_add_f32 v[118:119], v[64:65], v[118:119]
	v_add_f32_e32 v0, 1.0, v0
	v_rcp_f32_e32 v117, v0
	s_nop 0
	v_pk_fma_f32 v[116:117], v[116:117], 2.0, 1.0 op_sel_hi:[1,0,0] neg_lo:[1,0,0] neg_hi:[1,0,0]
	s_nop 0
	v_pk_add_f32 v[116:117], v[116:117], 1.0 op_sel_hi:[1,0]
	s_nop 0
	v_pk_mul_f32 v[114:115], v[114:115], v[116:117]
	s_nop 0
	v_pk_mul_f32 v[114:115], v[118:119], v[114:115]
	s_nop 0
	v_cvt_pk_bf16_f32 v93, v114, v115
	v_add_co_u32_e32 v114, vcc, s92, v176
	s_nop 1
	v_addc_co_u32_e32 v115, vcc, 0, v177, vcc
	global_store_dwordx4 v[114:115], v[90:93], off
	v_pk_mul_f32 v[114:115], v[32:33], v[66:67]
	s_nop 0
	v_pk_mul_f32 v[90:91], v[24:25], v[104:105]
	v_pk_fma_f32 v[114:115], v[16:17], v[172:173], v[114:115]
	v_pk_fma_f32 v[90:91], v[8:9], v[170:171], v[90:91]
	v_pk_fma_f32 v[114:115], v[48:49], v[112:113], v[114:115]
	v_pk_fma_f32 v[90:91], v[40:41], v[108:109], v[90:91]
	v_pk_add_f32 v[114:115], v[64:65], v[114:115]
	v_pk_add_f32 v[90:91], v[56:57], v[90:91]
	v_lshlrev_b32_e32 v170, 16, v69
	v_mul_f32_e32 v0, 0x3d372713, v90
	v_mul_f32_e32 v0, v90, v0
	v_fma_f32 v0, v90, v0, v90
	v_mul_f32_e32 v0, 0x3f4c422a, v0
	v_add_f32_e32 v0, v0, v0
	v_mul_f32_e32 v0, 0x3fb8aa3b, v0
	v_exp_f32_e32 v0, v0
	v_and_b32_e32 v171, 0xffff0000, v69
; DI unsigned pack2(float lo, float hi) { f32x2 v = {lo, hi}; bf2_t b = __builtin_convertvector(v, bf2_t); return __builtin_bit_cast(unsigned, b); }
; DI void unpack8(const u32x4& v, float* f) { f[0] = bflo(v.x); f[1] = bfhi(v.x); f[2] = bflo(v.y); f[3] = bfhi(v.y); f[4] = bflo(v.z); f[5] = bfhi(v.z); f[6] = bflo(v.w); f[7] = bfhi(v.w); }
; DI float gelu_tanh(float x) { const float y = 0.7978845608028654f * (x + 0.044715f * x * x * x); const float t = 1.f - 2.f * __builtin_amdgcn_rcpf(1.f + __expf(2.f * y)); return 0.5f * x * (1.f + t); }
; DI void ffn_act_phase(const Params& P, int l) {
;     ...
;   for (int item = blockIdx.x * 8 + w; item < 512 * 11; item += gridDim.x * 8) {
;     ...
;     for (int rb = 0; rb < 4; ++rb) {
;       u32x4 G[8], U[8];
; #pragma unroll
;       for (int i = 0; i < 8; ++i) { const size_t ro = (size_t)(r0 + rb * 8 + i) * DFF2 + ch; G[i] = __builtin_nontemporal_load((const u32x4*)(u + ro)); U[i] = __builtin_nontemporal_load((const u32x4*)(u + ro + DFF)); }
; #pragma unroll
;       for (int i = 0; i < 8; ++i) {
;         float g0[8], u0[8]; unpack8(G[i], g0); unpack8(U[i], u0);
;         float o[8];
; #pragma unroll
;         for (int e = 0; e < 8; ++e) { const float yg = wg[0][e] * g2[e] + wg[1][e] * g1[e] + wg[2][e] * g0[e] + bg[e]; const float yu = wu[0][e] * u2[e] + wu[1][e] * u1[e] + wu[2][e] * u0[e] + bu[e];
;           o[e] = gelu_tanh(yg) * yu; g2[e] = g1[e]; g1[e] = g0[e]; u2[e] = u1[e]; u1[e] = u0[e]; }
;         u32x4 pk = {pack2(o[0], o[1]), pack2(o[2], o[3]), pack2(o[4], o[5]), pack2(o[6], o[7])};
;         *(u32x4*)(act + (size_t)(r0 + rb * 8 + i) * DFF + ch) = pk;
;       }
	v_lshlrev_b32_e32 v172, 16, v73
	v_and_b32_e32 v173, 0xffff0000, v73
	v_add_f32_e32 v0, 1.0, v0
	v_rcp_f32_e32 v92, v0
	v_mul_f32_e32 v0, 0x3d372713, v91
	v_mul_f32_e32 v0, v91, v0
	v_fma_f32 v0, v91, v0, v91
	v_mul_f32_e32 v0, 0x3f4c422a, v0
	v_add_f32_e32 v0, v0, v0
	v_mul_f32_e32 v0, 0x3fb8aa3b, v0
	v_exp_f32_e32 v0, v0
	v_pk_mul_f32 v[90:91], v[90:91], 0.5 op_sel_hi:[1,0]
	v_pk_mul_f32 v[72:73], v[32:33], v[164:165]
	v_add_f32_e32 v0, 1.0, v0
	v_rcp_f32_e32 v93, v0
	v_pk_fma_f32 v[72:73], v[16:17], v[94:95], v[72:73]
	v_pk_fma_f32 v[92:93], v[92:93], 2.0, 1.0 op_sel_hi:[1,0,0] neg_lo:[1,0,0] neg_hi:[1,0,0]
	s_nop 0
	v_pk_add_f32 v[92:93], v[92:93], 1.0 op_sel_hi:[1,0]
	v_pk_fma_f32 v[72:73], v[48:49], v[172:173], v[72:73]
	v_pk_mul_f32 v[90:91], v[90:91], v[92:93]
	v_pk_add_f32 v[72:73], v[64:65], v[72:73]
	v_pk_mul_f32 v[90:91], v[114:115], v[90:91]
	s_nop 0
	v_cvt_pk_bf16_f32 v89, v90, v91
	v_add_co_u32_e32 v90, vcc, s23, v176
	s_mov_b32 s23, 0x62ed000
	s_nop 0
	v_addc_co_u32_e32 v91, vcc, 0, v177, vcc
	global_store_dwordx4 v[90:91], v[86:89], off offset:3072
	s_nop 1
	v_pk_mul_f32 v[86:87], v[24:25], v[108:109]
	v_pk_mul_f32 v[88:89], v[32:33], v[112:113]
	v_pk_fma_f32 v[86:87], v[8:9], v[104:105], v[86:87]
	v_pk_fma_f32 v[66:67], v[16:17], v[66:67], v[88:89]
	v_pk_fma_f32 v[86:87], v[40:41], v[110:111], v[86:87]
	v_pk_fma_f32 v[66:67], v[48:49], v[106:107], v[66:67]
	v_pk_add_f32 v[86:87], v[56:57], v[86:87]
	v_pk_add_f32 v[66:67], v[64:65], v[66:67]
	v_mul_f32_e32 v0, 0x3d372713, v86
	v_mul_f32_e32 v0, v86, v0
	v_fma_f32 v0, v86, v0, v86
	v_mul_f32_e32 v0, 0x3f4c422a, v0
	v_add_f32_e32 v0, v0, v0
	v_mul_f32_e32 v0, 0x3fb8aa3b, v0
	v_exp_f32_e32 v0, v0
	s_nop 0
	v_add_f32_e32 v0, 1.0, v0
	v_rcp_f32_e32 v90, v0
	v_mul_f32_e32 v0, 0x3d372713, v87
	v_mul_f32_e32 v0, v87, v0
	v_fma_f32 v0, v87, v0, v87
	v_mul_f32_e32 v0, 0x3f4c422a, v0
	v_add_f32_e32 v0, v0, v0
	v_mul_f32_e32 v0, 0x3fb8aa3b, v0
	v_exp_f32_e32 v0, v0
	v_pk_mul_f32 v[86:87], v[86:87], 0.5 op_sel_hi:[1,0]
	v_add_f32_e32 v0, 1.0, v0
	v_rcp_f32_e32 v91, v0
	s_nop 0
	v_pk_fma_f32 v[88:89], v[90:91], 2.0, 1.0 op_sel_hi:[1,0,0] neg_lo:[1,0,0] neg_hi:[1,0,0]
	s_nop 0
	v_pk_add_f32 v[88:89], v[88:89], 1.0 op_sel_hi:[1,0]
	s_nop 0
	v_pk_mul_f32 v[86:87], v[86:87], v[88:89]
	s_nop 0
	v_pk_mul_f32 v[66:67], v[66:67], v[86:87]
	s_nop 0
	v_cvt_pk_bf16_f32 v85, v66, v67
	v_add_co_u32_e32 v66, vcc, s23, v176
	s_mov_b32 s23, 0x62f8000
	s_nop 0
	v_addc_co_u32_e32 v67, vcc, 0, v177, vcc
	global_store_dwordx4 v[66:67], v[82:85], off offset:2048
	v_pk_mul_f32 v[66:67], v[24:25], v[98:99]
	s_nop 0
	v_pk_fma_f32 v[66:67], v[8:9], v[102:103], v[66:67]
	s_nop 0
	v_pk_fma_f32 v[66:67], v[40:41], v[178:179], v[66:67]
	s_nop 0
	v_pk_add_f32 v[66:67], v[56:57], v[66:67]
	s_nop 0
	v_mul_f32_e32 v0, 0x3d372713, v66
	v_mul_f32_e32 v0, v66, v0
	v_fma_f32 v0, v66, v0, v66
	v_mul_f32_e32 v0, 0x3f4c422a, v0
	v_add_f32_e32 v0, v0, v0
	v_mul_f32_e32 v0, 0x3fb8aa3b, v0
	v_exp_f32_e32 v0, v0
	s_nop 0
	v_add_f32_e32 v0, 1.0, v0
	v_rcp_f32_e32 v82, v0
	v_mul_f32_e32 v0, 0x3d372713, v67
	v_mul_f32_e32 v0, v67, v0
	v_fma_f32 v0, v67, v0, v67
	v_mul_f32_e32 v0, 0x3f4c422a, v0
	v_add_f32_e32 v0, v0, v0
	v_mul_f32_e32 v0, 0x3fb8aa3b, v0
	v_exp_f32_e32 v0, v0
	v_pk_mul_f32 v[66:67], v[66:67], 0.5 op_sel_hi:[1,0]
	v_add_f32_e32 v0, 1.0, v0
	v_rcp_f32_e32 v83, v0
	s_nop 0
	v_pk_fma_f32 v[82:83], v[82:83], 2.0, 1.0 op_sel_hi:[1,0,0] neg_lo:[1,0,0] neg_hi:[1,0,0]
	s_nop 0
	v_pk_add_f32 v[82:83], v[82:83], 1.0 op_sel_hi:[1,0]
	s_nop 0
	v_pk_mul_f32 v[66:67], v[66:67], v[82:83]
	s_nop 0
	v_pk_mul_f32 v[66:67], v[80:81], v[66:67]
	s_nop 0
	v_cvt_pk_bf16_f32 v77, v66, v67
	v_add_co_u32_e32 v66, vcc, s23, v176
	s_nop 1
	v_addc_co_u32_e32 v67, vcc, 0, v177, vcc
	global_store_dwordx4 v[66:67], v[74:77], off offset:2048
	v_pk_mul_f32 v[66:67], v[24:25], v[178:179]
	s_nop 0
	v_pk_fma_f32 v[66:67], v[8:9], v[98:99], v[66:67]
	s_nop 0
	v_pk_fma_f32 v[66:67], v[40:41], v[170:171], v[66:67]
	s_nop 0
	v_pk_add_f32 v[66:67], v[56:57], v[66:67]
	s_nop 0
	v_mul_f32_e32 v0, 0x3d372713, v66
	v_mul_f32_e32 v0, v66, v0
	v_fma_f32 v0, v66, v0, v66
	v_mul_f32_e32 v0, 0x3f4c422a, v0
	v_add_f32_e32 v0, v0, v0
	v_mul_f32_e32 v0, 0x3fb8aa3b, v0
	v_exp_f32_e32 v0, v0
	s_nop 0
	v_add_f32_e32 v0, 1.0, v0
	v_rcp_f32_e32 v68, v0
	v_mul_f32_e32 v0, 0x3d372713, v67
	v_mul_f32_e32 v0, v67, v0
	v_fma_f32 v0, v67, v0, v67
	v_mul_f32_e32 v0, 0x3f4c422a, v0
	v_add_f32_e32 v0, v0, v0
	v_mul_f32_e32 v0, 0x3fb8aa3b, v0
	v_exp_f32_e32 v0, v0
	v_pk_mul_f32 v[66:67], v[66:67], 0.5 op_sel_hi:[1,0]
	v_add_f32_e32 v0, 1.0, v0
	v_rcp_f32_e32 v69, v0
	s_nop 0
	v_pk_fma_f32 v[68:69], v[68:69], 2.0, 1.0 op_sel_hi:[1,0,0] neg_lo:[1,0,0] neg_hi:[1,0,0]
	s_nop 0
	v_pk_add_f32 v[68:69], v[68:69], 1.0 op_sel_hi:[1,0]
	s_nop 0
	v_pk_mul_f32 v[66:67], v[66:67], v[68:69]
	v_cvt_pk_bf16_f32 v68, v78, v79
	v_pk_mul_f32 v[72:73], v[72:73], v[66:67]
	v_cvt_pk_bf16_f32 v67, v70, v71
	v_add_co_u32_e32 v70, vcc, 0x62fb000, v176
	v_cvt_pk_bf16_f32 v66, v96, v97
	v_cvt_pk_bf16_f32 v69, v72, v73
	v_addc_co_u32_e32 v71, vcc, 0, v177, vcc
	global_store_dwordx4 v[70:71], v[66:69], off offset:1024
	s_cbranch_scc0 .LBB0_1021
	v_add_u32_e32 v209, s79, v209
	s_movk_i32 s22, 0x15ff
	v_cmp_lt_i32_e32 vcc, s22, v209
	s_or_b64 s[20:21], vcc, s[20:21]
	s_andn2_b64 exec, exec, s[20:21]
	s_cbranch_execnz .LBB0_1018

; DI float bflo(unsigned u) { return __uint_as_float(u << 16); }
; DI float bfhi(unsigned u) { return __uint_as_float(u & 0xffff0000u); }
; DI float wave_sum(float v) { v += __shfl_xor(v, 32); v += __shfl_xor(v, 16); v += __shfl_xor(v, 8); v += __shfl_xor(v, 4); v += __shfl_xor(v, 2); v += __shfl_xor(v, 1); return v; }
; DI void rownorm_phase(const Params& P, const float* xin, const bf16_t* yin, float* xout, bf16_t* hout, int lg, int gate_idx, const float* w_post,
;                       int lh, int scale_idx, int shift_idx, const float* w_pre, char* smem) {
;     ...
;   for (int row = blockIdx.x * 8 + w; row < S_; row += gridDim.x * 8) {
;     f32x4 xv[8];
; #pragma unroll
;     for (int j = 0; j < 8; ++j) xv[j] = __builtin_nontemporal_load((const f32x4*)(xin + (size_t)row * 2048 + (j * 64 + lane) * 4));
;     if (yin) {
;       f32x4 yv[8]; float ss = 0.f;
; #pragma unroll
;       for (int j = 0; j < 8; ++j) { const u32x2 yb = __builtin_nontemporal_load((const u32x2*)(yin + (size_t)row * 2048 + (j * 64 + lane) * 4)); yv[j] = (f32x4){bflo(yb.x), bfhi(yb.x), bflo(yb.y), bfhi(yb.y)};
;         ss += yv[j].x * yv[j].x + yv[j].y * yv[j].y + yv[j].z * yv[j].z + yv[j].w * yv[j].w; }
;       ss = wave_sum(ss); const float r = rsqrtf(ss * (1.f / 2048.f) + EPS);
; #pragma unroll
;       for (int j = 0; j < 8; ++j) { const f32x4 a = *(const f32x4*)(A1 + (j * 64 + lane) * 4); xv[j] += a * (yv[j] * r); }
.LBB0_1157:
	v_ashrrev_i32_e32 v37, 31, v36
	v_lshlrev_b64 v[2:3], 13, v[36:37]
	v_lshl_add_u64 v[2:3], v[34:35], 0, v[2:3]
	v_lshlrev_b64 v[58:59], 12, v[36:37]
	v_lshl_add_u64 v[54:55], v[2:3], 0, v[0:1]
	v_lshl_add_u64 v[82:83], v[38:39], 0, v[58:59]
	global_load_dwordx4 v[30:33], v[54:55], off nt
	global_load_dwordx4 v[26:29], v[54:55], off offset:1024 nt
	global_load_dwordx4 v[22:25], v[54:55], off offset:2048 nt
	global_load_dwordx4 v[18:21], v[54:55], off offset:3072 nt
	global_load_dwordx2 v[58:59], v[82:83], off nt
	v_mov_b32_e32 v41, v1
	v_mov_b32_e32 v43, v1
	v_mov_b32_e32 v45, v1
	v_mov_b32_e32 v47, v1
	v_lshl_add_u64 v[56:57], v[2:3], 0, v[40:41]
	v_lshl_add_u64 v[50:51], v[2:3], 0, v[42:43]
	v_lshl_add_u64 v[48:49], v[2:3], 0, v[44:45]
	v_lshl_add_u64 v[52:53], v[2:3], 0, v[46:47]
	global_load_dwordx4 v[14:17], v[56:57], off nt
	global_load_dwordx4 v[2:5], v[52:53], off nt
	global_load_dwordx4 v[10:13], v[50:51], off nt
	global_load_dwordx4 v[6:9], v[48:49], off nt
	v_add_u32_e32 v36, s79, v36
	s_waitcnt vmcnt(0)
	v_lshlrev_b32_e32 v66, 16, v58
	v_and_b32_e32 v67, 0xffff0000, v58
	v_lshlrev_b32_e32 v68, 16, v59
	v_and_b32_e32 v69, 0xffff0000, v59
	global_load_dwordx2 v[58:59], v[82:83], off offset:512 nt
	v_mul_f32_e32 v37, v67, v67
	v_fmac_f32_e32 v37, v66, v66
	v_fmac_f32_e32 v37, v68, v68
	v_fmac_f32_e32 v37, v69, v69
	s_waitcnt vmcnt(0)
	v_lshlrev_b32_e32 v70, 16, v58
	v_and_b32_e32 v71, 0xffff0000, v58
	v_lshlrev_b32_e32 v72, 16, v59
	v_and_b32_e32 v73, 0xffff0000, v59
	global_load_dwordx2 v[58:59], v[82:83], off offset:1024 nt
	v_mul_f32_e32 v41, v71, v71
	v_fmac_f32_e32 v41, v70, v70
	v_fmac_f32_e32 v41, v72, v72
	v_fmac_f32_e32 v41, v73, v73
	v_add_f32_e32 v37, v37, v41
	s_waitcnt vmcnt(0)
	v_lshlrev_b32_e32 v74, 16, v58
	v_and_b32_e32 v75, 0xffff0000, v58
	v_lshlrev_b32_e32 v76, 16, v59
	v_and_b32_e32 v77, 0xffff0000, v59
	global_load_dwordx2 v[58:59], v[82:83], off offset:1536 nt
	global_load_dwordx2 v[84:85], v[82:83], off offset:2048 nt
	global_load_dwordx2 v[62:63], v[82:83], off offset:2560 nt
	global_load_dwordx2 v[98:99], v[82:83], off offset:3072 nt
	global_load_dwordx2 v[88:89], v[82:83], off offset:3584 nt
	v_mul_f32_e32 v41, v75, v75
	v_fmac_f32_e32 v41, v74, v74
	v_fmac_f32_e32 v41, v76, v76
	v_fmac_f32_e32 v41, v77, v77
	v_add_f32_e32 v37, v37, v41
	s_waitcnt vmcnt(0)
	v_lshlrev_b32_e32 v60, 16, v84
	v_and_b32_e32 v79, 0xffff0000, v58
	v_lshlrev_b32_e32 v78, 16, v58
	v_lshlrev_b32_e32 v80, 16, v59
	v_and_b32_e32 v81, 0xffff0000, v59
	v_mul_f32_e32 v41, v79, v79
	v_and_b32_e32 v59, 0xffff0000, v62
	v_and_b32_e32 v58, 0xffff0000, v84
	v_fmac_f32_e32 v41, v78, v78
	v_lshlrev_b32_e32 v61, 16, v62
	v_lshlrev_b32_e32 v64, 16, v85
	v_and_b32_e32 v62, 0xffff0000, v85
	v_pk_mul_f32 v[84:85], v[58:59], v[58:59]
	v_fmac_f32_e32 v41, v80, v80
	v_lshlrev_b32_e32 v65, 16, v63
	v_pk_fma_f32 v[84:85], v[60:61], v[60:61], v[84:85]
	v_fmac_f32_e32 v41, v81, v81
	v_and_b32_e32 v63, 0xffff0000, v63
	v_pk_fma_f32 v[84:85], v[64:65], v[64:65], v[84:85]
	v_add_f32_e32 v37, v37, v41
	v_pk_fma_f32 v[84:85], v[62:63], v[62:63], v[84:85]
	v_lshlrev_b32_e32 v83, 16, v88
	v_add_f32_e32 v37, v37, v84
	v_add_f32_e32 v37, v37, v85
	v_and_b32_e32 v85, 0xffff0000, v88
	v_and_b32_e32 v84, 0xffff0000, v98
	v_lshlrev_b32_e32 v82, 16, v98
	v_lshlrev_b32_e32 v86, 16, v99
	v_and_b32_e32 v88, 0xffff0000, v99
	v_pk_mul_f32 v[98:99], v[84:85], v[84:85]
	v_lshlrev_b32_e32 v87, 16, v89
	v_pk_fma_f32 v[98:99], v[82:83], v[82:83], v[98:99]
	v_and_b32_e32 v89, 0xffff0000, v89
	v_pk_fma_f32 v[98:99], v[86:87], v[86:87], v[98:99]
	s_nop 0
	v_pk_fma_f32 v[98:99], v[88:89], v[88:89], v[98:99]
	s_nop 0
	v_add_f32_e32 v37, v37, v98
	v_add_f32_e32 v37, v37, v99
	ds_bpermute_b32 v41, v92, v37
	ds_read_b128 v[98:101], v91
	s_waitcnt lgkmcnt(0)
; DI float wave_sum(float v) { v += __shfl_xor(v, 32); v += __shfl_xor(v, 16); v += __shfl_xor(v, 8); v += __shfl_xor(v, 4); v += __shfl_xor(v, 2); v += __shfl_xor(v, 1); return v; }
; DI void rownorm_phase(const Params& P, const float* xin, const bf16_t* yin, float* xout, bf16_t* hout, int lg, int gate_idx, const float* w_post,
;                       int lh, int scale_idx, int shift_idx, const float* w_pre, char* smem) {
;     ...
;       ss = wave_sum(ss); const float r = rsqrtf(ss * (1.f / 2048.f) + EPS);
; #pragma unroll
;       for (int j = 0; j < 8; ++j) { const f32x4 a = *(const f32x4*)(A1 + (j * 64 + lane) * 4); xv[j] += a * (yv[j] * r); }
;     }
;     if (yin || xout != xin) {
; #pragma unroll
;       for (int j = 0; j < 8; ++j) __builtin_nontemporal_store(xv[j], (f32x4*)(xout + (size_t)row * 2048 + (j * 64 + lane) * 4));
	v_add_f32_e32 v37, v37, v41
	ds_bpermute_b32 v41, v93, v37
	s_waitcnt lgkmcnt(0)
	v_add_f32_e32 v37, v37, v41
	ds_bpermute_b32 v41, v94, v37
	s_waitcnt lgkmcnt(0)
	v_add_f32_e32 v37, v37, v41
	ds_bpermute_b32 v41, v95, v37
	s_waitcnt lgkmcnt(0)
	v_add_f32_e32 v37, v37, v41
	ds_bpermute_b32 v41, v96, v37
	s_waitcnt lgkmcnt(0)
	v_add_f32_e32 v37, v37, v41
	ds_bpermute_b32 v41, v97, v37
	s_waitcnt lgkmcnt(0)
	v_add_f32_e32 v37, v37, v41
	v_fmamk_f32 v37, v37, 0x3a000000, v245
	v_cmp_gt_f32_e32 vcc, s84, v37
	v_mul_f32_e32 v41, 0x4b800000, v37
	s_nop 0
	v_cndmask_b32_e32 v37, v37, v41, vcc
	v_rsq_f32_e32 v37, v37
	s_nop 0
	v_mul_f32_e32 v41, 0x45800000, v37
	v_cndmask_b32_e32 v90, v37, v41, vcc
	v_pk_mul_f32 v[66:67], v[66:67], v[90:91] op_sel_hi:[1,0]
	v_pk_mul_f32 v[68:69], v[68:69], v[90:91] op_sel_hi:[1,0]
	v_pk_fma_f32 v[30:31], v[98:99], v[66:67], v[30:31]
	v_pk_fma_f32 v[32:33], v[100:101], v[68:69], v[32:33]
	ds_read_b128 v[66:69], v91 offset:1024
	v_pk_mul_f32 v[70:71], v[70:71], v[90:91] op_sel_hi:[1,0]
	v_pk_mul_f32 v[72:73], v[72:73], v[90:91] op_sel_hi:[1,0]
	v_cmp_lt_i32_e32 vcc, s4, v36
	s_or_b64 s[2:3], vcc, s[2:3]
	s_waitcnt lgkmcnt(0)
	v_pk_fma_f32 v[28:29], v[68:69], v[72:73], v[28:29]
	v_pk_fma_f32 v[26:27], v[66:67], v[70:71], v[26:27]
	ds_read_b128 v[66:69], v91 offset:2048
	v_pk_mul_f32 v[70:71], v[74:75], v[90:91] op_sel_hi:[1,0]
	v_pk_mul_f32 v[72:73], v[76:77], v[90:91] op_sel_hi:[1,0]
	s_waitcnt lgkmcnt(0)
	v_pk_fma_f32 v[22:23], v[66:67], v[70:71], v[22:23]
	v_pk_fma_f32 v[24:25], v[68:69], v[72:73], v[24:25]
	ds_read_b128 v[66:69], v91 offset:3072
	v_pk_mul_f32 v[70:71], v[78:79], v[90:91] op_sel_hi:[1,0]
	v_pk_mul_f32 v[72:73], v[80:81], v[90:91] op_sel_hi:[1,0]
	s_waitcnt lgkmcnt(0)
	v_pk_fma_f32 v[18:19], v[66:67], v[70:71], v[18:19]
	v_pk_fma_f32 v[20:21], v[68:69], v[72:73], v[20:21]
	ds_read_b128 v[66:69], v91 offset:4096
	v_mov_b32_e32 v70, v60
	v_mov_b32_e32 v71, v58
	v_mov_b32_e32 v72, v64
	v_mov_b32_e32 v73, v62
	v_pk_mul_f32 v[70:71], v[70:71], v[90:91] op_sel_hi:[1,0]
	v_pk_mul_f32 v[72:73], v[72:73], v[90:91] op_sel_hi:[1,0]
	s_waitcnt lgkmcnt(0)
	v_pk_fma_f32 v[14:15], v[66:67], v[70:71], v[14:15]
	v_pk_fma_f32 v[16:17], v[68:69], v[72:73], v[16:17]
	ds_read_b128 v[66:69], v91 offset:5120
	v_mov_b32_e32 v58, v61
	v_mov_b32_e32 v62, v65
	v_pk_mul_f32 v[58:59], v[58:59], v[90:91] op_sel_hi:[1,0]
	v_pk_mul_f32 v[60:61], v[62:63], v[90:91] op_sel_hi:[1,0]
	s_waitcnt lgkmcnt(0)
	v_pk_fma_f32 v[10:11], v[66:67], v[58:59], v[10:11]
	v_pk_fma_f32 v[12:13], v[68:69], v[60:61], v[12:13]
	ds_read_b128 v[58:61], v91 offset:6144
	v_mov_b32_e32 v62, v82
	v_mov_b32_e32 v63, v84
	v_mov_b32_e32 v64, v86
	v_mov_b32_e32 v65, v88
	v_pk_mul_f32 v[62:63], v[62:63], v[90:91] op_sel_hi:[1,0]
	v_pk_mul_f32 v[64:65], v[64:65], v[90:91] op_sel_hi:[1,0]
	s_waitcnt lgkmcnt(0)
	v_pk_fma_f32 v[6:7], v[58:59], v[62:63], v[6:7]
	v_pk_fma_f32 v[8:9], v[60:61], v[64:65], v[8:9]
	ds_read_b128 v[58:61], v91 offset:7168
	v_mov_b32_e32 v84, v83
	v_mov_b32_e32 v88, v87
	v_pk_mul_f32 v[62:63], v[84:85], v[90:91] op_sel_hi:[1,0]
	v_pk_mul_f32 v[64:65], v[88:89], v[90:91] op_sel_hi:[1,0]
	s_waitcnt lgkmcnt(0)
	v_pk_fma_f32 v[2:3], v[58:59], v[62:63], v[2:3]
	v_pk_fma_f32 v[4:5], v[60:61], v[64:65], v[4:5]
	global_store_dwordx4 v[54:55], v[30:33], off nt
	global_store_dwordx4 v[54:55], v[26:29], off offset:1024 nt
	global_store_dwordx4 v[54:55], v[22:25], off offset:2048 nt
	global_store_dwordx4 v[54:55], v[18:21], off offset:3072 nt
	global_store_dwordx4 v[56:57], v[14:17], off nt
	global_store_dwordx4 v[50:51], v[10:13], off nt
	global_store_dwordx4 v[48:49], v[6:9], off nt
	global_store_dwordx4 v[52:53], v[2:5], off nt
	s_andn2_b64 exec, exec, s[2:3]
	s_cbranch_execnz .LBB0_1157

; DI unsigned pack2(float lo, float hi) { f32x2 v = {lo, hi}; bf2_t b = __builtin_convertvector(v, bf2_t); return __builtin_bit_cast(unsigned, b); }
; DI void convert_tile(const float* __restrict__ src, int K, int N, bf16_t* __restrict__ dst, int tk, int tn, const float* rowscale, char* smem) {
;     ...
;     for (int i = 0; i < 8; ++i) { const int kk = r + 8 * i; if (rowscale) v[i] *= rowscale[k0 + kk];
;       sm[kk * 257 + 4 * c4 + 0] = v[i].x; sm[kk * 257 + 4 * c4 + 1] = v[i].y; sm[kk * 257 + 4 * c4 + 2] = v[i].z; sm[kk * 257 + 4 * c4 + 3] = v[i].w; } }
;   __syncthreads();
;   { const int n = tid >> 1, kh = tid & 1;
; #pragma unroll
;     for (int j = 0; j < 4; ++j) { float f[8];
; #pragma unroll
;       for (int i = 0; i < 8; ++i) f[i] = sm[(32 * kh + 8 * j + i) * 257 + n];
;       u32x4 pk = {pack2(f[0], f[1]), pack2(f[2], f[3]), pack2(f[4], f[5]), pack2(f[6], f[7])};
;       *(u32x4*)(dst + (size_t)(n0 + n) * K + k0 + 32 * kh + 8 * j) = pk; } }
;   __syncthreads();
.LBB0_1162:
	s_or_b64 exec, exec, s[2:3]
	s_movk_i32 s2, 0x404
	v_mul_lo_u32 v36, v38, s2
	v_lshl_add_u32 v36, v39, 2, v36
	s_waitcnt vmcnt(0) lgkmcnt(0)
	ds_write2_b32 v36, v6, v7 offset1:1
	ds_write2_b32 v36, v8, v9 offset0:2 offset1:3
	v_add_u32_e32 v6, 0x2020, v36
	ds_write2_b32 v6, v2, v3 offset1:1
	v_add_u32_e32 v2, 0x2028, v36
	ds_write2_b32 v2, v4, v5 offset1:1
	v_add_u32_e32 v2, 0x4040, v36
	ds_write2_b32 v2, v14, v15 offset1:1
	v_add_u32_e32 v2, 0x4048, v36
	ds_write2_b32 v2, v16, v17 offset1:1
	v_add_u32_e32 v2, 0x6060, v36
	ds_write2_b32 v2, v10, v11 offset1:1
	v_add_u32_e32 v2, 0x6068, v36
	ds_write2_b32 v2, v12, v13 offset1:1
	v_add_u32_e32 v2, 0x8080, v36
	ds_write2_b32 v2, v22, v23 offset1:1
	v_add_u32_e32 v2, 0x8088, v36
	ds_write2_b32 v2, v24, v25 offset1:1
	v_add_u32_e32 v2, 0xa0a0, v36
	ds_write2_b32 v2, v18, v19 offset1:1
	v_add_u32_e32 v2, 0xa0a8, v36
	ds_write2_b32 v2, v20, v21 offset1:1
	v_add_u32_e32 v2, 0xc0c0, v36
	ds_write2_b32 v2, v30, v31 offset1:1
	v_add_u32_e32 v2, 0xc0c8, v36
	ds_write2_b32 v2, v32, v33 offset1:1
	v_add_u32_e32 v2, 0xe0e0, v36
	v_ashrrev_i32_e32 v4, 1, v0
	v_lshlrev_b32_e32 v0, 5, v0
	ds_write2_b32 v2, v26, v27 offset1:1
	v_add_u32_e32 v2, 0xe0e8, v36
	v_and_b32_e32 v5, 32, v0
	v_subrev_u32_e32 v0, s1, v4
	ds_write2_b32 v2, v28, v29 offset1:1
	v_add_u32_e32 v2, s12, v0
	v_ashrrev_i32_e32 v3, 31, v2
	v_lshlrev_b64 v[2:3], 12, v[2:3]
	v_lshl_add_u64 v[2:3], v[34:35], 0, v[2:3]
	s_ashr_i32 s1, s0, 31
	v_lshl_add_u64 v[2:3], s[0:1], 1, v[2:3]
	v_lshlrev_b32_e32 v0, 1, v5
	v_lshl_add_u64 v[6:7], v[2:3], 0, v[0:1]
	v_mul_u32_u24_e32 v0, 0x404, v5
	v_lshl_add_u32 v0, v4, 2, v0
	s_waitcnt lgkmcnt(0)
	s_barrier
	ds_read_b32 v2, v0
	ds_read_b32 v3, v0 offset:1028
	ds_read_b32 v4, v0 offset:2056
	ds_read_b32 v5, v0 offset:3084
	ds_read_b32 v10, v0 offset:4112
	ds_read_b32 v11, v0 offset:5140
	ds_read_b32 v12, v0 offset:6168
	ds_read_b32 v13, v0 offset:7196
	s_mov_b64 s[0:1], 0x200000
	v_lshl_add_u64 v[8:9], v[6:7], 0, s[0:1]
	s_mov_b32 s0, 0x200000
	s_waitcnt lgkmcnt(6)
	v_cvt_pk_bf16_f32 v2, v2, v3
	s_waitcnt lgkmcnt(4)
	v_cvt_pk_bf16_f32 v3, v4, v5
	s_waitcnt lgkmcnt(2)
	v_cvt_pk_bf16_f32 v4, v10, v11
	s_waitcnt lgkmcnt(0)
	v_cvt_pk_bf16_f32 v5, v12, v13
	v_add_co_u32_e32 v6, vcc, s0, v6
	ds_read_b32 v10, v0 offset:8224
	ds_read_b32 v11, v0 offset:9252
	ds_read_b32 v12, v0 offset:10280
	ds_read_b32 v13, v0 offset:11308
	ds_read_b32 v14, v0 offset:12336
	ds_read_b32 v15, v0 offset:13364
	ds_read_b32 v16, v0 offset:14392
	ds_read_b32 v17, v0 offset:15420
	v_addc_co_u32_e32 v7, vcc, 0, v7, vcc
	global_store_dwordx4 v[6:7], v[2:5], off
	s_waitcnt lgkmcnt(0)
	s_nop 0
	v_cvt_pk_bf16_f32 v2, v10, v11
	v_cvt_pk_bf16_f32 v3, v12, v13
	v_cvt_pk_bf16_f32 v4, v14, v15
	ds_read_b32 v6, v0 offset:16448
	ds_read_b32 v7, v0 offset:17476
	ds_read_b32 v10, v0 offset:18504
	ds_read_b32 v11, v0 offset:19532
	ds_read_b32 v12, v0 offset:20560
	ds_read_b32 v13, v0 offset:21588
	ds_read_b32 v14, v0 offset:22616
	ds_read_b32 v15, v0 offset:23644
	v_cvt_pk_bf16_f32 v5, v16, v17
	global_store_dwordx4 v[8:9], v[2:5], off offset:16
	s_waitcnt lgkmcnt(0)
	s_nop 0
	v_cvt_pk_bf16_f32 v2, v6, v7
	v_cvt_pk_bf16_f32 v3, v10, v11
	v_cvt_pk_bf16_f32 v4, v12, v13
	v_cvt_pk_bf16_f32 v5, v14, v15
	ds_read_b32 v6, v0 offset:24672
	ds_read_b32 v7, v0 offset:25700
	ds_read_b32 v10, v0 offset:26728
	ds_read_b32 v11, v0 offset:27756
	ds_read_b32 v12, v0 offset:28784
	ds_read_b32 v13, v0 offset:29812
	ds_read_b32 v14, v0 offset:30840
	ds_read_b32 v0, v0 offset:31868
	global_store_dwordx4 v[8:9], v[2:5], off offset:32
	s_waitcnt lgkmcnt(0)
	s_nop 0
	v_cvt_pk_bf16_f32 v2, v6, v7
	v_cvt_pk_bf16_f32 v3, v10, v11
	v_cvt_pk_bf16_f32 v4, v12, v13
	v_cvt_pk_bf16_f32 v5, v14, v0
	global_store_dwordx4 v[8:9], v[2:5], off offset:48
	s_waitcnt lgkmcnt(0)
	s_barrier

; DI int opaque_tid() { int t = threadIdx.x; asm volatile("" : "+v"(t)); return t; }
; DI void convert_tile(const float* __restrict__ src, int K, int N, bf16_t* __restrict__ dst, int tk, int tn, const float* rowscale, char* smem) {
;   float* sm = (float*)smem; const int tid = opaque_tid(); const int k0 = tk * 64, n0 = tn * 256;
;   { const int r = tid >> 6, c4 = tid & 63; const int n = n0 + 4 * c4;
;     f32x4 v[8];
; #pragma unroll
;     for (int i = 0; i < 8; ++i) { v[i] = (f32x4){0.f, 0.f, 0.f, 0.f}; if (n < N) v[i] = __builtin_nontemporal_load((const f32x4*)(src + (size_t)(k0 + r + 8 * i) * N + n)); }
; #pragma unroll
;     for (int i = 0; i < 8; ++i) { const int kk = r + 8 * i; if (rowscale) v[i] *= rowscale[k0 + kk];
;       sm[kk * 257 + 4 * c4 + 0] = v[i].x; sm[kk * 257 + 4 * c4 + 1] = v[i].y; sm[kk * 257 + 4 * c4 + 2] = v[i].z; sm[kk * 257 + 4 * c4 + 3] = v[i].w; } }
; DI void convert_item(const Params& P, int l, int it, char* smem) {
;   char* wb = P.ws + OFF_W;
;   if (it < CV_T0) convert_tile(P.w_in + (size_t)l * 2048 * 5520, 2048, 5520, (bf16_t*)(wb + W_IN), it / 22, it % 22, nullptr, smem);
;   else if (it < CV_T1) { it -= CV_T0; convert_tile(P.w_out + (size_t)l * 2048 * 2048, 2048, 2048, (bf16_t*)(wb + W_OUT), it / 8, it % 8, nullptr, smem); }
;   else if (it < CV_T2) { it -= CV_T1; convert_tile(P.ffn_w_up + (size_t)l * 2048 * 11264, 2048, 11264, (bf16_t*)(wb + W_UP), it / 44, it % 44, nullptr, smem); }
;   else if (it < CV_T3) { it -= CV_T2; convert_tile(P.ffn_w_down + (size_t)l * 5632 * 2048, 5632, 2048, (bf16_t*)(wb + W_DOWN), it / 8, it % 8, nullptr, smem); }
;   else if (it < CV_T4) { it -= CV_T3; convert_tile(P.mla_w_uq + (size_t)l * 448 * 768, 448, 768, (bf16_t*)(wb + W_UQ), it / 3, it % 3, P.mla_q_norm + l * 448, smem); }
;   else { it -= CV_T4; convert_tile(P.mla_w_ukv + (size_t)l * 128 * 1024, 128, 1024, (bf16_t*)(wb + W_UKV), it / 4, it % 4, P.mla_kv_norm + l * 128, smem); }
.LBB0_1164:
	global_load_dwordx2 v[34:35], v1, s[40:41] offset:1224
	s_cmpk_gt_i32 s13, 0x2bf
	s_mov_b64 s[0:1], -1
	s_cbranch_scc0 .LBB0_1213
	s_cmpk_gt_u32 s13, 0x3bf
	s_cbranch_scc0 .LBB0_1210
	s_cmpk_gt_u32 s13, 0x93f
	s_cbranch_scc0 .LBB0_1207
	s_cmpk_gt_u32 s13, 0xbff
	s_cbranch_scc0 .LBB0_1204
	s_cmpk_gt_u32 s13, 0xc14
	s_cbranch_scc0 .LBB0_1186
	global_load_dwordx4 v[42:45], v1, s[40:41] offset:1144
	v_mov_b32_e32 v38, v206
	s_add_i32 s1, s12, 0xfff3eb00
	s_and_b32 s0, s11, 0x7fffffc0
	v_lshlrev_b32_e32 v0, 2, v38
	s_and_b32 s1, s1, 0x300
	v_ashrrev_i32_e32 v39, 6, v38
	v_and_b32_e32 v40, 0xfc, v0
	v_add_u32_e32 v36, s0, v39
	v_or_b32_e32 v0, s1, v40
	v_ashrrev_i32_e32 v37, 31, v36
	v_lshlrev_b32_e32 v0, 2, v0
	v_lshlrev_b64 v[2:3], 12, v[36:37]
	s_mov_b32 s2, 0x88000
	s_waitcnt vmcnt(0)
	v_lshl_add_u64 v[4:5], v[44:45], 0, v[0:1]
	v_lshl_add_u64 v[2:3], v[4:5], 0, v[2:3]
	v_add_co_u32_e32 v4, vcc, s43, v2
	v_cmp_ne_u64_e64 s[4:5], 0, v[42:43]
	s_nop 0
	v_addc_co_u32_e32 v5, vcc, 0, v3, vcc
	v_add_co_u32_e32 v6, vcc, s2, v2
	s_mov_b32 s2, 0x90000
	s_nop 0
	v_addc_co_u32_e32 v7, vcc, 0, v3, vcc
	v_add_co_u32_e32 v8, vcc, s2, v2
	global_load_dwordx4 v[30:33], v[4:5], off nt
	global_load_dwordx4 v[26:29], v[6:7], off nt
	v_addc_co_u32_e32 v9, vcc, 0, v3, vcc
	v_add_co_u32_e32 v4, vcc, 0x98000, v2
	v_lshl_add_u64 v[36:37], v[36:37], 2, v[42:43]
	s_nop 0
	v_addc_co_u32_e32 v5, vcc, 0, v3, vcc
	v_add_co_u32_e32 v6, vcc, 0xa0000, v2
	global_load_dwordx4 v[22:25], v[8:9], off nt
	global_load_dwordx4 v[18:21], v[4:5], off nt
	v_addc_co_u32_e32 v7, vcc, 0, v3, vcc
	v_add_co_u32_e32 v4, vcc, 0xa8000, v2
	s_nop 1
	v_addc_co_u32_e32 v5, vcc, 0, v3, vcc
	v_add_co_u32_e32 v8, vcc, 0xb0000, v2
	global_load_dwordx4 v[14:17], v[6:7], off nt
	global_load_dwordx4 v[10:13], v[4:5], off nt
	v_addc_co_u32_e32 v9, vcc, 0, v3, vcc
	v_add_co_u32_e32 v2, vcc, 0xb8000, v2
	s_nop 1
	v_addc_co_u32_e32 v3, vcc, 0, v3, vcc
	global_load_dwordx4 v[6:9], v[8:9], off nt
	s_nop 0
	global_load_dwordx4 v[2:5], v[2:3], off nt
	v_cmp_eq_u64_e32 vcc, 0, v[42:43]
	s_cbranch_vccnz .LBB0_1171
	global_load_dword v0, v[36:37], off offset:512
	s_waitcnt vmcnt(0) lgkmcnt(0)
	v_pk_mul_f32 v[32:33], v[32:33], v[0:1] op_sel_hi:[1,0]
	v_pk_mul_f32 v[30:31], v[30:31], v[0:1] op_sel_hi:[1,0]
.LBB0_1171:
	s_movk_i32 s2, 0x404
	v_lshlrev_b32_e32 v0, 2, v40
	v_mul_lo_u32 v39, v39, s2
	v_add_u32_e32 v0, v0, v39
	s_waitcnt vmcnt(0) lgkmcnt(0)
	ds_write2_b32 v0, v30, v31 offset1:1
	v_cndmask_b32_e64 v30, 0, 1, s[4:5]
	v_cmp_ne_u32_e64 s[2:3], 1, v30
	s_andn2_b64 vcc, exec, s[4:5]
	ds_write2_b32 v0, v32, v33 offset0:2 offset1:3
	s_cbranch_vccnz .LBB0_1173
	global_load_dword v30, v[36:37], off offset:544
	s_waitcnt vmcnt(0) lgkmcnt(0)
	v_pk_mul_f32 v[28:29], v[28:29], v[30:31] op_sel_hi:[1,0]
	v_pk_mul_f32 v[26:27], v[26:27], v[30:31] op_sel_hi:[1,0]
.LBB0_1173:
	v_add_u32_e32 v30, 0x2020, v0
	ds_write2_b32 v30, v26, v27 offset1:1
	v_add_u32_e32 v26, 0x2028, v0
	s_and_b64 vcc, exec, s[2:3]
	ds_write2_b32 v26, v28, v29 offset1:1
	s_cbranch_vccnz .LBB0_1175
	global_load_dword v26, v[36:37], off offset:576
	s_waitcnt vmcnt(0) lgkmcnt(0)
	v_pk_mul_f32 v[24:25], v[24:25], v[26:27] op_sel_hi:[1,0]
	v_pk_mul_f32 v[22:23], v[22:23], v[26:27] op_sel_hi:[1,0]
.LBB0_1175:
	v_add_u32_e32 v26, 0x4040, v0
	ds_write2_b32 v26, v22, v23 offset1:1
	v_add_u32_e32 v22, 0x4048, v0
	s_and_b64 vcc, exec, s[2:3]
	ds_write2_b32 v22, v24, v25 offset1:1
	s_cbranch_vccnz .LBB0_1177
	global_load_dword v22, v[36:37], off offset:608
	s_waitcnt vmcnt(0) lgkmcnt(0)
	v_pk_mul_f32 v[20:21], v[20:21], v[22:23] op_sel_hi:[1,0]
	v_pk_mul_f32 v[18:19], v[18:19], v[22:23] op_sel_hi:[1,0]
.LBB0_1177:
	v_add_u32_e32 v22, 0x6060, v0
	ds_write2_b32 v22, v18, v19 offset1:1
	v_add_u32_e32 v18, 0x6068, v0
	s_and_b64 vcc, exec, s[2:3]
	ds_write2_b32 v18, v20, v21 offset1:1
	s_cbranch_vccnz .LBB0_1179
	global_load_dword v18, v[36:37], off offset:640
	s_waitcnt vmcnt(0) lgkmcnt(0)
	v_pk_mul_f32 v[16:17], v[16:17], v[18:19] op_sel_hi:[1,0]
	v_pk_mul_f32 v[14:15], v[14:15], v[18:19] op_sel_hi:[1,0]
.LBB0_1179:
	v_add_u32_e32 v18, 0x8080, v0
	ds_write2_b32 v18, v14, v15 offset1:1
	v_add_u32_e32 v14, 0x8088, v0
	s_and_b64 vcc, exec, s[2:3]
	ds_write2_b32 v14, v16, v17 offset1:1
	s_cbranch_vccnz .LBB0_1181
	global_load_dword v14, v[36:37], off offset:672
	s_waitcnt vmcnt(0) lgkmcnt(0)
	v_pk_mul_f32 v[12:13], v[12:13], v[14:15] op_sel_hi:[1,0]
	v_pk_mul_f32 v[10:11], v[10:11], v[14:15] op_sel_hi:[1,0]
.LBB0_1181:
	v_add_u32_e32 v14, 0xa0a0, v0
	ds_write2_b32 v14, v10, v11 offset1:1
	v_add_u32_e32 v10, 0xa0a8, v0
	s_and_b64 vcc, exec, s[2:3]
	ds_write2_b32 v10, v12, v13 offset1:1
	s_cbranch_vccnz .LBB0_1183
	global_load_dword v10, v[36:37], off offset:704
	s_waitcnt vmcnt(0) lgkmcnt(0)
	v_pk_mul_f32 v[8:9], v[8:9], v[10:11] op_sel_hi:[1,0]
	v_pk_mul_f32 v[6:7], v[6:7], v[10:11] op_sel_hi:[1,0]
.LBB0_1183:
	v_add_u32_e32 v10, 0xc0c0, v0
	ds_write2_b32 v10, v6, v7 offset1:1
	v_add_u32_e32 v6, 0xc0c8, v0
	s_and_b64 vcc, exec, s[2:3]
	ds_write2_b32 v6, v8, v9 offset1:1
	s_cbranch_vccnz .LBB0_1185
	global_load_dword v6, v[36:37], off offset:736
	s_waitcnt vmcnt(0) lgkmcnt(0)
	v_pk_mul_f32 v[4:5], v[4:5], v[6:7] op_sel_hi:[1,0]
	v_pk_mul_f32 v[2:3], v[2:3], v[6:7] op_sel_hi:[1,0]
; DI unsigned pack2(float lo, float hi) { f32x2 v = {lo, hi}; bf2_t b = __builtin_convertvector(v, bf2_t); return __builtin_bit_cast(unsigned, b); }
; DI int opaque_tid() { int t = threadIdx.x; asm volatile("" : "+v"(t)); return t; }
; DI void convert_tile(const float* __restrict__ src, int K, int N, bf16_t* __restrict__ dst, int tk, int tn, const float* rowscale, char* smem) {
;   float* sm = (float*)smem; const int tid = opaque_tid(); const int k0 = tk * 64, n0 = tn * 256;
;   { const int r = tid >> 6, c4 = tid & 63; const int n = n0 + 4 * c4;
;     f32x4 v[8];
; #pragma unroll
;     for (int i = 0; i < 8; ++i) { v[i] = (f32x4){0.f, 0.f, 0.f, 0.f}; if (n < N) v[i] = __builtin_nontemporal_load((const f32x4*)(src + (size_t)(k0 + r + 8 * i) * N + n)); }
; #pragma unroll
;     for (int i = 0; i < 8; ++i) { const int kk = r + 8 * i; if (rowscale) v[i] *= rowscale[k0 + kk];
;       sm[kk * 257 + 4 * c4 + 0] = v[i].x; sm[kk * 257 + 4 * c4 + 1] = v[i].y; sm[kk * 257 + 4 * c4 + 2] = v[i].z; sm[kk * 257 + 4 * c4 + 3] = v[i].w; } }
;   __syncthreads();
;   { const int n = tid >> 1, kh = tid & 1;
; #pragma unroll
;     for (int j = 0; j < 4; ++j) { float f[8];
; #pragma unroll
;       for (int i = 0; i < 8; ++i) f[i] = sm[(32 * kh + 8 * j + i) * 257 + n];
;       u32x4 pk = {pack2(f[0], f[1]), pack2(f[2], f[3]), pack2(f[4], f[5]), pack2(f[6], f[7])};
;       *(u32x4*)(dst + (size_t)(n0 + n) * K + k0 + 32 * kh + 8 * j) = pk; } }
; DI void convert_item(const Params& P, int l, int it, char* smem) {
;     ...
;   else if (it < CV_T4) { it -= CV_T3; convert_tile(P.mla_w_uq + (size_t)l * 448 * 768, 448, 768, (bf16_t*)(wb + W_UQ), it / 3, it % 3, P.mla_q_norm + l * 448, smem); }
.LBB0_1185:
	v_add_u32_e32 v6, 0xe0e0, v0
	v_add_u32_e32 v0, 0xe0e8, v0
	ds_write2_b32 v0, v4, v5 offset1:1
	v_ashrrev_i32_e32 v4, 1, v38
	ds_write2_b32 v6, v2, v3 offset1:1
	v_add_u32_e32 v2, s1, v4
	v_ashrrev_i32_e32 v3, 31, v2
	v_lshlrev_b32_e32 v0, 5, v38
	v_lshlrev_b64 v[2:3], 8, v[2:3]
	v_and_b32_e32 v5, 32, v0
	v_lshl_add_u64 v[2:3], v[34:35], 0, v[2:3]
	s_lshl_b32 s62, s0, 1
	v_lshl_add_u64 v[2:3], v[2:3], 0, s[62:63]
	v_lshlrev_b32_e32 v0, 1, v5
	v_lshl_add_u64 v[6:7], v[2:3], 0, v[0:1]
	v_mul_u32_u24_e32 v0, 0x404, v5
	v_lshl_add_u32 v0, v4, 2, v0
	s_waitcnt lgkmcnt(0)
	s_barrier
	ds_read_b32 v2, v0
	ds_read_b32 v3, v0 offset:1028
	ds_read_b32 v4, v0 offset:2056
	ds_read_b32 v5, v0 offset:3084
	ds_read_b32 v10, v0 offset:4112
	ds_read_b32 v11, v0 offset:5140
	ds_read_b32 v12, v0 offset:6168
	ds_read_b32 v13, v0 offset:7196
	s_mov_b64 s[0:1], 0x62a8000
	v_lshl_add_u64 v[8:9], v[6:7], 0, s[0:1]
	s_mov_b32 s0, 0x62a8000
	v_add_co_u32_e32 v6, vcc, s0, v6
	s_waitcnt lgkmcnt(6)
	v_cvt_pk_bf16_f32 v2, v2, v3
	s_waitcnt lgkmcnt(4)
	v_cvt_pk_bf16_f32 v3, v4, v5
	s_waitcnt lgkmcnt(2)
	v_cvt_pk_bf16_f32 v4, v10, v11
	s_waitcnt lgkmcnt(0)
	v_cvt_pk_bf16_f32 v5, v12, v13
	v_addc_co_u32_e32 v7, vcc, 0, v7, vcc
	global_store_dwordx4 v[6:7], v[2:5], off
	ds_read_b32 v2, v0 offset:8224
	ds_read_b32 v3, v0 offset:9252
	ds_read_b32 v4, v0 offset:10280
	ds_read_b32 v5, v0 offset:11308
	ds_read_b32 v6, v0 offset:12336
	ds_read_b32 v7, v0 offset:13364
	ds_read_b32 v10, v0 offset:14392
	ds_read_b32 v11, v0 offset:15420
	s_waitcnt lgkmcnt(0)
	v_cvt_pk_bf16_f32 v2, v2, v3
	v_cvt_pk_bf16_f32 v3, v4, v5
	v_cvt_pk_bf16_f32 v4, v6, v7
	s_mov_b64 s[0:1], 0
	v_cvt_pk_bf16_f32 v5, v10, v11
	global_store_dwordx4 v[8:9], v[2:5], off offset:16
	ds_read_b32 v2, v0 offset:16448
	ds_read_b32 v3, v0 offset:17476
	ds_read_b32 v4, v0 offset:18504
	ds_read_b32 v5, v0 offset:19532
	ds_read_b32 v6, v0 offset:20560
	ds_read_b32 v7, v0 offset:21588
	ds_read_b32 v10, v0 offset:22616
	ds_read_b32 v11, v0 offset:23644
	s_waitcnt lgkmcnt(0)
	v_cvt_pk_bf16_f32 v2, v2, v3
	v_cvt_pk_bf16_f32 v3, v4, v5
	v_cvt_pk_bf16_f32 v4, v6, v7
	v_cvt_pk_bf16_f32 v5, v10, v11
	global_store_dwordx4 v[8:9], v[2:5], off offset:32
	ds_read_b32 v2, v0 offset:24672
	ds_read_b32 v3, v0 offset:25700
	ds_read_b32 v4, v0 offset:26728
	ds_read_b32 v5, v0 offset:27756
	ds_read_b32 v6, v0 offset:28784
	ds_read_b32 v7, v0 offset:29812
	ds_read_b32 v10, v0 offset:30840
	ds_read_b32 v0, v0 offset:31868
	s_waitcnt lgkmcnt(0)
	v_cvt_pk_bf16_f32 v2, v2, v3
	v_cvt_pk_bf16_f32 v3, v4, v5
	v_cvt_pk_bf16_f32 v4, v6, v7
	v_cvt_pk_bf16_f32 v5, v10, v0
	global_store_dwordx4 v[8:9], v[2:5], off offset:48
	s_waitcnt lgkmcnt(0)
	s_barrier
.LBB0_1186:
	s_and_b64 vcc, exec, s[0:1]
	s_cbranch_vccz .LBB0_1230
	global_load_dwordx4 v[42:45], v1, s[40:41] offset:1128
	s_and_b32 s0, s13, 0xff
	s_mulk_i32 s0, 0xab
	s_lshr_b32 s0, s0, 9
	s_mul_i32 s1, s0, 3
	v_mov_b32_e32 v38, v206
	s_sub_i32 s1, s13, s1
	s_and_b32 s1, s1, 0xff
	v_lshlrev_b32_e32 v0, 2, v38
	v_and_b32_e32 v40, 0xfc, v0
	s_lshl_b32 s1, s1, 8
	v_or_b32_e32 v0, s1, v40
	v_ashrrev_i32_e32 v39, 6, v38
	s_lshl_b32 s0, s0, 6
	v_lshlrev_b32_e32 v0, 2, v0
	v_add_u32_e32 v36, s0, v39
	s_mov_b64 s[2:3], 0x150000
	v_add_u32_e32 v6, 8, v36
	v_add_u32_e32 v8, 16, v36
	v_add_u32_e32 v10, 24, v36
	v_add_u32_e32 v12, 32, v36
	v_add_u32_e32 v14, 40, v36
	v_add_u32_e32 v15, 48, v36
	v_add_u32_e32 v16, 56, v36
	s_movk_i32 s4, 0xc00
	v_ashrrev_i32_e32 v37, 31, v36
	s_waitcnt vmcnt(0)
	v_lshl_add_u64 v[2:3], v[44:45], 0, v[0:1]
	v_lshl_add_u64 v[2:3], v[2:3], 0, s[2:3]
	v_mad_i64_i32 v[4:5], s[2:3], v36, s4, v[2:3]
	v_mad_i64_i32 v[6:7], s[2:3], v6, s4, v[2:3]
	v_mad_i64_i32 v[8:9], s[2:3], v8, s4, v[2:3]
	v_mad_i64_i32 v[10:11], s[2:3], v10, s4, v[2:3]
	v_mad_i64_i32 v[12:13], s[2:3], v12, s4, v[2:3]
	v_mad_i64_i32 v[44:45], s[2:3], v14, s4, v[2:3]
	v_mad_i64_i32 v[46:47], s[2:3], v15, s4, v[2:3]
	v_mad_i64_i32 v[2:3], s[2:3], v16, s4, v[2:3]
	global_load_dwordx4 v[30:33], v[4:5], off nt
	global_load_dwordx4 v[26:29], v[6:7], off nt
	global_load_dwordx4 v[22:25], v[8:9], off nt
	global_load_dwordx4 v[18:21], v[10:11], off nt
	global_load_dwordx4 v[14:17], v[12:13], off nt
	s_nop 0
	global_load_dwordx4 v[10:13], v[44:45], off nt
	global_load_dwordx4 v[6:9], v[46:47], off nt
	s_nop 0
	global_load_dwordx4 v[2:5], v[2:3], off nt
	v_cmp_eq_u64_e32 vcc, 0, v[42:43]
	v_cmp_ne_u64_e64 s[4:5], 0, v[42:43]
	v_lshl_add_u64 v[36:37], v[36:37], 2, v[42:43]
	s_cbranch_vccnz .LBB0_1189
	global_load_dword v0, v[36:37], off offset:1792
	s_waitcnt vmcnt(0) lgkmcnt(0)
	v_pk_mul_f32 v[32:33], v[32:33], v[0:1] op_sel_hi:[1,0]
	v_pk_mul_f32 v[30:31], v[30:31], v[0:1] op_sel_hi:[1,0]
.LBB0_1189:
	s_movk_i32 s2, 0x404
	v_lshlrev_b32_e32 v0, 2, v40
	v_mul_lo_u32 v39, v39, s2
	v_add_u32_e32 v0, v0, v39
	s_waitcnt vmcnt(0) lgkmcnt(0)
	ds_write2_b32 v0, v30, v31 offset1:1
	v_cndmask_b32_e64 v30, 0, 1, s[4:5]
	v_cmp_ne_u32_e64 s[2:3], 1, v30
	s_andn2_b64 vcc, exec, s[4:5]
	ds_write2_b32 v0, v32, v33 offset0:2 offset1:3
	s_cbranch_vccnz .LBB0_1191
	global_load_dword v30, v[36:37], off offset:1824
	s_waitcnt vmcnt(0) lgkmcnt(0)
	v_pk_mul_f32 v[28:29], v[28:29], v[30:31] op_sel_hi:[1,0]
	v_pk_mul_f32 v[26:27], v[26:27], v[30:31] op_sel_hi:[1,0]
; DI unsigned pack2(float lo, float hi) { f32x2 v = {lo, hi}; bf2_t b = __builtin_convertvector(v, bf2_t); return __builtin_bit_cast(unsigned, b); }
; DI void convert_tile(const float* __restrict__ src, int K, int N, bf16_t* __restrict__ dst, int tk, int tn, const float* rowscale, char* smem) {
;     ...
;     for (int i = 0; i < 8; ++i) { const int kk = r + 8 * i; if (rowscale) v[i] *= rowscale[k0 + kk];
;       sm[kk * 257 + 4 * c4 + 0] = v[i].x; sm[kk * 257 + 4 * c4 + 1] = v[i].y; sm[kk * 257 + 4 * c4 + 2] = v[i].z; sm[kk * 257 + 4 * c4 + 3] = v[i].w; } }
;   __syncthreads();
;   { const int n = tid >> 1, kh = tid & 1;
; #pragma unroll
;     for (int j = 0; j < 4; ++j) { float f[8];
; #pragma unroll
;       for (int i = 0; i < 8; ++i) f[i] = sm[(32 * kh + 8 * j + i) * 257 + n];
;       u32x4 pk = {pack2(f[0], f[1]), pack2(f[2], f[3]), pack2(f[4], f[5]), pack2(f[6], f[7])};
;       *(u32x4*)(dst + (size_t)(n0 + n) * K + k0 + 32 * kh + 8 * j) = pk; } }
.LBB0_1191:
	v_add_u32_e32 v30, 0x2020, v0
	ds_write2_b32 v30, v26, v27 offset1:1
	v_add_u32_e32 v26, 0x2028, v0
	s_and_b64 vcc, exec, s[2:3]
	ds_write2_b32 v26, v28, v29 offset1:1
	s_cbranch_vccnz .LBB0_1193
	global_load_dword v26, v[36:37], off offset:1856
	s_waitcnt vmcnt(0) lgkmcnt(0)
	v_pk_mul_f32 v[24:25], v[24:25], v[26:27] op_sel_hi:[1,0]
	v_pk_mul_f32 v[22:23], v[22:23], v[26:27] op_sel_hi:[1,0]
.LBB0_1193:
	v_add_u32_e32 v26, 0x4040, v0
	ds_write2_b32 v26, v22, v23 offset1:1
	v_add_u32_e32 v22, 0x4048, v0
	s_and_b64 vcc, exec, s[2:3]
	ds_write2_b32 v22, v24, v25 offset1:1
	s_cbranch_vccnz .LBB0_1195
	global_load_dword v22, v[36:37], off offset:1888
	s_waitcnt vmcnt(0) lgkmcnt(0)
	v_pk_mul_f32 v[20:21], v[20:21], v[22:23] op_sel_hi:[1,0]
	v_pk_mul_f32 v[18:19], v[18:19], v[22:23] op_sel_hi:[1,0]
.LBB0_1195:
	v_add_u32_e32 v22, 0x6060, v0
	ds_write2_b32 v22, v18, v19 offset1:1
	v_add_u32_e32 v18, 0x6068, v0
	s_and_b64 vcc, exec, s[2:3]
	ds_write2_b32 v18, v20, v21 offset1:1
	s_cbranch_vccnz .LBB0_1197
	global_load_dword v18, v[36:37], off offset:1920
	s_waitcnt vmcnt(0) lgkmcnt(0)
	v_pk_mul_f32 v[16:17], v[16:17], v[18:19] op_sel_hi:[1,0]
	v_pk_mul_f32 v[14:15], v[14:15], v[18:19] op_sel_hi:[1,0]
.LBB0_1197:
	v_add_u32_e32 v18, 0x8080, v0
	ds_write2_b32 v18, v14, v15 offset1:1
	v_add_u32_e32 v14, 0x8088, v0
	s_and_b64 vcc, exec, s[2:3]
	ds_write2_b32 v14, v16, v17 offset1:1
	s_cbranch_vccnz .LBB0_1199
	global_load_dword v14, v[36:37], off offset:1952
	s_waitcnt vmcnt(0) lgkmcnt(0)
	v_pk_mul_f32 v[12:13], v[12:13], v[14:15] op_sel_hi:[1,0]
	v_pk_mul_f32 v[10:11], v[10:11], v[14:15] op_sel_hi:[1,0]
.LBB0_1199:
	v_add_u32_e32 v14, 0xa0a0, v0
	ds_write2_b32 v14, v10, v11 offset1:1
	v_add_u32_e32 v10, 0xa0a8, v0
	s_and_b64 vcc, exec, s[2:3]
	ds_write2_b32 v10, v12, v13 offset1:1
	s_cbranch_vccnz .LBB0_1201
	global_load_dword v10, v[36:37], off offset:1984
	s_waitcnt vmcnt(0) lgkmcnt(0)
	v_pk_mul_f32 v[8:9], v[8:9], v[10:11] op_sel_hi:[1,0]
	v_pk_mul_f32 v[6:7], v[6:7], v[10:11] op_sel_hi:[1,0]
.LBB0_1201:
	v_add_u32_e32 v10, 0xc0c0, v0
	ds_write2_b32 v10, v6, v7 offset1:1
	v_add_u32_e32 v6, 0xc0c8, v0
	s_and_b64 vcc, exec, s[2:3]
	ds_write2_b32 v6, v8, v9 offset1:1
	s_cbranch_vccnz .LBB0_1203
	global_load_dword v6, v[36:37], off offset:2016
	s_waitcnt vmcnt(0) lgkmcnt(0)
	v_pk_mul_f32 v[4:5], v[4:5], v[6:7] op_sel_hi:[1,0]
	v_pk_mul_f32 v[2:3], v[2:3], v[6:7] op_sel_hi:[1,0]
.LBB0_1203:
	v_add_u32_e32 v6, 0xe0e0, v0
	v_add_u32_e32 v0, 0xe0e8, v0
	ds_write2_b32 v0, v4, v5 offset1:1
	v_ashrrev_i32_e32 v4, 1, v38
	v_lshlrev_b32_e32 v0, 5, v38
	v_and_b32_e32 v5, 32, v0
	v_add_u32_e32 v0, s1, v4
	s_movk_i32 s1, 0x380
	ds_write2_b32 v6, v2, v3 offset1:1
	v_mad_i64_i32 v[2:3], s[2:3], v0, s1, v[34:35]
	s_lshl_b32 s62, s0, 1
	v_lshl_add_u64 v[2:3], v[2:3], 0, s[62:63]
	v_lshlrev_b32_e32 v0, 1, v5
	v_lshl_add_u64 v[6:7], v[2:3], 0, v[0:1]
	v_mul_u32_u24_e32 v0, 0x404, v5
	v_lshl_add_u32 v0, v4, 2, v0
	s_waitcnt lgkmcnt(0)
	s_barrier
	ds_read_b32 v2, v0
	ds_read_b32 v3, v0 offset:1028
	ds_read_b32 v4, v0 offset:2056
	ds_read_b32 v5, v0 offset:3084
	ds_read_b32 v10, v0 offset:4112
	ds_read_b32 v11, v0 offset:5140
	ds_read_b32 v12, v0 offset:6168
	ds_read_b32 v13, v0 offset:7196
	s_mov_b64 s[0:1], 0x6200000
	v_lshl_add_u64 v[8:9], v[6:7], 0, s[0:1]
	s_mov_b32 s0, 0x6200000
	v_add_co_u32_e32 v6, vcc, s0, v6
	s_waitcnt lgkmcnt(6)
	v_cvt_pk_bf16_f32 v2, v2, v3
	s_waitcnt lgkmcnt(4)
	v_cvt_pk_bf16_f32 v3, v4, v5
	s_waitcnt lgkmcnt(2)
	v_cvt_pk_bf16_f32 v4, v10, v11
	s_waitcnt lgkmcnt(0)
	v_cvt_pk_bf16_f32 v5, v12, v13
	v_addc_co_u32_e32 v7, vcc, 0, v7, vcc
	global_store_dwordx4 v[6:7], v[2:5], off
	ds_read_b32 v2, v0 offset:8224
	ds_read_b32 v3, v0 offset:9252
	ds_read_b32 v4, v0 offset:10280
	ds_read_b32 v5, v0 offset:11308
	ds_read_b32 v6, v0 offset:12336
	ds_read_b32 v7, v0 offset:13364
	ds_read_b32 v10, v0 offset:14392
	ds_read_b32 v11, v0 offset:15420
	s_waitcnt lgkmcnt(0)
	v_cvt_pk_bf16_f32 v2, v2, v3
	v_cvt_pk_bf16_f32 v3, v4, v5
	v_cvt_pk_bf16_f32 v4, v6, v7
	s_mov_b64 s[0:1], 0
	v_cvt_pk_bf16_f32 v5, v10, v11
	global_store_dwordx4 v[8:9], v[2:5], off offset:16
	ds_read_b32 v2, v0 offset:16448
	ds_read_b32 v3, v0 offset:17476
	ds_read_b32 v4, v0 offset:18504
	ds_read_b32 v5, v0 offset:19532
	ds_read_b32 v6, v0 offset:20560
	ds_read_b32 v7, v0 offset:21588
	ds_read_b32 v10, v0 offset:22616
	ds_read_b32 v11, v0 offset:23644
	s_waitcnt lgkmcnt(0)
	v_cvt_pk_bf16_f32 v2, v2, v3
	v_cvt_pk_bf16_f32 v3, v4, v5
	v_cvt_pk_bf16_f32 v4, v6, v7
	v_cvt_pk_bf16_f32 v5, v10, v11
	global_store_dwordx4 v[8:9], v[2:5], off offset:32
	ds_read_b32 v2, v0 offset:24672
	ds_read_b32 v3, v0 offset:25700
	ds_read_b32 v4, v0 offset:26728
	ds_read_b32 v5, v0 offset:27756
	ds_read_b32 v6, v0 offset:28784
	ds_read_b32 v7, v0 offset:29812
	ds_read_b32 v10, v0 offset:30840
	ds_read_b32 v0, v0 offset:31868
	s_waitcnt lgkmcnt(0)
	v_cvt_pk_bf16_f32 v2, v2, v3
	v_cvt_pk_bf16_f32 v3, v4, v5
	v_cvt_pk_bf16_f32 v4, v6, v7
	v_cvt_pk_bf16_f32 v5, v10, v0
	global_store_dwordx4 v[8:9], v[2:5], off offset:48
	s_waitcnt lgkmcnt(0)
	s_barrier

; DI unsigned pack2(float lo, float hi) { f32x2 v = {lo, hi}; bf2_t b = __builtin_convertvector(v, bf2_t); return __builtin_bit_cast(unsigned, b); }
; DI int opaque_tid() { int t = threadIdx.x; asm volatile("" : "+v"(t)); return t; }
; DI void convert_tile(const float* __restrict__ src, int K, int N, bf16_t* __restrict__ dst, int tk, int tn, const float* rowscale, char* smem) {
;   float* sm = (float*)smem; const int tid = opaque_tid(); const int k0 = tk * 64, n0 = tn * 256;
;   { const int r = tid >> 6, c4 = tid & 63; const int n = n0 + 4 * c4;
;     f32x4 v[8];
; #pragma unroll
;     for (int i = 0; i < 8; ++i) { v[i] = (f32x4){0.f, 0.f, 0.f, 0.f}; if (n < N) v[i] = __builtin_nontemporal_load((const f32x4*)(src + (size_t)(k0 + r + 8 * i) * N + n)); }
; #pragma unroll
;     for (int i = 0; i < 8; ++i) { const int kk = r + 8 * i; if (rowscale) v[i] *= rowscale[k0 + kk];
;       sm[kk * 257 + 4 * c4 + 0] = v[i].x; sm[kk * 257 + 4 * c4 + 1] = v[i].y; sm[kk * 257 + 4 * c4 + 2] = v[i].z; sm[kk * 257 + 4 * c4 + 3] = v[i].w; } }
;   __syncthreads();
;   { const int n = tid >> 1, kh = tid & 1;
; #pragma unroll
;     for (int j = 0; j < 4; ++j) { float f[8];
; #pragma unroll
;       for (int i = 0; i < 8; ++i) f[i] = sm[(32 * kh + 8 * j + i) * 257 + n];
;       u32x4 pk = {pack2(f[0], f[1]), pack2(f[2], f[3]), pack2(f[4], f[5]), pack2(f[6], f[7])};
;       *(u32x4*)(dst + (size_t)(n0 + n) * K + k0 + 32 * kh + 8 * j) = pk; } }
; DI void convert_item(const Params& P, int l, int it, char* smem) {
;     ...
;   else if (it < CV_T3) { it -= CV_T2; convert_tile(P.ffn_w_down + (size_t)l * 5632 * 2048, 5632, 2048, (bf16_t*)(wb + W_DOWN), it / 8, it % 8, nullptr, smem); }
.LBB0_1205:
	global_load_dwordx2 v[2:3], v1, s[40:41] offset:1208
	v_mov_b32_e32 v36, v206
	s_and_b32 s0, s10, 0x7fc0
	v_lshlrev_b32_e32 v0, 2, v36
	s_add_i32 s62, s0, 0xffffb600
	s_and_b32 s0, s12, 0x700
	v_ashrrev_i32_e32 v37, 6, v36
	v_and_b32_e32 v38, 0xfc, v0
	v_or_b32_e32 v0, s0, v38
	s_waitcnt vmcnt(0)
	v_add_u32_e32 v4, s62, v37
	v_lshlrev_b32_e32 v0, 2, v0
	v_ashrrev_i32_e32 v5, 31, v4
	v_lshlrev_b64 v[4:5], 13, v[4:5]
	s_mov_b32 s1, 0x2c00000
	v_lshl_add_u64 v[2:3], v[2:3], 0, v[0:1]
	v_lshl_add_u64 v[30:31], v[2:3], 0, v[4:5]
	v_add_co_u32_e32 v2, vcc, s1, v30
	s_mov_b32 s1, 0x2c10000
	s_nop 0
	v_addc_co_u32_e32 v3, vcc, 0, v31, vcc
	v_add_co_u32_e32 v6, vcc, s1, v30
	global_load_dwordx4 v[2:5], v[2:3], off nt
	s_nop 0
	v_addc_co_u32_e32 v7, vcc, 0, v31, vcc
	s_mov_b32 s1, 0x2c20000
	global_load_dwordx4 v[6:9], v[6:7], off nt
	v_add_co_u32_e32 v10, vcc, s1, v30
	s_mov_b32 s1, 0x2c30000
	s_nop 0
	v_addc_co_u32_e32 v11, vcc, 0, v31, vcc
	global_load_dwordx4 v[10:13], v[10:11], off nt
	v_add_co_u32_e32 v14, vcc, s1, v30
	s_mov_b32 s1, 0x2c40000
	s_nop 0
	v_addc_co_u32_e32 v15, vcc, 0, v31, vcc
	global_load_dwordx4 v[14:17], v[14:15], off nt
	v_add_co_u32_e32 v18, vcc, s1, v30
	s_mov_b32 s1, 0x2c50000
	s_nop 0
	v_addc_co_u32_e32 v19, vcc, 0, v31, vcc
	global_load_dwordx4 v[18:21], v[18:19], off nt
	v_add_co_u32_e32 v22, vcc, s1, v30
	s_mov_b32 s1, 0x2c60000
	s_nop 0
	v_addc_co_u32_e32 v23, vcc, 0, v31, vcc
	global_load_dwordx4 v[22:25], v[22:23], off nt
	v_add_co_u32_e32 v26, vcc, s1, v30
	s_mov_b32 s1, 0x2c70000
	s_nop 0
	v_addc_co_u32_e32 v27, vcc, 0, v31, vcc
	global_load_dwordx4 v[26:29], v[26:27], off nt
	v_add_co_u32_e32 v30, vcc, s1, v30
	s_movk_i32 s1, 0x404
	s_nop 0
	v_addc_co_u32_e32 v31, vcc, 0, v31, vcc
	global_load_dwordx4 v[30:33], v[30:31], off nt
	v_mul_lo_u32 v0, v37, s1
	v_lshl_add_u32 v0, v38, 2, v0
	s_waitcnt vmcnt(0) lgkmcnt(0)
	ds_write2_b32 v0, v2, v3 offset1:1
	ds_write2_b32 v0, v4, v5 offset0:2 offset1:3
	v_add_u32_e32 v2, 0x2020, v0
	ds_write2_b32 v2, v6, v7 offset1:1
	v_add_u32_e32 v2, 0x2028, v0
	ds_write2_b32 v2, v8, v9 offset1:1
	v_add_u32_e32 v2, 0x4040, v0
	v_ashrrev_i32_e32 v6, 1, v36
	ds_write2_b32 v2, v10, v11 offset1:1
	v_add_u32_e32 v2, 0x4048, v0
	ds_write2_b32 v2, v12, v13 offset1:1
	v_add_u32_e32 v2, 0x6060, v0
	ds_write2_b32 v2, v14, v15 offset1:1
	v_add_u32_e32 v2, 0x6068, v0
	ds_write2_b32 v2, v16, v17 offset1:1
	v_add_u32_e32 v2, 0x8080, v0
	ds_write2_b32 v2, v18, v19 offset1:1
	v_add_u32_e32 v2, 0x8088, v0
	ds_write2_b32 v2, v20, v21 offset1:1
	v_add_u32_e32 v2, 0xa0a0, v0
	ds_write2_b32 v2, v22, v23 offset1:1
	v_add_u32_e32 v2, 0xa0a8, v0
	ds_write2_b32 v2, v24, v25 offset1:1
	v_add_u32_e32 v2, 0xc0c0, v0
	ds_write2_b32 v2, v26, v27 offset1:1
	v_add_u32_e32 v2, 0xc0c8, v0
	ds_write2_b32 v2, v28, v29 offset1:1
	v_add_u32_e32 v2, 0xe0e0, v0
	v_add_u32_e32 v0, 0xe0e8, v0
	ds_write2_b32 v0, v32, v33 offset1:1
	v_lshlrev_b32_e32 v0, 5, v36
	v_and_b32_e32 v7, 32, v0
	v_add_u32_e32 v0, s0, v6
	ds_write2_b32 v2, v30, v31 offset1:1
	v_mad_i64_i32 v[2:3], s[0:1], v0, s81, v[34:35]
	v_lshl_add_u64 v[2:3], s[62:63], 1, v[2:3]
	v_lshlrev_b32_e32 v0, 1, v7
	v_lshl_add_u64 v[4:5], v[2:3], 0, v[0:1]
	v_mul_u32_u24_e32 v0, 0x404, v7
	v_lshl_add_u32 v0, v6, 2, v0
	s_waitcnt lgkmcnt(0)
	s_barrier
	ds_read_b32 v6, v0
	ds_read_b32 v7, v0 offset:1028
	ds_read_b32 v8, v0 offset:2056
	ds_read_b32 v9, v0 offset:3084
	ds_read_b32 v10, v0 offset:4112
	ds_read_b32 v11, v0 offset:5140
	ds_read_b32 v12, v0 offset:6168
	ds_read_b32 v13, v0 offset:7196
	s_mov_b64 s[0:1], 0x4c00000
	v_lshl_add_u64 v[2:3], v[4:5], 0, s[0:1]
	s_mov_b32 s0, 0x4c00000
	v_add_co_u32_e32 v4, vcc, s0, v4
	s_waitcnt lgkmcnt(6)
	v_cvt_pk_bf16_f32 v6, v6, v7
	s_waitcnt lgkmcnt(4)
	v_cvt_pk_bf16_f32 v7, v8, v9
	s_waitcnt lgkmcnt(2)
	v_cvt_pk_bf16_f32 v8, v10, v11
	s_waitcnt lgkmcnt(0)
	v_cvt_pk_bf16_f32 v9, v12, v13
	v_addc_co_u32_e32 v5, vcc, 0, v5, vcc
	global_store_dwordx4 v[4:5], v[6:9], off
	ds_read_b32 v4, v0 offset:8224
	ds_read_b32 v5, v0 offset:9252
	ds_read_b32 v6, v0 offset:10280
	ds_read_b32 v7, v0 offset:11308
	ds_read_b32 v8, v0 offset:12336
	ds_read_b32 v9, v0 offset:13364
	ds_read_b32 v10, v0 offset:14392
	ds_read_b32 v11, v0 offset:15420
	s_waitcnt lgkmcnt(0)
	v_cvt_pk_bf16_f32 v4, v4, v5
	v_cvt_pk_bf16_f32 v5, v6, v7
	v_cvt_pk_bf16_f32 v6, v8, v9
	v_cvt_pk_bf16_f32 v7, v10, v11
	global_store_dwordx4 v[2:3], v[4:7], off offset:16
	ds_read_b32 v4, v0 offset:16448
	ds_read_b32 v5, v0 offset:17476
	ds_read_b32 v6, v0 offset:18504
	ds_read_b32 v7, v0 offset:19532
	ds_read_b32 v8, v0 offset:20560
	ds_read_b32 v9, v0 offset:21588
	ds_read_b32 v10, v0 offset:22616
	ds_read_b32 v11, v0 offset:23644
	s_waitcnt lgkmcnt(0)
	v_cvt_pk_bf16_f32 v4, v4, v5
	v_cvt_pk_bf16_f32 v5, v6, v7
	v_cvt_pk_bf16_f32 v6, v8, v9
	v_cvt_pk_bf16_f32 v7, v10, v11
	global_store_dwordx4 v[2:3], v[4:7], off offset:32
	ds_read_b32 v4, v0 offset:24672
	ds_read_b32 v5, v0 offset:25700
	ds_read_b32 v6, v0 offset:26728
	ds_read_b32 v7, v0 offset:27756
	ds_read_b32 v8, v0 offset:28784
	ds_read_b32 v9, v0 offset:29812
	ds_read_b32 v10, v0 offset:30840
	ds_read_b32 v0, v0 offset:31868
	s_waitcnt lgkmcnt(0)
	v_cvt_pk_bf16_f32 v4, v4, v5
	v_cvt_pk_bf16_f32 v5, v6, v7
	v_cvt_pk_bf16_f32 v6, v8, v9
	v_cvt_pk_bf16_f32 v7, v10, v0
	global_store_dwordx4 v[2:3], v[4:7], off offset:48
	s_waitcnt lgkmcnt(0)
	s_barrier

; DI unsigned pack2(float lo, float hi) { f32x2 v = {lo, hi}; bf2_t b = __builtin_convertvector(v, bf2_t); return __builtin_bit_cast(unsigned, b); }
; DI int opaque_tid() { int t = threadIdx.x; asm volatile("" : "+v"(t)); return t; }
; DI void convert_tile(const float* __restrict__ src, int K, int N, bf16_t* __restrict__ dst, int tk, int tn, const float* rowscale, char* smem) {
;   float* sm = (float*)smem; const int tid = opaque_tid(); const int k0 = tk * 64, n0 = tn * 256;
;   { const int r = tid >> 6, c4 = tid & 63; const int n = n0 + 4 * c4;
;     f32x4 v[8];
; #pragma unroll
;     for (int i = 0; i < 8; ++i) { v[i] = (f32x4){0.f, 0.f, 0.f, 0.f}; if (n < N) v[i] = __builtin_nontemporal_load((const f32x4*)(src + (size_t)(k0 + r + 8 * i) * N + n)); }
; #pragma unroll
;     for (int i = 0; i < 8; ++i) { const int kk = r + 8 * i; if (rowscale) v[i] *= rowscale[k0 + kk];
;       sm[kk * 257 + 4 * c4 + 0] = v[i].x; sm[kk * 257 + 4 * c4 + 1] = v[i].y; sm[kk * 257 + 4 * c4 + 2] = v[i].z; sm[kk * 257 + 4 * c4 + 3] = v[i].w; } }
;   __syncthreads();
;   { const int n = tid >> 1, kh = tid & 1;
; #pragma unroll
;     for (int j = 0; j < 4; ++j) { float f[8];
; #pragma unroll
;       for (int i = 0; i < 8; ++i) f[i] = sm[(32 * kh + 8 * j + i) * 257 + n];
;       u32x4 pk = {pack2(f[0], f[1]), pack2(f[2], f[3]), pack2(f[4], f[5]), pack2(f[6], f[7])};
;       *(u32x4*)(dst + (size_t)(n0 + n) * K + k0 + 32 * kh + 8 * j) = pk; } }
; DI void convert_item(const Params& P, int l, int it, char* smem) {
;     ...
;   else if (it < CV_T2) { it -= CV_T1; convert_tile(P.ffn_w_up + (size_t)l * 2048 * 11264, 2048, 11264, (bf16_t*)(wb + W_UP), it / 44, it % 44, nullptr, smem); }
.LBB0_1207:
	s_andn2_b64 vcc, exec, s[0:1]
	s_cbranch_vccnz .LBB0_1209
	global_load_dwordx2 v[2:3], v1, s[40:41] offset:1184
	s_add_i32 s1, s13, 0xfc40
	s_and_b32 s0, s1, 0xffff
	s_mul_i32 s0, s0, 0xba2f
	s_lshr_b32 s0, s0, 21
	s_mul_i32 s2, s0, 44
	s_sub_i32 s1, s1, s2
	v_mov_b32_e32 v36, v206
	s_lshl_b32 s1, s1, 8
	v_lshlrev_b32_e32 v0, 2, v36
	s_and_b32 s1, s1, 0xff00
	v_and_b32_e32 v38, 0xfc, v0
	v_or_b32_e32 v0, s1, v38
	v_lshlrev_b32_e32 v0, 2, v0
	v_ashrrev_i32_e32 v37, 6, v36
	s_mov_b64 s[2:3], 0x5800000
	v_lshl_add_u32 v32, s0, 6, v37
	s_mov_b32 s4, 0xb000
	s_lshl_b32 s62, s0, 7
	s_waitcnt vmcnt(0)
	v_lshl_add_u64 v[2:3], v[2:3], 0, v[0:1]
	v_lshl_add_u64 v[30:31], v[2:3], 0, s[2:3]
	v_mad_i64_i32 v[2:3], s[2:3], v32, s4, v[30:31]
	v_add_u32_e32 v0, 8, v32
	global_load_dwordx4 v[2:5], v[2:3], off nt
	v_mad_i64_i32 v[6:7], s[2:3], v0, s4, v[30:31]
	global_load_dwordx4 v[6:9], v[6:7], off nt
	v_add_u32_e32 v0, 16, v32
	v_mad_i64_i32 v[10:11], s[2:3], v0, s4, v[30:31]
	global_load_dwordx4 v[10:13], v[10:11], off nt
	v_add_u32_e32 v0, 24, v32
	v_mad_i64_i32 v[14:15], s[2:3], v0, s4, v[30:31]
	global_load_dwordx4 v[14:17], v[14:15], off nt
	v_add_u32_e32 v0, 32, v32
	v_mad_i64_i32 v[18:19], s[2:3], v0, s4, v[30:31]
	global_load_dwordx4 v[18:21], v[18:19], off nt
	v_add_u32_e32 v0, 40, v32
	v_mad_i64_i32 v[22:23], s[2:3], v0, s4, v[30:31]
	global_load_dwordx4 v[22:25], v[22:23], off nt
	v_add_u32_e32 v0, 48, v32
	v_mad_i64_i32 v[26:27], s[2:3], v0, s4, v[30:31]
	global_load_dwordx4 v[26:29], v[26:27], off nt
	v_add_u32_e32 v0, 56, v32
	v_mad_i64_i32 v[30:31], s[2:3], v0, s4, v[30:31]
	global_load_dwordx4 v[30:33], v[30:31], off nt
	s_movk_i32 s2, 0x404
	v_mul_lo_u32 v0, v37, s2
	v_lshl_add_u32 v0, v38, 2, v0
	s_waitcnt vmcnt(0) lgkmcnt(0)
	ds_write2_b32 v0, v2, v3 offset1:1
	ds_write2_b32 v0, v4, v5 offset0:2 offset1:3
	v_add_u32_e32 v2, 0x2020, v0
	ds_write2_b32 v2, v6, v7 offset1:1
	v_add_u32_e32 v2, 0x2028, v0
	ds_write2_b32 v2, v8, v9 offset1:1
	v_add_u32_e32 v2, 0x4040, v0
	ds_write2_b32 v2, v10, v11 offset1:1
	v_add_u32_e32 v2, 0x4048, v0
	ds_write2_b32 v2, v12, v13 offset1:1
	v_add_u32_e32 v2, 0x6060, v0
	ds_write2_b32 v2, v14, v15 offset1:1
	v_add_u32_e32 v2, 0x6068, v0
	ds_write2_b32 v2, v16, v17 offset1:1
	v_add_u32_e32 v2, 0x8080, v0
	ds_write2_b32 v2, v18, v19 offset1:1
	v_add_u32_e32 v2, 0x8088, v0
	ds_write2_b32 v2, v20, v21 offset1:1
	v_add_u32_e32 v2, 0xa0a0, v0
	ds_write2_b32 v2, v22, v23 offset1:1
	v_add_u32_e32 v2, 0xa0a8, v0
	ds_write2_b32 v2, v24, v25 offset1:1
	v_add_u32_e32 v2, 0xc0c0, v0
	ds_write2_b32 v2, v26, v27 offset1:1
	v_add_u32_e32 v2, 0xc0c8, v0
	ds_write2_b32 v2, v28, v29 offset1:1
	v_add_u32_e32 v2, 0xe0e0, v0
	v_ashrrev_i32_e32 v6, 1, v36
	ds_write2_b32 v2, v30, v31 offset1:1
	v_add_u32_e32 v2, s1, v6
	v_add_u32_e32 v0, 0xe0e8, v0
	v_ashrrev_i32_e32 v3, 31, v2
	ds_write2_b32 v0, v32, v33 offset1:1
	v_lshlrev_b32_e32 v0, 5, v36
	v_lshlrev_b64 v[2:3], 12, v[2:3]
	v_and_b32_e32 v7, 32, v0
	v_lshl_add_u64 v[2:3], v[34:35], 0, v[2:3]
	v_lshl_add_u64 v[2:3], v[2:3], 0, s[62:63]
	v_lshlrev_b32_e32 v0, 1, v7
	v_lshl_add_u64 v[4:5], v[2:3], 0, v[0:1]
	v_mul_u32_u24_e32 v0, 0x404, v7
	v_lshl_add_u32 v0, v6, 2, v0
	s_waitcnt lgkmcnt(0)
	s_barrier
	ds_read_b32 v6, v0
	ds_read_b32 v7, v0 offset:1028
	ds_read_b32 v8, v0 offset:2056
	ds_read_b32 v9, v0 offset:3084
	ds_read_b32 v10, v0 offset:4112
	ds_read_b32 v11, v0 offset:5140
	ds_read_b32 v12, v0 offset:6168
	ds_read_b32 v13, v0 offset:7196
	s_mov_b64 s[0:1], 0x2000000
	v_lshl_add_u64 v[2:3], v[4:5], 0, s[0:1]
	s_brev_b32 s0, 64
	v_add_co_u32_e32 v4, vcc, s0, v4
	s_waitcnt lgkmcnt(6)
	v_cvt_pk_bf16_f32 v6, v6, v7
	s_waitcnt lgkmcnt(4)
	v_cvt_pk_bf16_f32 v7, v8, v9
	s_waitcnt lgkmcnt(2)
	v_cvt_pk_bf16_f32 v8, v10, v11
	s_waitcnt lgkmcnt(0)
	v_cvt_pk_bf16_f32 v9, v12, v13
	v_addc_co_u32_e32 v5, vcc, 0, v5, vcc
	global_store_dwordx4 v[4:5], v[6:9], off
	ds_read_b32 v4, v0 offset:8224
	ds_read_b32 v5, v0 offset:9252
	ds_read_b32 v6, v0 offset:10280
	ds_read_b32 v7, v0 offset:11308
	ds_read_b32 v8, v0 offset:12336
	ds_read_b32 v9, v0 offset:13364
	ds_read_b32 v10, v0 offset:14392
	ds_read_b32 v11, v0 offset:15420
	s_waitcnt lgkmcnt(0)
	v_cvt_pk_bf16_f32 v4, v4, v5
	v_cvt_pk_bf16_f32 v5, v6, v7
	v_cvt_pk_bf16_f32 v6, v8, v9
	v_cvt_pk_bf16_f32 v7, v10, v11
	global_store_dwordx4 v[2:3], v[4:7], off offset:16
	ds_read_b32 v4, v0 offset:16448
	ds_read_b32 v5, v0 offset:17476
	ds_read_b32 v6, v0 offset:18504
	ds_read_b32 v7, v0 offset:19532
	ds_read_b32 v8, v0 offset:20560
	ds_read_b32 v9, v0 offset:21588
	ds_read_b32 v10, v0 offset:22616
	ds_read_b32 v11, v0 offset:23644
	s_waitcnt lgkmcnt(0)
	v_cvt_pk_bf16_f32 v4, v4, v5
	v_cvt_pk_bf16_f32 v5, v6, v7
	v_cvt_pk_bf16_f32 v6, v8, v9
	v_cvt_pk_bf16_f32 v7, v10, v11
	global_store_dwordx4 v[2:3], v[4:7], off offset:32
	ds_read_b32 v4, v0 offset:24672
	ds_read_b32 v5, v0 offset:25700
	ds_read_b32 v6, v0 offset:26728
	ds_read_b32 v7, v0 offset:27756
	ds_read_b32 v8, v0 offset:28784
	ds_read_b32 v9, v0 offset:29812
	ds_read_b32 v10, v0 offset:30840
	ds_read_b32 v0, v0 offset:31868
	s_waitcnt lgkmcnt(0)
	v_cvt_pk_bf16_f32 v4, v4, v5
	v_cvt_pk_bf16_f32 v5, v6, v7
	v_cvt_pk_bf16_f32 v6, v8, v9
	v_cvt_pk_bf16_f32 v7, v10, v0
	global_store_dwordx4 v[2:3], v[4:7], off offset:48
	s_waitcnt lgkmcnt(0)
	s_barrier

; DI unsigned pack2(float lo, float hi) { f32x2 v = {lo, hi}; bf2_t b = __builtin_convertvector(v, bf2_t); return __builtin_bit_cast(unsigned, b); }
; DI int opaque_tid() { int t = threadIdx.x; asm volatile("" : "+v"(t)); return t; }
; DI void convert_tile(const float* __restrict__ src, int K, int N, bf16_t* __restrict__ dst, int tk, int tn, const float* rowscale, char* smem) {
;   float* sm = (float*)smem; const int tid = opaque_tid(); const int k0 = tk * 64, n0 = tn * 256;
;   { const int r = tid >> 6, c4 = tid & 63; const int n = n0 + 4 * c4;
;     f32x4 v[8];
; #pragma unroll
;     for (int i = 0; i < 8; ++i) { v[i] = (f32x4){0.f, 0.f, 0.f, 0.f}; if (n < N) v[i] = __builtin_nontemporal_load((const f32x4*)(src + (size_t)(k0 + r + 8 * i) * N + n)); }
; #pragma unroll
;     for (int i = 0; i < 8; ++i) { const int kk = r + 8 * i; if (rowscale) v[i] *= rowscale[k0 + kk];
;       sm[kk * 257 + 4 * c4 + 0] = v[i].x; sm[kk * 257 + 4 * c4 + 1] = v[i].y; sm[kk * 257 + 4 * c4 + 2] = v[i].z; sm[kk * 257 + 4 * c4 + 3] = v[i].w; } }
;   __syncthreads();
;   { const int n = tid >> 1, kh = tid & 1;
; #pragma unroll
;     for (int j = 0; j < 4; ++j) { float f[8];
; #pragma unroll
;       for (int i = 0; i < 8; ++i) f[i] = sm[(32 * kh + 8 * j + i) * 257 + n];
;       u32x4 pk = {pack2(f[0], f[1]), pack2(f[2], f[3]), pack2(f[4], f[5]), pack2(f[6], f[7])};
;       *(u32x4*)(dst + (size_t)(n0 + n) * K + k0 + 32 * kh + 8 * j) = pk; } }
; DI void convert_item(const Params& P, int l, int it, char* smem) {
;     ...
;   else if (it < CV_T1) { it -= CV_T0; convert_tile(P.w_out + (size_t)l * 2048 * 2048, 2048, 2048, (bf16_t*)(wb + W_OUT), it / 8, it % 8, nullptr, smem); }
.LBB0_1210:
	s_andn2_b64 vcc, exec, s[0:1]
	s_cbranch_vccnz .LBB0_1212
	global_load_dwordx2 v[2:3], v1, s[40:41] offset:1088
	v_mov_b32_e32 v36, v206
	s_and_b32 s0, s10, 0x1fc0
	v_lshlrev_b32_e32 v0, 2, v36
	s_add_i32 s62, s0, 0xffffea00
	s_and_b32 s0, s12, 0x700
	v_ashrrev_i32_e32 v37, 6, v36
	v_and_b32_e32 v38, 0xfc, v0
	v_or_b32_e32 v0, s0, v38
	s_waitcnt vmcnt(0)
	v_add_u32_e32 v4, s62, v37
	v_lshlrev_b32_e32 v0, 2, v0
	v_ashrrev_i32_e32 v5, 31, v4
	v_lshlrev_b64 v[4:5], 13, v[4:5]
	s_mov_b32 s1, 0x1000000
	v_lshl_add_u64 v[2:3], v[2:3], 0, v[0:1]
	v_lshl_add_u64 v[30:31], v[2:3], 0, v[4:5]
	v_add_co_u32_e32 v2, vcc, s1, v30
	s_mov_b32 s1, 0x1010000
	s_nop 0
	v_addc_co_u32_e32 v3, vcc, 0, v31, vcc
	v_add_co_u32_e32 v6, vcc, s1, v30
	global_load_dwordx4 v[2:5], v[2:3], off nt
	s_nop 0
	v_addc_co_u32_e32 v7, vcc, 0, v31, vcc
	s_mov_b32 s1, 0x1020000
	global_load_dwordx4 v[6:9], v[6:7], off nt
	v_add_co_u32_e32 v10, vcc, s1, v30
	s_mov_b32 s1, 0x1030000
	s_nop 0
	v_addc_co_u32_e32 v11, vcc, 0, v31, vcc
	global_load_dwordx4 v[10:13], v[10:11], off nt
	v_add_co_u32_e32 v14, vcc, s1, v30
	s_mov_b32 s1, 0x1040000
	s_nop 0
	v_addc_co_u32_e32 v15, vcc, 0, v31, vcc
	global_load_dwordx4 v[14:17], v[14:15], off nt
	v_add_co_u32_e32 v18, vcc, s1, v30
	s_mov_b32 s1, 0x1050000
	s_nop 0
	v_addc_co_u32_e32 v19, vcc, 0, v31, vcc
	global_load_dwordx4 v[18:21], v[18:19], off nt
	v_add_co_u32_e32 v22, vcc, s1, v30
	s_mov_b32 s1, 0x1060000
	s_nop 0
	v_addc_co_u32_e32 v23, vcc, 0, v31, vcc
	global_load_dwordx4 v[22:25], v[22:23], off nt
	v_add_co_u32_e32 v26, vcc, s1, v30
	s_mov_b32 s1, 0x1070000
	s_nop 0
	v_addc_co_u32_e32 v27, vcc, 0, v31, vcc
	global_load_dwordx4 v[26:29], v[26:27], off nt
	v_add_co_u32_e32 v30, vcc, s1, v30
	s_movk_i32 s1, 0x404
	s_nop 0
	v_addc_co_u32_e32 v31, vcc, 0, v31, vcc
	global_load_dwordx4 v[30:33], v[30:31], off nt
	v_mul_lo_u32 v0, v37, s1
	v_lshl_add_u32 v0, v38, 2, v0
	s_waitcnt vmcnt(0) lgkmcnt(0)
	ds_write2_b32 v0, v2, v3 offset1:1
	ds_write2_b32 v0, v4, v5 offset0:2 offset1:3
	v_add_u32_e32 v2, 0x2020, v0
	ds_write2_b32 v2, v6, v7 offset1:1
	v_add_u32_e32 v2, 0x2028, v0
	ds_write2_b32 v2, v8, v9 offset1:1
	v_add_u32_e32 v2, 0x4040, v0
	v_ashrrev_i32_e32 v6, 1, v36
	ds_write2_b32 v2, v10, v11 offset1:1
	v_add_u32_e32 v2, 0x4048, v0
	ds_write2_b32 v2, v12, v13 offset1:1
	v_add_u32_e32 v2, 0x6060, v0
	ds_write2_b32 v2, v14, v15 offset1:1
	v_add_u32_e32 v2, 0x6068, v0
	ds_write2_b32 v2, v16, v17 offset1:1
	v_add_u32_e32 v2, 0x8080, v0
	ds_write2_b32 v2, v18, v19 offset1:1
	v_add_u32_e32 v2, 0x8088, v0
	ds_write2_b32 v2, v20, v21 offset1:1
	v_add_u32_e32 v2, 0xa0a0, v0
	ds_write2_b32 v2, v22, v23 offset1:1
	v_add_u32_e32 v2, 0xa0a8, v0
	ds_write2_b32 v2, v24, v25 offset1:1
	v_add_u32_e32 v2, 0xc0c0, v0
	ds_write2_b32 v2, v26, v27 offset1:1
	v_add_u32_e32 v2, 0xc0c8, v0
	ds_write2_b32 v2, v28, v29 offset1:1
	v_add_u32_e32 v2, 0xe0e0, v0
	v_add_u32_e32 v0, 0xe0e8, v0
	ds_write2_b32 v2, v30, v31 offset1:1
	v_add_u32_e32 v2, s0, v6
	v_ashrrev_i32_e32 v3, 31, v2
	ds_write2_b32 v0, v32, v33 offset1:1
	v_lshlrev_b32_e32 v0, 5, v36
	v_lshlrev_b64 v[2:3], 12, v[2:3]
	v_and_b32_e32 v7, 32, v0
	v_lshl_add_u64 v[2:3], v[34:35], 0, v[2:3]
	v_lshl_add_u64 v[2:3], s[62:63], 1, v[2:3]
	v_lshlrev_b32_e32 v0, 1, v7
	v_lshl_add_u64 v[4:5], v[2:3], 0, v[0:1]
	v_mul_u32_u24_e32 v0, 0x404, v7
	v_lshl_add_u32 v0, v6, 2, v0
	s_waitcnt lgkmcnt(0)
	s_barrier
	ds_read_b32 v6, v0
	ds_read_b32 v7, v0 offset:1028
	ds_read_b32 v8, v0 offset:2056
	ds_read_b32 v9, v0 offset:3084
	ds_read_b32 v10, v0 offset:4112
	ds_read_b32 v11, v0 offset:5140
	ds_read_b32 v12, v0 offset:6168
	ds_read_b32 v13, v0 offset:7196
	s_mov_b64 s[0:1], 0x1800000
	v_lshl_add_u64 v[2:3], v[4:5], 0, s[0:1]
	s_mov_b32 s0, 0x1800000
	v_add_co_u32_e32 v4, vcc, s0, v4
	s_waitcnt lgkmcnt(6)
	v_cvt_pk_bf16_f32 v6, v6, v7
	s_waitcnt lgkmcnt(4)
	v_cvt_pk_bf16_f32 v7, v8, v9
	s_waitcnt lgkmcnt(2)
	v_cvt_pk_bf16_f32 v8, v10, v11
	s_waitcnt lgkmcnt(0)
	v_cvt_pk_bf16_f32 v9, v12, v13
	v_addc_co_u32_e32 v5, vcc, 0, v5, vcc
	global_store_dwordx4 v[4:5], v[6:9], off
	ds_read_b32 v4, v0 offset:8224
	ds_read_b32 v5, v0 offset:9252
	ds_read_b32 v6, v0 offset:10280
	ds_read_b32 v7, v0 offset:11308
	ds_read_b32 v8, v0 offset:12336
	ds_read_b32 v9, v0 offset:13364
	ds_read_b32 v10, v0 offset:14392
	ds_read_b32 v11, v0 offset:15420
	s_waitcnt lgkmcnt(0)
	v_cvt_pk_bf16_f32 v4, v4, v5
	v_cvt_pk_bf16_f32 v5, v6, v7
	v_cvt_pk_bf16_f32 v6, v8, v9
	v_cvt_pk_bf16_f32 v7, v10, v11
	global_store_dwordx4 v[2:3], v[4:7], off offset:16
	ds_read_b32 v4, v0 offset:16448
	ds_read_b32 v5, v0 offset:17476
	ds_read_b32 v6, v0 offset:18504
	ds_read_b32 v7, v0 offset:19532
	ds_read_b32 v8, v0 offset:20560
	ds_read_b32 v9, v0 offset:21588
	ds_read_b32 v10, v0 offset:22616
	ds_read_b32 v11, v0 offset:23644
	s_waitcnt lgkmcnt(0)
	v_cvt_pk_bf16_f32 v4, v4, v5
	v_cvt_pk_bf16_f32 v5, v6, v7
	v_cvt_pk_bf16_f32 v6, v8, v9
	v_cvt_pk_bf16_f32 v7, v10, v11
	global_store_dwordx4 v[2:3], v[4:7], off offset:32
	ds_read_b32 v4, v0 offset:24672
	ds_read_b32 v5, v0 offset:25700
	ds_read_b32 v6, v0 offset:26728
	ds_read_b32 v7, v0 offset:27756
	ds_read_b32 v8, v0 offset:28784
	ds_read_b32 v9, v0 offset:29812
	ds_read_b32 v10, v0 offset:30840
	ds_read_b32 v0, v0 offset:31868
	s_waitcnt lgkmcnt(0)
	v_cvt_pk_bf16_f32 v4, v4, v5
	v_cvt_pk_bf16_f32 v5, v6, v7
	v_cvt_pk_bf16_f32 v6, v8, v9
	v_cvt_pk_bf16_f32 v7, v10, v0
	global_store_dwordx4 v[2:3], v[4:7], off offset:48
	s_waitcnt lgkmcnt(0)
	s_barrier

; DI int opaque_tid() { int t = threadIdx.x; asm volatile("" : "+v"(t)); return t; }
; DI void convert_tile(const float* __restrict__ src, int K, int N, bf16_t* __restrict__ dst, int tk, int tn, const float* rowscale, char* smem) {
;   float* sm = (float*)smem; const int tid = opaque_tid(); const int k0 = tk * 64, n0 = tn * 256;
;   { const int r = tid >> 6, c4 = tid & 63; const int n = n0 + 4 * c4;
;     f32x4 v[8];
; #pragma unroll
;     for (int i = 0; i < 8; ++i) { v[i] = (f32x4){0.f, 0.f, 0.f, 0.f}; if (n < N) v[i] = __builtin_nontemporal_load((const f32x4*)(src + (size_t)(k0 + r + 8 * i) * N + n)); }
; DI void convert_item(const Params& P, int l, int it, char* smem) {
;     ...
;   if (it < CV_T0) convert_tile(P.w_in + (size_t)l * 2048 * 5520, 2048, 5520, (bf16_t*)(wb + W_IN), it / 22, it % 22, nullptr, smem);
.LBB0_1213:
	s_andn2_b64 vcc, exec, s[0:1]
	s_cbranch_vccnz .LBB0_1163
	global_load_dwordx2 v[2:3], v1, s[40:41] offset:1080
	s_mul_hi_i32 s0, s13, 0x2e8ba2e9
	s_lshr_b32 s1, s0, 31
	s_ashr_i32 s0, s0, 2
	v_mov_b32_e32 v0, v206
	s_add_i32 s1, s0, s1
	s_lshl_b32 s0, s1, 6
	s_waitcnt vmcnt(0)
	v_lshlrev_b32_e32 v4, 2, v0
	v_and_b32_e32 v39, 0xfc, v4
	s_mulk_i32 s1, 0x1600
	v_subrev_u32_e32 v4, s1, v39
	v_add_u32_e32 v4, s12, v4
	s_movk_i32 s2, 0x1590
	v_ashrrev_i32_e32 v5, 31, v4
	v_ashrrev_i32_e32 v38, 6, v0
	v_cmp_gt_i32_e32 vcc, s2, v4
	s_mov_b64 s[2:3], 0x2b20000
	v_add_u32_e32 v40, s0, v38
	v_mov_b32_e32 v6, 0
	v_mov_b32_e32 v7, 0
	v_mov_b32_e32 v8, 0
	v_mov_b32_e32 v9, 0
	v_lshl_add_u64 v[2:3], v[4:5], 2, v[2:3]
	v_lshl_add_u64 v[36:37], v[2:3], 0, s[2:3]
	v_mov_b32_e32 v2, 0
	s_and_saveexec_b64 s[2:3], vcc
	s_cbranch_execz .LBB0_1216
	s_movk_i32 s4, 0x5640
	v_mad_i64_i32 v[4:5], s[4:5], v40, s4, v[36:37]
	global_load_dwordx4 v[6:9], v[4:5], off nt
.LBB0_1216:
	s_or_b64 exec, exec, s[2:3]
	v_mov_b32_e32 v3, 0
	v_mov_b32_e32 v4, 0
	v_mov_b32_e32 v5, 0
	s_and_saveexec_b64 s[2:3], vcc
	s_cbranch_execz .LBB0_1218
	v_add_u32_e32 v2, 8, v40
	s_movk_i32 s4, 0x5640
	v_mad_i64_i32 v[2:3], s[4:5], v2, s4, v[36:37]
	global_load_dwordx4 v[2:5], v[2:3], off nt
.LBB0_1218:
	s_or_b64 exec, exec, s[2:3]
	v_mov_b32_e32 v10, 0
	v_mov_b32_e32 v14, 0
	v_mov_b32_e32 v15, 0
	v_mov_b32_e32 v16, 0
	v_mov_b32_e32 v17, 0
	s_and_saveexec_b64 s[2:3], vcc
	s_cbranch_execz .LBB0_1220
	v_add_u32_e32 v11, 16, v40
	s_movk_i32 s4, 0x5640
	v_mad_i64_i32 v[12:13], s[4:5], v11, s4, v[36:37]
	global_load_dwordx4 v[14:17], v[12:13], off nt
.LBB0_1220:
	s_or_b64 exec, exec, s[2:3]
	v_mov_b32_e32 v11, 0
	v_mov_b32_e32 v12, 0
	v_mov_b32_e32 v13, 0
	s_and_saveexec_b64 s[2:3], vcc
	s_cbranch_execz .LBB0_1222
	v_add_u32_e32 v10, 24, v40
	s_movk_i32 s4, 0x5640
	v_mad_i64_i32 v[10:11], s[4:5], v10, s4, v[36:37]
	global_load_dwordx4 v[10:13], v[10:11], off nt
.LBB0_1222:
	s_or_b64 exec, exec, s[2:3]
	v_mov_b32_e32 v18, 0
	v_mov_b32_e32 v22, 0
	v_mov_b32_e32 v23, 0
	v_mov_b32_e32 v24, 0
	v_mov_b32_e32 v25, 0
	s_and_saveexec_b64 s[2:3], vcc
	s_cbranch_execz .LBB0_1224
	v_add_u32_e32 v19, 32, v40
	s_movk_i32 s4, 0x5640
	v_mad_i64_i32 v[20:21], s[4:5], v19, s4, v[36:37]
	global_load_dwordx4 v[22:25], v[20:21], off nt
.LBB0_1224:
	s_or_b64 exec, exec, s[2:3]
	v_mov_b32_e32 v19, 0
	v_mov_b32_e32 v20, 0
	v_mov_b32_e32 v21, 0
	s_and_saveexec_b64 s[2:3], vcc
	s_cbranch_execz .LBB0_1226
	v_add_u32_e32 v18, 40, v40
	s_movk_i32 s4, 0x5640
	v_mad_i64_i32 v[18:19], s[4:5], v18, s4, v[36:37]
	global_load_dwordx4 v[18:21], v[18:19], off nt
.LBB0_1226:
	s_or_b64 exec, exec, s[2:3]
	v_mov_b32_e32 v26, 0
	v_mov_b32_e32 v30, 0
	v_mov_b32_e32 v31, 0
	v_mov_b32_e32 v32, 0
	v_mov_b32_e32 v33, 0
	s_and_saveexec_b64 s[2:3], vcc
	s_cbranch_execz .LBB0_1228
	v_add_u32_e32 v27, 48, v40
	s_movk_i32 s4, 0x5640
	v_mad_i64_i32 v[28:29], s[4:5], v27, s4, v[36:37]
	global_load_dwordx4 v[30:33], v[28:29], off nt
.LBB0_1228:
	s_or_b64 exec, exec, s[2:3]
	v_mov_b32_e32 v27, 0
	v_mov_b32_e32 v28, 0
	v_mov_b32_e32 v29, 0
	s_and_saveexec_b64 s[2:3], vcc
	s_cbranch_execz .LBB0_1162
	v_add_u32_e32 v26, 56, v40
	s_movk_i32 s4, 0x5640
	v_mad_i64_i32 v[26:27], s[4:5], v26, s4, v[36:37]
	global_load_dwordx4 v[26:29], v[26:27], off nt
	s_branch .LBB0_1162

; DI float bflo(unsigned u) { return __uint_as_float(u << 16); }
; DI float bfhi(unsigned u) { return __uint_as_float(u & 0xffff0000u); }
; DI float wave_sum(float v) { v += __shfl_xor(v, 32); v += __shfl_xor(v, 16); v += __shfl_xor(v, 8); v += __shfl_xor(v, 4); v += __shfl_xor(v, 2); v += __shfl_xor(v, 1); return v; }
; DI void rownorm_phase(const Params& P, const float* xin, const bf16_t* yin, float* xout, bf16_t* hout, int lg, int gate_idx, const float* w_post,
;                       int lh, int scale_idx, int shift_idx, const float* w_pre, char* smem) {
;     ...
;   for (int row = blockIdx.x * 8 + w; row < S_; row += gridDim.x * 8) {
;     f32x4 xv[8];
; #pragma unroll
;     for (int j = 0; j < 8; ++j) xv[j] = __builtin_nontemporal_load((const f32x4*)(xin + (size_t)row * 2048 + (j * 64 + lane) * 4));
;     if (yin) {
;       f32x4 yv[8]; float ss = 0.f;
; #pragma unroll
;       for (int j = 0; j < 8; ++j) { const u32x2 yb = __builtin_nontemporal_load((const u32x2*)(yin + (size_t)row * 2048 + (j * 64 + lane) * 4)); yv[j] = (f32x4){bflo(yb.x), bfhi(yb.x), bflo(yb.y), bfhi(yb.y)};
;         ss += yv[j].x * yv[j].x + yv[j].y * yv[j].y + yv[j].z * yv[j].z + yv[j].w * yv[j].w; }
;       ss = wave_sum(ss); const float r = rsqrtf(ss * (1.f / 2048.f) + EPS);
; #pragma unroll
;       for (int j = 0; j < 8; ++j) { const f32x4 a = *(const f32x4*)(A1 + (j * 64 + lane) * 4); xv[j] += a * (yv[j] * r); }
.LBB0_1236:
	v_ashrrev_i32_e32 v37, 31, v36
	v_lshlrev_b64 v[2:3], 13, v[36:37]
	v_lshl_add_u64 v[2:3], v[34:35], 0, v[2:3]
	v_lshlrev_b64 v[50:51], 12, v[36:37]
	v_lshl_add_u64 v[52:53], v[2:3], 0, v[0:1]
	v_lshl_add_u64 v[86:87], v[38:39], 0, v[50:51]
	global_load_dwordx4 v[30:33], v[52:53], off nt
	global_load_dwordx4 v[26:29], v[52:53], off offset:1024 nt
	global_load_dwordx4 v[22:25], v[52:53], off offset:2048 nt
	global_load_dwordx4 v[18:21], v[52:53], off offset:3072 nt
	global_load_dwordx2 v[62:63], v[86:87], off nt
	v_mov_b32_e32 v43, v1
	v_mov_b32_e32 v45, v1
	v_mov_b32_e32 v47, v1
	v_mov_b32_e32 v49, v1
	v_lshl_add_u64 v[54:55], v[2:3], 0, v[42:43]
	v_lshl_add_u64 v[56:57], v[2:3], 0, v[44:45]
	v_lshl_add_u64 v[58:59], v[2:3], 0, v[46:47]
	v_lshl_add_u64 v[60:61], v[2:3], 0, v[48:49]
	global_load_dwordx4 v[14:17], v[54:55], off nt
	global_load_dwordx4 v[10:13], v[56:57], off nt
	global_load_dwordx4 v[6:9], v[58:59], off nt
	global_load_dwordx4 v[2:5], v[60:61], off nt
	v_add_u32_e32 v36, s79, v36
	s_waitcnt vmcnt(0)
	v_lshlrev_b32_e32 v70, 16, v62
	v_and_b32_e32 v71, 0xffff0000, v62
	v_lshlrev_b32_e32 v72, 16, v63
	v_and_b32_e32 v73, 0xffff0000, v63
	global_load_dwordx2 v[62:63], v[86:87], off offset:512 nt
	v_mul_f32_e32 v37, v71, v71
	v_fmac_f32_e32 v37, v70, v70
	v_fmac_f32_e32 v37, v72, v72
	v_fmac_f32_e32 v37, v73, v73
	s_waitcnt vmcnt(0)
	v_lshlrev_b32_e32 v74, 16, v62
	v_and_b32_e32 v75, 0xffff0000, v62
	v_lshlrev_b32_e32 v76, 16, v63
	v_and_b32_e32 v77, 0xffff0000, v63
	global_load_dwordx2 v[62:63], v[86:87], off offset:1024 nt
	v_mul_f32_e32 v43, v75, v75
	v_fmac_f32_e32 v43, v74, v74
	v_fmac_f32_e32 v43, v76, v76
	v_fmac_f32_e32 v43, v77, v77
	v_add_f32_e32 v37, v37, v43
	s_waitcnt vmcnt(0)
	v_lshlrev_b32_e32 v78, 16, v62
	v_and_b32_e32 v79, 0xffff0000, v62
	v_lshlrev_b32_e32 v80, 16, v63
	v_and_b32_e32 v81, 0xffff0000, v63
	global_load_dwordx2 v[62:63], v[86:87], off offset:1536 nt
	global_load_dwordx2 v[88:89], v[86:87], off offset:2048 nt
	global_load_dwordx2 v[66:67], v[86:87], off offset:2560 nt
	global_load_dwordx2 v[102:103], v[86:87], off offset:3072 nt
	global_load_dwordx2 v[92:93], v[86:87], off offset:3584 nt
	v_mul_f32_e32 v43, v79, v79
	v_fmac_f32_e32 v43, v78, v78
	v_fmac_f32_e32 v43, v80, v80
	v_fmac_f32_e32 v43, v81, v81
	v_add_f32_e32 v37, v37, v43
	s_waitcnt vmcnt(0)
	v_lshlrev_b32_e32 v64, 16, v88
	v_and_b32_e32 v83, 0xffff0000, v62
	v_lshlrev_b32_e32 v82, 16, v62
	v_lshlrev_b32_e32 v84, 16, v63
	v_and_b32_e32 v85, 0xffff0000, v63
	v_mul_f32_e32 v43, v83, v83
	v_and_b32_e32 v63, 0xffff0000, v66
	v_and_b32_e32 v62, 0xffff0000, v88
	v_fmac_f32_e32 v43, v82, v82
	v_lshlrev_b32_e32 v65, 16, v66
	v_lshlrev_b32_e32 v68, 16, v89
	v_and_b32_e32 v66, 0xffff0000, v89
	v_pk_mul_f32 v[88:89], v[62:63], v[62:63]
	v_fmac_f32_e32 v43, v84, v84
	v_lshlrev_b32_e32 v69, 16, v67
	v_pk_fma_f32 v[88:89], v[64:65], v[64:65], v[88:89]
	v_fmac_f32_e32 v43, v85, v85
	v_and_b32_e32 v67, 0xffff0000, v67
	v_pk_fma_f32 v[88:89], v[68:69], v[68:69], v[88:89]
	v_add_f32_e32 v37, v37, v43
	v_pk_fma_f32 v[88:89], v[66:67], v[66:67], v[88:89]
	v_lshlrev_b32_e32 v87, 16, v92
	v_add_f32_e32 v37, v37, v88
	v_add_f32_e32 v37, v37, v89
	v_and_b32_e32 v89, 0xffff0000, v92
	v_and_b32_e32 v88, 0xffff0000, v102
	v_lshlrev_b32_e32 v86, 16, v102
	v_lshlrev_b32_e32 v90, 16, v103
	v_and_b32_e32 v92, 0xffff0000, v103
	v_pk_mul_f32 v[102:103], v[88:89], v[88:89]
	v_lshlrev_b32_e32 v91, 16, v93
	v_pk_fma_f32 v[102:103], v[86:87], v[86:87], v[102:103]
	v_and_b32_e32 v93, 0xffff0000, v93
	v_pk_fma_f32 v[102:103], v[90:91], v[90:91], v[102:103]
	s_nop 0
	v_pk_fma_f32 v[102:103], v[92:93], v[92:93], v[102:103]
	s_nop 0
	v_add_f32_e32 v37, v37, v102
	v_add_f32_e32 v37, v37, v103
	ds_bpermute_b32 v43, v96, v37
	ds_read_b128 v[102:105], v95
	s_waitcnt lgkmcnt(0)
	v_add_f32_e32 v37, v37, v43
	ds_bpermute_b32 v43, v97, v37
	s_waitcnt lgkmcnt(0)
	v_add_f32_e32 v37, v37, v43
	ds_bpermute_b32 v43, v98, v37
	s_waitcnt lgkmcnt(0)
	v_add_f32_e32 v37, v37, v43
	ds_bpermute_b32 v43, v99, v37
	s_waitcnt lgkmcnt(0)
	v_add_f32_e32 v37, v37, v43
	ds_bpermute_b32 v43, v100, v37
	s_waitcnt lgkmcnt(0)
	v_add_f32_e32 v37, v37, v43
	ds_bpermute_b32 v43, v101, v37
	s_waitcnt lgkmcnt(0)
	v_add_f32_e32 v37, v37, v43
	v_fmamk_f32 v37, v37, 0x3a000000, v245
	v_cmp_gt_f32_e32 vcc, s84, v37
	v_mul_f32_e32 v43, 0x4b800000, v37
	s_nop 0
	v_cndmask_b32_e32 v37, v37, v43, vcc
	v_rsq_f32_e32 v37, v37
	s_nop 0
	v_mul_f32_e32 v43, 0x45800000, v37
	v_cndmask_b32_e32 v94, v37, v43, vcc
	v_pk_mul_f32 v[70:71], v[70:71], v[94:95] op_sel_hi:[1,0]
	v_pk_mul_f32 v[72:73], v[72:73], v[94:95] op_sel_hi:[1,0]
	v_pk_fma_f32 v[30:31], v[102:103], v[70:71], v[30:31]
	v_pk_fma_f32 v[32:33], v[104:105], v[72:73], v[32:33]
	ds_read_b128 v[70:73], v95 offset:1024
	v_pk_mul_f32 v[74:75], v[74:75], v[94:95] op_sel_hi:[1,0]
	v_pk_mul_f32 v[76:77], v[76:77], v[94:95] op_sel_hi:[1,0]
	v_mul_f32_e32 v37, v31, v31
	v_fmac_f32_e32 v37, v30, v30
	s_waitcnt lgkmcnt(0)
	v_pk_fma_f32 v[28:29], v[72:73], v[76:77], v[28:29]
	v_pk_fma_f32 v[26:27], v[70:71], v[74:75], v[26:27]
	ds_read_b128 v[70:73], v95 offset:2048
	v_pk_mul_f32 v[74:75], v[78:79], v[94:95] op_sel_hi:[1,0]
	v_pk_mul_f32 v[76:77], v[80:81], v[94:95] op_sel_hi:[1,0]
	v_mul_f32_e32 v43, v27, v27
	v_fmac_f32_e32 v43, v26, v26
	s_waitcnt lgkmcnt(0)
	v_pk_fma_f32 v[24:25], v[72:73], v[76:77], v[24:25]
	v_pk_fma_f32 v[22:23], v[70:71], v[74:75], v[22:23]
	ds_read_b128 v[70:73], v95 offset:3072
	v_pk_mul_f32 v[74:75], v[82:83], v[94:95] op_sel_hi:[1,0]
	v_pk_mul_f32 v[76:77], v[84:85], v[94:95] op_sel_hi:[1,0]
	v_fmac_f32_e32 v37, v32, v32
	v_fmac_f32_e32 v43, v28, v28
	s_waitcnt lgkmcnt(0)
; DI float wave_sum(float v) { v += __shfl_xor(v, 32); v += __shfl_xor(v, 16); v += __shfl_xor(v, 8); v += __shfl_xor(v, 4); v += __shfl_xor(v, 2); v += __shfl_xor(v, 1); return v; }
; DI void rownorm_phase(const Params& P, const float* xin, const bf16_t* yin, float* xout, bf16_t* hout, int lg, int gate_idx, const float* w_post,
;                       int lh, int scale_idx, int shift_idx, const float* w_pre, char* smem) {
;     ...
;       for (int j = 0; j < 8; ++j) { const f32x4 a = *(const f32x4*)(A1 + (j * 64 + lane) * 4); xv[j] += a * (yv[j] * r); }
;     }
;     if (yin || xout != xin) {
; #pragma unroll
;       for (int j = 0; j < 8; ++j) __builtin_nontemporal_store(xv[j], (f32x4*)(xout + (size_t)row * 2048 + (j * 64 + lane) * 4));
;     }
;     if (hout) {
;       float ss = 0.f;
; #pragma unroll
;       for (int j = 0; j < 8; ++j) ss += xv[j].x * xv[j].x + xv[j].y * xv[j].y + xv[j].z * xv[j].z + xv[j].w * xv[j].w;
;       ss = wave_sum(ss); const float r = rsqrtf(ss * (1.f / 2048.f) + EPS);
	v_pk_fma_f32 v[20:21], v[72:73], v[76:77], v[20:21]
	v_pk_fma_f32 v[18:19], v[70:71], v[74:75], v[18:19]
	ds_read_b128 v[70:73], v95 offset:4096
	v_mov_b32_e32 v74, v64
	v_mov_b32_e32 v75, v62
	v_mov_b32_e32 v76, v68
	v_mov_b32_e32 v77, v66
	v_pk_mul_f32 v[74:75], v[74:75], v[94:95] op_sel_hi:[1,0]
	v_pk_mul_f32 v[76:77], v[76:77], v[94:95] op_sel_hi:[1,0]
	s_waitcnt lgkmcnt(0)
	v_pk_fma_f32 v[14:15], v[70:71], v[74:75], v[14:15]
	v_pk_fma_f32 v[16:17], v[72:73], v[76:77], v[16:17]
	ds_read_b128 v[70:73], v95 offset:5120
	v_mov_b32_e32 v62, v65
	v_mov_b32_e32 v66, v69
	v_pk_mul_f32 v[62:63], v[62:63], v[94:95] op_sel_hi:[1,0]
	v_pk_mul_f32 v[64:65], v[66:67], v[94:95] op_sel_hi:[1,0]
	s_waitcnt lgkmcnt(0)
	v_pk_fma_f32 v[10:11], v[70:71], v[62:63], v[10:11]
	v_pk_fma_f32 v[12:13], v[72:73], v[64:65], v[12:13]
	ds_read_b128 v[62:65], v95 offset:6144
	v_mov_b32_e32 v66, v86
	v_mov_b32_e32 v67, v88
	v_mov_b32_e32 v68, v90
	v_mov_b32_e32 v69, v92
	v_pk_mul_f32 v[66:67], v[66:67], v[94:95] op_sel_hi:[1,0]
	v_pk_mul_f32 v[68:69], v[68:69], v[94:95] op_sel_hi:[1,0]
	s_waitcnt lgkmcnt(0)
	v_pk_fma_f32 v[6:7], v[62:63], v[66:67], v[6:7]
	v_pk_fma_f32 v[8:9], v[64:65], v[68:69], v[8:9]
	ds_read_b128 v[62:65], v95 offset:7168
	v_fmac_f32_e32 v37, v33, v33
	v_fmac_f32_e32 v43, v29, v29
	v_add_f32_e32 v37, v37, v43
	v_mul_f32_e32 v43, v23, v23
	v_fmac_f32_e32 v43, v22, v22
	v_mov_b32_e32 v88, v87
	v_mov_b32_e32 v92, v91
	v_fmac_f32_e32 v43, v24, v24
	v_pk_mul_f32 v[66:67], v[88:89], v[94:95] op_sel_hi:[1,0]
	v_pk_mul_f32 v[68:69], v[92:93], v[94:95] op_sel_hi:[1,0]
	v_fmac_f32_e32 v43, v25, v25
	s_waitcnt lgkmcnt(0)
	v_pk_fma_f32 v[4:5], v[64:65], v[68:69], v[4:5]
	v_pk_fma_f32 v[2:3], v[62:63], v[66:67], v[2:3]
	global_store_dwordx4 v[52:53], v[30:33], off nt
	global_store_dwordx4 v[52:53], v[26:29], off offset:1024 nt
	global_store_dwordx4 v[52:53], v[22:25], off offset:2048 nt
	global_store_dwordx4 v[52:53], v[18:21], off offset:3072 nt
	global_store_dwordx4 v[54:55], v[14:17], off nt
	global_store_dwordx4 v[56:57], v[10:13], off nt
	global_store_dwordx4 v[58:59], v[6:9], off nt
	global_store_dwordx4 v[60:61], v[2:5], off nt
	v_add_f32_e32 v37, v43, v37
	v_mul_f32_e32 v43, v19, v19
	v_mov_b32_e32 v54, v11
	v_mov_b32_e32 v55, v15
	v_fmac_f32_e32 v43, v18, v18
	v_mov_b32_e32 v52, v10
	v_mov_b32_e32 v53, v14
	v_pk_mul_f32 v[54:55], v[54:55], v[54:55]
	v_fmac_f32_e32 v43, v20, v20
	v_pk_fma_f32 v[52:53], v[52:53], v[52:53], v[54:55]
	v_mov_b32_e32 v54, v12
	v_mov_b32_e32 v55, v16
	v_fmac_f32_e32 v43, v21, v21
	v_pk_fma_f32 v[52:53], v[54:55], v[54:55], v[52:53]
	v_mov_b32_e32 v54, v13
	v_mov_b32_e32 v55, v17
	v_add_f32_e32 v37, v43, v37
	v_pk_fma_f32 v[52:53], v[54:55], v[54:55], v[52:53]
	v_mov_b32_e32 v54, v3
	v_add_f32_e32 v37, v53, v37
	v_mov_b32_e32 v55, v7
	v_add_f32_e32 v37, v52, v37
	v_mov_b32_e32 v52, v2
	v_mov_b32_e32 v53, v6
	v_pk_mul_f32 v[54:55], v[54:55], v[54:55]
	s_nop 0
	v_pk_fma_f32 v[52:53], v[52:53], v[52:53], v[54:55]
	v_mov_b32_e32 v54, v4
	v_mov_b32_e32 v55, v8
	v_pk_fma_f32 v[52:53], v[54:55], v[54:55], v[52:53]
	v_mov_b32_e32 v54, v5
	v_mov_b32_e32 v55, v9
	v_pk_fma_f32 v[52:53], v[54:55], v[54:55], v[52:53]
	ds_read_b128 v[54:57], v95 offset:8192
	ds_read_b128 v[58:61], v95 offset:16384
	v_add_f32_e32 v37, v53, v37
	v_add_f32_e32 v37, v52, v37
	ds_bpermute_b32 v43, v96, v37
	s_waitcnt lgkmcnt(0)
	v_add_f32_e32 v37, v37, v43
	ds_bpermute_b32 v43, v97, v37
	s_waitcnt lgkmcnt(0)
	v_add_f32_e32 v37, v37, v43
	ds_bpermute_b32 v43, v98, v37
	s_waitcnt lgkmcnt(0)
	v_add_f32_e32 v37, v37, v43
	ds_bpermute_b32 v43, v99, v37
	s_waitcnt lgkmcnt(0)
	v_add_f32_e32 v37, v37, v43
	ds_bpermute_b32 v43, v100, v37
	s_waitcnt lgkmcnt(0)
	v_add_f32_e32 v37, v37, v43
	ds_bpermute_b32 v43, v101, v37
	s_waitcnt lgkmcnt(0)
; DI unsigned pack2(float lo, float hi) { f32x2 v = {lo, hi}; bf2_t b = __builtin_convertvector(v, bf2_t); return __builtin_bit_cast(unsigned, b); }
; DI float wave_sum(float v) { v += __shfl_xor(v, 32); v += __shfl_xor(v, 16); v += __shfl_xor(v, 8); v += __shfl_xor(v, 4); v += __shfl_xor(v, 2); v += __shfl_xor(v, 1); return v; }
; DI void rownorm_phase(const Params& P, const float* xin, const bf16_t* yin, float* xout, bf16_t* hout, int lg, int gate_idx, const float* w_post,
;                       int lh, int scale_idx, int shift_idx, const float* w_pre, char* smem) {
;     ...
;       ss = wave_sum(ss); const float r = rsqrtf(ss * (1.f / 2048.f) + EPS);
; #pragma unroll
;       for (int j = 0; j < 8; ++j) { const f32x4 a = *(const f32x4*)(A2 + (j * 64 + lane) * 4), b = *(const f32x4*)(B2 + (j * 64 + lane) * 4);
;         const f32x4 hv = xv[j] * r * a + b; u32x2 pk = {pack2(hv.x, hv.y), pack2(hv.z, hv.w)};
;         *(u32x2*)(hout + (size_t)row * 2048 + (j * 64 + lane) * 4) = pk; }
;     }
	v_add_f32_e32 v37, v37, v43
	v_fmamk_f32 v37, v37, 0x3a000000, v245
	v_cmp_gt_f32_e32 vcc, s84, v37
	v_mul_f32_e32 v43, 0x4b800000, v37
	s_nop 0
	v_cndmask_b32_e32 v37, v37, v43, vcc
	v_rsq_f32_e32 v37, v37
	s_nop 0
	v_mul_f32_e32 v43, 0x45800000, v37
	v_cndmask_b32_e32 v52, v37, v43, vcc
	v_pk_mul_f32 v[30:31], v[30:31], v[52:53] op_sel_hi:[1,0]
	v_pk_mul_f32 v[32:33], v[32:33], v[52:53] op_sel_hi:[1,0]
	v_pk_fma_f32 v[30:31], v[54:55], v[30:31], v[58:59]
	v_pk_fma_f32 v[32:33], v[56:57], v[32:33], v[60:61]
	v_cvt_pk_bf16_f32 v54, v30, v31
	v_cvt_pk_bf16_f32 v55, v32, v33
	v_lshl_add_u64 v[30:31], v[40:41], 0, v[50:51]
	global_store_dwordx2 v[30:31], v[54:55], off
	ds_read_b128 v[54:57], v95 offset:9216
	ds_read_b128 v[58:61], v95 offset:17408
	v_pk_mul_f32 v[26:27], v[26:27], v[52:53] op_sel_hi:[1,0]
	v_pk_mul_f32 v[28:29], v[28:29], v[52:53] op_sel_hi:[1,0]
	v_pk_mul_f32 v[22:23], v[22:23], v[52:53] op_sel_hi:[1,0]
	v_pk_mul_f32 v[24:25], v[24:25], v[52:53] op_sel_hi:[1,0]
	s_waitcnt lgkmcnt(0)
	v_pk_fma_f32 v[28:29], v[56:57], v[28:29], v[60:61]
	v_pk_fma_f32 v[26:27], v[54:55], v[26:27], v[58:59]
	v_pk_mul_f32 v[18:19], v[18:19], v[52:53] op_sel_hi:[1,0]
	v_cvt_pk_bf16_f32 v26, v26, v27
	v_cvt_pk_bf16_f32 v27, v28, v29
	global_store_dwordx2 v[30:31], v[26:27], off offset:512
	ds_read_b128 v[26:29], v95 offset:10240
	ds_read_b128 v[54:57], v95 offset:18432
	v_pk_mul_f32 v[20:21], v[20:21], v[52:53] op_sel_hi:[1,0]
	v_pk_mul_f32 v[14:15], v[14:15], v[52:53] op_sel_hi:[1,0]
	v_pk_mul_f32 v[16:17], v[16:17], v[52:53] op_sel_hi:[1,0]
	v_pk_mul_f32 v[10:11], v[10:11], v[52:53] op_sel_hi:[1,0]
	s_waitcnt lgkmcnt(0)
	v_pk_fma_f32 v[24:25], v[28:29], v[24:25], v[56:57]
	v_pk_fma_f32 v[22:23], v[26:27], v[22:23], v[54:55]
	v_pk_mul_f32 v[12:13], v[12:13], v[52:53] op_sel_hi:[1,0]
	v_cvt_pk_bf16_f32 v22, v22, v23
	v_cvt_pk_bf16_f32 v23, v24, v25
	global_store_dwordx2 v[30:31], v[22:23], off offset:1024
	ds_read_b128 v[22:25], v95 offset:11264
	ds_read_b128 v[26:29], v95 offset:19456
	v_pk_mul_f32 v[6:7], v[6:7], v[52:53] op_sel_hi:[1,0]
	v_pk_mul_f32 v[8:9], v[8:9], v[52:53] op_sel_hi:[1,0]
	v_pk_mul_f32 v[2:3], v[2:3], v[52:53] op_sel_hi:[1,0]
	v_pk_mul_f32 v[4:5], v[4:5], v[52:53] op_sel_hi:[1,0]
	s_waitcnt lgkmcnt(0)
	v_pk_fma_f32 v[20:21], v[24:25], v[20:21], v[28:29]
	v_pk_fma_f32 v[18:19], v[22:23], v[18:19], v[26:27]
	v_cmp_lt_i32_e32 vcc, s4, v36
	v_cvt_pk_bf16_f32 v18, v18, v19
	v_cvt_pk_bf16_f32 v19, v20, v21
	global_store_dwordx2 v[30:31], v[18:19], off offset:1536
	ds_read_b128 v[18:21], v95 offset:12288
	ds_read_b128 v[22:25], v95 offset:20480
	s_or_b64 s[2:3], vcc, s[2:3]
	s_waitcnt lgkmcnt(0)
	v_pk_fma_f32 v[16:17], v[20:21], v[16:17], v[24:25]
	v_pk_fma_f32 v[14:15], v[18:19], v[14:15], v[22:23]
	s_nop 0
	v_cvt_pk_bf16_f32 v14, v14, v15
	v_cvt_pk_bf16_f32 v15, v16, v17
	global_store_dwordx2 v[30:31], v[14:15], off offset:2048
	ds_read_b128 v[14:17], v95 offset:13312
	ds_read_b128 v[18:21], v95 offset:21504
	s_waitcnt lgkmcnt(0)
	v_pk_fma_f32 v[12:13], v[16:17], v[12:13], v[20:21]
	v_pk_fma_f32 v[10:11], v[14:15], v[10:11], v[18:19]
	s_nop 0
	v_cvt_pk_bf16_f32 v10, v10, v11
	v_cvt_pk_bf16_f32 v11, v12, v13
	global_store_dwordx2 v[30:31], v[10:11], off offset:2560
	ds_read_b128 v[10:13], v95 offset:14336
	ds_read_b128 v[14:17], v95 offset:22528
	s_waitcnt lgkmcnt(0)
	v_pk_fma_f32 v[8:9], v[12:13], v[8:9], v[16:17]
	v_pk_fma_f32 v[6:7], v[10:11], v[6:7], v[14:15]
	s_nop 0
	v_cvt_pk_bf16_f32 v6, v6, v7
	v_cvt_pk_bf16_f32 v7, v8, v9
	global_store_dwordx2 v[30:31], v[6:7], off offset:3072
	ds_read_b128 v[6:9], v95 offset:15360
	ds_read_b128 v[10:13], v95 offset:23552
	s_waitcnt lgkmcnt(0)
	v_pk_fma_f32 v[4:5], v[8:9], v[4:5], v[12:13]
	v_pk_fma_f32 v[2:3], v[6:7], v[2:3], v[10:11]
	s_nop 0
	v_cvt_pk_bf16_f32 v2, v2, v3
	v_cvt_pk_bf16_f32 v3, v4, v5
	global_store_dwordx2 v[30:31], v[2:3], off offset:3584
	s_andn2_b64 exec, exec, s[2:3]
	s_cbranch_execnz .LBB0_1236
